# wave priority raised during MFMA phases (attention PV+S phases; GEMM mainloops), lowered for softmax VALU / tile epilogues; on top of GQA row-sum on matrix pipe
# speedup vs baseline: 1.0296x; 1.0165x over previous
; #define GL1_(RA, RB, i) { RA[i] = *(const u32x4*)(ap + (aoff + (i) * astep)); if ((i) < NB) RB[(i) < NB ? (i) : 0] = *(const u32x4*)(bp + (boff + (i) * bstep)); }
; #define LS1_(RA, RB, ST, i) { char* sn_ = lds + (ST) * STAGE; *(u32x4*)(sn_ + wofs + (i) * 32 * LROW) = RA[i]; \
;                               if ((i) < NB) *(u32x4*)(sn_ + STAGE_OP + wofs + (i) * 32 * LROW) = RB[(i) < NB ? (i) : 0]; }
; template <int NJ> DI void gemm_mainloop_reg(const bf16_t* __restrict__ A, int lda, const bf16_t* __restrict__ Bt, int ldb, int K, f32x16 (&acc)[2][NJ], char* lds) {
;     ...
;   u32x4 ra0[4], rb0[NB], ra1[4], rb1[NB];
;   const int wofs = lr * LROW + lc * 16;
;   const int a_rd = (wm * 64 + (lane & 31)) * LROW + (lane >> 5) * 16;
;   const int b_rd = STAGE_OP + (wn * 32 * NJ + (lane & 31)) * LROW + (lane >> 5) * 16;
;     ...
; #pragma unroll
;   for (int i = 0; i < 4; ++i) GL1_(ra0, rb0, i);
;   ap += 128; bp += 128;
; #pragma unroll
;   for (int i = 0; i < 4; ++i) GL1_(ra1, rb1, i);
;   ap += 128; bp += 128;
; #pragma unroll
;   for (int i = 0; i < 4; ++i) LS1_(ra0, rb0, 0, i);
;   __syncthreads();
;   const int nk = K >> 6;
;   for (int kt = 0; kt < nk; kt += 2) {
;     const bool l0 = (kt + 2 < nk), l1 = (kt + 3 < nk);
;     STEP_(0, l0, ra0, rb0, true, ra1, rb1);
;     __syncthreads();
;     STEP_(1, l1, ra1, rb1, l0, ra0, rb0);
;     __syncthreads();
;   }
; DI void phase_ffn_in(const Ctx& c, const bf16_t* A, size_t woff, int site) {
;     ...
;   for (;;) {
;     const int j_ = grab_next(ctr, c.lds);
;     if (j_ >= 128 * 6) break;
;     const int mt = xcd_ * 16 + (j_ & 7) + 8 * ((j_ >> 6) & 1), nt = (j_ >> 7) * 8 + ((j_ >> 3) & 7);
;     if (nt >= 44) continue;
;     f32x16 acc[2][2]; zero_acc<2>(acc);
;     gemm_mainloop_reg<2>(A + (size_t)mt * 128 * LDX, LDX, Bt + (size_t)nt * 128 * LDX, LDX, DM, acc, c.lds);
.LBB0_365:
	s_or_b64 exec, exec, s[2:3]
	s_add_i32 s24, 0, 0x12210
	s_cmp_lg_u32 s24, -1
	s_cselect_b32 s2, s24, 0
	s_cselect_b32 s3, s79, 0
	v_mov_b32_e32 v2, s2
	v_mov_b32_e32 v3, s3
	s_waitcnt lgkmcnt(0)
	s_barrier
	flat_load_dword v2, v[2:3] sc0 sc1
	s_waitcnt vmcnt(0)
	s_mov_b64 s[2:3], -1
	s_waitcnt lgkmcnt(0)
	s_barrier
	v_readfirstlane_b32 s4, v2
	s_cmpk_gt_i32 s4, 0x2ff
	s_cbranch_scc1 .LBB0_360
	s_ashr_i32 s2, s4, 4
	s_and_b32 s2, s2, -8
	s_bfe_u32 s3, s4, 0x30003
	s_or_b32 s6, s2, s3
	s_cmp_gt_i32 s6, 43
	s_cbranch_scc1 .LBB0_359
	s_lshr_b32 s2, s4, 3
	s_and_b32 s7, s4, 7
	s_and_b32 s27, s2, 8
	s_or_b32 s2, s7, s27
	v_readlane_b32 s3, v250, 20
	s_or_b32 s34, s2, s3
	v_mov_b32_e32 v34, v199
	s_mul_i32 s2, s34, 0x44000
	s_add_u32 s2, s25, s2
	v_ashrrev_i32_e32 v35, 3, v34
	v_lshlrev_b32_e32 v2, 4, v34
	v_and_b32_e32 v36, 0x70, v2
	v_mul_lo_u32 v2, v35, s9
	s_addc_u32 s3, s26, 0
	s_mul_i32 s4, s6, 0x44000
	v_or_b32_e32 v80, v36, v2
	s_mul_hi_i32 s5, s6, 0x44000
	s_add_u32 s4, s22, s4
	v_add_u32_e32 v79, 0x11000, v80
	v_add_u32_e32 v78, 0x22000, v80
	v_add_u32_e32 v77, 0x33000, v80
	s_addc_u32 s5, s23, s5
	global_load_dwordx4 v[2:5], v80, s[2:3]
	global_load_dwordx4 v[6:9], v79, s[2:3]
	global_load_dwordx4 v[10:13], v78, s[2:3]
	global_load_dwordx4 v[14:17], v77, s[2:3]
	global_load_dwordx4 v[18:21], v80, s[4:5]
	global_load_dwordx4 v[22:25], v79, s[4:5]
	global_load_dwordx4 v[26:29], v78, s[4:5]
	global_load_dwordx4 v[30:33], v77, s[4:5]
	v_mul_lo_u32 v35, v35, s16
	v_lshrrev_b32_e32 v37, 1, v34
	v_and_b32_e32 v38, 31, v34
	v_add3_u32 v75, v35, v36, 0
	v_and_b32_e32 v39, 16, v37
	v_and_or_b32 v37, v37, s17, v38
	global_load_dwordx4 v[82:85], v80, s[2:3] offset:128
	global_load_dwordx4 v[86:89], v79, s[2:3] offset:128
	global_load_dwordx4 v[90:93], v78, s[2:3] offset:128
	global_load_dwordx4 v[94:97], v77, s[2:3] offset:128
	global_load_dwordx4 v[98:101], v80, s[4:5] offset:128
	global_load_dwordx4 v[102:105], v79, s[4:5] offset:128
	global_load_dwordx4 v[106:109], v78, s[4:5] offset:128
	global_load_dwordx4 v[110:113], v77, s[4:5] offset:128
	v_mul_lo_u32 v35, v37, s16
	v_add3_u32 v73, v35, v39, 0
	v_add_u32_e32 v76, 0xd800, v75
	s_waitcnt vmcnt(15)
	ds_write_b128 v75, v[2:5]
	s_waitcnt vmcnt(14)
	ds_write_b128 v75, v[6:9] offset:4608
	s_waitcnt vmcnt(13)
	ds_write_b128 v75, v[10:13] offset:9216
	s_waitcnt vmcnt(12)
	ds_write_b128 v75, v[14:17] offset:13824
	s_waitcnt vmcnt(11)
	ds_write_b128 v75, v[18:21] offset:18432
	s_waitcnt vmcnt(10)
	ds_write_b128 v75, v[22:25] offset:23040
	s_waitcnt vmcnt(9)
	ds_write_b128 v75, v[26:29] offset:27648
	s_waitcnt vmcnt(8)
	ds_write_b128 v75, v[30:33] offset:32256
	v_and_b32_e32 v2, 0x5f, v34
	v_mul_u32_u24_e32 v2, 0x90, v2
	v_add3_u32 v74, v2, v39, 0
	s_waitcnt lgkmcnt(0)
	s_barrier
	ds_read_b128 v[18:21], v73
	ds_read_b128 v[2:5], v74 offset:18432
	ds_read_b128 v[114:117], v73 offset:32
	ds_read_b128 v[118:121], v74 offset:18464
	ds_read_b128 v[22:25], v73 offset:4608
	ds_read_b128 v[122:125], v73 offset:4640
	ds_read_b128 v[26:29], v74 offset:23040
	ds_read_b128 v[126:129], v74 offset:23072
	global_load_dwordx4 v[130:133], v80, s[2:3] offset:256
	global_load_dwordx4 v[134:137], v80, s[4:5] offset:256
	s_waitcnt lgkmcnt(6)
	s_setprio 1
	v_mfma_f32_32x32x16_bf16 v[34:49], v[18:21], v[2:5], 0
	s_waitcnt vmcnt(9)
	ds_write_b128 v75, v[82:85] offset:36864
	s_waitcnt vmcnt(5)
	ds_write_b128 v75, v[98:101] offset:55296
	s_waitcnt lgkmcnt(5)
	v_mfma_f32_32x32x16_bf16 v[2:17], v[22:25], v[2:5], 0
	s_waitcnt lgkmcnt(3)
	v_mfma_f32_32x32x16_bf16 v[50:65], v[18:21], v[26:29], 0
	v_mfma_f32_32x32x16_bf16 v[18:33], v[22:25], v[26:29], 0
	global_load_dwordx4 v[82:85], v79, s[2:3] offset:256
	global_load_dwordx4 v[98:101], v79, s[4:5] offset:256
	v_mfma_f32_32x32x16_bf16 v[34:49], v[114:117], v[118:121], v[34:49]
	v_mfma_f32_32x32x16_bf16 v[2:17], v[122:125], v[118:121], v[2:17]
	s_waitcnt lgkmcnt(2)
	v_mfma_f32_32x32x16_bf16 v[50:65], v[114:117], v[126:129], v[50:65]
	ds_read_b128 v[114:117], v73 offset:64
	ds_read_b128 v[118:121], v73 offset:4672
	ds_read_b128 v[138:141], v74 offset:18496
	ds_read_b128 v[142:145], v74 offset:23104
	ds_write_b128 v75, v[86:89] offset:41472
	s_waitcnt vmcnt(6)
	ds_write_b128 v75, v[102:105] offset:59904
	v_mfma_f32_32x32x16_bf16 v[18:33], v[122:125], v[126:129], v[18:33]
	global_load_dwordx4 v[86:89], v78, s[2:3] offset:256
	global_load_dwordx4 v[102:105], v78, s[4:5] offset:256
	s_waitcnt lgkmcnt(3)
	v_mfma_f32_32x32x16_bf16 v[34:49], v[114:117], v[138:141], v[34:49]
	v_mfma_f32_32x32x16_bf16 v[2:17], v[118:121], v[138:141], v[2:17]
	s_waitcnt lgkmcnt(2)
	v_mfma_f32_32x32x16_bf16 v[50:65], v[114:117], v[142:145], v[50:65]
	ds_read_b128 v[114:117], v73 offset:96
	ds_read_b128 v[122:125], v73 offset:4704
	ds_read_b128 v[126:129], v74 offset:18528
	ds_read_b128 v[138:141], v74 offset:23136
	ds_write_b128 v75, v[90:93] offset:46080
	s_waitcnt vmcnt(7)
	ds_write_b128 v75, v[106:109] offset:64512
	v_mfma_f32_32x32x16_bf16 v[18:33], v[118:121], v[142:145], v[18:33]
	global_load_dwordx4 v[90:93], v77, s[2:3] offset:256
	global_load_dwordx4 v[106:109], v77, s[4:5] offset:256
	s_waitcnt lgkmcnt(3)
	v_mfma_f32_32x32x16_bf16 v[34:49], v[114:117], v[126:129], v[34:49]
	ds_write_b128 v75, v[94:97] offset:50688
	s_waitcnt vmcnt(8)
	ds_write_b128 v76, v[110:113] offset:13824
	v_mfma_f32_32x32x16_bf16 v[2:17], v[122:125], v[126:129], v[2:17]
	s_waitcnt lgkmcnt(4)
	v_mfma_f32_32x32x16_bf16 v[50:65], v[114:117], v[138:141], v[50:65]
	v_mfma_f32_32x32x16_bf16 v[18:33], v[122:125], v[138:141], v[18:33]
	s_waitcnt lgkmcnt(0)
	s_barrier
; #define GL1_(RA, RB, i) { RA[i] = *(const u32x4*)(ap + (aoff + (i) * astep)); if ((i) < NB) RB[(i) < NB ? (i) : 0] = *(const u32x4*)(bp + (boff + (i) * bstep)); }
; #define LS1_(RA, RB, ST, i) { char* sn_ = lds + (ST) * STAGE; *(u32x4*)(sn_ + wofs + (i) * 32 * LROW) = RA[i]; \
;                               if ((i) < NB) *(u32x4*)(sn_ + STAGE_OP + wofs + (i) * 32 * LROW) = RB[(i) < NB ? (i) : 0]; }
; template <int NJ> DI void gemm_mainloop_reg(const bf16_t* __restrict__ A, int lda, const bf16_t* __restrict__ Bt, int ldb, int K, f32x16 (&acc)[2][NJ], char* lds) {
;     ...
; #pragma unroll
;   for (int i = 0; i < 4; ++i) GL1_(ra0, rb0, i);
;   ap += 128; bp += 128;
; #pragma unroll
;   for (int i = 0; i < 4; ++i) GL1_(ra1, rb1, i);
;   ap += 128; bp += 128;
; #pragma unroll
;   for (int i = 0; i < 4; ++i) LS1_(ra0, rb0, 0, i);
;   __syncthreads();
;   const int nk = K >> 6;
;   for (int kt = 0; kt < nk; kt += 2) {
;     const bool l0 = (kt + 2 < nk), l1 = (kt + 3 < nk);
;     STEP_(0, l0, ra0, rb0, true, ra1, rb1);
;     __syncthreads();
;     STEP_(1, l1, ra1, rb1, l0, ra0, rb0);
;     __syncthreads();
;   }
	ds_read_b128 v[94:97], v73 offset:36864
	ds_read_b128 v[110:113], v74 offset:55296
	ds_read_b128 v[114:117], v73 offset:36896
	ds_read_b128 v[118:121], v74 offset:55328
	ds_read_b128 v[122:125], v73 offset:41472
	ds_read_b128 v[126:129], v73 offset:41504
	s_waitcnt lgkmcnt(4)
	v_mfma_f32_32x32x16_bf16 v[34:49], v[94:97], v[110:113], v[34:49]
	s_waitcnt lgkmcnt(1)
	v_mfma_f32_32x32x16_bf16 v[2:17], v[122:125], v[110:113], v[2:17]
	ds_read_b128 v[110:113], v74 offset:59904
	ds_read_b128 v[138:141], v74 offset:59936
	s_waitcnt lgkmcnt(1)
	v_mfma_f32_32x32x16_bf16 v[50:65], v[94:97], v[110:113], v[50:65]
	global_load_dwordx4 v[94:97], v80, s[2:3] offset:384
	global_load_dwordx4 v[142:145], v80, s[4:5] offset:384
	s_waitcnt vmcnt(9)
	ds_write_b128 v75, v[130:133]
	s_waitcnt vmcnt(8)
	ds_write_b128 v75, v[134:137] offset:18432
	v_mfma_f32_32x32x16_bf16 v[18:33], v[122:125], v[110:113], v[18:33]
	v_mfma_f32_32x32x16_bf16 v[34:49], v[114:117], v[118:121], v[34:49]
	s_waitcnt lgkmcnt(2)
	v_mfma_f32_32x32x16_bf16 v[50:65], v[114:117], v[138:141], v[50:65]
	global_load_dwordx4 v[110:113], v79, s[2:3] offset:384
	global_load_dwordx4 v[114:117], v79, s[4:5] offset:384
	v_mfma_f32_32x32x16_bf16 v[2:17], v[126:129], v[118:121], v[2:17]
	ds_read_b128 v[118:121], v73 offset:36928
	ds_read_b128 v[122:125], v73 offset:41536
	ds_read_b128 v[130:133], v74 offset:55360
	ds_read_b128 v[134:137], v74 offset:59968
	s_waitcnt vmcnt(9)
	ds_write_b128 v75, v[82:85] offset:4608
	s_waitcnt vmcnt(8)
	ds_write_b128 v75, v[98:101] offset:23040
	v_mfma_f32_32x32x16_bf16 v[18:33], v[126:129], v[138:141], v[18:33]
	global_load_dwordx4 v[82:85], v78, s[2:3] offset:384
	global_load_dwordx4 v[98:101], v78, s[4:5] offset:384
	s_waitcnt lgkmcnt(3)
	v_mfma_f32_32x32x16_bf16 v[34:49], v[118:121], v[130:133], v[34:49]
	v_mfma_f32_32x32x16_bf16 v[2:17], v[122:125], v[130:133], v[2:17]
	s_waitcnt lgkmcnt(2)
	v_mfma_f32_32x32x16_bf16 v[50:65], v[118:121], v[134:137], v[50:65]
	ds_read_b128 v[118:121], v73 offset:36960
	ds_read_b128 v[126:129], v73 offset:41568
	ds_read_b128 v[130:133], v74 offset:55392
	ds_read_b128 v[138:141], v74 offset:60000
	s_waitcnt vmcnt(9)
	ds_write_b128 v75, v[86:89] offset:9216
	s_waitcnt vmcnt(8)
	ds_write_b128 v75, v[102:105] offset:27648
	v_mfma_f32_32x32x16_bf16 v[18:33], v[122:125], v[134:137], v[18:33]
	global_load_dwordx4 v[86:89], v77, s[2:3] offset:384
	global_load_dwordx4 v[102:105], v77, s[4:5] offset:384
	s_waitcnt lgkmcnt(3)
	v_mfma_f32_32x32x16_bf16 v[34:49], v[118:121], v[130:133], v[34:49]
	s_waitcnt vmcnt(9)
	ds_write_b128 v75, v[90:93] offset:13824
	s_waitcnt vmcnt(8)
	ds_write_b128 v75, v[106:109] offset:32256
	v_mfma_f32_32x32x16_bf16 v[2:17], v[126:129], v[130:133], v[2:17]
	s_waitcnt lgkmcnt(4)
	v_mfma_f32_32x32x16_bf16 v[50:65], v[118:121], v[138:141], v[50:65]
	v_mfma_f32_32x32x16_bf16 v[18:33], v[126:129], v[138:141], v[18:33]
	s_waitcnt lgkmcnt(0)
	s_barrier
	ds_read_b128 v[90:93], v73
	ds_read_b128 v[106:109], v74 offset:18432
	ds_read_b128 v[118:121], v73 offset:32
	ds_read_b128 v[122:125], v74 offset:18464
	ds_read_b128 v[126:129], v73 offset:4608
	ds_read_b128 v[130:133], v73 offset:4640
	s_waitcnt lgkmcnt(4)
	v_mfma_f32_32x32x16_bf16 v[34:49], v[90:93], v[106:109], v[34:49]
	s_waitcnt lgkmcnt(1)
	v_mfma_f32_32x32x16_bf16 v[2:17], v[126:129], v[106:109], v[2:17]
	ds_read_b128 v[106:109], v74 offset:23040
	ds_read_b128 v[134:137], v74 offset:23072
	s_waitcnt lgkmcnt(1)
	v_mfma_f32_32x32x16_bf16 v[50:65], v[90:93], v[106:109], v[50:65]
	global_load_dwordx4 v[90:93], v80, s[2:3] offset:512
	global_load_dwordx4 v[138:141], v80, s[4:5] offset:512
	s_waitcnt vmcnt(9)
	ds_write_b128 v75, v[94:97] offset:36864
	s_waitcnt vmcnt(8)
	ds_write_b128 v75, v[142:145] offset:55296
	v_mfma_f32_32x32x16_bf16 v[18:33], v[126:129], v[106:109], v[18:33]
	global_load_dwordx4 v[94:97], v79, s[2:3] offset:512
	global_load_dwordx4 v[106:109], v79, s[4:5] offset:512
	v_mfma_f32_32x32x16_bf16 v[34:49], v[118:121], v[122:125], v[34:49]
	v_mfma_f32_32x32x16_bf16 v[2:17], v[130:133], v[122:125], v[2:17]
	s_waitcnt lgkmcnt(2)
	v_mfma_f32_32x32x16_bf16 v[50:65], v[118:121], v[134:137], v[50:65]
	ds_read_b128 v[118:121], v73 offset:64
	ds_read_b128 v[122:125], v73 offset:4672
	ds_read_b128 v[126:129], v74 offset:18496
	ds_read_b128 v[142:145], v74 offset:23104
	s_waitcnt vmcnt(9)
	ds_write_b128 v75, v[110:113] offset:41472
	s_waitcnt vmcnt(8)
	ds_write_b128 v75, v[114:117] offset:59904
	v_mfma_f32_32x32x16_bf16 v[18:33], v[130:133], v[134:137], v[18:33]
	global_load_dwordx4 v[110:113], v78, s[2:3] offset:512
	global_load_dwordx4 v[114:117], v78, s[4:5] offset:512
	s_waitcnt lgkmcnt(3)
	v_mfma_f32_32x32x16_bf16 v[34:49], v[118:121], v[126:129], v[34:49]
	v_mfma_f32_32x32x16_bf16 v[2:17], v[122:125], v[126:129], v[2:17]
	s_waitcnt lgkmcnt(2)
	v_mfma_f32_32x32x16_bf16 v[50:65], v[118:121], v[142:145], v[50:65]
	ds_read_b128 v[118:121], v73 offset:96
	ds_read_b128 v[126:129], v73 offset:4704
	ds_read_b128 v[130:133], v74 offset:18528
	ds_read_b128 v[134:137], v74 offset:23136
	s_waitcnt vmcnt(9)
	ds_write_b128 v75, v[82:85] offset:46080
	s_waitcnt vmcnt(8)
	ds_write_b128 v75, v[98:101] offset:64512
	v_mfma_f32_32x32x16_bf16 v[18:33], v[122:125], v[142:145], v[18:33]
	global_load_dwordx4 v[82:85], v77, s[2:3] offset:512
	global_load_dwordx4 v[98:101], v77, s[4:5] offset:512
	s_waitcnt lgkmcnt(3)
	v_mfma_f32_32x32x16_bf16 v[34:49], v[118:121], v[130:133], v[34:49]
	s_waitcnt vmcnt(9)
	ds_write_b128 v75, v[86:89] offset:50688
	s_waitcnt vmcnt(8)
	ds_write_b128 v76, v[102:105] offset:13824
	v_mfma_f32_32x32x16_bf16 v[2:17], v[126:129], v[130:133], v[2:17]
	s_waitcnt lgkmcnt(4)
	v_mfma_f32_32x32x16_bf16 v[50:65], v[118:121], v[134:137], v[50:65]
	v_mfma_f32_32x32x16_bf16 v[18:33], v[126:129], v[134:137], v[18:33]
	s_waitcnt lgkmcnt(0)
	s_barrier
; #define GL1_(RA, RB, i) { RA[i] = *(const u32x4*)(ap + (aoff + (i) * astep)); if ((i) < NB) RB[(i) < NB ? (i) : 0] = *(const u32x4*)(bp + (boff + (i) * bstep)); }
; #define LS1_(RA, RB, ST, i) { char* sn_ = lds + (ST) * STAGE; *(u32x4*)(sn_ + wofs + (i) * 32 * LROW) = RA[i]; \
;                               if ((i) < NB) *(u32x4*)(sn_ + STAGE_OP + wofs + (i) * 32 * LROW) = RB[(i) < NB ? (i) : 0]; }
; template <int NJ> DI void gemm_mainloop_reg(const bf16_t* __restrict__ A, int lda, const bf16_t* __restrict__ Bt, int ldb, int K, f32x16 (&acc)[2][NJ], char* lds) {
;     ...
; #pragma unroll
;   for (int i = 0; i < 4; ++i) GL1_(ra0, rb0, i);
;   ap += 128; bp += 128;
; #pragma unroll
;   for (int i = 0; i < 4; ++i) GL1_(ra1, rb1, i);
;   ap += 128; bp += 128;
; #pragma unroll
;   for (int i = 0; i < 4; ++i) LS1_(ra0, rb0, 0, i);
;   __syncthreads();
;   const int nk = K >> 6;
;   for (int kt = 0; kt < nk; kt += 2) {
;     const bool l0 = (kt + 2 < nk), l1 = (kt + 3 < nk);
;     STEP_(0, l0, ra0, rb0, true, ra1, rb1);
;     __syncthreads();
;     STEP_(1, l1, ra1, rb1, l0, ra0, rb0);
;     __syncthreads();
;   }
	ds_read_b128 v[86:89], v73 offset:36864
	ds_read_b128 v[102:105], v74 offset:55296
	ds_read_b128 v[118:121], v73 offset:36896
	ds_read_b128 v[122:125], v74 offset:55328
	ds_read_b128 v[126:129], v73 offset:41472
	ds_read_b128 v[130:133], v73 offset:41504
	s_waitcnt lgkmcnt(4)
	v_mfma_f32_32x32x16_bf16 v[34:49], v[86:89], v[102:105], v[34:49]
	s_waitcnt lgkmcnt(1)
	v_mfma_f32_32x32x16_bf16 v[2:17], v[126:129], v[102:105], v[2:17]
	ds_read_b128 v[102:105], v74 offset:59904
	ds_read_b128 v[134:137], v74 offset:59936
	s_waitcnt lgkmcnt(1)
	v_mfma_f32_32x32x16_bf16 v[50:65], v[86:89], v[102:105], v[50:65]
	global_load_dwordx4 v[86:89], v80, s[2:3] offset:640
	global_load_dwordx4 v[142:145], v80, s[4:5] offset:640
	s_waitcnt vmcnt(9)
	ds_write_b128 v75, v[90:93]
	s_waitcnt vmcnt(8)
	ds_write_b128 v75, v[138:141] offset:18432
	v_mfma_f32_32x32x16_bf16 v[18:33], v[126:129], v[102:105], v[18:33]
	global_load_dwordx4 v[90:93], v79, s[2:3] offset:640
	global_load_dwordx4 v[102:105], v79, s[4:5] offset:640
	v_mfma_f32_32x32x16_bf16 v[34:49], v[118:121], v[122:125], v[34:49]
	v_mfma_f32_32x32x16_bf16 v[2:17], v[130:133], v[122:125], v[2:17]
	s_waitcnt lgkmcnt(2)
	v_mfma_f32_32x32x16_bf16 v[50:65], v[118:121], v[134:137], v[50:65]
	ds_read_b128 v[118:121], v73 offset:36928
	ds_read_b128 v[122:125], v73 offset:41536
	ds_read_b128 v[126:129], v74 offset:55360
	ds_read_b128 v[138:141], v74 offset:59968
	s_waitcnt vmcnt(9)
	ds_write_b128 v75, v[94:97] offset:4608
	s_waitcnt vmcnt(8)
	ds_write_b128 v75, v[106:109] offset:23040
	v_mfma_f32_32x32x16_bf16 v[18:33], v[130:133], v[134:137], v[18:33]
	global_load_dwordx4 v[94:97], v78, s[2:3] offset:640
	global_load_dwordx4 v[106:109], v78, s[4:5] offset:640
	s_waitcnt lgkmcnt(3)
	v_mfma_f32_32x32x16_bf16 v[34:49], v[118:121], v[126:129], v[34:49]
	v_mfma_f32_32x32x16_bf16 v[2:17], v[122:125], v[126:129], v[2:17]
	s_waitcnt lgkmcnt(2)
	v_mfma_f32_32x32x16_bf16 v[50:65], v[118:121], v[138:141], v[50:65]
	ds_read_b128 v[118:121], v73 offset:36960
	ds_read_b128 v[126:129], v73 offset:41568
	ds_read_b128 v[130:133], v74 offset:55392
	ds_read_b128 v[134:137], v74 offset:60000
	s_waitcnt vmcnt(9)
	ds_write_b128 v75, v[110:113] offset:9216
	s_waitcnt vmcnt(8)
	ds_write_b128 v75, v[114:117] offset:27648
	v_mfma_f32_32x32x16_bf16 v[18:33], v[122:125], v[138:141], v[18:33]
	global_load_dwordx4 v[110:113], v77, s[2:3] offset:640
	global_load_dwordx4 v[114:117], v77, s[4:5] offset:640
	s_waitcnt lgkmcnt(3)
	v_mfma_f32_32x32x16_bf16 v[34:49], v[118:121], v[130:133], v[34:49]
	s_waitcnt vmcnt(9)
	ds_write_b128 v75, v[82:85] offset:13824
	s_waitcnt vmcnt(8)
	ds_write_b128 v75, v[98:101] offset:32256
	v_mfma_f32_32x32x16_bf16 v[2:17], v[126:129], v[130:133], v[2:17]
	s_waitcnt lgkmcnt(4)
	v_mfma_f32_32x32x16_bf16 v[50:65], v[118:121], v[134:137], v[50:65]
	v_mfma_f32_32x32x16_bf16 v[18:33], v[126:129], v[134:137], v[18:33]
	s_waitcnt lgkmcnt(0)
	s_barrier
	ds_read_b128 v[82:85], v73
	ds_read_b128 v[98:101], v74 offset:18432
	ds_read_b128 v[118:121], v73 offset:32
	ds_read_b128 v[122:125], v74 offset:18464
	ds_read_b128 v[126:129], v73 offset:4608
	ds_read_b128 v[130:133], v73 offset:4640
	s_waitcnt lgkmcnt(4)
	v_mfma_f32_32x32x16_bf16 v[34:49], v[82:85], v[98:101], v[34:49]
	s_waitcnt lgkmcnt(1)
	v_mfma_f32_32x32x16_bf16 v[2:17], v[126:129], v[98:101], v[2:17]
	ds_read_b128 v[98:101], v74 offset:23040
	ds_read_b128 v[134:137], v74 offset:23072
	s_waitcnt lgkmcnt(1)
	v_mfma_f32_32x32x16_bf16 v[50:65], v[82:85], v[98:101], v[50:65]
	global_load_dwordx4 v[82:85], v80, s[2:3] offset:768
	global_load_dwordx4 v[138:141], v80, s[4:5] offset:768
	s_waitcnt vmcnt(9)
	ds_write_b128 v75, v[86:89] offset:36864
	s_waitcnt vmcnt(8)
	ds_write_b128 v75, v[142:145] offset:55296
	v_mfma_f32_32x32x16_bf16 v[18:33], v[126:129], v[98:101], v[18:33]
	global_load_dwordx4 v[86:89], v79, s[2:3] offset:768
	global_load_dwordx4 v[98:101], v79, s[4:5] offset:768
	v_mfma_f32_32x32x16_bf16 v[34:49], v[118:121], v[122:125], v[34:49]
	v_mfma_f32_32x32x16_bf16 v[2:17], v[130:133], v[122:125], v[2:17]
	s_waitcnt lgkmcnt(2)
	v_mfma_f32_32x32x16_bf16 v[50:65], v[118:121], v[134:137], v[50:65]
	ds_read_b128 v[118:121], v73 offset:64
	ds_read_b128 v[122:125], v73 offset:4672
	ds_read_b128 v[126:129], v74 offset:18496
	ds_read_b128 v[142:145], v74 offset:23104
	s_waitcnt vmcnt(9)
	ds_write_b128 v75, v[90:93] offset:41472
	s_waitcnt vmcnt(8)
	ds_write_b128 v75, v[102:105] offset:59904
	v_mfma_f32_32x32x16_bf16 v[18:33], v[130:133], v[134:137], v[18:33]
	global_load_dwordx4 v[90:93], v78, s[2:3] offset:768
	global_load_dwordx4 v[102:105], v78, s[4:5] offset:768
	s_waitcnt lgkmcnt(3)
	v_mfma_f32_32x32x16_bf16 v[34:49], v[118:121], v[126:129], v[34:49]
	v_mfma_f32_32x32x16_bf16 v[2:17], v[122:125], v[126:129], v[2:17]
	s_waitcnt lgkmcnt(2)
	v_mfma_f32_32x32x16_bf16 v[50:65], v[118:121], v[142:145], v[50:65]
	ds_read_b128 v[118:121], v73 offset:96
	ds_read_b128 v[126:129], v73 offset:4704
	ds_read_b128 v[130:133], v74 offset:18528
	ds_read_b128 v[134:137], v74 offset:23136
	s_waitcnt vmcnt(9)
	ds_write_b128 v75, v[94:97] offset:46080
	s_waitcnt vmcnt(8)
	ds_write_b128 v75, v[106:109] offset:64512
	v_mfma_f32_32x32x16_bf16 v[18:33], v[122:125], v[142:145], v[18:33]
	global_load_dwordx4 v[94:97], v77, s[2:3] offset:768
	global_load_dwordx4 v[106:109], v77, s[4:5] offset:768
	s_waitcnt lgkmcnt(3)
	v_mfma_f32_32x32x16_bf16 v[34:49], v[118:121], v[130:133], v[34:49]
	s_waitcnt vmcnt(9)
	ds_write_b128 v75, v[110:113] offset:50688
	s_waitcnt vmcnt(8)
	ds_write_b128 v76, v[114:117] offset:13824
	v_mfma_f32_32x32x16_bf16 v[2:17], v[126:129], v[130:133], v[2:17]
	s_waitcnt lgkmcnt(4)
	v_mfma_f32_32x32x16_bf16 v[50:65], v[118:121], v[134:137], v[50:65]
	v_mfma_f32_32x32x16_bf16 v[18:33], v[126:129], v[134:137], v[18:33]
	s_waitcnt lgkmcnt(0)
	s_barrier
; #define GL1_(RA, RB, i) { RA[i] = *(const u32x4*)(ap + (aoff + (i) * astep)); if ((i) < NB) RB[(i) < NB ? (i) : 0] = *(const u32x4*)(bp + (boff + (i) * bstep)); }
; #define LS1_(RA, RB, ST, i) { char* sn_ = lds + (ST) * STAGE; *(u32x4*)(sn_ + wofs + (i) * 32 * LROW) = RA[i]; \
;                               if ((i) < NB) *(u32x4*)(sn_ + STAGE_OP + wofs + (i) * 32 * LROW) = RB[(i) < NB ? (i) : 0]; }
; template <int NJ> DI void gemm_mainloop_reg(const bf16_t* __restrict__ A, int lda, const bf16_t* __restrict__ Bt, int ldb, int K, f32x16 (&acc)[2][NJ], char* lds) {
;     ...
; #pragma unroll
;   for (int i = 0; i < 4; ++i) GL1_(ra0, rb0, i);
;   ap += 128; bp += 128;
; #pragma unroll
;   for (int i = 0; i < 4; ++i) GL1_(ra1, rb1, i);
;   ap += 128; bp += 128;
; #pragma unroll
;   for (int i = 0; i < 4; ++i) LS1_(ra0, rb0, 0, i);
;   __syncthreads();
;   const int nk = K >> 6;
;   for (int kt = 0; kt < nk; kt += 2) {
;     const bool l0 = (kt + 2 < nk), l1 = (kt + 3 < nk);
;     STEP_(0, l0, ra0, rb0, true, ra1, rb1);
;     __syncthreads();
;     STEP_(1, l1, ra1, rb1, l0, ra0, rb0);
;     __syncthreads();
;   }
	ds_read_b128 v[110:113], v73 offset:36864
	ds_read_b128 v[114:117], v74 offset:55296
	ds_read_b128 v[118:121], v73 offset:36896
	ds_read_b128 v[122:125], v74 offset:55328
	ds_read_b128 v[126:129], v73 offset:41472
	ds_read_b128 v[130:133], v73 offset:41504
	s_waitcnt lgkmcnt(4)
	v_mfma_f32_32x32x16_bf16 v[34:49], v[110:113], v[114:117], v[34:49]
	s_waitcnt lgkmcnt(1)
	v_mfma_f32_32x32x16_bf16 v[2:17], v[126:129], v[114:117], v[2:17]
	ds_read_b128 v[114:117], v74 offset:59904
	ds_read_b128 v[134:137], v74 offset:59936
	s_waitcnt lgkmcnt(1)
	v_mfma_f32_32x32x16_bf16 v[50:65], v[110:113], v[114:117], v[50:65]
	global_load_dwordx4 v[110:113], v80, s[2:3] offset:896
	global_load_dwordx4 v[142:145], v80, s[4:5] offset:896
	s_waitcnt vmcnt(9)
	ds_write_b128 v75, v[82:85]
	s_waitcnt vmcnt(8)
	ds_write_b128 v75, v[138:141] offset:18432
	v_mfma_f32_32x32x16_bf16 v[18:33], v[126:129], v[114:117], v[18:33]
	global_load_dwordx4 v[82:85], v79, s[2:3] offset:896
	global_load_dwordx4 v[114:117], v79, s[4:5] offset:896
	v_mfma_f32_32x32x16_bf16 v[34:49], v[118:121], v[122:125], v[34:49]
	v_mfma_f32_32x32x16_bf16 v[2:17], v[130:133], v[122:125], v[2:17]
	s_waitcnt lgkmcnt(2)
	v_mfma_f32_32x32x16_bf16 v[50:65], v[118:121], v[134:137], v[50:65]
	ds_read_b128 v[118:121], v73 offset:36928
	ds_read_b128 v[122:125], v73 offset:41536
	ds_read_b128 v[126:129], v74 offset:55360
	ds_read_b128 v[138:141], v74 offset:59968
	s_waitcnt vmcnt(9)
	ds_write_b128 v75, v[86:89] offset:4608
	s_waitcnt vmcnt(8)
	ds_write_b128 v75, v[98:101] offset:23040
	v_mfma_f32_32x32x16_bf16 v[18:33], v[130:133], v[134:137], v[18:33]
	global_load_dwordx4 v[86:89], v78, s[2:3] offset:896
	global_load_dwordx4 v[98:101], v78, s[4:5] offset:896
	s_waitcnt lgkmcnt(3)
	v_mfma_f32_32x32x16_bf16 v[34:49], v[118:121], v[126:129], v[34:49]
	v_mfma_f32_32x32x16_bf16 v[2:17], v[122:125], v[126:129], v[2:17]
	s_waitcnt lgkmcnt(2)
	v_mfma_f32_32x32x16_bf16 v[50:65], v[118:121], v[138:141], v[50:65]
	ds_read_b128 v[118:121], v73 offset:36960
	ds_read_b128 v[126:129], v73 offset:41568
	ds_read_b128 v[130:133], v74 offset:55392
	ds_read_b128 v[134:137], v74 offset:60000
	s_waitcnt vmcnt(9)
	ds_write_b128 v75, v[90:93] offset:9216
	s_waitcnt vmcnt(8)
	ds_write_b128 v75, v[102:105] offset:27648
	v_mfma_f32_32x32x16_bf16 v[18:33], v[122:125], v[138:141], v[18:33]
	global_load_dwordx4 v[90:93], v77, s[2:3] offset:896
	global_load_dwordx4 v[102:105], v77, s[4:5] offset:896
	s_waitcnt lgkmcnt(3)
	v_mfma_f32_32x32x16_bf16 v[34:49], v[118:121], v[130:133], v[34:49]
	s_waitcnt vmcnt(9)
	ds_write_b128 v75, v[94:97] offset:13824
	s_waitcnt vmcnt(8)
	ds_write_b128 v75, v[106:109] offset:32256
	v_mfma_f32_32x32x16_bf16 v[2:17], v[126:129], v[130:133], v[2:17]
	s_waitcnt lgkmcnt(4)
	v_mfma_f32_32x32x16_bf16 v[50:65], v[118:121], v[134:137], v[50:65]
	v_mfma_f32_32x32x16_bf16 v[18:33], v[126:129], v[134:137], v[18:33]
	s_waitcnt lgkmcnt(0)
	s_barrier
	ds_read_b128 v[94:97], v73
	ds_read_b128 v[106:109], v74 offset:18432
	ds_read_b128 v[118:121], v73 offset:32
	ds_read_b128 v[122:125], v74 offset:18464
	ds_read_b128 v[126:129], v73 offset:4608
	ds_read_b128 v[130:133], v73 offset:4640
	s_waitcnt lgkmcnt(4)
	v_mfma_f32_32x32x16_bf16 v[34:49], v[94:97], v[106:109], v[34:49]
	s_waitcnt lgkmcnt(1)
	v_mfma_f32_32x32x16_bf16 v[2:17], v[126:129], v[106:109], v[2:17]
	ds_read_b128 v[106:109], v74 offset:23040
	ds_read_b128 v[134:137], v74 offset:23072
	s_waitcnt lgkmcnt(1)
	v_mfma_f32_32x32x16_bf16 v[50:65], v[94:97], v[106:109], v[50:65]
	global_load_dwordx4 v[94:97], v80, s[2:3] offset:1024
	global_load_dwordx4 v[138:141], v80, s[4:5] offset:1024
	s_waitcnt vmcnt(9)
	ds_write_b128 v75, v[110:113] offset:36864
	s_waitcnt vmcnt(8)
	ds_write_b128 v75, v[142:145] offset:55296
	v_mfma_f32_32x32x16_bf16 v[18:33], v[126:129], v[106:109], v[18:33]
	global_load_dwordx4 v[106:109], v79, s[2:3] offset:1024
	global_load_dwordx4 v[110:113], v79, s[4:5] offset:1024
	v_mfma_f32_32x32x16_bf16 v[34:49], v[118:121], v[122:125], v[34:49]
	v_mfma_f32_32x32x16_bf16 v[2:17], v[130:133], v[122:125], v[2:17]
	s_waitcnt lgkmcnt(2)
	v_mfma_f32_32x32x16_bf16 v[50:65], v[118:121], v[134:137], v[50:65]
	ds_read_b128 v[118:121], v73 offset:64
	ds_read_b128 v[122:125], v73 offset:4672
	ds_read_b128 v[126:129], v74 offset:18496
	ds_read_b128 v[142:145], v74 offset:23104
	s_waitcnt vmcnt(9)
	ds_write_b128 v75, v[82:85] offset:41472
	s_waitcnt vmcnt(8)
	ds_write_b128 v75, v[114:117] offset:59904
	v_mfma_f32_32x32x16_bf16 v[18:33], v[130:133], v[134:137], v[18:33]
	global_load_dwordx4 v[82:85], v78, s[2:3] offset:1024
	global_load_dwordx4 v[114:117], v78, s[4:5] offset:1024
	s_waitcnt lgkmcnt(3)
	v_mfma_f32_32x32x16_bf16 v[34:49], v[118:121], v[126:129], v[34:49]
	v_mfma_f32_32x32x16_bf16 v[2:17], v[122:125], v[126:129], v[2:17]
	s_waitcnt lgkmcnt(2)
	v_mfma_f32_32x32x16_bf16 v[50:65], v[118:121], v[142:145], v[50:65]
	ds_read_b128 v[118:121], v73 offset:96
	ds_read_b128 v[126:129], v73 offset:4704
	ds_read_b128 v[130:133], v74 offset:18528
	ds_read_b128 v[134:137], v74 offset:23136
	s_waitcnt vmcnt(9)
	ds_write_b128 v75, v[86:89] offset:46080
	s_waitcnt vmcnt(8)
	ds_write_b128 v75, v[98:101] offset:64512
	v_mfma_f32_32x32x16_bf16 v[18:33], v[122:125], v[142:145], v[18:33]
	global_load_dwordx4 v[86:89], v77, s[2:3] offset:1024
	global_load_dwordx4 v[98:101], v77, s[4:5] offset:1024
	s_waitcnt lgkmcnt(3)
	v_mfma_f32_32x32x16_bf16 v[34:49], v[118:121], v[130:133], v[34:49]
	s_waitcnt vmcnt(9)
	ds_write_b128 v75, v[90:93] offset:50688
	s_waitcnt vmcnt(8)
	ds_write_b128 v76, v[102:105] offset:13824
	v_mfma_f32_32x32x16_bf16 v[2:17], v[126:129], v[130:133], v[2:17]
	s_waitcnt lgkmcnt(4)
	v_mfma_f32_32x32x16_bf16 v[50:65], v[118:121], v[134:137], v[50:65]
	v_mfma_f32_32x32x16_bf16 v[18:33], v[126:129], v[134:137], v[18:33]
	s_waitcnt lgkmcnt(0)
	s_barrier
; #define GL1_(RA, RB, i) { RA[i] = *(const u32x4*)(ap + (aoff + (i) * astep)); if ((i) < NB) RB[(i) < NB ? (i) : 0] = *(const u32x4*)(bp + (boff + (i) * bstep)); }
; #define LS1_(RA, RB, ST, i) { char* sn_ = lds + (ST) * STAGE; *(u32x4*)(sn_ + wofs + (i) * 32 * LROW) = RA[i]; \
;                               if ((i) < NB) *(u32x4*)(sn_ + STAGE_OP + wofs + (i) * 32 * LROW) = RB[(i) < NB ? (i) : 0]; }
; template <int NJ> DI void gemm_mainloop_reg(const bf16_t* __restrict__ A, int lda, const bf16_t* __restrict__ Bt, int ldb, int K, f32x16 (&acc)[2][NJ], char* lds) {
;     ...
; #pragma unroll
;   for (int i = 0; i < 4; ++i) GL1_(ra0, rb0, i);
;   ap += 128; bp += 128;
; #pragma unroll
;   for (int i = 0; i < 4; ++i) GL1_(ra1, rb1, i);
;   ap += 128; bp += 128;
; #pragma unroll
;   for (int i = 0; i < 4; ++i) LS1_(ra0, rb0, 0, i);
;   __syncthreads();
;   const int nk = K >> 6;
;   for (int kt = 0; kt < nk; kt += 2) {
;     const bool l0 = (kt + 2 < nk), l1 = (kt + 3 < nk);
;     STEP_(0, l0, ra0, rb0, true, ra1, rb1);
;     __syncthreads();
;     STEP_(1, l1, ra1, rb1, l0, ra0, rb0);
;     __syncthreads();
;   }
	ds_read_b128 v[90:93], v73 offset:36864
	ds_read_b128 v[102:105], v74 offset:55296
	ds_read_b128 v[118:121], v73 offset:36896
	ds_read_b128 v[122:125], v74 offset:55328
	ds_read_b128 v[126:129], v73 offset:41472
	ds_read_b128 v[130:133], v73 offset:41504
	s_waitcnt lgkmcnt(4)
	v_mfma_f32_32x32x16_bf16 v[34:49], v[90:93], v[102:105], v[34:49]
	s_waitcnt lgkmcnt(1)
	v_mfma_f32_32x32x16_bf16 v[2:17], v[126:129], v[102:105], v[2:17]
	ds_read_b128 v[102:105], v74 offset:59904
	ds_read_b128 v[134:137], v74 offset:59936
	s_waitcnt lgkmcnt(1)
	v_mfma_f32_32x32x16_bf16 v[50:65], v[90:93], v[102:105], v[50:65]
	global_load_dwordx4 v[90:93], v80, s[2:3] offset:1152
	global_load_dwordx4 v[142:145], v80, s[4:5] offset:1152
	s_waitcnt vmcnt(9)
	ds_write_b128 v75, v[94:97]
	s_waitcnt vmcnt(8)
	ds_write_b128 v75, v[138:141] offset:18432
	v_mfma_f32_32x32x16_bf16 v[18:33], v[126:129], v[102:105], v[18:33]
	global_load_dwordx4 v[94:97], v79, s[2:3] offset:1152
	global_load_dwordx4 v[102:105], v79, s[4:5] offset:1152
	v_mfma_f32_32x32x16_bf16 v[34:49], v[118:121], v[122:125], v[34:49]
	v_mfma_f32_32x32x16_bf16 v[2:17], v[130:133], v[122:125], v[2:17]
	s_waitcnt lgkmcnt(2)
	v_mfma_f32_32x32x16_bf16 v[50:65], v[118:121], v[134:137], v[50:65]
	ds_read_b128 v[118:121], v73 offset:36928
	ds_read_b128 v[122:125], v73 offset:41536
	ds_read_b128 v[126:129], v74 offset:55360
	ds_read_b128 v[138:141], v74 offset:59968
	s_waitcnt vmcnt(9)
	ds_write_b128 v75, v[106:109] offset:4608
	s_waitcnt vmcnt(8)
	ds_write_b128 v75, v[110:113] offset:23040
	v_mfma_f32_32x32x16_bf16 v[18:33], v[130:133], v[134:137], v[18:33]
	global_load_dwordx4 v[106:109], v78, s[2:3] offset:1152
	global_load_dwordx4 v[110:113], v78, s[4:5] offset:1152
	s_waitcnt lgkmcnt(3)
	v_mfma_f32_32x32x16_bf16 v[34:49], v[118:121], v[126:129], v[34:49]
	v_mfma_f32_32x32x16_bf16 v[2:17], v[122:125], v[126:129], v[2:17]
	s_waitcnt lgkmcnt(2)
	v_mfma_f32_32x32x16_bf16 v[50:65], v[118:121], v[138:141], v[50:65]
	ds_read_b128 v[118:121], v73 offset:36960
	ds_read_b128 v[126:129], v73 offset:41568
	ds_read_b128 v[130:133], v74 offset:55392
	ds_read_b128 v[134:137], v74 offset:60000
	s_waitcnt vmcnt(9)
	ds_write_b128 v75, v[82:85] offset:9216
	s_waitcnt vmcnt(8)
	ds_write_b128 v75, v[114:117] offset:27648
	v_mfma_f32_32x32x16_bf16 v[18:33], v[122:125], v[138:141], v[18:33]
	global_load_dwordx4 v[82:85], v77, s[2:3] offset:1152
	global_load_dwordx4 v[114:117], v77, s[4:5] offset:1152
	s_waitcnt lgkmcnt(3)
	v_mfma_f32_32x32x16_bf16 v[34:49], v[118:121], v[130:133], v[34:49]
	s_waitcnt vmcnt(9)
	ds_write_b128 v75, v[86:89] offset:13824
	s_waitcnt vmcnt(8)
	ds_write_b128 v75, v[98:101] offset:32256
	v_mfma_f32_32x32x16_bf16 v[2:17], v[126:129], v[130:133], v[2:17]
	s_waitcnt lgkmcnt(4)
	v_mfma_f32_32x32x16_bf16 v[50:65], v[118:121], v[134:137], v[50:65]
	v_mfma_f32_32x32x16_bf16 v[18:33], v[126:129], v[134:137], v[18:33]
	s_waitcnt lgkmcnt(0)
	s_barrier
	ds_read_b128 v[86:89], v73
	ds_read_b128 v[98:101], v74 offset:18432
	ds_read_b128 v[118:121], v73 offset:32
	ds_read_b128 v[122:125], v74 offset:18464
	ds_read_b128 v[126:129], v73 offset:4608
	ds_read_b128 v[130:133], v73 offset:4640
	s_waitcnt lgkmcnt(4)
	v_mfma_f32_32x32x16_bf16 v[34:49], v[86:89], v[98:101], v[34:49]
	s_waitcnt lgkmcnt(1)
	v_mfma_f32_32x32x16_bf16 v[2:17], v[126:129], v[98:101], v[2:17]
	ds_read_b128 v[98:101], v74 offset:23040
	ds_read_b128 v[134:137], v74 offset:23072
	s_waitcnt lgkmcnt(1)
	v_mfma_f32_32x32x16_bf16 v[50:65], v[86:89], v[98:101], v[50:65]
	global_load_dwordx4 v[86:89], v80, s[2:3] offset:1280
	global_load_dwordx4 v[138:141], v80, s[4:5] offset:1280
	s_waitcnt vmcnt(9)
	ds_write_b128 v75, v[90:93] offset:36864
	s_waitcnt vmcnt(8)
	ds_write_b128 v75, v[142:145] offset:55296
	v_mfma_f32_32x32x16_bf16 v[18:33], v[126:129], v[98:101], v[18:33]
	global_load_dwordx4 v[90:93], v79, s[2:3] offset:1280
	global_load_dwordx4 v[98:101], v79, s[4:5] offset:1280
	v_mfma_f32_32x32x16_bf16 v[34:49], v[118:121], v[122:125], v[34:49]
	v_mfma_f32_32x32x16_bf16 v[2:17], v[130:133], v[122:125], v[2:17]
	s_waitcnt lgkmcnt(2)
	v_mfma_f32_32x32x16_bf16 v[50:65], v[118:121], v[134:137], v[50:65]
	ds_read_b128 v[118:121], v73 offset:64
	ds_read_b128 v[122:125], v73 offset:4672
	ds_read_b128 v[126:129], v74 offset:18496
	ds_read_b128 v[142:145], v74 offset:23104
	s_waitcnt vmcnt(9)
	ds_write_b128 v75, v[94:97] offset:41472
	s_waitcnt vmcnt(8)
	ds_write_b128 v75, v[102:105] offset:59904
	v_mfma_f32_32x32x16_bf16 v[18:33], v[130:133], v[134:137], v[18:33]
	global_load_dwordx4 v[94:97], v78, s[2:3] offset:1280
	global_load_dwordx4 v[102:105], v78, s[4:5] offset:1280
	s_waitcnt lgkmcnt(3)
	v_mfma_f32_32x32x16_bf16 v[34:49], v[118:121], v[126:129], v[34:49]
	v_mfma_f32_32x32x16_bf16 v[2:17], v[122:125], v[126:129], v[2:17]
	s_waitcnt lgkmcnt(2)
	v_mfma_f32_32x32x16_bf16 v[50:65], v[118:121], v[142:145], v[50:65]
	ds_read_b128 v[118:121], v73 offset:96
	ds_read_b128 v[126:129], v73 offset:4704
	ds_read_b128 v[130:133], v74 offset:18528
	ds_read_b128 v[134:137], v74 offset:23136
	s_waitcnt vmcnt(9)
	ds_write_b128 v75, v[106:109] offset:46080
	s_waitcnt vmcnt(8)
	ds_write_b128 v75, v[110:113] offset:64512
	v_mfma_f32_32x32x16_bf16 v[18:33], v[122:125], v[142:145], v[18:33]
	global_load_dwordx4 v[106:109], v77, s[2:3] offset:1280
	global_load_dwordx4 v[110:113], v77, s[4:5] offset:1280
	s_waitcnt lgkmcnt(3)
	v_mfma_f32_32x32x16_bf16 v[34:49], v[118:121], v[130:133], v[34:49]
	s_waitcnt vmcnt(9)
	ds_write_b128 v75, v[82:85] offset:50688
	s_waitcnt vmcnt(8)
	ds_write_b128 v76, v[114:117] offset:13824
	v_mfma_f32_32x32x16_bf16 v[2:17], v[126:129], v[130:133], v[2:17]
	s_waitcnt lgkmcnt(4)
	v_mfma_f32_32x32x16_bf16 v[50:65], v[118:121], v[134:137], v[50:65]
	v_mfma_f32_32x32x16_bf16 v[18:33], v[126:129], v[134:137], v[18:33]
	s_waitcnt lgkmcnt(0)
	s_barrier
; #define GL1_(RA, RB, i) { RA[i] = *(const u32x4*)(ap + (aoff + (i) * astep)); if ((i) < NB) RB[(i) < NB ? (i) : 0] = *(const u32x4*)(bp + (boff + (i) * bstep)); }
; #define LS1_(RA, RB, ST, i) { char* sn_ = lds + (ST) * STAGE; *(u32x4*)(sn_ + wofs + (i) * 32 * LROW) = RA[i]; \
;                               if ((i) < NB) *(u32x4*)(sn_ + STAGE_OP + wofs + (i) * 32 * LROW) = RB[(i) < NB ? (i) : 0]; }
; template <int NJ> DI void gemm_mainloop_reg(const bf16_t* __restrict__ A, int lda, const bf16_t* __restrict__ Bt, int ldb, int K, f32x16 (&acc)[2][NJ], char* lds) {
;     ...
; #pragma unroll
;   for (int i = 0; i < 4; ++i) GL1_(ra0, rb0, i);
;   ap += 128; bp += 128;
; #pragma unroll
;   for (int i = 0; i < 4; ++i) GL1_(ra1, rb1, i);
;   ap += 128; bp += 128;
; #pragma unroll
;   for (int i = 0; i < 4; ++i) LS1_(ra0, rb0, 0, i);
;   __syncthreads();
;   const int nk = K >> 6;
;   for (int kt = 0; kt < nk; kt += 2) {
;     const bool l0 = (kt + 2 < nk), l1 = (kt + 3 < nk);
;     STEP_(0, l0, ra0, rb0, true, ra1, rb1);
;     __syncthreads();
;     STEP_(1, l1, ra1, rb1, l0, ra0, rb0);
;     __syncthreads();
;   }
	ds_read_b128 v[82:85], v73 offset:36864
	ds_read_b128 v[114:117], v74 offset:55296
	ds_read_b128 v[118:121], v73 offset:36896
	ds_read_b128 v[122:125], v74 offset:55328
	ds_read_b128 v[126:129], v73 offset:41472
	ds_read_b128 v[130:133], v73 offset:41504
	s_waitcnt lgkmcnt(4)
	v_mfma_f32_32x32x16_bf16 v[34:49], v[82:85], v[114:117], v[34:49]
	s_waitcnt lgkmcnt(1)
	v_mfma_f32_32x32x16_bf16 v[2:17], v[126:129], v[114:117], v[2:17]
	ds_read_b128 v[114:117], v74 offset:59904
	ds_read_b128 v[134:137], v74 offset:59936
	s_waitcnt lgkmcnt(1)
	v_mfma_f32_32x32x16_bf16 v[50:65], v[82:85], v[114:117], v[50:65]
	global_load_dwordx4 v[82:85], v80, s[2:3] offset:1408
	global_load_dwordx4 v[142:145], v80, s[4:5] offset:1408
	s_waitcnt vmcnt(9)
	ds_write_b128 v75, v[86:89]
	s_waitcnt vmcnt(8)
	ds_write_b128 v75, v[138:141] offset:18432
	v_mfma_f32_32x32x16_bf16 v[18:33], v[126:129], v[114:117], v[18:33]
	global_load_dwordx4 v[86:89], v79, s[2:3] offset:1408
	global_load_dwordx4 v[114:117], v79, s[4:5] offset:1408
	v_mfma_f32_32x32x16_bf16 v[34:49], v[118:121], v[122:125], v[34:49]
	v_mfma_f32_32x32x16_bf16 v[2:17], v[130:133], v[122:125], v[2:17]
	s_waitcnt lgkmcnt(2)
	v_mfma_f32_32x32x16_bf16 v[50:65], v[118:121], v[134:137], v[50:65]
	ds_read_b128 v[118:121], v73 offset:36928
	ds_read_b128 v[122:125], v73 offset:41536
	ds_read_b128 v[126:129], v74 offset:55360
	ds_read_b128 v[138:141], v74 offset:59968
	s_waitcnt vmcnt(9)
	ds_write_b128 v75, v[90:93] offset:4608
	s_waitcnt vmcnt(8)
	ds_write_b128 v75, v[98:101] offset:23040
	v_mfma_f32_32x32x16_bf16 v[18:33], v[130:133], v[134:137], v[18:33]
	global_load_dwordx4 v[90:93], v78, s[2:3] offset:1408
	global_load_dwordx4 v[98:101], v78, s[4:5] offset:1408
	s_waitcnt lgkmcnt(3)
	v_mfma_f32_32x32x16_bf16 v[34:49], v[118:121], v[126:129], v[34:49]
	v_mfma_f32_32x32x16_bf16 v[2:17], v[122:125], v[126:129], v[2:17]
	s_waitcnt lgkmcnt(2)
	v_mfma_f32_32x32x16_bf16 v[50:65], v[118:121], v[138:141], v[50:65]
	ds_read_b128 v[118:121], v73 offset:36960
	ds_read_b128 v[126:129], v73 offset:41568
	ds_read_b128 v[130:133], v74 offset:55392
	ds_read_b128 v[134:137], v74 offset:60000
	s_waitcnt vmcnt(9)
	ds_write_b128 v75, v[94:97] offset:9216
	s_waitcnt vmcnt(8)
	ds_write_b128 v75, v[102:105] offset:27648
	v_mfma_f32_32x32x16_bf16 v[18:33], v[122:125], v[138:141], v[18:33]
	global_load_dwordx4 v[94:97], v77, s[2:3] offset:1408
	global_load_dwordx4 v[102:105], v77, s[4:5] offset:1408
	s_waitcnt lgkmcnt(3)
	v_mfma_f32_32x32x16_bf16 v[34:49], v[118:121], v[130:133], v[34:49]
	s_waitcnt vmcnt(9)
	ds_write_b128 v75, v[106:109] offset:13824
	s_waitcnt vmcnt(8)
	ds_write_b128 v75, v[110:113] offset:32256
	v_mfma_f32_32x32x16_bf16 v[2:17], v[126:129], v[130:133], v[2:17]
	s_waitcnt lgkmcnt(4)
	v_mfma_f32_32x32x16_bf16 v[50:65], v[118:121], v[134:137], v[50:65]
	v_mfma_f32_32x32x16_bf16 v[18:33], v[126:129], v[134:137], v[18:33]
	s_waitcnt lgkmcnt(0)
	s_barrier
	ds_read_b128 v[106:109], v73
	ds_read_b128 v[110:113], v74 offset:18432
	ds_read_b128 v[118:121], v73 offset:32
	ds_read_b128 v[122:125], v74 offset:18464
	ds_read_b128 v[126:129], v73 offset:4608
	ds_read_b128 v[130:133], v73 offset:4640
	s_waitcnt lgkmcnt(4)
	v_mfma_f32_32x32x16_bf16 v[34:49], v[106:109], v[110:113], v[34:49]
	s_waitcnt lgkmcnt(1)
	v_mfma_f32_32x32x16_bf16 v[2:17], v[126:129], v[110:113], v[2:17]
	ds_read_b128 v[110:113], v74 offset:23040
	ds_read_b128 v[134:137], v74 offset:23072
	s_waitcnt lgkmcnt(1)
	v_mfma_f32_32x32x16_bf16 v[50:65], v[106:109], v[110:113], v[50:65]
	global_load_dwordx4 v[106:109], v80, s[2:3] offset:1536
	global_load_dwordx4 v[138:141], v80, s[4:5] offset:1536
	s_waitcnt vmcnt(9)
	ds_write_b128 v75, v[82:85] offset:36864
	s_waitcnt vmcnt(8)
	ds_write_b128 v75, v[142:145] offset:55296
	v_mfma_f32_32x32x16_bf16 v[18:33], v[126:129], v[110:113], v[18:33]
	global_load_dwordx4 v[82:85], v79, s[2:3] offset:1536
	global_load_dwordx4 v[110:113], v79, s[4:5] offset:1536
	v_mfma_f32_32x32x16_bf16 v[34:49], v[118:121], v[122:125], v[34:49]
	v_mfma_f32_32x32x16_bf16 v[2:17], v[130:133], v[122:125], v[2:17]
	s_waitcnt lgkmcnt(2)
	v_mfma_f32_32x32x16_bf16 v[50:65], v[118:121], v[134:137], v[50:65]
	ds_read_b128 v[118:121], v73 offset:64
	ds_read_b128 v[122:125], v73 offset:4672
	ds_read_b128 v[126:129], v74 offset:18496
	ds_read_b128 v[142:145], v74 offset:23104
	s_waitcnt vmcnt(9)
	ds_write_b128 v75, v[86:89] offset:41472
	s_waitcnt vmcnt(8)
	ds_write_b128 v75, v[114:117] offset:59904
	v_mfma_f32_32x32x16_bf16 v[18:33], v[130:133], v[134:137], v[18:33]
	global_load_dwordx4 v[86:89], v78, s[2:3] offset:1536
	global_load_dwordx4 v[114:117], v78, s[4:5] offset:1536
	s_waitcnt lgkmcnt(3)
	v_mfma_f32_32x32x16_bf16 v[34:49], v[118:121], v[126:129], v[34:49]
	v_mfma_f32_32x32x16_bf16 v[2:17], v[122:125], v[126:129], v[2:17]
	s_waitcnt lgkmcnt(2)
	v_mfma_f32_32x32x16_bf16 v[50:65], v[118:121], v[142:145], v[50:65]
	ds_read_b128 v[118:121], v73 offset:96
	ds_read_b128 v[126:129], v73 offset:4704
	ds_read_b128 v[130:133], v74 offset:18528
	ds_read_b128 v[134:137], v74 offset:23136
	s_waitcnt vmcnt(9)
	ds_write_b128 v75, v[90:93] offset:46080
	s_waitcnt vmcnt(8)
	ds_write_b128 v75, v[98:101] offset:64512
	v_mfma_f32_32x32x16_bf16 v[18:33], v[122:125], v[142:145], v[18:33]
	global_load_dwordx4 v[90:93], v77, s[2:3] offset:1536
	global_load_dwordx4 v[98:101], v77, s[4:5] offset:1536
	s_waitcnt lgkmcnt(3)
	v_mfma_f32_32x32x16_bf16 v[34:49], v[118:121], v[130:133], v[34:49]
	s_waitcnt vmcnt(9)
	ds_write_b128 v75, v[94:97] offset:50688
	s_waitcnt vmcnt(8)
	ds_write_b128 v76, v[102:105] offset:13824
	v_mfma_f32_32x32x16_bf16 v[2:17], v[126:129], v[130:133], v[2:17]
	s_waitcnt lgkmcnt(4)
	v_mfma_f32_32x32x16_bf16 v[50:65], v[118:121], v[134:137], v[50:65]
	v_mfma_f32_32x32x16_bf16 v[18:33], v[126:129], v[134:137], v[18:33]
	s_waitcnt lgkmcnt(0)
	s_barrier
; #define GL1_(RA, RB, i) { RA[i] = *(const u32x4*)(ap + (aoff + (i) * astep)); if ((i) < NB) RB[(i) < NB ? (i) : 0] = *(const u32x4*)(bp + (boff + (i) * bstep)); }
; #define LS1_(RA, RB, ST, i) { char* sn_ = lds + (ST) * STAGE; *(u32x4*)(sn_ + wofs + (i) * 32 * LROW) = RA[i]; \
;                               if ((i) < NB) *(u32x4*)(sn_ + STAGE_OP + wofs + (i) * 32 * LROW) = RB[(i) < NB ? (i) : 0]; }
; template <int NJ> DI void gemm_mainloop_reg(const bf16_t* __restrict__ A, int lda, const bf16_t* __restrict__ Bt, int ldb, int K, f32x16 (&acc)[2][NJ], char* lds) {
;     ...
; #pragma unroll
;   for (int i = 0; i < 4; ++i) GL1_(ra0, rb0, i);
;   ap += 128; bp += 128;
; #pragma unroll
;   for (int i = 0; i < 4; ++i) GL1_(ra1, rb1, i);
;   ap += 128; bp += 128;
; #pragma unroll
;   for (int i = 0; i < 4; ++i) LS1_(ra0, rb0, 0, i);
;   __syncthreads();
;   const int nk = K >> 6;
;   for (int kt = 0; kt < nk; kt += 2) {
;     const bool l0 = (kt + 2 < nk), l1 = (kt + 3 < nk);
;     STEP_(0, l0, ra0, rb0, true, ra1, rb1);
;     __syncthreads();
;     STEP_(1, l1, ra1, rb1, l0, ra0, rb0);
;     __syncthreads();
;   }
	ds_read_b128 v[94:97], v73 offset:36864
	ds_read_b128 v[102:105], v74 offset:55296
	ds_read_b128 v[118:121], v73 offset:36896
	ds_read_b128 v[122:125], v74 offset:55328
	ds_read_b128 v[126:129], v73 offset:41472
	ds_read_b128 v[130:133], v73 offset:41504
	s_waitcnt lgkmcnt(4)
	v_mfma_f32_32x32x16_bf16 v[34:49], v[94:97], v[102:105], v[34:49]
	s_waitcnt lgkmcnt(1)
	v_mfma_f32_32x32x16_bf16 v[2:17], v[126:129], v[102:105], v[2:17]
	ds_read_b128 v[102:105], v74 offset:59904
	ds_read_b128 v[134:137], v74 offset:59936
	s_waitcnt lgkmcnt(1)
	v_mfma_f32_32x32x16_bf16 v[50:65], v[94:97], v[102:105], v[50:65]
	global_load_dwordx4 v[94:97], v80, s[2:3] offset:1664
	global_load_dwordx4 v[142:145], v80, s[4:5] offset:1664
	s_waitcnt vmcnt(9)
	ds_write_b128 v75, v[106:109]
	s_waitcnt vmcnt(8)
	ds_write_b128 v75, v[138:141] offset:18432
	v_mfma_f32_32x32x16_bf16 v[18:33], v[126:129], v[102:105], v[18:33]
	global_load_dwordx4 v[102:105], v79, s[2:3] offset:1664
	global_load_dwordx4 v[106:109], v79, s[4:5] offset:1664
	v_mfma_f32_32x32x16_bf16 v[34:49], v[118:121], v[122:125], v[34:49]
	v_mfma_f32_32x32x16_bf16 v[2:17], v[130:133], v[122:125], v[2:17]
	s_waitcnt lgkmcnt(2)
	v_mfma_f32_32x32x16_bf16 v[50:65], v[118:121], v[134:137], v[50:65]
	ds_read_b128 v[118:121], v73 offset:36928
	ds_read_b128 v[122:125], v73 offset:41536
	ds_read_b128 v[126:129], v74 offset:55360
	ds_read_b128 v[138:141], v74 offset:59968
	s_waitcnt vmcnt(9)
	ds_write_b128 v75, v[82:85] offset:4608
	s_waitcnt vmcnt(8)
	ds_write_b128 v75, v[110:113] offset:23040
	v_mfma_f32_32x32x16_bf16 v[18:33], v[130:133], v[134:137], v[18:33]
	global_load_dwordx4 v[82:85], v78, s[2:3] offset:1664
	global_load_dwordx4 v[110:113], v78, s[4:5] offset:1664
	s_waitcnt lgkmcnt(3)
	v_mfma_f32_32x32x16_bf16 v[34:49], v[118:121], v[126:129], v[34:49]
	v_mfma_f32_32x32x16_bf16 v[2:17], v[122:125], v[126:129], v[2:17]
	s_waitcnt lgkmcnt(2)
	v_mfma_f32_32x32x16_bf16 v[50:65], v[118:121], v[138:141], v[50:65]
	ds_read_b128 v[118:121], v73 offset:36960
	ds_read_b128 v[126:129], v73 offset:41568
	ds_read_b128 v[130:133], v74 offset:55392
	ds_read_b128 v[134:137], v74 offset:60000
	s_waitcnt vmcnt(9)
	ds_write_b128 v75, v[86:89] offset:9216
	s_waitcnt vmcnt(8)
	ds_write_b128 v75, v[114:117] offset:27648
	v_mfma_f32_32x32x16_bf16 v[18:33], v[122:125], v[138:141], v[18:33]
	global_load_dwordx4 v[86:89], v77, s[2:3] offset:1664
	global_load_dwordx4 v[114:117], v77, s[4:5] offset:1664
	s_waitcnt lgkmcnt(3)
	v_mfma_f32_32x32x16_bf16 v[34:49], v[118:121], v[130:133], v[34:49]
	s_waitcnt vmcnt(9)
	ds_write_b128 v75, v[90:93] offset:13824
	s_waitcnt vmcnt(8)
	ds_write_b128 v75, v[98:101] offset:32256
	v_mfma_f32_32x32x16_bf16 v[2:17], v[126:129], v[130:133], v[2:17]
	s_waitcnt lgkmcnt(4)
	v_mfma_f32_32x32x16_bf16 v[50:65], v[118:121], v[134:137], v[50:65]
	v_mfma_f32_32x32x16_bf16 v[18:33], v[126:129], v[134:137], v[18:33]
	s_waitcnt lgkmcnt(0)
	s_barrier
	ds_read_b128 v[90:93], v73
	ds_read_b128 v[98:101], v74 offset:18432
	ds_read_b128 v[118:121], v73 offset:32
	ds_read_b128 v[122:125], v74 offset:18464
	ds_read_b128 v[126:129], v73 offset:4608
	ds_read_b128 v[130:133], v73 offset:4640
	s_waitcnt lgkmcnt(4)
	v_mfma_f32_32x32x16_bf16 v[34:49], v[90:93], v[98:101], v[34:49]
	s_waitcnt lgkmcnt(1)
	v_mfma_f32_32x32x16_bf16 v[2:17], v[126:129], v[98:101], v[2:17]
	ds_read_b128 v[98:101], v74 offset:23040
	ds_read_b128 v[134:137], v74 offset:23072
	s_waitcnt lgkmcnt(1)
	v_mfma_f32_32x32x16_bf16 v[50:65], v[90:93], v[98:101], v[50:65]
	global_load_dwordx4 v[90:93], v80, s[2:3] offset:1792
	global_load_dwordx4 v[138:141], v80, s[4:5] offset:1792
	s_waitcnt vmcnt(9)
	ds_write_b128 v75, v[94:97] offset:36864
	s_waitcnt vmcnt(8)
	ds_write_b128 v75, v[142:145] offset:55296
	v_mfma_f32_32x32x16_bf16 v[18:33], v[126:129], v[98:101], v[18:33]
	global_load_dwordx4 v[94:97], v79, s[2:3] offset:1792
	global_load_dwordx4 v[98:101], v79, s[4:5] offset:1792
	v_mfma_f32_32x32x16_bf16 v[34:49], v[118:121], v[122:125], v[34:49]
	v_mfma_f32_32x32x16_bf16 v[2:17], v[130:133], v[122:125], v[2:17]
	s_waitcnt lgkmcnt(2)
	v_mfma_f32_32x32x16_bf16 v[50:65], v[118:121], v[134:137], v[50:65]
	ds_read_b128 v[118:121], v73 offset:64
	ds_read_b128 v[122:125], v73 offset:4672
	ds_read_b128 v[126:129], v74 offset:18496
	ds_read_b128 v[142:145], v74 offset:23104
	s_waitcnt vmcnt(9)
	ds_write_b128 v75, v[102:105] offset:41472
	s_waitcnt vmcnt(8)
	ds_write_b128 v75, v[106:109] offset:59904
	v_mfma_f32_32x32x16_bf16 v[18:33], v[130:133], v[134:137], v[18:33]
	global_load_dwordx4 v[102:105], v78, s[2:3] offset:1792
	global_load_dwordx4 v[106:109], v78, s[4:5] offset:1792
	s_waitcnt lgkmcnt(3)
	v_mfma_f32_32x32x16_bf16 v[34:49], v[118:121], v[126:129], v[34:49]
	v_mfma_f32_32x32x16_bf16 v[2:17], v[122:125], v[126:129], v[2:17]
	s_waitcnt lgkmcnt(2)
	v_mfma_f32_32x32x16_bf16 v[50:65], v[118:121], v[142:145], v[50:65]
	ds_read_b128 v[118:121], v73 offset:96
	ds_read_b128 v[126:129], v73 offset:4704
	ds_read_b128 v[130:133], v74 offset:18528
	ds_read_b128 v[134:137], v74 offset:23136
	s_waitcnt vmcnt(9)
	ds_write_b128 v75, v[82:85] offset:46080
	s_waitcnt vmcnt(8)
	ds_write_b128 v75, v[110:113] offset:64512
	v_mfma_f32_32x32x16_bf16 v[18:33], v[122:125], v[142:145], v[18:33]
	global_load_dwordx4 v[82:85], v77, s[2:3] offset:1792
	global_load_dwordx4 v[110:113], v77, s[4:5] offset:1792
	s_waitcnt lgkmcnt(3)
	v_mfma_f32_32x32x16_bf16 v[34:49], v[118:121], v[130:133], v[34:49]
	s_waitcnt vmcnt(9)
	ds_write_b128 v75, v[86:89] offset:50688
	s_waitcnt vmcnt(8)
	ds_write_b128 v76, v[114:117] offset:13824
	v_mfma_f32_32x32x16_bf16 v[2:17], v[126:129], v[130:133], v[2:17]
	s_waitcnt lgkmcnt(4)
	v_mfma_f32_32x32x16_bf16 v[50:65], v[118:121], v[134:137], v[50:65]
	v_mfma_f32_32x32x16_bf16 v[18:33], v[126:129], v[134:137], v[18:33]
	s_waitcnt lgkmcnt(0)
	s_barrier
; #define GL1_(RA, RB, i) { RA[i] = *(const u32x4*)(ap + (aoff + (i) * astep)); if ((i) < NB) RB[(i) < NB ? (i) : 0] = *(const u32x4*)(bp + (boff + (i) * bstep)); }
; #define LS1_(RA, RB, ST, i) { char* sn_ = lds + (ST) * STAGE; *(u32x4*)(sn_ + wofs + (i) * 32 * LROW) = RA[i]; \
;                               if ((i) < NB) *(u32x4*)(sn_ + STAGE_OP + wofs + (i) * 32 * LROW) = RB[(i) < NB ? (i) : 0]; }
; template <int NJ> DI void gemm_mainloop_reg(const bf16_t* __restrict__ A, int lda, const bf16_t* __restrict__ Bt, int ldb, int K, f32x16 (&acc)[2][NJ], char* lds) {
;     ...
; #pragma unroll
;   for (int i = 0; i < 4; ++i) GL1_(ra0, rb0, i);
;   ap += 128; bp += 128;
; #pragma unroll
;   for (int i = 0; i < 4; ++i) GL1_(ra1, rb1, i);
;   ap += 128; bp += 128;
; #pragma unroll
;   for (int i = 0; i < 4; ++i) LS1_(ra0, rb0, 0, i);
;   __syncthreads();
;   const int nk = K >> 6;
;   for (int kt = 0; kt < nk; kt += 2) {
;     const bool l0 = (kt + 2 < nk), l1 = (kt + 3 < nk);
;     STEP_(0, l0, ra0, rb0, true, ra1, rb1);
;     __syncthreads();
;     STEP_(1, l1, ra1, rb1, l0, ra0, rb0);
;     __syncthreads();
;   }
	ds_read_b128 v[86:89], v73 offset:36864
	ds_read_b128 v[114:117], v74 offset:55296
	ds_read_b128 v[118:121], v73 offset:41472
	s_waitcnt lgkmcnt(1)
	v_mfma_f32_32x32x16_bf16 v[34:49], v[86:89], v[114:117], v[34:49]
	s_waitcnt lgkmcnt(0)
	v_mfma_f32_32x32x16_bf16 v[2:17], v[118:121], v[114:117], v[2:17]
	ds_read_b128 v[114:117], v74 offset:59904
	s_waitcnt lgkmcnt(0)
	v_mfma_f32_32x32x16_bf16 v[50:65], v[86:89], v[114:117], v[50:65]
	global_load_dwordx4 v[86:89], v80, s[2:3] offset:1920
	global_load_dwordx4 v[122:125], v80, s[4:5] offset:1920
	ds_read_b128 v[126:129], v73 offset:36896
	ds_read_b128 v[130:133], v74 offset:55328
	ds_read_b128 v[134:137], v73 offset:41504
	ds_read_b128 v[142:145], v74 offset:59936
	s_waitcnt vmcnt(9)
	ds_write_b128 v75, v[90:93]
	s_waitcnt vmcnt(8)
	ds_write_b128 v75, v[138:141] offset:18432
	v_mfma_f32_32x32x16_bf16 v[18:33], v[118:121], v[114:117], v[18:33]
	global_load_dwordx4 v[90:93], v79, s[2:3] offset:1920
	global_load_dwordx4 v[114:117], v79, s[4:5] offset:1920
	s_waitcnt lgkmcnt(4)
	v_mfma_f32_32x32x16_bf16 v[34:49], v[126:129], v[130:133], v[34:49]
	s_waitcnt lgkmcnt(3)
	v_mfma_f32_32x32x16_bf16 v[2:17], v[134:137], v[130:133], v[2:17]
	s_waitcnt lgkmcnt(2)
	v_mfma_f32_32x32x16_bf16 v[50:65], v[126:129], v[142:145], v[50:65]
	ds_read_b128 v[118:121], v73 offset:36928
	ds_read_b128 v[126:129], v73 offset:41536
	ds_read_b128 v[130:133], v74 offset:55360
	ds_read_b128 v[138:141], v74 offset:59968
	s_waitcnt vmcnt(9)
	ds_write_b128 v75, v[94:97] offset:4608
	s_waitcnt vmcnt(8)
	ds_write_b128 v75, v[98:101] offset:23040
	v_mfma_f32_32x32x16_bf16 v[18:33], v[134:137], v[142:145], v[18:33]
	global_load_dwordx4 v[94:97], v78, s[2:3] offset:1920
	s_nop 0
	global_load_dwordx4 v[78:81], v78, s[4:5] offset:1920
	s_waitcnt lgkmcnt(3)
	v_mfma_f32_32x32x16_bf16 v[34:49], v[118:121], v[130:133], v[34:49]
	v_mfma_f32_32x32x16_bf16 v[2:17], v[126:129], v[130:133], v[2:17]
	s_waitcnt lgkmcnt(2)
	v_mfma_f32_32x32x16_bf16 v[50:65], v[118:121], v[138:141], v[50:65]
	ds_read_b128 v[98:101], v73 offset:36960
	ds_read_b128 v[118:121], v73 offset:41568
	ds_read_b128 v[130:133], v74 offset:55392
	ds_read_b128 v[134:137], v74 offset:60000
	s_waitcnt vmcnt(9)
	ds_write_b128 v75, v[102:105] offset:9216
	s_waitcnt vmcnt(8)
	ds_write_b128 v75, v[106:109] offset:27648
	v_mfma_f32_32x32x16_bf16 v[18:33], v[126:129], v[138:141], v[18:33]
	s_waitcnt lgkmcnt(3)
	v_mfma_f32_32x32x16_bf16 v[34:49], v[98:101], v[130:133], v[34:49]
	s_waitcnt lgkmcnt(2)
	v_mfma_f32_32x32x16_bf16 v[50:65], v[98:101], v[134:137], v[50:65]
	global_load_dwordx4 v[98:101], v77, s[2:3] offset:1920
	global_load_dwordx4 v[102:105], v77, s[4:5] offset:1920
	s_waitcnt vmcnt(9)
	ds_write_b128 v75, v[82:85] offset:13824
	s_waitcnt vmcnt(8)
	ds_write_b128 v75, v[110:113] offset:32256
	v_mfma_f32_32x32x16_bf16 v[2:17], v[118:121], v[130:133], v[2:17]
	v_mfma_f32_32x32x16_bf16 v[18:33], v[118:121], v[134:137], v[18:33]
	s_waitcnt lgkmcnt(0)
	s_barrier
	ds_read_b128 v[82:85], v73
	ds_read_b128 v[106:109], v74 offset:18432
	ds_read_b128 v[110:113], v73 offset:4608
	s_waitcnt lgkmcnt(1)
	v_mfma_f32_32x32x16_bf16 v[34:49], v[82:85], v[106:109], v[34:49]
	s_waitcnt lgkmcnt(0)
	v_mfma_f32_32x32x16_bf16 v[2:17], v[110:113], v[106:109], v[2:17]
	ds_read_b128 v[106:109], v74 offset:23040
	s_waitcnt lgkmcnt(0)
	v_mfma_f32_32x32x16_bf16 v[50:65], v[82:85], v[106:109], v[50:65]
	ds_read_b128 v[82:85], v73 offset:32
	ds_read_b128 v[118:121], v74 offset:18464
	ds_read_b128 v[126:129], v73 offset:4640
	ds_read_b128 v[130:133], v74 offset:23072
	s_waitcnt vmcnt(7)
	ds_write_b128 v75, v[86:89] offset:36864
	s_waitcnt vmcnt(6)
	ds_write_b128 v75, v[122:125] offset:55296
	v_mfma_f32_32x32x16_bf16 v[18:33], v[110:113], v[106:109], v[18:33]
	s_waitcnt lgkmcnt(4)
	v_mfma_f32_32x32x16_bf16 v[34:49], v[82:85], v[118:121], v[34:49]
	s_waitcnt lgkmcnt(2)
	v_mfma_f32_32x32x16_bf16 v[50:65], v[82:85], v[130:133], v[50:65]
	ds_read_b128 v[82:85], v73 offset:64
	ds_read_b128 v[86:89], v73 offset:4672
	ds_read_b128 v[106:109], v74 offset:18496
	ds_read_b128 v[110:113], v74 offset:23104
	s_waitcnt vmcnt(5)
	ds_write_b128 v75, v[90:93] offset:41472
	s_waitcnt vmcnt(4)
	ds_write_b128 v75, v[114:117] offset:59904
	v_mfma_f32_32x32x16_bf16 v[2:17], v[126:129], v[118:121], v[2:17]
	v_mfma_f32_32x32x16_bf16 v[18:33], v[126:129], v[130:133], v[18:33]
	s_waitcnt lgkmcnt(3)
	v_mfma_f32_32x32x16_bf16 v[34:49], v[82:85], v[106:109], v[34:49]
	v_mfma_f32_32x32x16_bf16 v[2:17], v[86:89], v[106:109], v[2:17]
	s_waitcnt lgkmcnt(2)
	v_mfma_f32_32x32x16_bf16 v[50:65], v[82:85], v[110:113], v[50:65]
	ds_read_b128 v[82:85], v73 offset:96
	ds_read_b128 v[90:93], v73 offset:4704
	ds_read_b128 v[106:109], v74 offset:18528
	ds_read_b128 v[114:117], v74 offset:23136
	s_waitcnt vmcnt(3)
	ds_write_b128 v75, v[94:97] offset:46080
	s_waitcnt vmcnt(2)
	ds_write_b128 v75, v[78:81] offset:64512
	v_mfma_f32_32x32x16_bf16 v[18:33], v[86:89], v[110:113], v[18:33]
	s_waitcnt lgkmcnt(3)
	v_mfma_f32_32x32x16_bf16 v[34:49], v[82:85], v[106:109], v[34:49]
	s_waitcnt vmcnt(1)
	ds_write_b128 v75, v[98:101] offset:50688
	s_waitcnt vmcnt(0)
	ds_write_b128 v76, v[102:105] offset:13824
	v_mfma_f32_32x32x16_bf16 v[2:17], v[90:93], v[106:109], v[2:17]
	s_waitcnt lgkmcnt(4)
	v_mfma_f32_32x32x16_bf16 v[50:65], v[82:85], v[114:117], v[50:65]
	v_mfma_f32_32x32x16_bf16 v[18:33], v[90:93], v[114:117], v[18:33]
	s_waitcnt lgkmcnt(0)
	s_barrier
; DI int tid_() { int t = threadIdx.x; asm volatile("" : "+v"(t)); return t; }
; #define GL1_(RA, RB, i) { RA[i] = *(const u32x4*)(ap + (aoff + (i) * astep)); if ((i) < NB) RB[(i) < NB ? (i) : 0] = *(const u32x4*)(bp + (boff + (i) * bstep)); }
; #define LS1_(RA, RB, ST, i) { char* sn_ = lds + (ST) * STAGE; *(u32x4*)(sn_ + wofs + (i) * 32 * LROW) = RA[i]; \
;                               if ((i) < NB) *(u32x4*)(sn_ + STAGE_OP + wofs + (i) * 32 * LROW) = RB[(i) < NB ? (i) : 0]; }
; template <int NJ> DI void gemm_mainloop_reg(const bf16_t* __restrict__ A, int lda, const bf16_t* __restrict__ Bt, int ldb, int K, f32x16 (&acc)[2][NJ], char* lds) {
;     ...
; #pragma unroll
;   for (int i = 0; i < 4; ++i) GL1_(ra0, rb0, i);
;   ap += 128; bp += 128;
; #pragma unroll
;   for (int i = 0; i < 4; ++i) GL1_(ra1, rb1, i);
;   ap += 128; bp += 128;
; #pragma unroll
;   for (int i = 0; i < 4; ++i) LS1_(ra0, rb0, 0, i);
;   __syncthreads();
;   const int nk = K >> 6;
;   for (int kt = 0; kt < nk; kt += 2) {
;     const bool l0 = (kt + 2 < nk), l1 = (kt + 3 < nk);
;     STEP_(0, l0, ra0, rb0, true, ra1, rb1);
;     __syncthreads();
;     STEP_(1, l1, ra1, rb1, l0, ra0, rb0);
;     __syncthreads();
;   }
; template <int NJ> DI void acc_to_lds(const f32x16 (&acc)[2][NJ], float* cl) {
;   const int tid = tid_(), lane = tid & 63, w = tid >> 6, wm = w >> 1, wn = w & 1, h = lane >> 5, c = lane & 31;
; #pragma unroll
;   for (int i = 0; i < 2; ++i)
; #pragma unroll
;     for (int j = 0; j < NJ; ++j)
; #pragma unroll
;       for (int r = 0; r < 16; ++r) {
;         const int row = wm * 64 + i * 32 + (r & 3) + 8 * (r >> 2) + 4 * h;
;         cl[row * CLD + wn * 32 * NJ + j * 32 + c] = acc[i][j][r];
;       }
; }
	ds_read_b128 v[76:79], v73 offset:36864
	ds_read_b128 v[80:83], v74 offset:55296
	ds_read_b128 v[84:87], v73 offset:41472
	s_waitcnt lgkmcnt(1)
	v_mfma_f32_32x32x16_bf16 v[34:49], v[76:79], v[80:83], v[34:49]
	s_waitcnt lgkmcnt(0)
	v_mfma_f32_32x32x16_bf16 v[2:17], v[84:87], v[80:83], v[2:17]
	ds_read_b128 v[80:83], v74 offset:59904
	s_waitcnt lgkmcnt(0)
	v_mfma_f32_32x32x16_bf16 v[50:65], v[76:79], v[80:83], v[50:65]
	ds_read_b128 v[76:79], v73 offset:36896
	ds_read_b128 v[88:91], v74 offset:55328
	ds_read_b128 v[92:95], v73 offset:41504
	ds_read_b128 v[96:99], v74 offset:59936
	v_mfma_f32_32x32x16_bf16 v[18:33], v[84:87], v[80:83], v[18:33]
	s_waitcnt lgkmcnt(2)
	v_mfma_f32_32x32x16_bf16 v[34:49], v[76:79], v[88:91], v[34:49]
	s_waitcnt lgkmcnt(1)
	v_mfma_f32_32x32x16_bf16 v[2:17], v[92:95], v[88:91], v[2:17]
	s_waitcnt lgkmcnt(0)
	v_mfma_f32_32x32x16_bf16 v[50:65], v[76:79], v[96:99], v[50:65]
	ds_read_b128 v[76:79], v73 offset:36928
	ds_read_b128 v[80:83], v73 offset:41536
	ds_read_b128 v[84:87], v74 offset:55360
	ds_read_b128 v[88:91], v74 offset:59968
	v_mfma_f32_32x32x16_bf16 v[18:33], v[92:95], v[96:99], v[18:33]
	s_waitcnt lgkmcnt(1)
	v_mfma_f32_32x32x16_bf16 v[34:49], v[76:79], v[84:87], v[34:49]
	v_mfma_f32_32x32x16_bf16 v[2:17], v[80:83], v[84:87], v[2:17]
	s_waitcnt lgkmcnt(0)
	v_mfma_f32_32x32x16_bf16 v[50:65], v[76:79], v[88:91], v[50:65]
	ds_read_b128 v[76:79], v73 offset:36960
	ds_read_b128 v[84:87], v73 offset:41568
	ds_read_b128 v[92:95], v74 offset:55392
	ds_read_b128 v[96:99], v74 offset:60000
	v_mfma_f32_32x32x16_bf16 v[18:33], v[80:83], v[88:91], v[18:33]
	s_waitcnt lgkmcnt(1)
	v_mfma_f32_32x32x16_bf16 v[34:49], v[76:79], v[92:95], v[34:49]
	v_mfma_f32_32x32x16_bf16 v[2:17], v[84:87], v[92:95], v[2:17]
	s_waitcnt lgkmcnt(0)
	v_mfma_f32_32x32x16_bf16 v[50:65], v[76:79], v[96:99], v[50:65]
	v_mfma_f32_32x32x16_bf16 v[18:33], v[84:87], v[96:99], v[18:33]
	s_setprio 0
	v_mov_b32_e32 v73, v199
	s_barrier
	s_nop 0
	v_lshrrev_b32_e32 v75, 3, v73
	v_lshrrev_b32_e32 v74, 1, v73
	v_and_b32_e32 v75, 4, v75
	v_and_b32_e32 v73, 0x5f, v73
	v_and_or_b32 v74, v74, s17, v75
	v_mul_lo_u32 v74, v74, s15
	v_lshlrev_b32_e32 v73, 2, v73
	v_add3_u32 v73, 0, v74, v73
	ds_write2_b32 v73, v34, v50 offset1:32
	ds_write2_b32 v73, v35, v51 offset0:132 offset1:164
	v_add_u32_e32 v34, 0x400, v73
	ds_write2_b32 v34, v36, v52 offset0:8 offset1:40
	ds_write2_b32 v34, v37, v53 offset0:140 offset1:172
	v_add_u32_e32 v34, 0x1000, v73
	ds_write2_b32 v34, v38, v54 offset0:32 offset1:64
	ds_write2_b32 v34, v39, v55 offset0:164 offset1:196
	v_add_u32_e32 v34, 0x1400, v73
	ds_write2_b32 v34, v40, v56 offset0:40 offset1:72
	ds_write2_b32 v34, v41, v57 offset0:172 offset1:204
	v_add_u32_e32 v34, 0x2000, v73
	ds_write2_b32 v34, v42, v58 offset0:64 offset1:96
	ds_write2_b32 v34, v43, v59 offset0:196 offset1:228
	v_add_u32_e32 v34, 0x2400, v73
	ds_write2_b32 v34, v44, v60 offset0:72 offset1:104
	ds_write2_b32 v34, v45, v61 offset0:204 offset1:236
	v_add_u32_e32 v34, 0x3000, v73
	ds_write2_b32 v34, v46, v62 offset0:96 offset1:128
	v_add_u32_e32 v34, 0x3200, v73
	ds_write2_b32 v34, v47, v63 offset0:100 offset1:132
	v_add_u32_e32 v34, 0x3400, v73
	ds_write2_b32 v34, v48, v64 offset0:104 offset1:136
	v_add_u32_e32 v34, 0x3600, v73
	ds_write2_b32 v34, v49, v65 offset0:108 offset1:140
	v_add_u32_e32 v34, 0x4000, v73
	ds_write2_b32 v34, v2, v18 offset0:128 offset1:160
	v_add_u32_e32 v2, 0x4400, v73
	ds_write2_b32 v2, v3, v19 offset0:4 offset1:36
	ds_write2_b32 v2, v4, v20 offset0:136 offset1:168
	v_add_u32_e32 v2, 0x4800, v73
	ds_write2_b32 v2, v5, v21 offset0:12 offset1:44
	v_add_u32_e32 v2, 0x5000, v73
	ds_write2_b32 v2, v6, v22 offset0:160 offset1:192
	v_add_u32_e32 v2, 0x5400, v73
	ds_write2_b32 v2, v7, v23 offset0:36 offset1:68
	ds_write2_b32 v2, v8, v24 offset0:168 offset1:200
	v_add_u32_e32 v2, 0x5800, v73
	ds_write2_b32 v2, v9, v25 offset0:44 offset1:76
	v_add_u32_e32 v2, 0x6000, v73
	ds_write2_b32 v2, v10, v26 offset0:192 offset1:224
	v_add_u32_e32 v2, 0x6400, v73
	ds_write2_b32 v2, v11, v27 offset0:68 offset1:100
	ds_write2_b32 v2, v12, v28 offset0:200 offset1:232
	v_add_u32_e32 v2, 0x6800, v73
	ds_write2_b32 v2, v13, v29 offset0:76 offset1:108
	v_add_u32_e32 v2, 0x7200, v73
	ds_write2_b32 v2, v14, v30 offset0:96 offset1:128
	v_add_u32_e32 v2, 0x7400, v73
	ds_write2_b32 v2, v15, v31 offset0:100 offset1:132
	v_add_u32_e32 v2, 0x7600, v73
	ds_write2_b32 v2, v16, v32 offset0:104 offset1:136
	v_add_u32_e32 v2, 0x7800, v73
	ds_write2_b32 v2, v17, v33 offset0:108 offset1:140
	s_and_saveexec_b64 s[2:3], s[36:37]
	s_cbranch_execz .LBB0_369
	v_lshl_add_u32 v2, s34, 7, v68
	v_readlane_b32 s4, v248, 14
	v_ashrrev_i32_e32 v3, 31, v2
	v_readlane_b32 s5, v248, 15
	s_nop 1
	v_lshl_add_u64 v[2:3], v[2:3], 2, s[4:5]
	global_load_dword v2, v[2:3], off
	s_mov_b32 s4, 0x800000
	s_waitcnt vmcnt(0)
	v_fmamk_f32 v2, v2, 0x3a800000, v198
	v_mul_f32_e32 v3, 0x4b800000, v2
	v_cmp_gt_f32_e32 vcc, s4, v2
	s_nop 1
	v_cndmask_b32_e32 v2, v2, v3, vcc
	v_rsq_f32_e32 v2, v2
	s_nop 0
	v_mul_f32_e32 v3, 0x45800000, v2
	v_cndmask_b32_e32 v2, v2, v3, vcc
	ds_write_b32 v69, v2

; DI int tid_() { int t = threadIdx.x; asm volatile("" : "+v"(t)); return t; }
; #define GL1_(RA, RB, i) { RA[i] = *(const u32x4*)(ap + (aoff + (i) * astep)); if ((i) < NB) RB[(i) < NB ? (i) : 0] = *(const u32x4*)(bp + (boff + (i) * bstep)); }
; #define LS1_(RA, RB, ST, i) { char* sn_ = lds + (ST) * STAGE; *(u32x4*)(sn_ + wofs + (i) * 32 * LROW) = RA[i]; \
;                               if ((i) < NB) *(u32x4*)(sn_ + STAGE_OP + wofs + (i) * 32 * LROW) = RB[(i) < NB ? (i) : 0]; }
; template <int NJ> DI void gemm_mainloop_reg(const bf16_t* __restrict__ A, int lda, const bf16_t* __restrict__ Bt, int ldb, int K, f32x16 (&acc)[2][NJ], char* lds) {
;   const int tid = tid_(), lane = tid & 63, w = tid >> 6, wm = w >> 1, wn = w & 1;
;   const int lr = tid >> 3, lc = tid & 7;
;   const char* ap = (const char*)A;
;   const char* bp = (const char*)Bt;
;   const unsigned aoff = (unsigned)(lr * lda + lc * 8) * 2u, boff = (unsigned)(lr * ldb + lc * 8) * 2u;
;   const unsigned astep = (unsigned)(32 * lda) * 2u, bstep = (unsigned)(32 * ldb) * 2u;
;   constexpr int NB = 2 * NJ;
;   u32x4 ra0[4], rb0[NB], ra1[4], rb1[NB];
;   const int wofs = lr * LROW + lc * 16;
;   const int a_rd = (wm * 64 + (lane & 31)) * LROW + (lane >> 5) * 16;
;   const int b_rd = STAGE_OP + (wn * 32 * NJ + (lane & 31)) * LROW + (lane >> 5) * 16;
;     ...
; #pragma unroll
;   for (int i = 0; i < 4; ++i) GL1_(ra0, rb0, i);
;   ap += 128; bp += 128;
; #pragma unroll
;   for (int i = 0; i < 4; ++i) GL1_(ra1, rb1, i);
;   ap += 128; bp += 128;
; #pragma unroll
;   for (int i = 0; i < 4; ++i) LS1_(ra0, rb0, 0, i);
;   __syncthreads();
; DI void phase_resid_gemm(const Ctx& c, const bf16_t* A, int K, size_t woff, float scale, float* ssn) {
;     ...
;   for (int j_ = slot_; j_ < 16 * 8; j_ += nslot_) {
;     const int mt = xcd_ * 16 + (j_ & 15), nt = j_ >> 4;
;     f32x16 acc[2][2]; zero_acc<2>(acc);
;     gemm_mainloop_reg<2>(A + (size_t)mt * 128 * (K + PADK), K + PADK, Bt + (size_t)nt * 128 * (K + PADK), K + PADK, K, acc, c.lds);
.LBB0_427:
	s_and_b32 s0, s34, 15
	s_lshl_b32 s39, s0, 7
	s_lshl_b32 s0, s25, 1
	s_and_b32 s72, s0, 0x700
	s_lshl_b32 s0, s25, 2
	s_and_b32 s38, s0, 0xe00
	s_and_b32 s0, s35, 15
	s_add_i32 s41, s10, s39
	s_or_b32 s0, s0, s78
	s_lshl_b32 s40, s41, 2
	s_mul_i32 s0, s0, 0xb4000
	s_add_u32 s0, s86, s0
	s_addc_u32 s1, s87, 0
	s_lshl_b32 s2, s35, 3
	s_and_b32 s2, s2, 0x380
	s_mulk_i32 s2, 0x1680
	v_mov_b32_e32 v34, v199
	s_add_u32 s36, s4, s2
	s_movk_i32 s2, 0x1680
	v_ashrrev_i32_e32 v0, 3, v34
	v_lshlrev_b32_e32 v2, 4, v34
	v_and_b32_e32 v35, 0x70, v2
	v_mul_lo_u32 v2, v0, s2
	v_or_b32_e32 v72, v35, v2
	v_add_u32_e32 v71, 0x2d000, v72
	v_add_u32_e32 v70, 0x5a000, v72
	v_add_u32_e32 v69, 0x87000, v72
	s_addc_u32 s37, s5, 0
	global_load_dwordx4 v[2:5], v72, s[0:1]
	global_load_dwordx4 v[6:9], v71, s[0:1]
	global_load_dwordx4 v[10:13], v70, s[0:1]
	global_load_dwordx4 v[14:17], v69, s[0:1]
	global_load_dwordx4 v[18:21], v72, s[36:37]
	global_load_dwordx4 v[22:25], v71, s[36:37]
	global_load_dwordx4 v[26:29], v70, s[36:37]
	global_load_dwordx4 v[30:33], v69, s[36:37]
	v_mul_lo_u32 v0, v0, s16
	v_lshrrev_b32_e32 v36, 1, v34
	v_and_b32_e32 v37, 31, v34
	v_add3_u32 v67, v0, v35, 0
	v_and_b32_e32 v38, 16, v36
	v_and_or_b32 v36, v36, s17, v37
	global_load_dwordx4 v[74:77], v72, s[0:1] offset:128
	global_load_dwordx4 v[78:81], v71, s[0:1] offset:128
	global_load_dwordx4 v[82:85], v70, s[0:1] offset:128
	global_load_dwordx4 v[86:89], v69, s[0:1] offset:128
	global_load_dwordx4 v[90:93], v72, s[36:37] offset:128
	global_load_dwordx4 v[94:97], v71, s[36:37] offset:128
	global_load_dwordx4 v[98:101], v70, s[36:37] offset:128
	global_load_dwordx4 v[102:105], v69, s[36:37] offset:128
	v_mul_lo_u32 v0, v36, s16
	v_add3_u32 v0, v0, v38, 0
	v_add_u32_e32 v68, 0xd800, v67
	s_waitcnt vmcnt(15)
	ds_write_b128 v67, v[2:5]
	s_waitcnt vmcnt(14)
	ds_write_b128 v67, v[6:9] offset:4608
	s_waitcnt vmcnt(13)
	ds_write_b128 v67, v[10:13] offset:9216
	s_waitcnt vmcnt(12)
	ds_write_b128 v67, v[14:17] offset:13824
	s_waitcnt vmcnt(11)
	ds_write_b128 v67, v[18:21] offset:18432
	s_waitcnt vmcnt(10)
	ds_write_b128 v67, v[22:25] offset:23040
	s_waitcnt vmcnt(9)
	ds_write_b128 v67, v[26:29] offset:27648
	s_waitcnt vmcnt(8)
	ds_write_b128 v67, v[30:33] offset:32256
	v_and_b32_e32 v2, 0x5f, v34
	v_mul_u32_u24_e32 v2, 0x90, v2
	v_add3_u32 v66, v2, v38, 0
	s_waitcnt lgkmcnt(0)
	s_barrier
	ds_read_b128 v[18:21], v0
	ds_read_b128 v[2:5], v66 offset:18432
	ds_read_b128 v[106:109], v0 offset:32
	ds_read_b128 v[110:113], v66 offset:18464
	ds_read_b128 v[22:25], v0 offset:4608
	ds_read_b128 v[114:117], v0 offset:4640
	ds_read_b128 v[26:29], v66 offset:23040
	ds_read_b128 v[118:121], v66 offset:23072
	global_load_dwordx4 v[122:125], v72, s[0:1] offset:256
	global_load_dwordx4 v[126:129], v72, s[36:37] offset:256
	s_waitcnt lgkmcnt(6)
	s_setprio 1
	v_mfma_f32_32x32x16_bf16 v[34:49], v[18:21], v[2:5], 0
	s_waitcnt vmcnt(9)
	ds_write_b128 v67, v[74:77] offset:36864
	s_waitcnt vmcnt(5)
	ds_write_b128 v67, v[90:93] offset:55296
	s_waitcnt lgkmcnt(5)
	v_mfma_f32_32x32x16_bf16 v[2:17], v[22:25], v[2:5], 0
	s_waitcnt lgkmcnt(3)
	v_mfma_f32_32x32x16_bf16 v[50:65], v[18:21], v[26:29], 0
	v_mfma_f32_32x32x16_bf16 v[18:33], v[22:25], v[26:29], 0
	global_load_dwordx4 v[74:77], v71, s[0:1] offset:256
	global_load_dwordx4 v[90:93], v71, s[36:37] offset:256
	v_mfma_f32_32x32x16_bf16 v[2:17], v[114:117], v[110:113], v[2:17]
	s_waitcnt lgkmcnt(2)
	v_mfma_f32_32x32x16_bf16 v[18:33], v[114:117], v[118:121], v[18:33]
	v_mfma_f32_32x32x16_bf16 v[34:49], v[106:109], v[110:113], v[34:49]
	v_mfma_f32_32x32x16_bf16 v[50:65], v[106:109], v[118:121], v[50:65]
	ds_read_b128 v[106:109], v0 offset:64
	ds_read_b128 v[110:113], v0 offset:4672
	ds_read_b128 v[130:133], v66 offset:18496
	ds_read_b128 v[134:137], v66 offset:23104
	ds_write_b128 v67, v[78:81] offset:41472
	s_waitcnt vmcnt(6)
	ds_write_b128 v67, v[94:97] offset:59904
	global_load_dwordx4 v[78:81], v70, s[0:1] offset:256
	global_load_dwordx4 v[94:97], v70, s[36:37] offset:256
	s_waitcnt lgkmcnt(3)
	v_mfma_f32_32x32x16_bf16 v[2:17], v[110:113], v[130:133], v[2:17]
	s_waitcnt lgkmcnt(2)
	v_mfma_f32_32x32x16_bf16 v[18:33], v[110:113], v[134:137], v[18:33]
	v_mfma_f32_32x32x16_bf16 v[34:49], v[106:109], v[130:133], v[34:49]
	v_mfma_f32_32x32x16_bf16 v[50:65], v[106:109], v[134:137], v[50:65]
	ds_read_b128 v[106:109], v0 offset:96
	ds_read_b128 v[114:117], v0 offset:4704
	ds_read_b128 v[118:121], v66 offset:18528
	ds_read_b128 v[130:133], v66 offset:23136
	ds_write_b128 v67, v[82:85] offset:46080
	s_waitcnt vmcnt(7)
	ds_write_b128 v67, v[98:101] offset:64512
	global_load_dwordx4 v[82:85], v69, s[0:1] offset:256
	global_load_dwordx4 v[98:101], v69, s[36:37] offset:256
	s_waitcnt lgkmcnt(3)
	v_mfma_f32_32x32x16_bf16 v[2:17], v[114:117], v[118:121], v[2:17]
	ds_write_b128 v67, v[86:89] offset:50688
	s_waitcnt vmcnt(8)
	ds_write_b128 v68, v[102:105] offset:13824
	s_waitcnt lgkmcnt(4)
	v_mfma_f32_32x32x16_bf16 v[18:33], v[114:117], v[130:133], v[18:33]
	v_mfma_f32_32x32x16_bf16 v[34:49], v[106:109], v[118:121], v[34:49]
	v_mfma_f32_32x32x16_bf16 v[50:65], v[106:109], v[130:133], v[50:65]
	s_waitcnt lgkmcnt(0)
	s_barrier
; #define GL1_(RA, RB, i) { RA[i] = *(const u32x4*)(ap + (aoff + (i) * astep)); if ((i) < NB) RB[(i) < NB ? (i) : 0] = *(const u32x4*)(bp + (boff + (i) * bstep)); }
; #define LS1_(RA, RB, ST, i) { char* sn_ = lds + (ST) * STAGE; *(u32x4*)(sn_ + wofs + (i) * 32 * LROW) = RA[i]; \
;                               if ((i) < NB) *(u32x4*)(sn_ + STAGE_OP + wofs + (i) * 32 * LROW) = RB[(i) < NB ? (i) : 0]; }
; template <int NJ> DI void gemm_mainloop_reg(const bf16_t* __restrict__ A, int lda, const bf16_t* __restrict__ Bt, int ldb, int K, f32x16 (&acc)[2][NJ], char* lds) {
;     ...
; #pragma unroll
;   for (int i = 0; i < 4; ++i) GL1_(ra0, rb0, i);
;   ap += 128; bp += 128;
; #pragma unroll
;   for (int i = 0; i < 4; ++i) GL1_(ra1, rb1, i);
;   ap += 128; bp += 128;
; #pragma unroll
;   for (int i = 0; i < 4; ++i) LS1_(ra0, rb0, 0, i);
;   __syncthreads();
;   const int nk = K >> 6;
;   for (int kt = 0; kt < nk; kt += 2) {
;     const bool l0 = (kt + 2 < nk), l1 = (kt + 3 < nk);
;     STEP_(0, l0, ra0, rb0, true, ra1, rb1);
;     __syncthreads();
;     STEP_(1, l1, ra1, rb1, l0, ra0, rb0);
;     __syncthreads();
;   }
	ds_read_b128 v[86:89], v0 offset:36864
	ds_read_b128 v[102:105], v66 offset:55296
	ds_read_b128 v[106:109], v0 offset:36896
	ds_read_b128 v[110:113], v66 offset:55328
	ds_read_b128 v[114:117], v0 offset:41472
	ds_read_b128 v[118:121], v0 offset:41504
	s_waitcnt lgkmcnt(4)
	v_mfma_f32_32x32x16_bf16 v[34:49], v[86:89], v[102:105], v[34:49]
	s_waitcnt lgkmcnt(1)
	v_mfma_f32_32x32x16_bf16 v[2:17], v[114:117], v[102:105], v[2:17]
	ds_read_b128 v[102:105], v66 offset:59904
	ds_read_b128 v[130:133], v66 offset:59936
	s_waitcnt lgkmcnt(1)
	v_mfma_f32_32x32x16_bf16 v[50:65], v[86:89], v[102:105], v[50:65]
	global_load_dwordx4 v[86:89], v72, s[0:1] offset:384
	global_load_dwordx4 v[134:137], v72, s[36:37] offset:384
	s_waitcnt vmcnt(9)
	ds_write_b128 v67, v[122:125]
	s_waitcnt vmcnt(8)
	ds_write_b128 v67, v[126:129] offset:18432
	v_mfma_f32_32x32x16_bf16 v[18:33], v[114:117], v[102:105], v[18:33]
	v_mfma_f32_32x32x16_bf16 v[34:49], v[106:109], v[110:113], v[34:49]
	s_waitcnt lgkmcnt(2)
	v_mfma_f32_32x32x16_bf16 v[50:65], v[106:109], v[130:133], v[50:65]
	global_load_dwordx4 v[102:105], v71, s[0:1] offset:384
	global_load_dwordx4 v[106:109], v71, s[36:37] offset:384
	v_mfma_f32_32x32x16_bf16 v[2:17], v[118:121], v[110:113], v[2:17]
	ds_read_b128 v[110:113], v0 offset:36928
	ds_read_b128 v[114:117], v0 offset:41536
	ds_read_b128 v[122:125], v66 offset:55360
	ds_read_b128 v[126:129], v66 offset:59968
	s_waitcnt vmcnt(9)
	ds_write_b128 v67, v[74:77] offset:4608
	s_waitcnt vmcnt(8)
	ds_write_b128 v67, v[90:93] offset:23040
	v_mfma_f32_32x32x16_bf16 v[18:33], v[118:121], v[130:133], v[18:33]
	global_load_dwordx4 v[74:77], v70, s[0:1] offset:384
	global_load_dwordx4 v[90:93], v70, s[36:37] offset:384
	s_waitcnt lgkmcnt(3)
	v_mfma_f32_32x32x16_bf16 v[2:17], v[114:117], v[122:125], v[2:17]
	s_waitcnt lgkmcnt(2)
	v_mfma_f32_32x32x16_bf16 v[18:33], v[114:117], v[126:129], v[18:33]
	v_mfma_f32_32x32x16_bf16 v[34:49], v[110:113], v[122:125], v[34:49]
	v_mfma_f32_32x32x16_bf16 v[50:65], v[110:113], v[126:129], v[50:65]
	ds_read_b128 v[110:113], v0 offset:36960
	ds_read_b128 v[118:121], v0 offset:41568
	ds_read_b128 v[122:125], v66 offset:55392
	ds_read_b128 v[130:133], v66 offset:60000
	s_waitcnt vmcnt(9)
	ds_write_b128 v67, v[78:81] offset:9216
	s_waitcnt vmcnt(8)
	ds_write_b128 v67, v[94:97] offset:27648
	global_load_dwordx4 v[78:81], v69, s[0:1] offset:384
	global_load_dwordx4 v[94:97], v69, s[36:37] offset:384
	s_waitcnt lgkmcnt(3)
	v_mfma_f32_32x32x16_bf16 v[2:17], v[118:121], v[122:125], v[2:17]
	s_waitcnt vmcnt(9)
	ds_write_b128 v67, v[82:85] offset:13824
	s_waitcnt vmcnt(8)
	ds_write_b128 v67, v[98:101] offset:32256
	s_waitcnt lgkmcnt(4)
	v_mfma_f32_32x32x16_bf16 v[18:33], v[118:121], v[130:133], v[18:33]
	v_mfma_f32_32x32x16_bf16 v[34:49], v[110:113], v[122:125], v[34:49]
	v_mfma_f32_32x32x16_bf16 v[50:65], v[110:113], v[130:133], v[50:65]
	s_waitcnt lgkmcnt(0)
	s_barrier
	ds_read_b128 v[82:85], v0
	ds_read_b128 v[98:101], v66 offset:18432
	ds_read_b128 v[110:113], v0 offset:32
	ds_read_b128 v[114:117], v66 offset:18464
	ds_read_b128 v[118:121], v0 offset:4608
	ds_read_b128 v[122:125], v0 offset:4640
	s_waitcnt lgkmcnt(4)
	v_mfma_f32_32x32x16_bf16 v[34:49], v[82:85], v[98:101], v[34:49]
	s_waitcnt lgkmcnt(1)
	v_mfma_f32_32x32x16_bf16 v[2:17], v[118:121], v[98:101], v[2:17]
	ds_read_b128 v[98:101], v66 offset:23040
	ds_read_b128 v[126:129], v66 offset:23072
	s_waitcnt lgkmcnt(1)
	v_mfma_f32_32x32x16_bf16 v[50:65], v[82:85], v[98:101], v[50:65]
	global_load_dwordx4 v[82:85], v72, s[0:1] offset:512
	global_load_dwordx4 v[130:133], v72, s[36:37] offset:512
	s_waitcnt vmcnt(9)
	ds_write_b128 v67, v[86:89] offset:36864
	s_waitcnt vmcnt(8)
	ds_write_b128 v67, v[134:137] offset:55296
	v_mfma_f32_32x32x16_bf16 v[18:33], v[118:121], v[98:101], v[18:33]
	global_load_dwordx4 v[86:89], v71, s[0:1] offset:512
	global_load_dwordx4 v[98:101], v71, s[36:37] offset:512
	v_mfma_f32_32x32x16_bf16 v[2:17], v[122:125], v[114:117], v[2:17]
	s_waitcnt lgkmcnt(2)
	v_mfma_f32_32x32x16_bf16 v[18:33], v[122:125], v[126:129], v[18:33]
	v_mfma_f32_32x32x16_bf16 v[34:49], v[110:113], v[114:117], v[34:49]
	v_mfma_f32_32x32x16_bf16 v[50:65], v[110:113], v[126:129], v[50:65]
	ds_read_b128 v[110:113], v0 offset:64
	ds_read_b128 v[114:117], v0 offset:4672
	ds_read_b128 v[118:121], v66 offset:18496
	ds_read_b128 v[134:137], v66 offset:23104
	s_waitcnt vmcnt(9)
	ds_write_b128 v67, v[102:105] offset:41472
	s_waitcnt vmcnt(8)
	ds_write_b128 v67, v[106:109] offset:59904
	global_load_dwordx4 v[102:105], v70, s[0:1] offset:512
	global_load_dwordx4 v[106:109], v70, s[36:37] offset:512
	s_waitcnt lgkmcnt(3)
	v_mfma_f32_32x32x16_bf16 v[2:17], v[114:117], v[118:121], v[2:17]
	s_waitcnt lgkmcnt(2)
	v_mfma_f32_32x32x16_bf16 v[18:33], v[114:117], v[134:137], v[18:33]
	v_mfma_f32_32x32x16_bf16 v[34:49], v[110:113], v[118:121], v[34:49]
	v_mfma_f32_32x32x16_bf16 v[50:65], v[110:113], v[134:137], v[50:65]
	ds_read_b128 v[110:113], v0 offset:96
	ds_read_b128 v[118:121], v0 offset:4704
	ds_read_b128 v[122:125], v66 offset:18528
	ds_read_b128 v[126:129], v66 offset:23136
	s_waitcnt vmcnt(9)
	ds_write_b128 v67, v[74:77] offset:46080
	s_waitcnt vmcnt(8)
	ds_write_b128 v67, v[90:93] offset:64512
	global_load_dwordx4 v[74:77], v69, s[0:1] offset:512
	global_load_dwordx4 v[90:93], v69, s[36:37] offset:512
	s_waitcnt lgkmcnt(3)
	v_mfma_f32_32x32x16_bf16 v[2:17], v[118:121], v[122:125], v[2:17]
	s_waitcnt vmcnt(9)
	ds_write_b128 v67, v[78:81] offset:50688
	s_waitcnt vmcnt(8)
	ds_write_b128 v68, v[94:97] offset:13824
	s_waitcnt lgkmcnt(4)
	v_mfma_f32_32x32x16_bf16 v[18:33], v[118:121], v[126:129], v[18:33]
	v_mfma_f32_32x32x16_bf16 v[34:49], v[110:113], v[122:125], v[34:49]
	v_mfma_f32_32x32x16_bf16 v[50:65], v[110:113], v[126:129], v[50:65]
	s_waitcnt lgkmcnt(0)
	s_barrier
; #define GL1_(RA, RB, i) { RA[i] = *(const u32x4*)(ap + (aoff + (i) * astep)); if ((i) < NB) RB[(i) < NB ? (i) : 0] = *(const u32x4*)(bp + (boff + (i) * bstep)); }
; #define LS1_(RA, RB, ST, i) { char* sn_ = lds + (ST) * STAGE; *(u32x4*)(sn_ + wofs + (i) * 32 * LROW) = RA[i]; \
;                               if ((i) < NB) *(u32x4*)(sn_ + STAGE_OP + wofs + (i) * 32 * LROW) = RB[(i) < NB ? (i) : 0]; }
; template <int NJ> DI void gemm_mainloop_reg(const bf16_t* __restrict__ A, int lda, const bf16_t* __restrict__ Bt, int ldb, int K, f32x16 (&acc)[2][NJ], char* lds) {
;     ...
; #pragma unroll
;   for (int i = 0; i < 4; ++i) GL1_(ra0, rb0, i);
;   ap += 128; bp += 128;
; #pragma unroll
;   for (int i = 0; i < 4; ++i) GL1_(ra1, rb1, i);
;   ap += 128; bp += 128;
; #pragma unroll
;   for (int i = 0; i < 4; ++i) LS1_(ra0, rb0, 0, i);
;   __syncthreads();
;   const int nk = K >> 6;
;   for (int kt = 0; kt < nk; kt += 2) {
;     const bool l0 = (kt + 2 < nk), l1 = (kt + 3 < nk);
;     STEP_(0, l0, ra0, rb0, true, ra1, rb1);
;     __syncthreads();
;     STEP_(1, l1, ra1, rb1, l0, ra0, rb0);
;     __syncthreads();
;   }
	ds_read_b128 v[78:81], v0 offset:36864
	ds_read_b128 v[94:97], v66 offset:55296
	ds_read_b128 v[110:113], v0 offset:36896
	ds_read_b128 v[114:117], v66 offset:55328
	ds_read_b128 v[118:121], v0 offset:41472
	ds_read_b128 v[122:125], v0 offset:41504
	s_waitcnt lgkmcnt(4)
	v_mfma_f32_32x32x16_bf16 v[34:49], v[78:81], v[94:97], v[34:49]
	s_waitcnt lgkmcnt(1)
	v_mfma_f32_32x32x16_bf16 v[2:17], v[118:121], v[94:97], v[2:17]
	ds_read_b128 v[94:97], v66 offset:59904
	ds_read_b128 v[126:129], v66 offset:59936
	s_waitcnt lgkmcnt(1)
	v_mfma_f32_32x32x16_bf16 v[50:65], v[78:81], v[94:97], v[50:65]
	global_load_dwordx4 v[78:81], v72, s[0:1] offset:640
	global_load_dwordx4 v[134:137], v72, s[36:37] offset:640
	s_waitcnt vmcnt(9)
	ds_write_b128 v67, v[82:85]
	s_waitcnt vmcnt(8)
	ds_write_b128 v67, v[130:133] offset:18432
	v_mfma_f32_32x32x16_bf16 v[18:33], v[118:121], v[94:97], v[18:33]
	global_load_dwordx4 v[82:85], v71, s[0:1] offset:640
	global_load_dwordx4 v[94:97], v71, s[36:37] offset:640
	v_mfma_f32_32x32x16_bf16 v[2:17], v[122:125], v[114:117], v[2:17]
	s_waitcnt lgkmcnt(2)
	v_mfma_f32_32x32x16_bf16 v[18:33], v[122:125], v[126:129], v[18:33]
	v_mfma_f32_32x32x16_bf16 v[34:49], v[110:113], v[114:117], v[34:49]
	v_mfma_f32_32x32x16_bf16 v[50:65], v[110:113], v[126:129], v[50:65]
	ds_read_b128 v[110:113], v0 offset:36928
	ds_read_b128 v[114:117], v0 offset:41536
	ds_read_b128 v[118:121], v66 offset:55360
	ds_read_b128 v[130:133], v66 offset:59968
	s_waitcnt vmcnt(9)
	ds_write_b128 v67, v[86:89] offset:4608
	s_waitcnt vmcnt(8)
	ds_write_b128 v67, v[98:101] offset:23040
	global_load_dwordx4 v[86:89], v70, s[0:1] offset:640
	global_load_dwordx4 v[98:101], v70, s[36:37] offset:640
	s_waitcnt lgkmcnt(3)
	v_mfma_f32_32x32x16_bf16 v[2:17], v[114:117], v[118:121], v[2:17]
	s_waitcnt lgkmcnt(2)
	v_mfma_f32_32x32x16_bf16 v[18:33], v[114:117], v[130:133], v[18:33]
	v_mfma_f32_32x32x16_bf16 v[34:49], v[110:113], v[118:121], v[34:49]
	v_mfma_f32_32x32x16_bf16 v[50:65], v[110:113], v[130:133], v[50:65]
	ds_read_b128 v[110:113], v0 offset:36960
	ds_read_b128 v[118:121], v0 offset:41568
	ds_read_b128 v[122:125], v66 offset:55392
	ds_read_b128 v[126:129], v66 offset:60000
	s_waitcnt vmcnt(9)
	ds_write_b128 v67, v[102:105] offset:9216
	s_waitcnt vmcnt(8)
	ds_write_b128 v67, v[106:109] offset:27648
	global_load_dwordx4 v[102:105], v69, s[0:1] offset:640
	global_load_dwordx4 v[106:109], v69, s[36:37] offset:640
	s_waitcnt lgkmcnt(3)
	v_mfma_f32_32x32x16_bf16 v[2:17], v[118:121], v[122:125], v[2:17]
	s_waitcnt vmcnt(9)
	ds_write_b128 v67, v[74:77] offset:13824
	s_waitcnt vmcnt(8)
	ds_write_b128 v67, v[90:93] offset:32256
	s_waitcnt lgkmcnt(4)
	v_mfma_f32_32x32x16_bf16 v[18:33], v[118:121], v[126:129], v[18:33]
	v_mfma_f32_32x32x16_bf16 v[34:49], v[110:113], v[122:125], v[34:49]
	v_mfma_f32_32x32x16_bf16 v[50:65], v[110:113], v[126:129], v[50:65]
	s_waitcnt lgkmcnt(0)
	s_barrier
	ds_read_b128 v[74:77], v0
	ds_read_b128 v[90:93], v66 offset:18432
	ds_read_b128 v[110:113], v0 offset:32
	ds_read_b128 v[114:117], v66 offset:18464
	ds_read_b128 v[118:121], v0 offset:4608
	ds_read_b128 v[122:125], v0 offset:4640
	s_waitcnt lgkmcnt(4)
	v_mfma_f32_32x32x16_bf16 v[34:49], v[74:77], v[90:93], v[34:49]
	s_waitcnt lgkmcnt(1)
	v_mfma_f32_32x32x16_bf16 v[2:17], v[118:121], v[90:93], v[2:17]
	ds_read_b128 v[90:93], v66 offset:23040
	ds_read_b128 v[126:129], v66 offset:23072
	s_waitcnt lgkmcnt(1)
	v_mfma_f32_32x32x16_bf16 v[50:65], v[74:77], v[90:93], v[50:65]
	global_load_dwordx4 v[74:77], v72, s[0:1] offset:768
	global_load_dwordx4 v[130:133], v72, s[36:37] offset:768
	s_waitcnt vmcnt(9)
	ds_write_b128 v67, v[78:81] offset:36864
	s_waitcnt vmcnt(8)
	ds_write_b128 v67, v[134:137] offset:55296
	v_mfma_f32_32x32x16_bf16 v[18:33], v[118:121], v[90:93], v[18:33]
	global_load_dwordx4 v[78:81], v71, s[0:1] offset:768
	global_load_dwordx4 v[90:93], v71, s[36:37] offset:768
	v_mfma_f32_32x32x16_bf16 v[2:17], v[122:125], v[114:117], v[2:17]
	s_waitcnt lgkmcnt(2)
	v_mfma_f32_32x32x16_bf16 v[18:33], v[122:125], v[126:129], v[18:33]
	v_mfma_f32_32x32x16_bf16 v[34:49], v[110:113], v[114:117], v[34:49]
	v_mfma_f32_32x32x16_bf16 v[50:65], v[110:113], v[126:129], v[50:65]
	ds_read_b128 v[110:113], v0 offset:64
	ds_read_b128 v[114:117], v0 offset:4672
	ds_read_b128 v[118:121], v66 offset:18496
	ds_read_b128 v[134:137], v66 offset:23104
	s_waitcnt vmcnt(9)
	ds_write_b128 v67, v[82:85] offset:41472
	s_waitcnt vmcnt(8)
	ds_write_b128 v67, v[94:97] offset:59904
	global_load_dwordx4 v[82:85], v70, s[0:1] offset:768
	global_load_dwordx4 v[94:97], v70, s[36:37] offset:768
	s_waitcnt lgkmcnt(3)
	v_mfma_f32_32x32x16_bf16 v[2:17], v[114:117], v[118:121], v[2:17]
	s_waitcnt lgkmcnt(2)
	v_mfma_f32_32x32x16_bf16 v[18:33], v[114:117], v[134:137], v[18:33]
	v_mfma_f32_32x32x16_bf16 v[34:49], v[110:113], v[118:121], v[34:49]
	v_mfma_f32_32x32x16_bf16 v[50:65], v[110:113], v[134:137], v[50:65]
	ds_read_b128 v[110:113], v0 offset:96
	ds_read_b128 v[118:121], v0 offset:4704
	ds_read_b128 v[122:125], v66 offset:18528
	ds_read_b128 v[126:129], v66 offset:23136
	s_waitcnt vmcnt(9)
	ds_write_b128 v67, v[86:89] offset:46080
	s_waitcnt vmcnt(8)
	ds_write_b128 v67, v[98:101] offset:64512
	global_load_dwordx4 v[86:89], v69, s[0:1] offset:768
	global_load_dwordx4 v[98:101], v69, s[36:37] offset:768
	s_waitcnt lgkmcnt(3)
	v_mfma_f32_32x32x16_bf16 v[2:17], v[118:121], v[122:125], v[2:17]
	s_waitcnt vmcnt(9)
	ds_write_b128 v67, v[102:105] offset:50688
	s_waitcnt vmcnt(8)
	ds_write_b128 v68, v[106:109] offset:13824
	s_waitcnt lgkmcnt(4)
	v_mfma_f32_32x32x16_bf16 v[18:33], v[118:121], v[126:129], v[18:33]
	v_mfma_f32_32x32x16_bf16 v[34:49], v[110:113], v[122:125], v[34:49]
	v_mfma_f32_32x32x16_bf16 v[50:65], v[110:113], v[126:129], v[50:65]
	s_waitcnt lgkmcnt(0)
	s_barrier
; #define GL1_(RA, RB, i) { RA[i] = *(const u32x4*)(ap + (aoff + (i) * astep)); if ((i) < NB) RB[(i) < NB ? (i) : 0] = *(const u32x4*)(bp + (boff + (i) * bstep)); }
; #define LS1_(RA, RB, ST, i) { char* sn_ = lds + (ST) * STAGE; *(u32x4*)(sn_ + wofs + (i) * 32 * LROW) = RA[i]; \
;                               if ((i) < NB) *(u32x4*)(sn_ + STAGE_OP + wofs + (i) * 32 * LROW) = RB[(i) < NB ? (i) : 0]; }
; template <int NJ> DI void gemm_mainloop_reg(const bf16_t* __restrict__ A, int lda, const bf16_t* __restrict__ Bt, int ldb, int K, f32x16 (&acc)[2][NJ], char* lds) {
;     ...
; #pragma unroll
;   for (int i = 0; i < 4; ++i) GL1_(ra0, rb0, i);
;   ap += 128; bp += 128;
; #pragma unroll
;   for (int i = 0; i < 4; ++i) GL1_(ra1, rb1, i);
;   ap += 128; bp += 128;
; #pragma unroll
;   for (int i = 0; i < 4; ++i) LS1_(ra0, rb0, 0, i);
;   __syncthreads();
;   const int nk = K >> 6;
;   for (int kt = 0; kt < nk; kt += 2) {
;     const bool l0 = (kt + 2 < nk), l1 = (kt + 3 < nk);
;     STEP_(0, l0, ra0, rb0, true, ra1, rb1);
;     __syncthreads();
;     STEP_(1, l1, ra1, rb1, l0, ra0, rb0);
;     __syncthreads();
;   }
	ds_read_b128 v[102:105], v0 offset:36864
	ds_read_b128 v[106:109], v66 offset:55296
	ds_read_b128 v[110:113], v0 offset:36896
	ds_read_b128 v[114:117], v66 offset:55328
	ds_read_b128 v[118:121], v0 offset:41472
	ds_read_b128 v[122:125], v0 offset:41504
	s_waitcnt lgkmcnt(4)
	v_mfma_f32_32x32x16_bf16 v[34:49], v[102:105], v[106:109], v[34:49]
	s_waitcnt lgkmcnt(1)
	v_mfma_f32_32x32x16_bf16 v[2:17], v[118:121], v[106:109], v[2:17]
	ds_read_b128 v[106:109], v66 offset:59904
	ds_read_b128 v[126:129], v66 offset:59936
	s_waitcnt lgkmcnt(1)
	v_mfma_f32_32x32x16_bf16 v[50:65], v[102:105], v[106:109], v[50:65]
	global_load_dwordx4 v[102:105], v72, s[0:1] offset:896
	global_load_dwordx4 v[134:137], v72, s[36:37] offset:896
	s_waitcnt vmcnt(9)
	ds_write_b128 v67, v[74:77]
	s_waitcnt vmcnt(8)
	ds_write_b128 v67, v[130:133] offset:18432
	v_mfma_f32_32x32x16_bf16 v[18:33], v[118:121], v[106:109], v[18:33]
	global_load_dwordx4 v[74:77], v71, s[0:1] offset:896
	global_load_dwordx4 v[106:109], v71, s[36:37] offset:896
	v_mfma_f32_32x32x16_bf16 v[2:17], v[122:125], v[114:117], v[2:17]
	s_waitcnt lgkmcnt(2)
	v_mfma_f32_32x32x16_bf16 v[18:33], v[122:125], v[126:129], v[18:33]
	v_mfma_f32_32x32x16_bf16 v[34:49], v[110:113], v[114:117], v[34:49]
	v_mfma_f32_32x32x16_bf16 v[50:65], v[110:113], v[126:129], v[50:65]
	ds_read_b128 v[110:113], v0 offset:36928
	ds_read_b128 v[114:117], v0 offset:41536
	ds_read_b128 v[118:121], v66 offset:55360
	ds_read_b128 v[130:133], v66 offset:59968
	s_waitcnt vmcnt(9)
	ds_write_b128 v67, v[78:81] offset:4608
	s_waitcnt vmcnt(8)
	ds_write_b128 v67, v[90:93] offset:23040
	global_load_dwordx4 v[78:81], v70, s[0:1] offset:896
	global_load_dwordx4 v[90:93], v70, s[36:37] offset:896
	s_waitcnt lgkmcnt(3)
	v_mfma_f32_32x32x16_bf16 v[2:17], v[114:117], v[118:121], v[2:17]
	s_waitcnt lgkmcnt(2)
	v_mfma_f32_32x32x16_bf16 v[18:33], v[114:117], v[130:133], v[18:33]
	v_mfma_f32_32x32x16_bf16 v[34:49], v[110:113], v[118:121], v[34:49]
	v_mfma_f32_32x32x16_bf16 v[50:65], v[110:113], v[130:133], v[50:65]
	ds_read_b128 v[110:113], v0 offset:36960
	ds_read_b128 v[118:121], v0 offset:41568
	ds_read_b128 v[122:125], v66 offset:55392
	ds_read_b128 v[126:129], v66 offset:60000
	s_waitcnt vmcnt(9)
	ds_write_b128 v67, v[82:85] offset:9216
	s_waitcnt vmcnt(8)
	ds_write_b128 v67, v[94:97] offset:27648
	global_load_dwordx4 v[82:85], v69, s[0:1] offset:896
	global_load_dwordx4 v[94:97], v69, s[36:37] offset:896
	s_waitcnt lgkmcnt(3)
	v_mfma_f32_32x32x16_bf16 v[2:17], v[118:121], v[122:125], v[2:17]
	s_waitcnt vmcnt(9)
	ds_write_b128 v67, v[86:89] offset:13824
	s_waitcnt vmcnt(8)
	ds_write_b128 v67, v[98:101] offset:32256
	s_waitcnt lgkmcnt(4)
	v_mfma_f32_32x32x16_bf16 v[18:33], v[118:121], v[126:129], v[18:33]
	v_mfma_f32_32x32x16_bf16 v[34:49], v[110:113], v[122:125], v[34:49]
	v_mfma_f32_32x32x16_bf16 v[50:65], v[110:113], v[126:129], v[50:65]
	s_waitcnt lgkmcnt(0)
	s_barrier
	ds_read_b128 v[86:89], v0
	ds_read_b128 v[98:101], v66 offset:18432
	ds_read_b128 v[110:113], v0 offset:32
	ds_read_b128 v[114:117], v66 offset:18464
	ds_read_b128 v[118:121], v0 offset:4608
	ds_read_b128 v[122:125], v0 offset:4640
	s_waitcnt lgkmcnt(4)
	v_mfma_f32_32x32x16_bf16 v[34:49], v[86:89], v[98:101], v[34:49]
	s_waitcnt lgkmcnt(1)
	v_mfma_f32_32x32x16_bf16 v[2:17], v[118:121], v[98:101], v[2:17]
	ds_read_b128 v[98:101], v66 offset:23040
	ds_read_b128 v[126:129], v66 offset:23072
	s_waitcnt lgkmcnt(1)
	v_mfma_f32_32x32x16_bf16 v[50:65], v[86:89], v[98:101], v[50:65]
	global_load_dwordx4 v[86:89], v72, s[0:1] offset:1024
	global_load_dwordx4 v[130:133], v72, s[36:37] offset:1024
	s_waitcnt vmcnt(9)
	ds_write_b128 v67, v[102:105] offset:36864
	s_waitcnt vmcnt(8)
	ds_write_b128 v67, v[134:137] offset:55296
	v_mfma_f32_32x32x16_bf16 v[18:33], v[118:121], v[98:101], v[18:33]
	global_load_dwordx4 v[98:101], v71, s[0:1] offset:1024
	global_load_dwordx4 v[102:105], v71, s[36:37] offset:1024
	v_mfma_f32_32x32x16_bf16 v[2:17], v[122:125], v[114:117], v[2:17]
	s_waitcnt lgkmcnt(2)
	v_mfma_f32_32x32x16_bf16 v[18:33], v[122:125], v[126:129], v[18:33]
	v_mfma_f32_32x32x16_bf16 v[34:49], v[110:113], v[114:117], v[34:49]
	v_mfma_f32_32x32x16_bf16 v[50:65], v[110:113], v[126:129], v[50:65]
	ds_read_b128 v[110:113], v0 offset:64
	ds_read_b128 v[114:117], v0 offset:4672
	ds_read_b128 v[118:121], v66 offset:18496
	ds_read_b128 v[134:137], v66 offset:23104
	s_waitcnt vmcnt(9)
	ds_write_b128 v67, v[74:77] offset:41472
	s_waitcnt vmcnt(8)
	ds_write_b128 v67, v[106:109] offset:59904
	global_load_dwordx4 v[74:77], v70, s[0:1] offset:1024
	global_load_dwordx4 v[106:109], v70, s[36:37] offset:1024
	s_waitcnt lgkmcnt(3)
	v_mfma_f32_32x32x16_bf16 v[2:17], v[114:117], v[118:121], v[2:17]
	s_waitcnt lgkmcnt(2)
	v_mfma_f32_32x32x16_bf16 v[18:33], v[114:117], v[134:137], v[18:33]
	v_mfma_f32_32x32x16_bf16 v[34:49], v[110:113], v[118:121], v[34:49]
	v_mfma_f32_32x32x16_bf16 v[50:65], v[110:113], v[134:137], v[50:65]
	ds_read_b128 v[110:113], v0 offset:96
	ds_read_b128 v[118:121], v0 offset:4704
	ds_read_b128 v[122:125], v66 offset:18528
	ds_read_b128 v[126:129], v66 offset:23136
	s_waitcnt vmcnt(9)
	ds_write_b128 v67, v[78:81] offset:46080
	s_waitcnt vmcnt(8)
	ds_write_b128 v67, v[90:93] offset:64512
	global_load_dwordx4 v[78:81], v69, s[0:1] offset:1024
	global_load_dwordx4 v[90:93], v69, s[36:37] offset:1024
	s_waitcnt lgkmcnt(3)
	v_mfma_f32_32x32x16_bf16 v[2:17], v[118:121], v[122:125], v[2:17]
	s_waitcnt vmcnt(9)
	ds_write_b128 v67, v[82:85] offset:50688
	s_waitcnt vmcnt(8)
	ds_write_b128 v68, v[94:97] offset:13824
	s_waitcnt lgkmcnt(4)
	v_mfma_f32_32x32x16_bf16 v[18:33], v[118:121], v[126:129], v[18:33]
	v_mfma_f32_32x32x16_bf16 v[34:49], v[110:113], v[122:125], v[34:49]
	v_mfma_f32_32x32x16_bf16 v[50:65], v[110:113], v[126:129], v[50:65]
	s_waitcnt lgkmcnt(0)
	s_barrier
; #define GL1_(RA, RB, i) { RA[i] = *(const u32x4*)(ap + (aoff + (i) * astep)); if ((i) < NB) RB[(i) < NB ? (i) : 0] = *(const u32x4*)(bp + (boff + (i) * bstep)); }
; #define LS1_(RA, RB, ST, i) { char* sn_ = lds + (ST) * STAGE; *(u32x4*)(sn_ + wofs + (i) * 32 * LROW) = RA[i]; \
;                               if ((i) < NB) *(u32x4*)(sn_ + STAGE_OP + wofs + (i) * 32 * LROW) = RB[(i) < NB ? (i) : 0]; }
; template <int NJ> DI void gemm_mainloop_reg(const bf16_t* __restrict__ A, int lda, const bf16_t* __restrict__ Bt, int ldb, int K, f32x16 (&acc)[2][NJ], char* lds) {
;     ...
; #pragma unroll
;   for (int i = 0; i < 4; ++i) GL1_(ra0, rb0, i);
;   ap += 128; bp += 128;
; #pragma unroll
;   for (int i = 0; i < 4; ++i) GL1_(ra1, rb1, i);
;   ap += 128; bp += 128;
; #pragma unroll
;   for (int i = 0; i < 4; ++i) LS1_(ra0, rb0, 0, i);
;   __syncthreads();
;   const int nk = K >> 6;
;   for (int kt = 0; kt < nk; kt += 2) {
;     const bool l0 = (kt + 2 < nk), l1 = (kt + 3 < nk);
;     STEP_(0, l0, ra0, rb0, true, ra1, rb1);
;     __syncthreads();
;     STEP_(1, l1, ra1, rb1, l0, ra0, rb0);
;     __syncthreads();
;   }
	ds_read_b128 v[82:85], v0 offset:36864
	ds_read_b128 v[94:97], v66 offset:55296
	ds_read_b128 v[110:113], v0 offset:36896
	ds_read_b128 v[114:117], v66 offset:55328
	ds_read_b128 v[118:121], v0 offset:41472
	ds_read_b128 v[122:125], v0 offset:41504
	s_waitcnt lgkmcnt(4)
	v_mfma_f32_32x32x16_bf16 v[34:49], v[82:85], v[94:97], v[34:49]
	s_waitcnt lgkmcnt(1)
	v_mfma_f32_32x32x16_bf16 v[2:17], v[118:121], v[94:97], v[2:17]
	ds_read_b128 v[94:97], v66 offset:59904
	ds_read_b128 v[126:129], v66 offset:59936
	s_waitcnt lgkmcnt(1)
	v_mfma_f32_32x32x16_bf16 v[50:65], v[82:85], v[94:97], v[50:65]
	global_load_dwordx4 v[82:85], v72, s[0:1] offset:1152
	global_load_dwordx4 v[134:137], v72, s[36:37] offset:1152
	s_waitcnt vmcnt(9)
	ds_write_b128 v67, v[86:89]
	s_waitcnt vmcnt(8)
	ds_write_b128 v67, v[130:133] offset:18432
	v_mfma_f32_32x32x16_bf16 v[18:33], v[118:121], v[94:97], v[18:33]
	global_load_dwordx4 v[86:89], v71, s[0:1] offset:1152
	global_load_dwordx4 v[94:97], v71, s[36:37] offset:1152
	v_mfma_f32_32x32x16_bf16 v[2:17], v[122:125], v[114:117], v[2:17]
	s_waitcnt lgkmcnt(2)
	v_mfma_f32_32x32x16_bf16 v[18:33], v[122:125], v[126:129], v[18:33]
	v_mfma_f32_32x32x16_bf16 v[34:49], v[110:113], v[114:117], v[34:49]
	v_mfma_f32_32x32x16_bf16 v[50:65], v[110:113], v[126:129], v[50:65]
	ds_read_b128 v[110:113], v0 offset:36928
	ds_read_b128 v[114:117], v0 offset:41536
	ds_read_b128 v[118:121], v66 offset:55360
	ds_read_b128 v[130:133], v66 offset:59968
	s_waitcnt vmcnt(9)
	ds_write_b128 v67, v[98:101] offset:4608
	s_waitcnt vmcnt(8)
	ds_write_b128 v67, v[102:105] offset:23040
	global_load_dwordx4 v[98:101], v70, s[0:1] offset:1152
	global_load_dwordx4 v[102:105], v70, s[36:37] offset:1152
	s_waitcnt lgkmcnt(3)
	v_mfma_f32_32x32x16_bf16 v[2:17], v[114:117], v[118:121], v[2:17]
	s_waitcnt lgkmcnt(2)
	v_mfma_f32_32x32x16_bf16 v[18:33], v[114:117], v[130:133], v[18:33]
	v_mfma_f32_32x32x16_bf16 v[34:49], v[110:113], v[118:121], v[34:49]
	v_mfma_f32_32x32x16_bf16 v[50:65], v[110:113], v[130:133], v[50:65]
	ds_read_b128 v[110:113], v0 offset:36960
	ds_read_b128 v[118:121], v0 offset:41568
	ds_read_b128 v[122:125], v66 offset:55392
	ds_read_b128 v[126:129], v66 offset:60000
	s_waitcnt vmcnt(9)
	ds_write_b128 v67, v[74:77] offset:9216
	s_waitcnt vmcnt(8)
	ds_write_b128 v67, v[106:109] offset:27648
	global_load_dwordx4 v[74:77], v69, s[0:1] offset:1152
	global_load_dwordx4 v[106:109], v69, s[36:37] offset:1152
	s_waitcnt lgkmcnt(3)
	v_mfma_f32_32x32x16_bf16 v[2:17], v[118:121], v[122:125], v[2:17]
	s_waitcnt vmcnt(9)
	ds_write_b128 v67, v[78:81] offset:13824
	s_waitcnt vmcnt(8)
	ds_write_b128 v67, v[90:93] offset:32256
	s_waitcnt lgkmcnt(4)
	v_mfma_f32_32x32x16_bf16 v[18:33], v[118:121], v[126:129], v[18:33]
	v_mfma_f32_32x32x16_bf16 v[34:49], v[110:113], v[122:125], v[34:49]
	v_mfma_f32_32x32x16_bf16 v[50:65], v[110:113], v[126:129], v[50:65]
	s_waitcnt lgkmcnt(0)
	s_barrier
	ds_read_b128 v[78:81], v0
	ds_read_b128 v[90:93], v66 offset:18432
	ds_read_b128 v[110:113], v0 offset:32
	ds_read_b128 v[114:117], v66 offset:18464
	ds_read_b128 v[118:121], v0 offset:4608
	ds_read_b128 v[122:125], v0 offset:4640
	s_waitcnt lgkmcnt(4)
	v_mfma_f32_32x32x16_bf16 v[34:49], v[78:81], v[90:93], v[34:49]
	s_waitcnt lgkmcnt(1)
	v_mfma_f32_32x32x16_bf16 v[2:17], v[118:121], v[90:93], v[2:17]
	ds_read_b128 v[90:93], v66 offset:23040
	ds_read_b128 v[126:129], v66 offset:23072
	s_waitcnt lgkmcnt(1)
	v_mfma_f32_32x32x16_bf16 v[50:65], v[78:81], v[90:93], v[50:65]
	global_load_dwordx4 v[78:81], v72, s[0:1] offset:1280
	global_load_dwordx4 v[130:133], v72, s[36:37] offset:1280
	s_waitcnt vmcnt(9)
	ds_write_b128 v67, v[82:85] offset:36864
	s_waitcnt vmcnt(8)
	ds_write_b128 v67, v[134:137] offset:55296
	v_mfma_f32_32x32x16_bf16 v[18:33], v[118:121], v[90:93], v[18:33]
	global_load_dwordx4 v[82:85], v71, s[0:1] offset:1280
	global_load_dwordx4 v[90:93], v71, s[36:37] offset:1280
	v_mfma_f32_32x32x16_bf16 v[2:17], v[122:125], v[114:117], v[2:17]
	s_waitcnt lgkmcnt(2)
	v_mfma_f32_32x32x16_bf16 v[18:33], v[122:125], v[126:129], v[18:33]
	v_mfma_f32_32x32x16_bf16 v[34:49], v[110:113], v[114:117], v[34:49]
	v_mfma_f32_32x32x16_bf16 v[50:65], v[110:113], v[126:129], v[50:65]
	ds_read_b128 v[110:113], v0 offset:64
	ds_read_b128 v[114:117], v0 offset:4672
	ds_read_b128 v[118:121], v66 offset:18496
	ds_read_b128 v[134:137], v66 offset:23104
	s_waitcnt vmcnt(9)
	ds_write_b128 v67, v[86:89] offset:41472
	s_waitcnt vmcnt(8)
	ds_write_b128 v67, v[94:97] offset:59904
	global_load_dwordx4 v[86:89], v70, s[0:1] offset:1280
	global_load_dwordx4 v[94:97], v70, s[36:37] offset:1280
	s_waitcnt lgkmcnt(3)
	v_mfma_f32_32x32x16_bf16 v[2:17], v[114:117], v[118:121], v[2:17]
	s_waitcnt lgkmcnt(2)
	v_mfma_f32_32x32x16_bf16 v[18:33], v[114:117], v[134:137], v[18:33]
	v_mfma_f32_32x32x16_bf16 v[34:49], v[110:113], v[118:121], v[34:49]
	v_mfma_f32_32x32x16_bf16 v[50:65], v[110:113], v[134:137], v[50:65]
	ds_read_b128 v[110:113], v0 offset:96
	ds_read_b128 v[118:121], v0 offset:4704
	ds_read_b128 v[122:125], v66 offset:18528
	ds_read_b128 v[126:129], v66 offset:23136
	s_waitcnt vmcnt(9)
	ds_write_b128 v67, v[98:101] offset:46080
	s_waitcnt vmcnt(8)
	ds_write_b128 v67, v[102:105] offset:64512
	global_load_dwordx4 v[98:101], v69, s[0:1] offset:1280
	global_load_dwordx4 v[102:105], v69, s[36:37] offset:1280
	s_waitcnt lgkmcnt(3)
	v_mfma_f32_32x32x16_bf16 v[2:17], v[118:121], v[122:125], v[2:17]
	s_waitcnt vmcnt(9)
	ds_write_b128 v67, v[74:77] offset:50688
	s_waitcnt vmcnt(8)
	ds_write_b128 v68, v[106:109] offset:13824
	s_waitcnt lgkmcnt(4)
	v_mfma_f32_32x32x16_bf16 v[18:33], v[118:121], v[126:129], v[18:33]
	v_mfma_f32_32x32x16_bf16 v[34:49], v[110:113], v[122:125], v[34:49]
	v_mfma_f32_32x32x16_bf16 v[50:65], v[110:113], v[126:129], v[50:65]
	s_waitcnt lgkmcnt(0)
	s_barrier
; #define GL1_(RA, RB, i) { RA[i] = *(const u32x4*)(ap + (aoff + (i) * astep)); if ((i) < NB) RB[(i) < NB ? (i) : 0] = *(const u32x4*)(bp + (boff + (i) * bstep)); }
; #define LS1_(RA, RB, ST, i) { char* sn_ = lds + (ST) * STAGE; *(u32x4*)(sn_ + wofs + (i) * 32 * LROW) = RA[i]; \
;                               if ((i) < NB) *(u32x4*)(sn_ + STAGE_OP + wofs + (i) * 32 * LROW) = RB[(i) < NB ? (i) : 0]; }
; template <int NJ> DI void gemm_mainloop_reg(const bf16_t* __restrict__ A, int lda, const bf16_t* __restrict__ Bt, int ldb, int K, f32x16 (&acc)[2][NJ], char* lds) {
;     ...
; #pragma unroll
;   for (int i = 0; i < 4; ++i) GL1_(ra0, rb0, i);
;   ap += 128; bp += 128;
; #pragma unroll
;   for (int i = 0; i < 4; ++i) GL1_(ra1, rb1, i);
;   ap += 128; bp += 128;
; #pragma unroll
;   for (int i = 0; i < 4; ++i) LS1_(ra0, rb0, 0, i);
;   __syncthreads();
;   const int nk = K >> 6;
;   for (int kt = 0; kt < nk; kt += 2) {
;     const bool l0 = (kt + 2 < nk), l1 = (kt + 3 < nk);
;     STEP_(0, l0, ra0, rb0, true, ra1, rb1);
;     __syncthreads();
;     STEP_(1, l1, ra1, rb1, l0, ra0, rb0);
;     __syncthreads();
;   }
	ds_read_b128 v[74:77], v0 offset:36864
	ds_read_b128 v[106:109], v66 offset:55296
	ds_read_b128 v[110:113], v0 offset:36896
	ds_read_b128 v[114:117], v66 offset:55328
	ds_read_b128 v[118:121], v0 offset:41472
	ds_read_b128 v[122:125], v0 offset:41504
	s_waitcnt lgkmcnt(4)
	v_mfma_f32_32x32x16_bf16 v[34:49], v[74:77], v[106:109], v[34:49]
	s_waitcnt lgkmcnt(1)
	v_mfma_f32_32x32x16_bf16 v[2:17], v[118:121], v[106:109], v[2:17]
	ds_read_b128 v[106:109], v66 offset:59904
	ds_read_b128 v[126:129], v66 offset:59936
	s_waitcnt lgkmcnt(1)
	v_mfma_f32_32x32x16_bf16 v[50:65], v[74:77], v[106:109], v[50:65]
	global_load_dwordx4 v[74:77], v72, s[0:1] offset:1408
	global_load_dwordx4 v[134:137], v72, s[36:37] offset:1408
	s_waitcnt vmcnt(9)
	ds_write_b128 v67, v[78:81]
	s_waitcnt vmcnt(8)
	ds_write_b128 v67, v[130:133] offset:18432
	v_mfma_f32_32x32x16_bf16 v[18:33], v[118:121], v[106:109], v[18:33]
	global_load_dwordx4 v[78:81], v71, s[0:1] offset:1408
	global_load_dwordx4 v[106:109], v71, s[36:37] offset:1408
	v_mfma_f32_32x32x16_bf16 v[2:17], v[122:125], v[114:117], v[2:17]
	s_waitcnt lgkmcnt(2)
	v_mfma_f32_32x32x16_bf16 v[18:33], v[122:125], v[126:129], v[18:33]
	v_mfma_f32_32x32x16_bf16 v[34:49], v[110:113], v[114:117], v[34:49]
	v_mfma_f32_32x32x16_bf16 v[50:65], v[110:113], v[126:129], v[50:65]
	ds_read_b128 v[110:113], v0 offset:36928
	ds_read_b128 v[114:117], v0 offset:41536
	ds_read_b128 v[118:121], v66 offset:55360
	ds_read_b128 v[130:133], v66 offset:59968
	s_waitcnt vmcnt(9)
	ds_write_b128 v67, v[82:85] offset:4608
	s_waitcnt vmcnt(8)
	ds_write_b128 v67, v[90:93] offset:23040
	global_load_dwordx4 v[82:85], v70, s[0:1] offset:1408
	global_load_dwordx4 v[90:93], v70, s[36:37] offset:1408
	s_waitcnt lgkmcnt(3)
	v_mfma_f32_32x32x16_bf16 v[2:17], v[114:117], v[118:121], v[2:17]
	s_waitcnt lgkmcnt(2)
	v_mfma_f32_32x32x16_bf16 v[18:33], v[114:117], v[130:133], v[18:33]
	v_mfma_f32_32x32x16_bf16 v[34:49], v[110:113], v[118:121], v[34:49]
	v_mfma_f32_32x32x16_bf16 v[50:65], v[110:113], v[130:133], v[50:65]
	ds_read_b128 v[110:113], v0 offset:36960
	ds_read_b128 v[118:121], v0 offset:41568
	ds_read_b128 v[122:125], v66 offset:55392
	ds_read_b128 v[126:129], v66 offset:60000
	s_waitcnt vmcnt(9)
	ds_write_b128 v67, v[86:89] offset:9216
	s_waitcnt vmcnt(8)
	ds_write_b128 v67, v[94:97] offset:27648
	global_load_dwordx4 v[86:89], v69, s[0:1] offset:1408
	global_load_dwordx4 v[94:97], v69, s[36:37] offset:1408
	s_waitcnt lgkmcnt(3)
	v_mfma_f32_32x32x16_bf16 v[2:17], v[118:121], v[122:125], v[2:17]
	s_waitcnt vmcnt(9)
	ds_write_b128 v67, v[98:101] offset:13824
	s_waitcnt vmcnt(8)
	ds_write_b128 v67, v[102:105] offset:32256
	s_waitcnt lgkmcnt(4)
	v_mfma_f32_32x32x16_bf16 v[18:33], v[118:121], v[126:129], v[18:33]
	v_mfma_f32_32x32x16_bf16 v[34:49], v[110:113], v[122:125], v[34:49]
	v_mfma_f32_32x32x16_bf16 v[50:65], v[110:113], v[126:129], v[50:65]
	s_waitcnt lgkmcnt(0)
	s_barrier
	ds_read_b128 v[98:101], v0
	ds_read_b128 v[102:105], v66 offset:18432
	ds_read_b128 v[110:113], v0 offset:32
	ds_read_b128 v[114:117], v66 offset:18464
	ds_read_b128 v[118:121], v0 offset:4608
	ds_read_b128 v[122:125], v0 offset:4640
	s_waitcnt lgkmcnt(4)
	v_mfma_f32_32x32x16_bf16 v[34:49], v[98:101], v[102:105], v[34:49]
	s_waitcnt lgkmcnt(1)
	v_mfma_f32_32x32x16_bf16 v[2:17], v[118:121], v[102:105], v[2:17]
	ds_read_b128 v[102:105], v66 offset:23040
	ds_read_b128 v[126:129], v66 offset:23072
	s_waitcnt lgkmcnt(1)
	v_mfma_f32_32x32x16_bf16 v[50:65], v[98:101], v[102:105], v[50:65]
	global_load_dwordx4 v[98:101], v72, s[0:1] offset:1536
	global_load_dwordx4 v[130:133], v72, s[36:37] offset:1536
	s_waitcnt vmcnt(9)
	ds_write_b128 v67, v[74:77] offset:36864
	s_waitcnt vmcnt(8)
	ds_write_b128 v67, v[134:137] offset:55296
	v_mfma_f32_32x32x16_bf16 v[18:33], v[118:121], v[102:105], v[18:33]
	global_load_dwordx4 v[74:77], v71, s[0:1] offset:1536
	global_load_dwordx4 v[102:105], v71, s[36:37] offset:1536
	v_mfma_f32_32x32x16_bf16 v[2:17], v[122:125], v[114:117], v[2:17]
	s_waitcnt lgkmcnt(2)
	v_mfma_f32_32x32x16_bf16 v[18:33], v[122:125], v[126:129], v[18:33]
	v_mfma_f32_32x32x16_bf16 v[34:49], v[110:113], v[114:117], v[34:49]
	v_mfma_f32_32x32x16_bf16 v[50:65], v[110:113], v[126:129], v[50:65]
	ds_read_b128 v[110:113], v0 offset:64
	ds_read_b128 v[114:117], v0 offset:4672
	ds_read_b128 v[118:121], v66 offset:18496
	ds_read_b128 v[134:137], v66 offset:23104
	s_waitcnt vmcnt(9)
	ds_write_b128 v67, v[78:81] offset:41472
	s_waitcnt vmcnt(8)
	ds_write_b128 v67, v[106:109] offset:59904
	global_load_dwordx4 v[78:81], v70, s[0:1] offset:1536
	global_load_dwordx4 v[106:109], v70, s[36:37] offset:1536
	s_waitcnt lgkmcnt(3)
	v_mfma_f32_32x32x16_bf16 v[2:17], v[114:117], v[118:121], v[2:17]
	s_waitcnt lgkmcnt(2)
	v_mfma_f32_32x32x16_bf16 v[18:33], v[114:117], v[134:137], v[18:33]
	v_mfma_f32_32x32x16_bf16 v[34:49], v[110:113], v[118:121], v[34:49]
	v_mfma_f32_32x32x16_bf16 v[50:65], v[110:113], v[134:137], v[50:65]
	ds_read_b128 v[110:113], v0 offset:96
	ds_read_b128 v[118:121], v0 offset:4704
	ds_read_b128 v[122:125], v66 offset:18528
	ds_read_b128 v[126:129], v66 offset:23136
	s_waitcnt vmcnt(9)
	ds_write_b128 v67, v[82:85] offset:46080
	s_waitcnt vmcnt(8)
	ds_write_b128 v67, v[90:93] offset:64512
	global_load_dwordx4 v[82:85], v69, s[0:1] offset:1536
	global_load_dwordx4 v[90:93], v69, s[36:37] offset:1536
	s_waitcnt lgkmcnt(3)
	v_mfma_f32_32x32x16_bf16 v[2:17], v[118:121], v[122:125], v[2:17]
	s_waitcnt vmcnt(9)
	ds_write_b128 v67, v[86:89] offset:50688
	s_waitcnt vmcnt(8)
	ds_write_b128 v68, v[94:97] offset:13824
	s_waitcnt lgkmcnt(4)
	v_mfma_f32_32x32x16_bf16 v[18:33], v[118:121], v[126:129], v[18:33]
	v_mfma_f32_32x32x16_bf16 v[34:49], v[110:113], v[122:125], v[34:49]
	v_mfma_f32_32x32x16_bf16 v[50:65], v[110:113], v[126:129], v[50:65]
	s_waitcnt lgkmcnt(0)
	s_barrier
; #define GL1_(RA, RB, i) { RA[i] = *(const u32x4*)(ap + (aoff + (i) * astep)); if ((i) < NB) RB[(i) < NB ? (i) : 0] = *(const u32x4*)(bp + (boff + (i) * bstep)); }
; #define LS1_(RA, RB, ST, i) { char* sn_ = lds + (ST) * STAGE; *(u32x4*)(sn_ + wofs + (i) * 32 * LROW) = RA[i]; \
;                               if ((i) < NB) *(u32x4*)(sn_ + STAGE_OP + wofs + (i) * 32 * LROW) = RB[(i) < NB ? (i) : 0]; }
; template <int NJ> DI void gemm_mainloop_reg(const bf16_t* __restrict__ A, int lda, const bf16_t* __restrict__ Bt, int ldb, int K, f32x16 (&acc)[2][NJ], char* lds) {
;     ...
; #pragma unroll
;   for (int i = 0; i < 4; ++i) GL1_(ra0, rb0, i);
;   ap += 128; bp += 128;
; #pragma unroll
;   for (int i = 0; i < 4; ++i) GL1_(ra1, rb1, i);
;   ap += 128; bp += 128;
; #pragma unroll
;   for (int i = 0; i < 4; ++i) LS1_(ra0, rb0, 0, i);
;   __syncthreads();
;   const int nk = K >> 6;
;   for (int kt = 0; kt < nk; kt += 2) {
;     const bool l0 = (kt + 2 < nk), l1 = (kt + 3 < nk);
;     STEP_(0, l0, ra0, rb0, true, ra1, rb1);
;     __syncthreads();
;     STEP_(1, l1, ra1, rb1, l0, ra0, rb0);
;     __syncthreads();
;   }
	ds_read_b128 v[86:89], v0 offset:36864
	ds_read_b128 v[94:97], v66 offset:55296
	ds_read_b128 v[110:113], v0 offset:36896
	ds_read_b128 v[114:117], v66 offset:55328
	ds_read_b128 v[118:121], v0 offset:41472
	ds_read_b128 v[122:125], v0 offset:41504
	s_waitcnt lgkmcnt(4)
	v_mfma_f32_32x32x16_bf16 v[34:49], v[86:89], v[94:97], v[34:49]
	s_waitcnt lgkmcnt(1)
	v_mfma_f32_32x32x16_bf16 v[2:17], v[118:121], v[94:97], v[2:17]
	ds_read_b128 v[94:97], v66 offset:59904
	ds_read_b128 v[126:129], v66 offset:59936
	s_waitcnt lgkmcnt(1)
	v_mfma_f32_32x32x16_bf16 v[50:65], v[86:89], v[94:97], v[50:65]
	global_load_dwordx4 v[86:89], v72, s[0:1] offset:1664
	global_load_dwordx4 v[134:137], v72, s[36:37] offset:1664
	s_waitcnt vmcnt(9)
	ds_write_b128 v67, v[98:101]
	s_waitcnt vmcnt(8)
	ds_write_b128 v67, v[130:133] offset:18432
	v_mfma_f32_32x32x16_bf16 v[18:33], v[118:121], v[94:97], v[18:33]
	global_load_dwordx4 v[94:97], v71, s[0:1] offset:1664
	global_load_dwordx4 v[98:101], v71, s[36:37] offset:1664
	v_mfma_f32_32x32x16_bf16 v[2:17], v[122:125], v[114:117], v[2:17]
	s_waitcnt lgkmcnt(2)
	v_mfma_f32_32x32x16_bf16 v[18:33], v[122:125], v[126:129], v[18:33]
	v_mfma_f32_32x32x16_bf16 v[34:49], v[110:113], v[114:117], v[34:49]
	v_mfma_f32_32x32x16_bf16 v[50:65], v[110:113], v[126:129], v[50:65]
	ds_read_b128 v[110:113], v0 offset:36928
	ds_read_b128 v[114:117], v0 offset:41536
	ds_read_b128 v[118:121], v66 offset:55360
	ds_read_b128 v[130:133], v66 offset:59968
	s_waitcnt vmcnt(9)
	ds_write_b128 v67, v[74:77] offset:4608
	s_waitcnt vmcnt(8)
	ds_write_b128 v67, v[102:105] offset:23040
	global_load_dwordx4 v[74:77], v70, s[0:1] offset:1664
	global_load_dwordx4 v[102:105], v70, s[36:37] offset:1664
	s_waitcnt lgkmcnt(3)
	v_mfma_f32_32x32x16_bf16 v[2:17], v[114:117], v[118:121], v[2:17]
	s_waitcnt lgkmcnt(2)
	v_mfma_f32_32x32x16_bf16 v[18:33], v[114:117], v[130:133], v[18:33]
	v_mfma_f32_32x32x16_bf16 v[34:49], v[110:113], v[118:121], v[34:49]
	v_mfma_f32_32x32x16_bf16 v[50:65], v[110:113], v[130:133], v[50:65]
	ds_read_b128 v[110:113], v0 offset:36960
	ds_read_b128 v[118:121], v0 offset:41568
	ds_read_b128 v[122:125], v66 offset:55392
	ds_read_b128 v[126:129], v66 offset:60000
	s_waitcnt vmcnt(9)
	ds_write_b128 v67, v[78:81] offset:9216
	s_waitcnt vmcnt(8)
	ds_write_b128 v67, v[106:109] offset:27648
	global_load_dwordx4 v[78:81], v69, s[0:1] offset:1664
	global_load_dwordx4 v[106:109], v69, s[36:37] offset:1664
	s_waitcnt lgkmcnt(3)
	v_mfma_f32_32x32x16_bf16 v[2:17], v[118:121], v[122:125], v[2:17]
	s_waitcnt vmcnt(9)
	ds_write_b128 v67, v[82:85] offset:13824
	s_waitcnt vmcnt(8)
	ds_write_b128 v67, v[90:93] offset:32256
	s_waitcnt lgkmcnt(4)
	v_mfma_f32_32x32x16_bf16 v[18:33], v[118:121], v[126:129], v[18:33]
	v_mfma_f32_32x32x16_bf16 v[34:49], v[110:113], v[122:125], v[34:49]
	v_mfma_f32_32x32x16_bf16 v[50:65], v[110:113], v[126:129], v[50:65]
	s_waitcnt lgkmcnt(0)
	s_barrier
	ds_read_b128 v[82:85], v0
	ds_read_b128 v[90:93], v66 offset:18432
	ds_read_b128 v[110:113], v0 offset:32
	ds_read_b128 v[114:117], v66 offset:18464
	ds_read_b128 v[118:121], v0 offset:4608
	ds_read_b128 v[122:125], v0 offset:4640
	s_waitcnt lgkmcnt(4)
	v_mfma_f32_32x32x16_bf16 v[34:49], v[82:85], v[90:93], v[34:49]
	s_waitcnt lgkmcnt(1)
	v_mfma_f32_32x32x16_bf16 v[2:17], v[118:121], v[90:93], v[2:17]
	ds_read_b128 v[90:93], v66 offset:23040
	ds_read_b128 v[126:129], v66 offset:23072
	s_waitcnt lgkmcnt(1)
	v_mfma_f32_32x32x16_bf16 v[50:65], v[82:85], v[90:93], v[50:65]
	global_load_dwordx4 v[82:85], v72, s[0:1] offset:1792
	global_load_dwordx4 v[130:133], v72, s[36:37] offset:1792
	s_waitcnt vmcnt(9)
	ds_write_b128 v67, v[86:89] offset:36864
	s_waitcnt vmcnt(8)
	ds_write_b128 v67, v[134:137] offset:55296
	v_mfma_f32_32x32x16_bf16 v[18:33], v[118:121], v[90:93], v[18:33]
	global_load_dwordx4 v[86:89], v71, s[0:1] offset:1792
	global_load_dwordx4 v[90:93], v71, s[36:37] offset:1792
	v_mfma_f32_32x32x16_bf16 v[2:17], v[122:125], v[114:117], v[2:17]
	s_waitcnt lgkmcnt(2)
	v_mfma_f32_32x32x16_bf16 v[18:33], v[122:125], v[126:129], v[18:33]
	v_mfma_f32_32x32x16_bf16 v[34:49], v[110:113], v[114:117], v[34:49]
	v_mfma_f32_32x32x16_bf16 v[50:65], v[110:113], v[126:129], v[50:65]
	ds_read_b128 v[110:113], v0 offset:64
	ds_read_b128 v[114:117], v0 offset:4672
	ds_read_b128 v[118:121], v66 offset:18496
	ds_read_b128 v[134:137], v66 offset:23104
	s_waitcnt vmcnt(9)
	ds_write_b128 v67, v[94:97] offset:41472
	s_waitcnt vmcnt(8)
	ds_write_b128 v67, v[98:101] offset:59904
	global_load_dwordx4 v[94:97], v70, s[0:1] offset:1792
	global_load_dwordx4 v[98:101], v70, s[36:37] offset:1792
	s_waitcnt lgkmcnt(3)
	v_mfma_f32_32x32x16_bf16 v[2:17], v[114:117], v[118:121], v[2:17]
	s_waitcnt lgkmcnt(2)
	v_mfma_f32_32x32x16_bf16 v[18:33], v[114:117], v[134:137], v[18:33]
	v_mfma_f32_32x32x16_bf16 v[34:49], v[110:113], v[118:121], v[34:49]
	v_mfma_f32_32x32x16_bf16 v[50:65], v[110:113], v[134:137], v[50:65]
	ds_read_b128 v[110:113], v0 offset:96
	ds_read_b128 v[118:121], v0 offset:4704
	ds_read_b128 v[122:125], v66 offset:18528
	ds_read_b128 v[126:129], v66 offset:23136
	s_waitcnt vmcnt(9)
	ds_write_b128 v67, v[74:77] offset:46080
	s_waitcnt vmcnt(8)
	ds_write_b128 v67, v[102:105] offset:64512
	global_load_dwordx4 v[74:77], v69, s[0:1] offset:1792
	global_load_dwordx4 v[102:105], v69, s[36:37] offset:1792
	s_waitcnt lgkmcnt(3)
	v_mfma_f32_32x32x16_bf16 v[2:17], v[118:121], v[122:125], v[2:17]
	s_waitcnt vmcnt(9)
	ds_write_b128 v67, v[78:81] offset:50688
	s_waitcnt vmcnt(8)
	ds_write_b128 v68, v[106:109] offset:13824
	s_waitcnt lgkmcnt(4)
	v_mfma_f32_32x32x16_bf16 v[18:33], v[118:121], v[126:129], v[18:33]
	v_mfma_f32_32x32x16_bf16 v[34:49], v[110:113], v[122:125], v[34:49]
	v_mfma_f32_32x32x16_bf16 v[50:65], v[110:113], v[126:129], v[50:65]
	s_waitcnt lgkmcnt(0)
	s_barrier
; #define GL1_(RA, RB, i) { RA[i] = *(const u32x4*)(ap + (aoff + (i) * astep)); if ((i) < NB) RB[(i) < NB ? (i) : 0] = *(const u32x4*)(bp + (boff + (i) * bstep)); }
; #define LS1_(RA, RB, ST, i) { char* sn_ = lds + (ST) * STAGE; *(u32x4*)(sn_ + wofs + (i) * 32 * LROW) = RA[i]; \
;                               if ((i) < NB) *(u32x4*)(sn_ + STAGE_OP + wofs + (i) * 32 * LROW) = RB[(i) < NB ? (i) : 0]; }
; template <int NJ> DI void gemm_mainloop_reg(const bf16_t* __restrict__ A, int lda, const bf16_t* __restrict__ Bt, int ldb, int K, f32x16 (&acc)[2][NJ], char* lds) {
;     ...
; #pragma unroll
;   for (int i = 0; i < 4; ++i) GL1_(ra0, rb0, i);
;   ap += 128; bp += 128;
; #pragma unroll
;   for (int i = 0; i < 4; ++i) GL1_(ra1, rb1, i);
;   ap += 128; bp += 128;
; #pragma unroll
;   for (int i = 0; i < 4; ++i) LS1_(ra0, rb0, 0, i);
;   __syncthreads();
;   const int nk = K >> 6;
;   for (int kt = 0; kt < nk; kt += 2) {
;     const bool l0 = (kt + 2 < nk), l1 = (kt + 3 < nk);
;     STEP_(0, l0, ra0, rb0, true, ra1, rb1);
;     __syncthreads();
;     STEP_(1, l1, ra1, rb1, l0, ra0, rb0);
;     __syncthreads();
;   }
	ds_read_b128 v[78:81], v0 offset:36864
	ds_read_b128 v[106:109], v66 offset:55296
	ds_read_b128 v[110:113], v0 offset:36896
	ds_read_b128 v[114:117], v66 offset:55328
	ds_read_b128 v[118:121], v0 offset:41472
	ds_read_b128 v[122:125], v0 offset:41504
	s_waitcnt lgkmcnt(4)
	v_mfma_f32_32x32x16_bf16 v[34:49], v[78:81], v[106:109], v[34:49]
	s_waitcnt lgkmcnt(1)
	v_mfma_f32_32x32x16_bf16 v[2:17], v[118:121], v[106:109], v[2:17]
	ds_read_b128 v[106:109], v66 offset:59904
	ds_read_b128 v[126:129], v66 offset:59936
	s_waitcnt lgkmcnt(1)
	v_mfma_f32_32x32x16_bf16 v[50:65], v[78:81], v[106:109], v[50:65]
	global_load_dwordx4 v[78:81], v72, s[0:1] offset:1920
	global_load_dwordx4 v[134:137], v72, s[36:37] offset:1920
	s_waitcnt vmcnt(9)
	ds_write_b128 v67, v[82:85]
	s_waitcnt vmcnt(8)
	ds_write_b128 v67, v[130:133] offset:18432
	v_mfma_f32_32x32x16_bf16 v[18:33], v[118:121], v[106:109], v[18:33]
	global_load_dwordx4 v[82:85], v71, s[0:1] offset:1920
	global_load_dwordx4 v[106:109], v71, s[36:37] offset:1920
	v_mfma_f32_32x32x16_bf16 v[2:17], v[122:125], v[114:117], v[2:17]
	s_waitcnt lgkmcnt(2)
	v_mfma_f32_32x32x16_bf16 v[18:33], v[122:125], v[126:129], v[18:33]
	v_mfma_f32_32x32x16_bf16 v[34:49], v[110:113], v[114:117], v[34:49]
	v_mfma_f32_32x32x16_bf16 v[50:65], v[110:113], v[126:129], v[50:65]
	ds_read_b128 v[110:113], v0 offset:36928
	ds_read_b128 v[114:117], v0 offset:41536
	ds_read_b128 v[118:121], v66 offset:55360
	ds_read_b128 v[130:133], v66 offset:59968
	s_waitcnt vmcnt(9)
	ds_write_b128 v67, v[86:89] offset:4608
	s_waitcnt vmcnt(8)
	ds_write_b128 v67, v[90:93] offset:23040
	global_load_dwordx4 v[86:89], v70, s[0:1] offset:1920
	global_load_dwordx4 v[90:93], v70, s[36:37] offset:1920
	s_waitcnt lgkmcnt(3)
	v_mfma_f32_32x32x16_bf16 v[2:17], v[114:117], v[118:121], v[2:17]
	s_waitcnt lgkmcnt(2)
	v_mfma_f32_32x32x16_bf16 v[18:33], v[114:117], v[130:133], v[18:33]
	v_mfma_f32_32x32x16_bf16 v[34:49], v[110:113], v[118:121], v[34:49]
	v_mfma_f32_32x32x16_bf16 v[50:65], v[110:113], v[130:133], v[50:65]
	ds_read_b128 v[110:113], v0 offset:36960
	ds_read_b128 v[118:121], v0 offset:41568
	ds_read_b128 v[122:125], v66 offset:55392
	ds_read_b128 v[126:129], v66 offset:60000
	s_waitcnt vmcnt(9)
	ds_write_b128 v67, v[94:97] offset:9216
	s_waitcnt vmcnt(8)
	ds_write_b128 v67, v[98:101] offset:27648
	global_load_dwordx4 v[94:97], v69, s[0:1] offset:1920
	global_load_dwordx4 v[98:101], v69, s[36:37] offset:1920
	s_waitcnt lgkmcnt(3)
	v_mfma_f32_32x32x16_bf16 v[2:17], v[118:121], v[122:125], v[2:17]
	s_waitcnt vmcnt(9)
	ds_write_b128 v67, v[74:77] offset:13824
	s_waitcnt vmcnt(8)
	ds_write_b128 v67, v[102:105] offset:32256
	s_waitcnt lgkmcnt(4)
	v_mfma_f32_32x32x16_bf16 v[18:33], v[118:121], v[126:129], v[18:33]
	v_mfma_f32_32x32x16_bf16 v[34:49], v[110:113], v[122:125], v[34:49]
	v_mfma_f32_32x32x16_bf16 v[50:65], v[110:113], v[126:129], v[50:65]
	s_waitcnt lgkmcnt(0)
	s_barrier
	ds_read_b128 v[74:77], v0
	ds_read_b128 v[102:105], v66 offset:18432
	ds_read_b128 v[110:113], v0 offset:32
	ds_read_b128 v[114:117], v66 offset:18464
	ds_read_b128 v[118:121], v0 offset:4608
	ds_read_b128 v[122:125], v0 offset:4640
	s_waitcnt lgkmcnt(4)
	v_mfma_f32_32x32x16_bf16 v[34:49], v[74:77], v[102:105], v[34:49]
	s_waitcnt lgkmcnt(1)
	v_mfma_f32_32x32x16_bf16 v[2:17], v[118:121], v[102:105], v[2:17]
	ds_read_b128 v[102:105], v66 offset:23040
	ds_read_b128 v[126:129], v66 offset:23072
	s_waitcnt lgkmcnt(1)
	v_mfma_f32_32x32x16_bf16 v[50:65], v[74:77], v[102:105], v[50:65]
	global_load_dwordx4 v[74:77], v72, s[0:1] offset:2048
	global_load_dwordx4 v[130:133], v72, s[36:37] offset:2048
	s_waitcnt vmcnt(9)
	ds_write_b128 v67, v[78:81] offset:36864
	s_waitcnt vmcnt(8)
	ds_write_b128 v67, v[134:137] offset:55296
	v_mfma_f32_32x32x16_bf16 v[18:33], v[118:121], v[102:105], v[18:33]
	global_load_dwordx4 v[78:81], v71, s[0:1] offset:2048
	global_load_dwordx4 v[102:105], v71, s[36:37] offset:2048
	v_mfma_f32_32x32x16_bf16 v[2:17], v[122:125], v[114:117], v[2:17]
	s_waitcnt lgkmcnt(2)
	v_mfma_f32_32x32x16_bf16 v[18:33], v[122:125], v[126:129], v[18:33]
	v_mfma_f32_32x32x16_bf16 v[34:49], v[110:113], v[114:117], v[34:49]
	v_mfma_f32_32x32x16_bf16 v[50:65], v[110:113], v[126:129], v[50:65]
	ds_read_b128 v[110:113], v0 offset:64
	ds_read_b128 v[114:117], v0 offset:4672
	ds_read_b128 v[118:121], v66 offset:18496
	ds_read_b128 v[134:137], v66 offset:23104
	s_waitcnt vmcnt(9)
	ds_write_b128 v67, v[82:85] offset:41472
	s_waitcnt vmcnt(8)
	ds_write_b128 v67, v[106:109] offset:59904
	global_load_dwordx4 v[82:85], v70, s[0:1] offset:2048
	global_load_dwordx4 v[106:109], v70, s[36:37] offset:2048
	s_waitcnt lgkmcnt(3)
	v_mfma_f32_32x32x16_bf16 v[2:17], v[114:117], v[118:121], v[2:17]
	s_waitcnt lgkmcnt(2)
	v_mfma_f32_32x32x16_bf16 v[18:33], v[114:117], v[134:137], v[18:33]
	v_mfma_f32_32x32x16_bf16 v[34:49], v[110:113], v[118:121], v[34:49]
	v_mfma_f32_32x32x16_bf16 v[50:65], v[110:113], v[134:137], v[50:65]
	ds_read_b128 v[110:113], v0 offset:96
	ds_read_b128 v[118:121], v0 offset:4704
	ds_read_b128 v[122:125], v66 offset:18528
	ds_read_b128 v[126:129], v66 offset:23136
	s_waitcnt vmcnt(9)
	ds_write_b128 v67, v[86:89] offset:46080
	s_waitcnt vmcnt(8)
	ds_write_b128 v67, v[90:93] offset:64512
	global_load_dwordx4 v[86:89], v69, s[0:1] offset:2048
	global_load_dwordx4 v[90:93], v69, s[36:37] offset:2048
	s_waitcnt lgkmcnt(3)
	v_mfma_f32_32x32x16_bf16 v[2:17], v[118:121], v[122:125], v[2:17]
	s_waitcnt vmcnt(9)
	ds_write_b128 v67, v[94:97] offset:50688
	s_waitcnt vmcnt(8)
	ds_write_b128 v68, v[98:101] offset:13824
	s_waitcnt lgkmcnt(4)
	v_mfma_f32_32x32x16_bf16 v[18:33], v[118:121], v[126:129], v[18:33]
	v_mfma_f32_32x32x16_bf16 v[34:49], v[110:113], v[122:125], v[34:49]
	v_mfma_f32_32x32x16_bf16 v[50:65], v[110:113], v[126:129], v[50:65]
	s_waitcnt lgkmcnt(0)
	s_barrier
; #define GL1_(RA, RB, i) { RA[i] = *(const u32x4*)(ap + (aoff + (i) * astep)); if ((i) < NB) RB[(i) < NB ? (i) : 0] = *(const u32x4*)(bp + (boff + (i) * bstep)); }
; #define LS1_(RA, RB, ST, i) { char* sn_ = lds + (ST) * STAGE; *(u32x4*)(sn_ + wofs + (i) * 32 * LROW) = RA[i]; \
;                               if ((i) < NB) *(u32x4*)(sn_ + STAGE_OP + wofs + (i) * 32 * LROW) = RB[(i) < NB ? (i) : 0]; }
; template <int NJ> DI void gemm_mainloop_reg(const bf16_t* __restrict__ A, int lda, const bf16_t* __restrict__ Bt, int ldb, int K, f32x16 (&acc)[2][NJ], char* lds) {
;     ...
; #pragma unroll
;   for (int i = 0; i < 4; ++i) GL1_(ra0, rb0, i);
;   ap += 128; bp += 128;
; #pragma unroll
;   for (int i = 0; i < 4; ++i) GL1_(ra1, rb1, i);
;   ap += 128; bp += 128;
; #pragma unroll
;   for (int i = 0; i < 4; ++i) LS1_(ra0, rb0, 0, i);
;   __syncthreads();
;   const int nk = K >> 6;
;   for (int kt = 0; kt < nk; kt += 2) {
;     const bool l0 = (kt + 2 < nk), l1 = (kt + 3 < nk);
;     STEP_(0, l0, ra0, rb0, true, ra1, rb1);
;     __syncthreads();
;     STEP_(1, l1, ra1, rb1, l0, ra0, rb0);
;     __syncthreads();
;   }
	ds_read_b128 v[94:97], v0 offset:36864
	ds_read_b128 v[98:101], v66 offset:55296
	ds_read_b128 v[110:113], v0 offset:36896
	ds_read_b128 v[114:117], v66 offset:55328
	ds_read_b128 v[118:121], v0 offset:41472
	ds_read_b128 v[122:125], v0 offset:41504
	s_waitcnt lgkmcnt(4)
	v_mfma_f32_32x32x16_bf16 v[34:49], v[94:97], v[98:101], v[34:49]
	s_waitcnt lgkmcnt(1)
	v_mfma_f32_32x32x16_bf16 v[2:17], v[118:121], v[98:101], v[2:17]
	ds_read_b128 v[98:101], v66 offset:59904
	ds_read_b128 v[126:129], v66 offset:59936
	s_waitcnt lgkmcnt(1)
	v_mfma_f32_32x32x16_bf16 v[50:65], v[94:97], v[98:101], v[50:65]
	global_load_dwordx4 v[94:97], v72, s[0:1] offset:2176
	global_load_dwordx4 v[134:137], v72, s[36:37] offset:2176
	s_waitcnt vmcnt(9)
	ds_write_b128 v67, v[74:77]
	s_waitcnt vmcnt(8)
	ds_write_b128 v67, v[130:133] offset:18432
	v_mfma_f32_32x32x16_bf16 v[18:33], v[118:121], v[98:101], v[18:33]
	global_load_dwordx4 v[74:77], v71, s[0:1] offset:2176
	global_load_dwordx4 v[98:101], v71, s[36:37] offset:2176
	v_mfma_f32_32x32x16_bf16 v[2:17], v[122:125], v[114:117], v[2:17]
	s_waitcnt lgkmcnt(2)
	v_mfma_f32_32x32x16_bf16 v[18:33], v[122:125], v[126:129], v[18:33]
	v_mfma_f32_32x32x16_bf16 v[34:49], v[110:113], v[114:117], v[34:49]
	v_mfma_f32_32x32x16_bf16 v[50:65], v[110:113], v[126:129], v[50:65]
	ds_read_b128 v[110:113], v0 offset:36928
	ds_read_b128 v[114:117], v0 offset:41536
	ds_read_b128 v[118:121], v66 offset:55360
	ds_read_b128 v[130:133], v66 offset:59968
	s_waitcnt vmcnt(9)
	ds_write_b128 v67, v[78:81] offset:4608
	s_waitcnt vmcnt(8)
	ds_write_b128 v67, v[102:105] offset:23040
	global_load_dwordx4 v[78:81], v70, s[0:1] offset:2176
	global_load_dwordx4 v[102:105], v70, s[36:37] offset:2176
	s_waitcnt lgkmcnt(3)
	v_mfma_f32_32x32x16_bf16 v[2:17], v[114:117], v[118:121], v[2:17]
	s_waitcnt lgkmcnt(2)
	v_mfma_f32_32x32x16_bf16 v[18:33], v[114:117], v[130:133], v[18:33]
	v_mfma_f32_32x32x16_bf16 v[34:49], v[110:113], v[118:121], v[34:49]
	v_mfma_f32_32x32x16_bf16 v[50:65], v[110:113], v[130:133], v[50:65]
	ds_read_b128 v[110:113], v0 offset:36960
	ds_read_b128 v[118:121], v0 offset:41568
	ds_read_b128 v[122:125], v66 offset:55392
	ds_read_b128 v[126:129], v66 offset:60000
	s_waitcnt vmcnt(9)
	ds_write_b128 v67, v[82:85] offset:9216
	s_waitcnt vmcnt(8)
	ds_write_b128 v67, v[106:109] offset:27648
	global_load_dwordx4 v[82:85], v69, s[0:1] offset:2176
	global_load_dwordx4 v[106:109], v69, s[36:37] offset:2176
	s_waitcnt lgkmcnt(3)
	v_mfma_f32_32x32x16_bf16 v[2:17], v[118:121], v[122:125], v[2:17]
	s_waitcnt vmcnt(9)
	ds_write_b128 v67, v[86:89] offset:13824
	s_waitcnt vmcnt(8)
	ds_write_b128 v67, v[90:93] offset:32256
	s_waitcnt lgkmcnt(4)
	v_mfma_f32_32x32x16_bf16 v[18:33], v[118:121], v[126:129], v[18:33]
	v_mfma_f32_32x32x16_bf16 v[34:49], v[110:113], v[122:125], v[34:49]
	v_mfma_f32_32x32x16_bf16 v[50:65], v[110:113], v[126:129], v[50:65]
	s_waitcnt lgkmcnt(0)
	s_barrier
	ds_read_b128 v[86:89], v0
	ds_read_b128 v[90:93], v66 offset:18432
	ds_read_b128 v[110:113], v0 offset:32
	ds_read_b128 v[114:117], v66 offset:18464
	ds_read_b128 v[118:121], v0 offset:4608
	ds_read_b128 v[122:125], v0 offset:4640
	s_waitcnt lgkmcnt(4)
	v_mfma_f32_32x32x16_bf16 v[34:49], v[86:89], v[90:93], v[34:49]
	s_waitcnt lgkmcnt(1)
	v_mfma_f32_32x32x16_bf16 v[2:17], v[118:121], v[90:93], v[2:17]
	ds_read_b128 v[90:93], v66 offset:23040
	ds_read_b128 v[126:129], v66 offset:23072
	s_waitcnt lgkmcnt(1)
	v_mfma_f32_32x32x16_bf16 v[50:65], v[86:89], v[90:93], v[50:65]
	global_load_dwordx4 v[86:89], v72, s[0:1] offset:2304
	global_load_dwordx4 v[130:133], v72, s[36:37] offset:2304
	s_waitcnt vmcnt(9)
	ds_write_b128 v67, v[94:97] offset:36864
	s_waitcnt vmcnt(8)
	ds_write_b128 v67, v[134:137] offset:55296
	v_mfma_f32_32x32x16_bf16 v[18:33], v[118:121], v[90:93], v[18:33]
	global_load_dwordx4 v[90:93], v71, s[0:1] offset:2304
	global_load_dwordx4 v[94:97], v71, s[36:37] offset:2304
	v_mfma_f32_32x32x16_bf16 v[2:17], v[122:125], v[114:117], v[2:17]
	s_waitcnt lgkmcnt(2)
	v_mfma_f32_32x32x16_bf16 v[18:33], v[122:125], v[126:129], v[18:33]
	v_mfma_f32_32x32x16_bf16 v[34:49], v[110:113], v[114:117], v[34:49]
	v_mfma_f32_32x32x16_bf16 v[50:65], v[110:113], v[126:129], v[50:65]
	ds_read_b128 v[110:113], v0 offset:64
	ds_read_b128 v[114:117], v0 offset:4672
	ds_read_b128 v[118:121], v66 offset:18496
	ds_read_b128 v[134:137], v66 offset:23104
	s_waitcnt vmcnt(9)
	ds_write_b128 v67, v[74:77] offset:41472
	s_waitcnt vmcnt(8)
	ds_write_b128 v67, v[98:101] offset:59904
	global_load_dwordx4 v[74:77], v70, s[0:1] offset:2304
	global_load_dwordx4 v[98:101], v70, s[36:37] offset:2304
	s_waitcnt lgkmcnt(3)
	v_mfma_f32_32x32x16_bf16 v[2:17], v[114:117], v[118:121], v[2:17]
	s_waitcnt lgkmcnt(2)
	v_mfma_f32_32x32x16_bf16 v[18:33], v[114:117], v[134:137], v[18:33]
	v_mfma_f32_32x32x16_bf16 v[34:49], v[110:113], v[118:121], v[34:49]
	v_mfma_f32_32x32x16_bf16 v[50:65], v[110:113], v[134:137], v[50:65]
	ds_read_b128 v[110:113], v0 offset:96
	ds_read_b128 v[118:121], v0 offset:4704
	ds_read_b128 v[122:125], v66 offset:18528
	ds_read_b128 v[126:129], v66 offset:23136
	s_waitcnt vmcnt(9)
	ds_write_b128 v67, v[78:81] offset:46080
	s_waitcnt vmcnt(8)
	ds_write_b128 v67, v[102:105] offset:64512
	global_load_dwordx4 v[78:81], v69, s[0:1] offset:2304
	global_load_dwordx4 v[102:105], v69, s[36:37] offset:2304
	s_waitcnt lgkmcnt(3)
	v_mfma_f32_32x32x16_bf16 v[2:17], v[118:121], v[122:125], v[2:17]
	s_waitcnt vmcnt(9)
	ds_write_b128 v67, v[82:85] offset:50688
	s_waitcnt vmcnt(8)
	ds_write_b128 v68, v[106:109] offset:13824
	s_waitcnt lgkmcnt(4)
	v_mfma_f32_32x32x16_bf16 v[18:33], v[118:121], v[126:129], v[18:33]
	v_mfma_f32_32x32x16_bf16 v[34:49], v[110:113], v[122:125], v[34:49]
	v_mfma_f32_32x32x16_bf16 v[50:65], v[110:113], v[126:129], v[50:65]
	s_waitcnt lgkmcnt(0)
	s_barrier
; #define GL1_(RA, RB, i) { RA[i] = *(const u32x4*)(ap + (aoff + (i) * astep)); if ((i) < NB) RB[(i) < NB ? (i) : 0] = *(const u32x4*)(bp + (boff + (i) * bstep)); }
; #define LS1_(RA, RB, ST, i) { char* sn_ = lds + (ST) * STAGE; *(u32x4*)(sn_ + wofs + (i) * 32 * LROW) = RA[i]; \
;                               if ((i) < NB) *(u32x4*)(sn_ + STAGE_OP + wofs + (i) * 32 * LROW) = RB[(i) < NB ? (i) : 0]; }
; template <int NJ> DI void gemm_mainloop_reg(const bf16_t* __restrict__ A, int lda, const bf16_t* __restrict__ Bt, int ldb, int K, f32x16 (&acc)[2][NJ], char* lds) {
;     ...
; #pragma unroll
;   for (int i = 0; i < 4; ++i) GL1_(ra0, rb0, i);
;   ap += 128; bp += 128;
; #pragma unroll
;   for (int i = 0; i < 4; ++i) GL1_(ra1, rb1, i);
;   ap += 128; bp += 128;
; #pragma unroll
;   for (int i = 0; i < 4; ++i) LS1_(ra0, rb0, 0, i);
;   __syncthreads();
;   const int nk = K >> 6;
;   for (int kt = 0; kt < nk; kt += 2) {
;     const bool l0 = (kt + 2 < nk), l1 = (kt + 3 < nk);
;     STEP_(0, l0, ra0, rb0, true, ra1, rb1);
;     __syncthreads();
;     STEP_(1, l1, ra1, rb1, l0, ra0, rb0);
;     __syncthreads();
;   }
	ds_read_b128 v[82:85], v0 offset:36864
	ds_read_b128 v[106:109], v66 offset:55296
	ds_read_b128 v[110:113], v0 offset:36896
	ds_read_b128 v[114:117], v66 offset:55328
	ds_read_b128 v[118:121], v0 offset:41472
	ds_read_b128 v[122:125], v0 offset:41504
	s_waitcnt lgkmcnt(4)
	v_mfma_f32_32x32x16_bf16 v[34:49], v[82:85], v[106:109], v[34:49]
	s_waitcnt lgkmcnt(1)
	v_mfma_f32_32x32x16_bf16 v[2:17], v[118:121], v[106:109], v[2:17]
	ds_read_b128 v[106:109], v66 offset:59904
	ds_read_b128 v[126:129], v66 offset:59936
	s_waitcnt lgkmcnt(1)
	v_mfma_f32_32x32x16_bf16 v[50:65], v[82:85], v[106:109], v[50:65]
	global_load_dwordx4 v[82:85], v72, s[0:1] offset:2432
	global_load_dwordx4 v[134:137], v72, s[36:37] offset:2432
	s_waitcnt vmcnt(9)
	ds_write_b128 v67, v[86:89]
	s_waitcnt vmcnt(8)
	ds_write_b128 v67, v[130:133] offset:18432
	v_mfma_f32_32x32x16_bf16 v[18:33], v[118:121], v[106:109], v[18:33]
	global_load_dwordx4 v[86:89], v71, s[0:1] offset:2432
	global_load_dwordx4 v[106:109], v71, s[36:37] offset:2432
	v_mfma_f32_32x32x16_bf16 v[2:17], v[122:125], v[114:117], v[2:17]
	s_waitcnt lgkmcnt(2)
	v_mfma_f32_32x32x16_bf16 v[18:33], v[122:125], v[126:129], v[18:33]
	v_mfma_f32_32x32x16_bf16 v[34:49], v[110:113], v[114:117], v[34:49]
	v_mfma_f32_32x32x16_bf16 v[50:65], v[110:113], v[126:129], v[50:65]
	ds_read_b128 v[110:113], v0 offset:36928
	ds_read_b128 v[114:117], v0 offset:41536
	ds_read_b128 v[118:121], v66 offset:55360
	ds_read_b128 v[130:133], v66 offset:59968
	s_waitcnt vmcnt(9)
	ds_write_b128 v67, v[90:93] offset:4608
	s_waitcnt vmcnt(8)
	ds_write_b128 v67, v[94:97] offset:23040
	global_load_dwordx4 v[90:93], v70, s[0:1] offset:2432
	global_load_dwordx4 v[94:97], v70, s[36:37] offset:2432
	s_waitcnt lgkmcnt(3)
	v_mfma_f32_32x32x16_bf16 v[2:17], v[114:117], v[118:121], v[2:17]
	s_waitcnt lgkmcnt(2)
	v_mfma_f32_32x32x16_bf16 v[18:33], v[114:117], v[130:133], v[18:33]
	v_mfma_f32_32x32x16_bf16 v[34:49], v[110:113], v[118:121], v[34:49]
	v_mfma_f32_32x32x16_bf16 v[50:65], v[110:113], v[130:133], v[50:65]
	ds_read_b128 v[110:113], v0 offset:36960
	ds_read_b128 v[118:121], v0 offset:41568
	ds_read_b128 v[122:125], v66 offset:55392
	ds_read_b128 v[126:129], v66 offset:60000
	s_waitcnt vmcnt(9)
	ds_write_b128 v67, v[74:77] offset:9216
	s_waitcnt vmcnt(8)
	ds_write_b128 v67, v[98:101] offset:27648
	global_load_dwordx4 v[74:77], v69, s[0:1] offset:2432
	global_load_dwordx4 v[98:101], v69, s[36:37] offset:2432
	s_waitcnt lgkmcnt(3)
	v_mfma_f32_32x32x16_bf16 v[2:17], v[118:121], v[122:125], v[2:17]
	s_waitcnt vmcnt(9)
	ds_write_b128 v67, v[78:81] offset:13824
	s_waitcnt vmcnt(8)
	ds_write_b128 v67, v[102:105] offset:32256
	s_waitcnt lgkmcnt(4)
	v_mfma_f32_32x32x16_bf16 v[18:33], v[118:121], v[126:129], v[18:33]
	v_mfma_f32_32x32x16_bf16 v[34:49], v[110:113], v[122:125], v[34:49]
	v_mfma_f32_32x32x16_bf16 v[50:65], v[110:113], v[126:129], v[50:65]
	s_waitcnt lgkmcnt(0)
	s_barrier
	ds_read_b128 v[78:81], v0
	ds_read_b128 v[102:105], v66 offset:18432
	ds_read_b128 v[110:113], v0 offset:32
	ds_read_b128 v[114:117], v66 offset:18464
	ds_read_b128 v[118:121], v0 offset:4608
	ds_read_b128 v[122:125], v0 offset:4640
	s_waitcnt lgkmcnt(4)
	v_mfma_f32_32x32x16_bf16 v[34:49], v[78:81], v[102:105], v[34:49]
	s_waitcnt lgkmcnt(1)
	v_mfma_f32_32x32x16_bf16 v[2:17], v[118:121], v[102:105], v[2:17]
	ds_read_b128 v[102:105], v66 offset:23040
	ds_read_b128 v[126:129], v66 offset:23072
	s_waitcnt lgkmcnt(1)
	v_mfma_f32_32x32x16_bf16 v[50:65], v[78:81], v[102:105], v[50:65]
	global_load_dwordx4 v[78:81], v72, s[0:1] offset:2560
	global_load_dwordx4 v[130:133], v72, s[36:37] offset:2560
	s_waitcnt vmcnt(9)
	ds_write_b128 v67, v[82:85] offset:36864
	s_waitcnt vmcnt(8)
	ds_write_b128 v67, v[134:137] offset:55296
	v_mfma_f32_32x32x16_bf16 v[18:33], v[118:121], v[102:105], v[18:33]
	global_load_dwordx4 v[82:85], v71, s[0:1] offset:2560
	global_load_dwordx4 v[102:105], v71, s[36:37] offset:2560
	v_mfma_f32_32x32x16_bf16 v[2:17], v[122:125], v[114:117], v[2:17]
	s_waitcnt lgkmcnt(2)
	v_mfma_f32_32x32x16_bf16 v[18:33], v[122:125], v[126:129], v[18:33]
	v_mfma_f32_32x32x16_bf16 v[34:49], v[110:113], v[114:117], v[34:49]
	v_mfma_f32_32x32x16_bf16 v[50:65], v[110:113], v[126:129], v[50:65]
	ds_read_b128 v[110:113], v0 offset:64
	ds_read_b128 v[114:117], v0 offset:4672
	ds_read_b128 v[118:121], v66 offset:18496
	ds_read_b128 v[134:137], v66 offset:23104
	s_waitcnt vmcnt(9)
	ds_write_b128 v67, v[86:89] offset:41472
	s_waitcnt vmcnt(8)
	ds_write_b128 v67, v[106:109] offset:59904
	global_load_dwordx4 v[86:89], v70, s[0:1] offset:2560
	global_load_dwordx4 v[106:109], v70, s[36:37] offset:2560
	s_waitcnt lgkmcnt(3)
	v_mfma_f32_32x32x16_bf16 v[2:17], v[114:117], v[118:121], v[2:17]
	s_waitcnt lgkmcnt(2)
	v_mfma_f32_32x32x16_bf16 v[18:33], v[114:117], v[134:137], v[18:33]
	v_mfma_f32_32x32x16_bf16 v[34:49], v[110:113], v[118:121], v[34:49]
	v_mfma_f32_32x32x16_bf16 v[50:65], v[110:113], v[134:137], v[50:65]
	ds_read_b128 v[110:113], v0 offset:96
	ds_read_b128 v[118:121], v0 offset:4704
	ds_read_b128 v[122:125], v66 offset:18528
	ds_read_b128 v[126:129], v66 offset:23136
	s_waitcnt vmcnt(9)
	ds_write_b128 v67, v[90:93] offset:46080
	s_waitcnt vmcnt(8)
	ds_write_b128 v67, v[94:97] offset:64512
	global_load_dwordx4 v[90:93], v69, s[0:1] offset:2560
	global_load_dwordx4 v[94:97], v69, s[36:37] offset:2560
	s_waitcnt lgkmcnt(3)
	v_mfma_f32_32x32x16_bf16 v[2:17], v[118:121], v[122:125], v[2:17]
	s_waitcnt vmcnt(9)
	ds_write_b128 v67, v[74:77] offset:50688
	s_waitcnt vmcnt(8)
	ds_write_b128 v68, v[98:101] offset:13824
	s_waitcnt lgkmcnt(4)
	v_mfma_f32_32x32x16_bf16 v[18:33], v[118:121], v[126:129], v[18:33]
	v_mfma_f32_32x32x16_bf16 v[34:49], v[110:113], v[122:125], v[34:49]
	v_mfma_f32_32x32x16_bf16 v[50:65], v[110:113], v[126:129], v[50:65]
	s_waitcnt lgkmcnt(0)
	s_barrier
; #define GL1_(RA, RB, i) { RA[i] = *(const u32x4*)(ap + (aoff + (i) * astep)); if ((i) < NB) RB[(i) < NB ? (i) : 0] = *(const u32x4*)(bp + (boff + (i) * bstep)); }
; #define LS1_(RA, RB, ST, i) { char* sn_ = lds + (ST) * STAGE; *(u32x4*)(sn_ + wofs + (i) * 32 * LROW) = RA[i]; \
;                               if ((i) < NB) *(u32x4*)(sn_ + STAGE_OP + wofs + (i) * 32 * LROW) = RB[(i) < NB ? (i) : 0]; }
; template <int NJ> DI void gemm_mainloop_reg(const bf16_t* __restrict__ A, int lda, const bf16_t* __restrict__ Bt, int ldb, int K, f32x16 (&acc)[2][NJ], char* lds) {
;     ...
; #pragma unroll
;   for (int i = 0; i < 4; ++i) GL1_(ra0, rb0, i);
;   ap += 128; bp += 128;
; #pragma unroll
;   for (int i = 0; i < 4; ++i) GL1_(ra1, rb1, i);
;   ap += 128; bp += 128;
; #pragma unroll
;   for (int i = 0; i < 4; ++i) LS1_(ra0, rb0, 0, i);
;   __syncthreads();
;   const int nk = K >> 6;
;   for (int kt = 0; kt < nk; kt += 2) {
;     const bool l0 = (kt + 2 < nk), l1 = (kt + 3 < nk);
;     STEP_(0, l0, ra0, rb0, true, ra1, rb1);
;     __syncthreads();
;     STEP_(1, l1, ra1, rb1, l0, ra0, rb0);
;     __syncthreads();
;   }
	ds_read_b128 v[74:77], v0 offset:36864
	ds_read_b128 v[98:101], v66 offset:55296
	ds_read_b128 v[110:113], v0 offset:36896
	ds_read_b128 v[114:117], v66 offset:55328
	ds_read_b128 v[118:121], v0 offset:41472
	ds_read_b128 v[122:125], v0 offset:41504
	s_waitcnt lgkmcnt(4)
	v_mfma_f32_32x32x16_bf16 v[34:49], v[74:77], v[98:101], v[34:49]
	s_waitcnt lgkmcnt(1)
	v_mfma_f32_32x32x16_bf16 v[2:17], v[118:121], v[98:101], v[2:17]
	ds_read_b128 v[98:101], v66 offset:59904
	ds_read_b128 v[126:129], v66 offset:59936
	s_waitcnt lgkmcnt(1)
	v_mfma_f32_32x32x16_bf16 v[50:65], v[74:77], v[98:101], v[50:65]
	global_load_dwordx4 v[74:77], v72, s[0:1] offset:2688
	global_load_dwordx4 v[134:137], v72, s[36:37] offset:2688
	s_waitcnt vmcnt(9)
	ds_write_b128 v67, v[78:81]
	s_waitcnt vmcnt(8)
	ds_write_b128 v67, v[130:133] offset:18432
	v_mfma_f32_32x32x16_bf16 v[18:33], v[118:121], v[98:101], v[18:33]
	global_load_dwordx4 v[78:81], v71, s[0:1] offset:2688
	global_load_dwordx4 v[98:101], v71, s[36:37] offset:2688
	v_mfma_f32_32x32x16_bf16 v[2:17], v[122:125], v[114:117], v[2:17]
	s_waitcnt lgkmcnt(2)
	v_mfma_f32_32x32x16_bf16 v[18:33], v[122:125], v[126:129], v[18:33]
	v_mfma_f32_32x32x16_bf16 v[34:49], v[110:113], v[114:117], v[34:49]
	v_mfma_f32_32x32x16_bf16 v[50:65], v[110:113], v[126:129], v[50:65]
	ds_read_b128 v[110:113], v0 offset:36928
	ds_read_b128 v[114:117], v0 offset:41536
	ds_read_b128 v[118:121], v66 offset:55360
	ds_read_b128 v[130:133], v66 offset:59968
	s_waitcnt vmcnt(9)
	ds_write_b128 v67, v[82:85] offset:4608
	s_waitcnt vmcnt(8)
	ds_write_b128 v67, v[102:105] offset:23040
	global_load_dwordx4 v[82:85], v70, s[0:1] offset:2688
	global_load_dwordx4 v[102:105], v70, s[36:37] offset:2688
	s_waitcnt lgkmcnt(3)
	v_mfma_f32_32x32x16_bf16 v[2:17], v[114:117], v[118:121], v[2:17]
	s_waitcnt lgkmcnt(2)
	v_mfma_f32_32x32x16_bf16 v[18:33], v[114:117], v[130:133], v[18:33]
	v_mfma_f32_32x32x16_bf16 v[34:49], v[110:113], v[118:121], v[34:49]
	v_mfma_f32_32x32x16_bf16 v[50:65], v[110:113], v[130:133], v[50:65]
	ds_read_b128 v[110:113], v0 offset:36960
	ds_read_b128 v[118:121], v0 offset:41568
	ds_read_b128 v[122:125], v66 offset:55392
	ds_read_b128 v[126:129], v66 offset:60000
	s_waitcnt vmcnt(9)
	ds_write_b128 v67, v[86:89] offset:9216
	s_waitcnt vmcnt(8)
	ds_write_b128 v67, v[106:109] offset:27648
	global_load_dwordx4 v[86:89], v69, s[0:1] offset:2688
	global_load_dwordx4 v[106:109], v69, s[36:37] offset:2688
	s_waitcnt lgkmcnt(3)
	v_mfma_f32_32x32x16_bf16 v[2:17], v[118:121], v[122:125], v[2:17]
	s_waitcnt vmcnt(9)
	ds_write_b128 v67, v[90:93] offset:13824
	s_waitcnt vmcnt(8)
	ds_write_b128 v67, v[94:97] offset:32256
	s_waitcnt lgkmcnt(4)
	v_mfma_f32_32x32x16_bf16 v[18:33], v[118:121], v[126:129], v[18:33]
	v_mfma_f32_32x32x16_bf16 v[34:49], v[110:113], v[122:125], v[34:49]
	v_mfma_f32_32x32x16_bf16 v[50:65], v[110:113], v[126:129], v[50:65]
	s_waitcnt lgkmcnt(0)
	s_barrier
	ds_read_b128 v[90:93], v0
	ds_read_b128 v[94:97], v66 offset:18432
	ds_read_b128 v[110:113], v0 offset:32
	ds_read_b128 v[114:117], v66 offset:18464
	ds_read_b128 v[118:121], v0 offset:4608
	ds_read_b128 v[122:125], v0 offset:4640
	s_waitcnt lgkmcnt(4)
	v_mfma_f32_32x32x16_bf16 v[34:49], v[90:93], v[94:97], v[34:49]
	s_waitcnt lgkmcnt(1)
	v_mfma_f32_32x32x16_bf16 v[2:17], v[118:121], v[94:97], v[2:17]
	ds_read_b128 v[94:97], v66 offset:23040
	ds_read_b128 v[126:129], v66 offset:23072
	s_waitcnt lgkmcnt(1)
	v_mfma_f32_32x32x16_bf16 v[50:65], v[90:93], v[94:97], v[50:65]
	global_load_dwordx4 v[90:93], v72, s[0:1] offset:2816
	global_load_dwordx4 v[130:133], v72, s[36:37] offset:2816
	s_waitcnt vmcnt(9)
	ds_write_b128 v67, v[74:77] offset:36864
	s_waitcnt vmcnt(8)
	ds_write_b128 v67, v[134:137] offset:55296
	v_mfma_f32_32x32x16_bf16 v[18:33], v[118:121], v[94:97], v[18:33]
	global_load_dwordx4 v[74:77], v71, s[0:1] offset:2816
	global_load_dwordx4 v[94:97], v71, s[36:37] offset:2816
	v_mfma_f32_32x32x16_bf16 v[2:17], v[122:125], v[114:117], v[2:17]
	s_waitcnt lgkmcnt(2)
	v_mfma_f32_32x32x16_bf16 v[18:33], v[122:125], v[126:129], v[18:33]
	v_mfma_f32_32x32x16_bf16 v[34:49], v[110:113], v[114:117], v[34:49]
	v_mfma_f32_32x32x16_bf16 v[50:65], v[110:113], v[126:129], v[50:65]
	ds_read_b128 v[110:113], v0 offset:64
	ds_read_b128 v[114:117], v0 offset:4672
	ds_read_b128 v[118:121], v66 offset:18496
	ds_read_b128 v[134:137], v66 offset:23104
	s_waitcnt vmcnt(9)
	ds_write_b128 v67, v[78:81] offset:41472
	s_waitcnt vmcnt(8)
	ds_write_b128 v67, v[98:101] offset:59904
	global_load_dwordx4 v[78:81], v70, s[0:1] offset:2816
	global_load_dwordx4 v[98:101], v70, s[36:37] offset:2816
	s_waitcnt lgkmcnt(3)
	v_mfma_f32_32x32x16_bf16 v[2:17], v[114:117], v[118:121], v[2:17]
	s_waitcnt lgkmcnt(2)
	v_mfma_f32_32x32x16_bf16 v[18:33], v[114:117], v[134:137], v[18:33]
	v_mfma_f32_32x32x16_bf16 v[34:49], v[110:113], v[118:121], v[34:49]
	v_mfma_f32_32x32x16_bf16 v[50:65], v[110:113], v[134:137], v[50:65]
	ds_read_b128 v[110:113], v0 offset:96
	ds_read_b128 v[118:121], v0 offset:4704
	ds_read_b128 v[122:125], v66 offset:18528
	ds_read_b128 v[126:129], v66 offset:23136
	s_waitcnt vmcnt(9)
	ds_write_b128 v67, v[82:85] offset:46080
	s_waitcnt vmcnt(8)
	ds_write_b128 v67, v[102:105] offset:64512
	global_load_dwordx4 v[82:85], v69, s[0:1] offset:2816
	global_load_dwordx4 v[102:105], v69, s[36:37] offset:2816
	s_waitcnt lgkmcnt(3)
	v_mfma_f32_32x32x16_bf16 v[2:17], v[118:121], v[122:125], v[2:17]
	s_waitcnt vmcnt(9)
	ds_write_b128 v67, v[86:89] offset:50688
	s_waitcnt vmcnt(8)
	ds_write_b128 v68, v[106:109] offset:13824
	s_waitcnt lgkmcnt(4)
	v_mfma_f32_32x32x16_bf16 v[18:33], v[118:121], v[126:129], v[18:33]
	v_mfma_f32_32x32x16_bf16 v[34:49], v[110:113], v[122:125], v[34:49]
	v_mfma_f32_32x32x16_bf16 v[50:65], v[110:113], v[126:129], v[50:65]
	s_waitcnt lgkmcnt(0)
	s_barrier
; #define GL1_(RA, RB, i) { RA[i] = *(const u32x4*)(ap + (aoff + (i) * astep)); if ((i) < NB) RB[(i) < NB ? (i) : 0] = *(const u32x4*)(bp + (boff + (i) * bstep)); }
; #define LS1_(RA, RB, ST, i) { char* sn_ = lds + (ST) * STAGE; *(u32x4*)(sn_ + wofs + (i) * 32 * LROW) = RA[i]; \
;                               if ((i) < NB) *(u32x4*)(sn_ + STAGE_OP + wofs + (i) * 32 * LROW) = RB[(i) < NB ? (i) : 0]; }
; template <int NJ> DI void gemm_mainloop_reg(const bf16_t* __restrict__ A, int lda, const bf16_t* __restrict__ Bt, int ldb, int K, f32x16 (&acc)[2][NJ], char* lds) {
;     ...
; #pragma unroll
;   for (int i = 0; i < 4; ++i) GL1_(ra0, rb0, i);
;   ap += 128; bp += 128;
; #pragma unroll
;   for (int i = 0; i < 4; ++i) GL1_(ra1, rb1, i);
;   ap += 128; bp += 128;
; #pragma unroll
;   for (int i = 0; i < 4; ++i) LS1_(ra0, rb0, 0, i);
;   __syncthreads();
;   const int nk = K >> 6;
;   for (int kt = 0; kt < nk; kt += 2) {
;     const bool l0 = (kt + 2 < nk), l1 = (kt + 3 < nk);
;     STEP_(0, l0, ra0, rb0, true, ra1, rb1);
;     __syncthreads();
;     STEP_(1, l1, ra1, rb1, l0, ra0, rb0);
;     __syncthreads();
;   }
	ds_read_b128 v[86:89], v0 offset:36864
	ds_read_b128 v[106:109], v66 offset:55296
	ds_read_b128 v[110:113], v0 offset:36896
	ds_read_b128 v[114:117], v66 offset:55328
	ds_read_b128 v[118:121], v0 offset:41472
	ds_read_b128 v[122:125], v0 offset:41504
	s_waitcnt lgkmcnt(4)
	v_mfma_f32_32x32x16_bf16 v[34:49], v[86:89], v[106:109], v[34:49]
	s_waitcnt lgkmcnt(1)
	v_mfma_f32_32x32x16_bf16 v[2:17], v[118:121], v[106:109], v[2:17]
	ds_read_b128 v[106:109], v66 offset:59904
	ds_read_b128 v[126:129], v66 offset:59936
	s_waitcnt lgkmcnt(1)
	v_mfma_f32_32x32x16_bf16 v[50:65], v[86:89], v[106:109], v[50:65]
	global_load_dwordx4 v[86:89], v72, s[0:1] offset:2944
	global_load_dwordx4 v[134:137], v72, s[36:37] offset:2944
	s_waitcnt vmcnt(9)
	ds_write_b128 v67, v[90:93]
	s_waitcnt vmcnt(8)
	ds_write_b128 v67, v[130:133] offset:18432
	v_mfma_f32_32x32x16_bf16 v[18:33], v[118:121], v[106:109], v[18:33]
	global_load_dwordx4 v[90:93], v71, s[0:1] offset:2944
	global_load_dwordx4 v[106:109], v71, s[36:37] offset:2944
	v_mfma_f32_32x32x16_bf16 v[2:17], v[122:125], v[114:117], v[2:17]
	s_waitcnt lgkmcnt(2)
	v_mfma_f32_32x32x16_bf16 v[18:33], v[122:125], v[126:129], v[18:33]
	v_mfma_f32_32x32x16_bf16 v[34:49], v[110:113], v[114:117], v[34:49]
	v_mfma_f32_32x32x16_bf16 v[50:65], v[110:113], v[126:129], v[50:65]
	ds_read_b128 v[110:113], v0 offset:36928
	ds_read_b128 v[114:117], v0 offset:41536
	ds_read_b128 v[118:121], v66 offset:55360
	ds_read_b128 v[130:133], v66 offset:59968
	s_waitcnt vmcnt(9)
	ds_write_b128 v67, v[74:77] offset:4608
	s_waitcnt vmcnt(8)
	ds_write_b128 v67, v[94:97] offset:23040
	global_load_dwordx4 v[74:77], v70, s[0:1] offset:2944
	global_load_dwordx4 v[94:97], v70, s[36:37] offset:2944
	s_waitcnt lgkmcnt(3)
	v_mfma_f32_32x32x16_bf16 v[2:17], v[114:117], v[118:121], v[2:17]
	s_waitcnt lgkmcnt(2)
	v_mfma_f32_32x32x16_bf16 v[18:33], v[114:117], v[130:133], v[18:33]
	v_mfma_f32_32x32x16_bf16 v[34:49], v[110:113], v[118:121], v[34:49]
	v_mfma_f32_32x32x16_bf16 v[50:65], v[110:113], v[130:133], v[50:65]
	ds_read_b128 v[110:113], v0 offset:36960
	ds_read_b128 v[118:121], v0 offset:41568
	ds_read_b128 v[122:125], v66 offset:55392
	ds_read_b128 v[126:129], v66 offset:60000
	s_waitcnt vmcnt(9)
	ds_write_b128 v67, v[78:81] offset:9216
	s_waitcnt vmcnt(8)
	ds_write_b128 v67, v[98:101] offset:27648
	global_load_dwordx4 v[78:81], v69, s[0:1] offset:2944
	global_load_dwordx4 v[98:101], v69, s[36:37] offset:2944
	s_waitcnt lgkmcnt(3)
	v_mfma_f32_32x32x16_bf16 v[2:17], v[118:121], v[122:125], v[2:17]
	s_waitcnt vmcnt(9)
	ds_write_b128 v67, v[82:85] offset:13824
	s_waitcnt vmcnt(8)
	ds_write_b128 v67, v[102:105] offset:32256
	s_waitcnt lgkmcnt(4)
	v_mfma_f32_32x32x16_bf16 v[18:33], v[118:121], v[126:129], v[18:33]
	v_mfma_f32_32x32x16_bf16 v[34:49], v[110:113], v[122:125], v[34:49]
	v_mfma_f32_32x32x16_bf16 v[50:65], v[110:113], v[126:129], v[50:65]
	s_waitcnt lgkmcnt(0)
	s_barrier
	ds_read_b128 v[82:85], v0
	ds_read_b128 v[102:105], v66 offset:18432
	ds_read_b128 v[110:113], v0 offset:32
	ds_read_b128 v[114:117], v66 offset:18464
	ds_read_b128 v[118:121], v0 offset:4608
	ds_read_b128 v[122:125], v0 offset:4640
	s_waitcnt lgkmcnt(4)
	v_mfma_f32_32x32x16_bf16 v[34:49], v[82:85], v[102:105], v[34:49]
	s_waitcnt lgkmcnt(1)
	v_mfma_f32_32x32x16_bf16 v[2:17], v[118:121], v[102:105], v[2:17]
	ds_read_b128 v[102:105], v66 offset:23040
	ds_read_b128 v[126:129], v66 offset:23072
	s_waitcnt lgkmcnt(1)
	v_mfma_f32_32x32x16_bf16 v[50:65], v[82:85], v[102:105], v[50:65]
	global_load_dwordx4 v[82:85], v72, s[0:1] offset:3072
	global_load_dwordx4 v[130:133], v72, s[36:37] offset:3072
	s_waitcnt vmcnt(9)
	ds_write_b128 v67, v[86:89] offset:36864
	s_waitcnt vmcnt(8)
	ds_write_b128 v67, v[134:137] offset:55296
	v_mfma_f32_32x32x16_bf16 v[18:33], v[118:121], v[102:105], v[18:33]
	global_load_dwordx4 v[86:89], v71, s[0:1] offset:3072
	global_load_dwordx4 v[102:105], v71, s[36:37] offset:3072
	v_mfma_f32_32x32x16_bf16 v[2:17], v[122:125], v[114:117], v[2:17]
	s_waitcnt lgkmcnt(2)
	v_mfma_f32_32x32x16_bf16 v[18:33], v[122:125], v[126:129], v[18:33]
	v_mfma_f32_32x32x16_bf16 v[34:49], v[110:113], v[114:117], v[34:49]
	v_mfma_f32_32x32x16_bf16 v[50:65], v[110:113], v[126:129], v[50:65]
	ds_read_b128 v[110:113], v0 offset:64
	ds_read_b128 v[114:117], v0 offset:4672
	ds_read_b128 v[118:121], v66 offset:18496
	ds_read_b128 v[134:137], v66 offset:23104
	s_waitcnt vmcnt(9)
	ds_write_b128 v67, v[90:93] offset:41472
	s_waitcnt vmcnt(8)
	ds_write_b128 v67, v[106:109] offset:59904
	global_load_dwordx4 v[90:93], v70, s[0:1] offset:3072
	global_load_dwordx4 v[106:109], v70, s[36:37] offset:3072
	s_waitcnt lgkmcnt(3)
	v_mfma_f32_32x32x16_bf16 v[2:17], v[114:117], v[118:121], v[2:17]
	s_waitcnt lgkmcnt(2)
	v_mfma_f32_32x32x16_bf16 v[18:33], v[114:117], v[134:137], v[18:33]
	v_mfma_f32_32x32x16_bf16 v[34:49], v[110:113], v[118:121], v[34:49]
	v_mfma_f32_32x32x16_bf16 v[50:65], v[110:113], v[134:137], v[50:65]
	ds_read_b128 v[110:113], v0 offset:96
	ds_read_b128 v[118:121], v0 offset:4704
	ds_read_b128 v[122:125], v66 offset:18528
	ds_read_b128 v[126:129], v66 offset:23136
	s_waitcnt vmcnt(9)
	ds_write_b128 v67, v[74:77] offset:46080
	s_waitcnt vmcnt(8)
	ds_write_b128 v67, v[94:97] offset:64512
	global_load_dwordx4 v[74:77], v69, s[0:1] offset:3072
	global_load_dwordx4 v[94:97], v69, s[36:37] offset:3072
	s_waitcnt lgkmcnt(3)
	v_mfma_f32_32x32x16_bf16 v[2:17], v[118:121], v[122:125], v[2:17]
	s_waitcnt vmcnt(9)
	ds_write_b128 v67, v[78:81] offset:50688
	s_waitcnt vmcnt(8)
	ds_write_b128 v68, v[98:101] offset:13824
	s_waitcnt lgkmcnt(4)
	v_mfma_f32_32x32x16_bf16 v[18:33], v[118:121], v[126:129], v[18:33]
	v_mfma_f32_32x32x16_bf16 v[34:49], v[110:113], v[122:125], v[34:49]
	v_mfma_f32_32x32x16_bf16 v[50:65], v[110:113], v[126:129], v[50:65]
	s_waitcnt lgkmcnt(0)
	s_barrier
; #define GL1_(RA, RB, i) { RA[i] = *(const u32x4*)(ap + (aoff + (i) * astep)); if ((i) < NB) RB[(i) < NB ? (i) : 0] = *(const u32x4*)(bp + (boff + (i) * bstep)); }
; #define LS1_(RA, RB, ST, i) { char* sn_ = lds + (ST) * STAGE; *(u32x4*)(sn_ + wofs + (i) * 32 * LROW) = RA[i]; \
;                               if ((i) < NB) *(u32x4*)(sn_ + STAGE_OP + wofs + (i) * 32 * LROW) = RB[(i) < NB ? (i) : 0]; }
; template <int NJ> DI void gemm_mainloop_reg(const bf16_t* __restrict__ A, int lda, const bf16_t* __restrict__ Bt, int ldb, int K, f32x16 (&acc)[2][NJ], char* lds) {
;     ...
; #pragma unroll
;   for (int i = 0; i < 4; ++i) GL1_(ra0, rb0, i);
;   ap += 128; bp += 128;
; #pragma unroll
;   for (int i = 0; i < 4; ++i) GL1_(ra1, rb1, i);
;   ap += 128; bp += 128;
; #pragma unroll
;   for (int i = 0; i < 4; ++i) LS1_(ra0, rb0, 0, i);
;   __syncthreads();
;   const int nk = K >> 6;
;   for (int kt = 0; kt < nk; kt += 2) {
;     const bool l0 = (kt + 2 < nk), l1 = (kt + 3 < nk);
;     STEP_(0, l0, ra0, rb0, true, ra1, rb1);
;     __syncthreads();
;     STEP_(1, l1, ra1, rb1, l0, ra0, rb0);
;     __syncthreads();
	ds_read_b128 v[78:81], v0 offset:36864
	ds_read_b128 v[98:101], v66 offset:55296
	ds_read_b128 v[110:113], v0 offset:36896
	ds_read_b128 v[114:117], v66 offset:55328
	ds_read_b128 v[118:121], v0 offset:41472
	ds_read_b128 v[122:125], v0 offset:41504
	s_waitcnt lgkmcnt(4)
	v_mfma_f32_32x32x16_bf16 v[34:49], v[78:81], v[98:101], v[34:49]
	s_waitcnt lgkmcnt(1)
	v_mfma_f32_32x32x16_bf16 v[2:17], v[118:121], v[98:101], v[2:17]
	ds_read_b128 v[98:101], v66 offset:59904
	ds_read_b128 v[126:129], v66 offset:59936
	s_waitcnt lgkmcnt(1)
	v_mfma_f32_32x32x16_bf16 v[50:65], v[78:81], v[98:101], v[50:65]
	global_load_dwordx4 v[78:81], v72, s[0:1] offset:3200
	global_load_dwordx4 v[134:137], v72, s[36:37] offset:3200
	s_waitcnt vmcnt(9)
	ds_write_b128 v67, v[82:85]
	s_waitcnt vmcnt(8)
	ds_write_b128 v67, v[130:133] offset:18432
	v_mfma_f32_32x32x16_bf16 v[18:33], v[118:121], v[98:101], v[18:33]
	global_load_dwordx4 v[82:85], v71, s[0:1] offset:3200
	global_load_dwordx4 v[98:101], v71, s[36:37] offset:3200
	v_mfma_f32_32x32x16_bf16 v[2:17], v[122:125], v[114:117], v[2:17]
	s_waitcnt lgkmcnt(2)
	v_mfma_f32_32x32x16_bf16 v[18:33], v[122:125], v[126:129], v[18:33]
	v_mfma_f32_32x32x16_bf16 v[34:49], v[110:113], v[114:117], v[34:49]
	v_mfma_f32_32x32x16_bf16 v[50:65], v[110:113], v[126:129], v[50:65]
	ds_read_b128 v[110:113], v0 offset:36928
	ds_read_b128 v[114:117], v0 offset:41536
	ds_read_b128 v[118:121], v66 offset:55360
	ds_read_b128 v[130:133], v66 offset:59968
	s_waitcnt vmcnt(9)
	ds_write_b128 v67, v[86:89] offset:4608
	s_waitcnt vmcnt(8)
	ds_write_b128 v67, v[102:105] offset:23040
	global_load_dwordx4 v[86:89], v70, s[0:1] offset:3200
	global_load_dwordx4 v[102:105], v70, s[36:37] offset:3200
	s_waitcnt lgkmcnt(3)
	v_mfma_f32_32x32x16_bf16 v[2:17], v[114:117], v[118:121], v[2:17]
	s_waitcnt lgkmcnt(2)
	v_mfma_f32_32x32x16_bf16 v[18:33], v[114:117], v[130:133], v[18:33]
	v_mfma_f32_32x32x16_bf16 v[34:49], v[110:113], v[118:121], v[34:49]
	v_mfma_f32_32x32x16_bf16 v[50:65], v[110:113], v[130:133], v[50:65]
	ds_read_b128 v[110:113], v0 offset:36960
	ds_read_b128 v[118:121], v0 offset:41568
	ds_read_b128 v[122:125], v66 offset:55392
	ds_read_b128 v[126:129], v66 offset:60000
	s_waitcnt vmcnt(9)
	ds_write_b128 v67, v[90:93] offset:9216
	s_waitcnt vmcnt(8)
	ds_write_b128 v67, v[106:109] offset:27648
	global_load_dwordx4 v[90:93], v69, s[0:1] offset:3200
	global_load_dwordx4 v[106:109], v69, s[36:37] offset:3200
	s_waitcnt lgkmcnt(3)
	v_mfma_f32_32x32x16_bf16 v[2:17], v[118:121], v[122:125], v[2:17]
	s_waitcnt vmcnt(9)
	ds_write_b128 v67, v[74:77] offset:13824
	s_waitcnt vmcnt(8)
	ds_write_b128 v67, v[94:97] offset:32256
	s_waitcnt lgkmcnt(4)
	v_mfma_f32_32x32x16_bf16 v[18:33], v[118:121], v[126:129], v[18:33]
	v_mfma_f32_32x32x16_bf16 v[34:49], v[110:113], v[122:125], v[34:49]
	v_mfma_f32_32x32x16_bf16 v[50:65], v[110:113], v[126:129], v[50:65]
	s_waitcnt lgkmcnt(0)
	s_barrier
	ds_read_b128 v[74:77], v0
	ds_read_b128 v[94:97], v66 offset:18432
	ds_read_b128 v[110:113], v0 offset:32
	ds_read_b128 v[114:117], v66 offset:18464
	ds_read_b128 v[118:121], v0 offset:4608
	ds_read_b128 v[122:125], v0 offset:4640
	s_waitcnt lgkmcnt(4)
	v_mfma_f32_32x32x16_bf16 v[34:49], v[74:77], v[94:97], v[34:49]
	s_waitcnt lgkmcnt(1)
	v_mfma_f32_32x32x16_bf16 v[2:17], v[118:121], v[94:97], v[2:17]
	ds_read_b128 v[94:97], v66 offset:23040
	ds_read_b128 v[126:129], v66 offset:23072
	s_waitcnt lgkmcnt(1)
	v_mfma_f32_32x32x16_bf16 v[50:65], v[74:77], v[94:97], v[50:65]
	global_load_dwordx4 v[74:77], v72, s[0:1] offset:3328
	global_load_dwordx4 v[130:133], v72, s[36:37] offset:3328
	s_waitcnt vmcnt(9)
	ds_write_b128 v67, v[78:81] offset:36864
	s_waitcnt vmcnt(8)
	ds_write_b128 v67, v[134:137] offset:55296
	v_mfma_f32_32x32x16_bf16 v[18:33], v[118:121], v[94:97], v[18:33]
	global_load_dwordx4 v[78:81], v71, s[0:1] offset:3328
	global_load_dwordx4 v[94:97], v71, s[36:37] offset:3328
	v_mfma_f32_32x32x16_bf16 v[2:17], v[122:125], v[114:117], v[2:17]
	s_waitcnt lgkmcnt(2)
	v_mfma_f32_32x32x16_bf16 v[18:33], v[122:125], v[126:129], v[18:33]
	v_mfma_f32_32x32x16_bf16 v[34:49], v[110:113], v[114:117], v[34:49]
	v_mfma_f32_32x32x16_bf16 v[50:65], v[110:113], v[126:129], v[50:65]
	ds_read_b128 v[110:113], v0 offset:64
	ds_read_b128 v[114:117], v0 offset:4672
	ds_read_b128 v[118:121], v66 offset:18496
	ds_read_b128 v[134:137], v66 offset:23104
	s_waitcnt vmcnt(9)
	ds_write_b128 v67, v[82:85] offset:41472
	s_waitcnt vmcnt(8)
	ds_write_b128 v67, v[98:101] offset:59904
	global_load_dwordx4 v[82:85], v70, s[0:1] offset:3328
	global_load_dwordx4 v[98:101], v70, s[36:37] offset:3328
	s_waitcnt lgkmcnt(3)
	v_mfma_f32_32x32x16_bf16 v[2:17], v[114:117], v[118:121], v[2:17]
	s_waitcnt lgkmcnt(2)
	v_mfma_f32_32x32x16_bf16 v[18:33], v[114:117], v[134:137], v[18:33]
	v_mfma_f32_32x32x16_bf16 v[34:49], v[110:113], v[118:121], v[34:49]
	v_mfma_f32_32x32x16_bf16 v[50:65], v[110:113], v[134:137], v[50:65]
	ds_read_b128 v[110:113], v0 offset:96
	ds_read_b128 v[118:121], v0 offset:4704
	ds_read_b128 v[122:125], v66 offset:18528
	ds_read_b128 v[126:129], v66 offset:23136
	s_waitcnt vmcnt(9)
	ds_write_b128 v67, v[86:89] offset:46080
	s_waitcnt vmcnt(8)
	ds_write_b128 v67, v[102:105] offset:64512
	global_load_dwordx4 v[86:89], v69, s[0:1] offset:3328
	global_load_dwordx4 v[102:105], v69, s[36:37] offset:3328
	s_waitcnt lgkmcnt(3)
	v_mfma_f32_32x32x16_bf16 v[2:17], v[118:121], v[122:125], v[2:17]
	s_waitcnt vmcnt(9)
	ds_write_b128 v67, v[90:93] offset:50688
	s_waitcnt vmcnt(8)
	ds_write_b128 v68, v[106:109] offset:13824
	s_waitcnt lgkmcnt(4)
	v_mfma_f32_32x32x16_bf16 v[18:33], v[118:121], v[126:129], v[18:33]
	v_mfma_f32_32x32x16_bf16 v[34:49], v[110:113], v[122:125], v[34:49]
	v_mfma_f32_32x32x16_bf16 v[50:65], v[110:113], v[126:129], v[50:65]
	s_waitcnt lgkmcnt(0)
	s_barrier
; #define GL1_(RA, RB, i) { RA[i] = *(const u32x4*)(ap + (aoff + (i) * astep)); if ((i) < NB) RB[(i) < NB ? (i) : 0] = *(const u32x4*)(bp + (boff + (i) * bstep)); }
; #define LS1_(RA, RB, ST, i) { char* sn_ = lds + (ST) * STAGE; *(u32x4*)(sn_ + wofs + (i) * 32 * LROW) = RA[i]; \
;                               if ((i) < NB) *(u32x4*)(sn_ + STAGE_OP + wofs + (i) * 32 * LROW) = RB[(i) < NB ? (i) : 0]; }
; template <int NJ> DI void gemm_mainloop_reg(const bf16_t* __restrict__ A, int lda, const bf16_t* __restrict__ Bt, int ldb, int K, f32x16 (&acc)[2][NJ], char* lds) {
;     ...
; #pragma unroll
;   for (int i = 0; i < 4; ++i) GL1_(ra0, rb0, i);
;   ap += 128; bp += 128;
; #pragma unroll
;   for (int i = 0; i < 4; ++i) GL1_(ra1, rb1, i);
;   ap += 128; bp += 128;
; #pragma unroll
;   for (int i = 0; i < 4; ++i) LS1_(ra0, rb0, 0, i);
;   __syncthreads();
;   const int nk = K >> 6;
;   for (int kt = 0; kt < nk; kt += 2) {
;     const bool l0 = (kt + 2 < nk), l1 = (kt + 3 < nk);
;     STEP_(0, l0, ra0, rb0, true, ra1, rb1);
;     __syncthreads();
;     STEP_(1, l1, ra1, rb1, l0, ra0, rb0);
;     __syncthreads();
	ds_read_b128 v[90:93], v0 offset:36864
	ds_read_b128 v[106:109], v66 offset:55296
	ds_read_b128 v[110:113], v0 offset:36896
	ds_read_b128 v[114:117], v66 offset:55328
	ds_read_b128 v[118:121], v0 offset:41472
	ds_read_b128 v[122:125], v0 offset:41504
	s_waitcnt lgkmcnt(4)
	v_mfma_f32_32x32x16_bf16 v[34:49], v[90:93], v[106:109], v[34:49]
	s_waitcnt lgkmcnt(1)
	v_mfma_f32_32x32x16_bf16 v[2:17], v[118:121], v[106:109], v[2:17]
	ds_read_b128 v[106:109], v66 offset:59904
	ds_read_b128 v[126:129], v66 offset:59936
	s_waitcnt lgkmcnt(1)
	v_mfma_f32_32x32x16_bf16 v[50:65], v[90:93], v[106:109], v[50:65]
	global_load_dwordx4 v[90:93], v72, s[0:1] offset:3456
	global_load_dwordx4 v[134:137], v72, s[36:37] offset:3456
	s_waitcnt vmcnt(9)
	ds_write_b128 v67, v[74:77]
	s_waitcnt vmcnt(8)
	ds_write_b128 v67, v[130:133] offset:18432
	v_mfma_f32_32x32x16_bf16 v[18:33], v[118:121], v[106:109], v[18:33]
	global_load_dwordx4 v[74:77], v71, s[0:1] offset:3456
	global_load_dwordx4 v[106:109], v71, s[36:37] offset:3456
	v_mfma_f32_32x32x16_bf16 v[2:17], v[122:125], v[114:117], v[2:17]
	s_waitcnt lgkmcnt(2)
	v_mfma_f32_32x32x16_bf16 v[18:33], v[122:125], v[126:129], v[18:33]
	v_mfma_f32_32x32x16_bf16 v[34:49], v[110:113], v[114:117], v[34:49]
	v_mfma_f32_32x32x16_bf16 v[50:65], v[110:113], v[126:129], v[50:65]
	ds_read_b128 v[110:113], v0 offset:36928
	ds_read_b128 v[114:117], v0 offset:41536
	ds_read_b128 v[118:121], v66 offset:55360
	ds_read_b128 v[130:133], v66 offset:59968
	s_waitcnt vmcnt(9)
	ds_write_b128 v67, v[78:81] offset:4608
	s_waitcnt vmcnt(8)
	ds_write_b128 v67, v[94:97] offset:23040
	global_load_dwordx4 v[78:81], v70, s[0:1] offset:3456
	global_load_dwordx4 v[94:97], v70, s[36:37] offset:3456
	s_waitcnt lgkmcnt(3)
	v_mfma_f32_32x32x16_bf16 v[2:17], v[114:117], v[118:121], v[2:17]
	s_waitcnt lgkmcnt(2)
	v_mfma_f32_32x32x16_bf16 v[18:33], v[114:117], v[130:133], v[18:33]
	v_mfma_f32_32x32x16_bf16 v[34:49], v[110:113], v[118:121], v[34:49]
	v_mfma_f32_32x32x16_bf16 v[50:65], v[110:113], v[130:133], v[50:65]
	ds_read_b128 v[110:113], v0 offset:36960
	ds_read_b128 v[118:121], v0 offset:41568
	ds_read_b128 v[122:125], v66 offset:55392
	ds_read_b128 v[126:129], v66 offset:60000
	s_waitcnt vmcnt(9)
	ds_write_b128 v67, v[82:85] offset:9216
	s_waitcnt vmcnt(8)
	ds_write_b128 v67, v[98:101] offset:27648
	global_load_dwordx4 v[82:85], v69, s[0:1] offset:3456
	global_load_dwordx4 v[98:101], v69, s[36:37] offset:3456
	s_waitcnt lgkmcnt(3)
	v_mfma_f32_32x32x16_bf16 v[2:17], v[118:121], v[122:125], v[2:17]
	s_waitcnt vmcnt(9)
	ds_write_b128 v67, v[86:89] offset:13824
	s_waitcnt vmcnt(8)
	ds_write_b128 v67, v[102:105] offset:32256
	s_waitcnt lgkmcnt(4)
	v_mfma_f32_32x32x16_bf16 v[18:33], v[118:121], v[126:129], v[18:33]
	v_mfma_f32_32x32x16_bf16 v[34:49], v[110:113], v[122:125], v[34:49]
	v_mfma_f32_32x32x16_bf16 v[50:65], v[110:113], v[126:129], v[50:65]
	s_waitcnt lgkmcnt(0)
	s_barrier
	ds_read_b128 v[86:89], v0
	ds_read_b128 v[102:105], v66 offset:18432
	ds_read_b128 v[110:113], v0 offset:32
	ds_read_b128 v[114:117], v66 offset:18464
	ds_read_b128 v[118:121], v0 offset:4608
	ds_read_b128 v[122:125], v0 offset:4640
	s_waitcnt lgkmcnt(4)
	v_mfma_f32_32x32x16_bf16 v[34:49], v[86:89], v[102:105], v[34:49]
	s_waitcnt lgkmcnt(1)
	v_mfma_f32_32x32x16_bf16 v[2:17], v[118:121], v[102:105], v[2:17]
	ds_read_b128 v[102:105], v66 offset:23040
	ds_read_b128 v[126:129], v66 offset:23072
	s_waitcnt lgkmcnt(1)
	v_mfma_f32_32x32x16_bf16 v[50:65], v[86:89], v[102:105], v[50:65]
	global_load_dwordx4 v[86:89], v72, s[0:1] offset:3584
	global_load_dwordx4 v[130:133], v72, s[36:37] offset:3584
	s_waitcnt vmcnt(9)
	ds_write_b128 v67, v[90:93] offset:36864
	s_waitcnt vmcnt(8)
	ds_write_b128 v67, v[134:137] offset:55296
	v_mfma_f32_32x32x16_bf16 v[18:33], v[118:121], v[102:105], v[18:33]
	global_load_dwordx4 v[90:93], v71, s[0:1] offset:3584
	global_load_dwordx4 v[102:105], v71, s[36:37] offset:3584
	v_mfma_f32_32x32x16_bf16 v[2:17], v[122:125], v[114:117], v[2:17]
	s_waitcnt lgkmcnt(2)
	v_mfma_f32_32x32x16_bf16 v[18:33], v[122:125], v[126:129], v[18:33]
	v_mfma_f32_32x32x16_bf16 v[34:49], v[110:113], v[114:117], v[34:49]
	v_mfma_f32_32x32x16_bf16 v[50:65], v[110:113], v[126:129], v[50:65]
	ds_read_b128 v[110:113], v0 offset:64
	ds_read_b128 v[114:117], v0 offset:4672
	ds_read_b128 v[118:121], v66 offset:18496
	ds_read_b128 v[134:137], v66 offset:23104
	s_waitcnt vmcnt(9)
	ds_write_b128 v67, v[74:77] offset:41472
	s_waitcnt vmcnt(8)
	ds_write_b128 v67, v[106:109] offset:59904
	global_load_dwordx4 v[74:77], v70, s[0:1] offset:3584
	global_load_dwordx4 v[106:109], v70, s[36:37] offset:3584
	s_waitcnt lgkmcnt(3)
	v_mfma_f32_32x32x16_bf16 v[2:17], v[114:117], v[118:121], v[2:17]
	s_waitcnt lgkmcnt(2)
	v_mfma_f32_32x32x16_bf16 v[18:33], v[114:117], v[134:137], v[18:33]
	v_mfma_f32_32x32x16_bf16 v[34:49], v[110:113], v[118:121], v[34:49]
	v_mfma_f32_32x32x16_bf16 v[50:65], v[110:113], v[134:137], v[50:65]
	ds_read_b128 v[110:113], v0 offset:96
	ds_read_b128 v[118:121], v0 offset:4704
	ds_read_b128 v[122:125], v66 offset:18528
	ds_read_b128 v[126:129], v66 offset:23136
	s_waitcnt vmcnt(9)
	ds_write_b128 v67, v[78:81] offset:46080
	s_waitcnt vmcnt(8)
	ds_write_b128 v67, v[94:97] offset:64512
	global_load_dwordx4 v[78:81], v69, s[0:1] offset:3584
	global_load_dwordx4 v[94:97], v69, s[36:37] offset:3584
	s_waitcnt lgkmcnt(3)
	v_mfma_f32_32x32x16_bf16 v[2:17], v[118:121], v[122:125], v[2:17]
	s_waitcnt vmcnt(9)
	ds_write_b128 v67, v[82:85] offset:50688
	s_waitcnt vmcnt(8)
	ds_write_b128 v68, v[98:101] offset:13824
	s_waitcnt lgkmcnt(4)
	v_mfma_f32_32x32x16_bf16 v[18:33], v[118:121], v[126:129], v[18:33]
	v_mfma_f32_32x32x16_bf16 v[34:49], v[110:113], v[122:125], v[34:49]
	v_mfma_f32_32x32x16_bf16 v[50:65], v[110:113], v[126:129], v[50:65]
	s_waitcnt lgkmcnt(0)
	s_barrier
; #define GL1_(RA, RB, i) { RA[i] = *(const u32x4*)(ap + (aoff + (i) * astep)); if ((i) < NB) RB[(i) < NB ? (i) : 0] = *(const u32x4*)(bp + (boff + (i) * bstep)); }
; #define LS1_(RA, RB, ST, i) { char* sn_ = lds + (ST) * STAGE; *(u32x4*)(sn_ + wofs + (i) * 32 * LROW) = RA[i]; \
;                               if ((i) < NB) *(u32x4*)(sn_ + STAGE_OP + wofs + (i) * 32 * LROW) = RB[(i) < NB ? (i) : 0]; }
; template <int NJ> DI void gemm_mainloop_reg(const bf16_t* __restrict__ A, int lda, const bf16_t* __restrict__ Bt, int ldb, int K, f32x16 (&acc)[2][NJ], char* lds) {
;     ...
; #pragma unroll
;   for (int i = 0; i < 4; ++i) GL1_(ra0, rb0, i);
;   ap += 128; bp += 128;
; #pragma unroll
;   for (int i = 0; i < 4; ++i) GL1_(ra1, rb1, i);
;   ap += 128; bp += 128;
; #pragma unroll
;   for (int i = 0; i < 4; ++i) LS1_(ra0, rb0, 0, i);
;   __syncthreads();
;   const int nk = K >> 6;
;   for (int kt = 0; kt < nk; kt += 2) {
;     const bool l0 = (kt + 2 < nk), l1 = (kt + 3 < nk);
;     STEP_(0, l0, ra0, rb0, true, ra1, rb1);
;     __syncthreads();
;     STEP_(1, l1, ra1, rb1, l0, ra0, rb0);
;     __syncthreads();
	ds_read_b128 v[82:85], v0 offset:36864
	ds_read_b128 v[98:101], v66 offset:55296
	ds_read_b128 v[110:113], v0 offset:36896
	ds_read_b128 v[114:117], v66 offset:55328
	ds_read_b128 v[118:121], v0 offset:41472
	ds_read_b128 v[122:125], v0 offset:41504
	s_waitcnt lgkmcnt(4)
	v_mfma_f32_32x32x16_bf16 v[34:49], v[82:85], v[98:101], v[34:49]
	s_waitcnt lgkmcnt(1)
	v_mfma_f32_32x32x16_bf16 v[2:17], v[118:121], v[98:101], v[2:17]
	ds_read_b128 v[98:101], v66 offset:59904
	ds_read_b128 v[126:129], v66 offset:59936
	s_waitcnt lgkmcnt(1)
	v_mfma_f32_32x32x16_bf16 v[50:65], v[82:85], v[98:101], v[50:65]
	global_load_dwordx4 v[82:85], v72, s[0:1] offset:3712
	global_load_dwordx4 v[134:137], v72, s[36:37] offset:3712
	s_waitcnt vmcnt(9)
	ds_write_b128 v67, v[86:89]
	s_waitcnt vmcnt(8)
	ds_write_b128 v67, v[130:133] offset:18432
	v_mfma_f32_32x32x16_bf16 v[18:33], v[118:121], v[98:101], v[18:33]
	global_load_dwordx4 v[86:89], v71, s[0:1] offset:3712
	global_load_dwordx4 v[98:101], v71, s[36:37] offset:3712
	v_mfma_f32_32x32x16_bf16 v[2:17], v[122:125], v[114:117], v[2:17]
	s_waitcnt lgkmcnt(2)
	v_mfma_f32_32x32x16_bf16 v[18:33], v[122:125], v[126:129], v[18:33]
	v_mfma_f32_32x32x16_bf16 v[34:49], v[110:113], v[114:117], v[34:49]
	v_mfma_f32_32x32x16_bf16 v[50:65], v[110:113], v[126:129], v[50:65]
	ds_read_b128 v[110:113], v0 offset:36928
	ds_read_b128 v[114:117], v0 offset:41536
	ds_read_b128 v[118:121], v66 offset:55360
	ds_read_b128 v[130:133], v66 offset:59968
	s_waitcnt vmcnt(9)
	ds_write_b128 v67, v[90:93] offset:4608
	s_waitcnt vmcnt(8)
	ds_write_b128 v67, v[102:105] offset:23040
	global_load_dwordx4 v[90:93], v70, s[0:1] offset:3712
	global_load_dwordx4 v[102:105], v70, s[36:37] offset:3712
	s_waitcnt lgkmcnt(3)
	v_mfma_f32_32x32x16_bf16 v[2:17], v[114:117], v[118:121], v[2:17]
	s_waitcnt lgkmcnt(2)
	v_mfma_f32_32x32x16_bf16 v[18:33], v[114:117], v[130:133], v[18:33]
	v_mfma_f32_32x32x16_bf16 v[34:49], v[110:113], v[118:121], v[34:49]
	v_mfma_f32_32x32x16_bf16 v[50:65], v[110:113], v[130:133], v[50:65]
	ds_read_b128 v[110:113], v0 offset:36960
	ds_read_b128 v[118:121], v0 offset:41568
	ds_read_b128 v[122:125], v66 offset:55392
	ds_read_b128 v[126:129], v66 offset:60000
	s_waitcnt vmcnt(9)
	ds_write_b128 v67, v[74:77] offset:9216
	s_waitcnt vmcnt(8)
	ds_write_b128 v67, v[106:109] offset:27648
	global_load_dwordx4 v[74:77], v69, s[0:1] offset:3712
	global_load_dwordx4 v[106:109], v69, s[36:37] offset:3712
	s_waitcnt lgkmcnt(3)
	v_mfma_f32_32x32x16_bf16 v[2:17], v[118:121], v[122:125], v[2:17]
	s_waitcnt vmcnt(9)
	ds_write_b128 v67, v[78:81] offset:13824
	s_waitcnt vmcnt(8)
	ds_write_b128 v67, v[94:97] offset:32256
	s_waitcnt lgkmcnt(4)
	v_mfma_f32_32x32x16_bf16 v[18:33], v[118:121], v[126:129], v[18:33]
	v_mfma_f32_32x32x16_bf16 v[34:49], v[110:113], v[122:125], v[34:49]
	v_mfma_f32_32x32x16_bf16 v[50:65], v[110:113], v[126:129], v[50:65]
	s_waitcnt lgkmcnt(0)
	s_barrier
	ds_read_b128 v[78:81], v0
	ds_read_b128 v[94:97], v66 offset:18432
	ds_read_b128 v[110:113], v0 offset:32
	ds_read_b128 v[114:117], v66 offset:18464
	ds_read_b128 v[118:121], v0 offset:4608
	ds_read_b128 v[122:125], v0 offset:4640
	s_waitcnt lgkmcnt(4)
	v_mfma_f32_32x32x16_bf16 v[34:49], v[78:81], v[94:97], v[34:49]
	s_waitcnt lgkmcnt(1)
	v_mfma_f32_32x32x16_bf16 v[2:17], v[118:121], v[94:97], v[2:17]
	ds_read_b128 v[94:97], v66 offset:23040
	ds_read_b128 v[126:129], v66 offset:23072
	s_waitcnt lgkmcnt(1)
	v_mfma_f32_32x32x16_bf16 v[50:65], v[78:81], v[94:97], v[50:65]
	global_load_dwordx4 v[78:81], v72, s[0:1] offset:3840
	global_load_dwordx4 v[130:133], v72, s[36:37] offset:3840
	s_waitcnt vmcnt(9)
	ds_write_b128 v67, v[82:85] offset:36864
	s_waitcnt vmcnt(8)
	ds_write_b128 v67, v[134:137] offset:55296
	v_mfma_f32_32x32x16_bf16 v[18:33], v[118:121], v[94:97], v[18:33]
	global_load_dwordx4 v[82:85], v71, s[0:1] offset:3840
	global_load_dwordx4 v[94:97], v71, s[36:37] offset:3840
	v_mfma_f32_32x32x16_bf16 v[2:17], v[122:125], v[114:117], v[2:17]
	s_waitcnt lgkmcnt(2)
	v_mfma_f32_32x32x16_bf16 v[18:33], v[122:125], v[126:129], v[18:33]
	v_mfma_f32_32x32x16_bf16 v[34:49], v[110:113], v[114:117], v[34:49]
	v_mfma_f32_32x32x16_bf16 v[50:65], v[110:113], v[126:129], v[50:65]
	ds_read_b128 v[110:113], v0 offset:64
	ds_read_b128 v[114:117], v0 offset:4672
	ds_read_b128 v[118:121], v66 offset:18496
	ds_read_b128 v[134:137], v66 offset:23104
	s_waitcnt vmcnt(9)
	ds_write_b128 v67, v[86:89] offset:41472
	s_waitcnt vmcnt(8)
	ds_write_b128 v67, v[98:101] offset:59904
	global_load_dwordx4 v[86:89], v70, s[0:1] offset:3840
	global_load_dwordx4 v[98:101], v70, s[36:37] offset:3840
	s_waitcnt lgkmcnt(3)
	v_mfma_f32_32x32x16_bf16 v[2:17], v[114:117], v[118:121], v[2:17]
	s_waitcnt lgkmcnt(2)
	v_mfma_f32_32x32x16_bf16 v[18:33], v[114:117], v[134:137], v[18:33]
	v_mfma_f32_32x32x16_bf16 v[34:49], v[110:113], v[118:121], v[34:49]
	v_mfma_f32_32x32x16_bf16 v[50:65], v[110:113], v[134:137], v[50:65]
	ds_read_b128 v[110:113], v0 offset:96
	ds_read_b128 v[118:121], v0 offset:4704
	ds_read_b128 v[122:125], v66 offset:18528
	ds_read_b128 v[126:129], v66 offset:23136
	s_waitcnt vmcnt(9)
	ds_write_b128 v67, v[90:93] offset:46080
	s_waitcnt vmcnt(8)
	ds_write_b128 v67, v[102:105] offset:64512
	global_load_dwordx4 v[90:93], v69, s[0:1] offset:3840
	global_load_dwordx4 v[102:105], v69, s[36:37] offset:3840
	s_waitcnt lgkmcnt(3)
	v_mfma_f32_32x32x16_bf16 v[2:17], v[118:121], v[122:125], v[2:17]
	s_waitcnt vmcnt(9)
	ds_write_b128 v67, v[74:77] offset:50688
	s_waitcnt vmcnt(8)
	ds_write_b128 v68, v[106:109] offset:13824
	s_waitcnt lgkmcnt(4)
	v_mfma_f32_32x32x16_bf16 v[18:33], v[118:121], v[126:129], v[18:33]
	v_mfma_f32_32x32x16_bf16 v[34:49], v[110:113], v[122:125], v[34:49]
	v_mfma_f32_32x32x16_bf16 v[50:65], v[110:113], v[126:129], v[50:65]
	s_waitcnt lgkmcnt(0)
	s_barrier
; #define GL1_(RA, RB, i) { RA[i] = *(const u32x4*)(ap + (aoff + (i) * astep)); if ((i) < NB) RB[(i) < NB ? (i) : 0] = *(const u32x4*)(bp + (boff + (i) * bstep)); }
; #define LS1_(RA, RB, ST, i) { char* sn_ = lds + (ST) * STAGE; *(u32x4*)(sn_ + wofs + (i) * 32 * LROW) = RA[i]; \
;                               if ((i) < NB) *(u32x4*)(sn_ + STAGE_OP + wofs + (i) * 32 * LROW) = RB[(i) < NB ? (i) : 0]; }
; template <int NJ> DI void gemm_mainloop_reg(const bf16_t* __restrict__ A, int lda, const bf16_t* __restrict__ Bt, int ldb, int K, f32x16 (&acc)[2][NJ], char* lds) {
;     ...
; #pragma unroll
;   for (int i = 0; i < 4; ++i) GL1_(ra0, rb0, i);
;   ap += 128; bp += 128;
; #pragma unroll
;   for (int i = 0; i < 4; ++i) GL1_(ra1, rb1, i);
;   ap += 128; bp += 128;
; #pragma unroll
;   for (int i = 0; i < 4; ++i) LS1_(ra0, rb0, 0, i);
;   __syncthreads();
;   const int nk = K >> 6;
;   for (int kt = 0; kt < nk; kt += 2) {
;     const bool l0 = (kt + 2 < nk), l1 = (kt + 3 < nk);
;     STEP_(0, l0, ra0, rb0, true, ra1, rb1);
;     __syncthreads();
;     STEP_(1, l1, ra1, rb1, l0, ra0, rb0);
;     __syncthreads();
	ds_read_b128 v[74:77], v0 offset:36864
	ds_read_b128 v[106:109], v66 offset:55296
	ds_read_b128 v[110:113], v0 offset:36896
	ds_read_b128 v[114:117], v66 offset:55328
	ds_read_b128 v[118:121], v0 offset:41472
	ds_read_b128 v[122:125], v0 offset:41504
	s_waitcnt lgkmcnt(4)
	v_mfma_f32_32x32x16_bf16 v[34:49], v[74:77], v[106:109], v[34:49]
	s_waitcnt lgkmcnt(1)
	v_mfma_f32_32x32x16_bf16 v[2:17], v[118:121], v[106:109], v[2:17]
	ds_read_b128 v[106:109], v66 offset:59904
	ds_read_b128 v[126:129], v66 offset:59936
	s_waitcnt lgkmcnt(1)
	v_mfma_f32_32x32x16_bf16 v[50:65], v[74:77], v[106:109], v[50:65]
	global_load_dwordx4 v[74:77], v72, s[0:1] offset:3968
	global_load_dwordx4 v[134:137], v72, s[36:37] offset:3968
	s_waitcnt vmcnt(9)
	ds_write_b128 v67, v[78:81]
	s_waitcnt vmcnt(8)
	ds_write_b128 v67, v[130:133] offset:18432
	v_mfma_f32_32x32x16_bf16 v[18:33], v[118:121], v[106:109], v[18:33]
	global_load_dwordx4 v[78:81], v71, s[0:1] offset:3968
	global_load_dwordx4 v[106:109], v71, s[36:37] offset:3968
	v_mfma_f32_32x32x16_bf16 v[2:17], v[122:125], v[114:117], v[2:17]
	s_waitcnt lgkmcnt(2)
	v_mfma_f32_32x32x16_bf16 v[18:33], v[122:125], v[126:129], v[18:33]
	v_mfma_f32_32x32x16_bf16 v[34:49], v[110:113], v[114:117], v[34:49]
	v_mfma_f32_32x32x16_bf16 v[50:65], v[110:113], v[126:129], v[50:65]
	ds_read_b128 v[110:113], v0 offset:36928
	ds_read_b128 v[114:117], v0 offset:41536
	ds_read_b128 v[118:121], v66 offset:55360
	ds_read_b128 v[130:133], v66 offset:59968
	s_waitcnt vmcnt(9)
	ds_write_b128 v67, v[82:85] offset:4608
	s_waitcnt vmcnt(8)
	ds_write_b128 v67, v[94:97] offset:23040
	global_load_dwordx4 v[82:85], v70, s[0:1] offset:3968
	global_load_dwordx4 v[94:97], v70, s[36:37] offset:3968
	s_waitcnt lgkmcnt(3)
	v_mfma_f32_32x32x16_bf16 v[2:17], v[114:117], v[118:121], v[2:17]
	s_waitcnt lgkmcnt(2)
	v_mfma_f32_32x32x16_bf16 v[18:33], v[114:117], v[130:133], v[18:33]
	v_mfma_f32_32x32x16_bf16 v[34:49], v[110:113], v[118:121], v[34:49]
	v_mfma_f32_32x32x16_bf16 v[50:65], v[110:113], v[130:133], v[50:65]
	ds_read_b128 v[110:113], v0 offset:36960
	ds_read_b128 v[118:121], v0 offset:41568
	ds_read_b128 v[122:125], v66 offset:55392
	ds_read_b128 v[126:129], v66 offset:60000
	s_waitcnt vmcnt(9)
	ds_write_b128 v67, v[86:89] offset:9216
	s_waitcnt vmcnt(8)
	ds_write_b128 v67, v[98:101] offset:27648
	global_load_dwordx4 v[86:89], v69, s[0:1] offset:3968
	global_load_dwordx4 v[98:101], v69, s[36:37] offset:3968
	s_waitcnt lgkmcnt(3)
	v_mfma_f32_32x32x16_bf16 v[2:17], v[118:121], v[122:125], v[2:17]
	s_waitcnt vmcnt(9)
	ds_write_b128 v67, v[90:93] offset:13824
	s_waitcnt vmcnt(8)
	ds_write_b128 v67, v[102:105] offset:32256
	s_waitcnt lgkmcnt(4)
	v_mfma_f32_32x32x16_bf16 v[18:33], v[118:121], v[126:129], v[18:33]
	v_mfma_f32_32x32x16_bf16 v[34:49], v[110:113], v[122:125], v[34:49]
	v_mfma_f32_32x32x16_bf16 v[50:65], v[110:113], v[126:129], v[50:65]
	s_waitcnt lgkmcnt(0)
	s_barrier
	ds_read_b128 v[90:93], v0
	ds_read_b128 v[102:105], v66 offset:18432
	ds_read_b128 v[110:113], v0 offset:32
	ds_read_b128 v[114:117], v66 offset:18464
	ds_read_b128 v[118:121], v0 offset:4608
	ds_read_b128 v[122:125], v0 offset:4640
	s_waitcnt lgkmcnt(4)
	v_mfma_f32_32x32x16_bf16 v[34:49], v[90:93], v[102:105], v[34:49]
	s_add_u32 s2, s36, 0x1000
	s_addc_u32 s3, s37, 0
	s_add_u32 s26, s0, 0x1000
	s_addc_u32 s27, s1, 0
	ds_read_b128 v[126:129], v66 offset:23072
	s_waitcnt lgkmcnt(2)
	v_mfma_f32_32x32x16_bf16 v[2:17], v[118:121], v[102:105], v[2:17]
	ds_read_b128 v[102:105], v66 offset:23040
	s_waitcnt lgkmcnt(0)
	v_mfma_f32_32x32x16_bf16 v[50:65], v[90:93], v[102:105], v[50:65]
	global_load_dwordx4 v[90:93], v72, s[26:27]
	global_load_dwordx4 v[130:133], v72, s[2:3]
	s_waitcnt vmcnt(9)
	ds_write_b128 v67, v[74:77] offset:36864
	s_waitcnt vmcnt(8)
	ds_write_b128 v67, v[134:137] offset:55296
	v_mfma_f32_32x32x16_bf16 v[18:33], v[118:121], v[102:105], v[18:33]
	global_load_dwordx4 v[74:77], v71, s[26:27]
	global_load_dwordx4 v[102:105], v71, s[2:3]
	v_mfma_f32_32x32x16_bf16 v[2:17], v[122:125], v[114:117], v[2:17]
	v_mfma_f32_32x32x16_bf16 v[18:33], v[122:125], v[126:129], v[18:33]
	v_mfma_f32_32x32x16_bf16 v[34:49], v[110:113], v[114:117], v[34:49]
	v_mfma_f32_32x32x16_bf16 v[50:65], v[110:113], v[126:129], v[50:65]
	ds_read_b128 v[110:113], v0 offset:64
	ds_read_b128 v[114:117], v0 offset:4672
	ds_read_b128 v[118:121], v66 offset:18496
	ds_read_b128 v[134:137], v66 offset:23104
	s_waitcnt vmcnt(9)
	ds_write_b128 v67, v[78:81] offset:41472
	s_waitcnt vmcnt(8)
	ds_write_b128 v67, v[106:109] offset:59904
	global_load_dwordx4 v[78:81], v70, s[26:27]
	global_load_dwordx4 v[106:109], v70, s[2:3]
	s_waitcnt lgkmcnt(3)
	v_mfma_f32_32x32x16_bf16 v[2:17], v[114:117], v[118:121], v[2:17]
	s_waitcnt lgkmcnt(2)
	v_mfma_f32_32x32x16_bf16 v[18:33], v[114:117], v[134:137], v[18:33]
	v_mfma_f32_32x32x16_bf16 v[34:49], v[110:113], v[118:121], v[34:49]
	v_mfma_f32_32x32x16_bf16 v[50:65], v[110:113], v[134:137], v[50:65]
	ds_read_b128 v[110:113], v0 offset:96
	ds_read_b128 v[118:121], v0 offset:4704
	ds_read_b128 v[122:125], v66 offset:18528
	ds_read_b128 v[126:129], v66 offset:23136
	s_waitcnt vmcnt(9)
	ds_write_b128 v67, v[82:85] offset:46080
	s_waitcnt vmcnt(8)
	ds_write_b128 v67, v[94:97] offset:64512
	global_load_dwordx4 v[82:85], v69, s[26:27]
	global_load_dwordx4 v[94:97], v69, s[2:3]
	s_waitcnt lgkmcnt(3)
	v_mfma_f32_32x32x16_bf16 v[2:17], v[118:121], v[122:125], v[2:17]
	s_waitcnt vmcnt(9)
	ds_write_b128 v67, v[86:89] offset:50688
	s_waitcnt vmcnt(8)
	ds_write_b128 v68, v[98:101] offset:13824
	s_waitcnt lgkmcnt(4)
	v_mfma_f32_32x32x16_bf16 v[18:33], v[118:121], v[126:129], v[18:33]
	v_mfma_f32_32x32x16_bf16 v[34:49], v[110:113], v[122:125], v[34:49]
	v_mfma_f32_32x32x16_bf16 v[50:65], v[110:113], v[126:129], v[50:65]
	s_waitcnt lgkmcnt(0)
	s_barrier
; #define GL1_(RA, RB, i) { RA[i] = *(const u32x4*)(ap + (aoff + (i) * astep)); if ((i) < NB) RB[(i) < NB ? (i) : 0] = *(const u32x4*)(bp + (boff + (i) * bstep)); }
; #define LS1_(RA, RB, ST, i) { char* sn_ = lds + (ST) * STAGE; *(u32x4*)(sn_ + wofs + (i) * 32 * LROW) = RA[i]; \
;                               if ((i) < NB) *(u32x4*)(sn_ + STAGE_OP + wofs + (i) * 32 * LROW) = RB[(i) < NB ? (i) : 0]; }
; template <int NJ> DI void gemm_mainloop_reg(const bf16_t* __restrict__ A, int lda, const bf16_t* __restrict__ Bt, int ldb, int K, f32x16 (&acc)[2][NJ], char* lds) {
;     ...
; #pragma unroll
;   for (int i = 0; i < 4; ++i) GL1_(ra0, rb0, i);
;   ap += 128; bp += 128;
; #pragma unroll
;   for (int i = 0; i < 4; ++i) GL1_(ra1, rb1, i);
;   ap += 128; bp += 128;
; #pragma unroll
;   for (int i = 0; i < 4; ++i) LS1_(ra0, rb0, 0, i);
;   __syncthreads();
;   const int nk = K >> 6;
;   for (int kt = 0; kt < nk; kt += 2) {
;     const bool l0 = (kt + 2 < nk), l1 = (kt + 3 < nk);
;     STEP_(0, l0, ra0, rb0, true, ra1, rb1);
;     __syncthreads();
;     STEP_(1, l1, ra1, rb1, l0, ra0, rb0);
;     __syncthreads();
	ds_read_b128 v[86:89], v0 offset:36864
	ds_read_b128 v[98:101], v66 offset:55296
	ds_read_b128 v[110:113], v0 offset:36896
	ds_read_b128 v[114:117], v66 offset:55328
	ds_read_b128 v[118:121], v0 offset:41472
	ds_read_b128 v[122:125], v0 offset:41504
	s_waitcnt lgkmcnt(4)
	v_mfma_f32_32x32x16_bf16 v[34:49], v[86:89], v[98:101], v[34:49]
	s_add_u32 s2, s36, 0x1080
	s_addc_u32 s3, s37, 0
	s_add_u32 s26, s0, 0x1080
	s_addc_u32 s27, s1, 0
	ds_read_b128 v[126:129], v66 offset:59936
	s_waitcnt lgkmcnt(2)
	v_mfma_f32_32x32x16_bf16 v[2:17], v[118:121], v[98:101], v[2:17]
	ds_read_b128 v[98:101], v66 offset:59904
	s_waitcnt lgkmcnt(0)
	v_mfma_f32_32x32x16_bf16 v[50:65], v[86:89], v[98:101], v[50:65]
	global_load_dwordx4 v[86:89], v72, s[26:27]
	global_load_dwordx4 v[134:137], v72, s[2:3]
	s_waitcnt vmcnt(9)
	ds_write_b128 v67, v[90:93]
	s_waitcnt vmcnt(8)
	ds_write_b128 v67, v[130:133] offset:18432
	v_mfma_f32_32x32x16_bf16 v[18:33], v[118:121], v[98:101], v[18:33]
	global_load_dwordx4 v[90:93], v71, s[26:27]
	global_load_dwordx4 v[98:101], v71, s[2:3]
	v_mfma_f32_32x32x16_bf16 v[2:17], v[122:125], v[114:117], v[2:17]
	v_mfma_f32_32x32x16_bf16 v[18:33], v[122:125], v[126:129], v[18:33]
	v_mfma_f32_32x32x16_bf16 v[34:49], v[110:113], v[114:117], v[34:49]
	v_mfma_f32_32x32x16_bf16 v[50:65], v[110:113], v[126:129], v[50:65]
	ds_read_b128 v[110:113], v0 offset:36928
	ds_read_b128 v[114:117], v0 offset:41536
	ds_read_b128 v[118:121], v66 offset:55360
	ds_read_b128 v[130:133], v66 offset:59968
	s_waitcnt vmcnt(9)
	ds_write_b128 v67, v[74:77] offset:4608
	s_waitcnt vmcnt(8)
	ds_write_b128 v67, v[102:105] offset:23040
	global_load_dwordx4 v[74:77], v70, s[26:27]
	global_load_dwordx4 v[102:105], v70, s[2:3]
	s_waitcnt lgkmcnt(3)
	v_mfma_f32_32x32x16_bf16 v[2:17], v[114:117], v[118:121], v[2:17]
	s_waitcnt lgkmcnt(2)
	v_mfma_f32_32x32x16_bf16 v[18:33], v[114:117], v[130:133], v[18:33]
	v_mfma_f32_32x32x16_bf16 v[34:49], v[110:113], v[118:121], v[34:49]
	v_mfma_f32_32x32x16_bf16 v[50:65], v[110:113], v[130:133], v[50:65]
	ds_read_b128 v[110:113], v0 offset:36960
	ds_read_b128 v[118:121], v0 offset:41568
	ds_read_b128 v[122:125], v66 offset:55392
	ds_read_b128 v[126:129], v66 offset:60000
	s_waitcnt vmcnt(9)
	ds_write_b128 v67, v[78:81] offset:9216
	s_waitcnt vmcnt(8)
	ds_write_b128 v67, v[106:109] offset:27648
	global_load_dwordx4 v[78:81], v69, s[26:27]
	global_load_dwordx4 v[106:109], v69, s[2:3]
	s_waitcnt lgkmcnt(3)
	v_mfma_f32_32x32x16_bf16 v[2:17], v[118:121], v[122:125], v[2:17]
	s_waitcnt vmcnt(9)
	ds_write_b128 v67, v[82:85] offset:13824
	s_waitcnt vmcnt(8)
	ds_write_b128 v67, v[94:97] offset:32256
	s_waitcnt lgkmcnt(4)
	v_mfma_f32_32x32x16_bf16 v[18:33], v[118:121], v[126:129], v[18:33]
	v_mfma_f32_32x32x16_bf16 v[34:49], v[110:113], v[122:125], v[34:49]
	v_mfma_f32_32x32x16_bf16 v[50:65], v[110:113], v[126:129], v[50:65]
	s_waitcnt lgkmcnt(0)
	s_barrier
	ds_read_b128 v[82:85], v0
	ds_read_b128 v[94:97], v66 offset:18432
	ds_read_b128 v[110:113], v0 offset:32
	ds_read_b128 v[114:117], v66 offset:18464
	ds_read_b128 v[118:121], v0 offset:4608
	ds_read_b128 v[122:125], v0 offset:4640
	s_waitcnt lgkmcnt(4)
	v_mfma_f32_32x32x16_bf16 v[34:49], v[82:85], v[94:97], v[34:49]
	s_add_u32 s2, s36, 0x1100
	s_addc_u32 s3, s37, 0
	s_add_u32 s26, s0, 0x1100
	s_addc_u32 s27, s1, 0
	ds_read_b128 v[126:129], v66 offset:23072
	s_waitcnt lgkmcnt(2)
	v_mfma_f32_32x32x16_bf16 v[2:17], v[118:121], v[94:97], v[2:17]
	ds_read_b128 v[94:97], v66 offset:23040
	s_waitcnt lgkmcnt(0)
	v_mfma_f32_32x32x16_bf16 v[50:65], v[82:85], v[94:97], v[50:65]
	global_load_dwordx4 v[82:85], v72, s[26:27]
	global_load_dwordx4 v[130:133], v72, s[2:3]
	s_waitcnt vmcnt(9)
	ds_write_b128 v67, v[86:89] offset:36864
	s_waitcnt vmcnt(8)
	ds_write_b128 v67, v[134:137] offset:55296
	v_mfma_f32_32x32x16_bf16 v[18:33], v[118:121], v[94:97], v[18:33]
	global_load_dwordx4 v[86:89], v71, s[26:27]
	global_load_dwordx4 v[94:97], v71, s[2:3]
	v_mfma_f32_32x32x16_bf16 v[2:17], v[122:125], v[114:117], v[2:17]
	v_mfma_f32_32x32x16_bf16 v[18:33], v[122:125], v[126:129], v[18:33]
	v_mfma_f32_32x32x16_bf16 v[34:49], v[110:113], v[114:117], v[34:49]
	v_mfma_f32_32x32x16_bf16 v[50:65], v[110:113], v[126:129], v[50:65]
	ds_read_b128 v[110:113], v0 offset:64
	ds_read_b128 v[114:117], v0 offset:4672
	ds_read_b128 v[118:121], v66 offset:18496
	ds_read_b128 v[134:137], v66 offset:23104
	s_waitcnt vmcnt(9)
	ds_write_b128 v67, v[90:93] offset:41472
	s_waitcnt vmcnt(8)
	ds_write_b128 v67, v[98:101] offset:59904
	global_load_dwordx4 v[90:93], v70, s[26:27]
	global_load_dwordx4 v[98:101], v70, s[2:3]
	s_waitcnt lgkmcnt(3)
	v_mfma_f32_32x32x16_bf16 v[2:17], v[114:117], v[118:121], v[2:17]
	s_waitcnt lgkmcnt(2)
	v_mfma_f32_32x32x16_bf16 v[18:33], v[114:117], v[134:137], v[18:33]
	v_mfma_f32_32x32x16_bf16 v[34:49], v[110:113], v[118:121], v[34:49]
	v_mfma_f32_32x32x16_bf16 v[50:65], v[110:113], v[134:137], v[50:65]
	ds_read_b128 v[110:113], v0 offset:96
	ds_read_b128 v[118:121], v0 offset:4704
	ds_read_b128 v[122:125], v66 offset:18528
	ds_read_b128 v[126:129], v66 offset:23136
	s_waitcnt vmcnt(9)
	ds_write_b128 v67, v[74:77] offset:46080
	s_waitcnt vmcnt(8)
	ds_write_b128 v67, v[102:105] offset:64512
	global_load_dwordx4 v[74:77], v69, s[26:27]
	global_load_dwordx4 v[102:105], v69, s[2:3]
	s_waitcnt lgkmcnt(3)
	v_mfma_f32_32x32x16_bf16 v[2:17], v[118:121], v[122:125], v[2:17]
	s_waitcnt vmcnt(9)
	ds_write_b128 v67, v[78:81] offset:50688
	s_waitcnt vmcnt(8)
	ds_write_b128 v68, v[106:109] offset:13824
	s_waitcnt lgkmcnt(4)
	v_mfma_f32_32x32x16_bf16 v[18:33], v[118:121], v[126:129], v[18:33]
	v_mfma_f32_32x32x16_bf16 v[34:49], v[110:113], v[122:125], v[34:49]
	v_mfma_f32_32x32x16_bf16 v[50:65], v[110:113], v[126:129], v[50:65]
	s_waitcnt lgkmcnt(0)
	s_barrier
; #define GL1_(RA, RB, i) { RA[i] = *(const u32x4*)(ap + (aoff + (i) * astep)); if ((i) < NB) RB[(i) < NB ? (i) : 0] = *(const u32x4*)(bp + (boff + (i) * bstep)); }
; #define LS1_(RA, RB, ST, i) { char* sn_ = lds + (ST) * STAGE; *(u32x4*)(sn_ + wofs + (i) * 32 * LROW) = RA[i]; \
;                               if ((i) < NB) *(u32x4*)(sn_ + STAGE_OP + wofs + (i) * 32 * LROW) = RB[(i) < NB ? (i) : 0]; }
; template <int NJ> DI void gemm_mainloop_reg(const bf16_t* __restrict__ A, int lda, const bf16_t* __restrict__ Bt, int ldb, int K, f32x16 (&acc)[2][NJ], char* lds) {
;     ...
; #pragma unroll
;   for (int i = 0; i < 4; ++i) GL1_(ra0, rb0, i);
;   ap += 128; bp += 128;
; #pragma unroll
;   for (int i = 0; i < 4; ++i) GL1_(ra1, rb1, i);
;   ap += 128; bp += 128;
; #pragma unroll
;   for (int i = 0; i < 4; ++i) LS1_(ra0, rb0, 0, i);
;   __syncthreads();
;   const int nk = K >> 6;
;   for (int kt = 0; kt < nk; kt += 2) {
;     const bool l0 = (kt + 2 < nk), l1 = (kt + 3 < nk);
;     STEP_(0, l0, ra0, rb0, true, ra1, rb1);
;     __syncthreads();
;     STEP_(1, l1, ra1, rb1, l0, ra0, rb0);
;     __syncthreads();
	ds_read_b128 v[78:81], v0 offset:36864
	ds_read_b128 v[106:109], v66 offset:55296
	ds_read_b128 v[110:113], v0 offset:36896
	ds_read_b128 v[114:117], v66 offset:55328
	ds_read_b128 v[118:121], v0 offset:41472
	ds_read_b128 v[122:125], v0 offset:41504
	s_waitcnt lgkmcnt(4)
	v_mfma_f32_32x32x16_bf16 v[34:49], v[78:81], v[106:109], v[34:49]
	s_add_u32 s2, s36, 0x1180
	s_addc_u32 s3, s37, 0
	s_add_u32 s26, s0, 0x1180
	s_addc_u32 s27, s1, 0
	ds_read_b128 v[126:129], v66 offset:59936
	s_waitcnt lgkmcnt(2)
	v_mfma_f32_32x32x16_bf16 v[2:17], v[118:121], v[106:109], v[2:17]
	ds_read_b128 v[106:109], v66 offset:59904
	s_waitcnt lgkmcnt(0)
	v_mfma_f32_32x32x16_bf16 v[50:65], v[78:81], v[106:109], v[50:65]
	global_load_dwordx4 v[78:81], v72, s[26:27]
	global_load_dwordx4 v[134:137], v72, s[2:3]
	s_waitcnt vmcnt(9)
	ds_write_b128 v67, v[82:85]
	s_waitcnt vmcnt(8)
	ds_write_b128 v67, v[130:133] offset:18432
	v_mfma_f32_32x32x16_bf16 v[18:33], v[118:121], v[106:109], v[18:33]
	global_load_dwordx4 v[82:85], v71, s[26:27]
	global_load_dwordx4 v[106:109], v71, s[2:3]
	v_mfma_f32_32x32x16_bf16 v[2:17], v[122:125], v[114:117], v[2:17]
	v_mfma_f32_32x32x16_bf16 v[18:33], v[122:125], v[126:129], v[18:33]
	v_mfma_f32_32x32x16_bf16 v[34:49], v[110:113], v[114:117], v[34:49]
	v_mfma_f32_32x32x16_bf16 v[50:65], v[110:113], v[126:129], v[50:65]
	ds_read_b128 v[110:113], v0 offset:36928
	ds_read_b128 v[114:117], v0 offset:41536
	ds_read_b128 v[118:121], v66 offset:55360
	ds_read_b128 v[130:133], v66 offset:59968
	s_waitcnt vmcnt(9)
	ds_write_b128 v67, v[86:89] offset:4608
	s_waitcnt vmcnt(8)
	ds_write_b128 v67, v[94:97] offset:23040
	global_load_dwordx4 v[86:89], v70, s[26:27]
	global_load_dwordx4 v[94:97], v70, s[2:3]
	s_waitcnt lgkmcnt(3)
	v_mfma_f32_32x32x16_bf16 v[2:17], v[114:117], v[118:121], v[2:17]
	s_waitcnt lgkmcnt(2)
	v_mfma_f32_32x32x16_bf16 v[18:33], v[114:117], v[130:133], v[18:33]
	v_mfma_f32_32x32x16_bf16 v[34:49], v[110:113], v[118:121], v[34:49]
	v_mfma_f32_32x32x16_bf16 v[50:65], v[110:113], v[130:133], v[50:65]
	ds_read_b128 v[110:113], v0 offset:36960
	ds_read_b128 v[118:121], v0 offset:41568
	ds_read_b128 v[122:125], v66 offset:55392
	ds_read_b128 v[126:129], v66 offset:60000
	s_waitcnt vmcnt(9)
	ds_write_b128 v67, v[90:93] offset:9216
	s_waitcnt vmcnt(8)
	ds_write_b128 v67, v[98:101] offset:27648
	global_load_dwordx4 v[90:93], v69, s[26:27]
	global_load_dwordx4 v[98:101], v69, s[2:3]
	s_waitcnt lgkmcnt(3)
	v_mfma_f32_32x32x16_bf16 v[2:17], v[118:121], v[122:125], v[2:17]
	s_waitcnt vmcnt(9)
	ds_write_b128 v67, v[74:77] offset:13824
	s_waitcnt vmcnt(8)
	ds_write_b128 v67, v[102:105] offset:32256
	s_waitcnt lgkmcnt(4)
	v_mfma_f32_32x32x16_bf16 v[18:33], v[118:121], v[126:129], v[18:33]
	v_mfma_f32_32x32x16_bf16 v[34:49], v[110:113], v[122:125], v[34:49]
	v_mfma_f32_32x32x16_bf16 v[50:65], v[110:113], v[126:129], v[50:65]
	s_waitcnt lgkmcnt(0)
	s_barrier
	ds_read_b128 v[74:77], v0
	ds_read_b128 v[102:105], v66 offset:18432
	ds_read_b128 v[110:113], v0 offset:32
	ds_read_b128 v[114:117], v66 offset:18464
	ds_read_b128 v[118:121], v0 offset:4608
	ds_read_b128 v[122:125], v0 offset:4640
	s_waitcnt lgkmcnt(4)
	v_mfma_f32_32x32x16_bf16 v[34:49], v[74:77], v[102:105], v[34:49]
	s_add_u32 s2, s36, 0x1200
	s_addc_u32 s3, s37, 0
	s_add_u32 s26, s0, 0x1200
	s_addc_u32 s27, s1, 0
	ds_read_b128 v[126:129], v66 offset:23072
	s_waitcnt lgkmcnt(2)
	v_mfma_f32_32x32x16_bf16 v[2:17], v[118:121], v[102:105], v[2:17]
	ds_read_b128 v[102:105], v66 offset:23040
	s_waitcnt lgkmcnt(0)
	v_mfma_f32_32x32x16_bf16 v[50:65], v[74:77], v[102:105], v[50:65]
	global_load_dwordx4 v[74:77], v72, s[26:27]
	global_load_dwordx4 v[130:133], v72, s[2:3]
	s_waitcnt vmcnt(9)
	ds_write_b128 v67, v[78:81] offset:36864
	s_waitcnt vmcnt(8)
	ds_write_b128 v67, v[134:137] offset:55296
	v_mfma_f32_32x32x16_bf16 v[18:33], v[118:121], v[102:105], v[18:33]
	global_load_dwordx4 v[78:81], v71, s[26:27]
	global_load_dwordx4 v[102:105], v71, s[2:3]
	v_mfma_f32_32x32x16_bf16 v[2:17], v[122:125], v[114:117], v[2:17]
	v_mfma_f32_32x32x16_bf16 v[18:33], v[122:125], v[126:129], v[18:33]
	v_mfma_f32_32x32x16_bf16 v[34:49], v[110:113], v[114:117], v[34:49]
	v_mfma_f32_32x32x16_bf16 v[50:65], v[110:113], v[126:129], v[50:65]
	ds_read_b128 v[110:113], v0 offset:64
	ds_read_b128 v[114:117], v0 offset:4672
	ds_read_b128 v[118:121], v66 offset:18496
	ds_read_b128 v[134:137], v66 offset:23104
	s_waitcnt vmcnt(9)
	ds_write_b128 v67, v[82:85] offset:41472
	s_waitcnt vmcnt(8)
	ds_write_b128 v67, v[106:109] offset:59904
	global_load_dwordx4 v[82:85], v70, s[26:27]
	global_load_dwordx4 v[106:109], v70, s[2:3]
	s_waitcnt lgkmcnt(3)
	v_mfma_f32_32x32x16_bf16 v[2:17], v[114:117], v[118:121], v[2:17]
	s_waitcnt lgkmcnt(2)
	v_mfma_f32_32x32x16_bf16 v[18:33], v[114:117], v[134:137], v[18:33]
	v_mfma_f32_32x32x16_bf16 v[34:49], v[110:113], v[118:121], v[34:49]
	v_mfma_f32_32x32x16_bf16 v[50:65], v[110:113], v[134:137], v[50:65]
	ds_read_b128 v[110:113], v0 offset:96
	ds_read_b128 v[118:121], v0 offset:4704
	ds_read_b128 v[122:125], v66 offset:18528
	ds_read_b128 v[126:129], v66 offset:23136
	s_waitcnt vmcnt(9)
	ds_write_b128 v67, v[86:89] offset:46080
	s_waitcnt vmcnt(8)
	ds_write_b128 v67, v[94:97] offset:64512
	global_load_dwordx4 v[86:89], v69, s[26:27]
	global_load_dwordx4 v[94:97], v69, s[2:3]
	s_waitcnt lgkmcnt(3)
	v_mfma_f32_32x32x16_bf16 v[2:17], v[118:121], v[122:125], v[2:17]
	s_waitcnt vmcnt(9)
	ds_write_b128 v67, v[90:93] offset:50688
	s_waitcnt vmcnt(8)
	ds_write_b128 v68, v[98:101] offset:13824
	s_waitcnt lgkmcnt(4)
	v_mfma_f32_32x32x16_bf16 v[18:33], v[118:121], v[126:129], v[18:33]
	v_mfma_f32_32x32x16_bf16 v[34:49], v[110:113], v[122:125], v[34:49]
	v_mfma_f32_32x32x16_bf16 v[50:65], v[110:113], v[126:129], v[50:65]
	s_waitcnt lgkmcnt(0)
	s_barrier
; #define GL1_(RA, RB, i) { RA[i] = *(const u32x4*)(ap + (aoff + (i) * astep)); if ((i) < NB) RB[(i) < NB ? (i) : 0] = *(const u32x4*)(bp + (boff + (i) * bstep)); }
; #define LS1_(RA, RB, ST, i) { char* sn_ = lds + (ST) * STAGE; *(u32x4*)(sn_ + wofs + (i) * 32 * LROW) = RA[i]; \
;                               if ((i) < NB) *(u32x4*)(sn_ + STAGE_OP + wofs + (i) * 32 * LROW) = RB[(i) < NB ? (i) : 0]; }
; template <int NJ> DI void gemm_mainloop_reg(const bf16_t* __restrict__ A, int lda, const bf16_t* __restrict__ Bt, int ldb, int K, f32x16 (&acc)[2][NJ], char* lds) {
;     ...
; #pragma unroll
;   for (int i = 0; i < 4; ++i) GL1_(ra0, rb0, i);
;   ap += 128; bp += 128;
; #pragma unroll
;   for (int i = 0; i < 4; ++i) GL1_(ra1, rb1, i);
;   ap += 128; bp += 128;
; #pragma unroll
;   for (int i = 0; i < 4; ++i) LS1_(ra0, rb0, 0, i);
;   __syncthreads();
;   const int nk = K >> 6;
;   for (int kt = 0; kt < nk; kt += 2) {
;     const bool l0 = (kt + 2 < nk), l1 = (kt + 3 < nk);
;     STEP_(0, l0, ra0, rb0, true, ra1, rb1);
;     __syncthreads();
;     STEP_(1, l1, ra1, rb1, l0, ra0, rb0);
;     __syncthreads();
	ds_read_b128 v[90:93], v0 offset:36864
	ds_read_b128 v[98:101], v66 offset:55296
	ds_read_b128 v[110:113], v0 offset:36896
	ds_read_b128 v[114:117], v66 offset:55328
	ds_read_b128 v[118:121], v0 offset:41472
	ds_read_b128 v[122:125], v0 offset:41504
	s_waitcnt lgkmcnt(4)
	v_mfma_f32_32x32x16_bf16 v[34:49], v[90:93], v[98:101], v[34:49]
	s_add_u32 s2, s36, 0x1280
	s_addc_u32 s3, s37, 0
	s_add_u32 s26, s0, 0x1280
	s_addc_u32 s27, s1, 0
	ds_read_b128 v[126:129], v66 offset:59936
	s_waitcnt lgkmcnt(2)
	v_mfma_f32_32x32x16_bf16 v[2:17], v[118:121], v[98:101], v[2:17]
	ds_read_b128 v[98:101], v66 offset:59904
	s_waitcnt lgkmcnt(0)
	v_mfma_f32_32x32x16_bf16 v[50:65], v[90:93], v[98:101], v[50:65]
	global_load_dwordx4 v[90:93], v72, s[26:27]
	global_load_dwordx4 v[134:137], v72, s[2:3]
	s_waitcnt vmcnt(9)
	ds_write_b128 v67, v[74:77]
	s_waitcnt vmcnt(8)
	ds_write_b128 v67, v[130:133] offset:18432
	v_mfma_f32_32x32x16_bf16 v[18:33], v[118:121], v[98:101], v[18:33]
	global_load_dwordx4 v[74:77], v71, s[26:27]
	global_load_dwordx4 v[98:101], v71, s[2:3]
	v_mfma_f32_32x32x16_bf16 v[2:17], v[122:125], v[114:117], v[2:17]
	v_mfma_f32_32x32x16_bf16 v[18:33], v[122:125], v[126:129], v[18:33]
	v_mfma_f32_32x32x16_bf16 v[34:49], v[110:113], v[114:117], v[34:49]
	v_mfma_f32_32x32x16_bf16 v[50:65], v[110:113], v[126:129], v[50:65]
	ds_read_b128 v[110:113], v0 offset:36928
	ds_read_b128 v[114:117], v0 offset:41536
	ds_read_b128 v[118:121], v66 offset:55360
	ds_read_b128 v[130:133], v66 offset:59968
	s_waitcnt vmcnt(9)
	ds_write_b128 v67, v[78:81] offset:4608
	s_waitcnt vmcnt(8)
	ds_write_b128 v67, v[102:105] offset:23040
	global_load_dwordx4 v[78:81], v70, s[26:27]
	global_load_dwordx4 v[102:105], v70, s[2:3]
	s_waitcnt lgkmcnt(3)
	v_mfma_f32_32x32x16_bf16 v[2:17], v[114:117], v[118:121], v[2:17]
	s_waitcnt lgkmcnt(2)
	v_mfma_f32_32x32x16_bf16 v[18:33], v[114:117], v[130:133], v[18:33]
	v_mfma_f32_32x32x16_bf16 v[34:49], v[110:113], v[118:121], v[34:49]
	v_mfma_f32_32x32x16_bf16 v[50:65], v[110:113], v[130:133], v[50:65]
	ds_read_b128 v[110:113], v0 offset:36960
	ds_read_b128 v[118:121], v0 offset:41568
	ds_read_b128 v[122:125], v66 offset:55392
	ds_read_b128 v[126:129], v66 offset:60000
	s_waitcnt vmcnt(9)
	ds_write_b128 v67, v[82:85] offset:9216
	s_waitcnt vmcnt(8)
	ds_write_b128 v67, v[106:109] offset:27648
	global_load_dwordx4 v[82:85], v69, s[26:27]
	global_load_dwordx4 v[106:109], v69, s[2:3]
	s_waitcnt lgkmcnt(3)
	v_mfma_f32_32x32x16_bf16 v[2:17], v[118:121], v[122:125], v[2:17]
	s_waitcnt vmcnt(9)
	ds_write_b128 v67, v[86:89] offset:13824
	s_waitcnt vmcnt(8)
	ds_write_b128 v67, v[94:97] offset:32256
	s_waitcnt lgkmcnt(4)
	v_mfma_f32_32x32x16_bf16 v[18:33], v[118:121], v[126:129], v[18:33]
	v_mfma_f32_32x32x16_bf16 v[34:49], v[110:113], v[122:125], v[34:49]
	v_mfma_f32_32x32x16_bf16 v[50:65], v[110:113], v[126:129], v[50:65]
	s_waitcnt lgkmcnt(0)
	s_barrier
	ds_read_b128 v[86:89], v0
	ds_read_b128 v[94:97], v66 offset:18432
	ds_read_b128 v[110:113], v0 offset:32
	ds_read_b128 v[114:117], v66 offset:18464
	ds_read_b128 v[118:121], v0 offset:4608
	ds_read_b128 v[122:125], v0 offset:4640
	s_waitcnt lgkmcnt(4)
	v_mfma_f32_32x32x16_bf16 v[34:49], v[86:89], v[94:97], v[34:49]
	s_add_u32 s2, s36, 0x1300
	s_addc_u32 s3, s37, 0
	s_add_u32 s26, s0, 0x1300
	s_addc_u32 s27, s1, 0
	ds_read_b128 v[126:129], v66 offset:23072
	s_waitcnt lgkmcnt(2)
	v_mfma_f32_32x32x16_bf16 v[2:17], v[118:121], v[94:97], v[2:17]
	ds_read_b128 v[94:97], v66 offset:23040
	s_waitcnt lgkmcnt(0)
	v_mfma_f32_32x32x16_bf16 v[50:65], v[86:89], v[94:97], v[50:65]
	global_load_dwordx4 v[86:89], v72, s[26:27]
	global_load_dwordx4 v[130:133], v72, s[2:3]
	s_waitcnt vmcnt(9)
	ds_write_b128 v67, v[90:93] offset:36864
	s_waitcnt vmcnt(8)
	ds_write_b128 v67, v[134:137] offset:55296
	v_mfma_f32_32x32x16_bf16 v[18:33], v[118:121], v[94:97], v[18:33]
	global_load_dwordx4 v[90:93], v71, s[26:27]
	global_load_dwordx4 v[94:97], v71, s[2:3]
	v_mfma_f32_32x32x16_bf16 v[2:17], v[122:125], v[114:117], v[2:17]
	v_mfma_f32_32x32x16_bf16 v[18:33], v[122:125], v[126:129], v[18:33]
	v_mfma_f32_32x32x16_bf16 v[34:49], v[110:113], v[114:117], v[34:49]
	v_mfma_f32_32x32x16_bf16 v[50:65], v[110:113], v[126:129], v[50:65]
	ds_read_b128 v[110:113], v0 offset:64
	ds_read_b128 v[114:117], v0 offset:4672
	ds_read_b128 v[118:121], v66 offset:18496
	ds_read_b128 v[134:137], v66 offset:23104
	s_waitcnt vmcnt(9)
	ds_write_b128 v67, v[74:77] offset:41472
	s_waitcnt vmcnt(8)
	ds_write_b128 v67, v[98:101] offset:59904
	global_load_dwordx4 v[74:77], v70, s[26:27]
	global_load_dwordx4 v[98:101], v70, s[2:3]
	s_waitcnt lgkmcnt(3)
	v_mfma_f32_32x32x16_bf16 v[2:17], v[114:117], v[118:121], v[2:17]
	s_waitcnt lgkmcnt(2)
	v_mfma_f32_32x32x16_bf16 v[18:33], v[114:117], v[134:137], v[18:33]
	v_mfma_f32_32x32x16_bf16 v[34:49], v[110:113], v[118:121], v[34:49]
	v_mfma_f32_32x32x16_bf16 v[50:65], v[110:113], v[134:137], v[50:65]
	ds_read_b128 v[110:113], v0 offset:96
	ds_read_b128 v[118:121], v0 offset:4704
	ds_read_b128 v[122:125], v66 offset:18528
	ds_read_b128 v[126:129], v66 offset:23136
	s_waitcnt vmcnt(9)
	ds_write_b128 v67, v[78:81] offset:46080
	s_waitcnt vmcnt(8)
	ds_write_b128 v67, v[102:105] offset:64512
	global_load_dwordx4 v[78:81], v69, s[26:27]
	global_load_dwordx4 v[102:105], v69, s[2:3]
	s_waitcnt lgkmcnt(3)
	v_mfma_f32_32x32x16_bf16 v[2:17], v[118:121], v[122:125], v[2:17]
	s_waitcnt vmcnt(9)
	ds_write_b128 v67, v[82:85] offset:50688
	s_waitcnt vmcnt(8)
	ds_write_b128 v68, v[106:109] offset:13824
	s_waitcnt lgkmcnt(4)
	v_mfma_f32_32x32x16_bf16 v[18:33], v[118:121], v[126:129], v[18:33]
	v_mfma_f32_32x32x16_bf16 v[34:49], v[110:113], v[122:125], v[34:49]
	v_mfma_f32_32x32x16_bf16 v[50:65], v[110:113], v[126:129], v[50:65]
	s_waitcnt lgkmcnt(0)
	s_barrier
; #define GL1_(RA, RB, i) { RA[i] = *(const u32x4*)(ap + (aoff + (i) * astep)); if ((i) < NB) RB[(i) < NB ? (i) : 0] = *(const u32x4*)(bp + (boff + (i) * bstep)); }
; #define LS1_(RA, RB, ST, i) { char* sn_ = lds + (ST) * STAGE; *(u32x4*)(sn_ + wofs + (i) * 32 * LROW) = RA[i]; \
;                               if ((i) < NB) *(u32x4*)(sn_ + STAGE_OP + wofs + (i) * 32 * LROW) = RB[(i) < NB ? (i) : 0]; }
; template <int NJ> DI void gemm_mainloop_reg(const bf16_t* __restrict__ A, int lda, const bf16_t* __restrict__ Bt, int ldb, int K, f32x16 (&acc)[2][NJ], char* lds) {
;     ...
; #pragma unroll
;   for (int i = 0; i < 4; ++i) GL1_(ra0, rb0, i);
;   ap += 128; bp += 128;
; #pragma unroll
;   for (int i = 0; i < 4; ++i) GL1_(ra1, rb1, i);
;   ap += 128; bp += 128;
; #pragma unroll
;   for (int i = 0; i < 4; ++i) LS1_(ra0, rb0, 0, i);
;   __syncthreads();
;   const int nk = K >> 6;
;   for (int kt = 0; kt < nk; kt += 2) {
;     const bool l0 = (kt + 2 < nk), l1 = (kt + 3 < nk);
;     STEP_(0, l0, ra0, rb0, true, ra1, rb1);
;     __syncthreads();
;     STEP_(1, l1, ra1, rb1, l0, ra0, rb0);
;     __syncthreads();
	ds_read_b128 v[82:85], v0 offset:36864
	ds_read_b128 v[106:109], v66 offset:55296
	ds_read_b128 v[110:113], v0 offset:36896
	ds_read_b128 v[114:117], v66 offset:55328
	ds_read_b128 v[118:121], v0 offset:41472
	ds_read_b128 v[122:125], v0 offset:41504
	s_waitcnt lgkmcnt(4)
	v_mfma_f32_32x32x16_bf16 v[34:49], v[82:85], v[106:109], v[34:49]
	s_add_u32 s2, s36, 0x1380
	s_addc_u32 s3, s37, 0
	s_add_u32 s26, s0, 0x1380
	s_addc_u32 s27, s1, 0
	ds_read_b128 v[126:129], v66 offset:59936
	s_waitcnt lgkmcnt(2)
	v_mfma_f32_32x32x16_bf16 v[2:17], v[118:121], v[106:109], v[2:17]
	ds_read_b128 v[106:109], v66 offset:59904
	s_waitcnt lgkmcnt(0)
	v_mfma_f32_32x32x16_bf16 v[50:65], v[82:85], v[106:109], v[50:65]
	global_load_dwordx4 v[82:85], v72, s[26:27]
	global_load_dwordx4 v[134:137], v72, s[2:3]
	s_waitcnt vmcnt(9)
	ds_write_b128 v67, v[86:89]
	s_waitcnt vmcnt(8)
	ds_write_b128 v67, v[130:133] offset:18432
	v_mfma_f32_32x32x16_bf16 v[18:33], v[118:121], v[106:109], v[18:33]
	global_load_dwordx4 v[86:89], v71, s[26:27]
	global_load_dwordx4 v[106:109], v71, s[2:3]
	v_mfma_f32_32x32x16_bf16 v[2:17], v[122:125], v[114:117], v[2:17]
	v_mfma_f32_32x32x16_bf16 v[18:33], v[122:125], v[126:129], v[18:33]
	v_mfma_f32_32x32x16_bf16 v[34:49], v[110:113], v[114:117], v[34:49]
	v_mfma_f32_32x32x16_bf16 v[50:65], v[110:113], v[126:129], v[50:65]
	ds_read_b128 v[110:113], v0 offset:36928
	ds_read_b128 v[114:117], v0 offset:41536
	ds_read_b128 v[118:121], v66 offset:55360
	ds_read_b128 v[130:133], v66 offset:59968
	s_waitcnt vmcnt(9)
	ds_write_b128 v67, v[90:93] offset:4608
	s_waitcnt vmcnt(8)
	ds_write_b128 v67, v[94:97] offset:23040
	global_load_dwordx4 v[90:93], v70, s[26:27]
	global_load_dwordx4 v[94:97], v70, s[2:3]
	s_waitcnt lgkmcnt(3)
	v_mfma_f32_32x32x16_bf16 v[2:17], v[114:117], v[118:121], v[2:17]
	s_waitcnt lgkmcnt(2)
	v_mfma_f32_32x32x16_bf16 v[18:33], v[114:117], v[130:133], v[18:33]
	v_mfma_f32_32x32x16_bf16 v[34:49], v[110:113], v[118:121], v[34:49]
	v_mfma_f32_32x32x16_bf16 v[50:65], v[110:113], v[130:133], v[50:65]
	ds_read_b128 v[110:113], v0 offset:36960
	ds_read_b128 v[118:121], v0 offset:41568
	ds_read_b128 v[122:125], v66 offset:55392
	ds_read_b128 v[126:129], v66 offset:60000
	s_waitcnt vmcnt(9)
	ds_write_b128 v67, v[74:77] offset:9216
	s_waitcnt vmcnt(8)
	ds_write_b128 v67, v[98:101] offset:27648
	global_load_dwordx4 v[74:77], v69, s[26:27]
	global_load_dwordx4 v[98:101], v69, s[2:3]
	s_waitcnt lgkmcnt(3)
	v_mfma_f32_32x32x16_bf16 v[2:17], v[118:121], v[122:125], v[2:17]
	s_waitcnt vmcnt(9)
	ds_write_b128 v67, v[78:81] offset:13824
	s_waitcnt vmcnt(8)
	ds_write_b128 v67, v[102:105] offset:32256
	s_waitcnt lgkmcnt(4)
	v_mfma_f32_32x32x16_bf16 v[18:33], v[118:121], v[126:129], v[18:33]
	v_mfma_f32_32x32x16_bf16 v[34:49], v[110:113], v[122:125], v[34:49]
	v_mfma_f32_32x32x16_bf16 v[50:65], v[110:113], v[126:129], v[50:65]
	s_waitcnt lgkmcnt(0)
	s_barrier
	ds_read_b128 v[78:81], v0
	ds_read_b128 v[102:105], v66 offset:18432
	ds_read_b128 v[110:113], v0 offset:32
	ds_read_b128 v[114:117], v66 offset:18464
	ds_read_b128 v[118:121], v0 offset:4608
	ds_read_b128 v[122:125], v0 offset:4640
	s_waitcnt lgkmcnt(4)
	v_mfma_f32_32x32x16_bf16 v[34:49], v[78:81], v[102:105], v[34:49]
	s_add_u32 s2, s36, 0x1400
	s_addc_u32 s3, s37, 0
	s_add_u32 s26, s0, 0x1400
	s_addc_u32 s27, s1, 0
	ds_read_b128 v[126:129], v66 offset:23072
	s_waitcnt lgkmcnt(2)
	v_mfma_f32_32x32x16_bf16 v[2:17], v[118:121], v[102:105], v[2:17]
	ds_read_b128 v[102:105], v66 offset:23040
	s_waitcnt lgkmcnt(0)
	v_mfma_f32_32x32x16_bf16 v[50:65], v[78:81], v[102:105], v[50:65]
	global_load_dwordx4 v[78:81], v72, s[26:27]
	global_load_dwordx4 v[130:133], v72, s[2:3]
	s_waitcnt vmcnt(9)
	ds_write_b128 v67, v[82:85] offset:36864
	s_waitcnt vmcnt(8)
	ds_write_b128 v67, v[134:137] offset:55296
	v_mfma_f32_32x32x16_bf16 v[18:33], v[118:121], v[102:105], v[18:33]
	global_load_dwordx4 v[82:85], v71, s[26:27]
	global_load_dwordx4 v[102:105], v71, s[2:3]
	v_mfma_f32_32x32x16_bf16 v[2:17], v[122:125], v[114:117], v[2:17]
	v_mfma_f32_32x32x16_bf16 v[18:33], v[122:125], v[126:129], v[18:33]
	v_mfma_f32_32x32x16_bf16 v[34:49], v[110:113], v[114:117], v[34:49]
	v_mfma_f32_32x32x16_bf16 v[50:65], v[110:113], v[126:129], v[50:65]
	ds_read_b128 v[110:113], v0 offset:64
	ds_read_b128 v[114:117], v0 offset:4672
	ds_read_b128 v[118:121], v66 offset:18496
	ds_read_b128 v[134:137], v66 offset:23104
	s_waitcnt vmcnt(9)
	ds_write_b128 v67, v[86:89] offset:41472
	s_waitcnt vmcnt(8)
	ds_write_b128 v67, v[106:109] offset:59904
	global_load_dwordx4 v[86:89], v70, s[26:27]
	global_load_dwordx4 v[106:109], v70, s[2:3]
	s_waitcnt lgkmcnt(3)
	v_mfma_f32_32x32x16_bf16 v[2:17], v[114:117], v[118:121], v[2:17]
	s_waitcnt lgkmcnt(2)
	v_mfma_f32_32x32x16_bf16 v[18:33], v[114:117], v[134:137], v[18:33]
	v_mfma_f32_32x32x16_bf16 v[34:49], v[110:113], v[118:121], v[34:49]
	v_mfma_f32_32x32x16_bf16 v[50:65], v[110:113], v[134:137], v[50:65]
	ds_read_b128 v[110:113], v0 offset:96
	ds_read_b128 v[118:121], v0 offset:4704
	ds_read_b128 v[122:125], v66 offset:18528
	ds_read_b128 v[126:129], v66 offset:23136
	s_waitcnt vmcnt(9)
	ds_write_b128 v67, v[90:93] offset:46080
	s_waitcnt vmcnt(8)
	ds_write_b128 v67, v[94:97] offset:64512
	global_load_dwordx4 v[90:93], v69, s[26:27]
	global_load_dwordx4 v[94:97], v69, s[2:3]
	s_waitcnt lgkmcnt(3)
	v_mfma_f32_32x32x16_bf16 v[2:17], v[118:121], v[122:125], v[2:17]
	s_waitcnt vmcnt(9)
	ds_write_b128 v67, v[74:77] offset:50688
	s_waitcnt vmcnt(8)
	ds_write_b128 v68, v[98:101] offset:13824
	s_waitcnt lgkmcnt(4)
	v_mfma_f32_32x32x16_bf16 v[18:33], v[118:121], v[126:129], v[18:33]
	v_mfma_f32_32x32x16_bf16 v[34:49], v[110:113], v[122:125], v[34:49]
	v_mfma_f32_32x32x16_bf16 v[50:65], v[110:113], v[126:129], v[50:65]
	s_waitcnt lgkmcnt(0)
	s_barrier
; #define GL1_(RA, RB, i) { RA[i] = *(const u32x4*)(ap + (aoff + (i) * astep)); if ((i) < NB) RB[(i) < NB ? (i) : 0] = *(const u32x4*)(bp + (boff + (i) * bstep)); }
; #define LS1_(RA, RB, ST, i) { char* sn_ = lds + (ST) * STAGE; *(u32x4*)(sn_ + wofs + (i) * 32 * LROW) = RA[i]; \
;                               if ((i) < NB) *(u32x4*)(sn_ + STAGE_OP + wofs + (i) * 32 * LROW) = RB[(i) < NB ? (i) : 0]; }
; template <int NJ> DI void gemm_mainloop_reg(const bf16_t* __restrict__ A, int lda, const bf16_t* __restrict__ Bt, int ldb, int K, f32x16 (&acc)[2][NJ], char* lds) {
;     ...
; #pragma unroll
;   for (int i = 0; i < 4; ++i) GL1_(ra0, rb0, i);
;   ap += 128; bp += 128;
; #pragma unroll
;   for (int i = 0; i < 4; ++i) GL1_(ra1, rb1, i);
;   ap += 128; bp += 128;
; #pragma unroll
;   for (int i = 0; i < 4; ++i) LS1_(ra0, rb0, 0, i);
;   __syncthreads();
;   const int nk = K >> 6;
;   for (int kt = 0; kt < nk; kt += 2) {
;     const bool l0 = (kt + 2 < nk), l1 = (kt + 3 < nk);
;     STEP_(0, l0, ra0, rb0, true, ra1, rb1);
;     __syncthreads();
;     STEP_(1, l1, ra1, rb1, l0, ra0, rb0);
;     __syncthreads();
	ds_read_b128 v[74:77], v0 offset:36864
	ds_read_b128 v[98:101], v66 offset:55296
	ds_read_b128 v[110:113], v0 offset:36896
	ds_read_b128 v[114:117], v66 offset:55328
	ds_read_b128 v[118:121], v0 offset:41472
	ds_read_b128 v[122:125], v0 offset:41504
	s_waitcnt lgkmcnt(4)
	v_mfma_f32_32x32x16_bf16 v[34:49], v[74:77], v[98:101], v[34:49]
	s_add_u32 s2, s36, 0x1480
	s_addc_u32 s3, s37, 0
	s_add_u32 s26, s0, 0x1480
	s_addc_u32 s27, s1, 0
	ds_read_b128 v[126:129], v66 offset:59936
	s_waitcnt lgkmcnt(2)
	v_mfma_f32_32x32x16_bf16 v[2:17], v[118:121], v[98:101], v[2:17]
	ds_read_b128 v[98:101], v66 offset:59904
	s_waitcnt lgkmcnt(0)
	v_mfma_f32_32x32x16_bf16 v[50:65], v[74:77], v[98:101], v[50:65]
	global_load_dwordx4 v[74:77], v72, s[26:27]
	global_load_dwordx4 v[134:137], v72, s[2:3]
	s_waitcnt vmcnt(9)
	ds_write_b128 v67, v[78:81]
	s_waitcnt vmcnt(8)
	ds_write_b128 v67, v[130:133] offset:18432
	v_mfma_f32_32x32x16_bf16 v[18:33], v[118:121], v[98:101], v[18:33]
	global_load_dwordx4 v[78:81], v71, s[26:27]
	global_load_dwordx4 v[98:101], v71, s[2:3]
	v_mfma_f32_32x32x16_bf16 v[2:17], v[122:125], v[114:117], v[2:17]
	v_mfma_f32_32x32x16_bf16 v[18:33], v[122:125], v[126:129], v[18:33]
	v_mfma_f32_32x32x16_bf16 v[34:49], v[110:113], v[114:117], v[34:49]
	v_mfma_f32_32x32x16_bf16 v[50:65], v[110:113], v[126:129], v[50:65]
	ds_read_b128 v[110:113], v0 offset:36928
	ds_read_b128 v[114:117], v0 offset:41536
	ds_read_b128 v[118:121], v66 offset:55360
	ds_read_b128 v[130:133], v66 offset:59968
	s_waitcnt vmcnt(9)
	ds_write_b128 v67, v[82:85] offset:4608
	s_waitcnt vmcnt(8)
	ds_write_b128 v67, v[102:105] offset:23040
	global_load_dwordx4 v[82:85], v70, s[26:27]
	global_load_dwordx4 v[102:105], v70, s[2:3]
	s_waitcnt lgkmcnt(3)
	v_mfma_f32_32x32x16_bf16 v[2:17], v[114:117], v[118:121], v[2:17]
	s_waitcnt lgkmcnt(2)
	v_mfma_f32_32x32x16_bf16 v[18:33], v[114:117], v[130:133], v[18:33]
	v_mfma_f32_32x32x16_bf16 v[34:49], v[110:113], v[118:121], v[34:49]
	v_mfma_f32_32x32x16_bf16 v[50:65], v[110:113], v[130:133], v[50:65]
	ds_read_b128 v[110:113], v0 offset:36960
	ds_read_b128 v[118:121], v0 offset:41568
	ds_read_b128 v[122:125], v66 offset:55392
	ds_read_b128 v[126:129], v66 offset:60000
	s_waitcnt vmcnt(9)
	ds_write_b128 v67, v[86:89] offset:9216
	s_waitcnt vmcnt(8)
	ds_write_b128 v67, v[106:109] offset:27648
	global_load_dwordx4 v[86:89], v69, s[26:27]
	global_load_dwordx4 v[106:109], v69, s[2:3]
	s_waitcnt lgkmcnt(3)
	v_mfma_f32_32x32x16_bf16 v[2:17], v[118:121], v[122:125], v[2:17]
	s_waitcnt vmcnt(9)
	ds_write_b128 v67, v[90:93] offset:13824
	s_waitcnt vmcnt(8)
	ds_write_b128 v67, v[94:97] offset:32256
	s_waitcnt lgkmcnt(4)
	v_mfma_f32_32x32x16_bf16 v[18:33], v[118:121], v[126:129], v[18:33]
	v_mfma_f32_32x32x16_bf16 v[34:49], v[110:113], v[122:125], v[34:49]
	v_mfma_f32_32x32x16_bf16 v[50:65], v[110:113], v[126:129], v[50:65]
	s_waitcnt lgkmcnt(0)
	s_barrier
	ds_read_b128 v[90:93], v0
	ds_read_b128 v[94:97], v66 offset:18432
	ds_read_b128 v[110:113], v0 offset:32
	ds_read_b128 v[114:117], v66 offset:18464
	ds_read_b128 v[118:121], v0 offset:4608
	ds_read_b128 v[122:125], v0 offset:4640
	s_waitcnt lgkmcnt(4)
	v_mfma_f32_32x32x16_bf16 v[34:49], v[90:93], v[94:97], v[34:49]
	s_add_u32 s2, s36, 0x1500
	s_addc_u32 s3, s37, 0
	s_add_u32 s26, s0, 0x1500
	s_addc_u32 s27, s1, 0
	ds_read_b128 v[126:129], v66 offset:23072
	s_waitcnt lgkmcnt(2)
	v_mfma_f32_32x32x16_bf16 v[2:17], v[118:121], v[94:97], v[2:17]
	ds_read_b128 v[94:97], v66 offset:23040
	s_waitcnt lgkmcnt(0)
	v_mfma_f32_32x32x16_bf16 v[50:65], v[90:93], v[94:97], v[50:65]
	global_load_dwordx4 v[90:93], v72, s[26:27]
	global_load_dwordx4 v[130:133], v72, s[2:3]
	s_waitcnt vmcnt(9)
	ds_write_b128 v67, v[74:77] offset:36864
	s_waitcnt vmcnt(8)
	ds_write_b128 v67, v[134:137] offset:55296
	v_mfma_f32_32x32x16_bf16 v[18:33], v[118:121], v[94:97], v[18:33]
	global_load_dwordx4 v[74:77], v71, s[26:27]
	global_load_dwordx4 v[94:97], v71, s[2:3]
	v_mfma_f32_32x32x16_bf16 v[2:17], v[122:125], v[114:117], v[2:17]
	v_mfma_f32_32x32x16_bf16 v[18:33], v[122:125], v[126:129], v[18:33]
	v_mfma_f32_32x32x16_bf16 v[34:49], v[110:113], v[114:117], v[34:49]
	v_mfma_f32_32x32x16_bf16 v[50:65], v[110:113], v[126:129], v[50:65]
	ds_read_b128 v[110:113], v0 offset:64
	ds_read_b128 v[114:117], v0 offset:4672
	ds_read_b128 v[118:121], v66 offset:18496
	ds_read_b128 v[134:137], v66 offset:23104
	s_waitcnt vmcnt(9)
	ds_write_b128 v67, v[78:81] offset:41472
	s_waitcnt vmcnt(8)
	ds_write_b128 v67, v[98:101] offset:59904
	global_load_dwordx4 v[78:81], v70, s[26:27]
	global_load_dwordx4 v[98:101], v70, s[2:3]
	s_waitcnt lgkmcnt(3)
	v_mfma_f32_32x32x16_bf16 v[2:17], v[114:117], v[118:121], v[2:17]
	s_waitcnt lgkmcnt(2)
	v_mfma_f32_32x32x16_bf16 v[18:33], v[114:117], v[134:137], v[18:33]
	v_mfma_f32_32x32x16_bf16 v[34:49], v[110:113], v[118:121], v[34:49]
	v_mfma_f32_32x32x16_bf16 v[50:65], v[110:113], v[134:137], v[50:65]
	ds_read_b128 v[110:113], v0 offset:96
	ds_read_b128 v[118:121], v0 offset:4704
	ds_read_b128 v[122:125], v66 offset:18528
	ds_read_b128 v[126:129], v66 offset:23136
	s_waitcnt vmcnt(9)
	ds_write_b128 v67, v[82:85] offset:46080
	s_waitcnt vmcnt(8)
	ds_write_b128 v67, v[102:105] offset:64512
	global_load_dwordx4 v[82:85], v69, s[26:27]
	global_load_dwordx4 v[102:105], v69, s[2:3]
	s_waitcnt lgkmcnt(3)
	v_mfma_f32_32x32x16_bf16 v[2:17], v[118:121], v[122:125], v[2:17]
	s_waitcnt vmcnt(9)
	ds_write_b128 v67, v[86:89] offset:50688
	s_waitcnt vmcnt(8)
	ds_write_b128 v68, v[106:109] offset:13824
	s_waitcnt lgkmcnt(4)
	v_mfma_f32_32x32x16_bf16 v[18:33], v[118:121], v[126:129], v[18:33]
	v_mfma_f32_32x32x16_bf16 v[34:49], v[110:113], v[122:125], v[34:49]
	v_mfma_f32_32x32x16_bf16 v[50:65], v[110:113], v[126:129], v[50:65]
	s_waitcnt lgkmcnt(0)
	s_barrier
; #define GL1_(RA, RB, i) { RA[i] = *(const u32x4*)(ap + (aoff + (i) * astep)); if ((i) < NB) RB[(i) < NB ? (i) : 0] = *(const u32x4*)(bp + (boff + (i) * bstep)); }
; #define LS1_(RA, RB, ST, i) { char* sn_ = lds + (ST) * STAGE; *(u32x4*)(sn_ + wofs + (i) * 32 * LROW) = RA[i]; \
;                               if ((i) < NB) *(u32x4*)(sn_ + STAGE_OP + wofs + (i) * 32 * LROW) = RB[(i) < NB ? (i) : 0]; }
; template <int NJ> DI void gemm_mainloop_reg(const bf16_t* __restrict__ A, int lda, const bf16_t* __restrict__ Bt, int ldb, int K, f32x16 (&acc)[2][NJ], char* lds) {
;     ...
; #pragma unroll
;   for (int i = 0; i < 4; ++i) GL1_(ra0, rb0, i);
;   ap += 128; bp += 128;
; #pragma unroll
;   for (int i = 0; i < 4; ++i) GL1_(ra1, rb1, i);
;   ap += 128; bp += 128;
; #pragma unroll
;   for (int i = 0; i < 4; ++i) LS1_(ra0, rb0, 0, i);
;   __syncthreads();
;   const int nk = K >> 6;
;   for (int kt = 0; kt < nk; kt += 2) {
;     const bool l0 = (kt + 2 < nk), l1 = (kt + 3 < nk);
;     STEP_(0, l0, ra0, rb0, true, ra1, rb1);
;     __syncthreads();
;     STEP_(1, l1, ra1, rb1, l0, ra0, rb0);
;     __syncthreads();
	ds_read_b128 v[86:89], v0 offset:36864
	ds_read_b128 v[106:109], v66 offset:55296
	ds_read_b128 v[110:113], v0 offset:41472
	s_waitcnt lgkmcnt(1)
	v_mfma_f32_32x32x16_bf16 v[34:49], v[86:89], v[106:109], v[34:49]
	s_add_u32 s2, s36, 0x1580
	s_addc_u32 s3, s37, 0
	s_add_u32 s0, s0, 0x1580
	s_addc_u32 s1, s1, 0
	s_waitcnt lgkmcnt(0)
	v_mfma_f32_32x32x16_bf16 v[2:17], v[110:113], v[106:109], v[2:17]
	ds_read_b128 v[106:109], v66 offset:59904
	s_waitcnt lgkmcnt(0)
	v_mfma_f32_32x32x16_bf16 v[50:65], v[86:89], v[106:109], v[50:65]
	global_load_dwordx4 v[86:89], v72, s[0:1]
	global_load_dwordx4 v[114:117], v72, s[2:3]
	ds_read_b128 v[118:121], v0 offset:36896
	ds_read_b128 v[122:125], v66 offset:55328
	ds_read_b128 v[126:129], v0 offset:41504
	ds_read_b128 v[134:137], v66 offset:59936
	s_waitcnt vmcnt(9)
	ds_write_b128 v67, v[90:93]
	s_waitcnt vmcnt(8)
	ds_write_b128 v67, v[130:133] offset:18432
	v_mfma_f32_32x32x16_bf16 v[18:33], v[110:113], v[106:109], v[18:33]
	global_load_dwordx4 v[90:93], v71, s[0:1]
	global_load_dwordx4 v[106:109], v71, s[2:3]
	s_waitcnt lgkmcnt(3)
	v_mfma_f32_32x32x16_bf16 v[2:17], v[126:129], v[122:125], v[2:17]
	s_waitcnt lgkmcnt(2)
	v_mfma_f32_32x32x16_bf16 v[18:33], v[126:129], v[134:137], v[18:33]
	v_mfma_f32_32x32x16_bf16 v[34:49], v[118:121], v[122:125], v[34:49]
	v_mfma_f32_32x32x16_bf16 v[50:65], v[118:121], v[134:137], v[50:65]
	ds_read_b128 v[110:113], v0 offset:36928
	ds_read_b128 v[118:121], v0 offset:41536
	ds_read_b128 v[122:125], v66 offset:55360
	ds_read_b128 v[130:133], v66 offset:59968
	s_waitcnt vmcnt(9)
	ds_write_b128 v67, v[74:77] offset:4608
	s_waitcnt vmcnt(8)
	ds_write_b128 v67, v[94:97] offset:23040
	global_load_dwordx4 v[72:75], v70, s[0:1]
	global_load_dwordx4 v[94:97], v70, s[2:3]
	s_waitcnt lgkmcnt(3)
	v_mfma_f32_32x32x16_bf16 v[2:17], v[118:121], v[122:125], v[2:17]
	s_waitcnt lgkmcnt(2)
	v_mfma_f32_32x32x16_bf16 v[18:33], v[118:121], v[130:133], v[18:33]
	v_mfma_f32_32x32x16_bf16 v[34:49], v[110:113], v[122:125], v[34:49]
	v_mfma_f32_32x32x16_bf16 v[50:65], v[110:113], v[130:133], v[50:65]
	ds_read_b128 v[110:113], v0 offset:36960
	ds_read_b128 v[122:125], v0 offset:41568
	ds_read_b128 v[126:129], v66 offset:55392
	ds_read_b128 v[134:137], v66 offset:60000
	s_waitcnt vmcnt(9)
	ds_write_b128 v67, v[78:81] offset:9216
	s_waitcnt vmcnt(8)
	ds_write_b128 v67, v[98:101] offset:27648
	global_load_dwordx4 v[76:79], v69, s[0:1]
	global_load_dwordx4 v[98:101], v69, s[2:3]
	s_waitcnt lgkmcnt(3)
	v_mfma_f32_32x32x16_bf16 v[2:17], v[122:125], v[126:129], v[2:17]
	s_waitcnt vmcnt(9)
	ds_write_b128 v67, v[82:85] offset:13824
	s_waitcnt vmcnt(8)
	ds_write_b128 v67, v[102:105] offset:32256
	s_waitcnt lgkmcnt(4)
	v_mfma_f32_32x32x16_bf16 v[18:33], v[122:125], v[134:137], v[18:33]
	v_mfma_f32_32x32x16_bf16 v[34:49], v[110:113], v[126:129], v[34:49]
	v_mfma_f32_32x32x16_bf16 v[50:65], v[110:113], v[134:137], v[50:65]
	s_waitcnt lgkmcnt(0)
	s_barrier
	ds_read_b128 v[80:83], v0
	ds_read_b128 v[102:105], v66 offset:18432
	ds_read_b128 v[110:113], v0 offset:4608
	s_waitcnt lgkmcnt(1)
	v_mfma_f32_32x32x16_bf16 v[34:49], v[80:83], v[102:105], v[34:49]
	s_waitcnt lgkmcnt(0)
	v_mfma_f32_32x32x16_bf16 v[2:17], v[110:113], v[102:105], v[2:17]
	ds_read_b128 v[102:105], v66 offset:23040
	s_waitcnt lgkmcnt(0)
	v_mfma_f32_32x32x16_bf16 v[18:33], v[110:113], v[102:105], v[18:33]
	v_mfma_f32_32x32x16_bf16 v[50:65], v[80:83], v[102:105], v[50:65]
	ds_read_b128 v[80:83], v0 offset:32
	ds_read_b128 v[118:121], v66 offset:18464
	ds_read_b128 v[122:125], v0 offset:4640
	ds_read_b128 v[126:129], v66 offset:23072
	s_waitcnt vmcnt(7)
	ds_write_b128 v67, v[86:89] offset:36864
	s_waitcnt vmcnt(6)
	ds_write_b128 v67, v[114:117] offset:55296
	s_waitcnt lgkmcnt(3)
	v_mfma_f32_32x32x16_bf16 v[2:17], v[122:125], v[118:121], v[2:17]
	s_waitcnt lgkmcnt(2)
	v_mfma_f32_32x32x16_bf16 v[18:33], v[122:125], v[126:129], v[18:33]
	v_mfma_f32_32x32x16_bf16 v[34:49], v[80:83], v[118:121], v[34:49]
	v_mfma_f32_32x32x16_bf16 v[50:65], v[80:83], v[126:129], v[50:65]
	ds_read_b128 v[80:83], v0 offset:64
	ds_read_b128 v[84:87], v0 offset:4672
	ds_read_b128 v[102:105], v66 offset:18496
	ds_read_b128 v[110:113], v66 offset:23104
	s_waitcnt vmcnt(5)
	ds_write_b128 v67, v[90:93] offset:41472
	s_waitcnt vmcnt(4)
	ds_write_b128 v67, v[106:109] offset:59904
	s_waitcnt lgkmcnt(3)
	v_mfma_f32_32x32x16_bf16 v[2:17], v[84:87], v[102:105], v[2:17]
	s_waitcnt lgkmcnt(2)
	v_mfma_f32_32x32x16_bf16 v[18:33], v[84:87], v[110:113], v[18:33]
	v_mfma_f32_32x32x16_bf16 v[34:49], v[80:83], v[102:105], v[34:49]
	v_mfma_f32_32x32x16_bf16 v[50:65], v[80:83], v[110:113], v[50:65]
	ds_read_b128 v[80:83], v0 offset:96
	ds_read_b128 v[88:91], v0 offset:4704
	ds_read_b128 v[102:105], v66 offset:18528
	ds_read_b128 v[106:109], v66 offset:23136
	s_waitcnt vmcnt(3)
	ds_write_b128 v67, v[72:75] offset:46080
	s_waitcnt vmcnt(2)
	ds_write_b128 v67, v[94:97] offset:64512
	s_waitcnt lgkmcnt(3)
	v_mfma_f32_32x32x16_bf16 v[2:17], v[88:91], v[102:105], v[2:17]
	s_waitcnt vmcnt(1)
	ds_write_b128 v67, v[76:79] offset:50688
	s_waitcnt vmcnt(0)
	ds_write_b128 v68, v[98:101] offset:13824
	s_waitcnt lgkmcnt(4)
	v_mfma_f32_32x32x16_bf16 v[18:33], v[88:91], v[106:109], v[18:33]
	v_mfma_f32_32x32x16_bf16 v[34:49], v[80:83], v[102:105], v[34:49]
	v_mfma_f32_32x32x16_bf16 v[50:65], v[80:83], v[106:109], v[50:65]
	s_waitcnt lgkmcnt(0)
	s_barrier
; DI int tid_() { int t = threadIdx.x; asm volatile("" : "+v"(t)); return t; }
; template <int NJ> DI void gemm_mainloop_reg(const bf16_t* __restrict__ A, int lda, const bf16_t* __restrict__ Bt, int ldb, int K, f32x16 (&acc)[2][NJ], char* lds) {
;     ...
; #pragma unroll
;   for (int i = 0; i < 4; ++i) GL1_(ra0, rb0, i);
;   ap += 128; bp += 128;
; #pragma unroll
;   for (int i = 0; i < 4; ++i) GL1_(ra1, rb1, i);
;   ap += 128; bp += 128;
; #pragma unroll
;   for (int i = 0; i < 4; ++i) LS1_(ra0, rb0, 0, i);
;   __syncthreads();
;   const int nk = K >> 6;
;   for (int kt = 0; kt < nk; kt += 2) {
;     const bool l0 = (kt + 2 < nk), l1 = (kt + 3 < nk);
;     STEP_(0, l0, ra0, rb0, true, ra1, rb1);
;     __syncthreads();
;     STEP_(1, l1, ra1, rb1, l0, ra0, rb0);
;     __syncthreads();
; template <int NJ> DI void acc_to_lds(const f32x16 (&acc)[2][NJ], float* cl) {
;   const int tid = tid_(), lane = tid & 63, w = tid >> 6, wm = w >> 1, wn = w & 1, h = lane >> 5, c = lane & 31;
; #pragma unroll
;   for (int i = 0; i < 2; ++i)
; #pragma unroll
;     for (int j = 0; j < NJ; ++j)
; #pragma unroll
;       for (int r = 0; r < 16; ++r) {
;         const int row = wm * 64 + i * 32 + (r & 3) + 8 * (r >> 2) + 4 * h;
;         cl[row * CLD + wn * 32 * NJ + j * 32 + c] = acc[i][j][r];
;       }
; }
; template <int NJ> DI void resid_epilogue(float* __restrict__ x, bf16_t* __restrict__ xb, float* __restrict__ ssn, int mt, int nt, const float* cl, float scale) {
;   constexpr int LPR = 16 * NJ, RPP = 256 / LPR, NP = 128 / RPP;
;   const int tid = tid_(), c4 = (tid & (LPR - 1)) * 4, r0 = tid / LPR;
; #pragma unroll 4
;   for (int it = 0; it < NP; ++it) {
;     const int row = r0 + RPP * it;
;     const f32x4 c = *(const f32x4*)(cl + row * CLD + c4);
;     const size_t gi = (size_t)(mt * 128 + row) * DM + nt * (64 * NJ) + c4;
;     f32x4 xv = *(const f32x4*)(x + gi);
;     xv = xv + scale * c;
;     *(f32x4*)(x + gi) = xv;
;     u32x2 p; p.x = pk2(xv[0], xv[1]); p.y = pk2(xv[2], xv[3]);
;     *(u32x2*)(xb + (size_t)(mt * 128 + row) * LDX + nt * (64 * NJ) + c4) = p;
;     float s_ = xv[0] * xv[0] + xv[1] * xv[1] + xv[2] * xv[2] + xv[3] * xv[3];
;     if (NJ == 2) s_ += __shfl_xor(s_, 16);
;     s_ += __shfl_xor(s_, 8); s_ += __shfl_xor(s_, 4); s_ += __shfl_xor(s_, 2); s_ += __shfl_xor(s_, 1);
;     if ((tid & (LPR - 1)) == 0) atomicAdd(ssn + mt * 128 + row, s_);
;   }
	ds_read_b128 v[68:71], v0 offset:36864
	ds_read_b128 v[72:75], v66 offset:55296
	ds_read_b128 v[76:79], v0 offset:41472
	s_waitcnt lgkmcnt(1)
	v_mfma_f32_32x32x16_bf16 v[34:49], v[68:71], v[72:75], v[34:49]
	s_waitcnt lgkmcnt(0)
	v_mfma_f32_32x32x16_bf16 v[2:17], v[76:79], v[72:75], v[2:17]
	ds_read_b128 v[72:75], v66 offset:59904
	s_waitcnt lgkmcnt(0)
	v_mfma_f32_32x32x16_bf16 v[18:33], v[76:79], v[72:75], v[18:33]
	v_mfma_f32_32x32x16_bf16 v[50:65], v[68:71], v[72:75], v[50:65]
	ds_read_b128 v[68:71], v0 offset:36896
	ds_read_b128 v[80:83], v66 offset:55328
	ds_read_b128 v[84:87], v0 offset:41504
	ds_read_b128 v[88:91], v66 offset:59936
	s_waitcnt lgkmcnt(1)
	v_mfma_f32_32x32x16_bf16 v[2:17], v[84:87], v[80:83], v[2:17]
	s_waitcnt lgkmcnt(0)
	v_mfma_f32_32x32x16_bf16 v[18:33], v[84:87], v[88:91], v[18:33]
	v_mfma_f32_32x32x16_bf16 v[34:49], v[68:71], v[80:83], v[34:49]
	v_mfma_f32_32x32x16_bf16 v[50:65], v[68:71], v[88:91], v[50:65]
	ds_read_b128 v[68:71], v0 offset:36928
	ds_read_b128 v[72:75], v0 offset:41536
	ds_read_b128 v[76:79], v66 offset:55360
	ds_read_b128 v[80:83], v66 offset:59968
	s_waitcnt lgkmcnt(1)
	v_mfma_f32_32x32x16_bf16 v[2:17], v[72:75], v[76:79], v[2:17]
	s_waitcnt lgkmcnt(0)
	v_mfma_f32_32x32x16_bf16 v[18:33], v[72:75], v[80:83], v[18:33]
	v_mfma_f32_32x32x16_bf16 v[34:49], v[68:71], v[76:79], v[34:49]
	v_mfma_f32_32x32x16_bf16 v[50:65], v[68:71], v[80:83], v[50:65]
	ds_read_b128 v[68:71], v0 offset:36960
	ds_read_b128 v[76:79], v0 offset:41568
	ds_read_b128 v[84:87], v66 offset:55392
	ds_read_b128 v[88:91], v66 offset:60000
	s_waitcnt lgkmcnt(1)
	v_mfma_f32_32x32x16_bf16 v[2:17], v[76:79], v[84:87], v[2:17]
	s_waitcnt lgkmcnt(0)
	v_mfma_f32_32x32x16_bf16 v[18:33], v[76:79], v[88:91], v[18:33]
	v_mfma_f32_32x32x16_bf16 v[34:49], v[68:71], v[84:87], v[34:49]
	v_mfma_f32_32x32x16_bf16 v[50:65], v[68:71], v[88:91], v[50:65]
	s_setprio 0
	v_mov_b32_e32 v0, v199
	s_barrier
	s_add_i32 s0, s39, s11
	v_lshrrev_b32_e32 v67, 3, v0
	v_lshrrev_b32_e32 v66, 1, v0
	v_and_b32_e32 v67, 4, v67
	v_and_b32_e32 v0, 0x5f, v0
	v_and_or_b32 v66, v66, s17, v67
	v_mul_lo_u32 v66, v66, s15
	v_lshlrev_b32_e32 v0, 2, v0
	v_add3_u32 v0, 0, v66, v0
	s_nop 0
	ds_write2_b32 v0, v34, v50 offset1:32
	ds_write2_b32 v0, v35, v51 offset0:132 offset1:164
	v_add_u32_e32 v34, 0x400, v0
	ds_write2_b32 v34, v36, v52 offset0:8 offset1:40
	ds_write2_b32 v34, v37, v53 offset0:140 offset1:172
	v_add_u32_e32 v34, 0x1000, v0
	ds_write2_b32 v34, v38, v54 offset0:32 offset1:64
	ds_write2_b32 v34, v39, v55 offset0:164 offset1:196
	v_add_u32_e32 v34, 0x1400, v0
	ds_write2_b32 v34, v40, v56 offset0:40 offset1:72
	ds_write2_b32 v34, v41, v57 offset0:172 offset1:204
	v_add_u32_e32 v34, 0x2000, v0
	ds_write2_b32 v34, v42, v58 offset0:64 offset1:96
	ds_write2_b32 v34, v43, v59 offset0:196 offset1:228
	v_add_u32_e32 v34, 0x2400, v0
	ds_write2_b32 v34, v44, v60 offset0:72 offset1:104
	ds_write2_b32 v34, v45, v61 offset0:204 offset1:236
	v_add_u32_e32 v34, 0x3000, v0
	ds_write2_b32 v34, v46, v62 offset0:96 offset1:128
	v_add_u32_e32 v34, 0x3200, v0
	ds_write2_b32 v34, v47, v63 offset0:100 offset1:132
	v_add_u32_e32 v34, 0x3400, v0
	ds_write2_b32 v34, v48, v64 offset0:104 offset1:136
	v_add_u32_e32 v34, 0x3600, v0
	ds_write2_b32 v34, v49, v65 offset0:108 offset1:140
	v_add_u32_e32 v34, 0x4000, v0
	ds_write2_b32 v34, v2, v18 offset0:128 offset1:160
	v_add_u32_e32 v2, 0x4400, v0
	ds_write2_b32 v2, v3, v19 offset0:4 offset1:36
	ds_write2_b32 v2, v4, v20 offset0:136 offset1:168
	v_add_u32_e32 v2, 0x4800, v0
	ds_write2_b32 v2, v5, v21 offset0:12 offset1:44
	v_add_u32_e32 v2, 0x5000, v0
	ds_write2_b32 v2, v6, v22 offset0:160 offset1:192
	v_add_u32_e32 v2, 0x5400, v0
	ds_write2_b32 v2, v7, v23 offset0:36 offset1:68
	ds_write2_b32 v2, v8, v24 offset0:168 offset1:200
	v_add_u32_e32 v2, 0x5800, v0
	ds_write2_b32 v2, v9, v25 offset0:44 offset1:76
	v_add_u32_e32 v2, 0x6000, v0
	ds_write2_b32 v2, v10, v26 offset0:192 offset1:224
	v_add_u32_e32 v2, 0x6400, v0
	ds_write2_b32 v2, v11, v27 offset0:68 offset1:100
	ds_write2_b32 v2, v12, v28 offset0:200 offset1:232
	v_add_u32_e32 v2, 0x6800, v0
	ds_write2_b32 v2, v13, v29 offset0:76 offset1:108
	v_add_u32_e32 v2, 0x7200, v0
	ds_write2_b32 v2, v14, v30 offset0:96 offset1:128
	v_add_u32_e32 v2, 0x7400, v0
	ds_write2_b32 v2, v15, v31 offset0:100 offset1:132
	v_add_u32_e32 v2, 0x7600, v0
	v_add_u32_e32 v0, 0x7800, v0
	ds_write2_b32 v0, v17, v33 offset0:108 offset1:140
	v_mov_b32_e32 v0, v199
	ds_write2_b32 v2, v16, v32 offset0:104 offset1:136
	s_waitcnt lgkmcnt(0)
	s_barrier
	v_mov_b64_e32 v[18:19], s[72:73]
	v_ashrrev_i32_e32 v2, 31, v0
	v_lshrrev_b32_e32 v2, 27, v2
	v_and_b32_e32 v6, 31, v0
	v_add_u32_e32 v0, v0, v2
	v_ashrrev_i32_e32 v14, 5, v0
	v_add_u32_e32 v4, s0, v14
	v_mad_i64_i32 v[2:3], s[0:1], v4, s9, v[18:19]
	v_cmp_lt_i32_e32 vcc, v222, v220
	s_add_i32 s0, s39, s12
	v_add_u32_e32 v10, s0, v14
	v_cndmask_b32_e32 v0, v219, v222, vcc
	v_cmp_lt_i32_e32 vcc, v223, v220
	v_lshlrev_b32_e32 v22, 2, v0
	v_mad_i64_i32 v[8:9], s[0:1], v10, s9, v[18:19]
	v_cndmask_b32_e32 v0, v219, v223, vcc
	v_cmp_lt_i32_e32 vcc, v224, v220
	v_lshlrev_b32_e32 v23, 2, v0
	s_add_u32 s0, s40, s6
	v_cndmask_b32_e32 v0, v219, v224, vcc
	v_cmp_lt_i32_e32 vcc, v225, v220
	v_lshlrev_b32_e32 v24, 2, v0
	s_addc_u32 s1, 0, s7
	v_cndmask_b32_e32 v0, v219, v225, vcc
	v_cmp_lt_i32_e32 vcc, v226, v220
	s_add_i32 s39, s39, s13
	v_lshlrev_b32_e32 v25, 2, v0
	v_cndmask_b32_e32 v0, v219, v226, vcc
	v_add_u32_e32 v20, s41, v14
	v_add_u32_e32 v16, s39, v14
	v_lshlrev_b32_e32 v26, 2, v0
	v_cmp_eq_u32_e32 vcc, 0, v6
	v_ashrrev_i32_e32 v15, 31, v14
	v_ashrrev_i32_e32 v5, 31, v4
	v_lshlrev_b32_e32 v0, 3, v6
	v_lshlrev_b32_e32 v28, 4, v6
	v_mul_lo_u32 v6, v14, s15
	v_ashrrev_i32_e32 v21, 31, v20
	v_ashrrev_i32_e32 v11, 31, v10
	v_ashrrev_i32_e32 v17, 31, v16
	v_lshlrev_b64 v[4:5], 12, v[4:5]
	v_add3_u32 v27, v6, v28, 0
	v_lshlrev_b64 v[6:7], 12, v[20:21]
	v_lshlrev_b64 v[10:11], 12, v[10:11]
	v_lshl_add_u64 v[12:13], v[14:15], 2, s[0:1]
	v_mad_i64_i32 v[14:15], s[0:1], v16, s9, v[18:19]
	v_lshlrev_b64 v[16:17], 12, v[16:17]
	v_mad_i64_i32 v[18:19], s[0:1], v20, s9, v[18:19]
	v_lshl_add_u64 v[2:3], v[2:3], 0, v[0:1]
	v_or3_b32 v4, v4, s38, v28
	v_or3_b32 v6, v6, s38, v28
	v_lshl_add_u64 v[8:9], v[8:9], 0, v[0:1]
	v_or3_b32 v10, v10, s38, v28
	v_lshl_add_u64 v[14:15], v[14:15], 0, v[0:1]
	v_or3_b32 v16, v16, s38, v28
	v_lshl_add_u64 v[18:19], v[18:19], 0, v[0:1]
	v_lshl_add_u64 v[2:3], v[2:3], 0, s[80:81]
	v_lshl_add_u64 v[4:5], s[92:93], 0, v[4:5]
	v_lshl_add_u64 v[6:7], s[92:93], 0, v[6:7]
	v_lshl_add_u64 v[8:9], v[8:9], 0, s[80:81]
	v_lshl_add_u64 v[10:11], s[92:93], 0, v[10:11]
	v_lshl_add_u64 v[14:15], v[14:15], 0, s[80:81]
	v_lshl_add_u64 v[16:17], s[92:93], 0, v[16:17]
	v_lshl_add_u64 v[18:19], v[18:19], 0, s[80:81]
	s_mov_b64 s[0:1], 0
	s_branch .LBB0_429

; DI int tid_() { int t = threadIdx.x; asm volatile("" : "+v"(t)); return t; }
; #define GL1_(RA, RB, i) { RA[i] = *(const u32x4*)(ap + (aoff + (i) * astep)); if ((i) < NB) RB[(i) < NB ? (i) : 0] = *(const u32x4*)(bp + (boff + (i) * bstep)); }
; #define LS1_(RA, RB, ST, i) { char* sn_ = lds + (ST) * STAGE; *(u32x4*)(sn_ + wofs + (i) * 32 * LROW) = RA[i]; \
;                               if ((i) < NB) *(u32x4*)(sn_ + STAGE_OP + wofs + (i) * 32 * LROW) = RB[(i) < NB ? (i) : 0]; }
; template <int NJ> DI void gemm_mainloop_reg(const bf16_t* __restrict__ A, int lda, const bf16_t* __restrict__ Bt, int ldb, int K, f32x16 (&acc)[2][NJ], char* lds) {
;     ...
; #pragma unroll
;   for (int i = 0; i < 4; ++i) GL1_(ra0, rb0, i);
;   ap += 128; bp += 128;
; #pragma unroll
;   for (int i = 0; i < 4; ++i) GL1_(ra1, rb1, i);
;   ap += 128; bp += 128;
; #pragma unroll
;   for (int i = 0; i < 4; ++i) LS1_(ra0, rb0, 0, i);
;   __syncthreads();
;   const int nk = K >> 6;
;   for (int kt = 0; kt < nk; kt += 2) {
;     const bool l0 = (kt + 2 < nk), l1 = (kt + 3 < nk);
;     STEP_(0, l0, ra0, rb0, true, ra1, rb1);
; DI int grab_next(unsigned* ctr, char* lds) {
;   volatile int* nx = (volatile int*)(lds + OFF_RR + 528);
;   if (tid_() == 0) *nx = (int)__hip_atomic_fetch_add(ctr, 1u, __ATOMIC_RELAXED, __HIP_MEMORY_SCOPE_AGENT);
;   __syncthreads();
;   const int v = __builtin_amdgcn_readfirstlane(*nx);
;   __syncthreads();
;   return v;
; DI void phase_proj(const Ctx& c, bool dummy_ss = false) {
;     ...
;     const int j_ = grab_next(ctr, c.lds);
;     if (j_ >= 128 * 4) break;
;     const int mt = xcd_ * 16 + (j_ & 7) + 8 * ((j_ >> 6) & 1), nt = (j_ >> 7) * 8 + ((j_ >> 3) & 7);
;     if (nt >= 28) continue;
;     f32x16 acc[2][2]; zero_acc<2>(acc);
;     gemm_mainloop_reg<2>(A + (size_t)mt * 128 * LDX, LDX, Bt + (size_t)nt * 128 * LDX, LDX, DM, acc, c.lds);
.LBB0_497:
	s_or_b64 exec, exec, s[2:3]
	s_cmp_lg_u32 s24, -1
	s_cselect_b32 s2, s24, 0
	s_cselect_b32 s3, s79, 0
	v_mov_b32_e32 v2, s2
	v_mov_b32_e32 v3, s3
	s_waitcnt lgkmcnt(0)
	s_barrier
	flat_load_dword v0, v[2:3] sc0 sc1
	s_waitcnt vmcnt(0)
	s_mov_b64 s[2:3], -1
	s_waitcnt lgkmcnt(0)
	s_barrier
	v_readfirstlane_b32 s4, v0
	s_cmpk_gt_i32 s4, 0x1ff
	s_cbranch_scc1 .LBB0_492
	s_ashr_i32 s2, s4, 4
	s_and_b32 s2, s2, -8
	s_bfe_u32 s3, s4, 0x30003
	s_or_b32 s6, s2, s3
	s_cmp_gt_i32 s6, 27
	s_cbranch_scc1 .LBB0_491
	s_lshr_b32 s2, s4, 3
	s_and_b32 s3, s4, 7
	s_and_b32 s2, s2, 8
	s_or_b32 s2, s3, s2
	v_readlane_b32 s3, v250, 20
	s_or_b32 s7, s2, s3
	v_mov_b32_e32 v34, v199
	s_mul_i32 s2, s7, 0x44000
	v_readlane_b32 s3, v252, 10
	s_add_u32 s2, s3, s2
	v_ashrrev_i32_e32 v0, 3, v34
	v_lshlrev_b32_e32 v2, 4, v34
	v_readlane_b32 s3, v252, 11
	v_and_b32_e32 v35, 0x70, v2
	v_mul_lo_u32 v2, v0, s9
	s_addc_u32 s3, s3, 0
	s_mul_i32 s4, s6, 0x44000
	v_or_b32_e32 v72, v35, v2
	s_mul_hi_i32 s5, s6, 0x44000
	s_add_u32 s4, s37, s4
	v_add_u32_e32 v71, 0x11000, v72
	v_add_u32_e32 v70, 0x22000, v72
	v_add_u32_e32 v69, 0x33000, v72
	s_addc_u32 s5, s25, s5
	global_load_dwordx4 v[2:5], v72, s[2:3]
	global_load_dwordx4 v[6:9], v71, s[2:3]
	global_load_dwordx4 v[10:13], v70, s[2:3]
	global_load_dwordx4 v[14:17], v69, s[2:3]
	global_load_dwordx4 v[18:21], v72, s[4:5]
	global_load_dwordx4 v[22:25], v71, s[4:5]
	global_load_dwordx4 v[26:29], v70, s[4:5]
	global_load_dwordx4 v[30:33], v69, s[4:5]
	v_mul_lo_u32 v0, v0, s16
	v_lshrrev_b32_e32 v36, 1, v34
	v_and_b32_e32 v37, 31, v34
	v_add3_u32 v67, v0, v35, 0
	v_and_b32_e32 v38, 16, v36
	v_and_or_b32 v36, v36, s17, v37
	global_load_dwordx4 v[74:77], v72, s[2:3] offset:128
	global_load_dwordx4 v[78:81], v71, s[2:3] offset:128
	global_load_dwordx4 v[82:85], v70, s[2:3] offset:128
	global_load_dwordx4 v[86:89], v69, s[2:3] offset:128
	global_load_dwordx4 v[90:93], v72, s[4:5] offset:128
	global_load_dwordx4 v[94:97], v71, s[4:5] offset:128
	global_load_dwordx4 v[98:101], v70, s[4:5] offset:128
	global_load_dwordx4 v[102:105], v69, s[4:5] offset:128
	v_mul_lo_u32 v0, v36, s16
	v_add3_u32 v0, v0, v38, 0
	v_add_u32_e32 v68, 0xd800, v67
	s_waitcnt vmcnt(15)
	ds_write_b128 v67, v[2:5]
	s_waitcnt vmcnt(14)
	ds_write_b128 v67, v[6:9] offset:4608
	s_waitcnt vmcnt(13)
	ds_write_b128 v67, v[10:13] offset:9216
	s_waitcnt vmcnt(12)
	ds_write_b128 v67, v[14:17] offset:13824
	s_waitcnt vmcnt(11)
	ds_write_b128 v67, v[18:21] offset:18432
	s_waitcnt vmcnt(10)
	ds_write_b128 v67, v[22:25] offset:23040
	s_waitcnt vmcnt(9)
	ds_write_b128 v67, v[26:29] offset:27648
	s_waitcnt vmcnt(8)
	ds_write_b128 v67, v[30:33] offset:32256
	v_and_b32_e32 v2, 0x5f, v34
	v_mul_u32_u24_e32 v2, 0x90, v2
	v_add3_u32 v66, v2, v38, 0
	s_waitcnt lgkmcnt(0)
	s_barrier
	ds_read_b128 v[18:21], v0
	ds_read_b128 v[2:5], v66 offset:18432
	ds_read_b128 v[106:109], v0 offset:32
	ds_read_b128 v[110:113], v66 offset:18464
	ds_read_b128 v[22:25], v0 offset:4608
	ds_read_b128 v[114:117], v0 offset:4640
	ds_read_b128 v[26:29], v66 offset:23040
	ds_read_b128 v[118:121], v66 offset:23072
	global_load_dwordx4 v[122:125], v72, s[2:3] offset:256
	global_load_dwordx4 v[126:129], v72, s[4:5] offset:256
	s_waitcnt lgkmcnt(6)
	s_setprio 1
	v_mfma_f32_32x32x16_bf16 v[34:49], v[18:21], v[2:5], 0
	s_waitcnt vmcnt(9)
	ds_write_b128 v67, v[74:77] offset:36864
	s_waitcnt vmcnt(5)
	ds_write_b128 v67, v[90:93] offset:55296
	s_waitcnt lgkmcnt(5)
	v_mfma_f32_32x32x16_bf16 v[2:17], v[22:25], v[2:5], 0
	s_waitcnt lgkmcnt(3)
	v_mfma_f32_32x32x16_bf16 v[50:65], v[18:21], v[26:29], 0
	v_mfma_f32_32x32x16_bf16 v[18:33], v[22:25], v[26:29], 0
	global_load_dwordx4 v[74:77], v71, s[2:3] offset:256
	global_load_dwordx4 v[90:93], v71, s[4:5] offset:256
	v_mfma_f32_32x32x16_bf16 v[34:49], v[106:109], v[110:113], v[34:49]
	v_mfma_f32_32x32x16_bf16 v[2:17], v[114:117], v[110:113], v[2:17]
	s_waitcnt lgkmcnt(2)
	v_mfma_f32_32x32x16_bf16 v[50:65], v[106:109], v[118:121], v[50:65]
	ds_read_b128 v[106:109], v0 offset:64
	ds_read_b128 v[110:113], v0 offset:4672
	ds_read_b128 v[130:133], v66 offset:18496
	ds_read_b128 v[134:137], v66 offset:23104
	ds_write_b128 v67, v[78:81] offset:41472
	s_waitcnt vmcnt(6)
	ds_write_b128 v67, v[94:97] offset:59904
	v_mfma_f32_32x32x16_bf16 v[18:33], v[114:117], v[118:121], v[18:33]
	global_load_dwordx4 v[78:81], v70, s[2:3] offset:256
	global_load_dwordx4 v[94:97], v70, s[4:5] offset:256
	s_waitcnt lgkmcnt(3)
	v_mfma_f32_32x32x16_bf16 v[34:49], v[106:109], v[130:133], v[34:49]
	v_mfma_f32_32x32x16_bf16 v[2:17], v[110:113], v[130:133], v[2:17]
	s_waitcnt lgkmcnt(2)
	v_mfma_f32_32x32x16_bf16 v[50:65], v[106:109], v[134:137], v[50:65]
	ds_read_b128 v[106:109], v0 offset:96
	ds_read_b128 v[114:117], v0 offset:4704
	ds_read_b128 v[118:121], v66 offset:18528
	ds_read_b128 v[130:133], v66 offset:23136
	ds_write_b128 v67, v[82:85] offset:46080
	s_waitcnt vmcnt(7)
	ds_write_b128 v67, v[98:101] offset:64512
	v_mfma_f32_32x32x16_bf16 v[18:33], v[110:113], v[134:137], v[18:33]
	global_load_dwordx4 v[82:85], v69, s[2:3] offset:256
	global_load_dwordx4 v[98:101], v69, s[4:5] offset:256
	s_waitcnt lgkmcnt(3)
	v_mfma_f32_32x32x16_bf16 v[34:49], v[106:109], v[118:121], v[34:49]
	ds_write_b128 v67, v[86:89] offset:50688
	s_waitcnt vmcnt(8)
	ds_write_b128 v68, v[102:105] offset:13824
	v_mfma_f32_32x32x16_bf16 v[2:17], v[114:117], v[118:121], v[2:17]
	s_waitcnt lgkmcnt(4)
	v_mfma_f32_32x32x16_bf16 v[50:65], v[106:109], v[130:133], v[50:65]
	v_mfma_f32_32x32x16_bf16 v[18:33], v[114:117], v[130:133], v[18:33]
	s_waitcnt lgkmcnt(0)
	s_barrier
; #define GL1_(RA, RB, i) { RA[i] = *(const u32x4*)(ap + (aoff + (i) * astep)); if ((i) < NB) RB[(i) < NB ? (i) : 0] = *(const u32x4*)(bp + (boff + (i) * bstep)); }
; #define LS1_(RA, RB, ST, i) { char* sn_ = lds + (ST) * STAGE; *(u32x4*)(sn_ + wofs + (i) * 32 * LROW) = RA[i]; \
;                               if ((i) < NB) *(u32x4*)(sn_ + STAGE_OP + wofs + (i) * 32 * LROW) = RB[(i) < NB ? (i) : 0]; }
; template <int NJ> DI void gemm_mainloop_reg(const bf16_t* __restrict__ A, int lda, const bf16_t* __restrict__ Bt, int ldb, int K, f32x16 (&acc)[2][NJ], char* lds) {
;     ...
; #pragma unroll
;   for (int i = 0; i < 4; ++i) GL1_(ra0, rb0, i);
;   ap += 128; bp += 128;
; #pragma unroll
;   for (int i = 0; i < 4; ++i) GL1_(ra1, rb1, i);
;   ap += 128; bp += 128;
; #pragma unroll
;   for (int i = 0; i < 4; ++i) LS1_(ra0, rb0, 0, i);
;   __syncthreads();
;   const int nk = K >> 6;
;   for (int kt = 0; kt < nk; kt += 2) {
;     const bool l0 = (kt + 2 < nk), l1 = (kt + 3 < nk);
;     STEP_(0, l0, ra0, rb0, true, ra1, rb1);
;     __syncthreads();
;     STEP_(1, l1, ra1, rb1, l0, ra0, rb0);
;     __syncthreads();
	ds_read_b128 v[86:89], v0 offset:36864
	ds_read_b128 v[102:105], v66 offset:55296
	ds_read_b128 v[106:109], v0 offset:36896
	ds_read_b128 v[110:113], v66 offset:55328
	ds_read_b128 v[114:117], v0 offset:41472
	ds_read_b128 v[118:121], v0 offset:41504
	s_waitcnt lgkmcnt(4)
	v_mfma_f32_32x32x16_bf16 v[34:49], v[86:89], v[102:105], v[34:49]
	s_waitcnt lgkmcnt(1)
	v_mfma_f32_32x32x16_bf16 v[2:17], v[114:117], v[102:105], v[2:17]
	ds_read_b128 v[102:105], v66 offset:59904
	ds_read_b128 v[130:133], v66 offset:59936
	s_waitcnt lgkmcnt(1)
	v_mfma_f32_32x32x16_bf16 v[50:65], v[86:89], v[102:105], v[50:65]
	global_load_dwordx4 v[86:89], v72, s[2:3] offset:384
	global_load_dwordx4 v[134:137], v72, s[4:5] offset:384
	s_waitcnt vmcnt(9)
	ds_write_b128 v67, v[122:125]
	s_waitcnt vmcnt(8)
	ds_write_b128 v67, v[126:129] offset:18432
	v_mfma_f32_32x32x16_bf16 v[18:33], v[114:117], v[102:105], v[18:33]
	v_mfma_f32_32x32x16_bf16 v[34:49], v[106:109], v[110:113], v[34:49]
	s_waitcnt lgkmcnt(2)
	v_mfma_f32_32x32x16_bf16 v[50:65], v[106:109], v[130:133], v[50:65]
	global_load_dwordx4 v[102:105], v71, s[2:3] offset:384
	global_load_dwordx4 v[106:109], v71, s[4:5] offset:384
	v_mfma_f32_32x32x16_bf16 v[2:17], v[118:121], v[110:113], v[2:17]
	ds_read_b128 v[110:113], v0 offset:36928
	ds_read_b128 v[114:117], v0 offset:41536
	ds_read_b128 v[122:125], v66 offset:55360
	ds_read_b128 v[126:129], v66 offset:59968
	s_waitcnt vmcnt(9)
	ds_write_b128 v67, v[74:77] offset:4608
	s_waitcnt vmcnt(8)
	ds_write_b128 v67, v[90:93] offset:23040
	v_mfma_f32_32x32x16_bf16 v[18:33], v[118:121], v[130:133], v[18:33]
	global_load_dwordx4 v[74:77], v70, s[2:3] offset:384
	global_load_dwordx4 v[90:93], v70, s[4:5] offset:384
	s_waitcnt lgkmcnt(3)
	v_mfma_f32_32x32x16_bf16 v[34:49], v[110:113], v[122:125], v[34:49]
	v_mfma_f32_32x32x16_bf16 v[2:17], v[114:117], v[122:125], v[2:17]
	s_waitcnt lgkmcnt(2)
	v_mfma_f32_32x32x16_bf16 v[50:65], v[110:113], v[126:129], v[50:65]
	ds_read_b128 v[110:113], v0 offset:36960
	ds_read_b128 v[118:121], v0 offset:41568
	ds_read_b128 v[122:125], v66 offset:55392
	ds_read_b128 v[130:133], v66 offset:60000
	s_waitcnt vmcnt(9)
	ds_write_b128 v67, v[78:81] offset:9216
	s_waitcnt vmcnt(8)
	ds_write_b128 v67, v[94:97] offset:27648
	v_mfma_f32_32x32x16_bf16 v[18:33], v[114:117], v[126:129], v[18:33]
	global_load_dwordx4 v[78:81], v69, s[2:3] offset:384
	global_load_dwordx4 v[94:97], v69, s[4:5] offset:384
	s_waitcnt lgkmcnt(3)
	v_mfma_f32_32x32x16_bf16 v[34:49], v[110:113], v[122:125], v[34:49]
	s_waitcnt vmcnt(9)
	ds_write_b128 v67, v[82:85] offset:13824
	s_waitcnt vmcnt(8)
	ds_write_b128 v67, v[98:101] offset:32256
	v_mfma_f32_32x32x16_bf16 v[2:17], v[118:121], v[122:125], v[2:17]
	s_waitcnt lgkmcnt(4)
	v_mfma_f32_32x32x16_bf16 v[50:65], v[110:113], v[130:133], v[50:65]
	v_mfma_f32_32x32x16_bf16 v[18:33], v[118:121], v[130:133], v[18:33]
	s_waitcnt lgkmcnt(0)
	s_barrier
	ds_read_b128 v[82:85], v0
	ds_read_b128 v[98:101], v66 offset:18432
	ds_read_b128 v[110:113], v0 offset:32
	ds_read_b128 v[114:117], v66 offset:18464
	ds_read_b128 v[118:121], v0 offset:4608
	ds_read_b128 v[122:125], v0 offset:4640
	s_waitcnt lgkmcnt(4)
	v_mfma_f32_32x32x16_bf16 v[34:49], v[82:85], v[98:101], v[34:49]
	s_waitcnt lgkmcnt(1)
	v_mfma_f32_32x32x16_bf16 v[2:17], v[118:121], v[98:101], v[2:17]
	ds_read_b128 v[98:101], v66 offset:23040
	ds_read_b128 v[126:129], v66 offset:23072
	s_waitcnt lgkmcnt(1)
	v_mfma_f32_32x32x16_bf16 v[50:65], v[82:85], v[98:101], v[50:65]
	global_load_dwordx4 v[82:85], v72, s[2:3] offset:512
	global_load_dwordx4 v[130:133], v72, s[4:5] offset:512
	s_waitcnt vmcnt(9)
	ds_write_b128 v67, v[86:89] offset:36864
	s_waitcnt vmcnt(8)
	ds_write_b128 v67, v[134:137] offset:55296
	v_mfma_f32_32x32x16_bf16 v[18:33], v[118:121], v[98:101], v[18:33]
	global_load_dwordx4 v[86:89], v71, s[2:3] offset:512
	global_load_dwordx4 v[98:101], v71, s[4:5] offset:512
	v_mfma_f32_32x32x16_bf16 v[34:49], v[110:113], v[114:117], v[34:49]
	v_mfma_f32_32x32x16_bf16 v[2:17], v[122:125], v[114:117], v[2:17]
	s_waitcnt lgkmcnt(2)
	v_mfma_f32_32x32x16_bf16 v[50:65], v[110:113], v[126:129], v[50:65]
	ds_read_b128 v[110:113], v0 offset:64
	ds_read_b128 v[114:117], v0 offset:4672
	ds_read_b128 v[118:121], v66 offset:18496
	ds_read_b128 v[134:137], v66 offset:23104
	s_waitcnt vmcnt(9)
	ds_write_b128 v67, v[102:105] offset:41472
	s_waitcnt vmcnt(8)
	ds_write_b128 v67, v[106:109] offset:59904
	v_mfma_f32_32x32x16_bf16 v[18:33], v[122:125], v[126:129], v[18:33]
	global_load_dwordx4 v[102:105], v70, s[2:3] offset:512
	global_load_dwordx4 v[106:109], v70, s[4:5] offset:512
	s_waitcnt lgkmcnt(3)
	v_mfma_f32_32x32x16_bf16 v[34:49], v[110:113], v[118:121], v[34:49]
	v_mfma_f32_32x32x16_bf16 v[2:17], v[114:117], v[118:121], v[2:17]
	s_waitcnt lgkmcnt(2)
	v_mfma_f32_32x32x16_bf16 v[50:65], v[110:113], v[134:137], v[50:65]
	ds_read_b128 v[110:113], v0 offset:96
	ds_read_b128 v[118:121], v0 offset:4704
	ds_read_b128 v[122:125], v66 offset:18528
	ds_read_b128 v[126:129], v66 offset:23136
	s_waitcnt vmcnt(9)
	ds_write_b128 v67, v[74:77] offset:46080
	s_waitcnt vmcnt(8)
	ds_write_b128 v67, v[90:93] offset:64512
	v_mfma_f32_32x32x16_bf16 v[18:33], v[114:117], v[134:137], v[18:33]
	global_load_dwordx4 v[74:77], v69, s[2:3] offset:512
	global_load_dwordx4 v[90:93], v69, s[4:5] offset:512
	s_waitcnt lgkmcnt(3)
	v_mfma_f32_32x32x16_bf16 v[34:49], v[110:113], v[122:125], v[34:49]
	s_waitcnt vmcnt(9)
	ds_write_b128 v67, v[78:81] offset:50688
	s_waitcnt vmcnt(8)
	ds_write_b128 v68, v[94:97] offset:13824
	v_mfma_f32_32x32x16_bf16 v[2:17], v[118:121], v[122:125], v[2:17]
	s_waitcnt lgkmcnt(4)
	v_mfma_f32_32x32x16_bf16 v[50:65], v[110:113], v[126:129], v[50:65]
	v_mfma_f32_32x32x16_bf16 v[18:33], v[118:121], v[126:129], v[18:33]
	s_waitcnt lgkmcnt(0)
	s_barrier
; #define GL1_(RA, RB, i) { RA[i] = *(const u32x4*)(ap + (aoff + (i) * astep)); if ((i) < NB) RB[(i) < NB ? (i) : 0] = *(const u32x4*)(bp + (boff + (i) * bstep)); }
; #define LS1_(RA, RB, ST, i) { char* sn_ = lds + (ST) * STAGE; *(u32x4*)(sn_ + wofs + (i) * 32 * LROW) = RA[i]; \
;                               if ((i) < NB) *(u32x4*)(sn_ + STAGE_OP + wofs + (i) * 32 * LROW) = RB[(i) < NB ? (i) : 0]; }
; template <int NJ> DI void gemm_mainloop_reg(const bf16_t* __restrict__ A, int lda, const bf16_t* __restrict__ Bt, int ldb, int K, f32x16 (&acc)[2][NJ], char* lds) {
;     ...
; #pragma unroll
;   for (int i = 0; i < 4; ++i) GL1_(ra0, rb0, i);
;   ap += 128; bp += 128;
; #pragma unroll
;   for (int i = 0; i < 4; ++i) GL1_(ra1, rb1, i);
;   ap += 128; bp += 128;
; #pragma unroll
;   for (int i = 0; i < 4; ++i) LS1_(ra0, rb0, 0, i);
;   __syncthreads();
;   const int nk = K >> 6;
;   for (int kt = 0; kt < nk; kt += 2) {
;     const bool l0 = (kt + 2 < nk), l1 = (kt + 3 < nk);
;     STEP_(0, l0, ra0, rb0, true, ra1, rb1);
;     __syncthreads();
;     STEP_(1, l1, ra1, rb1, l0, ra0, rb0);
;     __syncthreads();
	ds_read_b128 v[78:81], v0 offset:36864
	ds_read_b128 v[94:97], v66 offset:55296
	ds_read_b128 v[110:113], v0 offset:36896
	ds_read_b128 v[114:117], v66 offset:55328
	ds_read_b128 v[118:121], v0 offset:41472
	ds_read_b128 v[122:125], v0 offset:41504
	s_waitcnt lgkmcnt(4)
	v_mfma_f32_32x32x16_bf16 v[34:49], v[78:81], v[94:97], v[34:49]
	s_waitcnt lgkmcnt(1)
	v_mfma_f32_32x32x16_bf16 v[2:17], v[118:121], v[94:97], v[2:17]
	ds_read_b128 v[94:97], v66 offset:59904
	ds_read_b128 v[126:129], v66 offset:59936
	s_waitcnt lgkmcnt(1)
	v_mfma_f32_32x32x16_bf16 v[50:65], v[78:81], v[94:97], v[50:65]
	global_load_dwordx4 v[78:81], v72, s[2:3] offset:640
	global_load_dwordx4 v[134:137], v72, s[4:5] offset:640
	s_waitcnt vmcnt(9)
	ds_write_b128 v67, v[82:85]
	s_waitcnt vmcnt(8)
	ds_write_b128 v67, v[130:133] offset:18432
	v_mfma_f32_32x32x16_bf16 v[18:33], v[118:121], v[94:97], v[18:33]
	global_load_dwordx4 v[82:85], v71, s[2:3] offset:640
	global_load_dwordx4 v[94:97], v71, s[4:5] offset:640
	v_mfma_f32_32x32x16_bf16 v[34:49], v[110:113], v[114:117], v[34:49]
	v_mfma_f32_32x32x16_bf16 v[2:17], v[122:125], v[114:117], v[2:17]
	s_waitcnt lgkmcnt(2)
	v_mfma_f32_32x32x16_bf16 v[50:65], v[110:113], v[126:129], v[50:65]
	ds_read_b128 v[110:113], v0 offset:36928
	ds_read_b128 v[114:117], v0 offset:41536
	ds_read_b128 v[118:121], v66 offset:55360
	ds_read_b128 v[130:133], v66 offset:59968
	s_waitcnt vmcnt(9)
	ds_write_b128 v67, v[86:89] offset:4608
	s_waitcnt vmcnt(8)
	ds_write_b128 v67, v[98:101] offset:23040
	v_mfma_f32_32x32x16_bf16 v[18:33], v[122:125], v[126:129], v[18:33]
	global_load_dwordx4 v[86:89], v70, s[2:3] offset:640
	global_load_dwordx4 v[98:101], v70, s[4:5] offset:640
	s_waitcnt lgkmcnt(3)
	v_mfma_f32_32x32x16_bf16 v[34:49], v[110:113], v[118:121], v[34:49]
	v_mfma_f32_32x32x16_bf16 v[2:17], v[114:117], v[118:121], v[2:17]
	s_waitcnt lgkmcnt(2)
	v_mfma_f32_32x32x16_bf16 v[50:65], v[110:113], v[130:133], v[50:65]
	ds_read_b128 v[110:113], v0 offset:36960
	ds_read_b128 v[118:121], v0 offset:41568
	ds_read_b128 v[122:125], v66 offset:55392
	ds_read_b128 v[126:129], v66 offset:60000
	s_waitcnt vmcnt(9)
	ds_write_b128 v67, v[102:105] offset:9216
	s_waitcnt vmcnt(8)
	ds_write_b128 v67, v[106:109] offset:27648
	v_mfma_f32_32x32x16_bf16 v[18:33], v[114:117], v[130:133], v[18:33]
	global_load_dwordx4 v[102:105], v69, s[2:3] offset:640
	global_load_dwordx4 v[106:109], v69, s[4:5] offset:640
	s_waitcnt lgkmcnt(3)
	v_mfma_f32_32x32x16_bf16 v[34:49], v[110:113], v[122:125], v[34:49]
	s_waitcnt vmcnt(9)
	ds_write_b128 v67, v[74:77] offset:13824
	s_waitcnt vmcnt(8)
	ds_write_b128 v67, v[90:93] offset:32256
	v_mfma_f32_32x32x16_bf16 v[2:17], v[118:121], v[122:125], v[2:17]
	s_waitcnt lgkmcnt(4)
	v_mfma_f32_32x32x16_bf16 v[50:65], v[110:113], v[126:129], v[50:65]
	v_mfma_f32_32x32x16_bf16 v[18:33], v[118:121], v[126:129], v[18:33]
	s_waitcnt lgkmcnt(0)
	s_barrier
	ds_read_b128 v[74:77], v0
	ds_read_b128 v[90:93], v66 offset:18432
	ds_read_b128 v[110:113], v0 offset:32
	ds_read_b128 v[114:117], v66 offset:18464
	ds_read_b128 v[118:121], v0 offset:4608
	ds_read_b128 v[122:125], v0 offset:4640
	s_waitcnt lgkmcnt(4)
	v_mfma_f32_32x32x16_bf16 v[34:49], v[74:77], v[90:93], v[34:49]
	s_waitcnt lgkmcnt(1)
	v_mfma_f32_32x32x16_bf16 v[2:17], v[118:121], v[90:93], v[2:17]
	ds_read_b128 v[90:93], v66 offset:23040
	ds_read_b128 v[126:129], v66 offset:23072
	s_waitcnt lgkmcnt(1)
	v_mfma_f32_32x32x16_bf16 v[50:65], v[74:77], v[90:93], v[50:65]
	global_load_dwordx4 v[74:77], v72, s[2:3] offset:768
	global_load_dwordx4 v[130:133], v72, s[4:5] offset:768
	s_waitcnt vmcnt(9)
	ds_write_b128 v67, v[78:81] offset:36864
	s_waitcnt vmcnt(8)
	ds_write_b128 v67, v[134:137] offset:55296
	v_mfma_f32_32x32x16_bf16 v[18:33], v[118:121], v[90:93], v[18:33]
	global_load_dwordx4 v[78:81], v71, s[2:3] offset:768
	global_load_dwordx4 v[90:93], v71, s[4:5] offset:768
	v_mfma_f32_32x32x16_bf16 v[34:49], v[110:113], v[114:117], v[34:49]
	v_mfma_f32_32x32x16_bf16 v[2:17], v[122:125], v[114:117], v[2:17]
	s_waitcnt lgkmcnt(2)
	v_mfma_f32_32x32x16_bf16 v[50:65], v[110:113], v[126:129], v[50:65]
	ds_read_b128 v[110:113], v0 offset:64
	ds_read_b128 v[114:117], v0 offset:4672
	ds_read_b128 v[118:121], v66 offset:18496
	ds_read_b128 v[134:137], v66 offset:23104
	s_waitcnt vmcnt(9)
	ds_write_b128 v67, v[82:85] offset:41472
	s_waitcnt vmcnt(8)
	ds_write_b128 v67, v[94:97] offset:59904
	v_mfma_f32_32x32x16_bf16 v[18:33], v[122:125], v[126:129], v[18:33]
	global_load_dwordx4 v[82:85], v70, s[2:3] offset:768
	global_load_dwordx4 v[94:97], v70, s[4:5] offset:768
	s_waitcnt lgkmcnt(3)
	v_mfma_f32_32x32x16_bf16 v[34:49], v[110:113], v[118:121], v[34:49]
	v_mfma_f32_32x32x16_bf16 v[2:17], v[114:117], v[118:121], v[2:17]
	s_waitcnt lgkmcnt(2)
	v_mfma_f32_32x32x16_bf16 v[50:65], v[110:113], v[134:137], v[50:65]
	ds_read_b128 v[110:113], v0 offset:96
	ds_read_b128 v[118:121], v0 offset:4704
	ds_read_b128 v[122:125], v66 offset:18528
	ds_read_b128 v[126:129], v66 offset:23136
	s_waitcnt vmcnt(9)
	ds_write_b128 v67, v[86:89] offset:46080
	s_waitcnt vmcnt(8)
	ds_write_b128 v67, v[98:101] offset:64512
	v_mfma_f32_32x32x16_bf16 v[18:33], v[114:117], v[134:137], v[18:33]
	global_load_dwordx4 v[86:89], v69, s[2:3] offset:768
	global_load_dwordx4 v[98:101], v69, s[4:5] offset:768
	s_waitcnt lgkmcnt(3)
	v_mfma_f32_32x32x16_bf16 v[34:49], v[110:113], v[122:125], v[34:49]
	s_waitcnt vmcnt(9)
	ds_write_b128 v67, v[102:105] offset:50688
	s_waitcnt vmcnt(8)
	ds_write_b128 v68, v[106:109] offset:13824
	v_mfma_f32_32x32x16_bf16 v[2:17], v[118:121], v[122:125], v[2:17]
	s_waitcnt lgkmcnt(4)
	v_mfma_f32_32x32x16_bf16 v[50:65], v[110:113], v[126:129], v[50:65]
	v_mfma_f32_32x32x16_bf16 v[18:33], v[118:121], v[126:129], v[18:33]
	s_waitcnt lgkmcnt(0)
	s_barrier
; #define GL1_(RA, RB, i) { RA[i] = *(const u32x4*)(ap + (aoff + (i) * astep)); if ((i) < NB) RB[(i) < NB ? (i) : 0] = *(const u32x4*)(bp + (boff + (i) * bstep)); }
; #define LS1_(RA, RB, ST, i) { char* sn_ = lds + (ST) * STAGE; *(u32x4*)(sn_ + wofs + (i) * 32 * LROW) = RA[i]; \
;                               if ((i) < NB) *(u32x4*)(sn_ + STAGE_OP + wofs + (i) * 32 * LROW) = RB[(i) < NB ? (i) : 0]; }
; template <int NJ> DI void gemm_mainloop_reg(const bf16_t* __restrict__ A, int lda, const bf16_t* __restrict__ Bt, int ldb, int K, f32x16 (&acc)[2][NJ], char* lds) {
;     ...
; #pragma unroll
;   for (int i = 0; i < 4; ++i) GL1_(ra0, rb0, i);
;   ap += 128; bp += 128;
; #pragma unroll
;   for (int i = 0; i < 4; ++i) GL1_(ra1, rb1, i);
;   ap += 128; bp += 128;
; #pragma unroll
;   for (int i = 0; i < 4; ++i) LS1_(ra0, rb0, 0, i);
;   __syncthreads();
;   const int nk = K >> 6;
;   for (int kt = 0; kt < nk; kt += 2) {
;     const bool l0 = (kt + 2 < nk), l1 = (kt + 3 < nk);
;     STEP_(0, l0, ra0, rb0, true, ra1, rb1);
;     __syncthreads();
;     STEP_(1, l1, ra1, rb1, l0, ra0, rb0);
;     __syncthreads();
	ds_read_b128 v[102:105], v0 offset:36864
	ds_read_b128 v[106:109], v66 offset:55296
	ds_read_b128 v[110:113], v0 offset:36896
	ds_read_b128 v[114:117], v66 offset:55328
	ds_read_b128 v[118:121], v0 offset:41472
	ds_read_b128 v[122:125], v0 offset:41504
	s_waitcnt lgkmcnt(4)
	v_mfma_f32_32x32x16_bf16 v[34:49], v[102:105], v[106:109], v[34:49]
	s_waitcnt lgkmcnt(1)
	v_mfma_f32_32x32x16_bf16 v[2:17], v[118:121], v[106:109], v[2:17]
	ds_read_b128 v[106:109], v66 offset:59904
	ds_read_b128 v[126:129], v66 offset:59936
	s_waitcnt lgkmcnt(1)
	v_mfma_f32_32x32x16_bf16 v[50:65], v[102:105], v[106:109], v[50:65]
	global_load_dwordx4 v[102:105], v72, s[2:3] offset:896
	global_load_dwordx4 v[134:137], v72, s[4:5] offset:896
	s_waitcnt vmcnt(9)
	ds_write_b128 v67, v[74:77]
	s_waitcnt vmcnt(8)
	ds_write_b128 v67, v[130:133] offset:18432
	v_mfma_f32_32x32x16_bf16 v[18:33], v[118:121], v[106:109], v[18:33]
	global_load_dwordx4 v[74:77], v71, s[2:3] offset:896
	global_load_dwordx4 v[106:109], v71, s[4:5] offset:896
	v_mfma_f32_32x32x16_bf16 v[34:49], v[110:113], v[114:117], v[34:49]
	v_mfma_f32_32x32x16_bf16 v[2:17], v[122:125], v[114:117], v[2:17]
	s_waitcnt lgkmcnt(2)
	v_mfma_f32_32x32x16_bf16 v[50:65], v[110:113], v[126:129], v[50:65]
	ds_read_b128 v[110:113], v0 offset:36928
	ds_read_b128 v[114:117], v0 offset:41536
	ds_read_b128 v[118:121], v66 offset:55360
	ds_read_b128 v[130:133], v66 offset:59968
	s_waitcnt vmcnt(9)
	ds_write_b128 v67, v[78:81] offset:4608
	s_waitcnt vmcnt(8)
	ds_write_b128 v67, v[90:93] offset:23040
	v_mfma_f32_32x32x16_bf16 v[18:33], v[122:125], v[126:129], v[18:33]
	global_load_dwordx4 v[78:81], v70, s[2:3] offset:896
	global_load_dwordx4 v[90:93], v70, s[4:5] offset:896
	s_waitcnt lgkmcnt(3)
	v_mfma_f32_32x32x16_bf16 v[34:49], v[110:113], v[118:121], v[34:49]
	v_mfma_f32_32x32x16_bf16 v[2:17], v[114:117], v[118:121], v[2:17]
	s_waitcnt lgkmcnt(2)
	v_mfma_f32_32x32x16_bf16 v[50:65], v[110:113], v[130:133], v[50:65]
	ds_read_b128 v[110:113], v0 offset:36960
	ds_read_b128 v[118:121], v0 offset:41568
	ds_read_b128 v[122:125], v66 offset:55392
	ds_read_b128 v[126:129], v66 offset:60000
	s_waitcnt vmcnt(9)
	ds_write_b128 v67, v[82:85] offset:9216
	s_waitcnt vmcnt(8)
	ds_write_b128 v67, v[94:97] offset:27648
	v_mfma_f32_32x32x16_bf16 v[18:33], v[114:117], v[130:133], v[18:33]
	global_load_dwordx4 v[82:85], v69, s[2:3] offset:896
	global_load_dwordx4 v[94:97], v69, s[4:5] offset:896
	s_waitcnt lgkmcnt(3)
	v_mfma_f32_32x32x16_bf16 v[34:49], v[110:113], v[122:125], v[34:49]
	s_waitcnt vmcnt(9)
	ds_write_b128 v67, v[86:89] offset:13824
	s_waitcnt vmcnt(8)
	ds_write_b128 v67, v[98:101] offset:32256
	v_mfma_f32_32x32x16_bf16 v[2:17], v[118:121], v[122:125], v[2:17]
	s_waitcnt lgkmcnt(4)
	v_mfma_f32_32x32x16_bf16 v[50:65], v[110:113], v[126:129], v[50:65]
	v_mfma_f32_32x32x16_bf16 v[18:33], v[118:121], v[126:129], v[18:33]
	s_waitcnt lgkmcnt(0)
	s_barrier
	ds_read_b128 v[86:89], v0
	ds_read_b128 v[98:101], v66 offset:18432
	ds_read_b128 v[110:113], v0 offset:32
	ds_read_b128 v[114:117], v66 offset:18464
	ds_read_b128 v[118:121], v0 offset:4608
	ds_read_b128 v[122:125], v0 offset:4640
	s_waitcnt lgkmcnt(4)
	v_mfma_f32_32x32x16_bf16 v[34:49], v[86:89], v[98:101], v[34:49]
	s_waitcnt lgkmcnt(1)
	v_mfma_f32_32x32x16_bf16 v[2:17], v[118:121], v[98:101], v[2:17]
	ds_read_b128 v[98:101], v66 offset:23040
	ds_read_b128 v[126:129], v66 offset:23072
	s_waitcnt lgkmcnt(1)
	v_mfma_f32_32x32x16_bf16 v[50:65], v[86:89], v[98:101], v[50:65]
	global_load_dwordx4 v[86:89], v72, s[2:3] offset:1024
	global_load_dwordx4 v[130:133], v72, s[4:5] offset:1024
	s_waitcnt vmcnt(9)
	ds_write_b128 v67, v[102:105] offset:36864
	s_waitcnt vmcnt(8)
	ds_write_b128 v67, v[134:137] offset:55296
	v_mfma_f32_32x32x16_bf16 v[18:33], v[118:121], v[98:101], v[18:33]
	global_load_dwordx4 v[98:101], v71, s[2:3] offset:1024
	global_load_dwordx4 v[102:105], v71, s[4:5] offset:1024
	v_mfma_f32_32x32x16_bf16 v[34:49], v[110:113], v[114:117], v[34:49]
	v_mfma_f32_32x32x16_bf16 v[2:17], v[122:125], v[114:117], v[2:17]
	s_waitcnt lgkmcnt(2)
	v_mfma_f32_32x32x16_bf16 v[50:65], v[110:113], v[126:129], v[50:65]
	ds_read_b128 v[110:113], v0 offset:64
	ds_read_b128 v[114:117], v0 offset:4672
	ds_read_b128 v[118:121], v66 offset:18496
	ds_read_b128 v[134:137], v66 offset:23104
	s_waitcnt vmcnt(9)
	ds_write_b128 v67, v[74:77] offset:41472
	s_waitcnt vmcnt(8)
	ds_write_b128 v67, v[106:109] offset:59904
	v_mfma_f32_32x32x16_bf16 v[18:33], v[122:125], v[126:129], v[18:33]
	global_load_dwordx4 v[74:77], v70, s[2:3] offset:1024
	global_load_dwordx4 v[106:109], v70, s[4:5] offset:1024
	s_waitcnt lgkmcnt(3)
	v_mfma_f32_32x32x16_bf16 v[34:49], v[110:113], v[118:121], v[34:49]
	v_mfma_f32_32x32x16_bf16 v[2:17], v[114:117], v[118:121], v[2:17]
	s_waitcnt lgkmcnt(2)
	v_mfma_f32_32x32x16_bf16 v[50:65], v[110:113], v[134:137], v[50:65]
	ds_read_b128 v[110:113], v0 offset:96
	ds_read_b128 v[118:121], v0 offset:4704
	ds_read_b128 v[122:125], v66 offset:18528
	ds_read_b128 v[126:129], v66 offset:23136
	s_waitcnt vmcnt(9)
	ds_write_b128 v67, v[78:81] offset:46080
	s_waitcnt vmcnt(8)
	ds_write_b128 v67, v[90:93] offset:64512
	v_mfma_f32_32x32x16_bf16 v[18:33], v[114:117], v[134:137], v[18:33]
	global_load_dwordx4 v[78:81], v69, s[2:3] offset:1024
	global_load_dwordx4 v[90:93], v69, s[4:5] offset:1024
	s_waitcnt lgkmcnt(3)
	v_mfma_f32_32x32x16_bf16 v[34:49], v[110:113], v[122:125], v[34:49]
	s_waitcnt vmcnt(9)
	ds_write_b128 v67, v[82:85] offset:50688
	s_waitcnt vmcnt(8)
	ds_write_b128 v68, v[94:97] offset:13824
	v_mfma_f32_32x32x16_bf16 v[2:17], v[118:121], v[122:125], v[2:17]
	s_waitcnt lgkmcnt(4)
	v_mfma_f32_32x32x16_bf16 v[50:65], v[110:113], v[126:129], v[50:65]
	v_mfma_f32_32x32x16_bf16 v[18:33], v[118:121], v[126:129], v[18:33]
	s_waitcnt lgkmcnt(0)
	s_barrier
; #define GL1_(RA, RB, i) { RA[i] = *(const u32x4*)(ap + (aoff + (i) * astep)); if ((i) < NB) RB[(i) < NB ? (i) : 0] = *(const u32x4*)(bp + (boff + (i) * bstep)); }
; #define LS1_(RA, RB, ST, i) { char* sn_ = lds + (ST) * STAGE; *(u32x4*)(sn_ + wofs + (i) * 32 * LROW) = RA[i]; \
;                               if ((i) < NB) *(u32x4*)(sn_ + STAGE_OP + wofs + (i) * 32 * LROW) = RB[(i) < NB ? (i) : 0]; }
; template <int NJ> DI void gemm_mainloop_reg(const bf16_t* __restrict__ A, int lda, const bf16_t* __restrict__ Bt, int ldb, int K, f32x16 (&acc)[2][NJ], char* lds) {
;     ...
; #pragma unroll
;   for (int i = 0; i < 4; ++i) GL1_(ra0, rb0, i);
;   ap += 128; bp += 128;
; #pragma unroll
;   for (int i = 0; i < 4; ++i) GL1_(ra1, rb1, i);
;   ap += 128; bp += 128;
; #pragma unroll
;   for (int i = 0; i < 4; ++i) LS1_(ra0, rb0, 0, i);
;   __syncthreads();
;   const int nk = K >> 6;
;   for (int kt = 0; kt < nk; kt += 2) {
;     const bool l0 = (kt + 2 < nk), l1 = (kt + 3 < nk);
;     STEP_(0, l0, ra0, rb0, true, ra1, rb1);
;     __syncthreads();
;     STEP_(1, l1, ra1, rb1, l0, ra0, rb0);
;     __syncthreads();
	ds_read_b128 v[82:85], v0 offset:36864
	ds_read_b128 v[94:97], v66 offset:55296
	ds_read_b128 v[110:113], v0 offset:36896
	ds_read_b128 v[114:117], v66 offset:55328
	ds_read_b128 v[118:121], v0 offset:41472
	ds_read_b128 v[122:125], v0 offset:41504
	s_waitcnt lgkmcnt(4)
	v_mfma_f32_32x32x16_bf16 v[34:49], v[82:85], v[94:97], v[34:49]
	s_waitcnt lgkmcnt(1)
	v_mfma_f32_32x32x16_bf16 v[2:17], v[118:121], v[94:97], v[2:17]
	ds_read_b128 v[94:97], v66 offset:59904
	ds_read_b128 v[126:129], v66 offset:59936
	s_waitcnt lgkmcnt(1)
	v_mfma_f32_32x32x16_bf16 v[50:65], v[82:85], v[94:97], v[50:65]
	global_load_dwordx4 v[82:85], v72, s[2:3] offset:1152
	global_load_dwordx4 v[134:137], v72, s[4:5] offset:1152
	s_waitcnt vmcnt(9)
	ds_write_b128 v67, v[86:89]
	s_waitcnt vmcnt(8)
	ds_write_b128 v67, v[130:133] offset:18432
	v_mfma_f32_32x32x16_bf16 v[18:33], v[118:121], v[94:97], v[18:33]
	global_load_dwordx4 v[86:89], v71, s[2:3] offset:1152
	global_load_dwordx4 v[94:97], v71, s[4:5] offset:1152
	v_mfma_f32_32x32x16_bf16 v[34:49], v[110:113], v[114:117], v[34:49]
	v_mfma_f32_32x32x16_bf16 v[2:17], v[122:125], v[114:117], v[2:17]
	s_waitcnt lgkmcnt(2)
	v_mfma_f32_32x32x16_bf16 v[50:65], v[110:113], v[126:129], v[50:65]
	ds_read_b128 v[110:113], v0 offset:36928
	ds_read_b128 v[114:117], v0 offset:41536
	ds_read_b128 v[118:121], v66 offset:55360
	ds_read_b128 v[130:133], v66 offset:59968
	s_waitcnt vmcnt(9)
	ds_write_b128 v67, v[98:101] offset:4608
	s_waitcnt vmcnt(8)
	ds_write_b128 v67, v[102:105] offset:23040
	v_mfma_f32_32x32x16_bf16 v[18:33], v[122:125], v[126:129], v[18:33]
	global_load_dwordx4 v[98:101], v70, s[2:3] offset:1152
	global_load_dwordx4 v[102:105], v70, s[4:5] offset:1152
	s_waitcnt lgkmcnt(3)
	v_mfma_f32_32x32x16_bf16 v[34:49], v[110:113], v[118:121], v[34:49]
	v_mfma_f32_32x32x16_bf16 v[2:17], v[114:117], v[118:121], v[2:17]
	s_waitcnt lgkmcnt(2)
	v_mfma_f32_32x32x16_bf16 v[50:65], v[110:113], v[130:133], v[50:65]
	ds_read_b128 v[110:113], v0 offset:36960
	ds_read_b128 v[118:121], v0 offset:41568
	ds_read_b128 v[122:125], v66 offset:55392
	ds_read_b128 v[126:129], v66 offset:60000
	s_waitcnt vmcnt(9)
	ds_write_b128 v67, v[74:77] offset:9216
	s_waitcnt vmcnt(8)
	ds_write_b128 v67, v[106:109] offset:27648
	v_mfma_f32_32x32x16_bf16 v[18:33], v[114:117], v[130:133], v[18:33]
	global_load_dwordx4 v[74:77], v69, s[2:3] offset:1152
	global_load_dwordx4 v[106:109], v69, s[4:5] offset:1152
	s_waitcnt lgkmcnt(3)
	v_mfma_f32_32x32x16_bf16 v[34:49], v[110:113], v[122:125], v[34:49]
	s_waitcnt vmcnt(9)
	ds_write_b128 v67, v[78:81] offset:13824
	s_waitcnt vmcnt(8)
	ds_write_b128 v67, v[90:93] offset:32256
	v_mfma_f32_32x32x16_bf16 v[2:17], v[118:121], v[122:125], v[2:17]
	s_waitcnt lgkmcnt(4)
	v_mfma_f32_32x32x16_bf16 v[50:65], v[110:113], v[126:129], v[50:65]
	v_mfma_f32_32x32x16_bf16 v[18:33], v[118:121], v[126:129], v[18:33]
	s_waitcnt lgkmcnt(0)
	s_barrier
	ds_read_b128 v[78:81], v0
	ds_read_b128 v[90:93], v66 offset:18432
	ds_read_b128 v[110:113], v0 offset:32
	ds_read_b128 v[114:117], v66 offset:18464
	ds_read_b128 v[118:121], v0 offset:4608
	ds_read_b128 v[122:125], v0 offset:4640
	s_waitcnt lgkmcnt(4)
	v_mfma_f32_32x32x16_bf16 v[34:49], v[78:81], v[90:93], v[34:49]
	s_waitcnt lgkmcnt(1)
	v_mfma_f32_32x32x16_bf16 v[2:17], v[118:121], v[90:93], v[2:17]
	ds_read_b128 v[90:93], v66 offset:23040
	ds_read_b128 v[126:129], v66 offset:23072
	s_waitcnt lgkmcnt(1)
	v_mfma_f32_32x32x16_bf16 v[50:65], v[78:81], v[90:93], v[50:65]
	global_load_dwordx4 v[78:81], v72, s[2:3] offset:1280
	global_load_dwordx4 v[130:133], v72, s[4:5] offset:1280
	s_waitcnt vmcnt(9)
	ds_write_b128 v67, v[82:85] offset:36864
	s_waitcnt vmcnt(8)
	ds_write_b128 v67, v[134:137] offset:55296
	v_mfma_f32_32x32x16_bf16 v[18:33], v[118:121], v[90:93], v[18:33]
	global_load_dwordx4 v[82:85], v71, s[2:3] offset:1280
	global_load_dwordx4 v[90:93], v71, s[4:5] offset:1280
	v_mfma_f32_32x32x16_bf16 v[34:49], v[110:113], v[114:117], v[34:49]
	v_mfma_f32_32x32x16_bf16 v[2:17], v[122:125], v[114:117], v[2:17]
	s_waitcnt lgkmcnt(2)
	v_mfma_f32_32x32x16_bf16 v[50:65], v[110:113], v[126:129], v[50:65]
	ds_read_b128 v[110:113], v0 offset:64
	ds_read_b128 v[114:117], v0 offset:4672
	ds_read_b128 v[118:121], v66 offset:18496
	ds_read_b128 v[134:137], v66 offset:23104
	s_waitcnt vmcnt(9)
	ds_write_b128 v67, v[86:89] offset:41472
	s_waitcnt vmcnt(8)
	ds_write_b128 v67, v[94:97] offset:59904
	v_mfma_f32_32x32x16_bf16 v[18:33], v[122:125], v[126:129], v[18:33]
	global_load_dwordx4 v[86:89], v70, s[2:3] offset:1280
	global_load_dwordx4 v[94:97], v70, s[4:5] offset:1280
	s_waitcnt lgkmcnt(3)
	v_mfma_f32_32x32x16_bf16 v[34:49], v[110:113], v[118:121], v[34:49]
	v_mfma_f32_32x32x16_bf16 v[2:17], v[114:117], v[118:121], v[2:17]
	s_waitcnt lgkmcnt(2)
	v_mfma_f32_32x32x16_bf16 v[50:65], v[110:113], v[134:137], v[50:65]
	ds_read_b128 v[110:113], v0 offset:96
	ds_read_b128 v[118:121], v0 offset:4704
	ds_read_b128 v[122:125], v66 offset:18528
	ds_read_b128 v[126:129], v66 offset:23136
	s_waitcnt vmcnt(9)
	ds_write_b128 v67, v[98:101] offset:46080
	s_waitcnt vmcnt(8)
	ds_write_b128 v67, v[102:105] offset:64512
	v_mfma_f32_32x32x16_bf16 v[18:33], v[114:117], v[134:137], v[18:33]
	global_load_dwordx4 v[98:101], v69, s[2:3] offset:1280
	global_load_dwordx4 v[102:105], v69, s[4:5] offset:1280
	s_waitcnt lgkmcnt(3)
	v_mfma_f32_32x32x16_bf16 v[34:49], v[110:113], v[122:125], v[34:49]
	s_waitcnt vmcnt(9)
	ds_write_b128 v67, v[74:77] offset:50688
	s_waitcnt vmcnt(8)
	ds_write_b128 v68, v[106:109] offset:13824
	v_mfma_f32_32x32x16_bf16 v[2:17], v[118:121], v[122:125], v[2:17]
	s_waitcnt lgkmcnt(4)
	v_mfma_f32_32x32x16_bf16 v[50:65], v[110:113], v[126:129], v[50:65]
	v_mfma_f32_32x32x16_bf16 v[18:33], v[118:121], v[126:129], v[18:33]
	s_waitcnt lgkmcnt(0)
	s_barrier
; #define GL1_(RA, RB, i) { RA[i] = *(const u32x4*)(ap + (aoff + (i) * astep)); if ((i) < NB) RB[(i) < NB ? (i) : 0] = *(const u32x4*)(bp + (boff + (i) * bstep)); }
; #define LS1_(RA, RB, ST, i) { char* sn_ = lds + (ST) * STAGE; *(u32x4*)(sn_ + wofs + (i) * 32 * LROW) = RA[i]; \
;                               if ((i) < NB) *(u32x4*)(sn_ + STAGE_OP + wofs + (i) * 32 * LROW) = RB[(i) < NB ? (i) : 0]; }
; template <int NJ> DI void gemm_mainloop_reg(const bf16_t* __restrict__ A, int lda, const bf16_t* __restrict__ Bt, int ldb, int K, f32x16 (&acc)[2][NJ], char* lds) {
;     ...
; #pragma unroll
;   for (int i = 0; i < 4; ++i) GL1_(ra0, rb0, i);
;   ap += 128; bp += 128;
; #pragma unroll
;   for (int i = 0; i < 4; ++i) GL1_(ra1, rb1, i);
;   ap += 128; bp += 128;
; #pragma unroll
;   for (int i = 0; i < 4; ++i) LS1_(ra0, rb0, 0, i);
;   __syncthreads();
;   const int nk = K >> 6;
;   for (int kt = 0; kt < nk; kt += 2) {
;     const bool l0 = (kt + 2 < nk), l1 = (kt + 3 < nk);
;     STEP_(0, l0, ra0, rb0, true, ra1, rb1);
;     __syncthreads();
;     STEP_(1, l1, ra1, rb1, l0, ra0, rb0);
;     __syncthreads();
	ds_read_b128 v[74:77], v0 offset:36864
	ds_read_b128 v[106:109], v66 offset:55296
	ds_read_b128 v[110:113], v0 offset:36896
	ds_read_b128 v[114:117], v66 offset:55328
	ds_read_b128 v[118:121], v0 offset:41472
	ds_read_b128 v[122:125], v0 offset:41504
	s_waitcnt lgkmcnt(4)
	v_mfma_f32_32x32x16_bf16 v[34:49], v[74:77], v[106:109], v[34:49]
	s_waitcnt lgkmcnt(1)
	v_mfma_f32_32x32x16_bf16 v[2:17], v[118:121], v[106:109], v[2:17]
	ds_read_b128 v[106:109], v66 offset:59904
	ds_read_b128 v[126:129], v66 offset:59936
	s_waitcnt lgkmcnt(1)
	v_mfma_f32_32x32x16_bf16 v[50:65], v[74:77], v[106:109], v[50:65]
	global_load_dwordx4 v[74:77], v72, s[2:3] offset:1408
	global_load_dwordx4 v[134:137], v72, s[4:5] offset:1408
	s_waitcnt vmcnt(9)
	ds_write_b128 v67, v[78:81]
	s_waitcnt vmcnt(8)
	ds_write_b128 v67, v[130:133] offset:18432
	v_mfma_f32_32x32x16_bf16 v[18:33], v[118:121], v[106:109], v[18:33]
	global_load_dwordx4 v[78:81], v71, s[2:3] offset:1408
	global_load_dwordx4 v[106:109], v71, s[4:5] offset:1408
	v_mfma_f32_32x32x16_bf16 v[34:49], v[110:113], v[114:117], v[34:49]
	v_mfma_f32_32x32x16_bf16 v[2:17], v[122:125], v[114:117], v[2:17]
	s_waitcnt lgkmcnt(2)
	v_mfma_f32_32x32x16_bf16 v[50:65], v[110:113], v[126:129], v[50:65]
	ds_read_b128 v[110:113], v0 offset:36928
	ds_read_b128 v[114:117], v0 offset:41536
	ds_read_b128 v[118:121], v66 offset:55360
	ds_read_b128 v[130:133], v66 offset:59968
	s_waitcnt vmcnt(9)
	ds_write_b128 v67, v[82:85] offset:4608
	s_waitcnt vmcnt(8)
	ds_write_b128 v67, v[90:93] offset:23040
	v_mfma_f32_32x32x16_bf16 v[18:33], v[122:125], v[126:129], v[18:33]
	global_load_dwordx4 v[82:85], v70, s[2:3] offset:1408
	global_load_dwordx4 v[90:93], v70, s[4:5] offset:1408
	s_waitcnt lgkmcnt(3)
	v_mfma_f32_32x32x16_bf16 v[34:49], v[110:113], v[118:121], v[34:49]
	v_mfma_f32_32x32x16_bf16 v[2:17], v[114:117], v[118:121], v[2:17]
	s_waitcnt lgkmcnt(2)
	v_mfma_f32_32x32x16_bf16 v[50:65], v[110:113], v[130:133], v[50:65]
	ds_read_b128 v[110:113], v0 offset:36960
	ds_read_b128 v[118:121], v0 offset:41568
	ds_read_b128 v[122:125], v66 offset:55392
	ds_read_b128 v[126:129], v66 offset:60000
	s_waitcnt vmcnt(9)
	ds_write_b128 v67, v[86:89] offset:9216
	s_waitcnt vmcnt(8)
	ds_write_b128 v67, v[94:97] offset:27648
	v_mfma_f32_32x32x16_bf16 v[18:33], v[114:117], v[130:133], v[18:33]
	global_load_dwordx4 v[86:89], v69, s[2:3] offset:1408
	global_load_dwordx4 v[94:97], v69, s[4:5] offset:1408
	s_waitcnt lgkmcnt(3)
	v_mfma_f32_32x32x16_bf16 v[34:49], v[110:113], v[122:125], v[34:49]
	s_waitcnt vmcnt(9)
	ds_write_b128 v67, v[98:101] offset:13824
	s_waitcnt vmcnt(8)
	ds_write_b128 v67, v[102:105] offset:32256
	v_mfma_f32_32x32x16_bf16 v[2:17], v[118:121], v[122:125], v[2:17]
	s_waitcnt lgkmcnt(4)
	v_mfma_f32_32x32x16_bf16 v[50:65], v[110:113], v[126:129], v[50:65]
	v_mfma_f32_32x32x16_bf16 v[18:33], v[118:121], v[126:129], v[18:33]
	s_waitcnt lgkmcnt(0)
	s_barrier
	ds_read_b128 v[98:101], v0
	ds_read_b128 v[102:105], v66 offset:18432
	ds_read_b128 v[110:113], v0 offset:32
	ds_read_b128 v[114:117], v66 offset:18464
	ds_read_b128 v[118:121], v0 offset:4608
	ds_read_b128 v[122:125], v0 offset:4640
	s_waitcnt lgkmcnt(4)
	v_mfma_f32_32x32x16_bf16 v[34:49], v[98:101], v[102:105], v[34:49]
	s_waitcnt lgkmcnt(1)
	v_mfma_f32_32x32x16_bf16 v[2:17], v[118:121], v[102:105], v[2:17]
	ds_read_b128 v[102:105], v66 offset:23040
	ds_read_b128 v[126:129], v66 offset:23072
	s_waitcnt lgkmcnt(1)
	v_mfma_f32_32x32x16_bf16 v[50:65], v[98:101], v[102:105], v[50:65]
	global_load_dwordx4 v[98:101], v72, s[2:3] offset:1536
	global_load_dwordx4 v[130:133], v72, s[4:5] offset:1536
	s_waitcnt vmcnt(9)
	ds_write_b128 v67, v[74:77] offset:36864
	s_waitcnt vmcnt(8)
	ds_write_b128 v67, v[134:137] offset:55296
	v_mfma_f32_32x32x16_bf16 v[18:33], v[118:121], v[102:105], v[18:33]
	global_load_dwordx4 v[74:77], v71, s[2:3] offset:1536
	global_load_dwordx4 v[102:105], v71, s[4:5] offset:1536
	v_mfma_f32_32x32x16_bf16 v[34:49], v[110:113], v[114:117], v[34:49]
	v_mfma_f32_32x32x16_bf16 v[2:17], v[122:125], v[114:117], v[2:17]
	s_waitcnt lgkmcnt(2)
	v_mfma_f32_32x32x16_bf16 v[50:65], v[110:113], v[126:129], v[50:65]
	ds_read_b128 v[110:113], v0 offset:64
	ds_read_b128 v[114:117], v0 offset:4672
	ds_read_b128 v[118:121], v66 offset:18496
	ds_read_b128 v[134:137], v66 offset:23104
	s_waitcnt vmcnt(9)
	ds_write_b128 v67, v[78:81] offset:41472
	s_waitcnt vmcnt(8)
	ds_write_b128 v67, v[106:109] offset:59904
	v_mfma_f32_32x32x16_bf16 v[18:33], v[122:125], v[126:129], v[18:33]
	global_load_dwordx4 v[78:81], v70, s[2:3] offset:1536
	global_load_dwordx4 v[106:109], v70, s[4:5] offset:1536
	s_waitcnt lgkmcnt(3)
	v_mfma_f32_32x32x16_bf16 v[34:49], v[110:113], v[118:121], v[34:49]
	v_mfma_f32_32x32x16_bf16 v[2:17], v[114:117], v[118:121], v[2:17]
	s_waitcnt lgkmcnt(2)
	v_mfma_f32_32x32x16_bf16 v[50:65], v[110:113], v[134:137], v[50:65]
	ds_read_b128 v[110:113], v0 offset:96
	ds_read_b128 v[118:121], v0 offset:4704
	ds_read_b128 v[122:125], v66 offset:18528
	ds_read_b128 v[126:129], v66 offset:23136
	s_waitcnt vmcnt(9)
	ds_write_b128 v67, v[82:85] offset:46080
	s_waitcnt vmcnt(8)
	ds_write_b128 v67, v[90:93] offset:64512
	v_mfma_f32_32x32x16_bf16 v[18:33], v[114:117], v[134:137], v[18:33]
	global_load_dwordx4 v[82:85], v69, s[2:3] offset:1536
	global_load_dwordx4 v[90:93], v69, s[4:5] offset:1536
	s_waitcnt lgkmcnt(3)
	v_mfma_f32_32x32x16_bf16 v[34:49], v[110:113], v[122:125], v[34:49]
	s_waitcnt vmcnt(9)
	ds_write_b128 v67, v[86:89] offset:50688
	s_waitcnt vmcnt(8)
	ds_write_b128 v68, v[94:97] offset:13824
	v_mfma_f32_32x32x16_bf16 v[2:17], v[118:121], v[122:125], v[2:17]
	s_waitcnt lgkmcnt(4)
	v_mfma_f32_32x32x16_bf16 v[50:65], v[110:113], v[126:129], v[50:65]
	v_mfma_f32_32x32x16_bf16 v[18:33], v[118:121], v[126:129], v[18:33]
	s_waitcnt lgkmcnt(0)
	s_barrier
; #define GL1_(RA, RB, i) { RA[i] = *(const u32x4*)(ap + (aoff + (i) * astep)); if ((i) < NB) RB[(i) < NB ? (i) : 0] = *(const u32x4*)(bp + (boff + (i) * bstep)); }
; #define LS1_(RA, RB, ST, i) { char* sn_ = lds + (ST) * STAGE; *(u32x4*)(sn_ + wofs + (i) * 32 * LROW) = RA[i]; \
;                               if ((i) < NB) *(u32x4*)(sn_ + STAGE_OP + wofs + (i) * 32 * LROW) = RB[(i) < NB ? (i) : 0]; }
; template <int NJ> DI void gemm_mainloop_reg(const bf16_t* __restrict__ A, int lda, const bf16_t* __restrict__ Bt, int ldb, int K, f32x16 (&acc)[2][NJ], char* lds) {
;     ...
; #pragma unroll
;   for (int i = 0; i < 4; ++i) GL1_(ra0, rb0, i);
;   ap += 128; bp += 128;
; #pragma unroll
;   for (int i = 0; i < 4; ++i) GL1_(ra1, rb1, i);
;   ap += 128; bp += 128;
; #pragma unroll
;   for (int i = 0; i < 4; ++i) LS1_(ra0, rb0, 0, i);
;   __syncthreads();
;   const int nk = K >> 6;
;   for (int kt = 0; kt < nk; kt += 2) {
;     const bool l0 = (kt + 2 < nk), l1 = (kt + 3 < nk);
;     STEP_(0, l0, ra0, rb0, true, ra1, rb1);
;     __syncthreads();
;     STEP_(1, l1, ra1, rb1, l0, ra0, rb0);
;     __syncthreads();
	ds_read_b128 v[86:89], v0 offset:36864
	ds_read_b128 v[94:97], v66 offset:55296
	ds_read_b128 v[110:113], v0 offset:36896
	ds_read_b128 v[114:117], v66 offset:55328
	ds_read_b128 v[118:121], v0 offset:41472
	ds_read_b128 v[122:125], v0 offset:41504
	s_waitcnt lgkmcnt(4)
	v_mfma_f32_32x32x16_bf16 v[34:49], v[86:89], v[94:97], v[34:49]
	s_waitcnt lgkmcnt(1)
	v_mfma_f32_32x32x16_bf16 v[2:17], v[118:121], v[94:97], v[2:17]
	ds_read_b128 v[94:97], v66 offset:59904
	ds_read_b128 v[126:129], v66 offset:59936
	s_waitcnt lgkmcnt(1)
	v_mfma_f32_32x32x16_bf16 v[50:65], v[86:89], v[94:97], v[50:65]
	global_load_dwordx4 v[86:89], v72, s[2:3] offset:1664
	global_load_dwordx4 v[134:137], v72, s[4:5] offset:1664
	s_waitcnt vmcnt(9)
	ds_write_b128 v67, v[98:101]
	s_waitcnt vmcnt(8)
	ds_write_b128 v67, v[130:133] offset:18432
	v_mfma_f32_32x32x16_bf16 v[18:33], v[118:121], v[94:97], v[18:33]
	global_load_dwordx4 v[94:97], v71, s[2:3] offset:1664
	global_load_dwordx4 v[98:101], v71, s[4:5] offset:1664
	v_mfma_f32_32x32x16_bf16 v[34:49], v[110:113], v[114:117], v[34:49]
	v_mfma_f32_32x32x16_bf16 v[2:17], v[122:125], v[114:117], v[2:17]
	s_waitcnt lgkmcnt(2)
	v_mfma_f32_32x32x16_bf16 v[50:65], v[110:113], v[126:129], v[50:65]
	ds_read_b128 v[110:113], v0 offset:36928
	ds_read_b128 v[114:117], v0 offset:41536
	ds_read_b128 v[118:121], v66 offset:55360
	ds_read_b128 v[130:133], v66 offset:59968
	s_waitcnt vmcnt(9)
	ds_write_b128 v67, v[74:77] offset:4608
	s_waitcnt vmcnt(8)
	ds_write_b128 v67, v[102:105] offset:23040
	v_mfma_f32_32x32x16_bf16 v[18:33], v[122:125], v[126:129], v[18:33]
	global_load_dwordx4 v[74:77], v70, s[2:3] offset:1664
	global_load_dwordx4 v[102:105], v70, s[4:5] offset:1664
	s_waitcnt lgkmcnt(3)
	v_mfma_f32_32x32x16_bf16 v[34:49], v[110:113], v[118:121], v[34:49]
	v_mfma_f32_32x32x16_bf16 v[2:17], v[114:117], v[118:121], v[2:17]
	s_waitcnt lgkmcnt(2)
	v_mfma_f32_32x32x16_bf16 v[50:65], v[110:113], v[130:133], v[50:65]
	ds_read_b128 v[110:113], v0 offset:36960
	ds_read_b128 v[118:121], v0 offset:41568
	ds_read_b128 v[122:125], v66 offset:55392
	ds_read_b128 v[126:129], v66 offset:60000
	s_waitcnt vmcnt(9)
	ds_write_b128 v67, v[78:81] offset:9216
	s_waitcnt vmcnt(8)
	ds_write_b128 v67, v[106:109] offset:27648
	v_mfma_f32_32x32x16_bf16 v[18:33], v[114:117], v[130:133], v[18:33]
	global_load_dwordx4 v[78:81], v69, s[2:3] offset:1664
	global_load_dwordx4 v[106:109], v69, s[4:5] offset:1664
	s_waitcnt lgkmcnt(3)
	v_mfma_f32_32x32x16_bf16 v[34:49], v[110:113], v[122:125], v[34:49]
	s_waitcnt vmcnt(9)
	ds_write_b128 v67, v[82:85] offset:13824
	s_waitcnt vmcnt(8)
	ds_write_b128 v67, v[90:93] offset:32256
	v_mfma_f32_32x32x16_bf16 v[2:17], v[118:121], v[122:125], v[2:17]
	s_waitcnt lgkmcnt(4)
	v_mfma_f32_32x32x16_bf16 v[50:65], v[110:113], v[126:129], v[50:65]
	v_mfma_f32_32x32x16_bf16 v[18:33], v[118:121], v[126:129], v[18:33]
	s_waitcnt lgkmcnt(0)
	s_barrier
	ds_read_b128 v[82:85], v0
	ds_read_b128 v[90:93], v66 offset:18432
	ds_read_b128 v[110:113], v0 offset:32
	ds_read_b128 v[114:117], v66 offset:18464
	ds_read_b128 v[118:121], v0 offset:4608
	ds_read_b128 v[122:125], v0 offset:4640
	s_waitcnt lgkmcnt(4)
	v_mfma_f32_32x32x16_bf16 v[34:49], v[82:85], v[90:93], v[34:49]
	s_waitcnt lgkmcnt(1)
	v_mfma_f32_32x32x16_bf16 v[2:17], v[118:121], v[90:93], v[2:17]
	ds_read_b128 v[90:93], v66 offset:23040
	ds_read_b128 v[126:129], v66 offset:23072
	s_waitcnt lgkmcnt(1)
	v_mfma_f32_32x32x16_bf16 v[50:65], v[82:85], v[90:93], v[50:65]
	global_load_dwordx4 v[82:85], v72, s[2:3] offset:1792
	global_load_dwordx4 v[130:133], v72, s[4:5] offset:1792
	s_waitcnt vmcnt(9)
	ds_write_b128 v67, v[86:89] offset:36864
	s_waitcnt vmcnt(8)
	ds_write_b128 v67, v[134:137] offset:55296
	v_mfma_f32_32x32x16_bf16 v[18:33], v[118:121], v[90:93], v[18:33]
	global_load_dwordx4 v[86:89], v71, s[2:3] offset:1792
	global_load_dwordx4 v[90:93], v71, s[4:5] offset:1792
	v_mfma_f32_32x32x16_bf16 v[34:49], v[110:113], v[114:117], v[34:49]
	v_mfma_f32_32x32x16_bf16 v[2:17], v[122:125], v[114:117], v[2:17]
	s_waitcnt lgkmcnt(2)
	v_mfma_f32_32x32x16_bf16 v[50:65], v[110:113], v[126:129], v[50:65]
	ds_read_b128 v[110:113], v0 offset:64
	ds_read_b128 v[114:117], v0 offset:4672
	ds_read_b128 v[118:121], v66 offset:18496
	ds_read_b128 v[134:137], v66 offset:23104
	s_waitcnt vmcnt(9)
	ds_write_b128 v67, v[94:97] offset:41472
	s_waitcnt vmcnt(8)
	ds_write_b128 v67, v[98:101] offset:59904
	v_mfma_f32_32x32x16_bf16 v[18:33], v[122:125], v[126:129], v[18:33]
	global_load_dwordx4 v[94:97], v70, s[2:3] offset:1792
	global_load_dwordx4 v[98:101], v70, s[4:5] offset:1792
	s_waitcnt lgkmcnt(3)
	v_mfma_f32_32x32x16_bf16 v[34:49], v[110:113], v[118:121], v[34:49]
	v_mfma_f32_32x32x16_bf16 v[2:17], v[114:117], v[118:121], v[2:17]
	s_waitcnt lgkmcnt(2)
	v_mfma_f32_32x32x16_bf16 v[50:65], v[110:113], v[134:137], v[50:65]
	ds_read_b128 v[110:113], v0 offset:96
	ds_read_b128 v[118:121], v0 offset:4704
	ds_read_b128 v[122:125], v66 offset:18528
	ds_read_b128 v[126:129], v66 offset:23136
	s_waitcnt vmcnt(9)
	ds_write_b128 v67, v[74:77] offset:46080
	s_waitcnt vmcnt(8)
	ds_write_b128 v67, v[102:105] offset:64512
	v_mfma_f32_32x32x16_bf16 v[18:33], v[114:117], v[134:137], v[18:33]
	global_load_dwordx4 v[74:77], v69, s[2:3] offset:1792
	global_load_dwordx4 v[102:105], v69, s[4:5] offset:1792
	s_waitcnt lgkmcnt(3)
	v_mfma_f32_32x32x16_bf16 v[34:49], v[110:113], v[122:125], v[34:49]
	s_waitcnt vmcnt(9)
	ds_write_b128 v67, v[78:81] offset:50688
	s_waitcnt vmcnt(8)
	ds_write_b128 v68, v[106:109] offset:13824
	v_mfma_f32_32x32x16_bf16 v[2:17], v[118:121], v[122:125], v[2:17]
	s_waitcnt lgkmcnt(4)
	v_mfma_f32_32x32x16_bf16 v[50:65], v[110:113], v[126:129], v[50:65]
	v_mfma_f32_32x32x16_bf16 v[18:33], v[118:121], v[126:129], v[18:33]
	s_waitcnt lgkmcnt(0)
	s_barrier
; #define GL1_(RA, RB, i) { RA[i] = *(const u32x4*)(ap + (aoff + (i) * astep)); if ((i) < NB) RB[(i) < NB ? (i) : 0] = *(const u32x4*)(bp + (boff + (i) * bstep)); }
; #define LS1_(RA, RB, ST, i) { char* sn_ = lds + (ST) * STAGE; *(u32x4*)(sn_ + wofs + (i) * 32 * LROW) = RA[i]; \
;                               if ((i) < NB) *(u32x4*)(sn_ + STAGE_OP + wofs + (i) * 32 * LROW) = RB[(i) < NB ? (i) : 0]; }
; template <int NJ> DI void gemm_mainloop_reg(const bf16_t* __restrict__ A, int lda, const bf16_t* __restrict__ Bt, int ldb, int K, f32x16 (&acc)[2][NJ], char* lds) {
;     ...
; #pragma unroll
;   for (int i = 0; i < 4; ++i) GL1_(ra0, rb0, i);
;   ap += 128; bp += 128;
; #pragma unroll
;   for (int i = 0; i < 4; ++i) GL1_(ra1, rb1, i);
;   ap += 128; bp += 128;
; #pragma unroll
;   for (int i = 0; i < 4; ++i) LS1_(ra0, rb0, 0, i);
;   __syncthreads();
;   const int nk = K >> 6;
;   for (int kt = 0; kt < nk; kt += 2) {
;     const bool l0 = (kt + 2 < nk), l1 = (kt + 3 < nk);
;     STEP_(0, l0, ra0, rb0, true, ra1, rb1);
;     __syncthreads();
;     STEP_(1, l1, ra1, rb1, l0, ra0, rb0);
;     __syncthreads();
	ds_read_b128 v[78:81], v0 offset:36864
	ds_read_b128 v[106:109], v66 offset:55296
	ds_read_b128 v[110:113], v0 offset:41472
	s_waitcnt lgkmcnt(1)
	v_mfma_f32_32x32x16_bf16 v[34:49], v[78:81], v[106:109], v[34:49]
	s_waitcnt lgkmcnt(0)
	v_mfma_f32_32x32x16_bf16 v[2:17], v[110:113], v[106:109], v[2:17]
	ds_read_b128 v[106:109], v66 offset:59904
	s_waitcnt lgkmcnt(0)
	v_mfma_f32_32x32x16_bf16 v[50:65], v[78:81], v[106:109], v[50:65]
	global_load_dwordx4 v[78:81], v72, s[2:3] offset:1920
	global_load_dwordx4 v[114:117], v72, s[4:5] offset:1920
	ds_read_b128 v[118:121], v0 offset:36896
	ds_read_b128 v[122:125], v66 offset:55328
	ds_read_b128 v[126:129], v0 offset:41504
	ds_read_b128 v[134:137], v66 offset:59936
	s_waitcnt vmcnt(9)
	ds_write_b128 v67, v[82:85]
	s_waitcnt vmcnt(8)
	ds_write_b128 v67, v[130:133] offset:18432
	v_mfma_f32_32x32x16_bf16 v[18:33], v[110:113], v[106:109], v[18:33]
	global_load_dwordx4 v[82:85], v71, s[2:3] offset:1920
	global_load_dwordx4 v[106:109], v71, s[4:5] offset:1920
	s_waitcnt lgkmcnt(4)
	v_mfma_f32_32x32x16_bf16 v[34:49], v[118:121], v[122:125], v[34:49]
	s_waitcnt lgkmcnt(3)
	v_mfma_f32_32x32x16_bf16 v[2:17], v[126:129], v[122:125], v[2:17]
	s_waitcnt lgkmcnt(2)
	v_mfma_f32_32x32x16_bf16 v[50:65], v[118:121], v[134:137], v[50:65]
	ds_read_b128 v[110:113], v0 offset:36928
	ds_read_b128 v[118:121], v0 offset:41536
	ds_read_b128 v[122:125], v66 offset:55360
	ds_read_b128 v[130:133], v66 offset:59968
	s_waitcnt vmcnt(9)
	ds_write_b128 v67, v[86:89] offset:4608
	s_waitcnt vmcnt(8)
	ds_write_b128 v67, v[90:93] offset:23040
	v_mfma_f32_32x32x16_bf16 v[18:33], v[126:129], v[134:137], v[18:33]
	global_load_dwordx4 v[86:89], v70, s[2:3] offset:1920
	s_nop 0
	global_load_dwordx4 v[70:73], v70, s[4:5] offset:1920
	s_waitcnt lgkmcnt(3)
	v_mfma_f32_32x32x16_bf16 v[34:49], v[110:113], v[122:125], v[34:49]
	v_mfma_f32_32x32x16_bf16 v[2:17], v[118:121], v[122:125], v[2:17]
	s_waitcnt lgkmcnt(2)
	v_mfma_f32_32x32x16_bf16 v[50:65], v[110:113], v[130:133], v[50:65]
	ds_read_b128 v[90:93], v0 offset:36960
	ds_read_b128 v[110:113], v0 offset:41568
	ds_read_b128 v[122:125], v66 offset:55392
	ds_read_b128 v[126:129], v66 offset:60000
	s_waitcnt vmcnt(9)
	ds_write_b128 v67, v[94:97] offset:9216
	s_waitcnt vmcnt(8)
	ds_write_b128 v67, v[98:101] offset:27648
	v_mfma_f32_32x32x16_bf16 v[18:33], v[118:121], v[130:133], v[18:33]
	s_waitcnt lgkmcnt(3)
	v_mfma_f32_32x32x16_bf16 v[34:49], v[90:93], v[122:125], v[34:49]
	s_waitcnt lgkmcnt(2)
	v_mfma_f32_32x32x16_bf16 v[50:65], v[90:93], v[126:129], v[50:65]
	global_load_dwordx4 v[90:93], v69, s[2:3] offset:1920
	global_load_dwordx4 v[94:97], v69, s[4:5] offset:1920
	s_waitcnt vmcnt(9)
	ds_write_b128 v67, v[74:77] offset:13824
	s_waitcnt vmcnt(8)
	ds_write_b128 v67, v[102:105] offset:32256
	v_mfma_f32_32x32x16_bf16 v[2:17], v[110:113], v[122:125], v[2:17]
	v_mfma_f32_32x32x16_bf16 v[18:33], v[110:113], v[126:129], v[18:33]
	s_waitcnt lgkmcnt(0)
	s_barrier
	ds_read_b128 v[74:77], v0
	ds_read_b128 v[98:101], v66 offset:18432
	ds_read_b128 v[102:105], v0 offset:4608
	s_waitcnt lgkmcnt(1)
	v_mfma_f32_32x32x16_bf16 v[34:49], v[74:77], v[98:101], v[34:49]
	s_waitcnt lgkmcnt(0)
	v_mfma_f32_32x32x16_bf16 v[2:17], v[102:105], v[98:101], v[2:17]
	ds_read_b128 v[98:101], v66 offset:23040
	s_waitcnt lgkmcnt(0)
	v_mfma_f32_32x32x16_bf16 v[50:65], v[74:77], v[98:101], v[50:65]
	ds_read_b128 v[74:77], v0 offset:32
	ds_read_b128 v[110:113], v66 offset:18464
	ds_read_b128 v[118:121], v0 offset:4640
	ds_read_b128 v[122:125], v66 offset:23072
	s_waitcnt vmcnt(7)
	ds_write_b128 v67, v[78:81] offset:36864
	s_waitcnt vmcnt(6)
	ds_write_b128 v67, v[114:117] offset:55296
	v_mfma_f32_32x32x16_bf16 v[18:33], v[102:105], v[98:101], v[18:33]
	s_waitcnt lgkmcnt(4)
	v_mfma_f32_32x32x16_bf16 v[34:49], v[74:77], v[110:113], v[34:49]
	s_waitcnt lgkmcnt(2)
	v_mfma_f32_32x32x16_bf16 v[50:65], v[74:77], v[122:125], v[50:65]
	ds_read_b128 v[74:77], v0 offset:64
	ds_read_b128 v[78:81], v0 offset:4672
	ds_read_b128 v[98:101], v66 offset:18496
	ds_read_b128 v[102:105], v66 offset:23104
	s_waitcnt vmcnt(5)
	ds_write_b128 v67, v[82:85] offset:41472
	s_waitcnt vmcnt(4)
	ds_write_b128 v67, v[106:109] offset:59904
	v_mfma_f32_32x32x16_bf16 v[2:17], v[118:121], v[110:113], v[2:17]
	v_mfma_f32_32x32x16_bf16 v[18:33], v[118:121], v[122:125], v[18:33]
	s_waitcnt lgkmcnt(3)
	v_mfma_f32_32x32x16_bf16 v[34:49], v[74:77], v[98:101], v[34:49]
	v_mfma_f32_32x32x16_bf16 v[2:17], v[78:81], v[98:101], v[2:17]
	s_waitcnt lgkmcnt(2)
	v_mfma_f32_32x32x16_bf16 v[50:65], v[74:77], v[102:105], v[50:65]
	ds_read_b128 v[74:77], v0 offset:96
	ds_read_b128 v[82:85], v0 offset:4704
	ds_read_b128 v[98:101], v66 offset:18528
	ds_read_b128 v[106:109], v66 offset:23136
	s_waitcnt vmcnt(3)
	ds_write_b128 v67, v[86:89] offset:46080
	s_waitcnt vmcnt(2)
	ds_write_b128 v67, v[70:73] offset:64512
	v_mfma_f32_32x32x16_bf16 v[18:33], v[78:81], v[102:105], v[18:33]
	s_waitcnt lgkmcnt(3)
	v_mfma_f32_32x32x16_bf16 v[34:49], v[74:77], v[98:101], v[34:49]
	s_waitcnt vmcnt(1)
	ds_write_b128 v67, v[90:93] offset:50688
	s_waitcnt vmcnt(0)
	ds_write_b128 v68, v[94:97] offset:13824
	v_mfma_f32_32x32x16_bf16 v[2:17], v[82:85], v[98:101], v[2:17]
	s_waitcnt lgkmcnt(4)
	v_mfma_f32_32x32x16_bf16 v[50:65], v[74:77], v[106:109], v[50:65]
	v_mfma_f32_32x32x16_bf16 v[18:33], v[82:85], v[106:109], v[18:33]
	s_waitcnt lgkmcnt(0)
	s_barrier
; DI int tid_() { int t = threadIdx.x; asm volatile("" : "+v"(t)); return t; }
; #define GL1_(RA, RB, i) { RA[i] = *(const u32x4*)(ap + (aoff + (i) * astep)); if ((i) < NB) RB[(i) < NB ? (i) : 0] = *(const u32x4*)(bp + (boff + (i) * bstep)); }
; #define LS1_(RA, RB, ST, i) { char* sn_ = lds + (ST) * STAGE; *(u32x4*)(sn_ + wofs + (i) * 32 * LROW) = RA[i]; \
;                               if ((i) < NB) *(u32x4*)(sn_ + STAGE_OP + wofs + (i) * 32 * LROW) = RB[(i) < NB ? (i) : 0]; }
; template <int NJ> DI void gemm_mainloop_reg(const bf16_t* __restrict__ A, int lda, const bf16_t* __restrict__ Bt, int ldb, int K, f32x16 (&acc)[2][NJ], char* lds) {
;     ...
; #pragma unroll
;   for (int i = 0; i < 4; ++i) GL1_(ra0, rb0, i);
;   ap += 128; bp += 128;
; #pragma unroll
;   for (int i = 0; i < 4; ++i) GL1_(ra1, rb1, i);
;   ap += 128; bp += 128;
; #pragma unroll
;   for (int i = 0; i < 4; ++i) LS1_(ra0, rb0, 0, i);
;   __syncthreads();
;   const int nk = K >> 6;
;   for (int kt = 0; kt < nk; kt += 2) {
;     const bool l0 = (kt + 2 < nk), l1 = (kt + 3 < nk);
;     STEP_(0, l0, ra0, rb0, true, ra1, rb1);
;     __syncthreads();
;     STEP_(1, l1, ra1, rb1, l0, ra0, rb0);
;     __syncthreads();
; template <int NJ> DI void acc_to_lds(const f32x16 (&acc)[2][NJ], float* cl) {
;   const int tid = tid_(), lane = tid & 63, w = tid >> 6, wm = w >> 1, wn = w & 1, h = lane >> 5, c = lane & 31;
; #pragma unroll
;   for (int i = 0; i < 2; ++i)
; #pragma unroll
;     for (int j = 0; j < NJ; ++j)
; #pragma unroll
;       for (int r = 0; r < 16; ++r) {
;         const int row = wm * 64 + i * 32 + (r & 3) + 8 * (r >> 2) + 4 * h;
;         cl[row * CLD + wn * 32 * NJ + j * 32 + c] = acc[i][j][r];
;       }
; DI void phase_proj(const Ctx& c, bool dummy_ss = false) {
;     ...
;     const int tid = tid_(), half = __builtin_amdgcn_readfirstlane(tid >> 7), u = tid & 127;
;     if (tid < 128) rr[tid] = rsqrtf(ss[mt * 128 + tid] * (1.0f / DM) + EPS);
	ds_read_b128 v[68:71], v0 offset:36864
	ds_read_b128 v[72:75], v66 offset:55296
	ds_read_b128 v[76:79], v0 offset:41472
	s_waitcnt lgkmcnt(1)
	v_mfma_f32_32x32x16_bf16 v[34:49], v[68:71], v[72:75], v[34:49]
	s_waitcnt lgkmcnt(0)
	v_mfma_f32_32x32x16_bf16 v[2:17], v[76:79], v[72:75], v[2:17]
	ds_read_b128 v[72:75], v66 offset:59904
	s_waitcnt lgkmcnt(0)
	v_mfma_f32_32x32x16_bf16 v[50:65], v[68:71], v[72:75], v[50:65]
	ds_read_b128 v[68:71], v0 offset:36896
	ds_read_b128 v[80:83], v66 offset:55328
	ds_read_b128 v[84:87], v0 offset:41504
	ds_read_b128 v[88:91], v66 offset:59936
	v_mfma_f32_32x32x16_bf16 v[18:33], v[76:79], v[72:75], v[18:33]
	s_waitcnt lgkmcnt(2)
	v_mfma_f32_32x32x16_bf16 v[34:49], v[68:71], v[80:83], v[34:49]
	s_waitcnt lgkmcnt(1)
	v_mfma_f32_32x32x16_bf16 v[2:17], v[84:87], v[80:83], v[2:17]
	s_waitcnt lgkmcnt(0)
	v_mfma_f32_32x32x16_bf16 v[50:65], v[68:71], v[88:91], v[50:65]
	ds_read_b128 v[68:71], v0 offset:36928
	ds_read_b128 v[72:75], v0 offset:41536
	ds_read_b128 v[76:79], v66 offset:55360
	ds_read_b128 v[80:83], v66 offset:59968
	v_mfma_f32_32x32x16_bf16 v[18:33], v[84:87], v[88:91], v[18:33]
	s_waitcnt lgkmcnt(1)
	v_mfma_f32_32x32x16_bf16 v[34:49], v[68:71], v[76:79], v[34:49]
	v_mfma_f32_32x32x16_bf16 v[2:17], v[72:75], v[76:79], v[2:17]
	s_waitcnt lgkmcnt(0)
	v_mfma_f32_32x32x16_bf16 v[50:65], v[68:71], v[80:83], v[50:65]
	ds_read_b128 v[68:71], v0 offset:36960
	ds_read_b128 v[76:79], v0 offset:41568
	ds_read_b128 v[84:87], v66 offset:55392
	ds_read_b128 v[88:91], v66 offset:60000
	v_mfma_f32_32x32x16_bf16 v[18:33], v[72:75], v[80:83], v[18:33]
	s_waitcnt lgkmcnt(1)
	v_mfma_f32_32x32x16_bf16 v[34:49], v[68:71], v[84:87], v[34:49]
	v_mfma_f32_32x32x16_bf16 v[2:17], v[76:79], v[84:87], v[2:17]
	s_waitcnt lgkmcnt(0)
	v_mfma_f32_32x32x16_bf16 v[50:65], v[68:71], v[88:91], v[50:65]
	v_mfma_f32_32x32x16_bf16 v[18:33], v[76:79], v[88:91], v[18:33]
	s_setprio 0
	v_mov_b32_e32 v0, v199
	s_barrier
	v_mov_b32_e32 v134, v199
	v_lshrrev_b32_e32 v67, 3, v0
	v_lshrrev_b32_e32 v66, 1, v0
	v_and_b32_e32 v67, 4, v67
	v_and_b32_e32 v0, 0x5f, v0
	v_and_or_b32 v66, v66, s17, v67
	v_mul_lo_u32 v66, v66, s15
	v_lshlrev_b32_e32 v0, 2, v0
	v_add3_u32 v0, 0, v66, v0
	ds_write2_b32 v0, v34, v50 offset1:32
	ds_write2_b32 v0, v35, v51 offset0:132 offset1:164
	v_add_u32_e32 v34, 0x400, v0
	ds_write2_b32 v34, v36, v52 offset0:8 offset1:40
	ds_write2_b32 v34, v37, v53 offset0:140 offset1:172
	v_add_u32_e32 v34, 0x1000, v0
	ds_write2_b32 v34, v38, v54 offset0:32 offset1:64
	ds_write2_b32 v34, v39, v55 offset0:164 offset1:196
	v_add_u32_e32 v34, 0x1400, v0
	ds_write2_b32 v34, v40, v56 offset0:40 offset1:72
	ds_write2_b32 v34, v41, v57 offset0:172 offset1:204
	v_add_u32_e32 v34, 0x2000, v0
	ds_write2_b32 v34, v42, v58 offset0:64 offset1:96
	ds_write2_b32 v34, v43, v59 offset0:196 offset1:228
	v_add_u32_e32 v34, 0x2400, v0
	ds_write2_b32 v34, v44, v60 offset0:72 offset1:104
	ds_write2_b32 v34, v45, v61 offset0:204 offset1:236
	v_add_u32_e32 v34, 0x3000, v0
	ds_write2_b32 v34, v46, v62 offset0:96 offset1:128
	v_add_u32_e32 v34, 0x3200, v0
	ds_write2_b32 v34, v47, v63 offset0:100 offset1:132
	v_add_u32_e32 v34, 0x3400, v0
	ds_write2_b32 v34, v48, v64 offset0:104 offset1:136
	v_add_u32_e32 v34, 0x3600, v0
	ds_write2_b32 v34, v49, v65 offset0:108 offset1:140
	v_add_u32_e32 v34, 0x4000, v0
	ds_write2_b32 v34, v2, v18 offset0:128 offset1:160
	v_add_u32_e32 v2, 0x4400, v0
	ds_write2_b32 v2, v3, v19 offset0:4 offset1:36
	ds_write2_b32 v2, v4, v20 offset0:136 offset1:168
	v_add_u32_e32 v2, 0x4800, v0
	ds_write2_b32 v2, v5, v21 offset0:12 offset1:44
	v_add_u32_e32 v2, 0x5000, v0
	ds_write2_b32 v2, v6, v22 offset0:160 offset1:192
	v_add_u32_e32 v2, 0x5400, v0
	ds_write2_b32 v2, v7, v23 offset0:36 offset1:68
	ds_write2_b32 v2, v8, v24 offset0:168 offset1:200
	v_add_u32_e32 v2, 0x5800, v0
	ds_write2_b32 v2, v9, v25 offset0:44 offset1:76
	v_add_u32_e32 v2, 0x6000, v0
	ds_write2_b32 v2, v10, v26 offset0:192 offset1:224
	v_add_u32_e32 v2, 0x6400, v0
	ds_write2_b32 v2, v11, v27 offset0:68 offset1:100
	ds_write2_b32 v2, v12, v28 offset0:200 offset1:232
	v_add_u32_e32 v2, 0x6800, v0
	ds_write2_b32 v2, v13, v29 offset0:76 offset1:108
	v_add_u32_e32 v2, 0x7200, v0
	ds_write2_b32 v2, v14, v30 offset0:96 offset1:128
	v_add_u32_e32 v2, 0x7400, v0
	ds_write2_b32 v2, v15, v31 offset0:100 offset1:132
	v_add_u32_e32 v2, 0x7600, v0
	v_add_u32_e32 v0, 0x7800, v0
	s_movk_i32 s2, 0x80
	ds_write2_b32 v2, v16, v32 offset0:104 offset1:136
	ds_write2_b32 v0, v17, v33 offset0:108 offset1:140
	s_lshl_b32 s52, s7, 7
	v_readfirstlane_b32 s4, v134
	v_cmp_gt_i32_e32 vcc, s2, v134
	s_and_saveexec_b64 s[2:3], vcc
	s_cbranch_execz .LBB0_501
	v_add_u32_e32 v2, s52, v134
	v_ashrrev_i32_e32 v3, 31, v2
	v_lshl_add_u64 v[2:3], v[2:3], 2, s[0:1]
	global_load_dword v0, v[2:3], off
	s_mov_b32 s5, 0x800000
	s_waitcnt vmcnt(0)
	v_fmamk_f32 v0, v0, 0x3a800000, v198
	v_mul_f32_e32 v2, 0x4b800000, v0
	v_cmp_gt_f32_e32 vcc, s5, v0
	s_nop 1
	v_cndmask_b32_e32 v0, v0, v2, vcc
	v_rsq_f32_e32 v0, v0
	v_lshl_add_u32 v2, v134, 2, 0
	v_add_u32_e32 v2, 0x12000, v2
	v_mul_f32_e32 v3, 0x45800000, v0
	v_cndmask_b32_e32 v0, v0, v3, vcc
	ds_write_b32 v2, v0

; #define GL1_(RA, RB, i) { RA[i] = *(const u32x4*)(ap + (aoff + (i) * astep)); if ((i) < NB) RB[(i) < NB ? (i) : 0] = *(const u32x4*)(bp + (boff + (i) * bstep)); }
; #define LS1_(RA, RB, ST, i) { char* sn_ = lds + (ST) * STAGE; *(u32x4*)(sn_ + wofs + (i) * 32 * LROW) = RA[i]; \
;                               if ((i) < NB) *(u32x4*)(sn_ + STAGE_OP + wofs + (i) * 32 * LROW) = RB[(i) < NB ? (i) : 0]; }
; DI bf16_t* wsb(const Ctx& c, size_t off) { return (bf16_t*)(c.ws + off); }
; DI const bf16_t* wgt(const Ctx& c, size_t off) { return (const bf16_t*)(c.ws + OFF_W) + (size_t)c.layer * W_LAYER + off; }
; template <int NJ> DI void gemm_mainloop_reg(const bf16_t* __restrict__ A, int lda, const bf16_t* __restrict__ Bt, int ldb, int K, f32x16 (&acc)[2][NJ], char* lds) {
;     ...
; #pragma unroll
;   for (int i = 0; i < 4; ++i) GL1_(ra0, rb0, i);
;   ap += 128; bp += 128;
; #pragma unroll
;   for (int i = 0; i < 4; ++i) GL1_(ra1, rb1, i);
;   ap += 128; bp += 128;
; #pragma unroll
;   for (int i = 0; i < 4; ++i) LS1_(ra0, rb0, 0, i);
;   __syncthreads();
;   const int nk = K >> 6;
;   for (int kt = 0; kt < nk; kt += 2) {
;     const bool l0 = (kt + 2 < nk), l1 = (kt + 3 < nk);
;     STEP_(0, l0, ra0, rb0, true, ra1, rb1);
;     __syncthreads();
;     STEP_(1, l1, ra1, rb1, l0, ra0, rb0);
;     __syncthreads();
; DI void phase_mlaup(const Ctx& c) {
;     ...
;     else gemm_mainloop_reg<2>(wsb(c, OFF_CKV) + (size_t)mt * 128 * LDCKV, LDCKV, wgt(c, W_UKV) + (size_t)(nt - 6) * 128 * LDCKV, LDCKV, 128, acc, c.lds);
.LBB0_593:
	s_and_b32 s0, s25, 15
	s_or_b32 s27, s0, s78
	s_lshr_b32 s26, s25, 4
	s_cmpk_lt_u32 s25, 0x60
	s_cselect_b64 s[38:39], -1, 0
	s_cmpk_gt_u32 s25, 0x5f
	s_cselect_b64 s[0:1], -1, 0
	s_mov_b64 s[2:3], -1
	s_and_b64 vcc, exec, s[0:1]
	s_cbranch_vccz .LBB0_595
	s_mul_i32 s2, s27, 0xc000
	v_readlane_b32 s3, v250, 34
	v_mov_b32_e32 v0, v199
	s_add_u32 s2, s3, s2
	v_readlane_b32 s3, v250, 35
	s_movk_i32 s44, 0x180
	v_ashrrev_i32_e32 v34, 3, v0
	v_lshlrev_b32_e32 v2, 4, v0
	s_addc_u32 s3, s3, 0
	s_add_i32 s4, s26, -6
	v_and_b32_e32 v35, 0x70, v2
	v_mul_lo_u32 v2, v34, s44
	s_mul_hi_u32 s5, s4, 0xc000
	s_mul_i32 s4, s4, 0xc000
	v_or_b32_e32 v36, v35, v2
	s_add_u32 s4, s6, s4
	v_add_u32_e32 v37, 0x3000, v36
	v_add_u32_e32 v38, 0x6000, v36
	s_addc_u32 s5, s7, s5
	global_load_dwordx4 v[2:5], v36, s[2:3]
	global_load_dwordx4 v[6:9], v36, s[4:5]
	global_load_dwordx4 v[10:13], v37, s[2:3]
	global_load_dwordx4 v[14:17], v37, s[4:5]
	global_load_dwordx4 v[18:21], v38, s[2:3]
	global_load_dwordx4 v[22:25], v38, s[4:5]
	v_add_u32_e32 v39, 0x9000, v36
	global_load_dwordx4 v[26:29], v39, s[2:3]
	global_load_dwordx4 v[30:33], v39, s[4:5]
	global_load_dwordx4 v[66:69], v36, s[2:3] offset:128
	global_load_dwordx4 v[70:73], v36, s[4:5] offset:128
	global_load_dwordx4 v[74:77], v37, s[2:3] offset:128
	global_load_dwordx4 v[78:81], v37, s[4:5] offset:128
	global_load_dwordx4 v[82:85], v38, s[2:3] offset:128
	global_load_dwordx4 v[86:89], v38, s[4:5] offset:128
	global_load_dwordx4 v[90:93], v39, s[2:3] offset:128
	global_load_dwordx4 v[94:97], v39, s[4:5] offset:128
	v_lshrrev_b32_e32 v36, 1, v0
	v_and_b32_e32 v37, 31, v0
	v_mul_lo_u32 v34, v34, s16
	v_and_b32_e32 v38, 16, v36
	v_and_or_b32 v36, v36, s17, v37
	v_add3_u32 v114, v34, v35, 0
	v_mul_lo_u32 v34, v36, s16
	v_add3_u32 v115, v34, v38, 0
	v_and_b32_e32 v0, 0x5f, v0
	v_mul_u32_u24_e32 v0, 0x90, v0
	v_add3_u32 v0, v0, v38, 0
	v_add_u32_e32 v116, 0xd800, v114
	s_waitcnt vmcnt(15)
	ds_write_b128 v114, v[2:5]
	s_waitcnt vmcnt(14)
	ds_write_b128 v114, v[6:9] offset:18432
	s_waitcnt vmcnt(13)
	ds_write_b128 v114, v[10:13] offset:4608
	s_waitcnt vmcnt(12)
	ds_write_b128 v114, v[14:17] offset:23040
	s_waitcnt vmcnt(11)
	ds_write_b128 v114, v[18:21] offset:9216
	s_waitcnt vmcnt(10)
	ds_write_b128 v114, v[22:25] offset:27648
	s_waitcnt vmcnt(9)
	ds_write_b128 v114, v[26:29] offset:13824
	s_waitcnt vmcnt(8)
	ds_write_b128 v114, v[30:33] offset:32256
	s_waitcnt lgkmcnt(0)
	s_barrier
	ds_read_b128 v[18:21], v115
	ds_read_b128 v[2:5], v0 offset:18432
	ds_read_b128 v[98:101], v115 offset:32
	ds_read_b128 v[102:105], v0 offset:18464
	ds_read_b128 v[22:25], v115 offset:4608
	ds_read_b128 v[106:109], v115 offset:4640
	ds_read_b128 v[26:29], v0 offset:23040
	ds_read_b128 v[110:113], v0 offset:23072
	s_waitcnt lgkmcnt(6)
	s_setprio 1
	v_mfma_f32_32x32x16_bf16 v[34:49], v[18:21], v[2:5], 0
	s_waitcnt vmcnt(7)
	ds_write_b128 v114, v[66:69] offset:36864
	s_waitcnt vmcnt(6)
	ds_write_b128 v114, v[70:73] offset:55296
	s_waitcnt lgkmcnt(5)
	v_mfma_f32_32x32x16_bf16 v[2:17], v[22:25], v[2:5], 0
	s_waitcnt lgkmcnt(3)
	v_mfma_f32_32x32x16_bf16 v[50:65], v[18:21], v[26:29], 0
	v_mfma_f32_32x32x16_bf16 v[18:33], v[22:25], v[26:29], 0
	v_mfma_f32_32x32x16_bf16 v[34:49], v[98:101], v[102:105], v[34:49]
	v_mfma_f32_32x32x16_bf16 v[2:17], v[106:109], v[102:105], v[2:17]
	s_waitcnt lgkmcnt(2)
	v_mfma_f32_32x32x16_bf16 v[50:65], v[98:101], v[110:113], v[50:65]
	ds_read_b128 v[66:69], v115 offset:64
	ds_read_b128 v[70:73], v115 offset:4672
	ds_read_b128 v[98:101], v0 offset:18496
	ds_read_b128 v[102:105], v0 offset:23104
	s_waitcnt vmcnt(5)
	ds_write_b128 v114, v[74:77] offset:41472
	s_waitcnt vmcnt(4)
	ds_write_b128 v114, v[78:81] offset:59904
	v_mfma_f32_32x32x16_bf16 v[18:33], v[106:109], v[110:113], v[18:33]
	s_waitcnt lgkmcnt(3)
	v_mfma_f32_32x32x16_bf16 v[34:49], v[66:69], v[98:101], v[34:49]
	v_mfma_f32_32x32x16_bf16 v[2:17], v[70:73], v[98:101], v[2:17]
	s_waitcnt lgkmcnt(2)
	v_mfma_f32_32x32x16_bf16 v[50:65], v[66:69], v[102:105], v[50:65]
	ds_read_b128 v[66:69], v115 offset:96
	ds_read_b128 v[74:77], v115 offset:4704
	ds_read_b128 v[78:81], v0 offset:18528
	ds_read_b128 v[98:101], v0 offset:23136
	s_waitcnt vmcnt(3)
	ds_write_b128 v114, v[82:85] offset:46080
	s_waitcnt vmcnt(2)
	ds_write_b128 v114, v[86:89] offset:64512
	v_mfma_f32_32x32x16_bf16 v[18:33], v[70:73], v[102:105], v[18:33]
	s_waitcnt lgkmcnt(3)
	v_mfma_f32_32x32x16_bf16 v[34:49], v[66:69], v[78:81], v[34:49]
	s_waitcnt vmcnt(1)
	ds_write_b128 v114, v[90:93] offset:50688
	s_waitcnt vmcnt(0)
	ds_write_b128 v116, v[94:97] offset:13824
	v_mfma_f32_32x32x16_bf16 v[2:17], v[74:77], v[78:81], v[2:17]
	s_waitcnt lgkmcnt(4)
	v_mfma_f32_32x32x16_bf16 v[50:65], v[66:69], v[98:101], v[50:65]
	v_mfma_f32_32x32x16_bf16 v[18:33], v[74:77], v[98:101], v[18:33]
	s_waitcnt lgkmcnt(0)
	s_barrier
	ds_read_b128 v[66:69], v115 offset:36864
	ds_read_b128 v[70:73], v0 offset:55296
	ds_read_b128 v[74:77], v115 offset:41472
	s_waitcnt lgkmcnt(1)
	v_mfma_f32_32x32x16_bf16 v[34:49], v[66:69], v[70:73], v[34:49]
	s_waitcnt lgkmcnt(0)
	v_mfma_f32_32x32x16_bf16 v[2:17], v[74:77], v[70:73], v[2:17]
	ds_read_b128 v[70:73], v0 offset:59904
	s_waitcnt lgkmcnt(0)
	v_mfma_f32_32x32x16_bf16 v[50:65], v[66:69], v[70:73], v[50:65]
	ds_read_b128 v[66:69], v115 offset:36896
	ds_read_b128 v[78:81], v0 offset:55328
	ds_read_b128 v[82:85], v115 offset:41504
	ds_read_b128 v[86:89], v0 offset:59936
	v_mfma_f32_32x32x16_bf16 v[18:33], v[74:77], v[70:73], v[18:33]
	s_waitcnt lgkmcnt(2)
	v_mfma_f32_32x32x16_bf16 v[34:49], v[66:69], v[78:81], v[34:49]
	s_waitcnt lgkmcnt(1)
	v_mfma_f32_32x32x16_bf16 v[2:17], v[82:85], v[78:81], v[2:17]
	s_waitcnt lgkmcnt(0)
	v_mfma_f32_32x32x16_bf16 v[50:65], v[66:69], v[86:89], v[50:65]
	ds_read_b128 v[66:69], v115 offset:36928
	ds_read_b128 v[70:73], v115 offset:41536
	ds_read_b128 v[74:77], v0 offset:55360
	ds_read_b128 v[78:81], v0 offset:59968
	v_mfma_f32_32x32x16_bf16 v[18:33], v[82:85], v[86:89], v[18:33]
	s_waitcnt lgkmcnt(1)
	v_mfma_f32_32x32x16_bf16 v[34:49], v[66:69], v[74:77], v[34:49]
	v_mfma_f32_32x32x16_bf16 v[2:17], v[70:73], v[74:77], v[2:17]
	s_waitcnt lgkmcnt(0)
	v_mfma_f32_32x32x16_bf16 v[50:65], v[66:69], v[78:81], v[50:65]
	ds_read_b128 v[66:69], v115 offset:36960
	ds_read_b128 v[74:77], v115 offset:41568
	ds_read_b128 v[82:85], v0 offset:55392
	ds_read_b128 v[86:89], v0 offset:60000
	v_mfma_f32_32x32x16_bf16 v[18:33], v[70:73], v[78:81], v[18:33]
	s_waitcnt lgkmcnt(1)
	v_mfma_f32_32x32x16_bf16 v[34:49], v[66:69], v[82:85], v[34:49]
	v_mfma_f32_32x32x16_bf16 v[2:17], v[74:77], v[82:85], v[2:17]
	s_waitcnt lgkmcnt(0)
	v_mfma_f32_32x32x16_bf16 v[50:65], v[66:69], v[86:89], v[50:65]
	v_mfma_f32_32x32x16_bf16 v[18:33], v[74:77], v[86:89], v[18:33]
	s_setprio 0
	s_barrier
	s_mov_b64 s[2:3], 0
; DI int tid_() { int t = threadIdx.x; asm volatile("" : "+v"(t)); return t; }
; #define GL1_(RA, RB, i) { RA[i] = *(const u32x4*)(ap + (aoff + (i) * astep)); if ((i) < NB) RB[(i) < NB ? (i) : 0] = *(const u32x4*)(bp + (boff + (i) * bstep)); }
; #define LS1_(RA, RB, ST, i) { char* sn_ = lds + (ST) * STAGE; *(u32x4*)(sn_ + wofs + (i) * 32 * LROW) = RA[i]; \
;                               if ((i) < NB) *(u32x4*)(sn_ + STAGE_OP + wofs + (i) * 32 * LROW) = RB[(i) < NB ? (i) : 0]; }
; template <int NJ> DI void gemm_mainloop_reg(const bf16_t* __restrict__ A, int lda, const bf16_t* __restrict__ Bt, int ldb, int K, f32x16 (&acc)[2][NJ], char* lds) {
;   const int tid = tid_(), lane = tid & 63, w = tid >> 6, wm = w >> 1, wn = w & 1;
;   const int lr = tid >> 3, lc = tid & 7;
;   const char* ap = (const char*)A;
;   const char* bp = (const char*)Bt;
;   const unsigned aoff = (unsigned)(lr * lda + lc * 8) * 2u, boff = (unsigned)(lr * ldb + lc * 8) * 2u;
;   const unsigned astep = (unsigned)(32 * lda) * 2u, bstep = (unsigned)(32 * ldb) * 2u;
;   constexpr int NB = 2 * NJ;
;   u32x4 ra0[4], rb0[NB], ra1[4], rb1[NB];
;   const int wofs = lr * LROW + lc * 16;
;   const int a_rd = (wm * 64 + (lane & 31)) * LROW + (lane >> 5) * 16;
;   const int b_rd = STAGE_OP + (wn * 32 * NJ + (lane & 31)) * LROW + (lane >> 5) * 16;
;     ...
; #pragma unroll
;   for (int i = 0; i < 4; ++i) GL1_(ra0, rb0, i);
;   ap += 128; bp += 128;
; #pragma unroll
;   for (int i = 0; i < 4; ++i) GL1_(ra1, rb1, i);
;   ap += 128; bp += 128;
; #pragma unroll
;   for (int i = 0; i < 4; ++i) LS1_(ra0, rb0, 0, i);
;   __syncthreads();
;   const int nk = K >> 6;
;   for (int kt = 0; kt < nk; kt += 2) {
;     const bool l0 = (kt + 2 < nk), l1 = (kt + 3 < nk);
;     STEP_(0, l0, ra0, rb0, true, ra1, rb1);
;     __syncthreads();
;     STEP_(1, l1, ra1, rb1, l0, ra0, rb0);
;     __syncthreads();
;   }
.LBB0_595:
	s_andn2_b64 vcc, exec, s[2:3]
	s_cbranch_vccnz .LBB0_597
	v_mov_b32_e32 v0, v199
	s_mul_i32 s2, s27, 0x14000
	s_add_u32 s2, s86, s2
	s_nop 0
	v_ashrrev_i32_e32 v34, 3, v0
	v_lshlrev_b32_e32 v2, 4, v0
	s_mul_i32 s72, s26, 0xa000
	v_and_b32_e32 v35, 0x70, v2
	v_mul_lo_u32 v2, v34, s68
	s_addc_u32 s3, s87, 0
	s_lshl_b64 s[4:5], s[72:73], 1
	v_or_b32_e32 v130, v35, v2
	s_add_u32 s4, s34, s4
	v_add_u32_e32 v131, 0x5000, v130
	v_add_u32_e32 v132, 0xa000, v130
	v_add_u32_e32 v133, 0xf000, v130
	s_addc_u32 s5, s35, s5
	global_load_dwordx4 v[2:5], v130, s[2:3]
	global_load_dwordx4 v[6:9], v130, s[4:5]
	global_load_dwordx4 v[10:13], v131, s[2:3]
	global_load_dwordx4 v[14:17], v131, s[4:5]
	global_load_dwordx4 v[18:21], v132, s[2:3]
	global_load_dwordx4 v[22:25], v132, s[4:5]
	global_load_dwordx4 v[26:29], v133, s[2:3]
	global_load_dwordx4 v[30:33], v133, s[4:5]
	v_lshrrev_b32_e32 v36, 1, v0
	v_and_b32_e32 v37, 31, v0
	global_load_dwordx4 v[66:69], v130, s[2:3] offset:128
	global_load_dwordx4 v[70:73], v130, s[4:5] offset:128
	global_load_dwordx4 v[74:77], v131, s[2:3] offset:128
	global_load_dwordx4 v[78:81], v131, s[4:5] offset:128
	global_load_dwordx4 v[82:85], v132, s[2:3] offset:128
	global_load_dwordx4 v[86:89], v132, s[4:5] offset:128
	global_load_dwordx4 v[90:93], v133, s[2:3] offset:128
	global_load_dwordx4 v[94:97], v133, s[4:5] offset:128
	v_mul_lo_u32 v34, v34, s16
	v_and_b32_e32 v38, 16, v36
	v_and_or_b32 v36, v36, s17, v37
	v_and_b32_e32 v0, 0x5f, v0
	v_add3_u32 v134, v34, v35, 0
	v_mul_lo_u32 v34, v36, s16
	v_mul_u32_u24_e32 v0, 0x90, v0
	v_add3_u32 v135, v34, v38, 0
	v_add3_u32 v0, v0, v38, 0
	v_add_u32_e32 v136, 0xd800, v134
	s_waitcnt vmcnt(15)
	ds_write_b128 v134, v[2:5]
	s_waitcnt vmcnt(14)
	ds_write_b128 v134, v[6:9] offset:18432
	s_waitcnt vmcnt(13)
	ds_write_b128 v134, v[10:13] offset:4608
	s_waitcnt vmcnt(12)
	ds_write_b128 v134, v[14:17] offset:23040
	s_waitcnt vmcnt(11)
	ds_write_b128 v134, v[18:21] offset:9216
	s_waitcnt vmcnt(10)
	ds_write_b128 v134, v[22:25] offset:27648
	s_waitcnt vmcnt(9)
	ds_write_b128 v134, v[26:29] offset:13824
	s_waitcnt vmcnt(8)
	ds_write_b128 v134, v[30:33] offset:32256
	s_waitcnt lgkmcnt(0)
	s_barrier
	ds_read_b128 v[18:21], v135
	ds_read_b128 v[2:5], v0 offset:18432
	ds_read_b128 v[98:101], v135 offset:32
	ds_read_b128 v[102:105], v0 offset:18464
	ds_read_b128 v[22:25], v135 offset:4608
	ds_read_b128 v[106:109], v135 offset:4640
	ds_read_b128 v[26:29], v0 offset:23040
	ds_read_b128 v[110:113], v0 offset:23072
	global_load_dwordx4 v[114:117], v130, s[2:3] offset:256
	global_load_dwordx4 v[118:121], v130, s[4:5] offset:256
	s_waitcnt lgkmcnt(6)
	s_setprio 1
	v_mfma_f32_32x32x16_bf16 v[34:49], v[18:21], v[2:5], 0
	s_waitcnt vmcnt(9)
	ds_write_b128 v134, v[66:69] offset:36864
	s_waitcnt vmcnt(8)
	ds_write_b128 v134, v[70:73] offset:55296
	s_waitcnt lgkmcnt(5)
	v_mfma_f32_32x32x16_bf16 v[2:17], v[22:25], v[2:5], 0
	s_waitcnt lgkmcnt(3)
	v_mfma_f32_32x32x16_bf16 v[50:65], v[18:21], v[26:29], 0
	v_mfma_f32_32x32x16_bf16 v[18:33], v[22:25], v[26:29], 0
	global_load_dwordx4 v[66:69], v131, s[2:3] offset:256
	global_load_dwordx4 v[70:73], v131, s[4:5] offset:256
	v_mfma_f32_32x32x16_bf16 v[34:49], v[98:101], v[102:105], v[34:49]
	v_mfma_f32_32x32x16_bf16 v[2:17], v[106:109], v[102:105], v[2:17]
	s_waitcnt lgkmcnt(2)
	v_mfma_f32_32x32x16_bf16 v[50:65], v[98:101], v[110:113], v[50:65]
	ds_read_b128 v[98:101], v135 offset:64
	ds_read_b128 v[102:105], v135 offset:4672
	ds_read_b128 v[122:125], v0 offset:18496
	ds_read_b128 v[126:129], v0 offset:23104
	s_waitcnt vmcnt(9)
	ds_write_b128 v134, v[74:77] offset:41472
	s_waitcnt vmcnt(8)
	ds_write_b128 v134, v[78:81] offset:59904
	v_mfma_f32_32x32x16_bf16 v[18:33], v[106:109], v[110:113], v[18:33]
	global_load_dwordx4 v[74:77], v132, s[2:3] offset:256
	global_load_dwordx4 v[78:81], v132, s[4:5] offset:256
	s_waitcnt lgkmcnt(3)
	v_mfma_f32_32x32x16_bf16 v[34:49], v[98:101], v[122:125], v[34:49]
	v_mfma_f32_32x32x16_bf16 v[2:17], v[102:105], v[122:125], v[2:17]
	s_waitcnt lgkmcnt(2)
	v_mfma_f32_32x32x16_bf16 v[50:65], v[98:101], v[126:129], v[50:65]
	ds_read_b128 v[98:101], v135 offset:96
	ds_read_b128 v[106:109], v135 offset:4704
	ds_read_b128 v[110:113], v0 offset:18528
	ds_read_b128 v[122:125], v0 offset:23136
	s_waitcnt vmcnt(9)
	ds_write_b128 v134, v[82:85] offset:46080
	s_waitcnt vmcnt(8)
	ds_write_b128 v134, v[86:89] offset:64512
	v_mfma_f32_32x32x16_bf16 v[18:33], v[102:105], v[126:129], v[18:33]
	global_load_dwordx4 v[82:85], v133, s[2:3] offset:256
	global_load_dwordx4 v[86:89], v133, s[4:5] offset:256
	s_waitcnt lgkmcnt(3)
	v_mfma_f32_32x32x16_bf16 v[34:49], v[98:101], v[110:113], v[34:49]
	s_waitcnt vmcnt(9)
	ds_write_b128 v134, v[90:93] offset:50688
	s_waitcnt vmcnt(8)
	ds_write_b128 v136, v[94:97] offset:13824
	v_mfma_f32_32x32x16_bf16 v[2:17], v[106:109], v[110:113], v[2:17]
	s_waitcnt lgkmcnt(4)
	v_mfma_f32_32x32x16_bf16 v[50:65], v[98:101], v[122:125], v[50:65]
	v_mfma_f32_32x32x16_bf16 v[18:33], v[106:109], v[122:125], v[18:33]
	s_waitcnt lgkmcnt(0)
	s_barrier
; #define GL1_(RA, RB, i) { RA[i] = *(const u32x4*)(ap + (aoff + (i) * astep)); if ((i) < NB) RB[(i) < NB ? (i) : 0] = *(const u32x4*)(bp + (boff + (i) * bstep)); }
; #define LS1_(RA, RB, ST, i) { char* sn_ = lds + (ST) * STAGE; *(u32x4*)(sn_ + wofs + (i) * 32 * LROW) = RA[i]; \
;                               if ((i) < NB) *(u32x4*)(sn_ + STAGE_OP + wofs + (i) * 32 * LROW) = RB[(i) < NB ? (i) : 0]; }
; template <int NJ> DI void gemm_mainloop_reg(const bf16_t* __restrict__ A, int lda, const bf16_t* __restrict__ Bt, int ldb, int K, f32x16 (&acc)[2][NJ], char* lds) {
;     ...
; #pragma unroll
;   for (int i = 0; i < 4; ++i) GL1_(ra0, rb0, i);
;   ap += 128; bp += 128;
; #pragma unroll
;   for (int i = 0; i < 4; ++i) GL1_(ra1, rb1, i);
;   ap += 128; bp += 128;
; #pragma unroll
;   for (int i = 0; i < 4; ++i) LS1_(ra0, rb0, 0, i);
;   __syncthreads();
;   const int nk = K >> 6;
;   for (int kt = 0; kt < nk; kt += 2) {
;     const bool l0 = (kt + 2 < nk), l1 = (kt + 3 < nk);
;     STEP_(0, l0, ra0, rb0, true, ra1, rb1);
;     __syncthreads();
;     STEP_(1, l1, ra1, rb1, l0, ra0, rb0);
;     __syncthreads();
;   }
	ds_read_b128 v[90:93], v135 offset:36864
	ds_read_b128 v[94:97], v0 offset:55296
	ds_read_b128 v[98:101], v135 offset:41472
	s_waitcnt lgkmcnt(1)
	v_mfma_f32_32x32x16_bf16 v[34:49], v[90:93], v[94:97], v[34:49]
	s_waitcnt lgkmcnt(0)
	v_mfma_f32_32x32x16_bf16 v[2:17], v[98:101], v[94:97], v[2:17]
	ds_read_b128 v[94:97], v0 offset:59904
	s_waitcnt lgkmcnt(0)
	v_mfma_f32_32x32x16_bf16 v[50:65], v[90:93], v[94:97], v[50:65]
	global_load_dwordx4 v[90:93], v130, s[2:3] offset:384
	global_load_dwordx4 v[102:105], v130, s[4:5] offset:384
	ds_read_b128 v[106:109], v135 offset:36896
	ds_read_b128 v[110:113], v0 offset:55328
	ds_read_b128 v[122:125], v135 offset:41504
	ds_read_b128 v[126:129], v0 offset:59936
	s_waitcnt vmcnt(9)
	ds_write_b128 v134, v[114:117]
	s_waitcnt vmcnt(8)
	ds_write_b128 v134, v[118:121] offset:18432
	v_mfma_f32_32x32x16_bf16 v[18:33], v[98:101], v[94:97], v[18:33]
	global_load_dwordx4 v[94:97], v131, s[2:3] offset:384
	global_load_dwordx4 v[98:101], v131, s[4:5] offset:384
	s_waitcnt lgkmcnt(4)
	v_mfma_f32_32x32x16_bf16 v[34:49], v[106:109], v[110:113], v[34:49]
	s_waitcnt lgkmcnt(3)
	v_mfma_f32_32x32x16_bf16 v[2:17], v[122:125], v[110:113], v[2:17]
	s_waitcnt lgkmcnt(2)
	v_mfma_f32_32x32x16_bf16 v[50:65], v[106:109], v[126:129], v[50:65]
	ds_read_b128 v[106:109], v135 offset:36928
	ds_read_b128 v[110:113], v135 offset:41536
	ds_read_b128 v[114:117], v0 offset:55360
	ds_read_b128 v[118:121], v0 offset:59968
	s_waitcnt vmcnt(9)
	ds_write_b128 v134, v[66:69] offset:4608
	s_waitcnt vmcnt(8)
	ds_write_b128 v134, v[70:73] offset:23040
	v_mfma_f32_32x32x16_bf16 v[18:33], v[122:125], v[126:129], v[18:33]
	global_load_dwordx4 v[66:69], v132, s[2:3] offset:384
	global_load_dwordx4 v[70:73], v132, s[4:5] offset:384
	s_waitcnt lgkmcnt(3)
	v_mfma_f32_32x32x16_bf16 v[34:49], v[106:109], v[114:117], v[34:49]
	v_mfma_f32_32x32x16_bf16 v[2:17], v[110:113], v[114:117], v[2:17]
	s_waitcnt lgkmcnt(2)
	v_mfma_f32_32x32x16_bf16 v[50:65], v[106:109], v[118:121], v[50:65]
	ds_read_b128 v[106:109], v135 offset:36960
	ds_read_b128 v[114:117], v135 offset:41568
	ds_read_b128 v[122:125], v0 offset:55392
	ds_read_b128 v[126:129], v0 offset:60000
	s_waitcnt vmcnt(9)
	ds_write_b128 v134, v[74:77] offset:9216
	s_waitcnt vmcnt(8)
	ds_write_b128 v134, v[78:81] offset:27648
	v_mfma_f32_32x32x16_bf16 v[18:33], v[110:113], v[118:121], v[18:33]
	global_load_dwordx4 v[74:77], v133, s[2:3] offset:384
	global_load_dwordx4 v[78:81], v133, s[4:5] offset:384
	s_waitcnt lgkmcnt(3)
	v_mfma_f32_32x32x16_bf16 v[34:49], v[106:109], v[122:125], v[34:49]
	s_waitcnt vmcnt(9)
	ds_write_b128 v134, v[82:85] offset:13824
	s_waitcnt vmcnt(8)
	ds_write_b128 v134, v[86:89] offset:32256
	v_mfma_f32_32x32x16_bf16 v[2:17], v[114:117], v[122:125], v[2:17]
	s_waitcnt lgkmcnt(4)
	v_mfma_f32_32x32x16_bf16 v[50:65], v[106:109], v[126:129], v[50:65]
	v_mfma_f32_32x32x16_bf16 v[18:33], v[114:117], v[126:129], v[18:33]
	s_waitcnt lgkmcnt(0)
	s_barrier
; #define GL1_(RA, RB, i) { RA[i] = *(const u32x4*)(ap + (aoff + (i) * astep)); if ((i) < NB) RB[(i) < NB ? (i) : 0] = *(const u32x4*)(bp + (boff + (i) * bstep)); }
; #define LS1_(RA, RB, ST, i) { char* sn_ = lds + (ST) * STAGE; *(u32x4*)(sn_ + wofs + (i) * 32 * LROW) = RA[i]; \
;                               if ((i) < NB) *(u32x4*)(sn_ + STAGE_OP + wofs + (i) * 32 * LROW) = RB[(i) < NB ? (i) : 0]; }
; template <int NJ> DI void gemm_mainloop_reg(const bf16_t* __restrict__ A, int lda, const bf16_t* __restrict__ Bt, int ldb, int K, f32x16 (&acc)[2][NJ], char* lds) {
;     ...
; #pragma unroll
;   for (int i = 0; i < 4; ++i) GL1_(ra0, rb0, i);
;   ap += 128; bp += 128;
; #pragma unroll
;   for (int i = 0; i < 4; ++i) GL1_(ra1, rb1, i);
;   ap += 128; bp += 128;
; #pragma unroll
;   for (int i = 0; i < 4; ++i) LS1_(ra0, rb0, 0, i);
;   __syncthreads();
;   const int nk = K >> 6;
;   for (int kt = 0; kt < nk; kt += 2) {
;     const bool l0 = (kt + 2 < nk), l1 = (kt + 3 < nk);
;     STEP_(0, l0, ra0, rb0, true, ra1, rb1);
;     __syncthreads();
;     STEP_(1, l1, ra1, rb1, l0, ra0, rb0);
;     __syncthreads();
;   }
	ds_read_b128 v[82:85], v135
	ds_read_b128 v[86:89], v0 offset:18432
	ds_read_b128 v[106:109], v135 offset:4608
	s_waitcnt lgkmcnt(1)
	v_mfma_f32_32x32x16_bf16 v[34:49], v[82:85], v[86:89], v[34:49]
	s_waitcnt lgkmcnt(0)
	v_mfma_f32_32x32x16_bf16 v[2:17], v[106:109], v[86:89], v[2:17]
	ds_read_b128 v[86:89], v0 offset:23040
	s_waitcnt lgkmcnt(0)
	v_mfma_f32_32x32x16_bf16 v[50:65], v[82:85], v[86:89], v[50:65]
	ds_read_b128 v[82:85], v135 offset:32
	ds_read_b128 v[110:113], v0 offset:18464
	ds_read_b128 v[114:117], v135 offset:4640
	ds_read_b128 v[118:121], v0 offset:23072
	s_waitcnt vmcnt(7)
	ds_write_b128 v134, v[90:93] offset:36864
	s_waitcnt vmcnt(6)
	ds_write_b128 v134, v[102:105] offset:55296
	v_mfma_f32_32x32x16_bf16 v[18:33], v[106:109], v[86:89], v[18:33]
	s_waitcnt lgkmcnt(4)
	v_mfma_f32_32x32x16_bf16 v[34:49], v[82:85], v[110:113], v[34:49]
	s_waitcnt lgkmcnt(3)
	v_mfma_f32_32x32x16_bf16 v[2:17], v[114:117], v[110:113], v[2:17]
	s_waitcnt lgkmcnt(2)
	v_mfma_f32_32x32x16_bf16 v[50:65], v[82:85], v[118:121], v[50:65]
	ds_read_b128 v[82:85], v135 offset:64
	ds_read_b128 v[86:89], v135 offset:4672
	ds_read_b128 v[90:93], v0 offset:18496
	ds_read_b128 v[102:105], v0 offset:23104
	s_waitcnt vmcnt(5)
	ds_write_b128 v134, v[94:97] offset:41472
	s_waitcnt vmcnt(4)
	ds_write_b128 v134, v[98:101] offset:59904
	v_mfma_f32_32x32x16_bf16 v[18:33], v[114:117], v[118:121], v[18:33]
	s_waitcnt lgkmcnt(3)
	v_mfma_f32_32x32x16_bf16 v[34:49], v[82:85], v[90:93], v[34:49]
	v_mfma_f32_32x32x16_bf16 v[2:17], v[86:89], v[90:93], v[2:17]
	s_waitcnt lgkmcnt(2)
	v_mfma_f32_32x32x16_bf16 v[50:65], v[82:85], v[102:105], v[50:65]
	ds_read_b128 v[82:85], v135 offset:96
	ds_read_b128 v[90:93], v135 offset:4704
	ds_read_b128 v[94:97], v0 offset:18528
	ds_read_b128 v[98:101], v0 offset:23136
	s_waitcnt vmcnt(3)
	ds_write_b128 v134, v[66:69] offset:46080
	s_waitcnt vmcnt(2)
	ds_write_b128 v134, v[70:73] offset:64512
	v_mfma_f32_32x32x16_bf16 v[18:33], v[86:89], v[102:105], v[18:33]
	s_waitcnt lgkmcnt(3)
	v_mfma_f32_32x32x16_bf16 v[34:49], v[82:85], v[94:97], v[34:49]
	s_waitcnt vmcnt(1)
	ds_write_b128 v134, v[74:77] offset:50688
	s_waitcnt vmcnt(0)
	ds_write_b128 v136, v[78:81] offset:13824
	v_mfma_f32_32x32x16_bf16 v[2:17], v[90:93], v[94:97], v[2:17]
	s_waitcnt lgkmcnt(4)
	v_mfma_f32_32x32x16_bf16 v[50:65], v[82:85], v[98:101], v[50:65]
	v_mfma_f32_32x32x16_bf16 v[18:33], v[90:93], v[98:101], v[18:33]
	s_waitcnt lgkmcnt(0)
	s_barrier
	ds_read_b128 v[66:69], v135 offset:36864
	ds_read_b128 v[70:73], v0 offset:55296
	ds_read_b128 v[74:77], v135 offset:41472
	s_waitcnt lgkmcnt(1)
	v_mfma_f32_32x32x16_bf16 v[34:49], v[66:69], v[70:73], v[34:49]
	s_waitcnt lgkmcnt(0)
	v_mfma_f32_32x32x16_bf16 v[2:17], v[74:77], v[70:73], v[2:17]
	ds_read_b128 v[70:73], v0 offset:59904
	s_waitcnt lgkmcnt(0)
	v_mfma_f32_32x32x16_bf16 v[50:65], v[66:69], v[70:73], v[50:65]
	ds_read_b128 v[66:69], v135 offset:36896
	ds_read_b128 v[78:81], v0 offset:55328
	ds_read_b128 v[82:85], v135 offset:41504
	ds_read_b128 v[86:89], v0 offset:59936
	v_mfma_f32_32x32x16_bf16 v[18:33], v[74:77], v[70:73], v[18:33]
	s_waitcnt lgkmcnt(2)
	v_mfma_f32_32x32x16_bf16 v[34:49], v[66:69], v[78:81], v[34:49]
	s_waitcnt lgkmcnt(1)
	v_mfma_f32_32x32x16_bf16 v[2:17], v[82:85], v[78:81], v[2:17]
	s_waitcnt lgkmcnt(0)
	v_mfma_f32_32x32x16_bf16 v[50:65], v[66:69], v[86:89], v[50:65]
	ds_read_b128 v[66:69], v135 offset:36928
	ds_read_b128 v[70:73], v135 offset:41536
	ds_read_b128 v[74:77], v0 offset:55360
	ds_read_b128 v[78:81], v0 offset:59968
	v_mfma_f32_32x32x16_bf16 v[18:33], v[82:85], v[86:89], v[18:33]
	s_waitcnt lgkmcnt(1)
	v_mfma_f32_32x32x16_bf16 v[34:49], v[66:69], v[74:77], v[34:49]
	v_mfma_f32_32x32x16_bf16 v[2:17], v[70:73], v[74:77], v[2:17]
	s_waitcnt lgkmcnt(0)
	v_mfma_f32_32x32x16_bf16 v[50:65], v[66:69], v[78:81], v[50:65]
	ds_read_b128 v[66:69], v135 offset:36960
	ds_read_b128 v[74:77], v135 offset:41568
	ds_read_b128 v[82:85], v0 offset:55392
	ds_read_b128 v[86:89], v0 offset:60000
	v_mfma_f32_32x32x16_bf16 v[18:33], v[70:73], v[78:81], v[18:33]
	s_waitcnt lgkmcnt(1)
	v_mfma_f32_32x32x16_bf16 v[34:49], v[66:69], v[82:85], v[34:49]
	v_mfma_f32_32x32x16_bf16 v[2:17], v[74:77], v[82:85], v[2:17]
	s_waitcnt lgkmcnt(0)
	v_mfma_f32_32x32x16_bf16 v[50:65], v[66:69], v[86:89], v[50:65]
	v_mfma_f32_32x32x16_bf16 v[18:33], v[74:77], v[86:89], v[18:33]
	s_setprio 0
	s_barrier

; #define MFMA(a, b, c) __builtin_amdgcn_mfma_f32_32x32x16_bf16((a), (b), (c), 0, 0, 0)
; template <int DQK, bool BAND, int QT> ...
;     ...
;       f32x16 s[2][QT];
; #pragma unroll
;       for (int a = 0; a < 2; ++a)
; #pragma unroll
;         for (int b = 0; b < QT; ++b)
; #pragma unroll
;           for (int r = 0; r < 16; ++r) s[a][b][r] = 0.f;
; #pragma unroll
;       for (int ks = 0; ks < NKS; ++ks) {
;         const bf16x8 k0 = *(const bf16x8*)(st + k_rd + ks * 32);
;         const bf16x8 k1 = *(const bf16x8*)(st + k_rd + 32 * KROW + ks * 32);
; #pragma unroll
;         for (int qt = 0; qt < QT; ++qt) {
;           s[0][qt] = MFMA(k0, qf[qt][ks], s[0][qt]);
;           s[1][qt] = MFMA(k1, qf[qt][ks], s[1][qt]);
;         }
;       }
;       __builtin_amdgcn_s_setprio(3);
;       bf16x8 pf[QT][4];
;       const float cc = BAND ? 1.0f : scale_log2;
;       const float th = BAND ? 8.0f : 8.0f / scale_log2;
; #pragma unroll
;       for (int qt = 0; qt < QT; ++qt) {
;         if (BAND) {
; #pragma unroll
;           for (int a = 0; a < 2; ++a)
; #pragma unroll
;             for (int r = 0; r < 16; ++r) {
;               const int kidx = kt + 32 * a + (r & 7) + 8 * h + 16 * (r >> 3);
;               const int rel = kidx - (qw0 + qt * 32 + ql);
;               const bool ok = (rel >= -64) && (rel <= 64);
;               const int bi = ok ? rel + 64 : 0;
;               s[a][qt][r] = ok ? fmaf(s[a][qt][r], scale_log2, bias_l[bi]) : -1e30f;
;             }
;         }
;         float mx = s[0][qt][0];
; #pragma unroll
;         for (int r = 1; r < 16; ++r) mx = fmaxf(mx, s[0][qt][r]);
; #pragma unroll
;         for (int r = 0; r < 16; ++r) mx = fmaxf(mx, s[1][qt][r]);
;         mx = fmaxf(mx, __shfl_xor(mx, 32));
;         if (__builtin_amdgcn_ballot_w64(mx > m[qt] + th) != 0) {
;           const float mn = fmaxf(m[qt], mx);
;           const float alpha = __builtin_amdgcn_exp2f((m[qt] - mn) * cc);
;           m[qt] = mn;
;           l[qt] *= alpha;
; #pragma unroll
;           for (int r = 0; r < 16; ++r) { o[0][qt][r] *= alpha; o[1][qt][r] *= alpha; }
;         }
.Lgqa_noload:
	ds_read_b128 v[206:209], v185
	ds_read_b128 v[210:213], v185 offset:4608
	ds_read_b128 v[214:217], v185 offset:32
	ds_read_b128 v[232:235], v185 offset:4640
	s_waitcnt lgkmcnt(3)
	v_mfma_f32_32x32x16_bf16 v[82:97], v[206:209], v[146:149], 0
	v_mfma_f32_32x32x16_bf16 v[114:129], v[206:209], v[162:165], 0
	ds_read_b128 v[206:209], v185 offset:64
	s_waitcnt lgkmcnt(3)
	v_mfma_f32_32x32x16_bf16 v[66:81], v[210:213], v[146:149], 0
	v_mfma_f32_32x32x16_bf16 v[98:113], v[210:213], v[162:165], 0
	ds_read_b128 v[210:213], v185 offset:4672
	s_waitcnt lgkmcnt(3)
	v_mfma_f32_32x32x16_bf16 v[82:97], v[214:217], v[150:153], v[82:97]
	v_mfma_f32_32x32x16_bf16 v[114:129], v[214:217], v[166:169], v[114:129]
	ds_read_b128 v[214:217], v185 offset:96
	s_waitcnt lgkmcnt(3)
	v_mfma_f32_32x32x16_bf16 v[66:81], v[232:235], v[150:153], v[66:81]
	v_mfma_f32_32x32x16_bf16 v[98:113], v[232:235], v[166:169], v[98:113]
	ds_read_b128 v[232:235], v185 offset:4704
	s_waitcnt lgkmcnt(3)
	v_mfma_f32_32x32x16_bf16 v[82:97], v[206:209], v[154:157], v[82:97]
	v_mfma_f32_32x32x16_bf16 v[114:129], v[206:209], v[170:173], v[114:129]
	s_waitcnt lgkmcnt(2)
	v_mfma_f32_32x32x16_bf16 v[66:81], v[210:213], v[154:157], v[66:81]
	v_mfma_f32_32x32x16_bf16 v[98:113], v[210:213], v[170:173], v[98:113]
	s_waitcnt lgkmcnt(1)
	v_mfma_f32_32x32x16_bf16 v[82:97], v[214:217], v[158:161], v[82:97]
	v_mfma_f32_32x32x16_bf16 v[114:129], v[214:217], v[174:177], v[114:129]
	s_waitcnt lgkmcnt(0)
	v_mfma_f32_32x32x16_bf16 v[66:81], v[232:235], v[158:161], v[66:81]
	v_mfma_f32_32x32x16_bf16 v[98:113], v[232:235], v[174:177], v[98:113]
	s_waitcnt vmcnt(0)
	s_nop 6
	s_setprio 0
	v_max_f32_e32 v203, v82, v83
	v_max_f32_e32 v253, v114, v115
	v_max3_f32 v203, v203, v84, v85
	v_max3_f32 v253, v253, v116, v117
	v_max3_f32 v203, v203, v86, v87
	v_max3_f32 v253, v253, v118, v119
	v_max3_f32 v203, v203, v88, v89
	v_max3_f32 v253, v253, v120, v121
	v_max3_f32 v203, v203, v90, v91
	v_max3_f32 v253, v253, v122, v123
	v_max3_f32 v203, v203, v92, v93
	v_max3_f32 v253, v253, v124, v125
	v_max3_f32 v203, v203, v94, v95
	v_max3_f32 v253, v253, v126, v127
	v_max3_f32 v203, v203, v96, v97
	v_max3_f32 v253, v253, v128, v129
	v_max3_f32 v203, v203, v66, v67
	v_max3_f32 v253, v253, v98, v99
	v_max3_f32 v203, v203, v68, v69
	v_max3_f32 v253, v253, v100, v101
	v_max3_f32 v203, v203, v70, v71
	v_max3_f32 v253, v253, v102, v103
	v_max3_f32 v203, v203, v72, v73
	v_max3_f32 v253, v253, v104, v105
	v_max3_f32 v203, v203, v74, v75
	v_max3_f32 v253, v253, v106, v107
	v_max3_f32 v203, v203, v76, v77
	v_max3_f32 v253, v253, v108, v109
	v_max3_f32 v203, v203, v78, v79
	v_max3_f32 v253, v253, v110, v111
	v_max3_f32 v203, v203, v80, v81
	v_max3_f32 v253, v253, v112, v113
	v_add_f32_e32 v254, 0x42317218, v197
	v_cmp_gt_f32_e32 vcc, v203, v254
	s_cbranch_vccz .Lgqa_nr0
	ds_bpermute_b32 v254, v179, v203
	s_waitcnt lgkmcnt(0)
	v_max_f32_e32 v254, v254, v254
	v_max_f32_e32 v203, v203, v254
	v_max_f32_e32 v254, v197, v197
	v_max_f32_e32 v203, v254, v203
	v_sub_f32_e32 v197, v197, v203
	v_mul_f32_e32 v197, 0x3e38aa3b, v197
	v_exp_f32_e32 v254, v197
	v_mov_b32_e32 v197, v203
	v_pk_mul_f32 v[64:65], v[64:65], v[254:255] op_sel_hi:[1,0]
	v_pk_mul_f32 v[62:63], v[62:63], v[254:255] op_sel_hi:[1,0]
	v_pk_mul_f32 v[60:61], v[60:61], v[254:255] op_sel_hi:[1,0]
	v_pk_mul_f32 v[58:59], v[58:59], v[254:255] op_sel_hi:[1,0]
	v_pk_mul_f32 v[56:57], v[56:57], v[254:255] op_sel_hi:[1,0]
	v_pk_mul_f32 v[54:55], v[54:55], v[254:255] op_sel_hi:[1,0]
	v_pk_mul_f32 v[52:53], v[52:53], v[254:255] op_sel_hi:[1,0]
	v_pk_mul_f32 v[50:51], v[50:51], v[254:255] op_sel_hi:[1,0]
	v_pk_mul_f32 v[48:49], v[48:49], v[254:255] op_sel_hi:[1,0]
	v_pk_mul_f32 v[46:47], v[46:47], v[254:255] op_sel_hi:[1,0]
	v_pk_mul_f32 v[44:45], v[44:45], v[254:255] op_sel_hi:[1,0]
	v_pk_mul_f32 v[42:43], v[42:43], v[254:255] op_sel_hi:[1,0]
	v_pk_mul_f32 v[40:41], v[40:41], v[254:255] op_sel_hi:[1,0]
	v_pk_mul_f32 v[38:39], v[38:39], v[254:255] op_sel_hi:[1,0]
	v_pk_mul_f32 v[36:37], v[36:37], v[254:255] op_sel_hi:[1,0]
	v_pk_mul_f32 v[34:35], v[34:35], v[254:255] op_sel_hi:[1,0]
	v_pk_mul_f32 v[240:241], v[240:241], v[254:255] op_sel_hi:[1,0]
	v_pk_mul_f32 v[242:243], v[242:243], v[254:255] op_sel_hi:[1,0]

; #define MFMA(a, b, c) __builtin_amdgcn_mfma_f32_32x32x16_bf16((a), (b), (c), 0, 0, 0)
; DI unsigned pk2(float a, float b) { f32x2 v = {a, b}; bf16x2_t r = __builtin_convertvector(v, bf16x2_t); return __builtin_bit_cast(unsigned, r); }
; template <int DQK, bool BAND, int QT> ...
;     ...
;         const float mc = -m[qt] * cc;
;         float ls = 0.f;
; #pragma unroll
;         for (int a = 0; a < 2; ++a) {
; #pragma unroll
;           for (int r = 0; r < 16; ++r) { const float pv = __builtin_amdgcn_exp2f(fmaf(s[a][qt][r], cc, mc)); s[a][qt][r] = pv; ls += pv; }
; #pragma unroll
;           for (int s2 = 0; s2 < 2; ++s2) {
;             u32x4 pk;
;             pk.x = pk2(s[a][qt][8 * s2 + 0], s[a][qt][8 * s2 + 1]);
;             pk.y = pk2(s[a][qt][8 * s2 + 2], s[a][qt][8 * s2 + 3]);
;             pk.z = pk2(s[a][qt][8 * s2 + 4], s[a][qt][8 * s2 + 5]);
;             pk.w = pk2(s[a][qt][8 * s2 + 6], s[a][qt][8 * s2 + 7]);
;             pf[qt][a * 2 + s2] = __builtin_bit_cast(bf16x8, pk);
;           }
;         }
;         l[qt] += ls;
;       }
;       __builtin_amdgcn_s_setprio(0);
;       if (more) lstore(lds + ((it + 1) & 1) * ST);
; #pragma unroll
;       for (int ks = 0; ks < 4; ++ks) {
;         const bf16x8 v0 = *(const bf16x8*)(st + v_rd + ks * 32);
;         const bf16x8 v1 = *(const bf16x8*)(st + v_rd + 32 * LROW + ks * 32);
; #pragma unroll
;         for (int qt = 0; qt < QT; ++qt) {
;           o[0][qt] = MFMA(v0, pf[qt][ks], o[0][qt]);
;           o[1][qt] = MFMA(v1, pf[qt][ks], o[1][qt]);
.Lgqa_nostage:
	v_mul_f32_e32 v254, 0xbe38aa3b, v197
	v_mul_f32_e32 v255, 0xbe38aa3b, v202
	v_fmamk_f32 v82, v82, 0x3e38aa3b, v254
	v_fmamk_f32 v114, v114, 0x3e38aa3b, v255
	v_fmamk_f32 v83, v83, 0x3e38aa3b, v254
	v_fmamk_f32 v115, v115, 0x3e38aa3b, v255
	v_fmamk_f32 v84, v84, 0x3e38aa3b, v254
	v_fmamk_f32 v116, v116, 0x3e38aa3b, v255
	v_fmamk_f32 v85, v85, 0x3e38aa3b, v254
	v_fmamk_f32 v117, v117, 0x3e38aa3b, v255
	v_fmamk_f32 v86, v86, 0x3e38aa3b, v254
	v_fmamk_f32 v118, v118, 0x3e38aa3b, v255
	v_fmamk_f32 v87, v87, 0x3e38aa3b, v254
	v_fmamk_f32 v119, v119, 0x3e38aa3b, v255
	v_fmamk_f32 v88, v88, 0x3e38aa3b, v254
	v_fmamk_f32 v120, v120, 0x3e38aa3b, v255
	v_fmamk_f32 v89, v89, 0x3e38aa3b, v254
	v_fmamk_f32 v121, v121, 0x3e38aa3b, v255
	v_exp_f32_e32 v82, v82
	v_exp_f32_e32 v114, v114
	v_exp_f32_e32 v83, v83
	v_exp_f32_e32 v115, v115
	v_exp_f32_e32 v84, v84
	v_exp_f32_e32 v116, v116
	v_exp_f32_e32 v85, v85
	v_exp_f32_e32 v117, v117
	v_exp_f32_e32 v86, v86
	v_exp_f32_e32 v118, v118
	v_exp_f32_e32 v87, v87
	v_exp_f32_e32 v119, v119
	v_exp_f32_e32 v88, v88
	v_exp_f32_e32 v120, v120
	v_exp_f32_e32 v89, v89
	v_exp_f32_e32 v121, v121
	v_fmamk_f32 v90, v90, 0x3e38aa3b, v254
	v_fmamk_f32 v122, v122, 0x3e38aa3b, v255
	v_fmamk_f32 v91, v91, 0x3e38aa3b, v254
	v_fmamk_f32 v123, v123, 0x3e38aa3b, v255
	v_fmamk_f32 v92, v92, 0x3e38aa3b, v254
	v_fmamk_f32 v124, v124, 0x3e38aa3b, v255
	v_fmamk_f32 v93, v93, 0x3e38aa3b, v254
	v_fmamk_f32 v125, v125, 0x3e38aa3b, v255
	v_fmamk_f32 v94, v94, 0x3e38aa3b, v254
	v_fmamk_f32 v126, v126, 0x3e38aa3b, v255
	v_fmamk_f32 v95, v95, 0x3e38aa3b, v254
	v_fmamk_f32 v127, v127, 0x3e38aa3b, v255
	v_fmamk_f32 v96, v96, 0x3e38aa3b, v254
	v_fmamk_f32 v128, v128, 0x3e38aa3b, v255
	v_fmamk_f32 v97, v97, 0x3e38aa3b, v254
	v_fmamk_f32 v129, v129, 0x3e38aa3b, v255
	v_exp_f32_e32 v90, v90
	v_exp_f32_e32 v122, v122
	v_exp_f32_e32 v91, v91
	v_exp_f32_e32 v123, v123
	v_exp_f32_e32 v92, v92
	v_exp_f32_e32 v124, v124
	v_exp_f32_e32 v93, v93
	v_exp_f32_e32 v125, v125
	v_exp_f32_e32 v94, v94
	v_exp_f32_e32 v126, v126
	v_exp_f32_e32 v95, v95
	v_exp_f32_e32 v127, v127
	v_exp_f32_e32 v96, v96
	v_exp_f32_e32 v128, v128
	v_exp_f32_e32 v97, v97
	v_exp_f32_e32 v129, v129
	v_cvt_pk_bf16_f32 v82, v82, v83
	v_cvt_pk_bf16_f32 v114, v114, v115
	v_cvt_pk_bf16_f32 v83, v84, v85
	v_cvt_pk_bf16_f32 v115, v116, v117
	v_cvt_pk_bf16_f32 v84, v86, v87
	v_cvt_pk_bf16_f32 v116, v118, v119
	v_cvt_pk_bf16_f32 v85, v88, v89
	v_cvt_pk_bf16_f32 v117, v120, v121
	v_fmamk_f32 v66, v66, 0x3e38aa3b, v254
	v_fmamk_f32 v98, v98, 0x3e38aa3b, v255
	v_fmamk_f32 v67, v67, 0x3e38aa3b, v254
	v_fmamk_f32 v99, v99, 0x3e38aa3b, v255
	v_fmamk_f32 v68, v68, 0x3e38aa3b, v254
	v_fmamk_f32 v100, v100, 0x3e38aa3b, v255
	v_fmamk_f32 v69, v69, 0x3e38aa3b, v254
	v_fmamk_f32 v101, v101, 0x3e38aa3b, v255
	v_fmamk_f32 v70, v70, 0x3e38aa3b, v254
	v_fmamk_f32 v102, v102, 0x3e38aa3b, v255
	v_fmamk_f32 v71, v71, 0x3e38aa3b, v254
	v_fmamk_f32 v103, v103, 0x3e38aa3b, v255
	v_fmamk_f32 v72, v72, 0x3e38aa3b, v254
	v_fmamk_f32 v104, v104, 0x3e38aa3b, v255
	v_fmamk_f32 v73, v73, 0x3e38aa3b, v254
	v_fmamk_f32 v105, v105, 0x3e38aa3b, v255
	v_exp_f32_e32 v66, v66
	v_exp_f32_e32 v98, v98
	v_exp_f32_e32 v67, v67
	v_exp_f32_e32 v99, v99
	v_exp_f32_e32 v68, v68
	v_exp_f32_e32 v100, v100
	v_exp_f32_e32 v69, v69
	v_exp_f32_e32 v101, v101
	v_exp_f32_e32 v70, v70
	v_exp_f32_e32 v102, v102
	v_exp_f32_e32 v71, v71
	v_exp_f32_e32 v103, v103
	v_exp_f32_e32 v72, v72
	v_exp_f32_e32 v104, v104
	v_exp_f32_e32 v73, v73
	v_exp_f32_e32 v105, v105
	v_cvt_pk_bf16_f32 v90, v90, v91
	v_cvt_pk_bf16_f32 v122, v122, v123
	v_cvt_pk_bf16_f32 v91, v92, v93
	v_cvt_pk_bf16_f32 v123, v124, v125
	v_cvt_pk_bf16_f32 v92, v94, v95
	v_cvt_pk_bf16_f32 v124, v126, v127
	v_cvt_pk_bf16_f32 v93, v96, v97
	v_cvt_pk_bf16_f32 v125, v128, v129
	v_fmamk_f32 v74, v74, 0x3e38aa3b, v254
	v_fmamk_f32 v106, v106, 0x3e38aa3b, v255
	v_fmamk_f32 v75, v75, 0x3e38aa3b, v254
	v_fmamk_f32 v107, v107, 0x3e38aa3b, v255
	v_fmamk_f32 v76, v76, 0x3e38aa3b, v254
	v_fmamk_f32 v108, v108, 0x3e38aa3b, v255
	v_fmamk_f32 v77, v77, 0x3e38aa3b, v254
	v_fmamk_f32 v109, v109, 0x3e38aa3b, v255
	v_fmamk_f32 v78, v78, 0x3e38aa3b, v254
	v_fmamk_f32 v110, v110, 0x3e38aa3b, v255
	v_fmamk_f32 v79, v79, 0x3e38aa3b, v254
	v_fmamk_f32 v111, v111, 0x3e38aa3b, v255
	v_fmamk_f32 v80, v80, 0x3e38aa3b, v254
	v_fmamk_f32 v112, v112, 0x3e38aa3b, v255
	v_fmamk_f32 v81, v81, 0x3e38aa3b, v254
	v_fmamk_f32 v113, v113, 0x3e38aa3b, v255
	v_exp_f32_e32 v74, v74
	v_exp_f32_e32 v106, v106
	v_exp_f32_e32 v75, v75
	v_exp_f32_e32 v107, v107
	v_exp_f32_e32 v76, v76
	v_exp_f32_e32 v108, v108
	v_exp_f32_e32 v77, v77
	v_exp_f32_e32 v109, v109
	v_exp_f32_e32 v78, v78
	v_exp_f32_e32 v110, v110
	v_exp_f32_e32 v79, v79
	v_exp_f32_e32 v111, v111
	v_exp_f32_e32 v80, v80
	v_exp_f32_e32 v112, v112
	v_exp_f32_e32 v81, v81
	v_exp_f32_e32 v113, v113
	v_cvt_pk_bf16_f32 v66, v66, v67
	v_cvt_pk_bf16_f32 v98, v98, v99
	v_cvt_pk_bf16_f32 v67, v68, v69
	v_cvt_pk_bf16_f32 v99, v100, v101
	v_cvt_pk_bf16_f32 v68, v70, v71
	v_cvt_pk_bf16_f32 v100, v102, v103
	v_cvt_pk_bf16_f32 v69, v72, v73
	v_cvt_pk_bf16_f32 v101, v104, v105
	v_cvt_pk_bf16_f32 v74, v74, v75
	v_cvt_pk_bf16_f32 v106, v106, v107
	v_cvt_pk_bf16_f32 v75, v76, v77
	v_cvt_pk_bf16_f32 v107, v108, v109
	v_cvt_pk_bf16_f32 v76, v78, v79
	v_cvt_pk_bf16_f32 v108, v110, v111
	v_cvt_pk_bf16_f32 v77, v80, v81
	v_cvt_pk_bf16_f32 v109, v112, v113
	s_setprio 2
	ds_read_b128 v[86:89], v183 offset:9216
	ds_read_b128 v[94:97], v183 offset:13824
	ds_read_b128 v[70:73], v183 offset:9248
	ds_read_b128 v[78:81], v183 offset:13856
	ds_read_b128 v[118:121], v183 offset:9280
	ds_read_b128 v[126:129], v183 offset:13888
	ds_read_b128 v[102:105], v183 offset:9312
	ds_read_b128 v[110:113], v183 offset:13920
	s_waitcnt lgkmcnt(7)
; #define MFMA(a, b, c) __builtin_amdgcn_mfma_f32_32x32x16_bf16((a), (b), (c), 0, 0, 0)
; template <int DQK, bool BAND, int QT> ...
;     ...
; #pragma unroll
;       for (int ks = 0; ks < 4; ++ks) {
;         const bf16x8 v0 = *(const bf16x8*)(st + v_rd + ks * 32);
;         const bf16x8 v1 = *(const bf16x8*)(st + v_rd + 32 * LROW + ks * 32);
; #pragma unroll
;         for (int qt = 0; qt < QT; ++qt) {
;           o[0][qt] = MFMA(v0, pf[qt][ks], o[0][qt]);
;           o[1][qt] = MFMA(v1, pf[qt][ks], o[1][qt]);
;         }
;       }
;     } else {
;       if (more) lstore(lds + ((it + 1) & 1) * ST);
;     }
;     __syncthreads();
;   }
; #pragma unroll
;   for (int qt = 0; qt < QT; ++qt) {
;     const float lt = l[qt] + __shfl_xor(l[qt], 32);
	v_mfma_f32_32x32x16_bf16 v[50:65], v[86:89], v[82:85], v[50:65]
	v_mfma_f32_32x32x16_bf16 v[18:33], v[86:89], v[114:117], v[18:33]
	s_waitcnt lgkmcnt(6)
	v_mfma_f32_32x32x16_bf16 v[34:49], v[94:97], v[82:85], v[34:49]
	v_mfma_f32_32x32x16_bf16 v[2:17], v[94:97], v[114:117], v[2:17]
	v_mfma_f32_16x16x32_bf16 v[240:243], v[244:247], v[82:85], v[240:243]
	v_mfma_f32_16x16x32_bf16 v[236:239], v[244:247], v[114:117], v[236:239]
	v_lshl_add_u64 v[192:193], v[192:193], 0, s[88:89]
	v_lshl_add_u64 v[194:195], v[194:195], 0, s[88:89]
	v_lshl_add_u64 v[188:189], v[188:189], 0, s[76:77]
	v_lshl_add_u64 v[190:191], v[190:191], 0, s[76:77]
	s_waitcnt lgkmcnt(5)
	v_mfma_f32_32x32x16_bf16 v[50:65], v[70:73], v[90:93], v[50:65]
	v_mfma_f32_32x32x16_bf16 v[18:33], v[70:73], v[122:125], v[18:33]
	s_waitcnt lgkmcnt(4)
	v_mfma_f32_32x32x16_bf16 v[34:49], v[78:81], v[90:93], v[34:49]
	v_mfma_f32_32x32x16_bf16 v[2:17], v[78:81], v[122:125], v[2:17]
	v_mfma_f32_16x16x32_bf16 v[240:243], v[244:247], v[90:93], v[240:243]
	v_mfma_f32_16x16x32_bf16 v[236:239], v[244:247], v[122:125], v[236:239]
	s_waitcnt lgkmcnt(3)
	v_mfma_f32_32x32x16_bf16 v[50:65], v[118:121], v[66:69], v[50:65]
	v_mfma_f32_32x32x16_bf16 v[18:33], v[118:121], v[98:101], v[18:33]
	s_waitcnt lgkmcnt(2)
	v_mfma_f32_32x32x16_bf16 v[34:49], v[126:129], v[66:69], v[34:49]
	v_mfma_f32_32x32x16_bf16 v[2:17], v[126:129], v[98:101], v[2:17]
	v_mfma_f32_16x16x32_bf16 v[240:243], v[244:247], v[66:69], v[240:243]
	v_mfma_f32_16x16x32_bf16 v[236:239], v[244:247], v[98:101], v[236:239]
	s_bitcmp1_b32 s1, 0
	s_cselect_b32 s7, -1, 1
	s_mulk_i32 s7, 0x4800
	v_add_u32_e32 v185, s7, v185
	v_add_u32_e32 v183, s7, v183
	s_add_i32 s1, s1, 1
	s_add_i32 s6, s6, 64
	s_waitcnt lgkmcnt(0)
	s_barrier
	v_mfma_f32_32x32x16_bf16 v[50:65], v[102:105], v[74:77], v[50:65]
	v_mfma_f32_32x32x16_bf16 v[18:33], v[102:105], v[106:109], v[18:33]
	v_mfma_f32_32x32x16_bf16 v[34:49], v[110:113], v[74:77], v[34:49]
	v_mfma_f32_32x32x16_bf16 v[2:17], v[110:113], v[106:109], v[2:17]
	v_mfma_f32_16x16x32_bf16 v[240:243], v[244:247], v[74:77], v[240:243]
	v_mfma_f32_16x16x32_bf16 v[236:239], v[244:247], v[106:109], v[236:239]
	s_cmp_lg_u32 s21, s1
	s_cbranch_scc1 .Lgqa_top
	s_nop 7
	v_mbcnt_lo_u32_b32 v254, -1, 0
	v_mbcnt_hi_u32_b32 v254, -1, v254
	v_and_b32_e32 v255, 15, v254
	v_lshlrev_b32_e32 v255, 2, v255
	ds_bpermute_b32 v203, v255, v240
	ds_bpermute_b32 v253, v255, v241
	s_waitcnt lgkmcnt(0)
	v_cmp_gt_u32_e32 vcc, 16, v254
	s_nop 1
	v_cndmask_b32_e32 v187, v253, v203, vcc
	v_cmp_gt_u32_e32 vcc, 32, v254
	s_nop 1
	v_cndmask_b32_e32 v187, 0, v187, vcc
	ds_bpermute_b32 v203, v255, v236
	ds_bpermute_b32 v253, v255, v237
	s_waitcnt lgkmcnt(0)
	v_cmp_gt_u32_e32 vcc, 16, v254
	s_nop 1
	v_cndmask_b32_e32 v181, v253, v203, vcc
	v_cmp_gt_u32_e32 vcc, 32, v254
	s_nop 1
	v_cndmask_b32_e32 v181, 0, v181, vcc

; #define MFMA(a, b, c) __builtin_amdgcn_mfma_f32_32x32x16_bf16((a), (b), (c), 0, 0, 0)
; template <int DQK, bool BAND, int QT> ...
;     ...
;       f32x16 s[2][QT];
; #pragma unroll
;       for (int a = 0; a < 2; ++a)
; #pragma unroll
;         for (int b = 0; b < QT; ++b)
; #pragma unroll
;           for (int r = 0; r < 16; ++r) s[a][b][r] = 0.f;
; #pragma unroll
;       for (int ks = 0; ks < NKS; ++ks) {
;         const bf16x8 k0 = *(const bf16x8*)(st + k_rd + ks * 32);
;         const bf16x8 k1 = *(const bf16x8*)(st + k_rd + 32 * KROW + ks * 32);
; #pragma unroll
;         for (int qt = 0; qt < QT; ++qt) {
;           s[0][qt] = MFMA(k0, qf[qt][ks], s[0][qt]);
;           s[1][qt] = MFMA(k1, qf[qt][ks], s[1][qt]);
;         }
;       }
;       __builtin_amdgcn_s_setprio(3);
;       bf16x8 pf[QT][4];
;       const float cc = BAND ? 1.0f : scale_log2;
;       const float th = BAND ? 8.0f : 8.0f / scale_log2;
; #pragma unroll
;       for (int qt = 0; qt < QT; ++qt) {
;         if (BAND) {
; #pragma unroll
;           for (int a = 0; a < 2; ++a)
; #pragma unroll
;             for (int r = 0; r < 16; ++r) {
;               const int kidx = kt + 32 * a + (r & 7) + 8 * h + 16 * (r >> 3);
;               const int rel = kidx - (qw0 + qt * 32 + ql);
;               const bool ok = (rel >= -64) && (rel <= 64);
;               const int bi = ok ? rel + 64 : 0;
;               s[a][qt][r] = ok ? fmaf(s[a][qt][r], scale_log2, bias_l[bi]) : -1e30f;
;             }
;         }
;         float mx = s[0][qt][0];
; #pragma unroll
;         for (int r = 1; r < 16; ++r) mx = fmaxf(mx, s[0][qt][r]);
; #pragma unroll
;         for (int r = 0; r < 16; ++r) mx = fmaxf(mx, s[1][qt][r]);
;         mx = fmaxf(mx, __shfl_xor(mx, 32));
;         if (__builtin_amdgcn_ballot_w64(mx > m[qt] + th) != 0) {
;           const float mn = fmaxf(m[qt], mx);
;           const float alpha = __builtin_amdgcn_exp2f((m[qt] - mn) * cc);
;           m[qt] = mn;
;           l[qt] *= alpha;
; #pragma unroll
;           for (int r = 0; r < 16; ++r) { o[0][qt][r] *= alpha; o[1][qt][r] *= alpha; }
;         }
.Lmla_noload:
	ds_read_b128 v[102:105], v235
	ds_read_b128 v[98:101], v235 offset:6656
	ds_read_b128 v[240:243], v235 offset:32
	ds_read_b128 v[244:247], v235 offset:6688
	s_waitcnt lgkmcnt(3)
	v_mfma_f32_32x32x16_bf16 v[82:97], v[102:105], v[142:145], 0
	v_mfma_f32_32x32x16_bf16 v[114:129], v[102:105], v[174:177], 0
	s_waitcnt lgkmcnt(2)
	v_mfma_f32_32x32x16_bf16 v[66:81], v[98:101], v[142:145], 0
	v_mfma_f32_32x32x16_bf16 v[98:113], v[98:101], v[174:177], 0
	s_waitcnt lgkmcnt(1)
	v_mfma_f32_32x32x16_bf16 v[82:97], v[240:243], v[150:153], v[82:97]
	v_mfma_f32_32x32x16_bf16 v[114:129], v[240:243], v[178:181], v[114:129]
	ds_read_b128 v[240:243], v235 offset:64
	s_waitcnt lgkmcnt(1)
	v_mfma_f32_32x32x16_bf16 v[66:81], v[244:247], v[150:153], v[66:81]
	v_mfma_f32_32x32x16_bf16 v[98:113], v[244:247], v[178:181], v[98:113]
	ds_read_b128 v[244:247], v235 offset:6720
	s_waitcnt lgkmcnt(1)
	v_mfma_f32_32x32x16_bf16 v[82:97], v[240:243], v[154:157], v[82:97]
	v_mfma_f32_32x32x16_bf16 v[114:129], v[240:243], v[182:185], v[114:129]
	ds_read_b128 v[240:243], v235 offset:96
	s_waitcnt lgkmcnt(1)
	v_mfma_f32_32x32x16_bf16 v[66:81], v[244:247], v[154:157], v[66:81]
	v_mfma_f32_32x32x16_bf16 v[98:113], v[244:247], v[182:185], v[98:113]
	ds_read_b128 v[244:247], v235 offset:6752
	s_waitcnt lgkmcnt(1)
	v_mfma_f32_32x32x16_bf16 v[82:97], v[240:243], v[158:161], v[82:97]
	v_mfma_f32_32x32x16_bf16 v[114:129], v[240:243], v[186:189], v[114:129]
	ds_read_b128 v[240:243], v235 offset:128
	s_waitcnt lgkmcnt(1)
	v_mfma_f32_32x32x16_bf16 v[66:81], v[244:247], v[158:161], v[66:81]
	v_mfma_f32_32x32x16_bf16 v[98:113], v[244:247], v[186:189], v[98:113]
	ds_read_b128 v[244:247], v235 offset:6784
	s_waitcnt lgkmcnt(1)
	v_mfma_f32_32x32x16_bf16 v[82:97], v[240:243], v[162:165], v[82:97]
	v_mfma_f32_32x32x16_bf16 v[114:129], v[240:243], v[190:193], v[114:129]
	ds_read_b128 v[240:243], v235 offset:160
	s_waitcnt lgkmcnt(1)
	v_mfma_f32_32x32x16_bf16 v[66:81], v[244:247], v[162:165], v[66:81]
	v_mfma_f32_32x32x16_bf16 v[98:113], v[244:247], v[190:193], v[98:113]
	ds_read_b128 v[244:247], v235 offset:6816
	s_waitcnt lgkmcnt(1)
	v_mfma_f32_32x32x16_bf16 v[82:97], v[240:243], v[166:169], v[82:97]
	v_mfma_f32_32x32x16_bf16 v[114:129], v[240:243], v[194:197], v[114:129]
	s_waitcnt lgkmcnt(0)
	v_mfma_f32_32x32x16_bf16 v[66:81], v[244:247], v[166:169], v[66:81]
	v_mfma_f32_32x32x16_bf16 v[98:113], v[244:247], v[194:197], v[98:113]
	s_waitcnt vmcnt(0)
	s_nop 6
	s_setprio 0
	v_max_f32_e32 v239, v82, v83
	v_max_f32_e32 v253, v114, v115
	v_max3_f32 v239, v239, v84, v85
	v_max3_f32 v253, v253, v116, v117
	v_max3_f32 v239, v239, v86, v87
	v_max3_f32 v253, v253, v118, v119
	v_max3_f32 v239, v239, v88, v89
	v_max3_f32 v253, v253, v120, v121
	v_max3_f32 v239, v239, v90, v91
	v_max3_f32 v253, v253, v122, v123
	v_max3_f32 v239, v239, v92, v93
	v_max3_f32 v253, v253, v124, v125
	v_max3_f32 v239, v239, v94, v95
	v_max3_f32 v253, v253, v126, v127
	v_max3_f32 v239, v239, v96, v97
	v_max3_f32 v253, v253, v128, v129
	v_max3_f32 v239, v239, v66, v67
	v_max3_f32 v253, v253, v98, v99
	v_max3_f32 v239, v239, v68, v69
	v_max3_f32 v253, v253, v100, v101
	v_max3_f32 v239, v239, v70, v71
	v_max3_f32 v253, v253, v102, v103
	v_max3_f32 v239, v239, v72, v73
	v_max3_f32 v253, v253, v104, v105
	v_max3_f32 v239, v239, v74, v75
	v_max3_f32 v253, v253, v106, v107
	v_max3_f32 v239, v239, v76, v77
	v_max3_f32 v253, v253, v108, v109
	v_max3_f32 v239, v239, v78, v79
	v_max3_f32 v253, v253, v110, v111
	v_max3_f32 v239, v239, v80, v81
	v_max3_f32 v253, v253, v112, v113
	v_add_f32_e32 v254, 0x4259535f, v237
	v_cmp_gt_f32_e32 vcc, v239, v254
	s_cbranch_vccz .Lmla_nr0
	ds_bpermute_b32 v254, v203, v239
	s_waitcnt lgkmcnt(0)
	v_max_f32_e32 v254, v254, v254
	v_max_f32_e32 v239, v239, v254
	v_max_f32_e32 v254, v237, v237
	v_max_f32_e32 v239, v254, v239
	v_sub_f32_e32 v237, v237, v239
	v_mul_f32_e32 v237, 0x3e16c740, v237
	v_exp_f32_e32 v254, v237
	v_mov_b32_e32 v237, v239
	v_pk_mul_f32 v[64:65], v[64:65], v[254:255] op_sel_hi:[1,0]
	v_pk_mul_f32 v[62:63], v[62:63], v[254:255] op_sel_hi:[1,0]
	v_pk_mul_f32 v[60:61], v[60:61], v[254:255] op_sel_hi:[1,0]
	v_pk_mul_f32 v[58:59], v[58:59], v[254:255] op_sel_hi:[1,0]
	v_pk_mul_f32 v[56:57], v[56:57], v[254:255] op_sel_hi:[1,0]
	v_pk_mul_f32 v[54:55], v[54:55], v[254:255] op_sel_hi:[1,0]
	v_pk_mul_f32 v[52:53], v[52:53], v[254:255] op_sel_hi:[1,0]
	v_pk_mul_f32 v[50:51], v[50:51], v[254:255] op_sel_hi:[1,0]
	v_pk_mul_f32 v[48:49], v[48:49], v[254:255] op_sel_hi:[1,0]
	v_pk_mul_f32 v[46:47], v[46:47], v[254:255] op_sel_hi:[1,0]
	v_pk_mul_f32 v[44:45], v[44:45], v[254:255] op_sel_hi:[1,0]
	v_pk_mul_f32 v[42:43], v[42:43], v[254:255] op_sel_hi:[1,0]
	v_pk_mul_f32 v[40:41], v[40:41], v[254:255] op_sel_hi:[1,0]
	v_pk_mul_f32 v[38:39], v[38:39], v[254:255] op_sel_hi:[1,0]
	v_pk_mul_f32 v[36:37], v[36:37], v[254:255] op_sel_hi:[1,0]
	v_pk_mul_f32 v[34:35], v[34:35], v[254:255] op_sel_hi:[1,0]
	v_mul_f32_e32 v236, v236, v254

; DI unsigned pk2(float a, float b) { f32x2 v = {a, b}; bf16x2_t r = __builtin_convertvector(v, bf16x2_t); return __builtin_bit_cast(unsigned, r); }
; template <int DQK, bool BAND, int QT> ...
;     ...
;         const float mc = -m[qt] * cc;
;         float ls = 0.f;
; #pragma unroll
;         for (int a = 0; a < 2; ++a) {
; #pragma unroll
;           for (int r = 0; r < 16; ++r) { const float pv = __builtin_amdgcn_exp2f(fmaf(s[a][qt][r], cc, mc)); s[a][qt][r] = pv; ls += pv; }
; #pragma unroll
;           for (int s2 = 0; s2 < 2; ++s2) {
;             u32x4 pk;
;             pk.x = pk2(s[a][qt][8 * s2 + 0], s[a][qt][8 * s2 + 1]);
;             pk.y = pk2(s[a][qt][8 * s2 + 2], s[a][qt][8 * s2 + 3]);
;             pk.z = pk2(s[a][qt][8 * s2 + 4], s[a][qt][8 * s2 + 5]);
;             pk.w = pk2(s[a][qt][8 * s2 + 6], s[a][qt][8 * s2 + 7]);
;             pf[qt][a * 2 + s2] = __builtin_bit_cast(bf16x8, pk);
;           }
;         }
;         l[qt] += ls;
.Lmla_nostage:
	v_mul_f32_e32 v254, 0xbe16c740, v237
	v_mul_f32_e32 v255, 0xbe16c740, v238
	v_fmamk_f32 v82, v82, 0x3e16c740, v254
	v_fmamk_f32 v114, v114, 0x3e16c740, v255
	v_fmamk_f32 v83, v83, 0x3e16c740, v254
	v_fmamk_f32 v115, v115, 0x3e16c740, v255
	v_fmamk_f32 v84, v84, 0x3e16c740, v254
	v_fmamk_f32 v116, v116, 0x3e16c740, v255
	v_fmamk_f32 v85, v85, 0x3e16c740, v254
	v_fmamk_f32 v117, v117, 0x3e16c740, v255
	v_fmamk_f32 v86, v86, 0x3e16c740, v254
	v_fmamk_f32 v118, v118, 0x3e16c740, v255
	v_fmamk_f32 v87, v87, 0x3e16c740, v254
	v_fmamk_f32 v119, v119, 0x3e16c740, v255
	v_fmamk_f32 v88, v88, 0x3e16c740, v254
	v_fmamk_f32 v120, v120, 0x3e16c740, v255
	v_fmamk_f32 v89, v89, 0x3e16c740, v254
	v_fmamk_f32 v121, v121, 0x3e16c740, v255
	v_exp_f32_e32 v82, v82
	v_exp_f32_e32 v114, v114
	v_exp_f32_e32 v83, v83
	v_exp_f32_e32 v115, v115
	v_exp_f32_e32 v84, v84
	v_exp_f32_e32 v116, v116
	v_exp_f32_e32 v85, v85
	v_exp_f32_e32 v117, v117
	v_exp_f32_e32 v86, v86
	v_exp_f32_e32 v118, v118
	v_exp_f32_e32 v87, v87
	v_exp_f32_e32 v119, v119
	v_exp_f32_e32 v88, v88
	v_exp_f32_e32 v120, v120
	v_exp_f32_e32 v89, v89
	v_exp_f32_e32 v121, v121
	v_fmamk_f32 v90, v90, 0x3e16c740, v254
	v_fmamk_f32 v122, v122, 0x3e16c740, v255
	v_fmamk_f32 v91, v91, 0x3e16c740, v254
	v_fmamk_f32 v123, v123, 0x3e16c740, v255
	v_fmamk_f32 v92, v92, 0x3e16c740, v254
	v_fmamk_f32 v124, v124, 0x3e16c740, v255
	v_fmamk_f32 v93, v93, 0x3e16c740, v254
	v_fmamk_f32 v125, v125, 0x3e16c740, v255
	v_fmamk_f32 v94, v94, 0x3e16c740, v254
	v_fmamk_f32 v126, v126, 0x3e16c740, v255
	v_fmamk_f32 v95, v95, 0x3e16c740, v254
	v_fmamk_f32 v127, v127, 0x3e16c740, v255
	v_fmamk_f32 v96, v96, 0x3e16c740, v254
	v_fmamk_f32 v128, v128, 0x3e16c740, v255
	v_fmamk_f32 v97, v97, 0x3e16c740, v254
	v_fmamk_f32 v129, v129, 0x3e16c740, v255
	v_exp_f32_e32 v90, v90
	v_exp_f32_e32 v122, v122
	v_mov_b32_e32 v239, v82
	v_mov_b32_e32 v253, v114
	v_exp_f32_e32 v91, v91
	v_exp_f32_e32 v123, v123
	v_add_f32_e32 v239, v239, v83
	v_add_f32_e32 v253, v253, v115
	v_exp_f32_e32 v92, v92
	v_exp_f32_e32 v124, v124
	v_add_f32_e32 v239, v239, v84
	v_add_f32_e32 v253, v253, v116
	v_exp_f32_e32 v93, v93
	v_exp_f32_e32 v125, v125
	v_add_f32_e32 v239, v239, v85
	v_add_f32_e32 v253, v253, v117
	v_exp_f32_e32 v94, v94
	v_exp_f32_e32 v126, v126
	v_add_f32_e32 v239, v239, v86
	v_add_f32_e32 v253, v253, v118
	v_exp_f32_e32 v95, v95
	v_exp_f32_e32 v127, v127
	v_add_f32_e32 v239, v239, v87
	v_add_f32_e32 v253, v253, v119
	v_exp_f32_e32 v96, v96
	v_exp_f32_e32 v128, v128
	v_add_f32_e32 v239, v239, v88
	v_add_f32_e32 v253, v253, v120
	v_exp_f32_e32 v97, v97
	v_exp_f32_e32 v129, v129
	v_add_f32_e32 v239, v239, v89
	v_add_f32_e32 v253, v253, v121
	v_cvt_pk_bf16_f32 v82, v82, v83
	v_cvt_pk_bf16_f32 v114, v114, v115
	v_cvt_pk_bf16_f32 v83, v84, v85
	v_cvt_pk_bf16_f32 v115, v116, v117
	v_cvt_pk_bf16_f32 v84, v86, v87
	v_cvt_pk_bf16_f32 v116, v118, v119
	v_cvt_pk_bf16_f32 v85, v88, v89
	v_cvt_pk_bf16_f32 v117, v120, v121
	v_fmamk_f32 v66, v66, 0x3e16c740, v254
	v_fmamk_f32 v98, v98, 0x3e16c740, v255
	v_fmamk_f32 v67, v67, 0x3e16c740, v254
	v_fmamk_f32 v99, v99, 0x3e16c740, v255
	v_fmamk_f32 v68, v68, 0x3e16c740, v254
	v_fmamk_f32 v100, v100, 0x3e16c740, v255
	v_fmamk_f32 v69, v69, 0x3e16c740, v254
	v_fmamk_f32 v101, v101, 0x3e16c740, v255
	v_fmamk_f32 v70, v70, 0x3e16c740, v254
	v_fmamk_f32 v102, v102, 0x3e16c740, v255
	v_fmamk_f32 v71, v71, 0x3e16c740, v254
	v_fmamk_f32 v103, v103, 0x3e16c740, v255
	v_fmamk_f32 v72, v72, 0x3e16c740, v254
	v_fmamk_f32 v104, v104, 0x3e16c740, v255
	v_fmamk_f32 v73, v73, 0x3e16c740, v254
	v_fmamk_f32 v105, v105, 0x3e16c740, v255
	v_exp_f32_e32 v66, v66
	v_exp_f32_e32 v98, v98
	v_add_f32_e32 v239, v239, v90
	v_add_f32_e32 v253, v253, v122
	v_exp_f32_e32 v67, v67
	v_exp_f32_e32 v99, v99
	v_add_f32_e32 v239, v239, v91
	v_add_f32_e32 v253, v253, v123
	v_exp_f32_e32 v68, v68
	v_exp_f32_e32 v100, v100
	v_add_f32_e32 v239, v239, v92
	v_add_f32_e32 v253, v253, v124
	v_exp_f32_e32 v69, v69
	v_exp_f32_e32 v101, v101
	v_add_f32_e32 v239, v239, v93
	v_add_f32_e32 v253, v253, v125
	v_exp_f32_e32 v70, v70
	v_exp_f32_e32 v102, v102
	v_add_f32_e32 v239, v239, v94
	v_add_f32_e32 v253, v253, v126
	v_exp_f32_e32 v71, v71
	v_exp_f32_e32 v103, v103
	v_add_f32_e32 v239, v239, v95
	v_add_f32_e32 v253, v253, v127
	v_exp_f32_e32 v72, v72
	v_exp_f32_e32 v104, v104
	v_add_f32_e32 v239, v239, v96
	v_add_f32_e32 v253, v253, v128
	v_exp_f32_e32 v73, v73
	v_exp_f32_e32 v105, v105
	v_add_f32_e32 v239, v239, v97
	v_add_f32_e32 v253, v253, v129
	v_cvt_pk_bf16_f32 v90, v90, v91
	v_cvt_pk_bf16_f32 v122, v122, v123
	v_cvt_pk_bf16_f32 v91, v92, v93
	v_cvt_pk_bf16_f32 v123, v124, v125
	v_cvt_pk_bf16_f32 v92, v94, v95
	v_cvt_pk_bf16_f32 v124, v126, v127
	v_cvt_pk_bf16_f32 v93, v96, v97
; #define MFMA(a, b, c) __builtin_amdgcn_mfma_f32_32x32x16_bf16((a), (b), (c), 0, 0, 0)
; DI unsigned pk2(float a, float b) { f32x2 v = {a, b}; bf16x2_t r = __builtin_convertvector(v, bf16x2_t); return __builtin_bit_cast(unsigned, r); }
; template <int DQK, bool BAND, int QT> ...
;     ...
;         const float mc = -m[qt] * cc;
;         float ls = 0.f;
; #pragma unroll
;         for (int a = 0; a < 2; ++a) {
; #pragma unroll
;           for (int r = 0; r < 16; ++r) { const float pv = __builtin_amdgcn_exp2f(fmaf(s[a][qt][r], cc, mc)); s[a][qt][r] = pv; ls += pv; }
; #pragma unroll
;           for (int s2 = 0; s2 < 2; ++s2) {
;             u32x4 pk;
;             pk.x = pk2(s[a][qt][8 * s2 + 0], s[a][qt][8 * s2 + 1]);
;             pk.y = pk2(s[a][qt][8 * s2 + 2], s[a][qt][8 * s2 + 3]);
;             pk.z = pk2(s[a][qt][8 * s2 + 4], s[a][qt][8 * s2 + 5]);
;             pk.w = pk2(s[a][qt][8 * s2 + 6], s[a][qt][8 * s2 + 7]);
;             pf[qt][a * 2 + s2] = __builtin_bit_cast(bf16x8, pk);
;           }
;         }
;         l[qt] += ls;
;       }
;       __builtin_amdgcn_s_setprio(0);
;       if (more) lstore(lds + ((it + 1) & 1) * ST);
; #pragma unroll
;       for (int ks = 0; ks < 4; ++ks) {
;         const bf16x8 v0 = *(const bf16x8*)(st + v_rd + ks * 32);
;         const bf16x8 v1 = *(const bf16x8*)(st + v_rd + 32 * LROW + ks * 32);
; #pragma unroll
;         for (int qt = 0; qt < QT; ++qt) {
;           o[0][qt] = MFMA(v0, pf[qt][ks], o[0][qt]);
;           o[1][qt] = MFMA(v1, pf[qt][ks], o[1][qt]);
;         }
;       }
	v_cvt_pk_bf16_f32 v125, v128, v129
	v_fmamk_f32 v74, v74, 0x3e16c740, v254
	v_fmamk_f32 v106, v106, 0x3e16c740, v255
	v_fmamk_f32 v75, v75, 0x3e16c740, v254
	v_fmamk_f32 v107, v107, 0x3e16c740, v255
	v_fmamk_f32 v76, v76, 0x3e16c740, v254
	v_fmamk_f32 v108, v108, 0x3e16c740, v255
	v_fmamk_f32 v77, v77, 0x3e16c740, v254
	v_fmamk_f32 v109, v109, 0x3e16c740, v255
	v_fmamk_f32 v78, v78, 0x3e16c740, v254
	v_fmamk_f32 v110, v110, 0x3e16c740, v255
	v_fmamk_f32 v79, v79, 0x3e16c740, v254
	v_fmamk_f32 v111, v111, 0x3e16c740, v255
	v_fmamk_f32 v80, v80, 0x3e16c740, v254
	v_fmamk_f32 v112, v112, 0x3e16c740, v255
	v_fmamk_f32 v81, v81, 0x3e16c740, v254
	v_fmamk_f32 v113, v113, 0x3e16c740, v255
	v_exp_f32_e32 v74, v74
	v_exp_f32_e32 v106, v106
	v_add_f32_e32 v239, v239, v66
	v_add_f32_e32 v253, v253, v98
	v_exp_f32_e32 v75, v75
	v_exp_f32_e32 v107, v107
	v_add_f32_e32 v239, v239, v67
	v_add_f32_e32 v253, v253, v99
	v_exp_f32_e32 v76, v76
	v_exp_f32_e32 v108, v108
	v_add_f32_e32 v239, v239, v68
	v_add_f32_e32 v253, v253, v100
	v_exp_f32_e32 v77, v77
	v_exp_f32_e32 v109, v109
	v_add_f32_e32 v239, v239, v69
	v_add_f32_e32 v253, v253, v101
	v_exp_f32_e32 v78, v78
	v_exp_f32_e32 v110, v110
	v_add_f32_e32 v239, v239, v70
	v_add_f32_e32 v253, v253, v102
	v_exp_f32_e32 v79, v79
	v_exp_f32_e32 v111, v111
	v_add_f32_e32 v239, v239, v71
	v_add_f32_e32 v253, v253, v103
	v_exp_f32_e32 v80, v80
	v_exp_f32_e32 v112, v112
	v_add_f32_e32 v239, v239, v72
	v_add_f32_e32 v253, v253, v104
	v_exp_f32_e32 v81, v81
	v_exp_f32_e32 v113, v113
	v_add_f32_e32 v239, v239, v73
	v_add_f32_e32 v253, v253, v105
	v_cvt_pk_bf16_f32 v66, v66, v67
	v_cvt_pk_bf16_f32 v98, v98, v99
	v_cvt_pk_bf16_f32 v67, v68, v69
	v_cvt_pk_bf16_f32 v99, v100, v101
	v_cvt_pk_bf16_f32 v68, v70, v71
	v_cvt_pk_bf16_f32 v100, v102, v103
	v_cvt_pk_bf16_f32 v69, v72, v73
	v_cvt_pk_bf16_f32 v101, v104, v105
	v_add_f32_e32 v239, v239, v74
	v_add_f32_e32 v253, v253, v106
	v_add_f32_e32 v239, v239, v75
	v_add_f32_e32 v253, v253, v107
	v_add_f32_e32 v239, v239, v76
	v_add_f32_e32 v253, v253, v108
	v_add_f32_e32 v239, v239, v77
	v_add_f32_e32 v253, v253, v109
	v_add_f32_e32 v239, v239, v78
	v_add_f32_e32 v253, v253, v110
	v_add_f32_e32 v239, v239, v79
	v_add_f32_e32 v253, v253, v111
	v_add_f32_e32 v239, v239, v80
	v_add_f32_e32 v253, v253, v112
	v_add_f32_e32 v239, v239, v81
	v_add_f32_e32 v253, v253, v113
	v_cvt_pk_bf16_f32 v74, v74, v75
	v_cvt_pk_bf16_f32 v106, v106, v107
	v_cvt_pk_bf16_f32 v75, v76, v77
	v_cvt_pk_bf16_f32 v107, v108, v109
	v_cvt_pk_bf16_f32 v76, v78, v79
	v_cvt_pk_bf16_f32 v108, v110, v111
	v_cvt_pk_bf16_f32 v77, v80, v81
	v_cvt_pk_bf16_f32 v109, v112, v113
	v_add_f32_e32 v236, v236, v239
	v_add_f32_e32 v207, v207, v253
	s_setprio 2
	ds_read_b128 v[86:89], v234 offset:13312
	ds_read_b128 v[94:97], v234 offset:17920
	ds_read_b128 v[70:73], v234 offset:13344
	ds_read_b128 v[78:81], v234 offset:17952
	ds_read_b128 v[118:121], v234 offset:13376
	ds_read_b128 v[126:129], v234 offset:17984
	ds_read_b128 v[102:105], v234 offset:13408
	ds_read_b128 v[110:113], v234 offset:18016
	s_waitcnt lgkmcnt(7)
	v_mfma_f32_32x32x16_bf16 v[50:65], v[86:89], v[82:85], v[50:65]
	v_mfma_f32_32x32x16_bf16 v[18:33], v[86:89], v[114:117], v[18:33]
	s_waitcnt lgkmcnt(6)
	v_mfma_f32_32x32x16_bf16 v[34:49], v[94:97], v[82:85], v[34:49]
	v_mfma_f32_32x32x16_bf16 v[2:17], v[94:97], v[114:117], v[2:17]
	v_lshl_add_u64 v[208:209], v[208:209], 0, s[76:77]
	v_lshl_add_u64 v[210:211], v[210:211], 0, s[76:77]
	v_lshl_add_u64 v[212:213], v[212:213], 0, s[84:85]
	v_lshl_add_u64 v[214:215], v[214:215], 0, s[84:85]
	v_lshl_add_u64 v[216:217], v[216:217], 0, s[84:85]
	s_waitcnt lgkmcnt(5)
	v_mfma_f32_32x32x16_bf16 v[50:65], v[70:73], v[90:93], v[50:65]
	v_mfma_f32_32x32x16_bf16 v[18:33], v[70:73], v[122:125], v[18:33]
	s_waitcnt lgkmcnt(4)
	v_mfma_f32_32x32x16_bf16 v[34:49], v[78:81], v[90:93], v[34:49]
	v_mfma_f32_32x32x16_bf16 v[2:17], v[78:81], v[122:125], v[2:17]
	s_waitcnt lgkmcnt(3)
	v_mfma_f32_32x32x16_bf16 v[50:65], v[118:121], v[66:69], v[50:65]
	v_mfma_f32_32x32x16_bf16 v[18:33], v[118:121], v[98:101], v[18:33]
	s_waitcnt lgkmcnt(2)
	v_mfma_f32_32x32x16_bf16 v[34:49], v[126:129], v[66:69], v[34:49]
	v_mfma_f32_32x32x16_bf16 v[2:17], v[126:129], v[98:101], v[2:17]
	s_bitcmp1_b32 s1, 0
	s_cselect_b32 s7, -1, 1
	s_mulk_i32 s7, 0x5800
	v_add_u32_e32 v235, s7, v235
	v_add_u32_e32 v234, s7, v234
	s_add_i32 s1, s1, 1
	s_add_i32 s6, s6, 64
	s_waitcnt lgkmcnt(0)
	s_barrier
	v_mfma_f32_32x32x16_bf16 v[50:65], v[102:105], v[74:77], v[50:65]
	v_mfma_f32_32x32x16_bf16 v[18:33], v[102:105], v[106:109], v[18:33]
	v_mfma_f32_32x32x16_bf16 v[34:49], v[110:113], v[74:77], v[34:49]
	v_mfma_f32_32x32x16_bf16 v[2:17], v[110:113], v[106:109], v[2:17]
	s_cmp_lg_u32 s21, s1
	s_cbranch_scc1 .Lmla_top
	s_branch .LBB0_663

; #define MFMA(a, b, c) __builtin_amdgcn_mfma_f32_32x32x16_bf16((a), (b), (c), 0, 0, 0)
; template <int NJ> DI void gemm_mainloop_glds(const bf16_t* __restrict__ A, int lda, const bf16_t* __restrict__ Bt, int ldb, int K, f32x16 (&acc)[2][NJ], char* lds) {
;     ...
;   GSTAGE_(0);
;   asm volatile("s_waitcnt vmcnt(0)" ::: "memory");
;   __syncthreads();
;   const int nk = K >> 6;
;   for (int kt = 0; kt < nk; ++kt) {
;     const int cur = kt & 1;
;     if (kt + 1 < nk) GSTAGE_(cur ^ 1);
;     const char* st_ = lds + cur * GSTG;
; #pragma unroll
;     for (int ks = 0; ks < 4; ++ks) {
;       const bf16x8 a0 = *(const bf16x8*)(st_ + a_rd[ks]);
;       const bf16x8 a1 = *(const bf16x8*)(st_ + a_rd[ks] + 4096);
; #pragma unroll
;       for (int j = 0; j < NJ; ++j) {
;         const bf16x8 b = *(const bf16x8*)(st_ + b_rd[ks] + j * 4096);
;         acc[0][j] = MFMA(a0, b, acc[0][j]); acc[1][j] = MFMA(a1, b, acc[1][j]);
;       }
;     }
;     asm volatile("s_waitcnt vmcnt(0)" ::: "memory");
;     __syncthreads();
;   }
.LBB0_963:
	s_and_b32 s52, s51, 0x8000
	s_xor_b32 s53, s52, 0x8000
	s_add_i32 s53, s27, s53
	v_lshl_add_u64 v[156:157], v[72:73], 0, s[2:3]
	s_mov_b32 m0, s53
	s_add_i32 s52, s52, 0
	global_load_lds_dwordx4 v[156:157], off
	v_lshl_add_u64 v[156:157], v[70:71], 0, s[2:3]
	s_add_i32 m0, s53, 0x1000
	v_add_u32_e32 v0, s52, v153
	global_load_lds_dwordx4 v[156:157], off
	v_lshl_add_u64 v[156:157], v[68:69], 0, s[2:3]
	s_add_i32 m0, s53, 0x2000
	s_nop 0
	global_load_lds_dwordx4 v[156:157], off
	v_lshl_add_u64 v[156:157], v[66:67], 0, s[2:3]
	s_add_i32 m0, s53, 0x3000
	s_nop 0
	global_load_lds_dwordx4 v[156:157], off
	s_add_i32 m0, s53, 0x4000
	v_lshl_add_u64 v[156:157], v[144:145], 0, s[2:3]
	global_load_lds_dwordx4 v[156:157], off
	v_lshl_add_u64 v[156:157], v[142:143], 0, s[2:3]
	s_add_i32 m0, s53, 0x5000
	s_nop 0
	global_load_lds_dwordx4 v[156:157], off
	v_lshl_add_u64 v[156:157], v[76:77], 0, s[2:3]
	s_add_i32 m0, s53, 0x6000
	s_nop 0
	global_load_lds_dwordx4 v[156:157], off
	v_lshl_add_u64 v[156:157], v[74:75], 0, s[2:3]
	s_add_i32 m0, s53, 0x7000
	s_add_u32 s2, s2, 0x80
	global_load_lds_dwordx4 v[156:157], off
	ds_read_b128 v[156:159], v0
	ds_read_b128 v[160:163], v0 offset:4096
	v_add_u32_e32 v0, s52, v154
	ds_read_b128 v[164:167], v0 offset:16384
	s_waitcnt lgkmcnt(0)
	s_setprio 1
	v_mfma_f32_32x32x16_bf16 v[50:65], v[156:159], v[164:167], v[50:65]
	s_addc_u32 s3, s3, 0
	s_add_i32 s51, s51, 0x8000
	s_cmpk_eq_i32 s2, 0x780
	v_mfma_f32_32x32x16_bf16 v[34:49], v[160:163], v[164:167], v[34:49]
	ds_read_b128 v[164:167], v0 offset:20480
	v_add_u32_e32 v0, s52, v151
	s_waitcnt lgkmcnt(0)
	v_mfma_f32_32x32x16_bf16 v[18:33], v[156:159], v[164:167], v[18:33]
	v_mfma_f32_32x32x16_bf16 v[2:17], v[160:163], v[164:167], v[2:17]
	ds_read_b128 v[156:159], v0
	ds_read_b128 v[160:163], v0 offset:4096
	v_add_u32_e32 v0, s52, v152
	ds_read_b128 v[164:167], v0 offset:16384
	s_waitcnt lgkmcnt(0)
	v_mfma_f32_32x32x16_bf16 v[50:65], v[156:159], v[164:167], v[50:65]
	v_mfma_f32_32x32x16_bf16 v[34:49], v[160:163], v[164:167], v[34:49]
	ds_read_b128 v[164:167], v0 offset:20480
	v_add_u32_e32 v0, s52, v148
	s_waitcnt lgkmcnt(0)
	v_mfma_f32_32x32x16_bf16 v[18:33], v[156:159], v[164:167], v[18:33]
	v_mfma_f32_32x32x16_bf16 v[2:17], v[160:163], v[164:167], v[2:17]
	ds_read_b128 v[156:159], v0
	ds_read_b128 v[160:163], v0 offset:4096
	v_add_u32_e32 v0, s52, v150
	ds_read_b128 v[164:167], v0 offset:16384
	s_waitcnt lgkmcnt(0)
	v_mfma_f32_32x32x16_bf16 v[50:65], v[156:159], v[164:167], v[50:65]
	v_mfma_f32_32x32x16_bf16 v[34:49], v[160:163], v[164:167], v[34:49]
	ds_read_b128 v[164:167], v0 offset:20480
	v_add_u32_e32 v0, s52, v147
	s_waitcnt lgkmcnt(0)
	v_mfma_f32_32x32x16_bf16 v[18:33], v[156:159], v[164:167], v[18:33]
	v_mfma_f32_32x32x16_bf16 v[2:17], v[160:163], v[164:167], v[2:17]
	ds_read_b128 v[156:159], v0
	ds_read_b128 v[160:163], v0 offset:4096
	v_add_u32_e32 v0, s52, v149
	ds_read_b128 v[164:167], v0 offset:16384
	s_waitcnt lgkmcnt(0)
	v_mfma_f32_32x32x16_bf16 v[50:65], v[156:159], v[164:167], v[50:65]
	v_mfma_f32_32x32x16_bf16 v[34:49], v[160:163], v[164:167], v[34:49]
	ds_read_b128 v[164:167], v0 offset:20480
	s_waitcnt vmcnt(0)
	s_waitcnt vmcnt(0) lgkmcnt(0)
	s_barrier
	v_mfma_f32_32x32x16_bf16 v[18:33], v[156:159], v[164:167], v[18:33]
	v_mfma_f32_32x32x16_bf16 v[2:17], v[160:163], v[164:167], v[2:17]
	s_cbranch_scc0 .LBB0_963
	v_add_u32_e32 v0, 0, v153
	ds_read_b128 v[66:69], v0 offset:32768
	ds_read_b128 v[70:73], v0 offset:36864
	v_add_u32_e32 v0, 0, v154
	ds_read_b128 v[74:77], v0 offset:49152
	s_cmp_eq_u32 s50, 1
	s_mov_b32 s3, 0x1a8a5900
	s_movk_i32 s2, 0x200
	s_waitcnt lgkmcnt(0)
	v_mfma_f32_32x32x16_bf16 v[50:65], v[66:69], v[74:77], v[50:65]
	s_cselect_b32 s2, 0x100, s2
	v_mfma_f32_32x32x16_bf16 v[34:49], v[70:73], v[74:77], v[34:49]
	ds_read_b128 v[74:77], v0 offset:53248
	v_add_u32_e32 v0, 0, v151
	s_waitcnt lgkmcnt(0)
	v_mfma_f32_32x32x16_bf16 v[18:33], v[66:69], v[74:77], v[18:33]
	v_mfma_f32_32x32x16_bf16 v[2:17], v[70:73], v[74:77], v[2:17]
	ds_read_b128 v[66:69], v0 offset:32768
	ds_read_b128 v[70:73], v0 offset:36864
	v_add_u32_e32 v0, 0, v152
	ds_read_b128 v[74:77], v0 offset:49152
	s_waitcnt lgkmcnt(0)
	v_mfma_f32_32x32x16_bf16 v[50:65], v[66:69], v[74:77], v[50:65]
	v_mfma_f32_32x32x16_bf16 v[34:49], v[70:73], v[74:77], v[34:49]
	ds_read_b128 v[74:77], v0 offset:53248
	v_add_u32_e32 v0, 0, v148
	s_waitcnt lgkmcnt(0)
	v_mfma_f32_32x32x16_bf16 v[18:33], v[66:69], v[74:77], v[18:33]
	v_mfma_f32_32x32x16_bf16 v[2:17], v[70:73], v[74:77], v[2:17]
	ds_read_b128 v[66:69], v0 offset:32768
	ds_read_b128 v[70:73], v0 offset:36864
	v_add_u32_e32 v0, 0, v150
	ds_read_b128 v[74:77], v0 offset:49152
	s_waitcnt lgkmcnt(0)
	v_mfma_f32_32x32x16_bf16 v[50:65], v[66:69], v[74:77], v[50:65]
	v_mfma_f32_32x32x16_bf16 v[34:49], v[70:73], v[74:77], v[34:49]
	ds_read_b128 v[74:77], v0 offset:53248
	v_add_u32_e32 v0, 0, v147
	s_waitcnt lgkmcnt(0)
	v_mfma_f32_32x32x16_bf16 v[18:33], v[66:69], v[74:77], v[18:33]
	v_mfma_f32_32x32x16_bf16 v[2:17], v[70:73], v[74:77], v[2:17]
	ds_read_b128 v[66:69], v0 offset:32768
	ds_read_b128 v[70:73], v0 offset:36864
	v_add_u32_e32 v0, 0, v149
	ds_read_b128 v[74:77], v0 offset:49152
	s_waitcnt lgkmcnt(0)
	v_mfma_f32_32x32x16_bf16 v[50:65], v[66:69], v[74:77], v[50:65]
	v_mfma_f32_32x32x16_bf16 v[34:49], v[70:73], v[74:77], v[34:49]
	ds_read_b128 v[74:77], v0 offset:53248
	s_waitcnt vmcnt(0)
	s_waitcnt lgkmcnt(0)
	s_barrier
; DI int tid_() { int t = threadIdx.x; asm volatile("" : "+v"(t)); return t; }
; DI unsigned pk2(float a, float b) { f32x2 v = {a, b}; bf16x2_t r = __builtin_convertvector(v, bf16x2_t); return __builtin_bit_cast(unsigned, r); }
; DI float sigmoidf_(float x) { return __builtin_amdgcn_rcpf(1.0f + __builtin_amdgcn_exp2f(-x * LOG2E)); }
; DI void phase_merge(const Ctx& c) {
;     ...
;         const int tid = tid_(), lane = tid & 63, w = tid >> 6, wm = w >> 1, wn = w & 1, h = lane >> 5, cc = lane & 31;
; #pragma unroll
;         for (int j = 0; j < 2; ++j) {
;           const float bv = bgate[k * 1024 + nt * 128 + wn * 64 + j * 32 + cc];
; #pragma unroll
;           for (int i = 0; i < 2; ++i)
; #pragma unroll
;             for (int r2 = 0; r2 < 8; ++r2) {
;               const int ra = 2 * r2, rb = 2 * r2 + 1;
;               const float r_a = rr[wm * 64 + i * 32 + (ra & 3) + 8 * (ra >> 2) + 4 * h];
;               const float r_b = rr[wm * 64 + i * 32 + (rb & 3) + 8 * (rb >> 2) + 4 * h];
;               gp[i][j][r2] = pk2(sigmoidf_(gacc[i][j][ra] * r_a + bv), sigmoidf_(gacc[i][j][rb] * r_b + bv));
;             }
;         }
	v_mfma_f32_32x32x16_bf16 v[18:33], v[66:69], v[74:77], v[18:33]
	v_mov_b32_e32 v66, v199
	s_nop 0
	v_and_b32_e32 v0, 0x5f, v66
	v_or_b32_e32 v0, s26, v0
	v_lshl_add_u64 v[142:143], v[0:1], 2, s[0:1]
	global_load_dword v0, v[142:143], off
	v_lshrrev_b32_e32 v67, 1, v66
	v_lshlrev_b32_e32 v66, 1, v66
	v_and_b32_e32 v66, 0xffffff00, v66
	v_and_b32_e32 v67, 16, v67
	v_add3_u32 v144, s14, v66, v67
	v_mfma_f32_32x32x16_bf16 v[2:17], v[70:73], v[74:77], v[2:17]
	s_setprio 0
	ds_read_b128 v[70:73], v144
	ds_read_b128 v[66:69], v144 offset:32
	ds_read_b128 v[74:77], v144 offset:64
	s_cselect_b32 s26, s3, 0x1b2a5900
	s_mov_b32 s3, 0x108c000
	s_cselect_b32 s27, s3, 0x10dc000
	s_cmp_eq_u32 s50, 0
	s_cselect_b32 s51, 0x17de5900, s26
	s_cselect_b32 s26, 0xffc000, s27
	s_add_u32 s27, s94, s51
	s_addc_u32 s53, s95, 0
	s_lshl_b32 s56, s26, 1
	s_add_u32 s54, s22, s56
	s_addc_u32 s55, s23, 0
	s_or_b32 s57, s2, 64
	s_mul_i32 s26, s57, s46
	s_lshl_b32 s26, s26, 1
	s_add_u32 s52, s27, s26
	s_mul_i32 s26, s57, s48
	s_mov_b32 s27, s73
	s_addc_u32 s53, s53, 0
	s_lshl_b64 s[26:27], s[26:27], 1
	s_add_u32 s54, s54, s26
	s_addc_u32 s55, s55, s27
	s_mov_b32 s3, 0
	s_waitcnt vmcnt(0) lgkmcnt(2)
	v_fma_f32 v50, v50, v70, v0
	v_mul_f32_e32 v50, 0xbfb8aa3b, v50
	v_exp_f32_e32 v50, v50
	s_nop 0
	v_add_f32_e32 v50, 1.0, v50
	v_rcp_f32_e32 v147, v50
	v_fma_f32 v50, v51, v71, v0
	v_mul_f32_e32 v50, 0xbfb8aa3b, v50
	v_exp_f32_e32 v50, v50
	s_nop 0
	v_add_f32_e32 v50, 1.0, v50
	v_rcp_f32_e32 v148, v50
	v_fma_f32 v50, v52, v72, v0
	v_mul_f32_e32 v50, 0xbfb8aa3b, v50
	v_exp_f32_e32 v50, v50
	s_nop 0
	v_add_f32_e32 v50, 1.0, v50
	v_rcp_f32_e32 v149, v50
	v_fma_f32 v50, v53, v73, v0
	v_mul_f32_e32 v50, 0xbfb8aa3b, v50
	v_exp_f32_e32 v50, v50
	s_nop 0
	v_add_f32_e32 v50, 1.0, v50
	v_rcp_f32_e32 v150, v50
	s_waitcnt lgkmcnt(1)
	v_fma_f32 v50, v54, v66, v0
	v_mul_f32_e32 v50, 0xbfb8aa3b, v50
	v_exp_f32_e32 v50, v50
	s_nop 0
	v_add_f32_e32 v50, 1.0, v50
	v_rcp_f32_e32 v151, v50
	v_fma_f32 v50, v55, v67, v0
	v_mul_f32_e32 v50, 0xbfb8aa3b, v50
	v_exp_f32_e32 v50, v50
	s_nop 0
	v_add_f32_e32 v50, 1.0, v50
	v_rcp_f32_e32 v152, v50
	v_fma_f32 v50, v56, v68, v0
	v_mul_f32_e32 v50, 0xbfb8aa3b, v50
	v_exp_f32_e32 v50, v50
	s_nop 0
	v_add_f32_e32 v50, 1.0, v50
	v_rcp_f32_e32 v153, v50
	v_fma_f32 v50, v57, v69, v0
	v_mul_f32_e32 v50, 0xbfb8aa3b, v50
	v_exp_f32_e32 v50, v50
	ds_read_b128 v[54:57], v144 offset:128
	v_add_f32_e32 v50, 1.0, v50
	v_rcp_f32_e32 v154, v50
	s_waitcnt lgkmcnt(1)
	v_fma_f32 v50, v58, v74, v0
	v_mul_f32_e32 v50, 0xbfb8aa3b, v50
	v_exp_f32_e32 v50, v50
	s_waitcnt lgkmcnt(0)
	v_fma_f32 v34, v34, v54, v0
	v_mul_f32_e32 v34, 0xbfb8aa3b, v34
	v_exp_f32_e32 v34, v34
	v_add_f32_e32 v50, 1.0, v50
	v_rcp_f32_e32 v155, v50
	v_fma_f32 v50, v59, v75, v0
	v_mul_f32_e32 v50, 0xbfb8aa3b, v50
	v_exp_f32_e32 v50, v50
	v_add_f32_e32 v34, 1.0, v34
	v_rcp_f32_e32 v163, v34
	v_fma_f32 v34, v35, v55, v0
	v_add_f32_e32 v50, 1.0, v50
	v_rcp_f32_e32 v156, v50
	v_fma_f32 v50, v60, v76, v0
	v_mul_f32_e32 v50, 0xbfb8aa3b, v50
	v_exp_f32_e32 v50, v50
	v_mul_f32_e32 v34, 0xbfb8aa3b, v34
	v_exp_f32_e32 v34, v34
	v_add_f32_e32 v50, 1.0, v50
	v_rcp_f32_e32 v157, v50
	v_fma_f32 v50, v61, v77, v0
	v_mul_f32_e32 v50, 0xbfb8aa3b, v50
	v_exp_f32_e32 v50, v50
	ds_read_b128 v[58:61], v144 offset:96
	v_add_f32_e32 v34, 1.0, v34
	v_rcp_f32_e32 v164, v34
	v_add_f32_e32 v50, 1.0, v50
	v_rcp_f32_e32 v158, v50
	s_waitcnt lgkmcnt(0)
	v_fma_f32 v50, v62, v58, v0
	v_mul_f32_e32 v50, 0xbfb8aa3b, v50
	v_exp_f32_e32 v50, v50
	v_fma_f32 v34, v36, v56, v0
	v_mul_f32_e32 v34, 0xbfb8aa3b, v34
	v_exp_f32_e32 v34, v34
	v_add_f32_e32 v50, 1.0, v50
	v_rcp_f32_e32 v159, v50
	v_fma_f32 v50, v63, v59, v0
	v_mul_f32_e32 v50, 0xbfb8aa3b, v50
	v_exp_f32_e32 v50, v50
	v_add_f32_e32 v34, 1.0, v34
	v_rcp_f32_e32 v165, v34
	v_fma_f32 v34, v37, v57, v0
	v_add_f32_e32 v50, 1.0, v50
	v_rcp_f32_e32 v160, v50
	v_fma_f32 v50, v64, v60, v0
	v_mul_f32_e32 v50, 0xbfb8aa3b, v50
	v_exp_f32_e32 v50, v50
	v_mul_f32_e32 v34, 0xbfb8aa3b, v34
	v_exp_f32_e32 v34, v34
	v_add_f32_e32 v50, 1.0, v50
	v_rcp_f32_e32 v161, v50
	v_fma_f32 v50, v65, v61, v0
	v_mul_f32_e32 v50, 0xbfb8aa3b, v50
	v_exp_f32_e32 v50, v50
	v_add_f32_e32 v34, 1.0, v34
	v_rcp_f32_e32 v166, v34
	v_add_f32_e32 v50, 1.0, v50
	v_rcp_f32_e32 v162, v50
	ds_read_b128 v[50:53], v144 offset:160
	s_waitcnt lgkmcnt(0)
	v_fma_f32 v34, v38, v50, v0
	v_mul_f32_e32 v34, 0xbfb8aa3b, v34
	v_exp_f32_e32 v34, v34
	s_nop 0
	v_add_f32_e32 v34, 1.0, v34
	v_rcp_f32_e32 v167, v34
	v_fma_f32 v34, v39, v51, v0
	v_mul_f32_e32 v34, 0xbfb8aa3b, v34
	v_exp_f32_e32 v34, v34
	s_nop 0
	v_add_f32_e32 v34, 1.0, v34
	v_rcp_f32_e32 v168, v34
	v_fma_f32 v34, v40, v52, v0
	v_mul_f32_e32 v34, 0xbfb8aa3b, v34
	v_exp_f32_e32 v34, v34
	s_nop 0
	v_add_f32_e32 v34, 1.0, v34
	v_rcp_f32_e32 v169, v34
	v_fma_f32 v34, v41, v53, v0
	v_mul_f32_e32 v34, 0xbfb8aa3b, v34
	v_exp_f32_e32 v34, v34
	ds_read_b128 v[38:41], v144 offset:192
	v_add_f32_e32 v34, 1.0, v34
	v_rcp_f32_e32 v170, v34
	s_waitcnt lgkmcnt(0)
	v_fma_f32 v34, v42, v38, v0
	v_mul_f32_e32 v34, 0xbfb8aa3b, v34
	v_exp_f32_e32 v34, v34
	s_nop 0
	v_add_f32_e32 v34, 1.0, v34
	v_rcp_f32_e32 v171, v34
	v_fma_f32 v34, v43, v39, v0
	v_mul_f32_e32 v34, 0xbfb8aa3b, v34
	v_exp_f32_e32 v34, v34
	s_nop 0
	v_add_f32_e32 v34, 1.0, v34
	v_rcp_f32_e32 v172, v34
	v_fma_f32 v34, v44, v40, v0
	v_mul_f32_e32 v34, 0xbfb8aa3b, v34
	v_exp_f32_e32 v34, v34
	s_nop 0
	v_add_f32_e32 v34, 1.0, v34
	v_rcp_f32_e32 v173, v34
	v_fma_f32 v34, v45, v41, v0
	v_mul_f32_e32 v34, 0xbfb8aa3b, v34
	v_exp_f32_e32 v34, v34
	s_nop 0
	v_add_f32_e32 v34, 1.0, v34
	v_rcp_f32_e32 v174, v34
	ds_read_b128 v[34:37], v144 offset:224
	s_waitcnt lgkmcnt(0)
; DI int tid_() { int t = threadIdx.x; asm volatile("" : "+v"(t)); return t; }
; DI unsigned pk2(float a, float b) { f32x2 v = {a, b}; bf16x2_t r = __builtin_convertvector(v, bf16x2_t); return __builtin_bit_cast(unsigned, r); }
; DI float sigmoidf_(float x) { return __builtin_amdgcn_rcpf(1.0f + __builtin_amdgcn_exp2f(-x * LOG2E)); }
; DI bf16_t* wsb(const Ctx& c, size_t off) { return (bf16_t*)(c.ws + off); }
; DI const bf16_t* wgt(const Ctx& c, size_t off) { return (const bf16_t*)(c.ws + OFF_W) + (size_t)c.layer * W_LAYER + off; }
; DI void phase_merge(const Ctx& c) {
;     ...
;         const int tid = tid_(), lane = tid & 63, w = tid >> 6, wm = w >> 1, wn = w & 1, h = lane >> 5, cc = lane & 31;
; #pragma unroll
;         for (int j = 0; j < 2; ++j) {
;           const float bv = bgate[k * 1024 + nt * 128 + wn * 64 + j * 32 + cc];
; #pragma unroll
;           for (int i = 0; i < 2; ++i)
; #pragma unroll
;             for (int r2 = 0; r2 < 8; ++r2) {
;               const int ra = 2 * r2, rb = 2 * r2 + 1;
;               const float r_a = rr[wm * 64 + i * 32 + (ra & 3) + 8 * (ra >> 2) + 4 * h];
;               const float r_b = rr[wm * 64 + i * 32 + (rb & 3) + 8 * (rb >> 2) + 4 * h];
;               gp[i][j][r2] = pk2(sigmoidf_(gacc[i][j][ra] * r_a + bv), sigmoidf_(gacc[i][j][rb] * r_b + bv));
;             }
;         }
;       }
;       {
;         f32x16 acc[2][2]; zero_acc<2>(acc);
;         const int Kk = (k == 1) ? 256 : 512;
;         const bf16_t* Ao = wsb(c, k == 0 ? OFF_OA : (k == 1 ? OFF_OB : OFF_OC));
;         const bf16_t* Wo = wgt(c, k == 0 ? W_OA : (k == 1 ? W_OB : W_OC));
;         gemm_mainloop_glds<2>(Ao + (size_t)mt * 128 * (Kk + PADK), Kk + PADK, Wo + (size_t)nt * 128 * (Kk + PADK), Kk + PADK, Kk, acc, c.lds);
	v_fma_f32 v42, v46, v34, v0
	v_mul_f32_e32 v42, 0xbfb8aa3b, v42
	v_exp_f32_e32 v42, v42
	s_nop 0
	v_add_f32_e32 v42, 1.0, v42
	v_rcp_f32_e32 v175, v42
	v_fma_f32 v42, v47, v35, v0
	v_mul_f32_e32 v42, 0xbfb8aa3b, v42
	v_exp_f32_e32 v42, v42
	s_nop 0
	v_add_f32_e32 v42, 1.0, v42
	v_rcp_f32_e32 v176, v42
	v_fma_f32 v42, v48, v36, v0
	v_fmac_f32_e32 v0, v49, v37
	v_mul_f32_e32 v0, 0xbfb8aa3b, v0
	v_exp_f32_e32 v0, v0
	v_mul_f32_e32 v42, 0xbfb8aa3b, v42
	v_exp_f32_e32 v42, v42
	v_add_f32_e32 v0, 1.0, v0
	v_rcp_f32_e32 v178, v0
	global_load_dword v0, v[142:143], off offset:128
	v_add_f32_e32 v42, 1.0, v42
	v_rcp_f32_e32 v177, v42
	s_waitcnt vmcnt(0)
	v_fma_f32 v18, v18, v70, v0
	v_mul_f32_e32 v18, 0xbfb8aa3b, v18
	v_exp_f32_e32 v18, v18
	v_fma_f32 v2, v2, v54, v0
	v_mul_f32_e32 v2, 0xbfb8aa3b, v2
	v_exp_f32_e32 v2, v2
	v_add_f32_e32 v18, 1.0, v18
	v_rcp_f32_e32 v179, v18
	v_fma_f32 v18, v19, v71, v0
	v_mul_f32_e32 v18, 0xbfb8aa3b, v18
	v_exp_f32_e32 v18, v18
	v_add_f32_e32 v2, 1.0, v2
	v_rcp_f32_e32 v203, v2
	v_fma_f32 v2, v3, v55, v0
	v_add_f32_e32 v18, 1.0, v18
	v_rcp_f32_e32 v180, v18
	v_fma_f32 v18, v20, v72, v0
	v_mul_f32_e32 v18, 0xbfb8aa3b, v18
	v_mul_f32_e32 v2, 0xbfb8aa3b, v2
	v_exp_f32_e32 v18, v18
	v_exp_f32_e32 v2, v2
	v_add_f32_e32 v18, 1.0, v18
	v_add_f32_e32 v2, 1.0, v2
	v_rcp_f32_e32 v181, v18
	v_fma_f32 v18, v21, v73, v0
	v_rcp_f32_e32 v204, v2
	v_fma_f32 v2, v4, v56, v0
	v_mul_f32_e32 v18, 0xbfb8aa3b, v18
	v_mul_f32_e32 v2, 0xbfb8aa3b, v2
	v_exp_f32_e32 v18, v18
	v_exp_f32_e32 v2, v2
	v_add_f32_e32 v18, 1.0, v18
	v_add_f32_e32 v2, 1.0, v2
	v_rcp_f32_e32 v182, v18
	v_fma_f32 v18, v22, v66, v0
	v_rcp_f32_e32 v206, v2
	v_fma_f32 v2, v5, v57, v0
	v_mul_f32_e32 v18, 0xbfb8aa3b, v18
	v_mul_f32_e32 v2, 0xbfb8aa3b, v2
	v_exp_f32_e32 v18, v18
	v_exp_f32_e32 v2, v2
	v_add_f32_e32 v18, 1.0, v18
	v_add_f32_e32 v2, 1.0, v2
	v_rcp_f32_e32 v183, v18
	v_fma_f32 v18, v23, v67, v0
	v_rcp_f32_e32 v207, v2
	v_fma_f32 v2, v6, v50, v0
	v_mul_f32_e32 v18, 0xbfb8aa3b, v18
	v_mul_f32_e32 v2, 0xbfb8aa3b, v2
	v_exp_f32_e32 v18, v18
	v_exp_f32_e32 v2, v2
	v_add_f32_e32 v18, 1.0, v18
	v_add_f32_e32 v2, 1.0, v2
	v_rcp_f32_e32 v184, v18
	v_fma_f32 v18, v24, v68, v0
	v_rcp_f32_e32 v208, v2
	v_fma_f32 v2, v7, v51, v0
	v_mul_f32_e32 v18, 0xbfb8aa3b, v18
	v_mul_f32_e32 v2, 0xbfb8aa3b, v2
	v_exp_f32_e32 v18, v18
	v_exp_f32_e32 v2, v2
	v_add_f32_e32 v18, 1.0, v18
	v_add_f32_e32 v2, 1.0, v2
	v_rcp_f32_e32 v185, v18
	v_fma_f32 v18, v25, v69, v0
	v_rcp_f32_e32 v210, v2
	v_fma_f32 v2, v8, v52, v0
	v_mul_f32_e32 v18, 0xbfb8aa3b, v18
	v_mul_f32_e32 v2, 0xbfb8aa3b, v2
	v_exp_f32_e32 v18, v18
	v_exp_f32_e32 v2, v2
	v_add_f32_e32 v18, 1.0, v18
	v_add_f32_e32 v2, 1.0, v2
	v_rcp_f32_e32 v186, v18
	v_fma_f32 v18, v26, v74, v0
	v_rcp_f32_e32 v211, v2
	v_fma_f32 v2, v9, v53, v0
	v_mul_f32_e32 v18, 0xbfb8aa3b, v18
	v_mul_f32_e32 v2, 0xbfb8aa3b, v2
	v_exp_f32_e32 v18, v18
	v_exp_f32_e32 v2, v2
	v_add_f32_e32 v18, 1.0, v18
	v_add_f32_e32 v2, 1.0, v2
	v_rcp_f32_e32 v187, v18
	v_fma_f32 v18, v27, v75, v0
	v_rcp_f32_e32 v213, v2
	v_fma_f32 v2, v10, v38, v0
	v_mul_f32_e32 v18, 0xbfb8aa3b, v18
	v_mul_f32_e32 v2, 0xbfb8aa3b, v2
	v_exp_f32_e32 v18, v18
	v_exp_f32_e32 v2, v2
	v_add_f32_e32 v18, 1.0, v18
	v_add_f32_e32 v2, 1.0, v2
	v_rcp_f32_e32 v188, v18
	v_fma_f32 v18, v28, v76, v0
	v_rcp_f32_e32 v214, v2
	v_fma_f32 v2, v11, v39, v0
	v_mul_f32_e32 v18, 0xbfb8aa3b, v18
	v_mul_f32_e32 v2, 0xbfb8aa3b, v2
	v_exp_f32_e32 v18, v18
	v_exp_f32_e32 v2, v2
	v_add_f32_e32 v18, 1.0, v18
	v_add_f32_e32 v2, 1.0, v2
	v_rcp_f32_e32 v189, v18
	v_fma_f32 v18, v29, v77, v0
	v_rcp_f32_e32 v215, v2
	v_fma_f32 v2, v12, v40, v0
	v_mul_f32_e32 v18, 0xbfb8aa3b, v18
	v_mul_f32_e32 v2, 0xbfb8aa3b, v2
	v_exp_f32_e32 v18, v18
	v_exp_f32_e32 v2, v2
	v_add_f32_e32 v18, 1.0, v18
	v_add_f32_e32 v2, 1.0, v2
	v_rcp_f32_e32 v190, v18
	v_fma_f32 v18, v30, v58, v0
	v_rcp_f32_e32 v216, v2
	v_fma_f32 v2, v13, v41, v0
	v_mul_f32_e32 v18, 0xbfb8aa3b, v18
	v_mul_f32_e32 v2, 0xbfb8aa3b, v2
	v_exp_f32_e32 v18, v18
	v_exp_f32_e32 v2, v2
	v_add_f32_e32 v18, 1.0, v18
	v_add_f32_e32 v2, 1.0, v2
	v_rcp_f32_e32 v192, v18
	v_fma_f32 v18, v31, v59, v0
	v_rcp_f32_e32 v230, v2
	v_fma_f32 v2, v14, v34, v0
	v_mul_f32_e32 v18, 0xbfb8aa3b, v18
	v_mul_f32_e32 v2, 0xbfb8aa3b, v2
	v_exp_f32_e32 v18, v18
	v_exp_f32_e32 v2, v2
	v_add_f32_e32 v18, 1.0, v18
	v_add_f32_e32 v2, 1.0, v2
	v_rcp_f32_e32 v193, v18
	v_fma_f32 v18, v32, v60, v0
	v_rcp_f32_e32 v231, v2
	v_fma_f32 v2, v15, v35, v0
	v_mul_f32_e32 v18, 0xbfb8aa3b, v18
	v_mul_f32_e32 v2, 0xbfb8aa3b, v2
	v_exp_f32_e32 v18, v18
	v_exp_f32_e32 v2, v2
	v_add_f32_e32 v18, 1.0, v18
	v_add_f32_e32 v2, 1.0, v2
	v_rcp_f32_e32 v195, v18
	v_fma_f32 v18, v33, v61, v0
	v_rcp_f32_e32 v233, v2
	v_fma_f32 v2, v16, v36, v0
	v_fmac_f32_e32 v0, v17, v37
	v_mul_f32_e32 v0, 0xbfb8aa3b, v0
	v_exp_f32_e32 v0, v0
	v_mul_f32_e32 v2, 0xbfb8aa3b, v2
	v_exp_f32_e32 v2, v2
	v_mul_f32_e32 v18, 0xbfb8aa3b, v18
	v_add_f32_e32 v0, 1.0, v0
	v_rcp_f32_e32 v235, v0
	v_mov_b32_e32 v0, v199
	v_add_f32_e32 v2, 1.0, v2
	v_readfirstlane_b32 s26, v0
	s_ashr_i32 s27, s26, 6
	s_and_b32 s58, s27, 1
	s_lshl_b32 s59, s58, 2
	v_bfe_u32 v4, v0, 4, 2
	v_and_b32_e32 v5, 7, v0
	s_lshr_b32 s26, s26, 1
	v_rcp_f32_e32 v234, v2
	v_and_b32_e32 v2, 31, v0
	v_bfe_u32 v3, v0, 5, 1
	v_bitop3_b32 v4, s59, v5, v4 bitop3:0x36
	v_bfe_u32 v5, v0, 3, 3
	v_lshrrev_b32_e32 v6, 1, v0
	v_bfe_u32 v0, v0, 1, 3
	s_and_b32 s26, s26, 0x1ffffc0
	v_or_b32_e32 v7, s26, v2
	v_bitop3_b32 v6, v3, v6, 7 bitop3:0x78
	v_bitop3_b32 v8, v3, v0, 2 bitop3:0x36
	v_bitop3_b32 v9, v3, v0, 4 bitop3:0x36
	v_bitop3_b32 v0, v3, v0, 6 bitop3:0x36
	v_lshl_or_b32 v5, s27, 3, v5
; DI int tid_() { int t = threadIdx.x; asm volatile("" : "+v"(t)); return t; }
; DI bf16_t* wsb(const Ctx& c, size_t off) { return (bf16_t*)(c.ws + off); }
; DI const bf16_t* wgt(const Ctx& c, size_t off) { return (const bf16_t*)(c.ws + OFF_W) + (size_t)c.layer * W_LAYER + off; }
; template <int NJ> DI void gemm_mainloop_glds(const bf16_t* __restrict__ A, int lda, const bf16_t* __restrict__ Bt, int ldb, int K, f32x16 (&acc)[2][NJ], char* lds) {
;   const int tid = tid_(), lane = tid & 63, w = __builtin_amdgcn_readfirstlane(tid >> 6), wm = w >> 1, wn = w & 1;
;   const int ql = lane & 31, h = lane >> 5;
;   const int sw_s = (4 * (w & 1) + (lane >> 4)) & 7;
;   const int csrc = (lane & 7) ^ sw_s;
;   const char* ap = (const char*)A;
;   const char* bp = (const char*)Bt;
;   const unsigned aoff = (unsigned)((8 * w + (lane >> 3)) * lda + csrc * 8) * 2u, boff = (unsigned)((8 * w + (lane >> 3)) * ldb + csrc * 8) * 2u;
;   const unsigned astep = (unsigned)(32 * lda) * 2u, bstep = (unsigned)(32 * ldb) * 2u;
;   constexpr int NB = 2 * NJ;
;   const int sw_r = (ql >> 1) & 7;
;   int a_rd[4], b_rd[4];
; #pragma unroll
;   for (int ks = 0; ks < 4; ++ks) { const int pos = ((2 * ks + h) ^ sw_r) * 16; a_rd[ks] = (wm * 64 + ql) * 128 + pos; b_rd[ks] = GSTG_B + (wn * 32 * NJ + ql) * 128 + pos; }
;     ...
;   GSTAGE_(0);
;   asm volatile("s_waitcnt vmcnt(0)" ::: "memory");
;   __syncthreads();
;   const int nk = K >> 6;
;   for (int kt = 0; kt < nk; ++kt) {
;     const int cur = kt & 1;
;     if (kt + 1 < nk) GSTAGE_(cur ^ 1);
; DI void phase_merge(const Ctx& c) {
;     ...
;       {
;         f32x16 acc[2][2]; zero_acc<2>(acc);
;         const int Kk = (k == 1) ? 256 : 512;
;         const bf16_t* Ao = wsb(c, k == 0 ? OFF_OA : (k == 1 ? OFF_OB : OFF_OC));
;         const bf16_t* Wo = wgt(c, k == 0 ? W_OA : (k == 1 ? W_OB : W_OC));
;         gemm_mainloop_glds<2>(Ao + (size_t)mt * 128 * (Kk + PADK), Kk + PADK, Wo + (size_t)nt * 128 * (Kk + PADK), Kk + PADK, Kk, acc, c.lds);
	v_lshlrev_b32_e32 v7, 7, v7
	v_lshlrev_b32_e32 v6, 4, v6
	v_lshlrev_b32_e32 v8, 4, v8
	v_lshlrev_b32_e32 v9, 4, v9
	v_lshlrev_b32_e32 v0, 4, v0
	s_lshl_b32 s26, s27, 10
	v_or_b32_e32 v217, v7, v6
	v_or_b32_e32 v209, v8, v7
	v_or_b32_e32 v196, v9, v7
	v_or_b32_e32 v191, v0, v7
	v_lshlrev_b32_e32 v7, 4, v4
	v_mul_lo_u32 v3, s57, v5
	s_add_i32 s26, s26, 0
	s_lshl_b32 s59, s57, 6
	v_lshl_or_b32 v3, v3, 1, v7
	s_mov_b32 m0, s26
	v_add_u32_e32 v4, s59, v3
	global_load_lds_dwordx4 v3, s[52:53]
	s_add_i32 m0, s26, 0x1000
	v_add_u32_e32 v10, s59, v4
	global_load_lds_dwordx4 v4, s[52:53]
	s_add_i32 m0, s26, 0x2000
	v_add_u32_e32 v11, s59, v10
	global_load_lds_dwordx4 v10, s[52:53]
	s_add_i32 m0, s26, 0x3000
	s_lshr_b32 s27, s2, 6
	global_load_lds_dwordx4 v11, s[52:53]
	s_add_i32 m0, s26, 0x4000
	s_mul_i32 s52, s44, s57
	global_load_lds_dwordx4 v3, s[54:55]
	s_add_i32 m0, s26, 0x5000
	s_lshl_b32 s52, s52, 1
	global_load_lds_dwordx4 v4, s[54:55]
	s_add_i32 m0, s26, 0x6000
	v_lshlrev_b32_e32 v2, 7, v2
	global_load_lds_dwordx4 v10, s[54:55]
	s_add_i32 m0, s26, 0x7000
	s_add_u32 s51, s51, s52
	global_load_lds_dwordx4 v11, s[54:55]
	s_addc_u32 s53, 0, 0
	s_add_u32 s52, s51, 0x80
	s_addc_u32 s53, s53, 0
	s_lshl_b32 s51, s2, 1
	v_lshl_or_b32 v2, s58, 13, v2
	s_bitset1_b32 s51, 7
	v_or_b32_e32 v232, v2, v6
	v_mul_lo_u32 v6, v5, s51
	s_mul_i32 s51, s2, 0xc0
	v_exp_f32_e32 v18, v18
	v_or_b32_e32 v212, v2, v8
	v_or_b32_e32 v202, v2, v9
	v_or_b32_e32 v194, v2, v0
	v_add_u32_e32 v0, s51, v6
	v_lshl_add_u32 v2, s2, 7, v6
	v_lshl_add_u32 v4, s2, 6, v6
	v_or_b32_e32 v0, v0, v7
	v_or_b32_e32 v2, v2, v7
	v_or_b32_e32 v4, v4, v7
	v_add_u32_e32 v0, 0x3000, v0
	v_add_u32_e32 v2, 0x2000, v2
	v_mov_b32_e32 v3, v1
	v_add_u32_e32 v4, 0x1000, v4
	v_mov_b32_e32 v5, v1
	v_or_b32_e32 v6, v6, v7
	v_mov_b32_e32 v7, v1
	v_lshl_add_u64 v[66:67], s[52:53], 0, v[0:1]
	v_lshl_add_u64 v[68:69], s[52:53], 0, v[2:3]
	v_lshl_add_u64 v[70:71], s[52:53], 0, v[4:5]
	v_lshl_add_u64 v[72:73], s[52:53], 0, v[6:7]
	s_add_u32 s2, s25, s56
	s_mul_i32 s52, s49, s57
	s_mov_b32 s53, s73
	v_add_f32_e32 v18, 1.0, v18
	s_addc_u32 s51, s34, 0
	s_lshl_b64 s[52:53], s[52:53], 1
	v_rcp_f32_e32 v197, v18
	s_add_u32 s52, s2, s52
	s_waitcnt vmcnt(0)
	s_addc_u32 s53, s51, s53
	v_lshl_add_u64 v[76:77], s[52:53], 0, v[2:3]
	v_mov_b32_e32 v2, 0
	v_lshl_add_u64 v[74:75], s[52:53], 0, v[0:1]
	v_lshl_add_u64 v[142:143], s[52:53], 0, v[4:5]
	v_lshl_add_u64 v[144:145], s[52:53], 0, v[6:7]
	s_add_i32 s2, s27, -1
	s_mov_b32 s27, 0
	v_mov_b32_e32 v3, v2
	v_mov_b32_e32 v4, v2
	v_mov_b32_e32 v5, v2
	v_mov_b32_e32 v6, v2
	v_mov_b32_e32 v7, v2
	v_mov_b32_e32 v8, v2
	v_mov_b32_e32 v9, v2
	v_mov_b32_e32 v10, v2
	v_mov_b32_e32 v11, v2
	v_mov_b32_e32 v12, v2
	v_mov_b32_e32 v13, v2
	v_mov_b32_e32 v14, v2
	v_mov_b32_e32 v15, v2
	v_mov_b32_e32 v16, v2
	v_mov_b32_e32 v17, v2
	v_mov_b32_e32 v18, v2
	v_mov_b32_e32 v19, v2
	v_mov_b32_e32 v20, v2
	v_mov_b32_e32 v21, v2
	v_mov_b32_e32 v22, v2
	v_mov_b32_e32 v23, v2
	v_mov_b32_e32 v24, v2
	v_mov_b32_e32 v25, v2
	v_mov_b32_e32 v26, v2
	v_mov_b32_e32 v27, v2
	v_mov_b32_e32 v28, v2
	v_mov_b32_e32 v29, v2
	v_mov_b32_e32 v30, v2
	v_mov_b32_e32 v31, v2
	v_mov_b32_e32 v32, v2
	v_mov_b32_e32 v33, v2
	v_mov_b32_e32 v34, v2
	v_mov_b32_e32 v35, v2
	v_mov_b32_e32 v36, v2
	v_mov_b32_e32 v37, v2
	v_mov_b32_e32 v38, v2
	v_mov_b32_e32 v39, v2
	v_mov_b32_e32 v40, v2
	v_mov_b32_e32 v41, v2
	v_mov_b32_e32 v42, v2
	v_mov_b32_e32 v43, v2
	v_mov_b32_e32 v44, v2
	v_mov_b32_e32 v45, v2
	v_mov_b32_e32 v46, v2
	v_mov_b32_e32 v47, v2
	v_mov_b32_e32 v48, v2
	v_mov_b32_e32 v49, v2
	v_mov_b32_e32 v50, v2
	v_mov_b32_e32 v51, v2
	v_mov_b32_e32 v52, v2
	v_mov_b32_e32 v53, v2
	v_mov_b32_e32 v54, v2
	v_mov_b32_e32 v55, v2
	v_mov_b32_e32 v56, v2
	v_mov_b32_e32 v57, v2
	v_mov_b32_e32 v58, v2
	v_mov_b32_e32 v59, v2
	v_mov_b32_e32 v60, v2
	v_mov_b32_e32 v61, v2
	v_mov_b32_e32 v62, v2
	v_mov_b32_e32 v63, v2
	v_mov_b32_e32 v64, v2
	v_mov_b32_e32 v65, v2
	s_waitcnt vmcnt(0) lgkmcnt(0)
	s_barrier
.LBB0_965:
	s_and_b32 s51, s3, 0x8000
	s_xor_b32 s52, s51, 0x8000
	s_add_i32 s52, s26, s52
	v_lshl_add_u64 v[236:237], s[94:95], 0, v[72:73]
	s_mov_b32 m0, s52
	s_add_i32 s51, s51, 0
	global_load_lds_dwordx4 v[236:237], off
	v_lshl_add_u64 v[236:237], s[94:95], 0, v[70:71]
	s_add_i32 m0, s52, 0x1000
	v_add_u32_e32 v0, s51, v217
	global_load_lds_dwordx4 v[236:237], off
	v_lshl_add_u64 v[236:237], s[94:95], 0, v[68:69]
	s_add_i32 m0, s52, 0x2000
	s_add_i32 s27, s27, 1
	global_load_lds_dwordx4 v[236:237], off
	v_lshl_add_u64 v[236:237], s[94:95], 0, v[66:67]
	s_add_i32 m0, s52, 0x3000
	s_add_i32 s3, s3, 0x8000
	global_load_lds_dwordx4 v[236:237], off
	s_add_i32 m0, s52, 0x4000
	v_lshl_add_u64 v[236:237], s[94:95], 0, v[144:145]
	global_load_lds_dwordx4 v[236:237], off
	v_lshl_add_u64 v[236:237], s[94:95], 0, v[142:143]
	s_add_i32 m0, s52, 0x5000
	v_lshl_add_u64 v[66:67], v[66:67], 0, s[76:77]
	global_load_lds_dwordx4 v[236:237], off
	v_lshl_add_u64 v[236:237], s[94:95], 0, v[76:77]
	s_add_i32 m0, s52, 0x6000
	v_lshl_add_u64 v[68:69], v[68:69], 0, s[76:77]
	global_load_lds_dwordx4 v[236:237], off
	v_lshl_add_u64 v[236:237], s[94:95], 0, v[74:75]
	s_add_i32 m0, s52, 0x7000
	v_lshl_add_u64 v[70:71], v[70:71], 0, s[76:77]
	global_load_lds_dwordx4 v[236:237], off
	ds_read_b128 v[236:239], v0
	ds_read_b128 v[240:243], v0 offset:4096
	v_add_u32_e32 v0, s51, v232
	ds_read_b128 v[244:247], v0 offset:16384
	s_waitcnt lgkmcnt(0)
; #define MFMA(a, b, c) __builtin_amdgcn_mfma_f32_32x32x16_bf16((a), (b), (c), 0, 0, 0)
; DI unsigned pk2(float a, float b) { f32x2 v = {a, b}; bf16x2_t r = __builtin_convertvector(v, bf16x2_t); return __builtin_bit_cast(unsigned, r); }
; DI float sigmoidf_(float x) { return __builtin_amdgcn_rcpf(1.0f + __builtin_amdgcn_exp2f(-x * LOG2E)); }
; template <int NJ> DI void gemm_mainloop_glds(const bf16_t* __restrict__ A, int lda, const bf16_t* __restrict__ Bt, int ldb, int K, f32x16 (&acc)[2][NJ], char* lds) {
;     ...
;   for (int kt = 0; kt < nk; ++kt) {
;     const int cur = kt & 1;
;     if (kt + 1 < nk) GSTAGE_(cur ^ 1);
;     const char* st_ = lds + cur * GSTG;
; #pragma unroll
;     for (int ks = 0; ks < 4; ++ks) {
;       const bf16x8 a0 = *(const bf16x8*)(st_ + a_rd[ks]);
;       const bf16x8 a1 = *(const bf16x8*)(st_ + a_rd[ks] + 4096);
; #pragma unroll
;       for (int j = 0; j < NJ; ++j) {
;         const bf16x8 b = *(const bf16x8*)(st_ + b_rd[ks] + j * 4096);
;         acc[0][j] = MFMA(a0, b, acc[0][j]); acc[1][j] = MFMA(a1, b, acc[1][j]);
;       }
;     }
;     asm volatile("s_waitcnt vmcnt(0)" ::: "memory");
;     __syncthreads();
;   }
; DI void phase_merge(const Ctx& c) {
;     ...
;               gp[i][j][r2] = pk2(sigmoidf_(gacc[i][j][ra] * r_a + bv), sigmoidf_(gacc[i][j][rb] * r_b + bv));
	s_setprio 1
	v_mfma_f32_32x32x16_bf16 v[50:65], v[236:239], v[244:247], v[50:65]
	v_lshl_add_u64 v[72:73], v[72:73], 0, s[76:77]
	v_lshl_add_u64 v[74:75], v[74:75], 0, s[76:77]
	v_lshl_add_u64 v[76:77], v[76:77], 0, s[76:77]
	v_lshl_add_u64 v[142:143], v[142:143], 0, s[76:77]
	v_lshl_add_u64 v[144:145], v[144:145], 0, s[76:77]
	s_cmp_eq_u32 s2, s27
	v_mfma_f32_32x32x16_bf16 v[18:33], v[240:243], v[244:247], v[18:33]
	ds_read_b128 v[244:247], v0 offset:20480
	v_add_u32_e32 v0, s51, v209
	s_waitcnt lgkmcnt(0)
	v_mfma_f32_32x32x16_bf16 v[34:49], v[236:239], v[244:247], v[34:49]
	v_mfma_f32_32x32x16_bf16 v[2:17], v[240:243], v[244:247], v[2:17]
	ds_read_b128 v[236:239], v0
	ds_read_b128 v[240:243], v0 offset:4096
	v_add_u32_e32 v0, s51, v212
	ds_read_b128 v[244:247], v0 offset:16384
	s_waitcnt lgkmcnt(0)
	v_mfma_f32_32x32x16_bf16 v[50:65], v[236:239], v[244:247], v[50:65]
	v_mfma_f32_32x32x16_bf16 v[18:33], v[240:243], v[244:247], v[18:33]
	ds_read_b128 v[244:247], v0 offset:20480
	v_add_u32_e32 v0, s51, v196
	s_waitcnt lgkmcnt(0)
	v_mfma_f32_32x32x16_bf16 v[34:49], v[236:239], v[244:247], v[34:49]
	v_mfma_f32_32x32x16_bf16 v[2:17], v[240:243], v[244:247], v[2:17]
	ds_read_b128 v[236:239], v0
	ds_read_b128 v[240:243], v0 offset:4096
	v_add_u32_e32 v0, s51, v202
	ds_read_b128 v[244:247], v0 offset:16384
	s_waitcnt lgkmcnt(0)
	v_mfma_f32_32x32x16_bf16 v[50:65], v[236:239], v[244:247], v[50:65]
	v_mfma_f32_32x32x16_bf16 v[18:33], v[240:243], v[244:247], v[18:33]
	ds_read_b128 v[244:247], v0 offset:20480
	v_add_u32_e32 v0, s51, v191
	s_waitcnt lgkmcnt(0)
	v_mfma_f32_32x32x16_bf16 v[34:49], v[236:239], v[244:247], v[34:49]
	v_mfma_f32_32x32x16_bf16 v[2:17], v[240:243], v[244:247], v[2:17]
	ds_read_b128 v[236:239], v0
	ds_read_b128 v[240:243], v0 offset:4096
	v_add_u32_e32 v0, s51, v194
	ds_read_b128 v[244:247], v0 offset:16384
	s_waitcnt lgkmcnt(0)
	v_mfma_f32_32x32x16_bf16 v[50:65], v[236:239], v[244:247], v[50:65]
	v_mfma_f32_32x32x16_bf16 v[18:33], v[240:243], v[244:247], v[18:33]
	ds_read_b128 v[244:247], v0 offset:20480
	s_waitcnt vmcnt(0)
	s_waitcnt vmcnt(0) lgkmcnt(0)
	s_barrier
	v_mfma_f32_32x32x16_bf16 v[34:49], v[236:239], v[244:247], v[34:49]
	v_mfma_f32_32x32x16_bf16 v[2:17], v[240:243], v[244:247], v[2:17]
	s_cbranch_scc0 .LBB0_965
	s_lshl_b32 s2, s2, 15
	s_and_b32 s2, s2, 0x8000
	s_add_i32 s2, s2, 0
	v_cvt_pk_bf16_f32 v236, v155, v156
	v_cvt_pk_bf16_f32 v156, v157, v158
	v_add_u32_e32 v157, s2, v217
	v_cvt_pk_bf16_f32 v240, v153, v154
	v_cvt_pk_bf16_f32 v155, v159, v160
	v_cvt_pk_bf16_f32 v153, v161, v162
	v_cvt_pk_bf16_f32 v144, v163, v164
	v_cvt_pk_bf16_f32 v143, v165, v166
	ds_read_b128 v[158:161], v157
	ds_read_b128 v[162:165], v157 offset:4096
	v_add_u32_e32 v157, s2, v232
	v_cvt_pk_bf16_f32 v142, v167, v168
	v_cvt_pk_bf16_f32 v77, v169, v170
	ds_read_b128 v[166:169], v157 offset:16384
	s_waitcnt lgkmcnt(0)
	v_mfma_f32_32x32x16_bf16 v[50:65], v[158:161], v[166:169], v[50:65]
	v_cvt_pk_bf16_f32 v237, v147, v148
	v_cvt_pk_bf16_f32 v238, v149, v150
	v_cvt_pk_bf16_f32 v239, v151, v152
	v_cvt_pk_bf16_f32 v154, v179, v180
	v_cvt_pk_bf16_f32 v152, v181, v182
	v_cvt_pk_bf16_f32 v151, v183, v184
	v_cvt_pk_bf16_f32 v150, v185, v186
	v_mfma_f32_32x32x16_bf16 v[18:33], v[162:165], v[166:169], v[18:33]
	ds_read_b128 v[166:169], v157 offset:20480
	v_add_u32_e32 v157, s2, v209
	v_cvt_pk_bf16_f32 v149, v187, v188
	v_cvt_pk_bf16_f32 v148, v189, v190
	v_cvt_pk_bf16_f32 v147, v192, v193
	v_cvt_pk_bf16_f32 v145, v195, v197
	v_cvt_pk_bf16_f32 v76, v171, v172
	s_waitcnt lgkmcnt(0)
	v_mfma_f32_32x32x16_bf16 v[34:49], v[158:161], v[166:169], v[34:49]
	v_cvt_pk_bf16_f32 v75, v173, v174
	v_cvt_pk_bf16_f32 v74, v175, v176
	v_cvt_pk_bf16_f32 v72, v177, v178
	v_cvt_pk_bf16_f32 v73, v203, v204
	v_cvt_pk_bf16_f32 v71, v206, v207
	v_cvt_pk_bf16_f32 v70, v208, v210
	v_cvt_pk_bf16_f32 v69, v211, v213
	v_mfma_f32_32x32x16_bf16 v[2:17], v[162:165], v[166:169], v[2:17]
	ds_read_b128 v[158:161], v157
	ds_read_b128 v[162:165], v157 offset:4096
	v_add_u32_e32 v157, s2, v212
	ds_read_b128 v[166:169], v157 offset:16384
	v_cvt_pk_bf16_f32 v68, v214, v215
	v_cvt_pk_bf16_f32 v67, v216, v230
	v_cvt_pk_bf16_f32 v66, v231, v233
	v_cvt_pk_bf16_f32 v0, v234, v235
	s_waitcnt lgkmcnt(0)
	v_mfma_f32_32x32x16_bf16 v[50:65], v[158:161], v[166:169], v[50:65]
	s_add_i32 s50, s50, 1
	s_add_i32 s72, s72, 0x110000
	s_cmp_eq_u32 s50, 3
	v_mfma_f32_32x32x16_bf16 v[18:33], v[162:165], v[166:169], v[18:33]
	ds_read_b128 v[166:169], v157 offset:20480
	v_add_u32_e32 v157, s2, v196
	s_waitcnt lgkmcnt(0)
	v_mfma_f32_32x32x16_bf16 v[34:49], v[158:161], v[166:169], v[34:49]
	v_mfma_f32_32x32x16_bf16 v[2:17], v[162:165], v[166:169], v[2:17]
	ds_read_b128 v[158:161], v157
	ds_read_b128 v[162:165], v157 offset:4096
	v_add_u32_e32 v157, s2, v202
	ds_read_b128 v[166:169], v157 offset:16384
	s_waitcnt lgkmcnt(0)
	v_mfma_f32_32x32x16_bf16 v[50:65], v[158:161], v[166:169], v[50:65]
	v_mfma_f32_32x32x16_bf16 v[18:33], v[162:165], v[166:169], v[18:33]
	ds_read_b128 v[166:169], v157 offset:20480
	v_add_u32_e32 v157, s2, v191
	s_waitcnt lgkmcnt(0)
	v_mfma_f32_32x32x16_bf16 v[34:49], v[158:161], v[166:169], v[34:49]
	v_mfma_f32_32x32x16_bf16 v[2:17], v[162:165], v[166:169], v[2:17]
	ds_read_b128 v[158:161], v157
	ds_read_b128 v[162:165], v157 offset:4096
	v_add_u32_e32 v157, s2, v194
	ds_read_b128 v[166:169], v157 offset:16384
	s_waitcnt lgkmcnt(0)
	v_mfma_f32_32x32x16_bf16 v[50:65], v[158:161], v[166:169], v[50:65]
	v_mfma_f32_32x32x16_bf16 v[18:33], v[162:165], v[166:169], v[18:33]
	ds_read_b128 v[166:169], v157 offset:20480
	s_waitcnt vmcnt(0)
	s_waitcnt lgkmcnt(0)
	s_barrier
; DI void phase_merge(const Ctx& c) {
;     ...
;         for (int i = 0; i < 2; ++i)
; #pragma unroll
;           for (int j = 0; j < 2; ++j)
; #pragma unroll
;             for (int r2 = 0; r2 < 8; ++r2) {
;               const unsigned g2 = gp[i][j][r2];
;               macc[i][j][2 * r2] += __uint_as_float(g2 << 16) * acc[i][j][2 * r2];
;               macc[i][j][2 * r2 + 1] += __uint_as_float(g2 & 0xffff0000u) * acc[i][j][2 * r2 + 1];
;             }
	v_mfma_f32_32x32x16_bf16 v[34:49], v[158:161], v[166:169], v[34:49]
	s_setprio 0
	v_lshlrev_b32_e32 v158, 16, v237
	v_and_b32_e32 v159, 0xffff0000, v237
	s_nop 4
	v_fma_f32 v104, v50, v158, v104
	v_fma_f32 v105, v51, v159, v105
	v_lshlrev_b32_e32 v50, 16, v238
	v_and_b32_e32 v51, 0xffff0000, v238
	v_pk_fma_f32 v[102:103], v[52:53], v[50:51], v[102:103]
	v_lshlrev_b32_e32 v50, 16, v239
	v_and_b32_e32 v51, 0xffff0000, v239
	v_pk_fma_f32 v[98:99], v[54:55], v[50:51], v[98:99]
	v_lshlrev_b32_e32 v50, 16, v240
	v_and_b32_e32 v51, 0xffff0000, v240
	v_pk_fma_f32 v[94:95], v[56:57], v[50:51], v[94:95]
	v_lshlrev_b32_e32 v50, 16, v236
	v_and_b32_e32 v51, 0xffff0000, v236
	v_pk_fma_f32 v[92:93], v[58:59], v[50:51], v[92:93]
	v_lshlrev_b32_e32 v50, 16, v156
	v_and_b32_e32 v51, 0xffff0000, v156
	v_pk_fma_f32 v[88:89], v[60:61], v[50:51], v[88:89]
	v_lshlrev_b32_e32 v50, 16, v155
	v_and_b32_e32 v51, 0xffff0000, v155
	v_pk_fma_f32 v[84:85], v[62:63], v[50:51], v[84:85]
	v_lshlrev_b32_e32 v50, 16, v153
	v_and_b32_e32 v51, 0xffff0000, v153
	v_pk_fma_f32 v[78:79], v[64:65], v[50:51], v[78:79]
	v_lshlrev_b32_e32 v50, 16, v154
	v_and_b32_e32 v51, 0xffff0000, v154
	v_pk_fma_f32 v[132:133], v[34:35], v[50:51], v[132:133]
	v_lshlrev_b32_e32 v34, 16, v152
	v_and_b32_e32 v35, 0xffff0000, v152
	v_pk_fma_f32 v[130:131], v[36:37], v[34:35], v[130:131]
	v_lshlrev_b32_e32 v34, 16, v151
	v_and_b32_e32 v35, 0xffff0000, v151
	v_pk_fma_f32 v[126:127], v[38:39], v[34:35], v[126:127]
	v_lshlrev_b32_e32 v34, 16, v150
	v_and_b32_e32 v35, 0xffff0000, v150
	v_pk_fma_f32 v[122:123], v[40:41], v[34:35], v[122:123]
	v_lshlrev_b32_e32 v34, 16, v149
	v_and_b32_e32 v35, 0xffff0000, v149
	v_pk_fma_f32 v[120:121], v[42:43], v[34:35], v[120:121]
	v_lshlrev_b32_e32 v34, 16, v148
	v_and_b32_e32 v35, 0xffff0000, v148
	v_pk_fma_f32 v[116:117], v[44:45], v[34:35], v[116:117]
	v_lshlrev_b32_e32 v34, 16, v147
	v_and_b32_e32 v35, 0xffff0000, v147
	v_pk_fma_f32 v[114:115], v[46:47], v[34:35], v[114:115]
	v_lshlrev_b32_e32 v34, 16, v145
	v_and_b32_e32 v35, 0xffff0000, v145
	v_pk_fma_f32 v[82:83], v[48:49], v[34:35], v[82:83]
	v_lshlrev_b32_e32 v34, 16, v144
	v_and_b32_e32 v35, 0xffff0000, v144
	v_mfma_f32_32x32x16_bf16 v[2:17], v[162:165], v[166:169], v[2:17]
	v_fma_f32 v112, v18, v34, v112
	v_fma_f32 v113, v19, v35, v113
	v_lshlrev_b32_e32 v18, 16, v143
	v_and_b32_e32 v19, 0xffff0000, v143
	v_fma_f32 v110, v20, v18, v110
	v_fma_f32 v111, v21, v19, v111
	v_lshlrev_b32_e32 v18, 16, v142
	v_and_b32_e32 v19, 0xffff0000, v142
	v_pk_fma_f32 v[108:109], v[22:23], v[18:19], v[108:109]
	v_lshlrev_b32_e32 v18, 16, v77
	v_and_b32_e32 v19, 0xffff0000, v77
	v_pk_fma_f32 v[106:107], v[24:25], v[18:19], v[106:107]
	v_lshlrev_b32_e32 v18, 16, v76
	v_and_b32_e32 v19, 0xffff0000, v76
	v_pk_fma_f32 v[100:101], v[26:27], v[18:19], v[100:101]
	v_lshlrev_b32_e32 v18, 16, v75
	v_and_b32_e32 v19, 0xffff0000, v75
	v_pk_fma_f32 v[96:97], v[28:29], v[18:19], v[96:97]
	v_lshlrev_b32_e32 v18, 16, v74
	v_and_b32_e32 v19, 0xffff0000, v74
	v_pk_fma_f32 v[90:91], v[30:31], v[18:19], v[90:91]
	v_lshlrev_b32_e32 v18, 16, v72
	v_and_b32_e32 v19, 0xffff0000, v72
	v_pk_fma_f32 v[80:81], v[32:33], v[18:19], v[80:81]
	v_lshlrev_b32_e32 v18, 16, v73
	v_and_b32_e32 v19, 0xffff0000, v73
	v_pk_fma_f32 v[140:141], v[2:3], v[18:19], v[140:141]
	v_lshlrev_b32_e32 v2, 16, v71
	v_and_b32_e32 v3, 0xffff0000, v71
	v_pk_fma_f32 v[138:139], v[4:5], v[2:3], v[138:139]
	v_lshlrev_b32_e32 v2, 16, v70
	v_and_b32_e32 v3, 0xffff0000, v70
	v_pk_fma_f32 v[136:137], v[6:7], v[2:3], v[136:137]
	v_lshlrev_b32_e32 v2, 16, v69
	v_and_b32_e32 v3, 0xffff0000, v69
	v_pk_fma_f32 v[134:135], v[8:9], v[2:3], v[134:135]
	v_lshlrev_b32_e32 v2, 16, v68
	v_and_b32_e32 v3, 0xffff0000, v68
	v_pk_fma_f32 v[128:129], v[10:11], v[2:3], v[128:129]
	v_lshlrev_b32_e32 v2, 16, v67
	v_and_b32_e32 v3, 0xffff0000, v67
	v_pk_fma_f32 v[124:125], v[12:13], v[2:3], v[124:125]
	v_lshlrev_b32_e32 v2, 16, v66
	v_and_b32_e32 v3, 0xffff0000, v66
	v_pk_fma_f32 v[118:119], v[14:15], v[2:3], v[118:119]
	v_lshlrev_b32_e32 v2, 16, v0
	v_and_b32_e32 v3, 0xffff0000, v0
	v_pk_fma_f32 v[86:87], v[16:17], v[2:3], v[86:87]
	s_cbranch_scc0 .LBB0_962
; DI int tid_() { int t = threadIdx.x; asm volatile("" : "+v"(t)); return t; }
; DI unsigned pk2(float a, float b) { f32x2 v = {a, b}; bf16x2_t r = __builtin_convertvector(v, bf16x2_t); return __builtin_bit_cast(unsigned, r); }
; template <int NJ> DI void acc_to_lds(const f32x16 (&acc)[2][NJ], float* cl) {
;   const int tid = tid_(), lane = tid & 63, w = tid >> 6, wm = w >> 1, wn = w & 1, h = lane >> 5, c = lane & 31;
; #pragma unroll
;   for (int i = 0; i < 2; ++i)
; #pragma unroll
;     for (int j = 0; j < NJ; ++j)
; #pragma unroll
;       for (int r = 0; r < 16; ++r) {
;         const int row = wm * 64 + i * 32 + (r & 3) + 8 * (r >> 2) + 4 * h;
;         cl[row * CLD + wn * 32 * NJ + j * 32 + c] = acc[i][j][r];
;       }
; DI void phase_merge(const Ctx& c) {
;     ...
;     acc_to_lds<2>(macc, cl);
;     __syncthreads();
;     const int tid = tid_();
;     const int c4 = (tid & 31) * 4, r0 = tid >> 5;
; #pragma unroll 4
;     for (int it = 0; it < 16; ++it) {
;       const int row = r0 + 8 * it;
;       const f32x4 v = *(const f32x4*)(cl + row * CLD + c4);
;       u32x2 p; p.x = pk2(v[0], v[1]); p.y = pk2(v[2], v[3]);
;       *(u32x2*)(mrg + (size_t)(mt * 128 + row) * LDX + nt * 128 + c4) = p;
	v_mov_b32_e32 v0, v199
	s_lshl_b32 s72, s47, 8
	v_lshrrev_b32_e32 v3, 3, v0
	v_lshrrev_b32_e32 v2, 1, v0
	v_and_b32_e32 v3, 4, v3
	v_and_b32_e32 v0, 0x5f, v0
	v_and_or_b32 v2, v2, s17, v3
	v_mul_lo_u32 v2, v2, s15
	v_lshlrev_b32_e32 v0, 2, v0
	v_add3_u32 v0, 0, v2, v0
	v_add_u32_e32 v2, 0x400, v0
	ds_write2_b32 v0, v104, v132 offset1:32
	ds_write2_b32 v0, v105, v133 offset0:132 offset1:164
	ds_write2_b32 v2, v102, v130 offset0:8 offset1:40
	ds_write2_b32 v2, v103, v131 offset0:140 offset1:172
	v_add_u32_e32 v2, 0x1000, v0
	ds_write2_b32 v2, v98, v126 offset0:32 offset1:64
	ds_write2_b32 v2, v99, v127 offset0:164 offset1:196
	v_add_u32_e32 v2, 0x1400, v0
	ds_write2_b32 v2, v94, v122 offset0:40 offset1:72
	ds_write2_b32 v2, v95, v123 offset0:172 offset1:204
	v_add_u32_e32 v2, 0x2000, v0
	ds_write2_b32 v2, v92, v120 offset0:64 offset1:96
	ds_write2_b32 v2, v93, v121 offset0:196 offset1:228
	v_add_u32_e32 v2, 0x2400, v0
	ds_write2_b32 v2, v88, v116 offset0:72 offset1:104
	ds_write2_b32 v2, v89, v117 offset0:204 offset1:236
	v_add_u32_e32 v2, 0x3000, v0
	ds_write2_b32 v2, v84, v114 offset0:96 offset1:128
	v_add_u32_e32 v2, 0x3200, v0
	ds_write2_b32 v2, v85, v115 offset0:100 offset1:132
	v_add_u32_e32 v2, 0x3400, v0
	ds_write2_b32 v2, v78, v82 offset0:104 offset1:136
	v_add_u32_e32 v2, 0x3600, v0
	ds_write2_b32 v2, v79, v83 offset0:108 offset1:140
	v_add_u32_e32 v2, 0x4000, v0
	ds_write2_b32 v2, v112, v140 offset0:128 offset1:160
	v_add_u32_e32 v2, 0x4400, v0
	ds_write2_b32 v2, v113, v141 offset0:4 offset1:36
	ds_write2_b32 v2, v110, v138 offset0:136 offset1:168
	v_add_u32_e32 v2, 0x4800, v0
	ds_write2_b32 v2, v111, v139 offset0:12 offset1:44
	v_add_u32_e32 v2, 0x5000, v0
	ds_write2_b32 v2, v108, v136 offset0:160 offset1:192
	v_add_u32_e32 v2, 0x5400, v0
	ds_write2_b32 v2, v109, v137 offset0:36 offset1:68
	ds_write2_b32 v2, v106, v134 offset0:168 offset1:200
	v_add_u32_e32 v2, 0x5800, v0
	ds_write2_b32 v2, v107, v135 offset0:44 offset1:76
	v_add_u32_e32 v2, 0x6000, v0
	ds_write2_b32 v2, v100, v128 offset0:192 offset1:224
	v_add_u32_e32 v2, 0x6400, v0
	ds_write2_b32 v2, v101, v129 offset0:68 offset1:100
	ds_write2_b32 v2, v96, v124 offset0:200 offset1:232
	v_add_u32_e32 v2, 0x6800, v0
	ds_write2_b32 v2, v97, v125 offset0:76 offset1:108
	v_add_u32_e32 v2, 0x7200, v0
	ds_write2_b32 v2, v90, v118 offset0:96 offset1:128
	v_add_u32_e32 v2, 0x7400, v0
	ds_write2_b32 v2, v91, v119 offset0:100 offset1:132
	v_add_u32_e32 v2, 0x7600, v0
	v_add_u32_e32 v0, 0x7800, v0
	ds_write2_b32 v0, v81, v87 offset0:108 offset1:140
	v_mov_b32_e32 v0, v199
	ds_write2_b32 v2, v80, v86 offset0:104 offset1:136
	s_waitcnt lgkmcnt(0)
	s_barrier
	s_add_i32 s2, s45, s11
	v_ashrrev_i32_e32 v11, 5, v0
	v_add_u32_e32 v2, s2, v11
	v_mov_b64_e32 v[8:9], s[72:73]
	v_mad_i64_i32 v[2:3], s[2:3], v2, s9, v[8:9]
	v_and_b32_e32 v4, 31, v0
	v_lshlrev_b32_e32 v0, 3, v4
	v_mul_lo_u32 v5, v11, s15
	v_lshlrev_b32_e32 v4, 4, v4
	s_add_i32 s2, s45, s12
	s_add_i32 s45, s45, s13
	v_add3_u32 v10, v5, v4, 0
	v_add_u32_e32 v4, s2, v11
	v_add_u32_e32 v6, s45, v11
	v_add_u32_e32 v11, s44, v11
	v_mad_i64_i32 v[4:5], s[2:3], v4, s9, v[8:9]
	v_mad_i64_i32 v[6:7], s[2:3], v6, s9, v[8:9]
	v_mad_i64_i32 v[8:9], s[2:3], v11, s9, v[8:9]
	v_lshl_add_u64 v[2:3], v[2:3], 0, v[0:1]
	v_lshl_add_u64 v[4:5], v[4:5], 0, v[0:1]
	v_lshl_add_u64 v[6:7], v[6:7], 0, v[0:1]
	v_lshl_add_u64 v[8:9], v[8:9], 0, v[0:1]
	v_lshl_add_u64 v[2:3], s[74:75], 0, v[2:3]
	v_lshl_add_u64 v[4:5], s[74:75], 0, v[4:5]
	v_lshl_add_u64 v[6:7], s[74:75], 0, v[6:7]
	v_lshl_add_u64 v[8:9], s[74:75], 0, v[8:9]
	s_mov_b64 s[2:3], 0

; DI int tid_() { int t = threadIdx.x; asm volatile("" : "+v"(t)); return t; }
; #define GL1_(RA, RB, i) { RA[i] = *(const u32x4*)(ap + (aoff + (i) * astep)); if ((i) < NB) RB[(i) < NB ? (i) : 0] = *(const u32x4*)(bp + (boff + (i) * bstep)); }
; #define LS1_(RA, RB, ST, i) { char* sn_ = lds + (ST) * STAGE; *(u32x4*)(sn_ + wofs + (i) * 32 * LROW) = RA[i]; \
;                               if ((i) < NB) *(u32x4*)(sn_ + STAGE_OP + wofs + (i) * 32 * LROW) = RB[(i) < NB ? (i) : 0]; }
; template <int NJ> DI void gemm_mainloop_reg(const bf16_t* __restrict__ A, int lda, const bf16_t* __restrict__ Bt, int ldb, int K, f32x16 (&acc)[2][NJ], char* lds) {
;   const int tid = tid_(), lane = tid & 63, w = tid >> 6, wm = w >> 1, wn = w & 1;
;   const int lr = tid >> 3, lc = tid & 7;
;   const char* ap = (const char*)A;
;   const char* bp = (const char*)Bt;
;   const unsigned aoff = (unsigned)(lr * lda + lc * 8) * 2u, boff = (unsigned)(lr * ldb + lc * 8) * 2u;
;   const unsigned astep = (unsigned)(32 * lda) * 2u, bstep = (unsigned)(32 * ldb) * 2u;
;   constexpr int NB = 2 * NJ;
;   u32x4 ra0[4], rb0[NB], ra1[4], rb1[NB];
;   const int wofs = lr * LROW + lc * 16;
;   const int a_rd = (wm * 64 + (lane & 31)) * LROW + (lane >> 5) * 16;
;   const int b_rd = STAGE_OP + (wn * 32 * NJ + (lane & 31)) * LROW + (lane >> 5) * 16;
;     ...
; #pragma unroll
;   for (int i = 0; i < 4; ++i) GL1_(ra0, rb0, i);
;   ap += 128; bp += 128;
; #pragma unroll
;   for (int i = 0; i < 4; ++i) GL1_(ra1, rb1, i);
;   ap += 128; bp += 128;
; #pragma unroll
;   for (int i = 0; i < 4; ++i) LS1_(ra0, rb0, 0, i);
;   __syncthreads();
;   const int nk = K >> 6;
;   for (int kt = 0; kt < nk; kt += 2) {
;     const bool l0 = (kt + 2 < nk), l1 = (kt + 3 < nk);
;     STEP_(0, l0, ra0, rb0, true, ra1, rb1);
;     __syncthreads();
;     STEP_(1, l1, ra1, rb1, l0, ra0, rb0);
;     __syncthreads();
;   }
.LBB0_1025:
	s_and_b32 s0, s26, 15
	s_lshl_b32 s35, s0, 7
	s_lshl_b32 s0, s25, 1
	s_and_b32 s72, s0, 0x700
	s_lshl_b32 s0, s25, 2
	s_and_b32 s34, s0, 0xe00
	s_and_b32 s0, s27, 15
	s_add_i32 s37, s10, s35
	s_or_b32 s0, s0, s78
	s_lshl_b32 s36, s37, 2
	s_mul_i32 s0, s0, 0x44000
	s_add_u32 s0, s74, s0
	v_mov_b32_e32 v34, v199
	s_addc_u32 s1, s75, 0
	s_lshl_b32 s2, s27, 3
	s_and_b32 s2, s2, 0x380
	v_ashrrev_i32_e32 v0, 3, v34
	v_lshlrev_b32_e32 v2, 4, v34
	v_and_b32_e32 v35, 0x70, v2
	v_mul_lo_u32 v2, v0, s9
	s_mulk_i32 s2, 0x880
	v_or_b32_e32 v72, v35, v2
	s_add_u32 s2, s4, s2
	v_add_u32_e32 v71, 0x11000, v72
	v_add_u32_e32 v70, 0x22000, v72
	v_add_u32_e32 v69, 0x33000, v72
	s_addc_u32 s3, s5, 0
	global_load_dwordx4 v[2:5], v72, s[0:1]
	global_load_dwordx4 v[6:9], v71, s[0:1]
	global_load_dwordx4 v[10:13], v70, s[0:1]
	global_load_dwordx4 v[14:17], v69, s[0:1]
	global_load_dwordx4 v[18:21], v72, s[2:3]
	global_load_dwordx4 v[22:25], v71, s[2:3]
	global_load_dwordx4 v[26:29], v70, s[2:3]
	global_load_dwordx4 v[30:33], v69, s[2:3]
	v_mul_lo_u32 v0, v0, s16
	v_lshrrev_b32_e32 v36, 1, v34
	v_and_b32_e32 v37, 31, v34
	v_add3_u32 v67, v0, v35, 0
	v_and_b32_e32 v38, 16, v36
	v_and_or_b32 v36, v36, s17, v37
	global_load_dwordx4 v[74:77], v72, s[0:1] offset:128
	global_load_dwordx4 v[78:81], v71, s[0:1] offset:128
	global_load_dwordx4 v[82:85], v70, s[0:1] offset:128
	global_load_dwordx4 v[86:89], v69, s[0:1] offset:128
	global_load_dwordx4 v[90:93], v72, s[2:3] offset:128
	global_load_dwordx4 v[94:97], v71, s[2:3] offset:128
	global_load_dwordx4 v[98:101], v70, s[2:3] offset:128
	global_load_dwordx4 v[102:105], v69, s[2:3] offset:128
	v_mul_lo_u32 v0, v36, s16
	v_add3_u32 v0, v0, v38, 0
	v_add_u32_e32 v68, 0xd800, v67
	s_waitcnt vmcnt(15)
	ds_write_b128 v67, v[2:5]
	s_waitcnt vmcnt(14)
	ds_write_b128 v67, v[6:9] offset:4608
	s_waitcnt vmcnt(13)
	ds_write_b128 v67, v[10:13] offset:9216
	s_waitcnt vmcnt(12)
	ds_write_b128 v67, v[14:17] offset:13824
	s_waitcnt vmcnt(11)
	ds_write_b128 v67, v[18:21] offset:18432
	s_waitcnt vmcnt(10)
	ds_write_b128 v67, v[22:25] offset:23040
	s_waitcnt vmcnt(9)
	ds_write_b128 v67, v[26:29] offset:27648
	s_waitcnt vmcnt(8)
	ds_write_b128 v67, v[30:33] offset:32256
	v_and_b32_e32 v2, 0x5f, v34
	v_mul_u32_u24_e32 v2, 0x90, v2
	v_add3_u32 v66, v2, v38, 0
	s_waitcnt lgkmcnt(0)
	s_barrier
	ds_read_b128 v[18:21], v0
	ds_read_b128 v[2:5], v66 offset:18432
	ds_read_b128 v[106:109], v0 offset:32
	ds_read_b128 v[110:113], v66 offset:18464
	ds_read_b128 v[22:25], v0 offset:4608
	ds_read_b128 v[114:117], v0 offset:4640
	ds_read_b128 v[26:29], v66 offset:23040
	ds_read_b128 v[118:121], v66 offset:23072
	global_load_dwordx4 v[122:125], v72, s[0:1] offset:256
	global_load_dwordx4 v[126:129], v72, s[2:3] offset:256
	s_waitcnt lgkmcnt(6)
	s_setprio 1
	v_mfma_f32_32x32x16_bf16 v[34:49], v[18:21], v[2:5], 0
	s_waitcnt vmcnt(9)
	ds_write_b128 v67, v[74:77] offset:36864
	s_waitcnt vmcnt(5)
	ds_write_b128 v67, v[90:93] offset:55296
	s_waitcnt lgkmcnt(5)
	v_mfma_f32_32x32x16_bf16 v[2:17], v[22:25], v[2:5], 0
	s_waitcnt lgkmcnt(3)
	v_mfma_f32_32x32x16_bf16 v[50:65], v[18:21], v[26:29], 0
	v_mfma_f32_32x32x16_bf16 v[18:33], v[22:25], v[26:29], 0
	global_load_dwordx4 v[74:77], v71, s[0:1] offset:256
	global_load_dwordx4 v[90:93], v71, s[2:3] offset:256
	v_mfma_f32_32x32x16_bf16 v[2:17], v[114:117], v[110:113], v[2:17]
	s_waitcnt lgkmcnt(2)
	v_mfma_f32_32x32x16_bf16 v[18:33], v[114:117], v[118:121], v[18:33]
	v_mfma_f32_32x32x16_bf16 v[34:49], v[106:109], v[110:113], v[34:49]
	v_mfma_f32_32x32x16_bf16 v[50:65], v[106:109], v[118:121], v[50:65]
	ds_read_b128 v[106:109], v0 offset:64
	ds_read_b128 v[110:113], v0 offset:4672
	ds_read_b128 v[130:133], v66 offset:18496
	ds_read_b128 v[134:137], v66 offset:23104
	ds_write_b128 v67, v[78:81] offset:41472
	s_waitcnt vmcnt(6)
	ds_write_b128 v67, v[94:97] offset:59904
	global_load_dwordx4 v[78:81], v70, s[0:1] offset:256
	global_load_dwordx4 v[94:97], v70, s[2:3] offset:256
	s_waitcnt lgkmcnt(3)
	v_mfma_f32_32x32x16_bf16 v[2:17], v[110:113], v[130:133], v[2:17]
	s_waitcnt lgkmcnt(2)
	v_mfma_f32_32x32x16_bf16 v[18:33], v[110:113], v[134:137], v[18:33]
	v_mfma_f32_32x32x16_bf16 v[34:49], v[106:109], v[130:133], v[34:49]
	v_mfma_f32_32x32x16_bf16 v[50:65], v[106:109], v[134:137], v[50:65]
	ds_read_b128 v[106:109], v0 offset:96
	ds_read_b128 v[114:117], v0 offset:4704
	ds_read_b128 v[118:121], v66 offset:18528
	ds_read_b128 v[130:133], v66 offset:23136
	ds_write_b128 v67, v[82:85] offset:46080
	s_waitcnt vmcnt(7)
	ds_write_b128 v67, v[98:101] offset:64512
	global_load_dwordx4 v[82:85], v69, s[0:1] offset:256
	global_load_dwordx4 v[98:101], v69, s[2:3] offset:256
	s_waitcnt lgkmcnt(3)
	v_mfma_f32_32x32x16_bf16 v[2:17], v[114:117], v[118:121], v[2:17]
	ds_write_b128 v67, v[86:89] offset:50688
	s_waitcnt vmcnt(8)
	ds_write_b128 v68, v[102:105] offset:13824
	s_waitcnt lgkmcnt(4)
	v_mfma_f32_32x32x16_bf16 v[18:33], v[114:117], v[130:133], v[18:33]
	v_mfma_f32_32x32x16_bf16 v[34:49], v[106:109], v[118:121], v[34:49]
	v_mfma_f32_32x32x16_bf16 v[50:65], v[106:109], v[130:133], v[50:65]
	s_waitcnt lgkmcnt(0)
	s_barrier
; #define GL1_(RA, RB, i) { RA[i] = *(const u32x4*)(ap + (aoff + (i) * astep)); if ((i) < NB) RB[(i) < NB ? (i) : 0] = *(const u32x4*)(bp + (boff + (i) * bstep)); }
; #define LS1_(RA, RB, ST, i) { char* sn_ = lds + (ST) * STAGE; *(u32x4*)(sn_ + wofs + (i) * 32 * LROW) = RA[i]; \
;                               if ((i) < NB) *(u32x4*)(sn_ + STAGE_OP + wofs + (i) * 32 * LROW) = RB[(i) < NB ? (i) : 0]; }
; template <int NJ> DI void gemm_mainloop_reg(const bf16_t* __restrict__ A, int lda, const bf16_t* __restrict__ Bt, int ldb, int K, f32x16 (&acc)[2][NJ], char* lds) {
;     ...
; #pragma unroll
;   for (int i = 0; i < 4; ++i) GL1_(ra0, rb0, i);
;   ap += 128; bp += 128;
; #pragma unroll
;   for (int i = 0; i < 4; ++i) GL1_(ra1, rb1, i);
;   ap += 128; bp += 128;
; #pragma unroll
;   for (int i = 0; i < 4; ++i) LS1_(ra0, rb0, 0, i);
;   __syncthreads();
;   const int nk = K >> 6;
;   for (int kt = 0; kt < nk; kt += 2) {
;     const bool l0 = (kt + 2 < nk), l1 = (kt + 3 < nk);
;     STEP_(0, l0, ra0, rb0, true, ra1, rb1);
;     __syncthreads();
;     STEP_(1, l1, ra1, rb1, l0, ra0, rb0);
;     __syncthreads();
;   }
	ds_read_b128 v[86:89], v0 offset:36864
	ds_read_b128 v[102:105], v66 offset:55296
	ds_read_b128 v[106:109], v0 offset:36896
	ds_read_b128 v[110:113], v66 offset:55328
	ds_read_b128 v[114:117], v0 offset:41472
	ds_read_b128 v[118:121], v0 offset:41504
	s_waitcnt lgkmcnt(4)
	v_mfma_f32_32x32x16_bf16 v[34:49], v[86:89], v[102:105], v[34:49]
	s_waitcnt lgkmcnt(1)
	v_mfma_f32_32x32x16_bf16 v[2:17], v[114:117], v[102:105], v[2:17]
	ds_read_b128 v[102:105], v66 offset:59904
	ds_read_b128 v[130:133], v66 offset:59936
	s_waitcnt lgkmcnt(1)
	v_mfma_f32_32x32x16_bf16 v[50:65], v[86:89], v[102:105], v[50:65]
	global_load_dwordx4 v[86:89], v72, s[0:1] offset:384
	global_load_dwordx4 v[134:137], v72, s[2:3] offset:384
	s_waitcnt vmcnt(9)
	ds_write_b128 v67, v[122:125]
	s_waitcnt vmcnt(8)
	ds_write_b128 v67, v[126:129] offset:18432
	v_mfma_f32_32x32x16_bf16 v[18:33], v[114:117], v[102:105], v[18:33]
	v_mfma_f32_32x32x16_bf16 v[34:49], v[106:109], v[110:113], v[34:49]
	s_waitcnt lgkmcnt(2)
	v_mfma_f32_32x32x16_bf16 v[50:65], v[106:109], v[130:133], v[50:65]
	global_load_dwordx4 v[102:105], v71, s[0:1] offset:384
	global_load_dwordx4 v[106:109], v71, s[2:3] offset:384
	v_mfma_f32_32x32x16_bf16 v[2:17], v[118:121], v[110:113], v[2:17]
	ds_read_b128 v[110:113], v0 offset:36928
	ds_read_b128 v[114:117], v0 offset:41536
	ds_read_b128 v[122:125], v66 offset:55360
	ds_read_b128 v[126:129], v66 offset:59968
	s_waitcnt vmcnt(9)
	ds_write_b128 v67, v[74:77] offset:4608
	s_waitcnt vmcnt(8)
	ds_write_b128 v67, v[90:93] offset:23040
	v_mfma_f32_32x32x16_bf16 v[18:33], v[118:121], v[130:133], v[18:33]
	global_load_dwordx4 v[74:77], v70, s[0:1] offset:384
	global_load_dwordx4 v[90:93], v70, s[2:3] offset:384
	s_waitcnt lgkmcnt(3)
	v_mfma_f32_32x32x16_bf16 v[2:17], v[114:117], v[122:125], v[2:17]
	s_waitcnt lgkmcnt(2)
	v_mfma_f32_32x32x16_bf16 v[18:33], v[114:117], v[126:129], v[18:33]
	v_mfma_f32_32x32x16_bf16 v[34:49], v[110:113], v[122:125], v[34:49]
	v_mfma_f32_32x32x16_bf16 v[50:65], v[110:113], v[126:129], v[50:65]
	ds_read_b128 v[110:113], v0 offset:36960
	ds_read_b128 v[118:121], v0 offset:41568
	ds_read_b128 v[122:125], v66 offset:55392
	ds_read_b128 v[130:133], v66 offset:60000
	s_waitcnt vmcnt(9)
	ds_write_b128 v67, v[78:81] offset:9216
	s_waitcnt vmcnt(8)
	ds_write_b128 v67, v[94:97] offset:27648
	global_load_dwordx4 v[78:81], v69, s[0:1] offset:384
	global_load_dwordx4 v[94:97], v69, s[2:3] offset:384
	s_waitcnt lgkmcnt(3)
	v_mfma_f32_32x32x16_bf16 v[2:17], v[118:121], v[122:125], v[2:17]
	s_waitcnt vmcnt(9)
	ds_write_b128 v67, v[82:85] offset:13824
	s_waitcnt vmcnt(8)
	ds_write_b128 v67, v[98:101] offset:32256
	s_waitcnt lgkmcnt(4)
	v_mfma_f32_32x32x16_bf16 v[18:33], v[118:121], v[130:133], v[18:33]
	v_mfma_f32_32x32x16_bf16 v[34:49], v[110:113], v[122:125], v[34:49]
	v_mfma_f32_32x32x16_bf16 v[50:65], v[110:113], v[130:133], v[50:65]
	s_waitcnt lgkmcnt(0)
	s_barrier
	ds_read_b128 v[82:85], v0
	ds_read_b128 v[98:101], v66 offset:18432
	ds_read_b128 v[110:113], v0 offset:32
	ds_read_b128 v[114:117], v66 offset:18464
	ds_read_b128 v[118:121], v0 offset:4608
	ds_read_b128 v[122:125], v0 offset:4640
	s_waitcnt lgkmcnt(4)
	v_mfma_f32_32x32x16_bf16 v[34:49], v[82:85], v[98:101], v[34:49]
	s_waitcnt lgkmcnt(1)
	v_mfma_f32_32x32x16_bf16 v[2:17], v[118:121], v[98:101], v[2:17]
	ds_read_b128 v[98:101], v66 offset:23040
	ds_read_b128 v[126:129], v66 offset:23072
	s_waitcnt lgkmcnt(1)
	v_mfma_f32_32x32x16_bf16 v[50:65], v[82:85], v[98:101], v[50:65]
	global_load_dwordx4 v[82:85], v72, s[0:1] offset:512
	global_load_dwordx4 v[130:133], v72, s[2:3] offset:512
	s_waitcnt vmcnt(9)
	ds_write_b128 v67, v[86:89] offset:36864
	s_waitcnt vmcnt(8)
	ds_write_b128 v67, v[134:137] offset:55296
	v_mfma_f32_32x32x16_bf16 v[18:33], v[118:121], v[98:101], v[18:33]
	global_load_dwordx4 v[86:89], v71, s[0:1] offset:512
	global_load_dwordx4 v[98:101], v71, s[2:3] offset:512
	v_mfma_f32_32x32x16_bf16 v[2:17], v[122:125], v[114:117], v[2:17]
	s_waitcnt lgkmcnt(2)
	v_mfma_f32_32x32x16_bf16 v[18:33], v[122:125], v[126:129], v[18:33]
	v_mfma_f32_32x32x16_bf16 v[34:49], v[110:113], v[114:117], v[34:49]
	v_mfma_f32_32x32x16_bf16 v[50:65], v[110:113], v[126:129], v[50:65]
	ds_read_b128 v[110:113], v0 offset:64
	ds_read_b128 v[114:117], v0 offset:4672
	ds_read_b128 v[118:121], v66 offset:18496
	ds_read_b128 v[134:137], v66 offset:23104
	s_waitcnt vmcnt(9)
	ds_write_b128 v67, v[102:105] offset:41472
	s_waitcnt vmcnt(8)
	ds_write_b128 v67, v[106:109] offset:59904
	global_load_dwordx4 v[102:105], v70, s[0:1] offset:512
	global_load_dwordx4 v[106:109], v70, s[2:3] offset:512
	s_waitcnt lgkmcnt(3)
	v_mfma_f32_32x32x16_bf16 v[2:17], v[114:117], v[118:121], v[2:17]
	s_waitcnt lgkmcnt(2)
	v_mfma_f32_32x32x16_bf16 v[18:33], v[114:117], v[134:137], v[18:33]
	v_mfma_f32_32x32x16_bf16 v[34:49], v[110:113], v[118:121], v[34:49]
	v_mfma_f32_32x32x16_bf16 v[50:65], v[110:113], v[134:137], v[50:65]
	ds_read_b128 v[110:113], v0 offset:96
	ds_read_b128 v[118:121], v0 offset:4704
	ds_read_b128 v[122:125], v66 offset:18528
	ds_read_b128 v[126:129], v66 offset:23136
	s_waitcnt vmcnt(9)
	ds_write_b128 v67, v[74:77] offset:46080
	s_waitcnt vmcnt(8)
	ds_write_b128 v67, v[90:93] offset:64512
	global_load_dwordx4 v[74:77], v69, s[0:1] offset:512
	global_load_dwordx4 v[90:93], v69, s[2:3] offset:512
	s_waitcnt lgkmcnt(3)
	v_mfma_f32_32x32x16_bf16 v[2:17], v[118:121], v[122:125], v[2:17]
	s_waitcnt vmcnt(9)
	ds_write_b128 v67, v[78:81] offset:50688
	s_waitcnt vmcnt(8)
	ds_write_b128 v68, v[94:97] offset:13824
	s_waitcnt lgkmcnt(4)
	v_mfma_f32_32x32x16_bf16 v[18:33], v[118:121], v[126:129], v[18:33]
	v_mfma_f32_32x32x16_bf16 v[34:49], v[110:113], v[122:125], v[34:49]
	v_mfma_f32_32x32x16_bf16 v[50:65], v[110:113], v[126:129], v[50:65]
	s_waitcnt lgkmcnt(0)
	s_barrier
; #define GL1_(RA, RB, i) { RA[i] = *(const u32x4*)(ap + (aoff + (i) * astep)); if ((i) < NB) RB[(i) < NB ? (i) : 0] = *(const u32x4*)(bp + (boff + (i) * bstep)); }
; #define LS1_(RA, RB, ST, i) { char* sn_ = lds + (ST) * STAGE; *(u32x4*)(sn_ + wofs + (i) * 32 * LROW) = RA[i]; \
;                               if ((i) < NB) *(u32x4*)(sn_ + STAGE_OP + wofs + (i) * 32 * LROW) = RB[(i) < NB ? (i) : 0]; }
; template <int NJ> DI void gemm_mainloop_reg(const bf16_t* __restrict__ A, int lda, const bf16_t* __restrict__ Bt, int ldb, int K, f32x16 (&acc)[2][NJ], char* lds) {
;     ...
; #pragma unroll
;   for (int i = 0; i < 4; ++i) GL1_(ra0, rb0, i);
;   ap += 128; bp += 128;
; #pragma unroll
;   for (int i = 0; i < 4; ++i) GL1_(ra1, rb1, i);
;   ap += 128; bp += 128;
; #pragma unroll
;   for (int i = 0; i < 4; ++i) LS1_(ra0, rb0, 0, i);
;   __syncthreads();
;   const int nk = K >> 6;
;   for (int kt = 0; kt < nk; kt += 2) {
;     const bool l0 = (kt + 2 < nk), l1 = (kt + 3 < nk);
;     STEP_(0, l0, ra0, rb0, true, ra1, rb1);
;     __syncthreads();
;     STEP_(1, l1, ra1, rb1, l0, ra0, rb0);
;     __syncthreads();
;   }
	ds_read_b128 v[78:81], v0 offset:36864
	ds_read_b128 v[94:97], v66 offset:55296
	ds_read_b128 v[110:113], v0 offset:36896
	ds_read_b128 v[114:117], v66 offset:55328
	ds_read_b128 v[118:121], v0 offset:41472
	ds_read_b128 v[122:125], v0 offset:41504
	s_waitcnt lgkmcnt(4)
	v_mfma_f32_32x32x16_bf16 v[34:49], v[78:81], v[94:97], v[34:49]
	s_waitcnt lgkmcnt(1)
	v_mfma_f32_32x32x16_bf16 v[2:17], v[118:121], v[94:97], v[2:17]
	ds_read_b128 v[94:97], v66 offset:59904
	ds_read_b128 v[126:129], v66 offset:59936
	s_waitcnt lgkmcnt(1)
	v_mfma_f32_32x32x16_bf16 v[50:65], v[78:81], v[94:97], v[50:65]
	global_load_dwordx4 v[78:81], v72, s[0:1] offset:640
	global_load_dwordx4 v[134:137], v72, s[2:3] offset:640
	s_waitcnt vmcnt(9)
	ds_write_b128 v67, v[82:85]
	s_waitcnt vmcnt(8)
	ds_write_b128 v67, v[130:133] offset:18432
	v_mfma_f32_32x32x16_bf16 v[18:33], v[118:121], v[94:97], v[18:33]
	global_load_dwordx4 v[82:85], v71, s[0:1] offset:640
	global_load_dwordx4 v[94:97], v71, s[2:3] offset:640
	v_mfma_f32_32x32x16_bf16 v[2:17], v[122:125], v[114:117], v[2:17]
	s_waitcnt lgkmcnt(2)
	v_mfma_f32_32x32x16_bf16 v[18:33], v[122:125], v[126:129], v[18:33]
	v_mfma_f32_32x32x16_bf16 v[34:49], v[110:113], v[114:117], v[34:49]
	v_mfma_f32_32x32x16_bf16 v[50:65], v[110:113], v[126:129], v[50:65]
	ds_read_b128 v[110:113], v0 offset:36928
	ds_read_b128 v[114:117], v0 offset:41536
	ds_read_b128 v[118:121], v66 offset:55360
	ds_read_b128 v[130:133], v66 offset:59968
	s_waitcnt vmcnt(9)
	ds_write_b128 v67, v[86:89] offset:4608
	s_waitcnt vmcnt(8)
	ds_write_b128 v67, v[98:101] offset:23040
	global_load_dwordx4 v[86:89], v70, s[0:1] offset:640
	global_load_dwordx4 v[98:101], v70, s[2:3] offset:640
	s_waitcnt lgkmcnt(3)
	v_mfma_f32_32x32x16_bf16 v[2:17], v[114:117], v[118:121], v[2:17]
	s_waitcnt lgkmcnt(2)
	v_mfma_f32_32x32x16_bf16 v[18:33], v[114:117], v[130:133], v[18:33]
	v_mfma_f32_32x32x16_bf16 v[34:49], v[110:113], v[118:121], v[34:49]
	v_mfma_f32_32x32x16_bf16 v[50:65], v[110:113], v[130:133], v[50:65]
	ds_read_b128 v[110:113], v0 offset:36960
	ds_read_b128 v[118:121], v0 offset:41568
	ds_read_b128 v[122:125], v66 offset:55392
	ds_read_b128 v[126:129], v66 offset:60000
	s_waitcnt vmcnt(9)
	ds_write_b128 v67, v[102:105] offset:9216
	s_waitcnt vmcnt(8)
	ds_write_b128 v67, v[106:109] offset:27648
	global_load_dwordx4 v[102:105], v69, s[0:1] offset:640
	global_load_dwordx4 v[106:109], v69, s[2:3] offset:640
	s_waitcnt lgkmcnt(3)
	v_mfma_f32_32x32x16_bf16 v[2:17], v[118:121], v[122:125], v[2:17]
	s_waitcnt vmcnt(9)
	ds_write_b128 v67, v[74:77] offset:13824
	s_waitcnt vmcnt(8)
	ds_write_b128 v67, v[90:93] offset:32256
	s_waitcnt lgkmcnt(4)
	v_mfma_f32_32x32x16_bf16 v[18:33], v[118:121], v[126:129], v[18:33]
	v_mfma_f32_32x32x16_bf16 v[34:49], v[110:113], v[122:125], v[34:49]
	v_mfma_f32_32x32x16_bf16 v[50:65], v[110:113], v[126:129], v[50:65]
	s_waitcnt lgkmcnt(0)
	s_barrier
	ds_read_b128 v[74:77], v0
	ds_read_b128 v[90:93], v66 offset:18432
	ds_read_b128 v[110:113], v0 offset:32
	ds_read_b128 v[114:117], v66 offset:18464
	ds_read_b128 v[118:121], v0 offset:4608
	ds_read_b128 v[122:125], v0 offset:4640
	s_waitcnt lgkmcnt(4)
	v_mfma_f32_32x32x16_bf16 v[34:49], v[74:77], v[90:93], v[34:49]
	s_waitcnt lgkmcnt(1)
	v_mfma_f32_32x32x16_bf16 v[2:17], v[118:121], v[90:93], v[2:17]
	ds_read_b128 v[90:93], v66 offset:23040
	ds_read_b128 v[126:129], v66 offset:23072
	s_waitcnt lgkmcnt(1)
	v_mfma_f32_32x32x16_bf16 v[50:65], v[74:77], v[90:93], v[50:65]
	global_load_dwordx4 v[74:77], v72, s[0:1] offset:768
	global_load_dwordx4 v[130:133], v72, s[2:3] offset:768
	s_waitcnt vmcnt(9)
	ds_write_b128 v67, v[78:81] offset:36864
	s_waitcnt vmcnt(8)
	ds_write_b128 v67, v[134:137] offset:55296
	v_mfma_f32_32x32x16_bf16 v[18:33], v[118:121], v[90:93], v[18:33]
	global_load_dwordx4 v[78:81], v71, s[0:1] offset:768
	global_load_dwordx4 v[90:93], v71, s[2:3] offset:768
	v_mfma_f32_32x32x16_bf16 v[2:17], v[122:125], v[114:117], v[2:17]
	s_waitcnt lgkmcnt(2)
	v_mfma_f32_32x32x16_bf16 v[18:33], v[122:125], v[126:129], v[18:33]
	v_mfma_f32_32x32x16_bf16 v[34:49], v[110:113], v[114:117], v[34:49]
	v_mfma_f32_32x32x16_bf16 v[50:65], v[110:113], v[126:129], v[50:65]
	ds_read_b128 v[110:113], v0 offset:64
	ds_read_b128 v[114:117], v0 offset:4672
	ds_read_b128 v[118:121], v66 offset:18496
	ds_read_b128 v[134:137], v66 offset:23104
	s_waitcnt vmcnt(9)
	ds_write_b128 v67, v[82:85] offset:41472
	s_waitcnt vmcnt(8)
	ds_write_b128 v67, v[94:97] offset:59904
	global_load_dwordx4 v[82:85], v70, s[0:1] offset:768
	global_load_dwordx4 v[94:97], v70, s[2:3] offset:768
	s_waitcnt lgkmcnt(3)
	v_mfma_f32_32x32x16_bf16 v[2:17], v[114:117], v[118:121], v[2:17]
	s_waitcnt lgkmcnt(2)
	v_mfma_f32_32x32x16_bf16 v[18:33], v[114:117], v[134:137], v[18:33]
	v_mfma_f32_32x32x16_bf16 v[34:49], v[110:113], v[118:121], v[34:49]
	v_mfma_f32_32x32x16_bf16 v[50:65], v[110:113], v[134:137], v[50:65]
	ds_read_b128 v[110:113], v0 offset:96
	ds_read_b128 v[118:121], v0 offset:4704
	ds_read_b128 v[122:125], v66 offset:18528
	ds_read_b128 v[126:129], v66 offset:23136
	s_waitcnt vmcnt(9)
	ds_write_b128 v67, v[86:89] offset:46080
	s_waitcnt vmcnt(8)
	ds_write_b128 v67, v[98:101] offset:64512
	global_load_dwordx4 v[86:89], v69, s[0:1] offset:768
	global_load_dwordx4 v[98:101], v69, s[2:3] offset:768
	s_waitcnt lgkmcnt(3)
	v_mfma_f32_32x32x16_bf16 v[2:17], v[118:121], v[122:125], v[2:17]
	s_waitcnt vmcnt(9)
	ds_write_b128 v67, v[102:105] offset:50688
	s_waitcnt vmcnt(8)
	ds_write_b128 v68, v[106:109] offset:13824
	s_waitcnt lgkmcnt(4)
	v_mfma_f32_32x32x16_bf16 v[18:33], v[118:121], v[126:129], v[18:33]
	v_mfma_f32_32x32x16_bf16 v[34:49], v[110:113], v[122:125], v[34:49]
	v_mfma_f32_32x32x16_bf16 v[50:65], v[110:113], v[126:129], v[50:65]
	s_waitcnt lgkmcnt(0)
	s_barrier
; #define GL1_(RA, RB, i) { RA[i] = *(const u32x4*)(ap + (aoff + (i) * astep)); if ((i) < NB) RB[(i) < NB ? (i) : 0] = *(const u32x4*)(bp + (boff + (i) * bstep)); }
; #define LS1_(RA, RB, ST, i) { char* sn_ = lds + (ST) * STAGE; *(u32x4*)(sn_ + wofs + (i) * 32 * LROW) = RA[i]; \
;                               if ((i) < NB) *(u32x4*)(sn_ + STAGE_OP + wofs + (i) * 32 * LROW) = RB[(i) < NB ? (i) : 0]; }
; template <int NJ> DI void gemm_mainloop_reg(const bf16_t* __restrict__ A, int lda, const bf16_t* __restrict__ Bt, int ldb, int K, f32x16 (&acc)[2][NJ], char* lds) {
;     ...
; #pragma unroll
;   for (int i = 0; i < 4; ++i) GL1_(ra0, rb0, i);
;   ap += 128; bp += 128;
; #pragma unroll
;   for (int i = 0; i < 4; ++i) GL1_(ra1, rb1, i);
;   ap += 128; bp += 128;
; #pragma unroll
;   for (int i = 0; i < 4; ++i) LS1_(ra0, rb0, 0, i);
;   __syncthreads();
;   const int nk = K >> 6;
;   for (int kt = 0; kt < nk; kt += 2) {
;     const bool l0 = (kt + 2 < nk), l1 = (kt + 3 < nk);
;     STEP_(0, l0, ra0, rb0, true, ra1, rb1);
;     __syncthreads();
;     STEP_(1, l1, ra1, rb1, l0, ra0, rb0);
;     __syncthreads();
;   }
	ds_read_b128 v[102:105], v0 offset:36864
	ds_read_b128 v[106:109], v66 offset:55296
	ds_read_b128 v[110:113], v0 offset:36896
	ds_read_b128 v[114:117], v66 offset:55328
	ds_read_b128 v[118:121], v0 offset:41472
	ds_read_b128 v[122:125], v0 offset:41504
	s_waitcnt lgkmcnt(4)
	v_mfma_f32_32x32x16_bf16 v[34:49], v[102:105], v[106:109], v[34:49]
	s_waitcnt lgkmcnt(1)
	v_mfma_f32_32x32x16_bf16 v[2:17], v[118:121], v[106:109], v[2:17]
	ds_read_b128 v[106:109], v66 offset:59904
	ds_read_b128 v[126:129], v66 offset:59936
	s_waitcnt lgkmcnt(1)
	v_mfma_f32_32x32x16_bf16 v[50:65], v[102:105], v[106:109], v[50:65]
	global_load_dwordx4 v[102:105], v72, s[0:1] offset:896
	global_load_dwordx4 v[134:137], v72, s[2:3] offset:896
	s_waitcnt vmcnt(9)
	ds_write_b128 v67, v[74:77]
	s_waitcnt vmcnt(8)
	ds_write_b128 v67, v[130:133] offset:18432
	v_mfma_f32_32x32x16_bf16 v[18:33], v[118:121], v[106:109], v[18:33]
	global_load_dwordx4 v[74:77], v71, s[0:1] offset:896
	global_load_dwordx4 v[106:109], v71, s[2:3] offset:896
	v_mfma_f32_32x32x16_bf16 v[2:17], v[122:125], v[114:117], v[2:17]
	s_waitcnt lgkmcnt(2)
	v_mfma_f32_32x32x16_bf16 v[18:33], v[122:125], v[126:129], v[18:33]
	v_mfma_f32_32x32x16_bf16 v[34:49], v[110:113], v[114:117], v[34:49]
	v_mfma_f32_32x32x16_bf16 v[50:65], v[110:113], v[126:129], v[50:65]
	ds_read_b128 v[110:113], v0 offset:36928
	ds_read_b128 v[114:117], v0 offset:41536
	ds_read_b128 v[118:121], v66 offset:55360
	ds_read_b128 v[130:133], v66 offset:59968
	s_waitcnt vmcnt(9)
	ds_write_b128 v67, v[78:81] offset:4608
	s_waitcnt vmcnt(8)
	ds_write_b128 v67, v[90:93] offset:23040
	global_load_dwordx4 v[78:81], v70, s[0:1] offset:896
	global_load_dwordx4 v[90:93], v70, s[2:3] offset:896
	s_waitcnt lgkmcnt(3)
	v_mfma_f32_32x32x16_bf16 v[2:17], v[114:117], v[118:121], v[2:17]
	s_waitcnt lgkmcnt(2)
	v_mfma_f32_32x32x16_bf16 v[18:33], v[114:117], v[130:133], v[18:33]
	v_mfma_f32_32x32x16_bf16 v[34:49], v[110:113], v[118:121], v[34:49]
	v_mfma_f32_32x32x16_bf16 v[50:65], v[110:113], v[130:133], v[50:65]
	ds_read_b128 v[110:113], v0 offset:36960
	ds_read_b128 v[118:121], v0 offset:41568
	ds_read_b128 v[122:125], v66 offset:55392
	ds_read_b128 v[126:129], v66 offset:60000
	s_waitcnt vmcnt(9)
	ds_write_b128 v67, v[82:85] offset:9216
	s_waitcnt vmcnt(8)
	ds_write_b128 v67, v[94:97] offset:27648
	global_load_dwordx4 v[82:85], v69, s[0:1] offset:896
	global_load_dwordx4 v[94:97], v69, s[2:3] offset:896
	s_waitcnt lgkmcnt(3)
	v_mfma_f32_32x32x16_bf16 v[2:17], v[118:121], v[122:125], v[2:17]
	s_waitcnt vmcnt(9)
	ds_write_b128 v67, v[86:89] offset:13824
	s_waitcnt vmcnt(8)
	ds_write_b128 v67, v[98:101] offset:32256
	s_waitcnt lgkmcnt(4)
	v_mfma_f32_32x32x16_bf16 v[18:33], v[118:121], v[126:129], v[18:33]
	v_mfma_f32_32x32x16_bf16 v[34:49], v[110:113], v[122:125], v[34:49]
	v_mfma_f32_32x32x16_bf16 v[50:65], v[110:113], v[126:129], v[50:65]
	s_waitcnt lgkmcnt(0)
	s_barrier
	ds_read_b128 v[86:89], v0
	ds_read_b128 v[98:101], v66 offset:18432
	ds_read_b128 v[110:113], v0 offset:32
	ds_read_b128 v[114:117], v66 offset:18464
	ds_read_b128 v[118:121], v0 offset:4608
	ds_read_b128 v[122:125], v0 offset:4640
	s_waitcnt lgkmcnt(4)
	v_mfma_f32_32x32x16_bf16 v[34:49], v[86:89], v[98:101], v[34:49]
	s_waitcnt lgkmcnt(1)
	v_mfma_f32_32x32x16_bf16 v[2:17], v[118:121], v[98:101], v[2:17]
	ds_read_b128 v[98:101], v66 offset:23040
	ds_read_b128 v[126:129], v66 offset:23072
	s_waitcnt lgkmcnt(1)
	v_mfma_f32_32x32x16_bf16 v[50:65], v[86:89], v[98:101], v[50:65]
	global_load_dwordx4 v[86:89], v72, s[0:1] offset:1024
	global_load_dwordx4 v[130:133], v72, s[2:3] offset:1024
	s_waitcnt vmcnt(9)
	ds_write_b128 v67, v[102:105] offset:36864
	s_waitcnt vmcnt(8)
	ds_write_b128 v67, v[134:137] offset:55296
	v_mfma_f32_32x32x16_bf16 v[18:33], v[118:121], v[98:101], v[18:33]
	global_load_dwordx4 v[98:101], v71, s[0:1] offset:1024
	global_load_dwordx4 v[102:105], v71, s[2:3] offset:1024
	v_mfma_f32_32x32x16_bf16 v[2:17], v[122:125], v[114:117], v[2:17]
	s_waitcnt lgkmcnt(2)
	v_mfma_f32_32x32x16_bf16 v[18:33], v[122:125], v[126:129], v[18:33]
	v_mfma_f32_32x32x16_bf16 v[34:49], v[110:113], v[114:117], v[34:49]
	v_mfma_f32_32x32x16_bf16 v[50:65], v[110:113], v[126:129], v[50:65]
	ds_read_b128 v[110:113], v0 offset:64
	ds_read_b128 v[114:117], v0 offset:4672
	ds_read_b128 v[118:121], v66 offset:18496
	ds_read_b128 v[134:137], v66 offset:23104
	s_waitcnt vmcnt(9)
	ds_write_b128 v67, v[74:77] offset:41472
	s_waitcnt vmcnt(8)
	ds_write_b128 v67, v[106:109] offset:59904
	global_load_dwordx4 v[74:77], v70, s[0:1] offset:1024
	global_load_dwordx4 v[106:109], v70, s[2:3] offset:1024
	s_waitcnt lgkmcnt(3)
	v_mfma_f32_32x32x16_bf16 v[2:17], v[114:117], v[118:121], v[2:17]
	s_waitcnt lgkmcnt(2)
	v_mfma_f32_32x32x16_bf16 v[18:33], v[114:117], v[134:137], v[18:33]
	v_mfma_f32_32x32x16_bf16 v[34:49], v[110:113], v[118:121], v[34:49]
	v_mfma_f32_32x32x16_bf16 v[50:65], v[110:113], v[134:137], v[50:65]
	ds_read_b128 v[110:113], v0 offset:96
	ds_read_b128 v[118:121], v0 offset:4704
	ds_read_b128 v[122:125], v66 offset:18528
	ds_read_b128 v[126:129], v66 offset:23136
	s_waitcnt vmcnt(9)
	ds_write_b128 v67, v[78:81] offset:46080
	s_waitcnt vmcnt(8)
	ds_write_b128 v67, v[90:93] offset:64512
	global_load_dwordx4 v[78:81], v69, s[0:1] offset:1024
	global_load_dwordx4 v[90:93], v69, s[2:3] offset:1024
	s_waitcnt lgkmcnt(3)
	v_mfma_f32_32x32x16_bf16 v[2:17], v[118:121], v[122:125], v[2:17]
	s_waitcnt vmcnt(9)
	ds_write_b128 v67, v[82:85] offset:50688
	s_waitcnt vmcnt(8)
	ds_write_b128 v68, v[94:97] offset:13824
	s_waitcnt lgkmcnt(4)
	v_mfma_f32_32x32x16_bf16 v[18:33], v[118:121], v[126:129], v[18:33]
	v_mfma_f32_32x32x16_bf16 v[34:49], v[110:113], v[122:125], v[34:49]
	v_mfma_f32_32x32x16_bf16 v[50:65], v[110:113], v[126:129], v[50:65]
	s_waitcnt lgkmcnt(0)
	s_barrier
; #define GL1_(RA, RB, i) { RA[i] = *(const u32x4*)(ap + (aoff + (i) * astep)); if ((i) < NB) RB[(i) < NB ? (i) : 0] = *(const u32x4*)(bp + (boff + (i) * bstep)); }
; #define LS1_(RA, RB, ST, i) { char* sn_ = lds + (ST) * STAGE; *(u32x4*)(sn_ + wofs + (i) * 32 * LROW) = RA[i]; \
;                               if ((i) < NB) *(u32x4*)(sn_ + STAGE_OP + wofs + (i) * 32 * LROW) = RB[(i) < NB ? (i) : 0]; }
; template <int NJ> DI void gemm_mainloop_reg(const bf16_t* __restrict__ A, int lda, const bf16_t* __restrict__ Bt, int ldb, int K, f32x16 (&acc)[2][NJ], char* lds) {
;     ...
; #pragma unroll
;   for (int i = 0; i < 4; ++i) GL1_(ra0, rb0, i);
;   ap += 128; bp += 128;
; #pragma unroll
;   for (int i = 0; i < 4; ++i) GL1_(ra1, rb1, i);
;   ap += 128; bp += 128;
; #pragma unroll
;   for (int i = 0; i < 4; ++i) LS1_(ra0, rb0, 0, i);
;   __syncthreads();
;   const int nk = K >> 6;
;   for (int kt = 0; kt < nk; kt += 2) {
;     const bool l0 = (kt + 2 < nk), l1 = (kt + 3 < nk);
;     STEP_(0, l0, ra0, rb0, true, ra1, rb1);
;     __syncthreads();
;     STEP_(1, l1, ra1, rb1, l0, ra0, rb0);
;     __syncthreads();
;   }
	ds_read_b128 v[82:85], v0 offset:36864
	ds_read_b128 v[94:97], v66 offset:55296
	ds_read_b128 v[110:113], v0 offset:36896
	ds_read_b128 v[114:117], v66 offset:55328
	ds_read_b128 v[118:121], v0 offset:41472
	ds_read_b128 v[122:125], v0 offset:41504
	s_waitcnt lgkmcnt(4)
	v_mfma_f32_32x32x16_bf16 v[34:49], v[82:85], v[94:97], v[34:49]
	s_waitcnt lgkmcnt(1)
	v_mfma_f32_32x32x16_bf16 v[2:17], v[118:121], v[94:97], v[2:17]
	ds_read_b128 v[94:97], v66 offset:59904
	ds_read_b128 v[126:129], v66 offset:59936
	s_waitcnt lgkmcnt(1)
	v_mfma_f32_32x32x16_bf16 v[50:65], v[82:85], v[94:97], v[50:65]
	global_load_dwordx4 v[82:85], v72, s[0:1] offset:1152
	global_load_dwordx4 v[134:137], v72, s[2:3] offset:1152
	s_waitcnt vmcnt(9)
	ds_write_b128 v67, v[86:89]
	s_waitcnt vmcnt(8)
	ds_write_b128 v67, v[130:133] offset:18432
	v_mfma_f32_32x32x16_bf16 v[18:33], v[118:121], v[94:97], v[18:33]
	global_load_dwordx4 v[86:89], v71, s[0:1] offset:1152
	global_load_dwordx4 v[94:97], v71, s[2:3] offset:1152
	v_mfma_f32_32x32x16_bf16 v[2:17], v[122:125], v[114:117], v[2:17]
	s_waitcnt lgkmcnt(2)
	v_mfma_f32_32x32x16_bf16 v[18:33], v[122:125], v[126:129], v[18:33]
	v_mfma_f32_32x32x16_bf16 v[34:49], v[110:113], v[114:117], v[34:49]
	v_mfma_f32_32x32x16_bf16 v[50:65], v[110:113], v[126:129], v[50:65]
	ds_read_b128 v[110:113], v0 offset:36928
	ds_read_b128 v[114:117], v0 offset:41536
	ds_read_b128 v[118:121], v66 offset:55360
	ds_read_b128 v[130:133], v66 offset:59968
	s_waitcnt vmcnt(9)
	ds_write_b128 v67, v[98:101] offset:4608
	s_waitcnt vmcnt(8)
	ds_write_b128 v67, v[102:105] offset:23040
	global_load_dwordx4 v[98:101], v70, s[0:1] offset:1152
	global_load_dwordx4 v[102:105], v70, s[2:3] offset:1152
	s_waitcnt lgkmcnt(3)
	v_mfma_f32_32x32x16_bf16 v[2:17], v[114:117], v[118:121], v[2:17]
	s_waitcnt lgkmcnt(2)
	v_mfma_f32_32x32x16_bf16 v[18:33], v[114:117], v[130:133], v[18:33]
	v_mfma_f32_32x32x16_bf16 v[34:49], v[110:113], v[118:121], v[34:49]
	v_mfma_f32_32x32x16_bf16 v[50:65], v[110:113], v[130:133], v[50:65]
	ds_read_b128 v[110:113], v0 offset:36960
	ds_read_b128 v[118:121], v0 offset:41568
	ds_read_b128 v[122:125], v66 offset:55392
	ds_read_b128 v[126:129], v66 offset:60000
	s_waitcnt vmcnt(9)
	ds_write_b128 v67, v[74:77] offset:9216
	s_waitcnt vmcnt(8)
	ds_write_b128 v67, v[106:109] offset:27648
	global_load_dwordx4 v[74:77], v69, s[0:1] offset:1152
	global_load_dwordx4 v[106:109], v69, s[2:3] offset:1152
	s_waitcnt lgkmcnt(3)
	v_mfma_f32_32x32x16_bf16 v[2:17], v[118:121], v[122:125], v[2:17]
	s_waitcnt vmcnt(9)
	ds_write_b128 v67, v[78:81] offset:13824
	s_waitcnt vmcnt(8)
	ds_write_b128 v67, v[90:93] offset:32256
	s_waitcnt lgkmcnt(4)
	v_mfma_f32_32x32x16_bf16 v[18:33], v[118:121], v[126:129], v[18:33]
	v_mfma_f32_32x32x16_bf16 v[34:49], v[110:113], v[122:125], v[34:49]
	v_mfma_f32_32x32x16_bf16 v[50:65], v[110:113], v[126:129], v[50:65]
	s_waitcnt lgkmcnt(0)
	s_barrier
	ds_read_b128 v[78:81], v0
	ds_read_b128 v[90:93], v66 offset:18432
	ds_read_b128 v[110:113], v0 offset:32
	ds_read_b128 v[114:117], v66 offset:18464
	ds_read_b128 v[118:121], v0 offset:4608
	ds_read_b128 v[122:125], v0 offset:4640
	s_waitcnt lgkmcnt(4)
	v_mfma_f32_32x32x16_bf16 v[34:49], v[78:81], v[90:93], v[34:49]
	s_waitcnt lgkmcnt(1)
	v_mfma_f32_32x32x16_bf16 v[2:17], v[118:121], v[90:93], v[2:17]
	ds_read_b128 v[90:93], v66 offset:23040
	ds_read_b128 v[126:129], v66 offset:23072
	s_waitcnt lgkmcnt(1)
	v_mfma_f32_32x32x16_bf16 v[50:65], v[78:81], v[90:93], v[50:65]
	global_load_dwordx4 v[78:81], v72, s[0:1] offset:1280
	global_load_dwordx4 v[130:133], v72, s[2:3] offset:1280
	s_waitcnt vmcnt(9)
	ds_write_b128 v67, v[82:85] offset:36864
	s_waitcnt vmcnt(8)
	ds_write_b128 v67, v[134:137] offset:55296
	v_mfma_f32_32x32x16_bf16 v[18:33], v[118:121], v[90:93], v[18:33]
	global_load_dwordx4 v[82:85], v71, s[0:1] offset:1280
	global_load_dwordx4 v[90:93], v71, s[2:3] offset:1280
	v_mfma_f32_32x32x16_bf16 v[2:17], v[122:125], v[114:117], v[2:17]
	s_waitcnt lgkmcnt(2)
	v_mfma_f32_32x32x16_bf16 v[18:33], v[122:125], v[126:129], v[18:33]
	v_mfma_f32_32x32x16_bf16 v[34:49], v[110:113], v[114:117], v[34:49]
	v_mfma_f32_32x32x16_bf16 v[50:65], v[110:113], v[126:129], v[50:65]
	ds_read_b128 v[110:113], v0 offset:64
	ds_read_b128 v[114:117], v0 offset:4672
	ds_read_b128 v[118:121], v66 offset:18496
	ds_read_b128 v[134:137], v66 offset:23104
	s_waitcnt vmcnt(9)
	ds_write_b128 v67, v[86:89] offset:41472
	s_waitcnt vmcnt(8)
	ds_write_b128 v67, v[94:97] offset:59904
	global_load_dwordx4 v[86:89], v70, s[0:1] offset:1280
	global_load_dwordx4 v[94:97], v70, s[2:3] offset:1280
	s_waitcnt lgkmcnt(3)
	v_mfma_f32_32x32x16_bf16 v[2:17], v[114:117], v[118:121], v[2:17]
	s_waitcnt lgkmcnt(2)
	v_mfma_f32_32x32x16_bf16 v[18:33], v[114:117], v[134:137], v[18:33]
	v_mfma_f32_32x32x16_bf16 v[34:49], v[110:113], v[118:121], v[34:49]
	v_mfma_f32_32x32x16_bf16 v[50:65], v[110:113], v[134:137], v[50:65]
	ds_read_b128 v[110:113], v0 offset:96
	ds_read_b128 v[118:121], v0 offset:4704
	ds_read_b128 v[122:125], v66 offset:18528
	ds_read_b128 v[126:129], v66 offset:23136
	s_waitcnt vmcnt(9)
	ds_write_b128 v67, v[98:101] offset:46080
	s_waitcnt vmcnt(8)
	ds_write_b128 v67, v[102:105] offset:64512
	global_load_dwordx4 v[98:101], v69, s[0:1] offset:1280
	global_load_dwordx4 v[102:105], v69, s[2:3] offset:1280
	s_waitcnt lgkmcnt(3)
	v_mfma_f32_32x32x16_bf16 v[2:17], v[118:121], v[122:125], v[2:17]
	s_waitcnt vmcnt(9)
	ds_write_b128 v67, v[74:77] offset:50688
	s_waitcnt vmcnt(8)
	ds_write_b128 v68, v[106:109] offset:13824
	s_waitcnt lgkmcnt(4)
	v_mfma_f32_32x32x16_bf16 v[18:33], v[118:121], v[126:129], v[18:33]
	v_mfma_f32_32x32x16_bf16 v[34:49], v[110:113], v[122:125], v[34:49]
	v_mfma_f32_32x32x16_bf16 v[50:65], v[110:113], v[126:129], v[50:65]
	s_waitcnt lgkmcnt(0)
	s_barrier
; #define GL1_(RA, RB, i) { RA[i] = *(const u32x4*)(ap + (aoff + (i) * astep)); if ((i) < NB) RB[(i) < NB ? (i) : 0] = *(const u32x4*)(bp + (boff + (i) * bstep)); }
; #define LS1_(RA, RB, ST, i) { char* sn_ = lds + (ST) * STAGE; *(u32x4*)(sn_ + wofs + (i) * 32 * LROW) = RA[i]; \
;                               if ((i) < NB) *(u32x4*)(sn_ + STAGE_OP + wofs + (i) * 32 * LROW) = RB[(i) < NB ? (i) : 0]; }
; template <int NJ> DI void gemm_mainloop_reg(const bf16_t* __restrict__ A, int lda, const bf16_t* __restrict__ Bt, int ldb, int K, f32x16 (&acc)[2][NJ], char* lds) {
;     ...
; #pragma unroll
;   for (int i = 0; i < 4; ++i) GL1_(ra0, rb0, i);
;   ap += 128; bp += 128;
; #pragma unroll
;   for (int i = 0; i < 4; ++i) GL1_(ra1, rb1, i);
;   ap += 128; bp += 128;
; #pragma unroll
;   for (int i = 0; i < 4; ++i) LS1_(ra0, rb0, 0, i);
;   __syncthreads();
;   const int nk = K >> 6;
;   for (int kt = 0; kt < nk; kt += 2) {
;     const bool l0 = (kt + 2 < nk), l1 = (kt + 3 < nk);
;     STEP_(0, l0, ra0, rb0, true, ra1, rb1);
;     __syncthreads();
;     STEP_(1, l1, ra1, rb1, l0, ra0, rb0);
;     __syncthreads();
;   }
	ds_read_b128 v[74:77], v0 offset:36864
	ds_read_b128 v[106:109], v66 offset:55296
	ds_read_b128 v[110:113], v0 offset:36896
	ds_read_b128 v[114:117], v66 offset:55328
	ds_read_b128 v[118:121], v0 offset:41472
	ds_read_b128 v[122:125], v0 offset:41504
	s_waitcnt lgkmcnt(4)
	v_mfma_f32_32x32x16_bf16 v[34:49], v[74:77], v[106:109], v[34:49]
	s_waitcnt lgkmcnt(1)
	v_mfma_f32_32x32x16_bf16 v[2:17], v[118:121], v[106:109], v[2:17]
	ds_read_b128 v[106:109], v66 offset:59904
	ds_read_b128 v[126:129], v66 offset:59936
	s_waitcnt lgkmcnt(1)
	v_mfma_f32_32x32x16_bf16 v[50:65], v[74:77], v[106:109], v[50:65]
	global_load_dwordx4 v[74:77], v72, s[0:1] offset:1408
	global_load_dwordx4 v[134:137], v72, s[2:3] offset:1408
	s_waitcnt vmcnt(9)
	ds_write_b128 v67, v[78:81]
	s_waitcnt vmcnt(8)
	ds_write_b128 v67, v[130:133] offset:18432
	v_mfma_f32_32x32x16_bf16 v[18:33], v[118:121], v[106:109], v[18:33]
	global_load_dwordx4 v[78:81], v71, s[0:1] offset:1408
	global_load_dwordx4 v[106:109], v71, s[2:3] offset:1408
	v_mfma_f32_32x32x16_bf16 v[2:17], v[122:125], v[114:117], v[2:17]
	s_waitcnt lgkmcnt(2)
	v_mfma_f32_32x32x16_bf16 v[18:33], v[122:125], v[126:129], v[18:33]
	v_mfma_f32_32x32x16_bf16 v[34:49], v[110:113], v[114:117], v[34:49]
	v_mfma_f32_32x32x16_bf16 v[50:65], v[110:113], v[126:129], v[50:65]
	ds_read_b128 v[110:113], v0 offset:36928
	ds_read_b128 v[114:117], v0 offset:41536
	ds_read_b128 v[118:121], v66 offset:55360
	ds_read_b128 v[130:133], v66 offset:59968
	s_waitcnt vmcnt(9)
	ds_write_b128 v67, v[82:85] offset:4608
	s_waitcnt vmcnt(8)
	ds_write_b128 v67, v[90:93] offset:23040
	global_load_dwordx4 v[82:85], v70, s[0:1] offset:1408
	global_load_dwordx4 v[90:93], v70, s[2:3] offset:1408
	s_waitcnt lgkmcnt(3)
	v_mfma_f32_32x32x16_bf16 v[2:17], v[114:117], v[118:121], v[2:17]
	s_waitcnt lgkmcnt(2)
	v_mfma_f32_32x32x16_bf16 v[18:33], v[114:117], v[130:133], v[18:33]
	v_mfma_f32_32x32x16_bf16 v[34:49], v[110:113], v[118:121], v[34:49]
	v_mfma_f32_32x32x16_bf16 v[50:65], v[110:113], v[130:133], v[50:65]
	ds_read_b128 v[110:113], v0 offset:36960
	ds_read_b128 v[118:121], v0 offset:41568
	ds_read_b128 v[122:125], v66 offset:55392
	ds_read_b128 v[126:129], v66 offset:60000
	s_waitcnt vmcnt(9)
	ds_write_b128 v67, v[86:89] offset:9216
	s_waitcnt vmcnt(8)
	ds_write_b128 v67, v[94:97] offset:27648
	global_load_dwordx4 v[86:89], v69, s[0:1] offset:1408
	global_load_dwordx4 v[94:97], v69, s[2:3] offset:1408
	s_waitcnt lgkmcnt(3)
	v_mfma_f32_32x32x16_bf16 v[2:17], v[118:121], v[122:125], v[2:17]
	s_waitcnt vmcnt(9)
	ds_write_b128 v67, v[98:101] offset:13824
	s_waitcnt vmcnt(8)
	ds_write_b128 v67, v[102:105] offset:32256
	s_waitcnt lgkmcnt(4)
	v_mfma_f32_32x32x16_bf16 v[18:33], v[118:121], v[126:129], v[18:33]
	v_mfma_f32_32x32x16_bf16 v[34:49], v[110:113], v[122:125], v[34:49]
	v_mfma_f32_32x32x16_bf16 v[50:65], v[110:113], v[126:129], v[50:65]
	s_waitcnt lgkmcnt(0)
	s_barrier
	ds_read_b128 v[98:101], v0
	ds_read_b128 v[102:105], v66 offset:18432
	ds_read_b128 v[110:113], v0 offset:32
	ds_read_b128 v[114:117], v66 offset:18464
	ds_read_b128 v[118:121], v0 offset:4608
	ds_read_b128 v[122:125], v0 offset:4640
	s_waitcnt lgkmcnt(4)
	v_mfma_f32_32x32x16_bf16 v[34:49], v[98:101], v[102:105], v[34:49]
	s_waitcnt lgkmcnt(1)
	v_mfma_f32_32x32x16_bf16 v[2:17], v[118:121], v[102:105], v[2:17]
	ds_read_b128 v[102:105], v66 offset:23040
	ds_read_b128 v[126:129], v66 offset:23072
	s_waitcnt lgkmcnt(1)
	v_mfma_f32_32x32x16_bf16 v[50:65], v[98:101], v[102:105], v[50:65]
	global_load_dwordx4 v[98:101], v72, s[0:1] offset:1536
	global_load_dwordx4 v[130:133], v72, s[2:3] offset:1536
	s_waitcnt vmcnt(9)
	ds_write_b128 v67, v[74:77] offset:36864
	s_waitcnt vmcnt(8)
	ds_write_b128 v67, v[134:137] offset:55296
	v_mfma_f32_32x32x16_bf16 v[18:33], v[118:121], v[102:105], v[18:33]
	global_load_dwordx4 v[74:77], v71, s[0:1] offset:1536
	global_load_dwordx4 v[102:105], v71, s[2:3] offset:1536
	v_mfma_f32_32x32x16_bf16 v[2:17], v[122:125], v[114:117], v[2:17]
	s_waitcnt lgkmcnt(2)
	v_mfma_f32_32x32x16_bf16 v[18:33], v[122:125], v[126:129], v[18:33]
	v_mfma_f32_32x32x16_bf16 v[34:49], v[110:113], v[114:117], v[34:49]
	v_mfma_f32_32x32x16_bf16 v[50:65], v[110:113], v[126:129], v[50:65]
	ds_read_b128 v[110:113], v0 offset:64
	ds_read_b128 v[114:117], v0 offset:4672
	ds_read_b128 v[118:121], v66 offset:18496
	ds_read_b128 v[134:137], v66 offset:23104
	s_waitcnt vmcnt(9)
	ds_write_b128 v67, v[78:81] offset:41472
	s_waitcnt vmcnt(8)
	ds_write_b128 v67, v[106:109] offset:59904
	global_load_dwordx4 v[78:81], v70, s[0:1] offset:1536
	global_load_dwordx4 v[106:109], v70, s[2:3] offset:1536
	s_waitcnt lgkmcnt(3)
	v_mfma_f32_32x32x16_bf16 v[2:17], v[114:117], v[118:121], v[2:17]
	s_waitcnt lgkmcnt(2)
	v_mfma_f32_32x32x16_bf16 v[18:33], v[114:117], v[134:137], v[18:33]
	v_mfma_f32_32x32x16_bf16 v[34:49], v[110:113], v[118:121], v[34:49]
	v_mfma_f32_32x32x16_bf16 v[50:65], v[110:113], v[134:137], v[50:65]
	ds_read_b128 v[110:113], v0 offset:96
	ds_read_b128 v[118:121], v0 offset:4704
	ds_read_b128 v[122:125], v66 offset:18528
	ds_read_b128 v[126:129], v66 offset:23136
	s_waitcnt vmcnt(9)
	ds_write_b128 v67, v[82:85] offset:46080
	s_waitcnt vmcnt(8)
	ds_write_b128 v67, v[90:93] offset:64512
	global_load_dwordx4 v[82:85], v69, s[0:1] offset:1536
	global_load_dwordx4 v[90:93], v69, s[2:3] offset:1536
	s_waitcnt lgkmcnt(3)
	v_mfma_f32_32x32x16_bf16 v[2:17], v[118:121], v[122:125], v[2:17]
	s_waitcnt vmcnt(9)
	ds_write_b128 v67, v[86:89] offset:50688
	s_waitcnt vmcnt(8)
	ds_write_b128 v68, v[94:97] offset:13824
	s_waitcnt lgkmcnt(4)
	v_mfma_f32_32x32x16_bf16 v[18:33], v[118:121], v[126:129], v[18:33]
	v_mfma_f32_32x32x16_bf16 v[34:49], v[110:113], v[122:125], v[34:49]
	v_mfma_f32_32x32x16_bf16 v[50:65], v[110:113], v[126:129], v[50:65]
	s_waitcnt lgkmcnt(0)
	s_barrier
; #define GL1_(RA, RB, i) { RA[i] = *(const u32x4*)(ap + (aoff + (i) * astep)); if ((i) < NB) RB[(i) < NB ? (i) : 0] = *(const u32x4*)(bp + (boff + (i) * bstep)); }
; #define LS1_(RA, RB, ST, i) { char* sn_ = lds + (ST) * STAGE; *(u32x4*)(sn_ + wofs + (i) * 32 * LROW) = RA[i]; \
;                               if ((i) < NB) *(u32x4*)(sn_ + STAGE_OP + wofs + (i) * 32 * LROW) = RB[(i) < NB ? (i) : 0]; }
; template <int NJ> DI void gemm_mainloop_reg(const bf16_t* __restrict__ A, int lda, const bf16_t* __restrict__ Bt, int ldb, int K, f32x16 (&acc)[2][NJ], char* lds) {
;     ...
; #pragma unroll
;   for (int i = 0; i < 4; ++i) GL1_(ra0, rb0, i);
;   ap += 128; bp += 128;
; #pragma unroll
;   for (int i = 0; i < 4; ++i) GL1_(ra1, rb1, i);
;   ap += 128; bp += 128;
; #pragma unroll
;   for (int i = 0; i < 4; ++i) LS1_(ra0, rb0, 0, i);
;   __syncthreads();
;   const int nk = K >> 6;
;   for (int kt = 0; kt < nk; kt += 2) {
;     const bool l0 = (kt + 2 < nk), l1 = (kt + 3 < nk);
;     STEP_(0, l0, ra0, rb0, true, ra1, rb1);
;     __syncthreads();
;     STEP_(1, l1, ra1, rb1, l0, ra0, rb0);
;     __syncthreads();
;   }
	ds_read_b128 v[86:89], v0 offset:36864
	ds_read_b128 v[94:97], v66 offset:55296
	ds_read_b128 v[110:113], v0 offset:36896
	ds_read_b128 v[114:117], v66 offset:55328
	ds_read_b128 v[118:121], v0 offset:41472
	ds_read_b128 v[122:125], v0 offset:41504
	s_waitcnt lgkmcnt(4)
	v_mfma_f32_32x32x16_bf16 v[34:49], v[86:89], v[94:97], v[34:49]
	s_waitcnt lgkmcnt(1)
	v_mfma_f32_32x32x16_bf16 v[2:17], v[118:121], v[94:97], v[2:17]
	ds_read_b128 v[94:97], v66 offset:59904
	ds_read_b128 v[126:129], v66 offset:59936
	s_waitcnt lgkmcnt(1)
	v_mfma_f32_32x32x16_bf16 v[50:65], v[86:89], v[94:97], v[50:65]
	global_load_dwordx4 v[86:89], v72, s[0:1] offset:1664
	global_load_dwordx4 v[134:137], v72, s[2:3] offset:1664
	s_waitcnt vmcnt(9)
	ds_write_b128 v67, v[98:101]
	s_waitcnt vmcnt(8)
	ds_write_b128 v67, v[130:133] offset:18432
	v_mfma_f32_32x32x16_bf16 v[18:33], v[118:121], v[94:97], v[18:33]
	global_load_dwordx4 v[94:97], v71, s[0:1] offset:1664
	global_load_dwordx4 v[98:101], v71, s[2:3] offset:1664
	v_mfma_f32_32x32x16_bf16 v[2:17], v[122:125], v[114:117], v[2:17]
	s_waitcnt lgkmcnt(2)
	v_mfma_f32_32x32x16_bf16 v[18:33], v[122:125], v[126:129], v[18:33]
	v_mfma_f32_32x32x16_bf16 v[34:49], v[110:113], v[114:117], v[34:49]
	v_mfma_f32_32x32x16_bf16 v[50:65], v[110:113], v[126:129], v[50:65]
	ds_read_b128 v[110:113], v0 offset:36928
	ds_read_b128 v[114:117], v0 offset:41536
	ds_read_b128 v[118:121], v66 offset:55360
	ds_read_b128 v[130:133], v66 offset:59968
	s_waitcnt vmcnt(9)
	ds_write_b128 v67, v[74:77] offset:4608
	s_waitcnt vmcnt(8)
	ds_write_b128 v67, v[102:105] offset:23040
	global_load_dwordx4 v[74:77], v70, s[0:1] offset:1664
	global_load_dwordx4 v[102:105], v70, s[2:3] offset:1664
	s_waitcnt lgkmcnt(3)
	v_mfma_f32_32x32x16_bf16 v[2:17], v[114:117], v[118:121], v[2:17]
	s_waitcnt lgkmcnt(2)
	v_mfma_f32_32x32x16_bf16 v[18:33], v[114:117], v[130:133], v[18:33]
	v_mfma_f32_32x32x16_bf16 v[34:49], v[110:113], v[118:121], v[34:49]
	v_mfma_f32_32x32x16_bf16 v[50:65], v[110:113], v[130:133], v[50:65]
	ds_read_b128 v[110:113], v0 offset:36960
	ds_read_b128 v[118:121], v0 offset:41568
	ds_read_b128 v[122:125], v66 offset:55392
	ds_read_b128 v[126:129], v66 offset:60000
	s_waitcnt vmcnt(9)
	ds_write_b128 v67, v[78:81] offset:9216
	s_waitcnt vmcnt(8)
	ds_write_b128 v67, v[106:109] offset:27648
	global_load_dwordx4 v[78:81], v69, s[0:1] offset:1664
	global_load_dwordx4 v[106:109], v69, s[2:3] offset:1664
	s_waitcnt lgkmcnt(3)
	v_mfma_f32_32x32x16_bf16 v[2:17], v[118:121], v[122:125], v[2:17]
	s_waitcnt vmcnt(9)
	ds_write_b128 v67, v[82:85] offset:13824
	s_waitcnt vmcnt(8)
	ds_write_b128 v67, v[90:93] offset:32256
	s_waitcnt lgkmcnt(4)
	v_mfma_f32_32x32x16_bf16 v[18:33], v[118:121], v[126:129], v[18:33]
	v_mfma_f32_32x32x16_bf16 v[34:49], v[110:113], v[122:125], v[34:49]
	v_mfma_f32_32x32x16_bf16 v[50:65], v[110:113], v[126:129], v[50:65]
	s_waitcnt lgkmcnt(0)
	s_barrier
	ds_read_b128 v[82:85], v0
	ds_read_b128 v[90:93], v66 offset:18432
	ds_read_b128 v[110:113], v0 offset:32
	ds_read_b128 v[114:117], v66 offset:18464
	ds_read_b128 v[118:121], v0 offset:4608
	ds_read_b128 v[122:125], v0 offset:4640
	s_waitcnt lgkmcnt(4)
	v_mfma_f32_32x32x16_bf16 v[34:49], v[82:85], v[90:93], v[34:49]
	s_waitcnt lgkmcnt(1)
	v_mfma_f32_32x32x16_bf16 v[2:17], v[118:121], v[90:93], v[2:17]
	ds_read_b128 v[90:93], v66 offset:23040
	ds_read_b128 v[126:129], v66 offset:23072
	s_waitcnt lgkmcnt(1)
	v_mfma_f32_32x32x16_bf16 v[50:65], v[82:85], v[90:93], v[50:65]
	global_load_dwordx4 v[82:85], v72, s[0:1] offset:1792
	global_load_dwordx4 v[130:133], v72, s[2:3] offset:1792
	s_waitcnt vmcnt(9)
	ds_write_b128 v67, v[86:89] offset:36864
	s_waitcnt vmcnt(8)
	ds_write_b128 v67, v[134:137] offset:55296
	v_mfma_f32_32x32x16_bf16 v[18:33], v[118:121], v[90:93], v[18:33]
	global_load_dwordx4 v[86:89], v71, s[0:1] offset:1792
	global_load_dwordx4 v[90:93], v71, s[2:3] offset:1792
	v_mfma_f32_32x32x16_bf16 v[2:17], v[122:125], v[114:117], v[2:17]
	s_waitcnt lgkmcnt(2)
	v_mfma_f32_32x32x16_bf16 v[18:33], v[122:125], v[126:129], v[18:33]
	v_mfma_f32_32x32x16_bf16 v[34:49], v[110:113], v[114:117], v[34:49]
	v_mfma_f32_32x32x16_bf16 v[50:65], v[110:113], v[126:129], v[50:65]
	ds_read_b128 v[110:113], v0 offset:64
	ds_read_b128 v[114:117], v0 offset:4672
	ds_read_b128 v[118:121], v66 offset:18496
	ds_read_b128 v[134:137], v66 offset:23104
	s_waitcnt vmcnt(9)
	ds_write_b128 v67, v[94:97] offset:41472
	s_waitcnt vmcnt(8)
	ds_write_b128 v67, v[98:101] offset:59904
	global_load_dwordx4 v[94:97], v70, s[0:1] offset:1792
	global_load_dwordx4 v[98:101], v70, s[2:3] offset:1792
	s_waitcnt lgkmcnt(3)
	v_mfma_f32_32x32x16_bf16 v[2:17], v[114:117], v[118:121], v[2:17]
	s_waitcnt lgkmcnt(2)
	v_mfma_f32_32x32x16_bf16 v[18:33], v[114:117], v[134:137], v[18:33]
	v_mfma_f32_32x32x16_bf16 v[34:49], v[110:113], v[118:121], v[34:49]
	v_mfma_f32_32x32x16_bf16 v[50:65], v[110:113], v[134:137], v[50:65]
	ds_read_b128 v[110:113], v0 offset:96
	ds_read_b128 v[118:121], v0 offset:4704
	ds_read_b128 v[122:125], v66 offset:18528
	ds_read_b128 v[126:129], v66 offset:23136
	s_waitcnt vmcnt(9)
	ds_write_b128 v67, v[74:77] offset:46080
	s_waitcnt vmcnt(8)
	ds_write_b128 v67, v[102:105] offset:64512
	global_load_dwordx4 v[74:77], v69, s[0:1] offset:1792
	global_load_dwordx4 v[102:105], v69, s[2:3] offset:1792
	s_waitcnt lgkmcnt(3)
	v_mfma_f32_32x32x16_bf16 v[2:17], v[118:121], v[122:125], v[2:17]
	s_waitcnt vmcnt(9)
	ds_write_b128 v67, v[78:81] offset:50688
	s_waitcnt vmcnt(8)
	ds_write_b128 v68, v[106:109] offset:13824
	s_waitcnt lgkmcnt(4)
	v_mfma_f32_32x32x16_bf16 v[18:33], v[118:121], v[126:129], v[18:33]
	v_mfma_f32_32x32x16_bf16 v[34:49], v[110:113], v[122:125], v[34:49]
	v_mfma_f32_32x32x16_bf16 v[50:65], v[110:113], v[126:129], v[50:65]
	s_waitcnt lgkmcnt(0)
	s_barrier
; #define GL1_(RA, RB, i) { RA[i] = *(const u32x4*)(ap + (aoff + (i) * astep)); if ((i) < NB) RB[(i) < NB ? (i) : 0] = *(const u32x4*)(bp + (boff + (i) * bstep)); }
; #define LS1_(RA, RB, ST, i) { char* sn_ = lds + (ST) * STAGE; *(u32x4*)(sn_ + wofs + (i) * 32 * LROW) = RA[i]; \
;                               if ((i) < NB) *(u32x4*)(sn_ + STAGE_OP + wofs + (i) * 32 * LROW) = RB[(i) < NB ? (i) : 0]; }
; template <int NJ> DI void gemm_mainloop_reg(const bf16_t* __restrict__ A, int lda, const bf16_t* __restrict__ Bt, int ldb, int K, f32x16 (&acc)[2][NJ], char* lds) {
;     ...
; #pragma unroll
;   for (int i = 0; i < 4; ++i) GL1_(ra0, rb0, i);
;   ap += 128; bp += 128;
; #pragma unroll
;   for (int i = 0; i < 4; ++i) GL1_(ra1, rb1, i);
;   ap += 128; bp += 128;
; #pragma unroll
;   for (int i = 0; i < 4; ++i) LS1_(ra0, rb0, 0, i);
;   __syncthreads();
;   const int nk = K >> 6;
;   for (int kt = 0; kt < nk; kt += 2) {
;     const bool l0 = (kt + 2 < nk), l1 = (kt + 3 < nk);
;     STEP_(0, l0, ra0, rb0, true, ra1, rb1);
;     __syncthreads();
;     STEP_(1, l1, ra1, rb1, l0, ra0, rb0);
;     __syncthreads();
;   }
	ds_read_b128 v[78:81], v0 offset:36864
	ds_read_b128 v[106:109], v66 offset:55296
	ds_read_b128 v[110:113], v0 offset:41472
	s_waitcnt lgkmcnt(1)
	v_mfma_f32_32x32x16_bf16 v[34:49], v[78:81], v[106:109], v[34:49]
	s_waitcnt lgkmcnt(0)
	v_mfma_f32_32x32x16_bf16 v[2:17], v[110:113], v[106:109], v[2:17]
	ds_read_b128 v[106:109], v66 offset:59904
	s_waitcnt lgkmcnt(0)
	v_mfma_f32_32x32x16_bf16 v[50:65], v[78:81], v[106:109], v[50:65]
	global_load_dwordx4 v[78:81], v72, s[0:1] offset:1920
	global_load_dwordx4 v[114:117], v72, s[2:3] offset:1920
	ds_read_b128 v[118:121], v0 offset:36896
	ds_read_b128 v[122:125], v66 offset:55328
	ds_read_b128 v[126:129], v0 offset:41504
	ds_read_b128 v[134:137], v66 offset:59936
	s_waitcnt vmcnt(9)
	ds_write_b128 v67, v[82:85]
	s_waitcnt vmcnt(8)
	ds_write_b128 v67, v[130:133] offset:18432
	v_mfma_f32_32x32x16_bf16 v[18:33], v[110:113], v[106:109], v[18:33]
	global_load_dwordx4 v[82:85], v71, s[0:1] offset:1920
	global_load_dwordx4 v[106:109], v71, s[2:3] offset:1920
	s_waitcnt lgkmcnt(3)
	v_mfma_f32_32x32x16_bf16 v[2:17], v[126:129], v[122:125], v[2:17]
	s_waitcnt lgkmcnt(2)
	v_mfma_f32_32x32x16_bf16 v[18:33], v[126:129], v[134:137], v[18:33]
	v_mfma_f32_32x32x16_bf16 v[34:49], v[118:121], v[122:125], v[34:49]
	v_mfma_f32_32x32x16_bf16 v[50:65], v[118:121], v[134:137], v[50:65]
	ds_read_b128 v[110:113], v0 offset:36928
	ds_read_b128 v[118:121], v0 offset:41536
	ds_read_b128 v[122:125], v66 offset:55360
	ds_read_b128 v[130:133], v66 offset:59968
	s_waitcnt vmcnt(9)
	ds_write_b128 v67, v[86:89] offset:4608
	s_waitcnt vmcnt(8)
	ds_write_b128 v67, v[90:93] offset:23040
	global_load_dwordx4 v[86:89], v70, s[0:1] offset:1920
	s_nop 0
	global_load_dwordx4 v[70:73], v70, s[2:3] offset:1920
	s_waitcnt lgkmcnt(3)
	v_mfma_f32_32x32x16_bf16 v[2:17], v[118:121], v[122:125], v[2:17]
	s_waitcnt lgkmcnt(2)
	v_mfma_f32_32x32x16_bf16 v[18:33], v[118:121], v[130:133], v[18:33]
	v_mfma_f32_32x32x16_bf16 v[34:49], v[110:113], v[122:125], v[34:49]
	v_mfma_f32_32x32x16_bf16 v[50:65], v[110:113], v[130:133], v[50:65]
	ds_read_b128 v[90:93], v0 offset:36960
	ds_read_b128 v[110:113], v0 offset:41568
	ds_read_b128 v[122:125], v66 offset:55392
	ds_read_b128 v[126:129], v66 offset:60000
	s_waitcnt vmcnt(9)
	ds_write_b128 v67, v[94:97] offset:9216
	s_waitcnt vmcnt(8)
	ds_write_b128 v67, v[98:101] offset:27648
	s_waitcnt lgkmcnt(3)
	v_mfma_f32_32x32x16_bf16 v[34:49], v[90:93], v[122:125], v[34:49]
	s_waitcnt lgkmcnt(2)
	v_mfma_f32_32x32x16_bf16 v[50:65], v[90:93], v[126:129], v[50:65]
	global_load_dwordx4 v[90:93], v69, s[0:1] offset:1920
	global_load_dwordx4 v[94:97], v69, s[2:3] offset:1920
	s_waitcnt vmcnt(9)
	ds_write_b128 v67, v[74:77] offset:13824
	s_waitcnt vmcnt(8)
	ds_write_b128 v67, v[102:105] offset:32256
	v_mfma_f32_32x32x16_bf16 v[2:17], v[110:113], v[122:125], v[2:17]
	v_mfma_f32_32x32x16_bf16 v[18:33], v[110:113], v[126:129], v[18:33]
	s_waitcnt lgkmcnt(0)
	s_barrier
	ds_read_b128 v[74:77], v0
	ds_read_b128 v[98:101], v66 offset:18432
	ds_read_b128 v[102:105], v0 offset:4608
	s_waitcnt lgkmcnt(1)
	v_mfma_f32_32x32x16_bf16 v[34:49], v[74:77], v[98:101], v[34:49]
	s_waitcnt lgkmcnt(0)
	v_mfma_f32_32x32x16_bf16 v[2:17], v[102:105], v[98:101], v[2:17]
	ds_read_b128 v[98:101], v66 offset:23040
	s_waitcnt lgkmcnt(0)
	v_mfma_f32_32x32x16_bf16 v[18:33], v[102:105], v[98:101], v[18:33]
	v_mfma_f32_32x32x16_bf16 v[50:65], v[74:77], v[98:101], v[50:65]
	ds_read_b128 v[74:77], v0 offset:32
	ds_read_b128 v[110:113], v66 offset:18464
	ds_read_b128 v[118:121], v0 offset:4640
	ds_read_b128 v[122:125], v66 offset:23072
	s_waitcnt vmcnt(7)
	ds_write_b128 v67, v[78:81] offset:36864
	s_waitcnt vmcnt(6)
	ds_write_b128 v67, v[114:117] offset:55296
	s_waitcnt lgkmcnt(3)
	v_mfma_f32_32x32x16_bf16 v[2:17], v[118:121], v[110:113], v[2:17]
	s_waitcnt lgkmcnt(2)
	v_mfma_f32_32x32x16_bf16 v[18:33], v[118:121], v[122:125], v[18:33]
	v_mfma_f32_32x32x16_bf16 v[34:49], v[74:77], v[110:113], v[34:49]
	v_mfma_f32_32x32x16_bf16 v[50:65], v[74:77], v[122:125], v[50:65]
	ds_read_b128 v[74:77], v0 offset:64
	ds_read_b128 v[78:81], v0 offset:4672
	ds_read_b128 v[98:101], v66 offset:18496
	ds_read_b128 v[102:105], v66 offset:23104
	s_waitcnt vmcnt(5)
	ds_write_b128 v67, v[82:85] offset:41472
	s_waitcnt vmcnt(4)
	ds_write_b128 v67, v[106:109] offset:59904
	s_waitcnt lgkmcnt(3)
	v_mfma_f32_32x32x16_bf16 v[2:17], v[78:81], v[98:101], v[2:17]
	s_waitcnt lgkmcnt(2)
	v_mfma_f32_32x32x16_bf16 v[18:33], v[78:81], v[102:105], v[18:33]
	v_mfma_f32_32x32x16_bf16 v[34:49], v[74:77], v[98:101], v[34:49]
	v_mfma_f32_32x32x16_bf16 v[50:65], v[74:77], v[102:105], v[50:65]
	ds_read_b128 v[74:77], v0 offset:96
	ds_read_b128 v[82:85], v0 offset:4704
	ds_read_b128 v[98:101], v66 offset:18528
	ds_read_b128 v[106:109], v66 offset:23136
	s_waitcnt vmcnt(3)
	ds_write_b128 v67, v[86:89] offset:46080
	s_waitcnt vmcnt(2)
	ds_write_b128 v67, v[70:73] offset:64512
	s_waitcnt lgkmcnt(3)
	v_mfma_f32_32x32x16_bf16 v[2:17], v[82:85], v[98:101], v[2:17]
	s_waitcnt vmcnt(1)
	ds_write_b128 v67, v[90:93] offset:50688
	s_waitcnt vmcnt(0)
	ds_write_b128 v68, v[94:97] offset:13824
	s_waitcnt lgkmcnt(4)
	v_mfma_f32_32x32x16_bf16 v[18:33], v[82:85], v[106:109], v[18:33]
	v_mfma_f32_32x32x16_bf16 v[34:49], v[74:77], v[98:101], v[34:49]
	v_mfma_f32_32x32x16_bf16 v[50:65], v[74:77], v[106:109], v[50:65]
	s_waitcnt lgkmcnt(0)
	s_barrier
; DI int tid_() { int t = threadIdx.x; asm volatile("" : "+v"(t)); return t; }
; DI unsigned pk2(float a, float b) { f32x2 v = {a, b}; bf16x2_t r = __builtin_convertvector(v, bf16x2_t); return __builtin_bit_cast(unsigned, r); }
; template <int NJ> DI void acc_to_lds(const f32x16 (&acc)[2][NJ], float* cl) {
;   const int tid = tid_(), lane = tid & 63, w = tid >> 6, wm = w >> 1, wn = w & 1, h = lane >> 5, c = lane & 31;
; #pragma unroll
;   for (int i = 0; i < 2; ++i)
; #pragma unroll
;     for (int j = 0; j < NJ; ++j)
; #pragma unroll
;       for (int r = 0; r < 16; ++r) {
;         const int row = wm * 64 + i * 32 + (r & 3) + 8 * (r >> 2) + 4 * h;
;         cl[row * CLD + wn * 32 * NJ + j * 32 + c] = acc[i][j][r];
;       }
; }
; template <int NJ> DI void resid_epilogue(float* __restrict__ x, bf16_t* __restrict__ xb, float* __restrict__ ssn, int mt, int nt, const float* cl, float scale) {
;   constexpr int LPR = 16 * NJ, RPP = 256 / LPR, NP = 128 / RPP;
;   const int tid = tid_(), c4 = (tid & (LPR - 1)) * 4, r0 = tid / LPR;
; #pragma unroll 4
;   for (int it = 0; it < NP; ++it) {
;     const int row = r0 + RPP * it;
;     const f32x4 c = *(const f32x4*)(cl + row * CLD + c4);
;     const size_t gi = (size_t)(mt * 128 + row) * DM + nt * (64 * NJ) + c4;
;     f32x4 xv = *(const f32x4*)(x + gi);
;     xv = xv + scale * c;
;     *(f32x4*)(x + gi) = xv;
;     u32x2 p; p.x = pk2(xv[0], xv[1]); p.y = pk2(xv[2], xv[3]);
;     *(u32x2*)(xb + (size_t)(mt * 128 + row) * LDX + nt * (64 * NJ) + c4) = p;
;     float s_ = xv[0] * xv[0] + xv[1] * xv[1] + xv[2] * xv[2] + xv[3] * xv[3];
;     if (NJ == 2) s_ += __shfl_xor(s_, 16);
;     s_ += __shfl_xor(s_, 8); s_ += __shfl_xor(s_, 4); s_ += __shfl_xor(s_, 2); s_ += __shfl_xor(s_, 1);
;     if ((tid & (LPR - 1)) == 0) atomicAdd(ssn + mt * 128 + row, s_);
;   }
	ds_read_b128 v[68:71], v0 offset:36864
	ds_read_b128 v[72:75], v66 offset:55296
	ds_read_b128 v[76:79], v0 offset:41472
	s_waitcnt lgkmcnt(1)
	v_mfma_f32_32x32x16_bf16 v[34:49], v[68:71], v[72:75], v[34:49]
	s_waitcnt lgkmcnt(0)
	v_mfma_f32_32x32x16_bf16 v[2:17], v[76:79], v[72:75], v[2:17]
	ds_read_b128 v[72:75], v66 offset:59904
	s_waitcnt lgkmcnt(0)
	v_mfma_f32_32x32x16_bf16 v[18:33], v[76:79], v[72:75], v[18:33]
	v_mfma_f32_32x32x16_bf16 v[50:65], v[68:71], v[72:75], v[50:65]
	ds_read_b128 v[68:71], v0 offset:36896
	ds_read_b128 v[80:83], v66 offset:55328
	ds_read_b128 v[84:87], v0 offset:41504
	ds_read_b128 v[88:91], v66 offset:59936
	s_waitcnt lgkmcnt(1)
	v_mfma_f32_32x32x16_bf16 v[2:17], v[84:87], v[80:83], v[2:17]
	s_waitcnt lgkmcnt(0)
	v_mfma_f32_32x32x16_bf16 v[18:33], v[84:87], v[88:91], v[18:33]
	v_mfma_f32_32x32x16_bf16 v[34:49], v[68:71], v[80:83], v[34:49]
	v_mfma_f32_32x32x16_bf16 v[50:65], v[68:71], v[88:91], v[50:65]
	ds_read_b128 v[68:71], v0 offset:36928
	ds_read_b128 v[72:75], v0 offset:41536
	ds_read_b128 v[76:79], v66 offset:55360
	ds_read_b128 v[80:83], v66 offset:59968
	s_waitcnt lgkmcnt(1)
	v_mfma_f32_32x32x16_bf16 v[2:17], v[72:75], v[76:79], v[2:17]
	s_waitcnt lgkmcnt(0)
	v_mfma_f32_32x32x16_bf16 v[18:33], v[72:75], v[80:83], v[18:33]
	v_mfma_f32_32x32x16_bf16 v[34:49], v[68:71], v[76:79], v[34:49]
	v_mfma_f32_32x32x16_bf16 v[50:65], v[68:71], v[80:83], v[50:65]
	ds_read_b128 v[68:71], v0 offset:36960
	ds_read_b128 v[76:79], v0 offset:41568
	ds_read_b128 v[84:87], v66 offset:55392
	ds_read_b128 v[88:91], v66 offset:60000
	s_waitcnt lgkmcnt(1)
	v_mfma_f32_32x32x16_bf16 v[2:17], v[76:79], v[84:87], v[2:17]
	s_waitcnt lgkmcnt(0)
	v_mfma_f32_32x32x16_bf16 v[18:33], v[76:79], v[88:91], v[18:33]
	v_mfma_f32_32x32x16_bf16 v[34:49], v[68:71], v[84:87], v[34:49]
	v_mfma_f32_32x32x16_bf16 v[50:65], v[68:71], v[88:91], v[50:65]
	s_setprio 0
	v_mov_b32_e32 v0, v199
	s_barrier
	s_add_i32 s0, s35, s11
	v_lshrrev_b32_e32 v67, 3, v0
	v_lshrrev_b32_e32 v66, 1, v0
	v_and_b32_e32 v67, 4, v67
	v_and_b32_e32 v0, 0x5f, v0
	v_and_or_b32 v66, v66, s17, v67
	v_mul_lo_u32 v66, v66, s15
	v_lshlrev_b32_e32 v0, 2, v0
	v_add3_u32 v0, 0, v66, v0
	s_nop 0
	ds_write2_b32 v0, v34, v50 offset1:32
	ds_write2_b32 v0, v35, v51 offset0:132 offset1:164
	v_add_u32_e32 v34, 0x400, v0
	ds_write2_b32 v34, v36, v52 offset0:8 offset1:40
	ds_write2_b32 v34, v37, v53 offset0:140 offset1:172
	v_add_u32_e32 v34, 0x1000, v0
	ds_write2_b32 v34, v38, v54 offset0:32 offset1:64
	ds_write2_b32 v34, v39, v55 offset0:164 offset1:196
	v_add_u32_e32 v34, 0x1400, v0
	ds_write2_b32 v34, v40, v56 offset0:40 offset1:72
	ds_write2_b32 v34, v41, v57 offset0:172 offset1:204
	v_add_u32_e32 v34, 0x2000, v0
	ds_write2_b32 v34, v42, v58 offset0:64 offset1:96
	ds_write2_b32 v34, v43, v59 offset0:196 offset1:228
	v_add_u32_e32 v34, 0x2400, v0
	ds_write2_b32 v34, v44, v60 offset0:72 offset1:104
	ds_write2_b32 v34, v45, v61 offset0:204 offset1:236
	v_add_u32_e32 v34, 0x3000, v0
	ds_write2_b32 v34, v46, v62 offset0:96 offset1:128
	v_add_u32_e32 v34, 0x3200, v0
	ds_write2_b32 v34, v47, v63 offset0:100 offset1:132
	v_add_u32_e32 v34, 0x3400, v0
	ds_write2_b32 v34, v48, v64 offset0:104 offset1:136
	v_add_u32_e32 v34, 0x3600, v0
	ds_write2_b32 v34, v49, v65 offset0:108 offset1:140
	v_add_u32_e32 v34, 0x4000, v0
	ds_write2_b32 v34, v2, v18 offset0:128 offset1:160
	v_add_u32_e32 v2, 0x4400, v0
	ds_write2_b32 v2, v3, v19 offset0:4 offset1:36
	ds_write2_b32 v2, v4, v20 offset0:136 offset1:168
	v_add_u32_e32 v2, 0x4800, v0
	ds_write2_b32 v2, v5, v21 offset0:12 offset1:44
	v_add_u32_e32 v2, 0x5000, v0
	ds_write2_b32 v2, v6, v22 offset0:160 offset1:192
	v_add_u32_e32 v2, 0x5400, v0
	ds_write2_b32 v2, v7, v23 offset0:36 offset1:68
	ds_write2_b32 v2, v8, v24 offset0:168 offset1:200
	v_add_u32_e32 v2, 0x5800, v0
	ds_write2_b32 v2, v9, v25 offset0:44 offset1:76
	v_add_u32_e32 v2, 0x6000, v0
	ds_write2_b32 v2, v10, v26 offset0:192 offset1:224
	v_add_u32_e32 v2, 0x6400, v0
	ds_write2_b32 v2, v11, v27 offset0:68 offset1:100
	ds_write2_b32 v2, v12, v28 offset0:200 offset1:232
	v_add_u32_e32 v2, 0x6800, v0
	ds_write2_b32 v2, v13, v29 offset0:76 offset1:108
	v_add_u32_e32 v2, 0x7200, v0
	ds_write2_b32 v2, v14, v30 offset0:96 offset1:128
	v_add_u32_e32 v2, 0x7400, v0
	ds_write2_b32 v2, v15, v31 offset0:100 offset1:132
	v_add_u32_e32 v2, 0x7600, v0
	v_add_u32_e32 v0, 0x7800, v0
	ds_write2_b32 v0, v17, v33 offset0:108 offset1:140
	v_mov_b32_e32 v0, v199
	ds_write2_b32 v2, v16, v32 offset0:104 offset1:136
	s_waitcnt lgkmcnt(0)
	s_barrier
	v_mov_b64_e32 v[18:19], s[72:73]
	v_ashrrev_i32_e32 v2, 31, v0
	v_lshrrev_b32_e32 v2, 27, v2
	v_and_b32_e32 v6, 31, v0
	v_add_u32_e32 v0, v0, v2
	v_ashrrev_i32_e32 v14, 5, v0
	v_add_u32_e32 v4, s0, v14
	v_mad_i64_i32 v[2:3], s[0:1], v4, s9, v[18:19]
	v_cmp_lt_i32_e32 vcc, v222, v220
	s_add_i32 s0, s35, s12
	v_add_u32_e32 v10, s0, v14
	v_cndmask_b32_e32 v0, v219, v222, vcc
	v_cmp_lt_i32_e32 vcc, v223, v220
	v_lshlrev_b32_e32 v22, 2, v0
	v_mad_i64_i32 v[8:9], s[0:1], v10, s9, v[18:19]
	v_cndmask_b32_e32 v0, v219, v223, vcc
	v_cmp_lt_i32_e32 vcc, v224, v220
	v_lshlrev_b32_e32 v23, 2, v0
	s_add_u32 s0, s36, s6
	v_cndmask_b32_e32 v0, v219, v224, vcc
	v_cmp_lt_i32_e32 vcc, v225, v220
	v_lshlrev_b32_e32 v24, 2, v0
	s_addc_u32 s1, 0, s7
	v_cndmask_b32_e32 v0, v219, v225, vcc
	v_cmp_lt_i32_e32 vcc, v226, v220
	s_add_i32 s35, s35, s13
	v_lshlrev_b32_e32 v25, 2, v0
	v_cndmask_b32_e32 v0, v219, v226, vcc
	v_add_u32_e32 v20, s37, v14
	v_add_u32_e32 v16, s35, v14
	v_lshlrev_b32_e32 v26, 2, v0
	v_cmp_eq_u32_e32 vcc, 0, v6
	v_ashrrev_i32_e32 v15, 31, v14
	v_ashrrev_i32_e32 v5, 31, v4
	v_lshlrev_b32_e32 v0, 3, v6
	v_lshlrev_b32_e32 v28, 4, v6
	v_mul_lo_u32 v6, v14, s15
	v_ashrrev_i32_e32 v21, 31, v20
	v_ashrrev_i32_e32 v11, 31, v10
	v_ashrrev_i32_e32 v17, 31, v16
	v_lshlrev_b64 v[4:5], 12, v[4:5]
	v_add3_u32 v27, v6, v28, 0
	v_lshlrev_b64 v[6:7], 12, v[20:21]
	v_lshlrev_b64 v[10:11], 12, v[10:11]
	v_lshl_add_u64 v[12:13], v[14:15], 2, s[0:1]
	v_mad_i64_i32 v[14:15], s[0:1], v16, s9, v[18:19]
	v_lshlrev_b64 v[16:17], 12, v[16:17]
	v_mad_i64_i32 v[18:19], s[0:1], v20, s9, v[18:19]
	v_lshl_add_u64 v[2:3], v[2:3], 0, v[0:1]
	v_or3_b32 v4, v4, s34, v28
	v_or3_b32 v6, v6, s34, v28
	v_lshl_add_u64 v[8:9], v[8:9], 0, v[0:1]
	v_or3_b32 v10, v10, s34, v28
	v_lshl_add_u64 v[14:15], v[14:15], 0, v[0:1]
	v_or3_b32 v16, v16, s34, v28
	v_lshl_add_u64 v[18:19], v[18:19], 0, v[0:1]
	v_lshl_add_u64 v[2:3], v[2:3], 0, s[80:81]
	v_lshl_add_u64 v[4:5], s[92:93], 0, v[4:5]
	v_lshl_add_u64 v[6:7], s[92:93], 0, v[6:7]
	v_lshl_add_u64 v[8:9], v[8:9], 0, s[80:81]
	v_lshl_add_u64 v[10:11], s[92:93], 0, v[10:11]
	v_lshl_add_u64 v[14:15], v[14:15], 0, s[80:81]
	v_lshl_add_u64 v[16:17], s[92:93], 0, v[16:17]
	v_lshl_add_u64 v[18:19], v[18:19], 0, s[80:81]
	s_mov_b64 s[0:1], 0
	s_branch .LBB0_1027

; template <int NJ> DI void gemm_mainloop_reg(const bf16_t* __restrict__ A, int lda, const bf16_t* __restrict__ Bt, int ldb, int K, f32x16 (&acc)[2][NJ], char* lds) {
;   const int tid = tid_(), lane = tid & 63, w = tid >> 6, wm = w >> 1, wn = w & 1;
;   const int lr = tid >> 3, lc = tid & 7;
;   const char* ap = (const char*)A;
;   const char* bp = (const char*)Bt;
;   const unsigned aoff = (unsigned)(lr * lda + lc * 8) * 2u, boff = (unsigned)(lr * ldb + lc * 8) * 2u;
;   const unsigned astep = (unsigned)(32 * lda) * 2u, bstep = (unsigned)(32 * ldb) * 2u;
;   constexpr int NB = 2 * NJ;
;   u32x4 ra0[4], rb0[NB], ra1[4], rb1[NB];
;   const int wofs = lr * LROW + lc * 16;
;   const int a_rd = (wm * 64 + (lane & 31)) * LROW + (lane >> 5) * 16;
;   const int b_rd = STAGE_OP + (wn * 32 * NJ + (lane & 31)) * LROW + (lane >> 5) * 16;
;     ...
; #pragma unroll
; DI int grab_next(unsigned* ctr, char* lds) {
;   volatile int* nx = (volatile int*)(lds + OFF_RR + 528);
;   if (tid_() == 0) *nx = (int)__hip_atomic_fetch_add(ctr, 1u, __ATOMIC_RELAXED, __HIP_MEMORY_SCOPE_AGENT);
;   __syncthreads();
;   const int v = __builtin_amdgcn_readfirstlane(*nx);
;   __syncthreads();
;   return v;
; }
; DI bf16_t* wsb(const Ctx& c, size_t off) { return (bf16_t*)(c.ws + off); }
; DI float* ss_site(const Ctx& c, int layer, int site) { return (float*)(c.ws + OFF_SS) + ((size_t)layer * 6 + site) * TC; }
; DI const bf16_t* wgt(const Ctx& c, size_t off) { return (const bf16_t*)(c.ws + OFF_W) + (size_t)c.layer * W_LAYER + off; }
; DI void phase_ffn_in(const Ctx& c, const bf16_t* A, size_t woff, int site) {
;   const bf16_t* Bt = wgt(c, woff);
;   bf16_t* act = wsb(c, OFF_ACT);
;   const float* ss = ss_site(c, c.layer, site);
;   float* cl = (float*)c.lds; float* rr = (float*)(c.lds + OFF_RR);
;   const int tid = tid_();
;   const int xcd_ = blockIdx.x & 7;
;   unsigned* ctr = (unsigned*)(c.ws + OFF_BAR) + CTR_FFN + ((c.chunk * 2 + c.layer) * 2 + (site == 2 ? 1 : 0)) * 8 + xcd_;
;   for (;;) {
;     const int j_ = grab_next(ctr, c.lds);
;     if (j_ >= 128 * 6) break;
;     const int mt = xcd_ * 16 + (j_ & 7) + 8 * ((j_ >> 6) & 1), nt = (j_ >> 7) * 8 + ((j_ >> 3) & 7);
;     if (nt >= 44) continue;
;     f32x16 acc[2][2]; zero_acc<2>(acc);
;     gemm_mainloop_reg<2>(A + (size_t)mt * 128 * LDX, LDX, Bt + (size_t)nt * 128 * LDX, LDX, DM, acc, c.lds);
.LBB0_1094:
	s_or_b64 exec, exec, s[2:3]
	s_cmp_lg_u32 s24, -1
	s_cselect_b32 s2, s24, 0
	s_cselect_b32 s3, s79, 0
	v_mov_b32_e32 v2, s2
	v_mov_b32_e32 v3, s3
	s_waitcnt lgkmcnt(0)
	s_barrier
	flat_load_dword v2, v[2:3] sc0 sc1
	s_waitcnt vmcnt(0)
	s_mov_b64 s[2:3], -1
	s_waitcnt lgkmcnt(0)
	s_barrier
	v_readfirstlane_b32 s4, v2
	s_cmpk_gt_i32 s4, 0x2ff
	s_cbranch_scc1 .LBB0_1089
	s_ashr_i32 s2, s4, 4
	s_and_b32 s2, s2, -8
	s_bfe_u32 s3, s4, 0x30003
	s_or_b32 s6, s2, s3
	s_cmp_gt_i32 s6, 43
	s_cbranch_scc1 .LBB0_1088
	s_lshr_b32 s2, s4, 3
	s_and_b32 s7, s4, 7
	s_and_b32 s27, s2, 8
	s_or_b32 s2, s7, s27
	v_readlane_b32 s3, v250, 20
	s_or_b32 s36, s2, s3
	v_mov_b32_e32 v34, v199
	s_mul_i32 s2, s36, 0x44000
	v_readlane_b32 s3, v252, 10
	s_add_u32 s2, s3, s2
	v_ashrrev_i32_e32 v35, 3, v34
	v_lshlrev_b32_e32 v2, 4, v34
	v_readlane_b32 s3, v252, 11
	v_and_b32_e32 v36, 0x70, v2
	v_mul_lo_u32 v2, v35, s9
	s_addc_u32 s3, s3, 0
	s_mul_i32 s4, s6, 0x44000
	v_or_b32_e32 v80, v36, v2
	s_mul_hi_i32 s5, s6, 0x44000
	s_add_u32 s4, s25, s4
	v_add_u32_e32 v79, 0x11000, v80
	v_add_u32_e32 v78, 0x22000, v80
	v_add_u32_e32 v77, 0x33000, v80
	s_addc_u32 s5, s26, s5
	global_load_dwordx4 v[2:5], v80, s[2:3]
	global_load_dwordx4 v[6:9], v79, s[2:3]
	global_load_dwordx4 v[10:13], v78, s[2:3]
	global_load_dwordx4 v[14:17], v77, s[2:3]
	global_load_dwordx4 v[18:21], v80, s[4:5]
	global_load_dwordx4 v[22:25], v79, s[4:5]
	global_load_dwordx4 v[26:29], v78, s[4:5]
	global_load_dwordx4 v[30:33], v77, s[4:5]
	v_mul_lo_u32 v35, v35, s16
	v_lshrrev_b32_e32 v37, 1, v34
	v_and_b32_e32 v38, 31, v34
	v_add3_u32 v75, v35, v36, 0
	v_and_b32_e32 v39, 16, v37
	v_and_or_b32 v37, v37, s17, v38
	global_load_dwordx4 v[82:85], v80, s[2:3] offset:128
	global_load_dwordx4 v[86:89], v79, s[2:3] offset:128
	global_load_dwordx4 v[90:93], v78, s[2:3] offset:128
	global_load_dwordx4 v[94:97], v77, s[2:3] offset:128
	global_load_dwordx4 v[98:101], v80, s[4:5] offset:128
	global_load_dwordx4 v[102:105], v79, s[4:5] offset:128
	global_load_dwordx4 v[106:109], v78, s[4:5] offset:128
	global_load_dwordx4 v[110:113], v77, s[4:5] offset:128
	v_mul_lo_u32 v35, v37, s16
	v_add3_u32 v73, v35, v39, 0
	v_add_u32_e32 v76, 0xd800, v75
	s_waitcnt vmcnt(15)
	ds_write_b128 v75, v[2:5]
	s_waitcnt vmcnt(14)
	ds_write_b128 v75, v[6:9] offset:4608
	s_waitcnt vmcnt(13)
	ds_write_b128 v75, v[10:13] offset:9216
	s_waitcnt vmcnt(12)
	ds_write_b128 v75, v[14:17] offset:13824
	s_waitcnt vmcnt(11)
	ds_write_b128 v75, v[18:21] offset:18432
	s_waitcnt vmcnt(10)
	ds_write_b128 v75, v[22:25] offset:23040
	s_waitcnt vmcnt(9)
	ds_write_b128 v75, v[26:29] offset:27648
	s_waitcnt vmcnt(8)
	ds_write_b128 v75, v[30:33] offset:32256
	v_and_b32_e32 v2, 0x5f, v34
	v_mul_u32_u24_e32 v2, 0x90, v2
	v_add3_u32 v74, v2, v39, 0
	s_waitcnt lgkmcnt(0)
	s_barrier
	ds_read_b128 v[18:21], v73
	ds_read_b128 v[2:5], v74 offset:18432
	ds_read_b128 v[114:117], v73 offset:32
	ds_read_b128 v[118:121], v74 offset:18464
	ds_read_b128 v[22:25], v73 offset:4608
	ds_read_b128 v[122:125], v73 offset:4640
	ds_read_b128 v[26:29], v74 offset:23040
	ds_read_b128 v[126:129], v74 offset:23072
	global_load_dwordx4 v[130:133], v80, s[2:3] offset:256
	global_load_dwordx4 v[134:137], v80, s[4:5] offset:256
	s_waitcnt lgkmcnt(6)
	s_setprio 1
	v_mfma_f32_32x32x16_bf16 v[34:49], v[18:21], v[2:5], 0
	s_waitcnt vmcnt(9)
	ds_write_b128 v75, v[82:85] offset:36864
	s_waitcnt vmcnt(5)
	ds_write_b128 v75, v[98:101] offset:55296
	s_waitcnt lgkmcnt(5)
	v_mfma_f32_32x32x16_bf16 v[2:17], v[22:25], v[2:5], 0
	s_waitcnt lgkmcnt(3)
	v_mfma_f32_32x32x16_bf16 v[50:65], v[18:21], v[26:29], 0
	v_mfma_f32_32x32x16_bf16 v[18:33], v[22:25], v[26:29], 0
	global_load_dwordx4 v[82:85], v79, s[2:3] offset:256
	global_load_dwordx4 v[98:101], v79, s[4:5] offset:256
	v_mfma_f32_32x32x16_bf16 v[34:49], v[114:117], v[118:121], v[34:49]
	v_mfma_f32_32x32x16_bf16 v[2:17], v[122:125], v[118:121], v[2:17]
	s_waitcnt lgkmcnt(2)
	v_mfma_f32_32x32x16_bf16 v[50:65], v[114:117], v[126:129], v[50:65]
	ds_read_b128 v[114:117], v73 offset:64
	ds_read_b128 v[118:121], v73 offset:4672
	ds_read_b128 v[138:141], v74 offset:18496
	ds_read_b128 v[142:145], v74 offset:23104
	ds_write_b128 v75, v[86:89] offset:41472
	s_waitcnt vmcnt(6)
	ds_write_b128 v75, v[102:105] offset:59904
	v_mfma_f32_32x32x16_bf16 v[18:33], v[122:125], v[126:129], v[18:33]
	global_load_dwordx4 v[86:89], v78, s[2:3] offset:256
	global_load_dwordx4 v[102:105], v78, s[4:5] offset:256
	s_waitcnt lgkmcnt(3)
	v_mfma_f32_32x32x16_bf16 v[34:49], v[114:117], v[138:141], v[34:49]
	v_mfma_f32_32x32x16_bf16 v[2:17], v[118:121], v[138:141], v[2:17]
	s_waitcnt lgkmcnt(2)
	v_mfma_f32_32x32x16_bf16 v[50:65], v[114:117], v[142:145], v[50:65]
	ds_read_b128 v[114:117], v73 offset:96
	ds_read_b128 v[122:125], v73 offset:4704
	ds_read_b128 v[126:129], v74 offset:18528
	ds_read_b128 v[138:141], v74 offset:23136
	ds_write_b128 v75, v[90:93] offset:46080
	s_waitcnt vmcnt(7)
	ds_write_b128 v75, v[106:109] offset:64512
	v_mfma_f32_32x32x16_bf16 v[18:33], v[118:121], v[142:145], v[18:33]
	global_load_dwordx4 v[90:93], v77, s[2:3] offset:256
	global_load_dwordx4 v[106:109], v77, s[4:5] offset:256
	s_waitcnt lgkmcnt(3)
	v_mfma_f32_32x32x16_bf16 v[34:49], v[114:117], v[126:129], v[34:49]
	ds_write_b128 v75, v[94:97] offset:50688
	s_waitcnt vmcnt(8)
	ds_write_b128 v76, v[110:113] offset:13824
	v_mfma_f32_32x32x16_bf16 v[2:17], v[122:125], v[126:129], v[2:17]
	s_waitcnt lgkmcnt(4)
	v_mfma_f32_32x32x16_bf16 v[50:65], v[114:117], v[138:141], v[50:65]
	v_mfma_f32_32x32x16_bf16 v[18:33], v[122:125], v[138:141], v[18:33]
	s_waitcnt lgkmcnt(0)
	s_barrier
; #define GL1_(RA, RB, i) { RA[i] = *(const u32x4*)(ap + (aoff + (i) * astep)); if ((i) < NB) RB[(i) < NB ? (i) : 0] = *(const u32x4*)(bp + (boff + (i) * bstep)); }
; #define LS1_(RA, RB, ST, i) { char* sn_ = lds + (ST) * STAGE; *(u32x4*)(sn_ + wofs + (i) * 32 * LROW) = RA[i]; \
;                               if ((i) < NB) *(u32x4*)(sn_ + STAGE_OP + wofs + (i) * 32 * LROW) = RB[(i) < NB ? (i) : 0]; }
; template <int NJ> DI void gemm_mainloop_reg(const bf16_t* __restrict__ A, int lda, const bf16_t* __restrict__ Bt, int ldb, int K, f32x16 (&acc)[2][NJ], char* lds) {
;     ...
; #pragma unroll
;   for (int i = 0; i < 4; ++i) GL1_(ra0, rb0, i);
;   ap += 128; bp += 128;
; #pragma unroll
;   for (int i = 0; i < 4; ++i) GL1_(ra1, rb1, i);
;   ap += 128; bp += 128;
; #pragma unroll
;   for (int i = 0; i < 4; ++i) LS1_(ra0, rb0, 0, i);
;   __syncthreads();
;   const int nk = K >> 6;
;   for (int kt = 0; kt < nk; kt += 2) {
;     const bool l0 = (kt + 2 < nk), l1 = (kt + 3 < nk);
;     STEP_(0, l0, ra0, rb0, true, ra1, rb1);
;     __syncthreads();
;     STEP_(1, l1, ra1, rb1, l0, ra0, rb0);
;     __syncthreads();
	ds_read_b128 v[94:97], v73 offset:36864
	ds_read_b128 v[110:113], v74 offset:55296
	ds_read_b128 v[114:117], v73 offset:36896
	ds_read_b128 v[118:121], v74 offset:55328
	ds_read_b128 v[122:125], v73 offset:41472
	ds_read_b128 v[126:129], v73 offset:41504
	s_waitcnt lgkmcnt(4)
	v_mfma_f32_32x32x16_bf16 v[34:49], v[94:97], v[110:113], v[34:49]
	s_waitcnt lgkmcnt(1)
	v_mfma_f32_32x32x16_bf16 v[2:17], v[122:125], v[110:113], v[2:17]
	ds_read_b128 v[110:113], v74 offset:59904
	ds_read_b128 v[138:141], v74 offset:59936
	s_waitcnt lgkmcnt(1)
	v_mfma_f32_32x32x16_bf16 v[50:65], v[94:97], v[110:113], v[50:65]
	global_load_dwordx4 v[94:97], v80, s[2:3] offset:384
	global_load_dwordx4 v[142:145], v80, s[4:5] offset:384
	s_waitcnt vmcnt(9)
	ds_write_b128 v75, v[130:133]
	s_waitcnt vmcnt(8)
	ds_write_b128 v75, v[134:137] offset:18432
	v_mfma_f32_32x32x16_bf16 v[18:33], v[122:125], v[110:113], v[18:33]
	v_mfma_f32_32x32x16_bf16 v[34:49], v[114:117], v[118:121], v[34:49]
	s_waitcnt lgkmcnt(2)
	v_mfma_f32_32x32x16_bf16 v[50:65], v[114:117], v[138:141], v[50:65]
	global_load_dwordx4 v[110:113], v79, s[2:3] offset:384
	global_load_dwordx4 v[114:117], v79, s[4:5] offset:384
	v_mfma_f32_32x32x16_bf16 v[2:17], v[126:129], v[118:121], v[2:17]
	ds_read_b128 v[118:121], v73 offset:36928
	ds_read_b128 v[122:125], v73 offset:41536
	ds_read_b128 v[130:133], v74 offset:55360
	ds_read_b128 v[134:137], v74 offset:59968
	s_waitcnt vmcnt(9)
	ds_write_b128 v75, v[82:85] offset:4608
	s_waitcnt vmcnt(8)
	ds_write_b128 v75, v[98:101] offset:23040
	v_mfma_f32_32x32x16_bf16 v[18:33], v[126:129], v[138:141], v[18:33]
	global_load_dwordx4 v[82:85], v78, s[2:3] offset:384
	global_load_dwordx4 v[98:101], v78, s[4:5] offset:384
	s_waitcnt lgkmcnt(3)
	v_mfma_f32_32x32x16_bf16 v[34:49], v[118:121], v[130:133], v[34:49]
	v_mfma_f32_32x32x16_bf16 v[2:17], v[122:125], v[130:133], v[2:17]
	s_waitcnt lgkmcnt(2)
	v_mfma_f32_32x32x16_bf16 v[50:65], v[118:121], v[134:137], v[50:65]
	ds_read_b128 v[118:121], v73 offset:36960
	ds_read_b128 v[126:129], v73 offset:41568
	ds_read_b128 v[130:133], v74 offset:55392
	ds_read_b128 v[138:141], v74 offset:60000
	s_waitcnt vmcnt(9)
	ds_write_b128 v75, v[86:89] offset:9216
	s_waitcnt vmcnt(8)
	ds_write_b128 v75, v[102:105] offset:27648
	v_mfma_f32_32x32x16_bf16 v[18:33], v[122:125], v[134:137], v[18:33]
	global_load_dwordx4 v[86:89], v77, s[2:3] offset:384
	global_load_dwordx4 v[102:105], v77, s[4:5] offset:384
	s_waitcnt lgkmcnt(3)
	v_mfma_f32_32x32x16_bf16 v[34:49], v[118:121], v[130:133], v[34:49]
	s_waitcnt vmcnt(9)
	ds_write_b128 v75, v[90:93] offset:13824
	s_waitcnt vmcnt(8)
	ds_write_b128 v75, v[106:109] offset:32256
	v_mfma_f32_32x32x16_bf16 v[2:17], v[126:129], v[130:133], v[2:17]
	s_waitcnt lgkmcnt(4)
	v_mfma_f32_32x32x16_bf16 v[50:65], v[118:121], v[138:141], v[50:65]
	v_mfma_f32_32x32x16_bf16 v[18:33], v[126:129], v[138:141], v[18:33]
	s_waitcnt lgkmcnt(0)
	s_barrier
	ds_read_b128 v[90:93], v73
	ds_read_b128 v[106:109], v74 offset:18432
	ds_read_b128 v[118:121], v73 offset:32
	ds_read_b128 v[122:125], v74 offset:18464
	ds_read_b128 v[126:129], v73 offset:4608
	ds_read_b128 v[130:133], v73 offset:4640
	s_waitcnt lgkmcnt(4)
	v_mfma_f32_32x32x16_bf16 v[34:49], v[90:93], v[106:109], v[34:49]
	s_waitcnt lgkmcnt(1)
	v_mfma_f32_32x32x16_bf16 v[2:17], v[126:129], v[106:109], v[2:17]
	ds_read_b128 v[106:109], v74 offset:23040
	ds_read_b128 v[134:137], v74 offset:23072
	s_waitcnt lgkmcnt(1)
	v_mfma_f32_32x32x16_bf16 v[50:65], v[90:93], v[106:109], v[50:65]
	global_load_dwordx4 v[90:93], v80, s[2:3] offset:512
	global_load_dwordx4 v[138:141], v80, s[4:5] offset:512
	s_waitcnt vmcnt(9)
	ds_write_b128 v75, v[94:97] offset:36864
	s_waitcnt vmcnt(8)
	ds_write_b128 v75, v[142:145] offset:55296
	v_mfma_f32_32x32x16_bf16 v[18:33], v[126:129], v[106:109], v[18:33]
	global_load_dwordx4 v[94:97], v79, s[2:3] offset:512
	global_load_dwordx4 v[106:109], v79, s[4:5] offset:512
	v_mfma_f32_32x32x16_bf16 v[34:49], v[118:121], v[122:125], v[34:49]
	v_mfma_f32_32x32x16_bf16 v[2:17], v[130:133], v[122:125], v[2:17]
	s_waitcnt lgkmcnt(2)
	v_mfma_f32_32x32x16_bf16 v[50:65], v[118:121], v[134:137], v[50:65]
	ds_read_b128 v[118:121], v73 offset:64
	ds_read_b128 v[122:125], v73 offset:4672
	ds_read_b128 v[126:129], v74 offset:18496
	ds_read_b128 v[142:145], v74 offset:23104
	s_waitcnt vmcnt(9)
	ds_write_b128 v75, v[110:113] offset:41472
	s_waitcnt vmcnt(8)
	ds_write_b128 v75, v[114:117] offset:59904
	v_mfma_f32_32x32x16_bf16 v[18:33], v[130:133], v[134:137], v[18:33]
	global_load_dwordx4 v[110:113], v78, s[2:3] offset:512
	global_load_dwordx4 v[114:117], v78, s[4:5] offset:512
	s_waitcnt lgkmcnt(3)
	v_mfma_f32_32x32x16_bf16 v[34:49], v[118:121], v[126:129], v[34:49]
	v_mfma_f32_32x32x16_bf16 v[2:17], v[122:125], v[126:129], v[2:17]
	s_waitcnt lgkmcnt(2)
	v_mfma_f32_32x32x16_bf16 v[50:65], v[118:121], v[142:145], v[50:65]
	ds_read_b128 v[118:121], v73 offset:96
	ds_read_b128 v[126:129], v73 offset:4704
	ds_read_b128 v[130:133], v74 offset:18528
	ds_read_b128 v[134:137], v74 offset:23136
	s_waitcnt vmcnt(9)
	ds_write_b128 v75, v[82:85] offset:46080
	s_waitcnt vmcnt(8)
	ds_write_b128 v75, v[98:101] offset:64512
	v_mfma_f32_32x32x16_bf16 v[18:33], v[122:125], v[142:145], v[18:33]
	global_load_dwordx4 v[82:85], v77, s[2:3] offset:512
	global_load_dwordx4 v[98:101], v77, s[4:5] offset:512
	s_waitcnt lgkmcnt(3)
	v_mfma_f32_32x32x16_bf16 v[34:49], v[118:121], v[130:133], v[34:49]
	s_waitcnt vmcnt(9)
	ds_write_b128 v75, v[86:89] offset:50688
	s_waitcnt vmcnt(8)
	ds_write_b128 v76, v[102:105] offset:13824
	v_mfma_f32_32x32x16_bf16 v[2:17], v[126:129], v[130:133], v[2:17]
	s_waitcnt lgkmcnt(4)
	v_mfma_f32_32x32x16_bf16 v[50:65], v[118:121], v[134:137], v[50:65]
	v_mfma_f32_32x32x16_bf16 v[18:33], v[126:129], v[134:137], v[18:33]
	s_waitcnt lgkmcnt(0)
	s_barrier
; #define GL1_(RA, RB, i) { RA[i] = *(const u32x4*)(ap + (aoff + (i) * astep)); if ((i) < NB) RB[(i) < NB ? (i) : 0] = *(const u32x4*)(bp + (boff + (i) * bstep)); }
; #define LS1_(RA, RB, ST, i) { char* sn_ = lds + (ST) * STAGE; *(u32x4*)(sn_ + wofs + (i) * 32 * LROW) = RA[i]; \
;                               if ((i) < NB) *(u32x4*)(sn_ + STAGE_OP + wofs + (i) * 32 * LROW) = RB[(i) < NB ? (i) : 0]; }
; template <int NJ> DI void gemm_mainloop_reg(const bf16_t* __restrict__ A, int lda, const bf16_t* __restrict__ Bt, int ldb, int K, f32x16 (&acc)[2][NJ], char* lds) {
;     ...
; #pragma unroll
;   for (int i = 0; i < 4; ++i) GL1_(ra0, rb0, i);
;   ap += 128; bp += 128;
; #pragma unroll
;   for (int i = 0; i < 4; ++i) GL1_(ra1, rb1, i);
;   ap += 128; bp += 128;
; #pragma unroll
;   for (int i = 0; i < 4; ++i) LS1_(ra0, rb0, 0, i);
;   __syncthreads();
;   const int nk = K >> 6;
;   for (int kt = 0; kt < nk; kt += 2) {
;     const bool l0 = (kt + 2 < nk), l1 = (kt + 3 < nk);
;     STEP_(0, l0, ra0, rb0, true, ra1, rb1);
;     __syncthreads();
;     STEP_(1, l1, ra1, rb1, l0, ra0, rb0);
;     __syncthreads();
	ds_read_b128 v[86:89], v73 offset:36864
	ds_read_b128 v[102:105], v74 offset:55296
	ds_read_b128 v[118:121], v73 offset:36896
	ds_read_b128 v[122:125], v74 offset:55328
	ds_read_b128 v[126:129], v73 offset:41472
	ds_read_b128 v[130:133], v73 offset:41504
	s_waitcnt lgkmcnt(4)
	v_mfma_f32_32x32x16_bf16 v[34:49], v[86:89], v[102:105], v[34:49]
	s_waitcnt lgkmcnt(1)
	v_mfma_f32_32x32x16_bf16 v[2:17], v[126:129], v[102:105], v[2:17]
	ds_read_b128 v[102:105], v74 offset:59904
	ds_read_b128 v[134:137], v74 offset:59936
	s_waitcnt lgkmcnt(1)
	v_mfma_f32_32x32x16_bf16 v[50:65], v[86:89], v[102:105], v[50:65]
	global_load_dwordx4 v[86:89], v80, s[2:3] offset:640
	global_load_dwordx4 v[142:145], v80, s[4:5] offset:640
	s_waitcnt vmcnt(9)
	ds_write_b128 v75, v[90:93]
	s_waitcnt vmcnt(8)
	ds_write_b128 v75, v[138:141] offset:18432
	v_mfma_f32_32x32x16_bf16 v[18:33], v[126:129], v[102:105], v[18:33]
	global_load_dwordx4 v[90:93], v79, s[2:3] offset:640
	global_load_dwordx4 v[102:105], v79, s[4:5] offset:640
	v_mfma_f32_32x32x16_bf16 v[34:49], v[118:121], v[122:125], v[34:49]
	v_mfma_f32_32x32x16_bf16 v[2:17], v[130:133], v[122:125], v[2:17]
	s_waitcnt lgkmcnt(2)
	v_mfma_f32_32x32x16_bf16 v[50:65], v[118:121], v[134:137], v[50:65]
	ds_read_b128 v[118:121], v73 offset:36928
	ds_read_b128 v[122:125], v73 offset:41536
	ds_read_b128 v[126:129], v74 offset:55360
	ds_read_b128 v[138:141], v74 offset:59968
	s_waitcnt vmcnt(9)
	ds_write_b128 v75, v[94:97] offset:4608
	s_waitcnt vmcnt(8)
	ds_write_b128 v75, v[106:109] offset:23040
	v_mfma_f32_32x32x16_bf16 v[18:33], v[130:133], v[134:137], v[18:33]
	global_load_dwordx4 v[94:97], v78, s[2:3] offset:640
	global_load_dwordx4 v[106:109], v78, s[4:5] offset:640
	s_waitcnt lgkmcnt(3)
	v_mfma_f32_32x32x16_bf16 v[34:49], v[118:121], v[126:129], v[34:49]
	v_mfma_f32_32x32x16_bf16 v[2:17], v[122:125], v[126:129], v[2:17]
	s_waitcnt lgkmcnt(2)
	v_mfma_f32_32x32x16_bf16 v[50:65], v[118:121], v[138:141], v[50:65]
	ds_read_b128 v[118:121], v73 offset:36960
	ds_read_b128 v[126:129], v73 offset:41568
	ds_read_b128 v[130:133], v74 offset:55392
	ds_read_b128 v[134:137], v74 offset:60000
	s_waitcnt vmcnt(9)
	ds_write_b128 v75, v[110:113] offset:9216
	s_waitcnt vmcnt(8)
	ds_write_b128 v75, v[114:117] offset:27648
	v_mfma_f32_32x32x16_bf16 v[18:33], v[122:125], v[138:141], v[18:33]
	global_load_dwordx4 v[110:113], v77, s[2:3] offset:640
	global_load_dwordx4 v[114:117], v77, s[4:5] offset:640
	s_waitcnt lgkmcnt(3)
	v_mfma_f32_32x32x16_bf16 v[34:49], v[118:121], v[130:133], v[34:49]
	s_waitcnt vmcnt(9)
	ds_write_b128 v75, v[82:85] offset:13824
	s_waitcnt vmcnt(8)
	ds_write_b128 v75, v[98:101] offset:32256
	v_mfma_f32_32x32x16_bf16 v[2:17], v[126:129], v[130:133], v[2:17]
	s_waitcnt lgkmcnt(4)
	v_mfma_f32_32x32x16_bf16 v[50:65], v[118:121], v[134:137], v[50:65]
	v_mfma_f32_32x32x16_bf16 v[18:33], v[126:129], v[134:137], v[18:33]
	s_waitcnt lgkmcnt(0)
	s_barrier
	ds_read_b128 v[82:85], v73
	ds_read_b128 v[98:101], v74 offset:18432
	ds_read_b128 v[118:121], v73 offset:32
	ds_read_b128 v[122:125], v74 offset:18464
	ds_read_b128 v[126:129], v73 offset:4608
	ds_read_b128 v[130:133], v73 offset:4640
	s_waitcnt lgkmcnt(4)
	v_mfma_f32_32x32x16_bf16 v[34:49], v[82:85], v[98:101], v[34:49]
	s_waitcnt lgkmcnt(1)
	v_mfma_f32_32x32x16_bf16 v[2:17], v[126:129], v[98:101], v[2:17]
	ds_read_b128 v[98:101], v74 offset:23040
	ds_read_b128 v[134:137], v74 offset:23072
	s_waitcnt lgkmcnt(1)
	v_mfma_f32_32x32x16_bf16 v[50:65], v[82:85], v[98:101], v[50:65]
	global_load_dwordx4 v[82:85], v80, s[2:3] offset:768
	global_load_dwordx4 v[138:141], v80, s[4:5] offset:768
	s_waitcnt vmcnt(9)
	ds_write_b128 v75, v[86:89] offset:36864
	s_waitcnt vmcnt(8)
	ds_write_b128 v75, v[142:145] offset:55296
	v_mfma_f32_32x32x16_bf16 v[18:33], v[126:129], v[98:101], v[18:33]
	global_load_dwordx4 v[86:89], v79, s[2:3] offset:768
	global_load_dwordx4 v[98:101], v79, s[4:5] offset:768
	v_mfma_f32_32x32x16_bf16 v[34:49], v[118:121], v[122:125], v[34:49]
	v_mfma_f32_32x32x16_bf16 v[2:17], v[130:133], v[122:125], v[2:17]
	s_waitcnt lgkmcnt(2)
	v_mfma_f32_32x32x16_bf16 v[50:65], v[118:121], v[134:137], v[50:65]
	ds_read_b128 v[118:121], v73 offset:64
	ds_read_b128 v[122:125], v73 offset:4672
	ds_read_b128 v[126:129], v74 offset:18496
	ds_read_b128 v[142:145], v74 offset:23104
	s_waitcnt vmcnt(9)
	ds_write_b128 v75, v[90:93] offset:41472
	s_waitcnt vmcnt(8)
	ds_write_b128 v75, v[102:105] offset:59904
	v_mfma_f32_32x32x16_bf16 v[18:33], v[130:133], v[134:137], v[18:33]
	global_load_dwordx4 v[90:93], v78, s[2:3] offset:768
	global_load_dwordx4 v[102:105], v78, s[4:5] offset:768
	s_waitcnt lgkmcnt(3)
	v_mfma_f32_32x32x16_bf16 v[34:49], v[118:121], v[126:129], v[34:49]
	v_mfma_f32_32x32x16_bf16 v[2:17], v[122:125], v[126:129], v[2:17]
	s_waitcnt lgkmcnt(2)
	v_mfma_f32_32x32x16_bf16 v[50:65], v[118:121], v[142:145], v[50:65]
	ds_read_b128 v[118:121], v73 offset:96
	ds_read_b128 v[126:129], v73 offset:4704
	ds_read_b128 v[130:133], v74 offset:18528
	ds_read_b128 v[134:137], v74 offset:23136
	s_waitcnt vmcnt(9)
	ds_write_b128 v75, v[94:97] offset:46080
	s_waitcnt vmcnt(8)
	ds_write_b128 v75, v[106:109] offset:64512
	v_mfma_f32_32x32x16_bf16 v[18:33], v[122:125], v[142:145], v[18:33]
	global_load_dwordx4 v[94:97], v77, s[2:3] offset:768
	global_load_dwordx4 v[106:109], v77, s[4:5] offset:768
	s_waitcnt lgkmcnt(3)
	v_mfma_f32_32x32x16_bf16 v[34:49], v[118:121], v[130:133], v[34:49]
	s_waitcnt vmcnt(9)
	ds_write_b128 v75, v[110:113] offset:50688
	s_waitcnt vmcnt(8)
	ds_write_b128 v76, v[114:117] offset:13824
	v_mfma_f32_32x32x16_bf16 v[2:17], v[126:129], v[130:133], v[2:17]
	s_waitcnt lgkmcnt(4)
	v_mfma_f32_32x32x16_bf16 v[50:65], v[118:121], v[134:137], v[50:65]
	v_mfma_f32_32x32x16_bf16 v[18:33], v[126:129], v[134:137], v[18:33]
	s_waitcnt lgkmcnt(0)
	s_barrier
; #define GL1_(RA, RB, i) { RA[i] = *(const u32x4*)(ap + (aoff + (i) * astep)); if ((i) < NB) RB[(i) < NB ? (i) : 0] = *(const u32x4*)(bp + (boff + (i) * bstep)); }
; #define LS1_(RA, RB, ST, i) { char* sn_ = lds + (ST) * STAGE; *(u32x4*)(sn_ + wofs + (i) * 32 * LROW) = RA[i]; \
;                               if ((i) < NB) *(u32x4*)(sn_ + STAGE_OP + wofs + (i) * 32 * LROW) = RB[(i) < NB ? (i) : 0]; }
; template <int NJ> DI void gemm_mainloop_reg(const bf16_t* __restrict__ A, int lda, const bf16_t* __restrict__ Bt, int ldb, int K, f32x16 (&acc)[2][NJ], char* lds) {
;     ...
; #pragma unroll
;   for (int i = 0; i < 4; ++i) GL1_(ra0, rb0, i);
;   ap += 128; bp += 128;
; #pragma unroll
;   for (int i = 0; i < 4; ++i) GL1_(ra1, rb1, i);
;   ap += 128; bp += 128;
; #pragma unroll
;   for (int i = 0; i < 4; ++i) LS1_(ra0, rb0, 0, i);
;   __syncthreads();
;   const int nk = K >> 6;
;   for (int kt = 0; kt < nk; kt += 2) {
;     const bool l0 = (kt + 2 < nk), l1 = (kt + 3 < nk);
;     STEP_(0, l0, ra0, rb0, true, ra1, rb1);
;     __syncthreads();
;     STEP_(1, l1, ra1, rb1, l0, ra0, rb0);
;     __syncthreads();
	ds_read_b128 v[110:113], v73 offset:36864
	ds_read_b128 v[114:117], v74 offset:55296
	ds_read_b128 v[118:121], v73 offset:36896
	ds_read_b128 v[122:125], v74 offset:55328
	ds_read_b128 v[126:129], v73 offset:41472
	ds_read_b128 v[130:133], v73 offset:41504
	s_waitcnt lgkmcnt(4)
	v_mfma_f32_32x32x16_bf16 v[34:49], v[110:113], v[114:117], v[34:49]
	s_waitcnt lgkmcnt(1)
	v_mfma_f32_32x32x16_bf16 v[2:17], v[126:129], v[114:117], v[2:17]
	ds_read_b128 v[114:117], v74 offset:59904
	ds_read_b128 v[134:137], v74 offset:59936
	s_waitcnt lgkmcnt(1)
	v_mfma_f32_32x32x16_bf16 v[50:65], v[110:113], v[114:117], v[50:65]
	global_load_dwordx4 v[110:113], v80, s[2:3] offset:896
	global_load_dwordx4 v[142:145], v80, s[4:5] offset:896
	s_waitcnt vmcnt(9)
	ds_write_b128 v75, v[82:85]
	s_waitcnt vmcnt(8)
	ds_write_b128 v75, v[138:141] offset:18432
	v_mfma_f32_32x32x16_bf16 v[18:33], v[126:129], v[114:117], v[18:33]
	global_load_dwordx4 v[82:85], v79, s[2:3] offset:896
	global_load_dwordx4 v[114:117], v79, s[4:5] offset:896
	v_mfma_f32_32x32x16_bf16 v[34:49], v[118:121], v[122:125], v[34:49]
	v_mfma_f32_32x32x16_bf16 v[2:17], v[130:133], v[122:125], v[2:17]
	s_waitcnt lgkmcnt(2)
	v_mfma_f32_32x32x16_bf16 v[50:65], v[118:121], v[134:137], v[50:65]
	ds_read_b128 v[118:121], v73 offset:36928
	ds_read_b128 v[122:125], v73 offset:41536
	ds_read_b128 v[126:129], v74 offset:55360
	ds_read_b128 v[138:141], v74 offset:59968
	s_waitcnt vmcnt(9)
	ds_write_b128 v75, v[86:89] offset:4608
	s_waitcnt vmcnt(8)
	ds_write_b128 v75, v[98:101] offset:23040
	v_mfma_f32_32x32x16_bf16 v[18:33], v[130:133], v[134:137], v[18:33]
	global_load_dwordx4 v[86:89], v78, s[2:3] offset:896
	global_load_dwordx4 v[98:101], v78, s[4:5] offset:896
	s_waitcnt lgkmcnt(3)
	v_mfma_f32_32x32x16_bf16 v[34:49], v[118:121], v[126:129], v[34:49]
	v_mfma_f32_32x32x16_bf16 v[2:17], v[122:125], v[126:129], v[2:17]
	s_waitcnt lgkmcnt(2)
	v_mfma_f32_32x32x16_bf16 v[50:65], v[118:121], v[138:141], v[50:65]
	ds_read_b128 v[118:121], v73 offset:36960
	ds_read_b128 v[126:129], v73 offset:41568
	ds_read_b128 v[130:133], v74 offset:55392
	ds_read_b128 v[134:137], v74 offset:60000
	s_waitcnt vmcnt(9)
	ds_write_b128 v75, v[90:93] offset:9216
	s_waitcnt vmcnt(8)
	ds_write_b128 v75, v[102:105] offset:27648
	v_mfma_f32_32x32x16_bf16 v[18:33], v[122:125], v[138:141], v[18:33]
	global_load_dwordx4 v[90:93], v77, s[2:3] offset:896
	global_load_dwordx4 v[102:105], v77, s[4:5] offset:896
	s_waitcnt lgkmcnt(3)
	v_mfma_f32_32x32x16_bf16 v[34:49], v[118:121], v[130:133], v[34:49]
	s_waitcnt vmcnt(9)
	ds_write_b128 v75, v[94:97] offset:13824
	s_waitcnt vmcnt(8)
	ds_write_b128 v75, v[106:109] offset:32256
	v_mfma_f32_32x32x16_bf16 v[2:17], v[126:129], v[130:133], v[2:17]
	s_waitcnt lgkmcnt(4)
	v_mfma_f32_32x32x16_bf16 v[50:65], v[118:121], v[134:137], v[50:65]
	v_mfma_f32_32x32x16_bf16 v[18:33], v[126:129], v[134:137], v[18:33]
	s_waitcnt lgkmcnt(0)
	s_barrier
	ds_read_b128 v[94:97], v73
	ds_read_b128 v[106:109], v74 offset:18432
	ds_read_b128 v[118:121], v73 offset:32
	ds_read_b128 v[122:125], v74 offset:18464
	ds_read_b128 v[126:129], v73 offset:4608
	ds_read_b128 v[130:133], v73 offset:4640
	s_waitcnt lgkmcnt(4)
	v_mfma_f32_32x32x16_bf16 v[34:49], v[94:97], v[106:109], v[34:49]
	s_waitcnt lgkmcnt(1)
	v_mfma_f32_32x32x16_bf16 v[2:17], v[126:129], v[106:109], v[2:17]
	ds_read_b128 v[106:109], v74 offset:23040
	ds_read_b128 v[134:137], v74 offset:23072
	s_waitcnt lgkmcnt(1)
	v_mfma_f32_32x32x16_bf16 v[50:65], v[94:97], v[106:109], v[50:65]
	global_load_dwordx4 v[94:97], v80, s[2:3] offset:1024
	global_load_dwordx4 v[138:141], v80, s[4:5] offset:1024
	s_waitcnt vmcnt(9)
	ds_write_b128 v75, v[110:113] offset:36864
	s_waitcnt vmcnt(8)
	ds_write_b128 v75, v[142:145] offset:55296
	v_mfma_f32_32x32x16_bf16 v[18:33], v[126:129], v[106:109], v[18:33]
	global_load_dwordx4 v[106:109], v79, s[2:3] offset:1024
	global_load_dwordx4 v[110:113], v79, s[4:5] offset:1024
	v_mfma_f32_32x32x16_bf16 v[34:49], v[118:121], v[122:125], v[34:49]
	v_mfma_f32_32x32x16_bf16 v[2:17], v[130:133], v[122:125], v[2:17]
	s_waitcnt lgkmcnt(2)
	v_mfma_f32_32x32x16_bf16 v[50:65], v[118:121], v[134:137], v[50:65]
	ds_read_b128 v[118:121], v73 offset:64
	ds_read_b128 v[122:125], v73 offset:4672
	ds_read_b128 v[126:129], v74 offset:18496
	ds_read_b128 v[142:145], v74 offset:23104
	s_waitcnt vmcnt(9)
	ds_write_b128 v75, v[82:85] offset:41472
	s_waitcnt vmcnt(8)
	ds_write_b128 v75, v[114:117] offset:59904
	v_mfma_f32_32x32x16_bf16 v[18:33], v[130:133], v[134:137], v[18:33]
	global_load_dwordx4 v[82:85], v78, s[2:3] offset:1024
	global_load_dwordx4 v[114:117], v78, s[4:5] offset:1024
	s_waitcnt lgkmcnt(3)
	v_mfma_f32_32x32x16_bf16 v[34:49], v[118:121], v[126:129], v[34:49]
	v_mfma_f32_32x32x16_bf16 v[2:17], v[122:125], v[126:129], v[2:17]
	s_waitcnt lgkmcnt(2)
	v_mfma_f32_32x32x16_bf16 v[50:65], v[118:121], v[142:145], v[50:65]
	ds_read_b128 v[118:121], v73 offset:96
	ds_read_b128 v[126:129], v73 offset:4704
	ds_read_b128 v[130:133], v74 offset:18528
	ds_read_b128 v[134:137], v74 offset:23136
	s_waitcnt vmcnt(9)
	ds_write_b128 v75, v[86:89] offset:46080
	s_waitcnt vmcnt(8)
	ds_write_b128 v75, v[98:101] offset:64512
	v_mfma_f32_32x32x16_bf16 v[18:33], v[122:125], v[142:145], v[18:33]
	global_load_dwordx4 v[86:89], v77, s[2:3] offset:1024
	global_load_dwordx4 v[98:101], v77, s[4:5] offset:1024
	s_waitcnt lgkmcnt(3)
	v_mfma_f32_32x32x16_bf16 v[34:49], v[118:121], v[130:133], v[34:49]
	s_waitcnt vmcnt(9)
	ds_write_b128 v75, v[90:93] offset:50688
	s_waitcnt vmcnt(8)
	ds_write_b128 v76, v[102:105] offset:13824
	v_mfma_f32_32x32x16_bf16 v[2:17], v[126:129], v[130:133], v[2:17]
	s_waitcnt lgkmcnt(4)
	v_mfma_f32_32x32x16_bf16 v[50:65], v[118:121], v[134:137], v[50:65]
	v_mfma_f32_32x32x16_bf16 v[18:33], v[126:129], v[134:137], v[18:33]
	s_waitcnt lgkmcnt(0)
	s_barrier
; #define GL1_(RA, RB, i) { RA[i] = *(const u32x4*)(ap + (aoff + (i) * astep)); if ((i) < NB) RB[(i) < NB ? (i) : 0] = *(const u32x4*)(bp + (boff + (i) * bstep)); }
; #define LS1_(RA, RB, ST, i) { char* sn_ = lds + (ST) * STAGE; *(u32x4*)(sn_ + wofs + (i) * 32 * LROW) = RA[i]; \
;                               if ((i) < NB) *(u32x4*)(sn_ + STAGE_OP + wofs + (i) * 32 * LROW) = RB[(i) < NB ? (i) : 0]; }
; template <int NJ> DI void gemm_mainloop_reg(const bf16_t* __restrict__ A, int lda, const bf16_t* __restrict__ Bt, int ldb, int K, f32x16 (&acc)[2][NJ], char* lds) {
;     ...
; #pragma unroll
;   for (int i = 0; i < 4; ++i) GL1_(ra0, rb0, i);
;   ap += 128; bp += 128;
; #pragma unroll
;   for (int i = 0; i < 4; ++i) GL1_(ra1, rb1, i);
;   ap += 128; bp += 128;
; #pragma unroll
;   for (int i = 0; i < 4; ++i) LS1_(ra0, rb0, 0, i);
;   __syncthreads();
;   const int nk = K >> 6;
;   for (int kt = 0; kt < nk; kt += 2) {
;     const bool l0 = (kt + 2 < nk), l1 = (kt + 3 < nk);
;     STEP_(0, l0, ra0, rb0, true, ra1, rb1);
;     __syncthreads();
;     STEP_(1, l1, ra1, rb1, l0, ra0, rb0);
;     __syncthreads();
	ds_read_b128 v[90:93], v73 offset:36864
	ds_read_b128 v[102:105], v74 offset:55296
	ds_read_b128 v[118:121], v73 offset:36896
	ds_read_b128 v[122:125], v74 offset:55328
	ds_read_b128 v[126:129], v73 offset:41472
	ds_read_b128 v[130:133], v73 offset:41504
	s_waitcnt lgkmcnt(4)
	v_mfma_f32_32x32x16_bf16 v[34:49], v[90:93], v[102:105], v[34:49]
	s_waitcnt lgkmcnt(1)
	v_mfma_f32_32x32x16_bf16 v[2:17], v[126:129], v[102:105], v[2:17]
	ds_read_b128 v[102:105], v74 offset:59904
	ds_read_b128 v[134:137], v74 offset:59936
	s_waitcnt lgkmcnt(1)
	v_mfma_f32_32x32x16_bf16 v[50:65], v[90:93], v[102:105], v[50:65]
	global_load_dwordx4 v[90:93], v80, s[2:3] offset:1152
	global_load_dwordx4 v[142:145], v80, s[4:5] offset:1152
	s_waitcnt vmcnt(9)
	ds_write_b128 v75, v[94:97]
	s_waitcnt vmcnt(8)
	ds_write_b128 v75, v[138:141] offset:18432
	v_mfma_f32_32x32x16_bf16 v[18:33], v[126:129], v[102:105], v[18:33]
	global_load_dwordx4 v[94:97], v79, s[2:3] offset:1152
	global_load_dwordx4 v[102:105], v79, s[4:5] offset:1152
	v_mfma_f32_32x32x16_bf16 v[34:49], v[118:121], v[122:125], v[34:49]
	v_mfma_f32_32x32x16_bf16 v[2:17], v[130:133], v[122:125], v[2:17]
	s_waitcnt lgkmcnt(2)
	v_mfma_f32_32x32x16_bf16 v[50:65], v[118:121], v[134:137], v[50:65]
	ds_read_b128 v[118:121], v73 offset:36928
	ds_read_b128 v[122:125], v73 offset:41536
	ds_read_b128 v[126:129], v74 offset:55360
	ds_read_b128 v[138:141], v74 offset:59968
	s_waitcnt vmcnt(9)
	ds_write_b128 v75, v[106:109] offset:4608
	s_waitcnt vmcnt(8)
	ds_write_b128 v75, v[110:113] offset:23040
	v_mfma_f32_32x32x16_bf16 v[18:33], v[130:133], v[134:137], v[18:33]
	global_load_dwordx4 v[106:109], v78, s[2:3] offset:1152
	global_load_dwordx4 v[110:113], v78, s[4:5] offset:1152
	s_waitcnt lgkmcnt(3)
	v_mfma_f32_32x32x16_bf16 v[34:49], v[118:121], v[126:129], v[34:49]
	v_mfma_f32_32x32x16_bf16 v[2:17], v[122:125], v[126:129], v[2:17]
	s_waitcnt lgkmcnt(2)
	v_mfma_f32_32x32x16_bf16 v[50:65], v[118:121], v[138:141], v[50:65]
	ds_read_b128 v[118:121], v73 offset:36960
	ds_read_b128 v[126:129], v73 offset:41568
	ds_read_b128 v[130:133], v74 offset:55392
	ds_read_b128 v[134:137], v74 offset:60000
	s_waitcnt vmcnt(9)
	ds_write_b128 v75, v[82:85] offset:9216
	s_waitcnt vmcnt(8)
	ds_write_b128 v75, v[114:117] offset:27648
	v_mfma_f32_32x32x16_bf16 v[18:33], v[122:125], v[138:141], v[18:33]
	global_load_dwordx4 v[82:85], v77, s[2:3] offset:1152
	global_load_dwordx4 v[114:117], v77, s[4:5] offset:1152
	s_waitcnt lgkmcnt(3)
	v_mfma_f32_32x32x16_bf16 v[34:49], v[118:121], v[130:133], v[34:49]
	s_waitcnt vmcnt(9)
	ds_write_b128 v75, v[86:89] offset:13824
	s_waitcnt vmcnt(8)
	ds_write_b128 v75, v[98:101] offset:32256
	v_mfma_f32_32x32x16_bf16 v[2:17], v[126:129], v[130:133], v[2:17]
	s_waitcnt lgkmcnt(4)
	v_mfma_f32_32x32x16_bf16 v[50:65], v[118:121], v[134:137], v[50:65]
	v_mfma_f32_32x32x16_bf16 v[18:33], v[126:129], v[134:137], v[18:33]
	s_waitcnt lgkmcnt(0)
	s_barrier
	ds_read_b128 v[86:89], v73
	ds_read_b128 v[98:101], v74 offset:18432
	ds_read_b128 v[118:121], v73 offset:32
	ds_read_b128 v[122:125], v74 offset:18464
	ds_read_b128 v[126:129], v73 offset:4608
	ds_read_b128 v[130:133], v73 offset:4640
	s_waitcnt lgkmcnt(4)
	v_mfma_f32_32x32x16_bf16 v[34:49], v[86:89], v[98:101], v[34:49]
	s_waitcnt lgkmcnt(1)
	v_mfma_f32_32x32x16_bf16 v[2:17], v[126:129], v[98:101], v[2:17]
	ds_read_b128 v[98:101], v74 offset:23040
	ds_read_b128 v[134:137], v74 offset:23072
	s_waitcnt lgkmcnt(1)
	v_mfma_f32_32x32x16_bf16 v[50:65], v[86:89], v[98:101], v[50:65]
	global_load_dwordx4 v[86:89], v80, s[2:3] offset:1280
	global_load_dwordx4 v[138:141], v80, s[4:5] offset:1280
	s_waitcnt vmcnt(9)
	ds_write_b128 v75, v[90:93] offset:36864
	s_waitcnt vmcnt(8)
	ds_write_b128 v75, v[142:145] offset:55296
	v_mfma_f32_32x32x16_bf16 v[18:33], v[126:129], v[98:101], v[18:33]
	global_load_dwordx4 v[90:93], v79, s[2:3] offset:1280
	global_load_dwordx4 v[98:101], v79, s[4:5] offset:1280
	v_mfma_f32_32x32x16_bf16 v[34:49], v[118:121], v[122:125], v[34:49]
	v_mfma_f32_32x32x16_bf16 v[2:17], v[130:133], v[122:125], v[2:17]
	s_waitcnt lgkmcnt(2)
	v_mfma_f32_32x32x16_bf16 v[50:65], v[118:121], v[134:137], v[50:65]
	ds_read_b128 v[118:121], v73 offset:64
	ds_read_b128 v[122:125], v73 offset:4672
	ds_read_b128 v[126:129], v74 offset:18496
	ds_read_b128 v[142:145], v74 offset:23104
	s_waitcnt vmcnt(9)
	ds_write_b128 v75, v[94:97] offset:41472
	s_waitcnt vmcnt(8)
	ds_write_b128 v75, v[102:105] offset:59904
	v_mfma_f32_32x32x16_bf16 v[18:33], v[130:133], v[134:137], v[18:33]
	global_load_dwordx4 v[94:97], v78, s[2:3] offset:1280
	global_load_dwordx4 v[102:105], v78, s[4:5] offset:1280
	s_waitcnt lgkmcnt(3)
	v_mfma_f32_32x32x16_bf16 v[34:49], v[118:121], v[126:129], v[34:49]
	v_mfma_f32_32x32x16_bf16 v[2:17], v[122:125], v[126:129], v[2:17]
	s_waitcnt lgkmcnt(2)
	v_mfma_f32_32x32x16_bf16 v[50:65], v[118:121], v[142:145], v[50:65]
	ds_read_b128 v[118:121], v73 offset:96
	ds_read_b128 v[126:129], v73 offset:4704
	ds_read_b128 v[130:133], v74 offset:18528
	ds_read_b128 v[134:137], v74 offset:23136
	s_waitcnt vmcnt(9)
	ds_write_b128 v75, v[106:109] offset:46080
	s_waitcnt vmcnt(8)
	ds_write_b128 v75, v[110:113] offset:64512
	v_mfma_f32_32x32x16_bf16 v[18:33], v[122:125], v[142:145], v[18:33]
	global_load_dwordx4 v[106:109], v77, s[2:3] offset:1280
	global_load_dwordx4 v[110:113], v77, s[4:5] offset:1280
	s_waitcnt lgkmcnt(3)
	v_mfma_f32_32x32x16_bf16 v[34:49], v[118:121], v[130:133], v[34:49]
	s_waitcnt vmcnt(9)
	ds_write_b128 v75, v[82:85] offset:50688
	s_waitcnt vmcnt(8)
	ds_write_b128 v76, v[114:117] offset:13824
	v_mfma_f32_32x32x16_bf16 v[2:17], v[126:129], v[130:133], v[2:17]
	s_waitcnt lgkmcnt(4)
	v_mfma_f32_32x32x16_bf16 v[50:65], v[118:121], v[134:137], v[50:65]
	v_mfma_f32_32x32x16_bf16 v[18:33], v[126:129], v[134:137], v[18:33]
	s_waitcnt lgkmcnt(0)
	s_barrier
; #define GL1_(RA, RB, i) { RA[i] = *(const u32x4*)(ap + (aoff + (i) * astep)); if ((i) < NB) RB[(i) < NB ? (i) : 0] = *(const u32x4*)(bp + (boff + (i) * bstep)); }
; #define LS1_(RA, RB, ST, i) { char* sn_ = lds + (ST) * STAGE; *(u32x4*)(sn_ + wofs + (i) * 32 * LROW) = RA[i]; \
;                               if ((i) < NB) *(u32x4*)(sn_ + STAGE_OP + wofs + (i) * 32 * LROW) = RB[(i) < NB ? (i) : 0]; }
; template <int NJ> DI void gemm_mainloop_reg(const bf16_t* __restrict__ A, int lda, const bf16_t* __restrict__ Bt, int ldb, int K, f32x16 (&acc)[2][NJ], char* lds) {
;     ...
; #pragma unroll
;   for (int i = 0; i < 4; ++i) GL1_(ra0, rb0, i);
;   ap += 128; bp += 128;
; #pragma unroll
;   for (int i = 0; i < 4; ++i) GL1_(ra1, rb1, i);
;   ap += 128; bp += 128;
; #pragma unroll
;   for (int i = 0; i < 4; ++i) LS1_(ra0, rb0, 0, i);
;   __syncthreads();
;   const int nk = K >> 6;
;   for (int kt = 0; kt < nk; kt += 2) {
;     const bool l0 = (kt + 2 < nk), l1 = (kt + 3 < nk);
;     STEP_(0, l0, ra0, rb0, true, ra1, rb1);
;     __syncthreads();
;     STEP_(1, l1, ra1, rb1, l0, ra0, rb0);
;     __syncthreads();
	ds_read_b128 v[82:85], v73 offset:36864
	ds_read_b128 v[114:117], v74 offset:55296
	ds_read_b128 v[118:121], v73 offset:36896
	ds_read_b128 v[122:125], v74 offset:55328
	ds_read_b128 v[126:129], v73 offset:41472
	ds_read_b128 v[130:133], v73 offset:41504
	s_waitcnt lgkmcnt(4)
	v_mfma_f32_32x32x16_bf16 v[34:49], v[82:85], v[114:117], v[34:49]
	s_waitcnt lgkmcnt(1)
	v_mfma_f32_32x32x16_bf16 v[2:17], v[126:129], v[114:117], v[2:17]
	ds_read_b128 v[114:117], v74 offset:59904
	ds_read_b128 v[134:137], v74 offset:59936
	s_waitcnt lgkmcnt(1)
	v_mfma_f32_32x32x16_bf16 v[50:65], v[82:85], v[114:117], v[50:65]
	global_load_dwordx4 v[82:85], v80, s[2:3] offset:1408
	global_load_dwordx4 v[142:145], v80, s[4:5] offset:1408
	s_waitcnt vmcnt(9)
	ds_write_b128 v75, v[86:89]
	s_waitcnt vmcnt(8)
	ds_write_b128 v75, v[138:141] offset:18432
	v_mfma_f32_32x32x16_bf16 v[18:33], v[126:129], v[114:117], v[18:33]
	global_load_dwordx4 v[86:89], v79, s[2:3] offset:1408
	global_load_dwordx4 v[114:117], v79, s[4:5] offset:1408
	v_mfma_f32_32x32x16_bf16 v[34:49], v[118:121], v[122:125], v[34:49]
	v_mfma_f32_32x32x16_bf16 v[2:17], v[130:133], v[122:125], v[2:17]
	s_waitcnt lgkmcnt(2)
	v_mfma_f32_32x32x16_bf16 v[50:65], v[118:121], v[134:137], v[50:65]
	ds_read_b128 v[118:121], v73 offset:36928
	ds_read_b128 v[122:125], v73 offset:41536
	ds_read_b128 v[126:129], v74 offset:55360
	ds_read_b128 v[138:141], v74 offset:59968
	s_waitcnt vmcnt(9)
	ds_write_b128 v75, v[90:93] offset:4608
	s_waitcnt vmcnt(8)
	ds_write_b128 v75, v[98:101] offset:23040
	v_mfma_f32_32x32x16_bf16 v[18:33], v[130:133], v[134:137], v[18:33]
	global_load_dwordx4 v[90:93], v78, s[2:3] offset:1408
	global_load_dwordx4 v[98:101], v78, s[4:5] offset:1408
	s_waitcnt lgkmcnt(3)
	v_mfma_f32_32x32x16_bf16 v[34:49], v[118:121], v[126:129], v[34:49]
	v_mfma_f32_32x32x16_bf16 v[2:17], v[122:125], v[126:129], v[2:17]
	s_waitcnt lgkmcnt(2)
	v_mfma_f32_32x32x16_bf16 v[50:65], v[118:121], v[138:141], v[50:65]
	ds_read_b128 v[118:121], v73 offset:36960
	ds_read_b128 v[126:129], v73 offset:41568
	ds_read_b128 v[130:133], v74 offset:55392
	ds_read_b128 v[134:137], v74 offset:60000
	s_waitcnt vmcnt(9)
	ds_write_b128 v75, v[94:97] offset:9216
	s_waitcnt vmcnt(8)
	ds_write_b128 v75, v[102:105] offset:27648
	v_mfma_f32_32x32x16_bf16 v[18:33], v[122:125], v[138:141], v[18:33]
	global_load_dwordx4 v[94:97], v77, s[2:3] offset:1408
	global_load_dwordx4 v[102:105], v77, s[4:5] offset:1408
	s_waitcnt lgkmcnt(3)
	v_mfma_f32_32x32x16_bf16 v[34:49], v[118:121], v[130:133], v[34:49]
	s_waitcnt vmcnt(9)
	ds_write_b128 v75, v[106:109] offset:13824
	s_waitcnt vmcnt(8)
	ds_write_b128 v75, v[110:113] offset:32256
	v_mfma_f32_32x32x16_bf16 v[2:17], v[126:129], v[130:133], v[2:17]
	s_waitcnt lgkmcnt(4)
	v_mfma_f32_32x32x16_bf16 v[50:65], v[118:121], v[134:137], v[50:65]
	v_mfma_f32_32x32x16_bf16 v[18:33], v[126:129], v[134:137], v[18:33]
	s_waitcnt lgkmcnt(0)
	s_barrier
	ds_read_b128 v[106:109], v73
	ds_read_b128 v[110:113], v74 offset:18432
	ds_read_b128 v[118:121], v73 offset:32
	ds_read_b128 v[122:125], v74 offset:18464
	ds_read_b128 v[126:129], v73 offset:4608
	ds_read_b128 v[130:133], v73 offset:4640
	s_waitcnt lgkmcnt(4)
	v_mfma_f32_32x32x16_bf16 v[34:49], v[106:109], v[110:113], v[34:49]
	s_waitcnt lgkmcnt(1)
	v_mfma_f32_32x32x16_bf16 v[2:17], v[126:129], v[110:113], v[2:17]
	ds_read_b128 v[110:113], v74 offset:23040
	ds_read_b128 v[134:137], v74 offset:23072
	s_waitcnt lgkmcnt(1)
	v_mfma_f32_32x32x16_bf16 v[50:65], v[106:109], v[110:113], v[50:65]
	global_load_dwordx4 v[106:109], v80, s[2:3] offset:1536
	global_load_dwordx4 v[138:141], v80, s[4:5] offset:1536
	s_waitcnt vmcnt(9)
	ds_write_b128 v75, v[82:85] offset:36864
	s_waitcnt vmcnt(8)
	ds_write_b128 v75, v[142:145] offset:55296
	v_mfma_f32_32x32x16_bf16 v[18:33], v[126:129], v[110:113], v[18:33]
	global_load_dwordx4 v[82:85], v79, s[2:3] offset:1536
	global_load_dwordx4 v[110:113], v79, s[4:5] offset:1536
	v_mfma_f32_32x32x16_bf16 v[34:49], v[118:121], v[122:125], v[34:49]
	v_mfma_f32_32x32x16_bf16 v[2:17], v[130:133], v[122:125], v[2:17]
	s_waitcnt lgkmcnt(2)
	v_mfma_f32_32x32x16_bf16 v[50:65], v[118:121], v[134:137], v[50:65]
	ds_read_b128 v[118:121], v73 offset:64
	ds_read_b128 v[122:125], v73 offset:4672
	ds_read_b128 v[126:129], v74 offset:18496
	ds_read_b128 v[142:145], v74 offset:23104
	s_waitcnt vmcnt(9)
	ds_write_b128 v75, v[86:89] offset:41472
	s_waitcnt vmcnt(8)
	ds_write_b128 v75, v[114:117] offset:59904
	v_mfma_f32_32x32x16_bf16 v[18:33], v[130:133], v[134:137], v[18:33]
	global_load_dwordx4 v[86:89], v78, s[2:3] offset:1536
	global_load_dwordx4 v[114:117], v78, s[4:5] offset:1536
	s_waitcnt lgkmcnt(3)
	v_mfma_f32_32x32x16_bf16 v[34:49], v[118:121], v[126:129], v[34:49]
	v_mfma_f32_32x32x16_bf16 v[2:17], v[122:125], v[126:129], v[2:17]
	s_waitcnt lgkmcnt(2)
	v_mfma_f32_32x32x16_bf16 v[50:65], v[118:121], v[142:145], v[50:65]
	ds_read_b128 v[118:121], v73 offset:96
	ds_read_b128 v[126:129], v73 offset:4704
	ds_read_b128 v[130:133], v74 offset:18528
	ds_read_b128 v[134:137], v74 offset:23136
	s_waitcnt vmcnt(9)
	ds_write_b128 v75, v[90:93] offset:46080
	s_waitcnt vmcnt(8)
	ds_write_b128 v75, v[98:101] offset:64512
	v_mfma_f32_32x32x16_bf16 v[18:33], v[122:125], v[142:145], v[18:33]
	global_load_dwordx4 v[90:93], v77, s[2:3] offset:1536
	global_load_dwordx4 v[98:101], v77, s[4:5] offset:1536
	s_waitcnt lgkmcnt(3)
	v_mfma_f32_32x32x16_bf16 v[34:49], v[118:121], v[130:133], v[34:49]
	s_waitcnt vmcnt(9)
	ds_write_b128 v75, v[94:97] offset:50688
	s_waitcnt vmcnt(8)
	ds_write_b128 v76, v[102:105] offset:13824
	v_mfma_f32_32x32x16_bf16 v[2:17], v[126:129], v[130:133], v[2:17]
	s_waitcnt lgkmcnt(4)
	v_mfma_f32_32x32x16_bf16 v[50:65], v[118:121], v[134:137], v[50:65]
	v_mfma_f32_32x32x16_bf16 v[18:33], v[126:129], v[134:137], v[18:33]
	s_waitcnt lgkmcnt(0)
	s_barrier
; #define GL1_(RA, RB, i) { RA[i] = *(const u32x4*)(ap + (aoff + (i) * astep)); if ((i) < NB) RB[(i) < NB ? (i) : 0] = *(const u32x4*)(bp + (boff + (i) * bstep)); }
; #define LS1_(RA, RB, ST, i) { char* sn_ = lds + (ST) * STAGE; *(u32x4*)(sn_ + wofs + (i) * 32 * LROW) = RA[i]; \
;                               if ((i) < NB) *(u32x4*)(sn_ + STAGE_OP + wofs + (i) * 32 * LROW) = RB[(i) < NB ? (i) : 0]; }
; template <int NJ> DI void gemm_mainloop_reg(const bf16_t* __restrict__ A, int lda, const bf16_t* __restrict__ Bt, int ldb, int K, f32x16 (&acc)[2][NJ], char* lds) {
;     ...
; #pragma unroll
;   for (int i = 0; i < 4; ++i) GL1_(ra0, rb0, i);
;   ap += 128; bp += 128;
; #pragma unroll
;   for (int i = 0; i < 4; ++i) GL1_(ra1, rb1, i);
;   ap += 128; bp += 128;
; #pragma unroll
;   for (int i = 0; i < 4; ++i) LS1_(ra0, rb0, 0, i);
;   __syncthreads();
;   const int nk = K >> 6;
;   for (int kt = 0; kt < nk; kt += 2) {
;     const bool l0 = (kt + 2 < nk), l1 = (kt + 3 < nk);
;     STEP_(0, l0, ra0, rb0, true, ra1, rb1);
;     __syncthreads();
;     STEP_(1, l1, ra1, rb1, l0, ra0, rb0);
;     __syncthreads();
	ds_read_b128 v[94:97], v73 offset:36864
	ds_read_b128 v[102:105], v74 offset:55296
	ds_read_b128 v[118:121], v73 offset:36896
	ds_read_b128 v[122:125], v74 offset:55328
	ds_read_b128 v[126:129], v73 offset:41472
	ds_read_b128 v[130:133], v73 offset:41504
	s_waitcnt lgkmcnt(4)
	v_mfma_f32_32x32x16_bf16 v[34:49], v[94:97], v[102:105], v[34:49]
	s_waitcnt lgkmcnt(1)
	v_mfma_f32_32x32x16_bf16 v[2:17], v[126:129], v[102:105], v[2:17]
	ds_read_b128 v[102:105], v74 offset:59904
	ds_read_b128 v[134:137], v74 offset:59936
	s_waitcnt lgkmcnt(1)
	v_mfma_f32_32x32x16_bf16 v[50:65], v[94:97], v[102:105], v[50:65]
	global_load_dwordx4 v[94:97], v80, s[2:3] offset:1664
	global_load_dwordx4 v[142:145], v80, s[4:5] offset:1664
	s_waitcnt vmcnt(9)
	ds_write_b128 v75, v[106:109]
	s_waitcnt vmcnt(8)
	ds_write_b128 v75, v[138:141] offset:18432
	v_mfma_f32_32x32x16_bf16 v[18:33], v[126:129], v[102:105], v[18:33]
	global_load_dwordx4 v[102:105], v79, s[2:3] offset:1664
	global_load_dwordx4 v[106:109], v79, s[4:5] offset:1664
	v_mfma_f32_32x32x16_bf16 v[34:49], v[118:121], v[122:125], v[34:49]
	v_mfma_f32_32x32x16_bf16 v[2:17], v[130:133], v[122:125], v[2:17]
	s_waitcnt lgkmcnt(2)
	v_mfma_f32_32x32x16_bf16 v[50:65], v[118:121], v[134:137], v[50:65]
	ds_read_b128 v[118:121], v73 offset:36928
	ds_read_b128 v[122:125], v73 offset:41536
	ds_read_b128 v[126:129], v74 offset:55360
	ds_read_b128 v[138:141], v74 offset:59968
	s_waitcnt vmcnt(9)
	ds_write_b128 v75, v[82:85] offset:4608
	s_waitcnt vmcnt(8)
	ds_write_b128 v75, v[110:113] offset:23040
	v_mfma_f32_32x32x16_bf16 v[18:33], v[130:133], v[134:137], v[18:33]
	global_load_dwordx4 v[82:85], v78, s[2:3] offset:1664
	global_load_dwordx4 v[110:113], v78, s[4:5] offset:1664
	s_waitcnt lgkmcnt(3)
	v_mfma_f32_32x32x16_bf16 v[34:49], v[118:121], v[126:129], v[34:49]
	v_mfma_f32_32x32x16_bf16 v[2:17], v[122:125], v[126:129], v[2:17]
	s_waitcnt lgkmcnt(2)
	v_mfma_f32_32x32x16_bf16 v[50:65], v[118:121], v[138:141], v[50:65]
	ds_read_b128 v[118:121], v73 offset:36960
	ds_read_b128 v[126:129], v73 offset:41568
	ds_read_b128 v[130:133], v74 offset:55392
	ds_read_b128 v[134:137], v74 offset:60000
	s_waitcnt vmcnt(9)
	ds_write_b128 v75, v[86:89] offset:9216
	s_waitcnt vmcnt(8)
	ds_write_b128 v75, v[114:117] offset:27648
	v_mfma_f32_32x32x16_bf16 v[18:33], v[122:125], v[138:141], v[18:33]
	global_load_dwordx4 v[86:89], v77, s[2:3] offset:1664
	global_load_dwordx4 v[114:117], v77, s[4:5] offset:1664
	s_waitcnt lgkmcnt(3)
	v_mfma_f32_32x32x16_bf16 v[34:49], v[118:121], v[130:133], v[34:49]
	s_waitcnt vmcnt(9)
	ds_write_b128 v75, v[90:93] offset:13824
	s_waitcnt vmcnt(8)
	ds_write_b128 v75, v[98:101] offset:32256
	v_mfma_f32_32x32x16_bf16 v[2:17], v[126:129], v[130:133], v[2:17]
	s_waitcnt lgkmcnt(4)
	v_mfma_f32_32x32x16_bf16 v[50:65], v[118:121], v[134:137], v[50:65]
	v_mfma_f32_32x32x16_bf16 v[18:33], v[126:129], v[134:137], v[18:33]
	s_waitcnt lgkmcnt(0)
	s_barrier
	ds_read_b128 v[90:93], v73
	ds_read_b128 v[98:101], v74 offset:18432
	ds_read_b128 v[118:121], v73 offset:32
	ds_read_b128 v[122:125], v74 offset:18464
	ds_read_b128 v[126:129], v73 offset:4608
	ds_read_b128 v[130:133], v73 offset:4640
	s_waitcnt lgkmcnt(4)
	v_mfma_f32_32x32x16_bf16 v[34:49], v[90:93], v[98:101], v[34:49]
	s_waitcnt lgkmcnt(1)
	v_mfma_f32_32x32x16_bf16 v[2:17], v[126:129], v[98:101], v[2:17]
	ds_read_b128 v[98:101], v74 offset:23040
	ds_read_b128 v[134:137], v74 offset:23072
	s_waitcnt lgkmcnt(1)
	v_mfma_f32_32x32x16_bf16 v[50:65], v[90:93], v[98:101], v[50:65]
	global_load_dwordx4 v[90:93], v80, s[2:3] offset:1792
	global_load_dwordx4 v[138:141], v80, s[4:5] offset:1792
	s_waitcnt vmcnt(9)
	ds_write_b128 v75, v[94:97] offset:36864
	s_waitcnt vmcnt(8)
	ds_write_b128 v75, v[142:145] offset:55296
	v_mfma_f32_32x32x16_bf16 v[18:33], v[126:129], v[98:101], v[18:33]
	global_load_dwordx4 v[94:97], v79, s[2:3] offset:1792
	global_load_dwordx4 v[98:101], v79, s[4:5] offset:1792
	v_mfma_f32_32x32x16_bf16 v[34:49], v[118:121], v[122:125], v[34:49]
	v_mfma_f32_32x32x16_bf16 v[2:17], v[130:133], v[122:125], v[2:17]
	s_waitcnt lgkmcnt(2)
	v_mfma_f32_32x32x16_bf16 v[50:65], v[118:121], v[134:137], v[50:65]
	ds_read_b128 v[118:121], v73 offset:64
	ds_read_b128 v[122:125], v73 offset:4672
	ds_read_b128 v[126:129], v74 offset:18496
	ds_read_b128 v[142:145], v74 offset:23104
	s_waitcnt vmcnt(9)
	ds_write_b128 v75, v[102:105] offset:41472
	s_waitcnt vmcnt(8)
	ds_write_b128 v75, v[106:109] offset:59904
	v_mfma_f32_32x32x16_bf16 v[18:33], v[130:133], v[134:137], v[18:33]
	global_load_dwordx4 v[102:105], v78, s[2:3] offset:1792
	global_load_dwordx4 v[106:109], v78, s[4:5] offset:1792
	s_waitcnt lgkmcnt(3)
	v_mfma_f32_32x32x16_bf16 v[34:49], v[118:121], v[126:129], v[34:49]
	v_mfma_f32_32x32x16_bf16 v[2:17], v[122:125], v[126:129], v[2:17]
	s_waitcnt lgkmcnt(2)
	v_mfma_f32_32x32x16_bf16 v[50:65], v[118:121], v[142:145], v[50:65]
	ds_read_b128 v[118:121], v73 offset:96
	ds_read_b128 v[126:129], v73 offset:4704
	ds_read_b128 v[130:133], v74 offset:18528
	ds_read_b128 v[134:137], v74 offset:23136
	s_waitcnt vmcnt(9)
	ds_write_b128 v75, v[82:85] offset:46080
	s_waitcnt vmcnt(8)
	ds_write_b128 v75, v[110:113] offset:64512
	v_mfma_f32_32x32x16_bf16 v[18:33], v[122:125], v[142:145], v[18:33]
	global_load_dwordx4 v[82:85], v77, s[2:3] offset:1792
	global_load_dwordx4 v[110:113], v77, s[4:5] offset:1792
	s_waitcnt lgkmcnt(3)
	v_mfma_f32_32x32x16_bf16 v[34:49], v[118:121], v[130:133], v[34:49]
	s_waitcnt vmcnt(9)
	ds_write_b128 v75, v[86:89] offset:50688
	s_waitcnt vmcnt(8)
	ds_write_b128 v76, v[114:117] offset:13824
	v_mfma_f32_32x32x16_bf16 v[2:17], v[126:129], v[130:133], v[2:17]
	s_waitcnt lgkmcnt(4)
	v_mfma_f32_32x32x16_bf16 v[50:65], v[118:121], v[134:137], v[50:65]
	v_mfma_f32_32x32x16_bf16 v[18:33], v[126:129], v[134:137], v[18:33]
	s_waitcnt lgkmcnt(0)
	s_barrier
; #define GL1_(RA, RB, i) { RA[i] = *(const u32x4*)(ap + (aoff + (i) * astep)); if ((i) < NB) RB[(i) < NB ? (i) : 0] = *(const u32x4*)(bp + (boff + (i) * bstep)); }
; #define LS1_(RA, RB, ST, i) { char* sn_ = lds + (ST) * STAGE; *(u32x4*)(sn_ + wofs + (i) * 32 * LROW) = RA[i]; \
;                               if ((i) < NB) *(u32x4*)(sn_ + STAGE_OP + wofs + (i) * 32 * LROW) = RB[(i) < NB ? (i) : 0]; }
; template <int NJ> DI void gemm_mainloop_reg(const bf16_t* __restrict__ A, int lda, const bf16_t* __restrict__ Bt, int ldb, int K, f32x16 (&acc)[2][NJ], char* lds) {
;     ...
; #pragma unroll
;   for (int i = 0; i < 4; ++i) GL1_(ra0, rb0, i);
;   ap += 128; bp += 128;
; #pragma unroll
;   for (int i = 0; i < 4; ++i) GL1_(ra1, rb1, i);
;   ap += 128; bp += 128;
; #pragma unroll
;   for (int i = 0; i < 4; ++i) LS1_(ra0, rb0, 0, i);
;   __syncthreads();
;   const int nk = K >> 6;
;   for (int kt = 0; kt < nk; kt += 2) {
;     const bool l0 = (kt + 2 < nk), l1 = (kt + 3 < nk);
;     STEP_(0, l0, ra0, rb0, true, ra1, rb1);
;     __syncthreads();
;     STEP_(1, l1, ra1, rb1, l0, ra0, rb0);
;     __syncthreads();
	ds_read_b128 v[86:89], v73 offset:36864
	ds_read_b128 v[114:117], v74 offset:55296
	ds_read_b128 v[118:121], v73 offset:41472
	s_waitcnt lgkmcnt(1)
	v_mfma_f32_32x32x16_bf16 v[34:49], v[86:89], v[114:117], v[34:49]
	s_waitcnt lgkmcnt(0)
	v_mfma_f32_32x32x16_bf16 v[2:17], v[118:121], v[114:117], v[2:17]
	ds_read_b128 v[114:117], v74 offset:59904
	s_waitcnt lgkmcnt(0)
	v_mfma_f32_32x32x16_bf16 v[50:65], v[86:89], v[114:117], v[50:65]
	global_load_dwordx4 v[86:89], v80, s[2:3] offset:1920
	global_load_dwordx4 v[122:125], v80, s[4:5] offset:1920
	ds_read_b128 v[126:129], v73 offset:36896
	ds_read_b128 v[130:133], v74 offset:55328
	ds_read_b128 v[134:137], v73 offset:41504
	ds_read_b128 v[142:145], v74 offset:59936
	s_waitcnt vmcnt(9)
	ds_write_b128 v75, v[90:93]
	s_waitcnt vmcnt(8)
	ds_write_b128 v75, v[138:141] offset:18432
	v_mfma_f32_32x32x16_bf16 v[18:33], v[118:121], v[114:117], v[18:33]
	global_load_dwordx4 v[90:93], v79, s[2:3] offset:1920
	global_load_dwordx4 v[114:117], v79, s[4:5] offset:1920
	s_waitcnt lgkmcnt(4)
	v_mfma_f32_32x32x16_bf16 v[34:49], v[126:129], v[130:133], v[34:49]
	s_waitcnt lgkmcnt(3)
	v_mfma_f32_32x32x16_bf16 v[2:17], v[134:137], v[130:133], v[2:17]
	s_waitcnt lgkmcnt(2)
	v_mfma_f32_32x32x16_bf16 v[50:65], v[126:129], v[142:145], v[50:65]
	ds_read_b128 v[118:121], v73 offset:36928
	ds_read_b128 v[126:129], v73 offset:41536
	ds_read_b128 v[130:133], v74 offset:55360
	ds_read_b128 v[138:141], v74 offset:59968
	s_waitcnt vmcnt(9)
	ds_write_b128 v75, v[94:97] offset:4608
	s_waitcnt vmcnt(8)
	ds_write_b128 v75, v[98:101] offset:23040
	v_mfma_f32_32x32x16_bf16 v[18:33], v[134:137], v[142:145], v[18:33]
	global_load_dwordx4 v[94:97], v78, s[2:3] offset:1920
	s_nop 0
	global_load_dwordx4 v[78:81], v78, s[4:5] offset:1920
	s_waitcnt lgkmcnt(3)
	v_mfma_f32_32x32x16_bf16 v[34:49], v[118:121], v[130:133], v[34:49]
	v_mfma_f32_32x32x16_bf16 v[2:17], v[126:129], v[130:133], v[2:17]
	s_waitcnt lgkmcnt(2)
	v_mfma_f32_32x32x16_bf16 v[50:65], v[118:121], v[138:141], v[50:65]
	ds_read_b128 v[98:101], v73 offset:36960
	ds_read_b128 v[118:121], v73 offset:41568
	ds_read_b128 v[130:133], v74 offset:55392
	ds_read_b128 v[134:137], v74 offset:60000
	s_waitcnt vmcnt(9)
	ds_write_b128 v75, v[102:105] offset:9216
	s_waitcnt vmcnt(8)
	ds_write_b128 v75, v[106:109] offset:27648
	v_mfma_f32_32x32x16_bf16 v[18:33], v[126:129], v[138:141], v[18:33]
	s_waitcnt lgkmcnt(3)
	v_mfma_f32_32x32x16_bf16 v[34:49], v[98:101], v[130:133], v[34:49]
	s_waitcnt lgkmcnt(2)
	v_mfma_f32_32x32x16_bf16 v[50:65], v[98:101], v[134:137], v[50:65]
	global_load_dwordx4 v[98:101], v77, s[2:3] offset:1920
	global_load_dwordx4 v[102:105], v77, s[4:5] offset:1920
	s_waitcnt vmcnt(9)
	ds_write_b128 v75, v[82:85] offset:13824
	s_waitcnt vmcnt(8)
	ds_write_b128 v75, v[110:113] offset:32256
	v_mfma_f32_32x32x16_bf16 v[2:17], v[118:121], v[130:133], v[2:17]
	v_mfma_f32_32x32x16_bf16 v[18:33], v[118:121], v[134:137], v[18:33]
	s_waitcnt lgkmcnt(0)
	s_barrier
	ds_read_b128 v[82:85], v73
	ds_read_b128 v[106:109], v74 offset:18432
	ds_read_b128 v[110:113], v73 offset:4608
	s_waitcnt lgkmcnt(1)
	v_mfma_f32_32x32x16_bf16 v[34:49], v[82:85], v[106:109], v[34:49]
	s_waitcnt lgkmcnt(0)
	v_mfma_f32_32x32x16_bf16 v[2:17], v[110:113], v[106:109], v[2:17]
	ds_read_b128 v[106:109], v74 offset:23040
	s_waitcnt lgkmcnt(0)
	v_mfma_f32_32x32x16_bf16 v[50:65], v[82:85], v[106:109], v[50:65]
	ds_read_b128 v[82:85], v73 offset:32
	ds_read_b128 v[118:121], v74 offset:18464
	ds_read_b128 v[126:129], v73 offset:4640
	ds_read_b128 v[130:133], v74 offset:23072
	s_waitcnt vmcnt(7)
	ds_write_b128 v75, v[86:89] offset:36864
	s_waitcnt vmcnt(6)
	ds_write_b128 v75, v[122:125] offset:55296
	v_mfma_f32_32x32x16_bf16 v[18:33], v[110:113], v[106:109], v[18:33]
	s_waitcnt lgkmcnt(4)
	v_mfma_f32_32x32x16_bf16 v[34:49], v[82:85], v[118:121], v[34:49]
	s_waitcnt lgkmcnt(2)
	v_mfma_f32_32x32x16_bf16 v[50:65], v[82:85], v[130:133], v[50:65]
	ds_read_b128 v[82:85], v73 offset:64
	ds_read_b128 v[86:89], v73 offset:4672
	ds_read_b128 v[106:109], v74 offset:18496
	ds_read_b128 v[110:113], v74 offset:23104
	s_waitcnt vmcnt(5)
	ds_write_b128 v75, v[90:93] offset:41472
	s_waitcnt vmcnt(4)
	ds_write_b128 v75, v[114:117] offset:59904
	v_mfma_f32_32x32x16_bf16 v[2:17], v[126:129], v[118:121], v[2:17]
	v_mfma_f32_32x32x16_bf16 v[18:33], v[126:129], v[130:133], v[18:33]
	s_waitcnt lgkmcnt(3)
	v_mfma_f32_32x32x16_bf16 v[34:49], v[82:85], v[106:109], v[34:49]
	v_mfma_f32_32x32x16_bf16 v[2:17], v[86:89], v[106:109], v[2:17]
	s_waitcnt lgkmcnt(2)
	v_mfma_f32_32x32x16_bf16 v[50:65], v[82:85], v[110:113], v[50:65]
	ds_read_b128 v[82:85], v73 offset:96
	ds_read_b128 v[90:93], v73 offset:4704
	ds_read_b128 v[106:109], v74 offset:18528
	ds_read_b128 v[114:117], v74 offset:23136
	s_waitcnt vmcnt(3)
	ds_write_b128 v75, v[94:97] offset:46080
	s_waitcnt vmcnt(2)
	ds_write_b128 v75, v[78:81] offset:64512
	v_mfma_f32_32x32x16_bf16 v[18:33], v[86:89], v[110:113], v[18:33]
	s_waitcnt lgkmcnt(3)
	v_mfma_f32_32x32x16_bf16 v[34:49], v[82:85], v[106:109], v[34:49]
	s_waitcnt vmcnt(1)
	ds_write_b128 v75, v[98:101] offset:50688
	s_waitcnt vmcnt(0)
	ds_write_b128 v76, v[102:105] offset:13824
	v_mfma_f32_32x32x16_bf16 v[2:17], v[90:93], v[106:109], v[2:17]
	s_waitcnt lgkmcnt(4)
	v_mfma_f32_32x32x16_bf16 v[50:65], v[82:85], v[114:117], v[50:65]
	v_mfma_f32_32x32x16_bf16 v[18:33], v[90:93], v[114:117], v[18:33]
	s_waitcnt lgkmcnt(0)
	s_barrier
; DI int tid_() { int t = threadIdx.x; asm volatile("" : "+v"(t)); return t; }
; template <int NJ> DI void acc_to_lds(const f32x16 (&acc)[2][NJ], float* cl) {
;   const int tid = tid_(), lane = tid & 63, w = tid >> 6, wm = w >> 1, wn = w & 1, h = lane >> 5, c = lane & 31;
; #pragma unroll
;   for (int i = 0; i < 2; ++i)
; #pragma unroll
;     for (int j = 0; j < NJ; ++j)
; #pragma unroll
;       for (int r = 0; r < 16; ++r) {
;         const int row = wm * 64 + i * 32 + (r & 3) + 8 * (r >> 2) + 4 * h;
;         cl[row * CLD + wn * 32 * NJ + j * 32 + c] = acc[i][j][r];
;       }
; }
	ds_read_b128 v[76:79], v73 offset:36864
	ds_read_b128 v[80:83], v74 offset:55296
	ds_read_b128 v[84:87], v73 offset:41472
	s_waitcnt lgkmcnt(1)
	v_mfma_f32_32x32x16_bf16 v[34:49], v[76:79], v[80:83], v[34:49]
	s_waitcnt lgkmcnt(0)
	v_mfma_f32_32x32x16_bf16 v[2:17], v[84:87], v[80:83], v[2:17]
	ds_read_b128 v[80:83], v74 offset:59904
	s_waitcnt lgkmcnt(0)
	v_mfma_f32_32x32x16_bf16 v[50:65], v[76:79], v[80:83], v[50:65]
	ds_read_b128 v[76:79], v73 offset:36896
	ds_read_b128 v[88:91], v74 offset:55328
	ds_read_b128 v[92:95], v73 offset:41504
	ds_read_b128 v[96:99], v74 offset:59936
	v_mfma_f32_32x32x16_bf16 v[18:33], v[84:87], v[80:83], v[18:33]
	s_waitcnt lgkmcnt(2)
	v_mfma_f32_32x32x16_bf16 v[34:49], v[76:79], v[88:91], v[34:49]
	s_waitcnt lgkmcnt(1)
	v_mfma_f32_32x32x16_bf16 v[2:17], v[92:95], v[88:91], v[2:17]
	s_waitcnt lgkmcnt(0)
	v_mfma_f32_32x32x16_bf16 v[50:65], v[76:79], v[96:99], v[50:65]
	ds_read_b128 v[76:79], v73 offset:36928
	ds_read_b128 v[80:83], v73 offset:41536
	ds_read_b128 v[84:87], v74 offset:55360
	ds_read_b128 v[88:91], v74 offset:59968
	v_mfma_f32_32x32x16_bf16 v[18:33], v[92:95], v[96:99], v[18:33]
	s_waitcnt lgkmcnt(1)
	v_mfma_f32_32x32x16_bf16 v[34:49], v[76:79], v[84:87], v[34:49]
	v_mfma_f32_32x32x16_bf16 v[2:17], v[80:83], v[84:87], v[2:17]
	s_waitcnt lgkmcnt(0)
	v_mfma_f32_32x32x16_bf16 v[50:65], v[76:79], v[88:91], v[50:65]
	ds_read_b128 v[76:79], v73 offset:36960
	ds_read_b128 v[84:87], v73 offset:41568
	ds_read_b128 v[92:95], v74 offset:55392
	ds_read_b128 v[96:99], v74 offset:60000
	v_mfma_f32_32x32x16_bf16 v[18:33], v[80:83], v[88:91], v[18:33]
	s_waitcnt lgkmcnt(1)
	v_mfma_f32_32x32x16_bf16 v[34:49], v[76:79], v[92:95], v[34:49]
	v_mfma_f32_32x32x16_bf16 v[2:17], v[84:87], v[92:95], v[2:17]
	s_waitcnt lgkmcnt(0)
	v_mfma_f32_32x32x16_bf16 v[50:65], v[76:79], v[96:99], v[50:65]
	v_mfma_f32_32x32x16_bf16 v[18:33], v[84:87], v[96:99], v[18:33]
	s_setprio 0
	v_mov_b32_e32 v73, v199
	s_barrier
	s_nop 0
	v_lshrrev_b32_e32 v75, 3, v73
	v_lshrrev_b32_e32 v74, 1, v73
	v_and_b32_e32 v75, 4, v75
	v_and_b32_e32 v73, 0x5f, v73
	v_and_or_b32 v74, v74, s17, v75
	v_mul_lo_u32 v74, v74, s15
	v_lshlrev_b32_e32 v73, 2, v73
	v_add3_u32 v73, 0, v74, v73
	ds_write2_b32 v73, v34, v50 offset1:32
	ds_write2_b32 v73, v35, v51 offset0:132 offset1:164
	v_add_u32_e32 v34, 0x400, v73
	ds_write2_b32 v34, v36, v52 offset0:8 offset1:40
	ds_write2_b32 v34, v37, v53 offset0:140 offset1:172
	v_add_u32_e32 v34, 0x1000, v73
	ds_write2_b32 v34, v38, v54 offset0:32 offset1:64
	ds_write2_b32 v34, v39, v55 offset0:164 offset1:196
	v_add_u32_e32 v34, 0x1400, v73
	ds_write2_b32 v34, v40, v56 offset0:40 offset1:72
	ds_write2_b32 v34, v41, v57 offset0:172 offset1:204
	v_add_u32_e32 v34, 0x2000, v73
	ds_write2_b32 v34, v42, v58 offset0:64 offset1:96
	ds_write2_b32 v34, v43, v59 offset0:196 offset1:228
	v_add_u32_e32 v34, 0x2400, v73
	ds_write2_b32 v34, v44, v60 offset0:72 offset1:104
	ds_write2_b32 v34, v45, v61 offset0:204 offset1:236
	v_add_u32_e32 v34, 0x3000, v73
	ds_write2_b32 v34, v46, v62 offset0:96 offset1:128
	v_add_u32_e32 v34, 0x3200, v73
	ds_write2_b32 v34, v47, v63 offset0:100 offset1:132
	v_add_u32_e32 v34, 0x3400, v73
	ds_write2_b32 v34, v48, v64 offset0:104 offset1:136
	v_add_u32_e32 v34, 0x3600, v73
	ds_write2_b32 v34, v49, v65 offset0:108 offset1:140
	v_add_u32_e32 v34, 0x4000, v73
	ds_write2_b32 v34, v2, v18 offset0:128 offset1:160
	v_add_u32_e32 v2, 0x4400, v73
	ds_write2_b32 v2, v3, v19 offset0:4 offset1:36
	ds_write2_b32 v2, v4, v20 offset0:136 offset1:168
	v_add_u32_e32 v2, 0x4800, v73
	ds_write2_b32 v2, v5, v21 offset0:12 offset1:44
	v_add_u32_e32 v2, 0x5000, v73
	ds_write2_b32 v2, v6, v22 offset0:160 offset1:192
	v_add_u32_e32 v2, 0x5400, v73
	ds_write2_b32 v2, v7, v23 offset0:36 offset1:68
	ds_write2_b32 v2, v8, v24 offset0:168 offset1:200
	v_add_u32_e32 v2, 0x5800, v73
	ds_write2_b32 v2, v9, v25 offset0:44 offset1:76
	v_add_u32_e32 v2, 0x6000, v73
	ds_write2_b32 v2, v10, v26 offset0:192 offset1:224
	v_add_u32_e32 v2, 0x6400, v73
	ds_write2_b32 v2, v11, v27 offset0:68 offset1:100
	ds_write2_b32 v2, v12, v28 offset0:200 offset1:232
	v_add_u32_e32 v2, 0x6800, v73
	ds_write2_b32 v2, v13, v29 offset0:76 offset1:108
	v_add_u32_e32 v2, 0x7200, v73
	ds_write2_b32 v2, v14, v30 offset0:96 offset1:128
	v_add_u32_e32 v2, 0x7400, v73
	ds_write2_b32 v2, v15, v31 offset0:100 offset1:132
	v_add_u32_e32 v2, 0x7600, v73
	ds_write2_b32 v2, v16, v32 offset0:104 offset1:136
	v_add_u32_e32 v2, 0x7800, v73
	ds_write2_b32 v2, v17, v33 offset0:108 offset1:140
	s_and_saveexec_b64 s[2:3], s[38:39]
	s_cbranch_execz .LBB0_1098
	v_lshl_add_u32 v2, s36, 7, v68
	v_ashrrev_i32_e32 v3, 31, v2
	v_lshl_add_u64 v[2:3], v[2:3], 2, s[0:1]
	global_load_dword v2, v[2:3], off
	s_mov_b32 s4, 0x800000
	s_waitcnt vmcnt(0)
	v_fmamk_f32 v2, v2, 0x3a800000, v198
	v_mul_f32_e32 v3, 0x4b800000, v2
	v_cmp_gt_f32_e32 vcc, s4, v2
	s_nop 1
	v_cndmask_b32_e32 v2, v2, v3, vcc
	v_rsq_f32_e32 v2, v2
	s_nop 0
	v_mul_f32_e32 v3, 0x45800000, v2
	v_cndmask_b32_e32 v2, v2, v3, vcc
	ds_write_b32 v69, v2

; DI int tid_() { int t = threadIdx.x; asm volatile("" : "+v"(t)); return t; }
; #define GL1_(RA, RB, i) { RA[i] = *(const u32x4*)(ap + (aoff + (i) * astep)); if ((i) < NB) RB[(i) < NB ? (i) : 0] = *(const u32x4*)(bp + (boff + (i) * bstep)); }
; DI bf16_t* wsb(const Ctx& c, size_t off) { return (bf16_t*)(c.ws + off); }
; template <int NJ> DI void gemm_mainloop_reg(const bf16_t* __restrict__ A, int lda, const bf16_t* __restrict__ Bt, int ldb, int K, f32x16 (&acc)[2][NJ], char* lds) {
;   const int tid = tid_(), lane = tid & 63, w = tid >> 6, wm = w >> 1, wn = w & 1;
;   const int lr = tid >> 3, lc = tid & 7;
;   const char* ap = (const char*)A;
;   const char* bp = (const char*)Bt;
;   const unsigned aoff = (unsigned)(lr * lda + lc * 8) * 2u, boff = (unsigned)(lr * ldb + lc * 8) * 2u;
;   const unsigned astep = (unsigned)(32 * lda) * 2u, bstep = (unsigned)(32 * ldb) * 2u;
;   constexpr int NB = 2 * NJ;
;   u32x4 ra0[4], rb0[NB], ra1[4], rb1[NB];
;   const int wofs = lr * LROW + lc * 16;
;   const int a_rd = (wm * 64 + (lane & 31)) * LROW + (lane >> 5) * 16;
;   const int b_rd = STAGE_OP + (wn * 32 * NJ + (lane & 31)) * LROW + (lane >> 5) * 16;
;     ...
; #pragma unroll
;   for (int i = 0; i < 4; ++i) GL1_(ra0, rb0, i);
;   ap += 128; bp += 128;
; #pragma unroll
;   for (int i = 0; i < 4; ++i) GL1_(ra1, rb1, i);
;   ap += 128; bp += 128;
; #pragma unroll
;   for (int i = 0; i < 4; ++i) LS1_(ra0, rb0, 0, i);
;   __syncthreads();
;   const int nk = K >> 6;
;   for (int kt = 0; kt < nk; kt += 2) {
;     const bool l0 = (kt + 2 < nk), l1 = (kt + 3 < nk);
;     STEP_(0, l0, ra0, rb0, true, ra1, rb1);
;     __syncthreads();
;     STEP_(1, l1, ra1, rb1, l0, ra0, rb0);
;     __syncthreads();
; DI void phase_resid_gemm(const Ctx& c, const bf16_t* A, int K, size_t woff, float scale, float* ssn) {
;   const bf16_t* Bt = wgt(c, woff);
;   bf16_t* xb = wsb(c, OFF_XB);
;   float* cl = (float*)c.lds;
;   const int xcd_ = blockIdx.x & 7, slot_ = blockIdx.x >> 3, nslot_ = gridDim.x >> 3;
;   for (int j_ = slot_; j_ < 16 * 8; j_ += nslot_) {
;     const int mt = xcd_ * 16 + (j_ & 15), nt = j_ >> 4;
;     f32x16 acc[2][2]; zero_acc<2>(acc);
;     gemm_mainloop_reg<2>(A + (size_t)mt * 128 * (K + PADK), K + PADK, Bt + (size_t)nt * 128 * (K + PADK), K + PADK, K, acc, c.lds);
.LBB0_1156:
	s_and_b32 s0, s25, 15
	s_lshl_b32 s38, s0, 7
	s_lshl_b32 s0, s24, 1
	s_and_b32 s72, s0, 0x700
	s_lshl_b32 s0, s24, 2
	s_and_b32 s35, s0, 0xe00
	s_and_b32 s0, s34, 15
	s_add_i32 s40, s10, s38
	s_or_b32 s0, s0, s78
	s_lshl_b32 s39, s40, 2
	s_mul_i32 s0, s0, 0xb4000
	s_add_u32 s0, s86, s0
	s_addc_u32 s1, s87, 0
	s_lshl_b32 s2, s34, 3
	s_and_b32 s2, s2, 0x380
	s_mulk_i32 s2, 0x1680
	v_mov_b32_e32 v34, v199
	s_add_u32 s36, s4, s2
	s_movk_i32 s2, 0x1680
	v_ashrrev_i32_e32 v0, 3, v34
	v_lshlrev_b32_e32 v2, 4, v34
	v_and_b32_e32 v35, 0x70, v2
	v_mul_lo_u32 v2, v0, s2
	v_or_b32_e32 v72, v35, v2
	v_add_u32_e32 v71, 0x2d000, v72
	v_add_u32_e32 v70, 0x5a000, v72
	v_add_u32_e32 v69, 0x87000, v72
	s_addc_u32 s37, s5, 0
	global_load_dwordx4 v[2:5], v72, s[0:1]
	global_load_dwordx4 v[6:9], v71, s[0:1]
	global_load_dwordx4 v[10:13], v70, s[0:1]
	global_load_dwordx4 v[14:17], v69, s[0:1]
	global_load_dwordx4 v[18:21], v72, s[36:37]
	global_load_dwordx4 v[22:25], v71, s[36:37]
	global_load_dwordx4 v[26:29], v70, s[36:37]
	global_load_dwordx4 v[30:33], v69, s[36:37]
	v_mul_lo_u32 v0, v0, s16
	v_lshrrev_b32_e32 v36, 1, v34
	v_and_b32_e32 v37, 31, v34
	v_add3_u32 v67, v0, v35, 0
	v_and_b32_e32 v38, 16, v36
	v_and_or_b32 v36, v36, s17, v37
	global_load_dwordx4 v[74:77], v72, s[0:1] offset:128
	global_load_dwordx4 v[78:81], v71, s[0:1] offset:128
	global_load_dwordx4 v[82:85], v70, s[0:1] offset:128
	global_load_dwordx4 v[86:89], v69, s[0:1] offset:128
	global_load_dwordx4 v[90:93], v72, s[36:37] offset:128
	global_load_dwordx4 v[94:97], v71, s[36:37] offset:128
	global_load_dwordx4 v[98:101], v70, s[36:37] offset:128
	global_load_dwordx4 v[102:105], v69, s[36:37] offset:128
	v_mul_lo_u32 v0, v36, s16
	v_add3_u32 v0, v0, v38, 0
	v_add_u32_e32 v68, 0xd800, v67
	s_waitcnt vmcnt(15)
	ds_write_b128 v67, v[2:5]
	s_waitcnt vmcnt(14)
	ds_write_b128 v67, v[6:9] offset:4608
	s_waitcnt vmcnt(13)
	ds_write_b128 v67, v[10:13] offset:9216
	s_waitcnt vmcnt(12)
	ds_write_b128 v67, v[14:17] offset:13824
	s_waitcnt vmcnt(11)
	ds_write_b128 v67, v[18:21] offset:18432
	s_waitcnt vmcnt(10)
	ds_write_b128 v67, v[22:25] offset:23040
	s_waitcnt vmcnt(9)
	ds_write_b128 v67, v[26:29] offset:27648
	s_waitcnt vmcnt(8)
	ds_write_b128 v67, v[30:33] offset:32256
	v_and_b32_e32 v2, 0x5f, v34
	v_mul_u32_u24_e32 v2, 0x90, v2
	v_add3_u32 v66, v2, v38, 0
	s_waitcnt lgkmcnt(0)
	s_barrier
	ds_read_b128 v[18:21], v0
	ds_read_b128 v[2:5], v66 offset:18432
	ds_read_b128 v[106:109], v0 offset:32
	ds_read_b128 v[110:113], v66 offset:18464
	ds_read_b128 v[22:25], v0 offset:4608
	ds_read_b128 v[114:117], v0 offset:4640
	ds_read_b128 v[26:29], v66 offset:23040
	ds_read_b128 v[118:121], v66 offset:23072
	global_load_dwordx4 v[122:125], v72, s[0:1] offset:256
	global_load_dwordx4 v[126:129], v72, s[36:37] offset:256
	s_waitcnt lgkmcnt(6)
	s_setprio 1
	v_mfma_f32_32x32x16_bf16 v[34:49], v[18:21], v[2:5], 0
	s_waitcnt vmcnt(9)
	ds_write_b128 v67, v[74:77] offset:36864
	s_waitcnt vmcnt(5)
	ds_write_b128 v67, v[90:93] offset:55296
	s_waitcnt lgkmcnt(5)
	v_mfma_f32_32x32x16_bf16 v[2:17], v[22:25], v[2:5], 0
	s_waitcnt lgkmcnt(3)
	v_mfma_f32_32x32x16_bf16 v[50:65], v[18:21], v[26:29], 0
	v_mfma_f32_32x32x16_bf16 v[18:33], v[22:25], v[26:29], 0
	global_load_dwordx4 v[74:77], v71, s[0:1] offset:256
	global_load_dwordx4 v[90:93], v71, s[36:37] offset:256
	v_mfma_f32_32x32x16_bf16 v[2:17], v[114:117], v[110:113], v[2:17]
	s_waitcnt lgkmcnt(2)
	v_mfma_f32_32x32x16_bf16 v[18:33], v[114:117], v[118:121], v[18:33]
	v_mfma_f32_32x32x16_bf16 v[34:49], v[106:109], v[110:113], v[34:49]
	v_mfma_f32_32x32x16_bf16 v[50:65], v[106:109], v[118:121], v[50:65]
	ds_read_b128 v[106:109], v0 offset:64
	ds_read_b128 v[110:113], v0 offset:4672
	ds_read_b128 v[130:133], v66 offset:18496
	ds_read_b128 v[134:137], v66 offset:23104
	ds_write_b128 v67, v[78:81] offset:41472
	s_waitcnt vmcnt(6)
	ds_write_b128 v67, v[94:97] offset:59904
	global_load_dwordx4 v[78:81], v70, s[0:1] offset:256
	global_load_dwordx4 v[94:97], v70, s[36:37] offset:256
	s_waitcnt lgkmcnt(3)
	v_mfma_f32_32x32x16_bf16 v[2:17], v[110:113], v[130:133], v[2:17]
	s_waitcnt lgkmcnt(2)
	v_mfma_f32_32x32x16_bf16 v[18:33], v[110:113], v[134:137], v[18:33]
	v_mfma_f32_32x32x16_bf16 v[34:49], v[106:109], v[130:133], v[34:49]
	v_mfma_f32_32x32x16_bf16 v[50:65], v[106:109], v[134:137], v[50:65]
	ds_read_b128 v[106:109], v0 offset:96
	ds_read_b128 v[114:117], v0 offset:4704
	ds_read_b128 v[118:121], v66 offset:18528
	ds_read_b128 v[130:133], v66 offset:23136
	ds_write_b128 v67, v[82:85] offset:46080
	s_waitcnt vmcnt(7)
	ds_write_b128 v67, v[98:101] offset:64512
	global_load_dwordx4 v[82:85], v69, s[0:1] offset:256
	global_load_dwordx4 v[98:101], v69, s[36:37] offset:256
	s_waitcnt lgkmcnt(3)
	v_mfma_f32_32x32x16_bf16 v[2:17], v[114:117], v[118:121], v[2:17]
	ds_write_b128 v67, v[86:89] offset:50688
	s_waitcnt vmcnt(8)
	ds_write_b128 v68, v[102:105] offset:13824
	s_waitcnt lgkmcnt(4)
	v_mfma_f32_32x32x16_bf16 v[18:33], v[114:117], v[130:133], v[18:33]
	v_mfma_f32_32x32x16_bf16 v[34:49], v[106:109], v[118:121], v[34:49]
	v_mfma_f32_32x32x16_bf16 v[50:65], v[106:109], v[130:133], v[50:65]
	s_waitcnt lgkmcnt(0)
	s_barrier
; #define GL1_(RA, RB, i) { RA[i] = *(const u32x4*)(ap + (aoff + (i) * astep)); if ((i) < NB) RB[(i) < NB ? (i) : 0] = *(const u32x4*)(bp + (boff + (i) * bstep)); }
; #define LS1_(RA, RB, ST, i) { char* sn_ = lds + (ST) * STAGE; *(u32x4*)(sn_ + wofs + (i) * 32 * LROW) = RA[i]; \
;                               if ((i) < NB) *(u32x4*)(sn_ + STAGE_OP + wofs + (i) * 32 * LROW) = RB[(i) < NB ? (i) : 0]; }
; template <int NJ> DI void gemm_mainloop_reg(const bf16_t* __restrict__ A, int lda, const bf16_t* __restrict__ Bt, int ldb, int K, f32x16 (&acc)[2][NJ], char* lds) {
;     ...
; #pragma unroll
;   for (int i = 0; i < 4; ++i) GL1_(ra0, rb0, i);
;   ap += 128; bp += 128;
; #pragma unroll
;   for (int i = 0; i < 4; ++i) GL1_(ra1, rb1, i);
;   ap += 128; bp += 128;
; #pragma unroll
;   for (int i = 0; i < 4; ++i) LS1_(ra0, rb0, 0, i);
;   __syncthreads();
;   const int nk = K >> 6;
;   for (int kt = 0; kt < nk; kt += 2) {
;     const bool l0 = (kt + 2 < nk), l1 = (kt + 3 < nk);
;     STEP_(0, l0, ra0, rb0, true, ra1, rb1);
;     __syncthreads();
;     STEP_(1, l1, ra1, rb1, l0, ra0, rb0);
;     __syncthreads();
	ds_read_b128 v[86:89], v0 offset:36864
	ds_read_b128 v[102:105], v66 offset:55296
	ds_read_b128 v[106:109], v0 offset:36896
	ds_read_b128 v[110:113], v66 offset:55328
	ds_read_b128 v[114:117], v0 offset:41472
	ds_read_b128 v[118:121], v0 offset:41504
	s_waitcnt lgkmcnt(4)
	v_mfma_f32_32x32x16_bf16 v[34:49], v[86:89], v[102:105], v[34:49]
	s_waitcnt lgkmcnt(1)
	v_mfma_f32_32x32x16_bf16 v[2:17], v[114:117], v[102:105], v[2:17]
	ds_read_b128 v[102:105], v66 offset:59904
	ds_read_b128 v[130:133], v66 offset:59936
	s_waitcnt lgkmcnt(1)
	v_mfma_f32_32x32x16_bf16 v[50:65], v[86:89], v[102:105], v[50:65]
	global_load_dwordx4 v[86:89], v72, s[0:1] offset:384
	global_load_dwordx4 v[134:137], v72, s[36:37] offset:384
	s_waitcnt vmcnt(9)
	ds_write_b128 v67, v[122:125]
	s_waitcnt vmcnt(8)
	ds_write_b128 v67, v[126:129] offset:18432
	v_mfma_f32_32x32x16_bf16 v[18:33], v[114:117], v[102:105], v[18:33]
	v_mfma_f32_32x32x16_bf16 v[34:49], v[106:109], v[110:113], v[34:49]
	s_waitcnt lgkmcnt(2)
	v_mfma_f32_32x32x16_bf16 v[50:65], v[106:109], v[130:133], v[50:65]
	global_load_dwordx4 v[102:105], v71, s[0:1] offset:384
	global_load_dwordx4 v[106:109], v71, s[36:37] offset:384
	v_mfma_f32_32x32x16_bf16 v[2:17], v[118:121], v[110:113], v[2:17]
	ds_read_b128 v[110:113], v0 offset:36928
	ds_read_b128 v[114:117], v0 offset:41536
	ds_read_b128 v[122:125], v66 offset:55360
	ds_read_b128 v[126:129], v66 offset:59968
	s_waitcnt vmcnt(9)
	ds_write_b128 v67, v[74:77] offset:4608
	s_waitcnt vmcnt(8)
	ds_write_b128 v67, v[90:93] offset:23040
	v_mfma_f32_32x32x16_bf16 v[18:33], v[118:121], v[130:133], v[18:33]
	global_load_dwordx4 v[74:77], v70, s[0:1] offset:384
	global_load_dwordx4 v[90:93], v70, s[36:37] offset:384
	s_waitcnt lgkmcnt(3)
	v_mfma_f32_32x32x16_bf16 v[2:17], v[114:117], v[122:125], v[2:17]
	s_waitcnt lgkmcnt(2)
	v_mfma_f32_32x32x16_bf16 v[18:33], v[114:117], v[126:129], v[18:33]
	v_mfma_f32_32x32x16_bf16 v[34:49], v[110:113], v[122:125], v[34:49]
	v_mfma_f32_32x32x16_bf16 v[50:65], v[110:113], v[126:129], v[50:65]
	ds_read_b128 v[110:113], v0 offset:36960
	ds_read_b128 v[118:121], v0 offset:41568
	ds_read_b128 v[122:125], v66 offset:55392
	ds_read_b128 v[130:133], v66 offset:60000
	s_waitcnt vmcnt(9)
	ds_write_b128 v67, v[78:81] offset:9216
	s_waitcnt vmcnt(8)
	ds_write_b128 v67, v[94:97] offset:27648
	global_load_dwordx4 v[78:81], v69, s[0:1] offset:384
	global_load_dwordx4 v[94:97], v69, s[36:37] offset:384
	s_waitcnt lgkmcnt(3)
	v_mfma_f32_32x32x16_bf16 v[2:17], v[118:121], v[122:125], v[2:17]
	s_waitcnt vmcnt(9)
	ds_write_b128 v67, v[82:85] offset:13824
	s_waitcnt vmcnt(8)
	ds_write_b128 v67, v[98:101] offset:32256
	s_waitcnt lgkmcnt(4)
	v_mfma_f32_32x32x16_bf16 v[18:33], v[118:121], v[130:133], v[18:33]
	v_mfma_f32_32x32x16_bf16 v[34:49], v[110:113], v[122:125], v[34:49]
	v_mfma_f32_32x32x16_bf16 v[50:65], v[110:113], v[130:133], v[50:65]
	s_waitcnt lgkmcnt(0)
	s_barrier
	ds_read_b128 v[82:85], v0
	ds_read_b128 v[98:101], v66 offset:18432
	ds_read_b128 v[110:113], v0 offset:32
	ds_read_b128 v[114:117], v66 offset:18464
	ds_read_b128 v[118:121], v0 offset:4608
	ds_read_b128 v[122:125], v0 offset:4640
	s_waitcnt lgkmcnt(4)
	v_mfma_f32_32x32x16_bf16 v[34:49], v[82:85], v[98:101], v[34:49]
	s_waitcnt lgkmcnt(1)
	v_mfma_f32_32x32x16_bf16 v[2:17], v[118:121], v[98:101], v[2:17]
	ds_read_b128 v[98:101], v66 offset:23040
	ds_read_b128 v[126:129], v66 offset:23072
	s_waitcnt lgkmcnt(1)
	v_mfma_f32_32x32x16_bf16 v[50:65], v[82:85], v[98:101], v[50:65]
	global_load_dwordx4 v[82:85], v72, s[0:1] offset:512
	global_load_dwordx4 v[130:133], v72, s[36:37] offset:512
	s_waitcnt vmcnt(9)
	ds_write_b128 v67, v[86:89] offset:36864
	s_waitcnt vmcnt(8)
	ds_write_b128 v67, v[134:137] offset:55296
	v_mfma_f32_32x32x16_bf16 v[18:33], v[118:121], v[98:101], v[18:33]
	global_load_dwordx4 v[86:89], v71, s[0:1] offset:512
	global_load_dwordx4 v[98:101], v71, s[36:37] offset:512
	v_mfma_f32_32x32x16_bf16 v[2:17], v[122:125], v[114:117], v[2:17]
	s_waitcnt lgkmcnt(2)
	v_mfma_f32_32x32x16_bf16 v[18:33], v[122:125], v[126:129], v[18:33]
	v_mfma_f32_32x32x16_bf16 v[34:49], v[110:113], v[114:117], v[34:49]
	v_mfma_f32_32x32x16_bf16 v[50:65], v[110:113], v[126:129], v[50:65]
	ds_read_b128 v[110:113], v0 offset:64
	ds_read_b128 v[114:117], v0 offset:4672
	ds_read_b128 v[118:121], v66 offset:18496
	ds_read_b128 v[134:137], v66 offset:23104
	s_waitcnt vmcnt(9)
	ds_write_b128 v67, v[102:105] offset:41472
	s_waitcnt vmcnt(8)
	ds_write_b128 v67, v[106:109] offset:59904
	global_load_dwordx4 v[102:105], v70, s[0:1] offset:512
	global_load_dwordx4 v[106:109], v70, s[36:37] offset:512
	s_waitcnt lgkmcnt(3)
	v_mfma_f32_32x32x16_bf16 v[2:17], v[114:117], v[118:121], v[2:17]
	s_waitcnt lgkmcnt(2)
	v_mfma_f32_32x32x16_bf16 v[18:33], v[114:117], v[134:137], v[18:33]
	v_mfma_f32_32x32x16_bf16 v[34:49], v[110:113], v[118:121], v[34:49]
	v_mfma_f32_32x32x16_bf16 v[50:65], v[110:113], v[134:137], v[50:65]
	ds_read_b128 v[110:113], v0 offset:96
	ds_read_b128 v[118:121], v0 offset:4704
	ds_read_b128 v[122:125], v66 offset:18528
	ds_read_b128 v[126:129], v66 offset:23136
	s_waitcnt vmcnt(9)
	ds_write_b128 v67, v[74:77] offset:46080
	s_waitcnt vmcnt(8)
	ds_write_b128 v67, v[90:93] offset:64512
	global_load_dwordx4 v[74:77], v69, s[0:1] offset:512
	global_load_dwordx4 v[90:93], v69, s[36:37] offset:512
	s_waitcnt lgkmcnt(3)
	v_mfma_f32_32x32x16_bf16 v[2:17], v[118:121], v[122:125], v[2:17]
	s_waitcnt vmcnt(9)
	ds_write_b128 v67, v[78:81] offset:50688
	s_waitcnt vmcnt(8)
	ds_write_b128 v68, v[94:97] offset:13824
	s_waitcnt lgkmcnt(4)
	v_mfma_f32_32x32x16_bf16 v[18:33], v[118:121], v[126:129], v[18:33]
	v_mfma_f32_32x32x16_bf16 v[34:49], v[110:113], v[122:125], v[34:49]
	v_mfma_f32_32x32x16_bf16 v[50:65], v[110:113], v[126:129], v[50:65]
	s_waitcnt lgkmcnt(0)
	s_barrier
; #define GL1_(RA, RB, i) { RA[i] = *(const u32x4*)(ap + (aoff + (i) * astep)); if ((i) < NB) RB[(i) < NB ? (i) : 0] = *(const u32x4*)(bp + (boff + (i) * bstep)); }
; #define LS1_(RA, RB, ST, i) { char* sn_ = lds + (ST) * STAGE; *(u32x4*)(sn_ + wofs + (i) * 32 * LROW) = RA[i]; \
;                               if ((i) < NB) *(u32x4*)(sn_ + STAGE_OP + wofs + (i) * 32 * LROW) = RB[(i) < NB ? (i) : 0]; }
; template <int NJ> DI void gemm_mainloop_reg(const bf16_t* __restrict__ A, int lda, const bf16_t* __restrict__ Bt, int ldb, int K, f32x16 (&acc)[2][NJ], char* lds) {
;     ...
; #pragma unroll
;   for (int i = 0; i < 4; ++i) GL1_(ra0, rb0, i);
;   ap += 128; bp += 128;
; #pragma unroll
;   for (int i = 0; i < 4; ++i) GL1_(ra1, rb1, i);
;   ap += 128; bp += 128;
; #pragma unroll
;   for (int i = 0; i < 4; ++i) LS1_(ra0, rb0, 0, i);
;   __syncthreads();
;   const int nk = K >> 6;
;   for (int kt = 0; kt < nk; kt += 2) {
;     const bool l0 = (kt + 2 < nk), l1 = (kt + 3 < nk);
;     STEP_(0, l0, ra0, rb0, true, ra1, rb1);
;     __syncthreads();
;     STEP_(1, l1, ra1, rb1, l0, ra0, rb0);
;     __syncthreads();
	ds_read_b128 v[78:81], v0 offset:36864
	ds_read_b128 v[94:97], v66 offset:55296
	ds_read_b128 v[110:113], v0 offset:36896
	ds_read_b128 v[114:117], v66 offset:55328
	ds_read_b128 v[118:121], v0 offset:41472
	ds_read_b128 v[122:125], v0 offset:41504
	s_waitcnt lgkmcnt(4)
	v_mfma_f32_32x32x16_bf16 v[34:49], v[78:81], v[94:97], v[34:49]
	s_waitcnt lgkmcnt(1)
	v_mfma_f32_32x32x16_bf16 v[2:17], v[118:121], v[94:97], v[2:17]
	ds_read_b128 v[94:97], v66 offset:59904
	ds_read_b128 v[126:129], v66 offset:59936
	s_waitcnt lgkmcnt(1)
	v_mfma_f32_32x32x16_bf16 v[50:65], v[78:81], v[94:97], v[50:65]
	global_load_dwordx4 v[78:81], v72, s[0:1] offset:640
	global_load_dwordx4 v[134:137], v72, s[36:37] offset:640
	s_waitcnt vmcnt(9)
	ds_write_b128 v67, v[82:85]
	s_waitcnt vmcnt(8)
	ds_write_b128 v67, v[130:133] offset:18432
	v_mfma_f32_32x32x16_bf16 v[18:33], v[118:121], v[94:97], v[18:33]
	global_load_dwordx4 v[82:85], v71, s[0:1] offset:640
	global_load_dwordx4 v[94:97], v71, s[36:37] offset:640
	v_mfma_f32_32x32x16_bf16 v[2:17], v[122:125], v[114:117], v[2:17]
	s_waitcnt lgkmcnt(2)
	v_mfma_f32_32x32x16_bf16 v[18:33], v[122:125], v[126:129], v[18:33]
	v_mfma_f32_32x32x16_bf16 v[34:49], v[110:113], v[114:117], v[34:49]
	v_mfma_f32_32x32x16_bf16 v[50:65], v[110:113], v[126:129], v[50:65]
	ds_read_b128 v[110:113], v0 offset:36928
	ds_read_b128 v[114:117], v0 offset:41536
	ds_read_b128 v[118:121], v66 offset:55360
	ds_read_b128 v[130:133], v66 offset:59968
	s_waitcnt vmcnt(9)
	ds_write_b128 v67, v[86:89] offset:4608
	s_waitcnt vmcnt(8)
	ds_write_b128 v67, v[98:101] offset:23040
	global_load_dwordx4 v[86:89], v70, s[0:1] offset:640
	global_load_dwordx4 v[98:101], v70, s[36:37] offset:640
	s_waitcnt lgkmcnt(3)
	v_mfma_f32_32x32x16_bf16 v[2:17], v[114:117], v[118:121], v[2:17]
	s_waitcnt lgkmcnt(2)
	v_mfma_f32_32x32x16_bf16 v[18:33], v[114:117], v[130:133], v[18:33]
	v_mfma_f32_32x32x16_bf16 v[34:49], v[110:113], v[118:121], v[34:49]
	v_mfma_f32_32x32x16_bf16 v[50:65], v[110:113], v[130:133], v[50:65]
	ds_read_b128 v[110:113], v0 offset:36960
	ds_read_b128 v[118:121], v0 offset:41568
	ds_read_b128 v[122:125], v66 offset:55392
	ds_read_b128 v[126:129], v66 offset:60000
	s_waitcnt vmcnt(9)
	ds_write_b128 v67, v[102:105] offset:9216
	s_waitcnt vmcnt(8)
	ds_write_b128 v67, v[106:109] offset:27648
	global_load_dwordx4 v[102:105], v69, s[0:1] offset:640
	global_load_dwordx4 v[106:109], v69, s[36:37] offset:640
	s_waitcnt lgkmcnt(3)
	v_mfma_f32_32x32x16_bf16 v[2:17], v[118:121], v[122:125], v[2:17]
	s_waitcnt vmcnt(9)
	ds_write_b128 v67, v[74:77] offset:13824
	s_waitcnt vmcnt(8)
	ds_write_b128 v67, v[90:93] offset:32256
	s_waitcnt lgkmcnt(4)
	v_mfma_f32_32x32x16_bf16 v[18:33], v[118:121], v[126:129], v[18:33]
	v_mfma_f32_32x32x16_bf16 v[34:49], v[110:113], v[122:125], v[34:49]
	v_mfma_f32_32x32x16_bf16 v[50:65], v[110:113], v[126:129], v[50:65]
	s_waitcnt lgkmcnt(0)
	s_barrier
	ds_read_b128 v[74:77], v0
	ds_read_b128 v[90:93], v66 offset:18432
	ds_read_b128 v[110:113], v0 offset:32
	ds_read_b128 v[114:117], v66 offset:18464
	ds_read_b128 v[118:121], v0 offset:4608
	ds_read_b128 v[122:125], v0 offset:4640
	s_waitcnt lgkmcnt(4)
	v_mfma_f32_32x32x16_bf16 v[34:49], v[74:77], v[90:93], v[34:49]
	s_waitcnt lgkmcnt(1)
	v_mfma_f32_32x32x16_bf16 v[2:17], v[118:121], v[90:93], v[2:17]
	ds_read_b128 v[90:93], v66 offset:23040
	ds_read_b128 v[126:129], v66 offset:23072
	s_waitcnt lgkmcnt(1)
	v_mfma_f32_32x32x16_bf16 v[50:65], v[74:77], v[90:93], v[50:65]
	global_load_dwordx4 v[74:77], v72, s[0:1] offset:768
	global_load_dwordx4 v[130:133], v72, s[36:37] offset:768
	s_waitcnt vmcnt(9)
	ds_write_b128 v67, v[78:81] offset:36864
	s_waitcnt vmcnt(8)
	ds_write_b128 v67, v[134:137] offset:55296
	v_mfma_f32_32x32x16_bf16 v[18:33], v[118:121], v[90:93], v[18:33]
	global_load_dwordx4 v[78:81], v71, s[0:1] offset:768
	global_load_dwordx4 v[90:93], v71, s[36:37] offset:768
	v_mfma_f32_32x32x16_bf16 v[2:17], v[122:125], v[114:117], v[2:17]
	s_waitcnt lgkmcnt(2)
	v_mfma_f32_32x32x16_bf16 v[18:33], v[122:125], v[126:129], v[18:33]
	v_mfma_f32_32x32x16_bf16 v[34:49], v[110:113], v[114:117], v[34:49]
	v_mfma_f32_32x32x16_bf16 v[50:65], v[110:113], v[126:129], v[50:65]
	ds_read_b128 v[110:113], v0 offset:64
	ds_read_b128 v[114:117], v0 offset:4672
	ds_read_b128 v[118:121], v66 offset:18496
	ds_read_b128 v[134:137], v66 offset:23104
	s_waitcnt vmcnt(9)
	ds_write_b128 v67, v[82:85] offset:41472
	s_waitcnt vmcnt(8)
	ds_write_b128 v67, v[94:97] offset:59904
	global_load_dwordx4 v[82:85], v70, s[0:1] offset:768
	global_load_dwordx4 v[94:97], v70, s[36:37] offset:768
	s_waitcnt lgkmcnt(3)
	v_mfma_f32_32x32x16_bf16 v[2:17], v[114:117], v[118:121], v[2:17]
	s_waitcnt lgkmcnt(2)
	v_mfma_f32_32x32x16_bf16 v[18:33], v[114:117], v[134:137], v[18:33]
	v_mfma_f32_32x32x16_bf16 v[34:49], v[110:113], v[118:121], v[34:49]
	v_mfma_f32_32x32x16_bf16 v[50:65], v[110:113], v[134:137], v[50:65]
	ds_read_b128 v[110:113], v0 offset:96
	ds_read_b128 v[118:121], v0 offset:4704
	ds_read_b128 v[122:125], v66 offset:18528
	ds_read_b128 v[126:129], v66 offset:23136
	s_waitcnt vmcnt(9)
	ds_write_b128 v67, v[86:89] offset:46080
	s_waitcnt vmcnt(8)
	ds_write_b128 v67, v[98:101] offset:64512
	global_load_dwordx4 v[86:89], v69, s[0:1] offset:768
	global_load_dwordx4 v[98:101], v69, s[36:37] offset:768
	s_waitcnt lgkmcnt(3)
	v_mfma_f32_32x32x16_bf16 v[2:17], v[118:121], v[122:125], v[2:17]
	s_waitcnt vmcnt(9)
	ds_write_b128 v67, v[102:105] offset:50688
	s_waitcnt vmcnt(8)
	ds_write_b128 v68, v[106:109] offset:13824
	s_waitcnt lgkmcnt(4)
	v_mfma_f32_32x32x16_bf16 v[18:33], v[118:121], v[126:129], v[18:33]
	v_mfma_f32_32x32x16_bf16 v[34:49], v[110:113], v[122:125], v[34:49]
	v_mfma_f32_32x32x16_bf16 v[50:65], v[110:113], v[126:129], v[50:65]
	s_waitcnt lgkmcnt(0)
	s_barrier
; #define GL1_(RA, RB, i) { RA[i] = *(const u32x4*)(ap + (aoff + (i) * astep)); if ((i) < NB) RB[(i) < NB ? (i) : 0] = *(const u32x4*)(bp + (boff + (i) * bstep)); }
; #define LS1_(RA, RB, ST, i) { char* sn_ = lds + (ST) * STAGE; *(u32x4*)(sn_ + wofs + (i) * 32 * LROW) = RA[i]; \
;                               if ((i) < NB) *(u32x4*)(sn_ + STAGE_OP + wofs + (i) * 32 * LROW) = RB[(i) < NB ? (i) : 0]; }
; template <int NJ> DI void gemm_mainloop_reg(const bf16_t* __restrict__ A, int lda, const bf16_t* __restrict__ Bt, int ldb, int K, f32x16 (&acc)[2][NJ], char* lds) {
;     ...
; #pragma unroll
;   for (int i = 0; i < 4; ++i) GL1_(ra0, rb0, i);
;   ap += 128; bp += 128;
; #pragma unroll
;   for (int i = 0; i < 4; ++i) GL1_(ra1, rb1, i);
;   ap += 128; bp += 128;
; #pragma unroll
;   for (int i = 0; i < 4; ++i) LS1_(ra0, rb0, 0, i);
;   __syncthreads();
;   const int nk = K >> 6;
;   for (int kt = 0; kt < nk; kt += 2) {
;     const bool l0 = (kt + 2 < nk), l1 = (kt + 3 < nk);
;     STEP_(0, l0, ra0, rb0, true, ra1, rb1);
;     __syncthreads();
;     STEP_(1, l1, ra1, rb1, l0, ra0, rb0);
;     __syncthreads();
	ds_read_b128 v[102:105], v0 offset:36864
	ds_read_b128 v[106:109], v66 offset:55296
	ds_read_b128 v[110:113], v0 offset:36896
	ds_read_b128 v[114:117], v66 offset:55328
	ds_read_b128 v[118:121], v0 offset:41472
	ds_read_b128 v[122:125], v0 offset:41504
	s_waitcnt lgkmcnt(4)
	v_mfma_f32_32x32x16_bf16 v[34:49], v[102:105], v[106:109], v[34:49]
	s_waitcnt lgkmcnt(1)
	v_mfma_f32_32x32x16_bf16 v[2:17], v[118:121], v[106:109], v[2:17]
	ds_read_b128 v[106:109], v66 offset:59904
	ds_read_b128 v[126:129], v66 offset:59936
	s_waitcnt lgkmcnt(1)
	v_mfma_f32_32x32x16_bf16 v[50:65], v[102:105], v[106:109], v[50:65]
	global_load_dwordx4 v[102:105], v72, s[0:1] offset:896
	global_load_dwordx4 v[134:137], v72, s[36:37] offset:896
	s_waitcnt vmcnt(9)
	ds_write_b128 v67, v[74:77]
	s_waitcnt vmcnt(8)
	ds_write_b128 v67, v[130:133] offset:18432
	v_mfma_f32_32x32x16_bf16 v[18:33], v[118:121], v[106:109], v[18:33]
	global_load_dwordx4 v[74:77], v71, s[0:1] offset:896
	global_load_dwordx4 v[106:109], v71, s[36:37] offset:896
	v_mfma_f32_32x32x16_bf16 v[2:17], v[122:125], v[114:117], v[2:17]
	s_waitcnt lgkmcnt(2)
	v_mfma_f32_32x32x16_bf16 v[18:33], v[122:125], v[126:129], v[18:33]
	v_mfma_f32_32x32x16_bf16 v[34:49], v[110:113], v[114:117], v[34:49]
	v_mfma_f32_32x32x16_bf16 v[50:65], v[110:113], v[126:129], v[50:65]
	ds_read_b128 v[110:113], v0 offset:36928
	ds_read_b128 v[114:117], v0 offset:41536
	ds_read_b128 v[118:121], v66 offset:55360
	ds_read_b128 v[130:133], v66 offset:59968
	s_waitcnt vmcnt(9)
	ds_write_b128 v67, v[78:81] offset:4608
	s_waitcnt vmcnt(8)
	ds_write_b128 v67, v[90:93] offset:23040
	global_load_dwordx4 v[78:81], v70, s[0:1] offset:896
	global_load_dwordx4 v[90:93], v70, s[36:37] offset:896
	s_waitcnt lgkmcnt(3)
	v_mfma_f32_32x32x16_bf16 v[2:17], v[114:117], v[118:121], v[2:17]
	s_waitcnt lgkmcnt(2)
	v_mfma_f32_32x32x16_bf16 v[18:33], v[114:117], v[130:133], v[18:33]
	v_mfma_f32_32x32x16_bf16 v[34:49], v[110:113], v[118:121], v[34:49]
	v_mfma_f32_32x32x16_bf16 v[50:65], v[110:113], v[130:133], v[50:65]
	ds_read_b128 v[110:113], v0 offset:36960
	ds_read_b128 v[118:121], v0 offset:41568
	ds_read_b128 v[122:125], v66 offset:55392
	ds_read_b128 v[126:129], v66 offset:60000
	s_waitcnt vmcnt(9)
	ds_write_b128 v67, v[82:85] offset:9216
	s_waitcnt vmcnt(8)
	ds_write_b128 v67, v[94:97] offset:27648
	global_load_dwordx4 v[82:85], v69, s[0:1] offset:896
	global_load_dwordx4 v[94:97], v69, s[36:37] offset:896
	s_waitcnt lgkmcnt(3)
	v_mfma_f32_32x32x16_bf16 v[2:17], v[118:121], v[122:125], v[2:17]
	s_waitcnt vmcnt(9)
	ds_write_b128 v67, v[86:89] offset:13824
	s_waitcnt vmcnt(8)
	ds_write_b128 v67, v[98:101] offset:32256
	s_waitcnt lgkmcnt(4)
	v_mfma_f32_32x32x16_bf16 v[18:33], v[118:121], v[126:129], v[18:33]
	v_mfma_f32_32x32x16_bf16 v[34:49], v[110:113], v[122:125], v[34:49]
	v_mfma_f32_32x32x16_bf16 v[50:65], v[110:113], v[126:129], v[50:65]
	s_waitcnt lgkmcnt(0)
	s_barrier
	ds_read_b128 v[86:89], v0
	ds_read_b128 v[98:101], v66 offset:18432
	ds_read_b128 v[110:113], v0 offset:32
	ds_read_b128 v[114:117], v66 offset:18464
	ds_read_b128 v[118:121], v0 offset:4608
	ds_read_b128 v[122:125], v0 offset:4640
	s_waitcnt lgkmcnt(4)
	v_mfma_f32_32x32x16_bf16 v[34:49], v[86:89], v[98:101], v[34:49]
	s_waitcnt lgkmcnt(1)
	v_mfma_f32_32x32x16_bf16 v[2:17], v[118:121], v[98:101], v[2:17]
	ds_read_b128 v[98:101], v66 offset:23040
	ds_read_b128 v[126:129], v66 offset:23072
	s_waitcnt lgkmcnt(1)
	v_mfma_f32_32x32x16_bf16 v[50:65], v[86:89], v[98:101], v[50:65]
	global_load_dwordx4 v[86:89], v72, s[0:1] offset:1024
	global_load_dwordx4 v[130:133], v72, s[36:37] offset:1024
	s_waitcnt vmcnt(9)
	ds_write_b128 v67, v[102:105] offset:36864
	s_waitcnt vmcnt(8)
	ds_write_b128 v67, v[134:137] offset:55296
	v_mfma_f32_32x32x16_bf16 v[18:33], v[118:121], v[98:101], v[18:33]
	global_load_dwordx4 v[98:101], v71, s[0:1] offset:1024
	global_load_dwordx4 v[102:105], v71, s[36:37] offset:1024
	v_mfma_f32_32x32x16_bf16 v[2:17], v[122:125], v[114:117], v[2:17]
	s_waitcnt lgkmcnt(2)
	v_mfma_f32_32x32x16_bf16 v[18:33], v[122:125], v[126:129], v[18:33]
	v_mfma_f32_32x32x16_bf16 v[34:49], v[110:113], v[114:117], v[34:49]
	v_mfma_f32_32x32x16_bf16 v[50:65], v[110:113], v[126:129], v[50:65]
	ds_read_b128 v[110:113], v0 offset:64
	ds_read_b128 v[114:117], v0 offset:4672
	ds_read_b128 v[118:121], v66 offset:18496
	ds_read_b128 v[134:137], v66 offset:23104
	s_waitcnt vmcnt(9)
	ds_write_b128 v67, v[74:77] offset:41472
	s_waitcnt vmcnt(8)
	ds_write_b128 v67, v[106:109] offset:59904
	global_load_dwordx4 v[74:77], v70, s[0:1] offset:1024
	global_load_dwordx4 v[106:109], v70, s[36:37] offset:1024
	s_waitcnt lgkmcnt(3)
	v_mfma_f32_32x32x16_bf16 v[2:17], v[114:117], v[118:121], v[2:17]
	s_waitcnt lgkmcnt(2)
	v_mfma_f32_32x32x16_bf16 v[18:33], v[114:117], v[134:137], v[18:33]
	v_mfma_f32_32x32x16_bf16 v[34:49], v[110:113], v[118:121], v[34:49]
	v_mfma_f32_32x32x16_bf16 v[50:65], v[110:113], v[134:137], v[50:65]
	ds_read_b128 v[110:113], v0 offset:96
	ds_read_b128 v[118:121], v0 offset:4704
	ds_read_b128 v[122:125], v66 offset:18528
	ds_read_b128 v[126:129], v66 offset:23136
	s_waitcnt vmcnt(9)
	ds_write_b128 v67, v[78:81] offset:46080
	s_waitcnt vmcnt(8)
	ds_write_b128 v67, v[90:93] offset:64512
	global_load_dwordx4 v[78:81], v69, s[0:1] offset:1024
	global_load_dwordx4 v[90:93], v69, s[36:37] offset:1024
	s_waitcnt lgkmcnt(3)
	v_mfma_f32_32x32x16_bf16 v[2:17], v[118:121], v[122:125], v[2:17]
	s_waitcnt vmcnt(9)
	ds_write_b128 v67, v[82:85] offset:50688
	s_waitcnt vmcnt(8)
	ds_write_b128 v68, v[94:97] offset:13824
	s_waitcnt lgkmcnt(4)
	v_mfma_f32_32x32x16_bf16 v[18:33], v[118:121], v[126:129], v[18:33]
	v_mfma_f32_32x32x16_bf16 v[34:49], v[110:113], v[122:125], v[34:49]
	v_mfma_f32_32x32x16_bf16 v[50:65], v[110:113], v[126:129], v[50:65]
	s_waitcnt lgkmcnt(0)
	s_barrier
; #define GL1_(RA, RB, i) { RA[i] = *(const u32x4*)(ap + (aoff + (i) * astep)); if ((i) < NB) RB[(i) < NB ? (i) : 0] = *(const u32x4*)(bp + (boff + (i) * bstep)); }
; #define LS1_(RA, RB, ST, i) { char* sn_ = lds + (ST) * STAGE; *(u32x4*)(sn_ + wofs + (i) * 32 * LROW) = RA[i]; \
;                               if ((i) < NB) *(u32x4*)(sn_ + STAGE_OP + wofs + (i) * 32 * LROW) = RB[(i) < NB ? (i) : 0]; }
; template <int NJ> DI void gemm_mainloop_reg(const bf16_t* __restrict__ A, int lda, const bf16_t* __restrict__ Bt, int ldb, int K, f32x16 (&acc)[2][NJ], char* lds) {
;     ...
; #pragma unroll
;   for (int i = 0; i < 4; ++i) GL1_(ra0, rb0, i);
;   ap += 128; bp += 128;
; #pragma unroll
;   for (int i = 0; i < 4; ++i) GL1_(ra1, rb1, i);
;   ap += 128; bp += 128;
; #pragma unroll
;   for (int i = 0; i < 4; ++i) LS1_(ra0, rb0, 0, i);
;   __syncthreads();
;   const int nk = K >> 6;
;   for (int kt = 0; kt < nk; kt += 2) {
;     const bool l0 = (kt + 2 < nk), l1 = (kt + 3 < nk);
;     STEP_(0, l0, ra0, rb0, true, ra1, rb1);
;     __syncthreads();
;     STEP_(1, l1, ra1, rb1, l0, ra0, rb0);
;     __syncthreads();
	ds_read_b128 v[82:85], v0 offset:36864
	ds_read_b128 v[94:97], v66 offset:55296
	ds_read_b128 v[110:113], v0 offset:36896
	ds_read_b128 v[114:117], v66 offset:55328
	ds_read_b128 v[118:121], v0 offset:41472
	ds_read_b128 v[122:125], v0 offset:41504
	s_waitcnt lgkmcnt(4)
	v_mfma_f32_32x32x16_bf16 v[34:49], v[82:85], v[94:97], v[34:49]
	s_waitcnt lgkmcnt(1)
	v_mfma_f32_32x32x16_bf16 v[2:17], v[118:121], v[94:97], v[2:17]
	ds_read_b128 v[94:97], v66 offset:59904
	ds_read_b128 v[126:129], v66 offset:59936
	s_waitcnt lgkmcnt(1)
	v_mfma_f32_32x32x16_bf16 v[50:65], v[82:85], v[94:97], v[50:65]
	global_load_dwordx4 v[82:85], v72, s[0:1] offset:1152
	global_load_dwordx4 v[134:137], v72, s[36:37] offset:1152
	s_waitcnt vmcnt(9)
	ds_write_b128 v67, v[86:89]
	s_waitcnt vmcnt(8)
	ds_write_b128 v67, v[130:133] offset:18432
	v_mfma_f32_32x32x16_bf16 v[18:33], v[118:121], v[94:97], v[18:33]
	global_load_dwordx4 v[86:89], v71, s[0:1] offset:1152
	global_load_dwordx4 v[94:97], v71, s[36:37] offset:1152
	v_mfma_f32_32x32x16_bf16 v[2:17], v[122:125], v[114:117], v[2:17]
	s_waitcnt lgkmcnt(2)
	v_mfma_f32_32x32x16_bf16 v[18:33], v[122:125], v[126:129], v[18:33]
	v_mfma_f32_32x32x16_bf16 v[34:49], v[110:113], v[114:117], v[34:49]
	v_mfma_f32_32x32x16_bf16 v[50:65], v[110:113], v[126:129], v[50:65]
	ds_read_b128 v[110:113], v0 offset:36928
	ds_read_b128 v[114:117], v0 offset:41536
	ds_read_b128 v[118:121], v66 offset:55360
	ds_read_b128 v[130:133], v66 offset:59968
	s_waitcnt vmcnt(9)
	ds_write_b128 v67, v[98:101] offset:4608
	s_waitcnt vmcnt(8)
	ds_write_b128 v67, v[102:105] offset:23040
	global_load_dwordx4 v[98:101], v70, s[0:1] offset:1152
	global_load_dwordx4 v[102:105], v70, s[36:37] offset:1152
	s_waitcnt lgkmcnt(3)
	v_mfma_f32_32x32x16_bf16 v[2:17], v[114:117], v[118:121], v[2:17]
	s_waitcnt lgkmcnt(2)
	v_mfma_f32_32x32x16_bf16 v[18:33], v[114:117], v[130:133], v[18:33]
	v_mfma_f32_32x32x16_bf16 v[34:49], v[110:113], v[118:121], v[34:49]
	v_mfma_f32_32x32x16_bf16 v[50:65], v[110:113], v[130:133], v[50:65]
	ds_read_b128 v[110:113], v0 offset:36960
	ds_read_b128 v[118:121], v0 offset:41568
	ds_read_b128 v[122:125], v66 offset:55392
	ds_read_b128 v[126:129], v66 offset:60000
	s_waitcnt vmcnt(9)
	ds_write_b128 v67, v[74:77] offset:9216
	s_waitcnt vmcnt(8)
	ds_write_b128 v67, v[106:109] offset:27648
	global_load_dwordx4 v[74:77], v69, s[0:1] offset:1152
	global_load_dwordx4 v[106:109], v69, s[36:37] offset:1152
	s_waitcnt lgkmcnt(3)
	v_mfma_f32_32x32x16_bf16 v[2:17], v[118:121], v[122:125], v[2:17]
	s_waitcnt vmcnt(9)
	ds_write_b128 v67, v[78:81] offset:13824
	s_waitcnt vmcnt(8)
	ds_write_b128 v67, v[90:93] offset:32256
	s_waitcnt lgkmcnt(4)
	v_mfma_f32_32x32x16_bf16 v[18:33], v[118:121], v[126:129], v[18:33]
	v_mfma_f32_32x32x16_bf16 v[34:49], v[110:113], v[122:125], v[34:49]
	v_mfma_f32_32x32x16_bf16 v[50:65], v[110:113], v[126:129], v[50:65]
	s_waitcnt lgkmcnt(0)
	s_barrier
	ds_read_b128 v[78:81], v0
	ds_read_b128 v[90:93], v66 offset:18432
	ds_read_b128 v[110:113], v0 offset:32
	ds_read_b128 v[114:117], v66 offset:18464
	ds_read_b128 v[118:121], v0 offset:4608
	ds_read_b128 v[122:125], v0 offset:4640
	s_waitcnt lgkmcnt(4)
	v_mfma_f32_32x32x16_bf16 v[34:49], v[78:81], v[90:93], v[34:49]
	s_waitcnt lgkmcnt(1)
	v_mfma_f32_32x32x16_bf16 v[2:17], v[118:121], v[90:93], v[2:17]
	ds_read_b128 v[90:93], v66 offset:23040
	ds_read_b128 v[126:129], v66 offset:23072
	s_waitcnt lgkmcnt(1)
	v_mfma_f32_32x32x16_bf16 v[50:65], v[78:81], v[90:93], v[50:65]
	global_load_dwordx4 v[78:81], v72, s[0:1] offset:1280
	global_load_dwordx4 v[130:133], v72, s[36:37] offset:1280
	s_waitcnt vmcnt(9)
	ds_write_b128 v67, v[82:85] offset:36864
	s_waitcnt vmcnt(8)
	ds_write_b128 v67, v[134:137] offset:55296
	v_mfma_f32_32x32x16_bf16 v[18:33], v[118:121], v[90:93], v[18:33]
	global_load_dwordx4 v[82:85], v71, s[0:1] offset:1280
	global_load_dwordx4 v[90:93], v71, s[36:37] offset:1280
	v_mfma_f32_32x32x16_bf16 v[2:17], v[122:125], v[114:117], v[2:17]
	s_waitcnt lgkmcnt(2)
	v_mfma_f32_32x32x16_bf16 v[18:33], v[122:125], v[126:129], v[18:33]
	v_mfma_f32_32x32x16_bf16 v[34:49], v[110:113], v[114:117], v[34:49]
	v_mfma_f32_32x32x16_bf16 v[50:65], v[110:113], v[126:129], v[50:65]
	ds_read_b128 v[110:113], v0 offset:64
	ds_read_b128 v[114:117], v0 offset:4672
	ds_read_b128 v[118:121], v66 offset:18496
	ds_read_b128 v[134:137], v66 offset:23104
	s_waitcnt vmcnt(9)
	ds_write_b128 v67, v[86:89] offset:41472
	s_waitcnt vmcnt(8)
	ds_write_b128 v67, v[94:97] offset:59904
	global_load_dwordx4 v[86:89], v70, s[0:1] offset:1280
	global_load_dwordx4 v[94:97], v70, s[36:37] offset:1280
	s_waitcnt lgkmcnt(3)
	v_mfma_f32_32x32x16_bf16 v[2:17], v[114:117], v[118:121], v[2:17]
	s_waitcnt lgkmcnt(2)
	v_mfma_f32_32x32x16_bf16 v[18:33], v[114:117], v[134:137], v[18:33]
	v_mfma_f32_32x32x16_bf16 v[34:49], v[110:113], v[118:121], v[34:49]
	v_mfma_f32_32x32x16_bf16 v[50:65], v[110:113], v[134:137], v[50:65]
	ds_read_b128 v[110:113], v0 offset:96
	ds_read_b128 v[118:121], v0 offset:4704
	ds_read_b128 v[122:125], v66 offset:18528
	ds_read_b128 v[126:129], v66 offset:23136
	s_waitcnt vmcnt(9)
	ds_write_b128 v67, v[98:101] offset:46080
	s_waitcnt vmcnt(8)
	ds_write_b128 v67, v[102:105] offset:64512
	global_load_dwordx4 v[98:101], v69, s[0:1] offset:1280
	global_load_dwordx4 v[102:105], v69, s[36:37] offset:1280
	s_waitcnt lgkmcnt(3)
	v_mfma_f32_32x32x16_bf16 v[2:17], v[118:121], v[122:125], v[2:17]
	s_waitcnt vmcnt(9)
	ds_write_b128 v67, v[74:77] offset:50688
	s_waitcnt vmcnt(8)
	ds_write_b128 v68, v[106:109] offset:13824
	s_waitcnt lgkmcnt(4)
	v_mfma_f32_32x32x16_bf16 v[18:33], v[118:121], v[126:129], v[18:33]
	v_mfma_f32_32x32x16_bf16 v[34:49], v[110:113], v[122:125], v[34:49]
	v_mfma_f32_32x32x16_bf16 v[50:65], v[110:113], v[126:129], v[50:65]
	s_waitcnt lgkmcnt(0)
	s_barrier
; #define GL1_(RA, RB, i) { RA[i] = *(const u32x4*)(ap + (aoff + (i) * astep)); if ((i) < NB) RB[(i) < NB ? (i) : 0] = *(const u32x4*)(bp + (boff + (i) * bstep)); }
; #define LS1_(RA, RB, ST, i) { char* sn_ = lds + (ST) * STAGE; *(u32x4*)(sn_ + wofs + (i) * 32 * LROW) = RA[i]; \
;                               if ((i) < NB) *(u32x4*)(sn_ + STAGE_OP + wofs + (i) * 32 * LROW) = RB[(i) < NB ? (i) : 0]; }
; template <int NJ> DI void gemm_mainloop_reg(const bf16_t* __restrict__ A, int lda, const bf16_t* __restrict__ Bt, int ldb, int K, f32x16 (&acc)[2][NJ], char* lds) {
;     ...
; #pragma unroll
;   for (int i = 0; i < 4; ++i) GL1_(ra0, rb0, i);
;   ap += 128; bp += 128;
; #pragma unroll
;   for (int i = 0; i < 4; ++i) GL1_(ra1, rb1, i);
;   ap += 128; bp += 128;
; #pragma unroll
;   for (int i = 0; i < 4; ++i) LS1_(ra0, rb0, 0, i);
;   __syncthreads();
;   const int nk = K >> 6;
;   for (int kt = 0; kt < nk; kt += 2) {
;     const bool l0 = (kt + 2 < nk), l1 = (kt + 3 < nk);
;     STEP_(0, l0, ra0, rb0, true, ra1, rb1);
;     __syncthreads();
;     STEP_(1, l1, ra1, rb1, l0, ra0, rb0);
;     __syncthreads();
	ds_read_b128 v[74:77], v0 offset:36864
	ds_read_b128 v[106:109], v66 offset:55296
	ds_read_b128 v[110:113], v0 offset:36896
	ds_read_b128 v[114:117], v66 offset:55328
	ds_read_b128 v[118:121], v0 offset:41472
	ds_read_b128 v[122:125], v0 offset:41504
	s_waitcnt lgkmcnt(4)
	v_mfma_f32_32x32x16_bf16 v[34:49], v[74:77], v[106:109], v[34:49]
	s_waitcnt lgkmcnt(1)
	v_mfma_f32_32x32x16_bf16 v[2:17], v[118:121], v[106:109], v[2:17]
	ds_read_b128 v[106:109], v66 offset:59904
	ds_read_b128 v[126:129], v66 offset:59936
	s_waitcnt lgkmcnt(1)
	v_mfma_f32_32x32x16_bf16 v[50:65], v[74:77], v[106:109], v[50:65]
	global_load_dwordx4 v[74:77], v72, s[0:1] offset:1408
	global_load_dwordx4 v[134:137], v72, s[36:37] offset:1408
	s_waitcnt vmcnt(9)
	ds_write_b128 v67, v[78:81]
	s_waitcnt vmcnt(8)
	ds_write_b128 v67, v[130:133] offset:18432
	v_mfma_f32_32x32x16_bf16 v[18:33], v[118:121], v[106:109], v[18:33]
	global_load_dwordx4 v[78:81], v71, s[0:1] offset:1408
	global_load_dwordx4 v[106:109], v71, s[36:37] offset:1408
	v_mfma_f32_32x32x16_bf16 v[2:17], v[122:125], v[114:117], v[2:17]
	s_waitcnt lgkmcnt(2)
	v_mfma_f32_32x32x16_bf16 v[18:33], v[122:125], v[126:129], v[18:33]
	v_mfma_f32_32x32x16_bf16 v[34:49], v[110:113], v[114:117], v[34:49]
	v_mfma_f32_32x32x16_bf16 v[50:65], v[110:113], v[126:129], v[50:65]
	ds_read_b128 v[110:113], v0 offset:36928
	ds_read_b128 v[114:117], v0 offset:41536
	ds_read_b128 v[118:121], v66 offset:55360
	ds_read_b128 v[130:133], v66 offset:59968
	s_waitcnt vmcnt(9)
	ds_write_b128 v67, v[82:85] offset:4608
	s_waitcnt vmcnt(8)
	ds_write_b128 v67, v[90:93] offset:23040
	global_load_dwordx4 v[82:85], v70, s[0:1] offset:1408
	global_load_dwordx4 v[90:93], v70, s[36:37] offset:1408
	s_waitcnt lgkmcnt(3)
	v_mfma_f32_32x32x16_bf16 v[2:17], v[114:117], v[118:121], v[2:17]
	s_waitcnt lgkmcnt(2)
	v_mfma_f32_32x32x16_bf16 v[18:33], v[114:117], v[130:133], v[18:33]
	v_mfma_f32_32x32x16_bf16 v[34:49], v[110:113], v[118:121], v[34:49]
	v_mfma_f32_32x32x16_bf16 v[50:65], v[110:113], v[130:133], v[50:65]
	ds_read_b128 v[110:113], v0 offset:36960
	ds_read_b128 v[118:121], v0 offset:41568
	ds_read_b128 v[122:125], v66 offset:55392
	ds_read_b128 v[126:129], v66 offset:60000
	s_waitcnt vmcnt(9)
	ds_write_b128 v67, v[86:89] offset:9216
	s_waitcnt vmcnt(8)
	ds_write_b128 v67, v[94:97] offset:27648
	global_load_dwordx4 v[86:89], v69, s[0:1] offset:1408
	global_load_dwordx4 v[94:97], v69, s[36:37] offset:1408
	s_waitcnt lgkmcnt(3)
	v_mfma_f32_32x32x16_bf16 v[2:17], v[118:121], v[122:125], v[2:17]
	s_waitcnt vmcnt(9)
	ds_write_b128 v67, v[98:101] offset:13824
	s_waitcnt vmcnt(8)
	ds_write_b128 v67, v[102:105] offset:32256
	s_waitcnt lgkmcnt(4)
	v_mfma_f32_32x32x16_bf16 v[18:33], v[118:121], v[126:129], v[18:33]
	v_mfma_f32_32x32x16_bf16 v[34:49], v[110:113], v[122:125], v[34:49]
	v_mfma_f32_32x32x16_bf16 v[50:65], v[110:113], v[126:129], v[50:65]
	s_waitcnt lgkmcnt(0)
	s_barrier
	ds_read_b128 v[98:101], v0
	ds_read_b128 v[102:105], v66 offset:18432
	ds_read_b128 v[110:113], v0 offset:32
	ds_read_b128 v[114:117], v66 offset:18464
	ds_read_b128 v[118:121], v0 offset:4608
	ds_read_b128 v[122:125], v0 offset:4640
	s_waitcnt lgkmcnt(4)
	v_mfma_f32_32x32x16_bf16 v[34:49], v[98:101], v[102:105], v[34:49]
	s_waitcnt lgkmcnt(1)
	v_mfma_f32_32x32x16_bf16 v[2:17], v[118:121], v[102:105], v[2:17]
	ds_read_b128 v[102:105], v66 offset:23040
	ds_read_b128 v[126:129], v66 offset:23072
	s_waitcnt lgkmcnt(1)
	v_mfma_f32_32x32x16_bf16 v[50:65], v[98:101], v[102:105], v[50:65]
	global_load_dwordx4 v[98:101], v72, s[0:1] offset:1536
	global_load_dwordx4 v[130:133], v72, s[36:37] offset:1536
	s_waitcnt vmcnt(9)
	ds_write_b128 v67, v[74:77] offset:36864
	s_waitcnt vmcnt(8)
	ds_write_b128 v67, v[134:137] offset:55296
	v_mfma_f32_32x32x16_bf16 v[18:33], v[118:121], v[102:105], v[18:33]
	global_load_dwordx4 v[74:77], v71, s[0:1] offset:1536
	global_load_dwordx4 v[102:105], v71, s[36:37] offset:1536
	v_mfma_f32_32x32x16_bf16 v[2:17], v[122:125], v[114:117], v[2:17]
	s_waitcnt lgkmcnt(2)
	v_mfma_f32_32x32x16_bf16 v[18:33], v[122:125], v[126:129], v[18:33]
	v_mfma_f32_32x32x16_bf16 v[34:49], v[110:113], v[114:117], v[34:49]
	v_mfma_f32_32x32x16_bf16 v[50:65], v[110:113], v[126:129], v[50:65]
	ds_read_b128 v[110:113], v0 offset:64
	ds_read_b128 v[114:117], v0 offset:4672
	ds_read_b128 v[118:121], v66 offset:18496
	ds_read_b128 v[134:137], v66 offset:23104
	s_waitcnt vmcnt(9)
	ds_write_b128 v67, v[78:81] offset:41472
	s_waitcnt vmcnt(8)
	ds_write_b128 v67, v[106:109] offset:59904
	global_load_dwordx4 v[78:81], v70, s[0:1] offset:1536
	global_load_dwordx4 v[106:109], v70, s[36:37] offset:1536
	s_waitcnt lgkmcnt(3)
	v_mfma_f32_32x32x16_bf16 v[2:17], v[114:117], v[118:121], v[2:17]
	s_waitcnt lgkmcnt(2)
	v_mfma_f32_32x32x16_bf16 v[18:33], v[114:117], v[134:137], v[18:33]
	v_mfma_f32_32x32x16_bf16 v[34:49], v[110:113], v[118:121], v[34:49]
	v_mfma_f32_32x32x16_bf16 v[50:65], v[110:113], v[134:137], v[50:65]
	ds_read_b128 v[110:113], v0 offset:96
	ds_read_b128 v[118:121], v0 offset:4704
	ds_read_b128 v[122:125], v66 offset:18528
	ds_read_b128 v[126:129], v66 offset:23136
	s_waitcnt vmcnt(9)
	ds_write_b128 v67, v[82:85] offset:46080
	s_waitcnt vmcnt(8)
	ds_write_b128 v67, v[90:93] offset:64512
	global_load_dwordx4 v[82:85], v69, s[0:1] offset:1536
	global_load_dwordx4 v[90:93], v69, s[36:37] offset:1536
	s_waitcnt lgkmcnt(3)
	v_mfma_f32_32x32x16_bf16 v[2:17], v[118:121], v[122:125], v[2:17]
	s_waitcnt vmcnt(9)
	ds_write_b128 v67, v[86:89] offset:50688
	s_waitcnt vmcnt(8)
	ds_write_b128 v68, v[94:97] offset:13824
	s_waitcnt lgkmcnt(4)
	v_mfma_f32_32x32x16_bf16 v[18:33], v[118:121], v[126:129], v[18:33]
	v_mfma_f32_32x32x16_bf16 v[34:49], v[110:113], v[122:125], v[34:49]
	v_mfma_f32_32x32x16_bf16 v[50:65], v[110:113], v[126:129], v[50:65]
	s_waitcnt lgkmcnt(0)
	s_barrier
; #define GL1_(RA, RB, i) { RA[i] = *(const u32x4*)(ap + (aoff + (i) * astep)); if ((i) < NB) RB[(i) < NB ? (i) : 0] = *(const u32x4*)(bp + (boff + (i) * bstep)); }
; #define LS1_(RA, RB, ST, i) { char* sn_ = lds + (ST) * STAGE; *(u32x4*)(sn_ + wofs + (i) * 32 * LROW) = RA[i]; \
;                               if ((i) < NB) *(u32x4*)(sn_ + STAGE_OP + wofs + (i) * 32 * LROW) = RB[(i) < NB ? (i) : 0]; }
; template <int NJ> DI void gemm_mainloop_reg(const bf16_t* __restrict__ A, int lda, const bf16_t* __restrict__ Bt, int ldb, int K, f32x16 (&acc)[2][NJ], char* lds) {
;     ...
; #pragma unroll
;   for (int i = 0; i < 4; ++i) GL1_(ra0, rb0, i);
;   ap += 128; bp += 128;
; #pragma unroll
;   for (int i = 0; i < 4; ++i) GL1_(ra1, rb1, i);
;   ap += 128; bp += 128;
; #pragma unroll
;   for (int i = 0; i < 4; ++i) LS1_(ra0, rb0, 0, i);
;   __syncthreads();
;   const int nk = K >> 6;
;   for (int kt = 0; kt < nk; kt += 2) {
;     const bool l0 = (kt + 2 < nk), l1 = (kt + 3 < nk);
;     STEP_(0, l0, ra0, rb0, true, ra1, rb1);
;     __syncthreads();
;     STEP_(1, l1, ra1, rb1, l0, ra0, rb0);
;     __syncthreads();
	ds_read_b128 v[86:89], v0 offset:36864
	ds_read_b128 v[94:97], v66 offset:55296
	ds_read_b128 v[110:113], v0 offset:36896
	ds_read_b128 v[114:117], v66 offset:55328
	ds_read_b128 v[118:121], v0 offset:41472
	ds_read_b128 v[122:125], v0 offset:41504
	s_waitcnt lgkmcnt(4)
	v_mfma_f32_32x32x16_bf16 v[34:49], v[86:89], v[94:97], v[34:49]
	s_waitcnt lgkmcnt(1)
	v_mfma_f32_32x32x16_bf16 v[2:17], v[118:121], v[94:97], v[2:17]
	ds_read_b128 v[94:97], v66 offset:59904
	ds_read_b128 v[126:129], v66 offset:59936
	s_waitcnt lgkmcnt(1)
	v_mfma_f32_32x32x16_bf16 v[50:65], v[86:89], v[94:97], v[50:65]
	global_load_dwordx4 v[86:89], v72, s[0:1] offset:1664
	global_load_dwordx4 v[134:137], v72, s[36:37] offset:1664
	s_waitcnt vmcnt(9)
	ds_write_b128 v67, v[98:101]
	s_waitcnt vmcnt(8)
	ds_write_b128 v67, v[130:133] offset:18432
	v_mfma_f32_32x32x16_bf16 v[18:33], v[118:121], v[94:97], v[18:33]
	global_load_dwordx4 v[94:97], v71, s[0:1] offset:1664
	global_load_dwordx4 v[98:101], v71, s[36:37] offset:1664
	v_mfma_f32_32x32x16_bf16 v[2:17], v[122:125], v[114:117], v[2:17]
	s_waitcnt lgkmcnt(2)
	v_mfma_f32_32x32x16_bf16 v[18:33], v[122:125], v[126:129], v[18:33]
	v_mfma_f32_32x32x16_bf16 v[34:49], v[110:113], v[114:117], v[34:49]
	v_mfma_f32_32x32x16_bf16 v[50:65], v[110:113], v[126:129], v[50:65]
	ds_read_b128 v[110:113], v0 offset:36928
	ds_read_b128 v[114:117], v0 offset:41536
	ds_read_b128 v[118:121], v66 offset:55360
	ds_read_b128 v[130:133], v66 offset:59968
	s_waitcnt vmcnt(9)
	ds_write_b128 v67, v[74:77] offset:4608
	s_waitcnt vmcnt(8)
	ds_write_b128 v67, v[102:105] offset:23040
	global_load_dwordx4 v[74:77], v70, s[0:1] offset:1664
	global_load_dwordx4 v[102:105], v70, s[36:37] offset:1664
	s_waitcnt lgkmcnt(3)
	v_mfma_f32_32x32x16_bf16 v[2:17], v[114:117], v[118:121], v[2:17]
	s_waitcnt lgkmcnt(2)
	v_mfma_f32_32x32x16_bf16 v[18:33], v[114:117], v[130:133], v[18:33]
	v_mfma_f32_32x32x16_bf16 v[34:49], v[110:113], v[118:121], v[34:49]
	v_mfma_f32_32x32x16_bf16 v[50:65], v[110:113], v[130:133], v[50:65]
	ds_read_b128 v[110:113], v0 offset:36960
	ds_read_b128 v[118:121], v0 offset:41568
	ds_read_b128 v[122:125], v66 offset:55392
	ds_read_b128 v[126:129], v66 offset:60000
	s_waitcnt vmcnt(9)
	ds_write_b128 v67, v[78:81] offset:9216
	s_waitcnt vmcnt(8)
	ds_write_b128 v67, v[106:109] offset:27648
	global_load_dwordx4 v[78:81], v69, s[0:1] offset:1664
	global_load_dwordx4 v[106:109], v69, s[36:37] offset:1664
	s_waitcnt lgkmcnt(3)
	v_mfma_f32_32x32x16_bf16 v[2:17], v[118:121], v[122:125], v[2:17]
	s_waitcnt vmcnt(9)
	ds_write_b128 v67, v[82:85] offset:13824
	s_waitcnt vmcnt(8)
	ds_write_b128 v67, v[90:93] offset:32256
	s_waitcnt lgkmcnt(4)
	v_mfma_f32_32x32x16_bf16 v[18:33], v[118:121], v[126:129], v[18:33]
	v_mfma_f32_32x32x16_bf16 v[34:49], v[110:113], v[122:125], v[34:49]
	v_mfma_f32_32x32x16_bf16 v[50:65], v[110:113], v[126:129], v[50:65]
	s_waitcnt lgkmcnt(0)
	s_barrier
	ds_read_b128 v[82:85], v0
	ds_read_b128 v[90:93], v66 offset:18432
	ds_read_b128 v[110:113], v0 offset:32
	ds_read_b128 v[114:117], v66 offset:18464
	ds_read_b128 v[118:121], v0 offset:4608
	ds_read_b128 v[122:125], v0 offset:4640
	s_waitcnt lgkmcnt(4)
	v_mfma_f32_32x32x16_bf16 v[34:49], v[82:85], v[90:93], v[34:49]
	s_waitcnt lgkmcnt(1)
	v_mfma_f32_32x32x16_bf16 v[2:17], v[118:121], v[90:93], v[2:17]
	ds_read_b128 v[90:93], v66 offset:23040
	ds_read_b128 v[126:129], v66 offset:23072
	s_waitcnt lgkmcnt(1)
	v_mfma_f32_32x32x16_bf16 v[50:65], v[82:85], v[90:93], v[50:65]
	global_load_dwordx4 v[82:85], v72, s[0:1] offset:1792
	global_load_dwordx4 v[130:133], v72, s[36:37] offset:1792
	s_waitcnt vmcnt(9)
	ds_write_b128 v67, v[86:89] offset:36864
	s_waitcnt vmcnt(8)
	ds_write_b128 v67, v[134:137] offset:55296
	v_mfma_f32_32x32x16_bf16 v[18:33], v[118:121], v[90:93], v[18:33]
	global_load_dwordx4 v[86:89], v71, s[0:1] offset:1792
	global_load_dwordx4 v[90:93], v71, s[36:37] offset:1792
	v_mfma_f32_32x32x16_bf16 v[2:17], v[122:125], v[114:117], v[2:17]
	s_waitcnt lgkmcnt(2)
	v_mfma_f32_32x32x16_bf16 v[18:33], v[122:125], v[126:129], v[18:33]
	v_mfma_f32_32x32x16_bf16 v[34:49], v[110:113], v[114:117], v[34:49]
	v_mfma_f32_32x32x16_bf16 v[50:65], v[110:113], v[126:129], v[50:65]
	ds_read_b128 v[110:113], v0 offset:64
	ds_read_b128 v[114:117], v0 offset:4672
	ds_read_b128 v[118:121], v66 offset:18496
	ds_read_b128 v[134:137], v66 offset:23104
	s_waitcnt vmcnt(9)
	ds_write_b128 v67, v[94:97] offset:41472
	s_waitcnt vmcnt(8)
	ds_write_b128 v67, v[98:101] offset:59904
	global_load_dwordx4 v[94:97], v70, s[0:1] offset:1792
	global_load_dwordx4 v[98:101], v70, s[36:37] offset:1792
	s_waitcnt lgkmcnt(3)
	v_mfma_f32_32x32x16_bf16 v[2:17], v[114:117], v[118:121], v[2:17]
	s_waitcnt lgkmcnt(2)
	v_mfma_f32_32x32x16_bf16 v[18:33], v[114:117], v[134:137], v[18:33]
	v_mfma_f32_32x32x16_bf16 v[34:49], v[110:113], v[118:121], v[34:49]
	v_mfma_f32_32x32x16_bf16 v[50:65], v[110:113], v[134:137], v[50:65]
	ds_read_b128 v[110:113], v0 offset:96
	ds_read_b128 v[118:121], v0 offset:4704
	ds_read_b128 v[122:125], v66 offset:18528
	ds_read_b128 v[126:129], v66 offset:23136
	s_waitcnt vmcnt(9)
	ds_write_b128 v67, v[74:77] offset:46080
	s_waitcnt vmcnt(8)
	ds_write_b128 v67, v[102:105] offset:64512
	global_load_dwordx4 v[74:77], v69, s[0:1] offset:1792
	global_load_dwordx4 v[102:105], v69, s[36:37] offset:1792
	s_waitcnt lgkmcnt(3)
	v_mfma_f32_32x32x16_bf16 v[2:17], v[118:121], v[122:125], v[2:17]
	s_waitcnt vmcnt(9)
	ds_write_b128 v67, v[78:81] offset:50688
	s_waitcnt vmcnt(8)
	ds_write_b128 v68, v[106:109] offset:13824
	s_waitcnt lgkmcnt(4)
	v_mfma_f32_32x32x16_bf16 v[18:33], v[118:121], v[126:129], v[18:33]
	v_mfma_f32_32x32x16_bf16 v[34:49], v[110:113], v[122:125], v[34:49]
	v_mfma_f32_32x32x16_bf16 v[50:65], v[110:113], v[126:129], v[50:65]
	s_waitcnt lgkmcnt(0)
	s_barrier
; #define GL1_(RA, RB, i) { RA[i] = *(const u32x4*)(ap + (aoff + (i) * astep)); if ((i) < NB) RB[(i) < NB ? (i) : 0] = *(const u32x4*)(bp + (boff + (i) * bstep)); }
; #define LS1_(RA, RB, ST, i) { char* sn_ = lds + (ST) * STAGE; *(u32x4*)(sn_ + wofs + (i) * 32 * LROW) = RA[i]; \
;                               if ((i) < NB) *(u32x4*)(sn_ + STAGE_OP + wofs + (i) * 32 * LROW) = RB[(i) < NB ? (i) : 0]; }
; template <int NJ> DI void gemm_mainloop_reg(const bf16_t* __restrict__ A, int lda, const bf16_t* __restrict__ Bt, int ldb, int K, f32x16 (&acc)[2][NJ], char* lds) {
;     ...
; #pragma unroll
;   for (int i = 0; i < 4; ++i) GL1_(ra0, rb0, i);
;   ap += 128; bp += 128;
; #pragma unroll
;   for (int i = 0; i < 4; ++i) GL1_(ra1, rb1, i);
;   ap += 128; bp += 128;
; #pragma unroll
;   for (int i = 0; i < 4; ++i) LS1_(ra0, rb0, 0, i);
;   __syncthreads();
;   const int nk = K >> 6;
;   for (int kt = 0; kt < nk; kt += 2) {
;     const bool l0 = (kt + 2 < nk), l1 = (kt + 3 < nk);
;     STEP_(0, l0, ra0, rb0, true, ra1, rb1);
;     __syncthreads();
;     STEP_(1, l1, ra1, rb1, l0, ra0, rb0);
;     __syncthreads();
	ds_read_b128 v[78:81], v0 offset:36864
	ds_read_b128 v[106:109], v66 offset:55296
	ds_read_b128 v[110:113], v0 offset:36896
	ds_read_b128 v[114:117], v66 offset:55328
	ds_read_b128 v[118:121], v0 offset:41472
	ds_read_b128 v[122:125], v0 offset:41504
	s_waitcnt lgkmcnt(4)
	v_mfma_f32_32x32x16_bf16 v[34:49], v[78:81], v[106:109], v[34:49]
	s_waitcnt lgkmcnt(1)
	v_mfma_f32_32x32x16_bf16 v[2:17], v[118:121], v[106:109], v[2:17]
	ds_read_b128 v[106:109], v66 offset:59904
	ds_read_b128 v[126:129], v66 offset:59936
	s_waitcnt lgkmcnt(1)
	v_mfma_f32_32x32x16_bf16 v[50:65], v[78:81], v[106:109], v[50:65]
	global_load_dwordx4 v[78:81], v72, s[0:1] offset:1920
	global_load_dwordx4 v[134:137], v72, s[36:37] offset:1920
	s_waitcnt vmcnt(9)
	ds_write_b128 v67, v[82:85]
	s_waitcnt vmcnt(8)
	ds_write_b128 v67, v[130:133] offset:18432
	v_mfma_f32_32x32x16_bf16 v[18:33], v[118:121], v[106:109], v[18:33]
	global_load_dwordx4 v[82:85], v71, s[0:1] offset:1920
	global_load_dwordx4 v[106:109], v71, s[36:37] offset:1920
	v_mfma_f32_32x32x16_bf16 v[2:17], v[122:125], v[114:117], v[2:17]
	s_waitcnt lgkmcnt(2)
	v_mfma_f32_32x32x16_bf16 v[18:33], v[122:125], v[126:129], v[18:33]
	v_mfma_f32_32x32x16_bf16 v[34:49], v[110:113], v[114:117], v[34:49]
	v_mfma_f32_32x32x16_bf16 v[50:65], v[110:113], v[126:129], v[50:65]
	ds_read_b128 v[110:113], v0 offset:36928
	ds_read_b128 v[114:117], v0 offset:41536
	ds_read_b128 v[118:121], v66 offset:55360
	ds_read_b128 v[130:133], v66 offset:59968
	s_waitcnt vmcnt(9)
	ds_write_b128 v67, v[86:89] offset:4608
	s_waitcnt vmcnt(8)
	ds_write_b128 v67, v[90:93] offset:23040
	global_load_dwordx4 v[86:89], v70, s[0:1] offset:1920
	global_load_dwordx4 v[90:93], v70, s[36:37] offset:1920
	s_waitcnt lgkmcnt(3)
	v_mfma_f32_32x32x16_bf16 v[2:17], v[114:117], v[118:121], v[2:17]
	s_waitcnt lgkmcnt(2)
	v_mfma_f32_32x32x16_bf16 v[18:33], v[114:117], v[130:133], v[18:33]
	v_mfma_f32_32x32x16_bf16 v[34:49], v[110:113], v[118:121], v[34:49]
	v_mfma_f32_32x32x16_bf16 v[50:65], v[110:113], v[130:133], v[50:65]
	ds_read_b128 v[110:113], v0 offset:36960
	ds_read_b128 v[118:121], v0 offset:41568
	ds_read_b128 v[122:125], v66 offset:55392
	ds_read_b128 v[126:129], v66 offset:60000
	s_waitcnt vmcnt(9)
	ds_write_b128 v67, v[94:97] offset:9216
	s_waitcnt vmcnt(8)
	ds_write_b128 v67, v[98:101] offset:27648
	global_load_dwordx4 v[94:97], v69, s[0:1] offset:1920
	global_load_dwordx4 v[98:101], v69, s[36:37] offset:1920
	s_waitcnt lgkmcnt(3)
	v_mfma_f32_32x32x16_bf16 v[2:17], v[118:121], v[122:125], v[2:17]
	s_waitcnt vmcnt(9)
	ds_write_b128 v67, v[74:77] offset:13824
	s_waitcnt vmcnt(8)
	ds_write_b128 v67, v[102:105] offset:32256
	s_waitcnt lgkmcnt(4)
	v_mfma_f32_32x32x16_bf16 v[18:33], v[118:121], v[126:129], v[18:33]
	v_mfma_f32_32x32x16_bf16 v[34:49], v[110:113], v[122:125], v[34:49]
	v_mfma_f32_32x32x16_bf16 v[50:65], v[110:113], v[126:129], v[50:65]
	s_waitcnt lgkmcnt(0)
	s_barrier
	ds_read_b128 v[74:77], v0
	ds_read_b128 v[102:105], v66 offset:18432
	ds_read_b128 v[110:113], v0 offset:32
	ds_read_b128 v[114:117], v66 offset:18464
	ds_read_b128 v[118:121], v0 offset:4608
	ds_read_b128 v[122:125], v0 offset:4640
	s_waitcnt lgkmcnt(4)
	v_mfma_f32_32x32x16_bf16 v[34:49], v[74:77], v[102:105], v[34:49]
	s_waitcnt lgkmcnt(1)
	v_mfma_f32_32x32x16_bf16 v[2:17], v[118:121], v[102:105], v[2:17]
	ds_read_b128 v[102:105], v66 offset:23040
	ds_read_b128 v[126:129], v66 offset:23072
	s_waitcnt lgkmcnt(1)
	v_mfma_f32_32x32x16_bf16 v[50:65], v[74:77], v[102:105], v[50:65]
	global_load_dwordx4 v[74:77], v72, s[0:1] offset:2048
	global_load_dwordx4 v[130:133], v72, s[36:37] offset:2048
	s_waitcnt vmcnt(9)
	ds_write_b128 v67, v[78:81] offset:36864
	s_waitcnt vmcnt(8)
	ds_write_b128 v67, v[134:137] offset:55296
	v_mfma_f32_32x32x16_bf16 v[18:33], v[118:121], v[102:105], v[18:33]
	global_load_dwordx4 v[78:81], v71, s[0:1] offset:2048
	global_load_dwordx4 v[102:105], v71, s[36:37] offset:2048
	v_mfma_f32_32x32x16_bf16 v[2:17], v[122:125], v[114:117], v[2:17]
	s_waitcnt lgkmcnt(2)
	v_mfma_f32_32x32x16_bf16 v[18:33], v[122:125], v[126:129], v[18:33]
	v_mfma_f32_32x32x16_bf16 v[34:49], v[110:113], v[114:117], v[34:49]
	v_mfma_f32_32x32x16_bf16 v[50:65], v[110:113], v[126:129], v[50:65]
	ds_read_b128 v[110:113], v0 offset:64
	ds_read_b128 v[114:117], v0 offset:4672
	ds_read_b128 v[118:121], v66 offset:18496
	ds_read_b128 v[134:137], v66 offset:23104
	s_waitcnt vmcnt(9)
	ds_write_b128 v67, v[82:85] offset:41472
	s_waitcnt vmcnt(8)
	ds_write_b128 v67, v[106:109] offset:59904
	global_load_dwordx4 v[82:85], v70, s[0:1] offset:2048
	global_load_dwordx4 v[106:109], v70, s[36:37] offset:2048
	s_waitcnt lgkmcnt(3)
	v_mfma_f32_32x32x16_bf16 v[2:17], v[114:117], v[118:121], v[2:17]
	s_waitcnt lgkmcnt(2)
	v_mfma_f32_32x32x16_bf16 v[18:33], v[114:117], v[134:137], v[18:33]
	v_mfma_f32_32x32x16_bf16 v[34:49], v[110:113], v[118:121], v[34:49]
	v_mfma_f32_32x32x16_bf16 v[50:65], v[110:113], v[134:137], v[50:65]
	ds_read_b128 v[110:113], v0 offset:96
	ds_read_b128 v[118:121], v0 offset:4704
	ds_read_b128 v[122:125], v66 offset:18528
	ds_read_b128 v[126:129], v66 offset:23136
	s_waitcnt vmcnt(9)
	ds_write_b128 v67, v[86:89] offset:46080
	s_waitcnt vmcnt(8)
	ds_write_b128 v67, v[90:93] offset:64512
	global_load_dwordx4 v[86:89], v69, s[0:1] offset:2048
	global_load_dwordx4 v[90:93], v69, s[36:37] offset:2048
	s_waitcnt lgkmcnt(3)
	v_mfma_f32_32x32x16_bf16 v[2:17], v[118:121], v[122:125], v[2:17]
	s_waitcnt vmcnt(9)
	ds_write_b128 v67, v[94:97] offset:50688
	s_waitcnt vmcnt(8)
	ds_write_b128 v68, v[98:101] offset:13824
	s_waitcnt lgkmcnt(4)
	v_mfma_f32_32x32x16_bf16 v[18:33], v[118:121], v[126:129], v[18:33]
	v_mfma_f32_32x32x16_bf16 v[34:49], v[110:113], v[122:125], v[34:49]
	v_mfma_f32_32x32x16_bf16 v[50:65], v[110:113], v[126:129], v[50:65]
	s_waitcnt lgkmcnt(0)
	s_barrier
; #define GL1_(RA, RB, i) { RA[i] = *(const u32x4*)(ap + (aoff + (i) * astep)); if ((i) < NB) RB[(i) < NB ? (i) : 0] = *(const u32x4*)(bp + (boff + (i) * bstep)); }
; #define LS1_(RA, RB, ST, i) { char* sn_ = lds + (ST) * STAGE; *(u32x4*)(sn_ + wofs + (i) * 32 * LROW) = RA[i]; \
;                               if ((i) < NB) *(u32x4*)(sn_ + STAGE_OP + wofs + (i) * 32 * LROW) = RB[(i) < NB ? (i) : 0]; }
; template <int NJ> DI void gemm_mainloop_reg(const bf16_t* __restrict__ A, int lda, const bf16_t* __restrict__ Bt, int ldb, int K, f32x16 (&acc)[2][NJ], char* lds) {
;     ...
; #pragma unroll
;   for (int i = 0; i < 4; ++i) GL1_(ra0, rb0, i);
;   ap += 128; bp += 128;
; #pragma unroll
;   for (int i = 0; i < 4; ++i) GL1_(ra1, rb1, i);
;   ap += 128; bp += 128;
; #pragma unroll
;   for (int i = 0; i < 4; ++i) LS1_(ra0, rb0, 0, i);
;   __syncthreads();
;   const int nk = K >> 6;
;   for (int kt = 0; kt < nk; kt += 2) {
;     const bool l0 = (kt + 2 < nk), l1 = (kt + 3 < nk);
;     STEP_(0, l0, ra0, rb0, true, ra1, rb1);
;     __syncthreads();
;     STEP_(1, l1, ra1, rb1, l0, ra0, rb0);
;     __syncthreads();
	ds_read_b128 v[94:97], v0 offset:36864
	ds_read_b128 v[98:101], v66 offset:55296
	ds_read_b128 v[110:113], v0 offset:36896
	ds_read_b128 v[114:117], v66 offset:55328
	ds_read_b128 v[118:121], v0 offset:41472
	ds_read_b128 v[122:125], v0 offset:41504
	s_waitcnt lgkmcnt(4)
	v_mfma_f32_32x32x16_bf16 v[34:49], v[94:97], v[98:101], v[34:49]
	s_waitcnt lgkmcnt(1)
	v_mfma_f32_32x32x16_bf16 v[2:17], v[118:121], v[98:101], v[2:17]
	ds_read_b128 v[98:101], v66 offset:59904
	ds_read_b128 v[126:129], v66 offset:59936
	s_waitcnt lgkmcnt(1)
	v_mfma_f32_32x32x16_bf16 v[50:65], v[94:97], v[98:101], v[50:65]
	global_load_dwordx4 v[94:97], v72, s[0:1] offset:2176
	global_load_dwordx4 v[134:137], v72, s[36:37] offset:2176
	s_waitcnt vmcnt(9)
	ds_write_b128 v67, v[74:77]
	s_waitcnt vmcnt(8)
	ds_write_b128 v67, v[130:133] offset:18432
	v_mfma_f32_32x32x16_bf16 v[18:33], v[118:121], v[98:101], v[18:33]
	global_load_dwordx4 v[74:77], v71, s[0:1] offset:2176
	global_load_dwordx4 v[98:101], v71, s[36:37] offset:2176
	v_mfma_f32_32x32x16_bf16 v[2:17], v[122:125], v[114:117], v[2:17]
	s_waitcnt lgkmcnt(2)
	v_mfma_f32_32x32x16_bf16 v[18:33], v[122:125], v[126:129], v[18:33]
	v_mfma_f32_32x32x16_bf16 v[34:49], v[110:113], v[114:117], v[34:49]
	v_mfma_f32_32x32x16_bf16 v[50:65], v[110:113], v[126:129], v[50:65]
	ds_read_b128 v[110:113], v0 offset:36928
	ds_read_b128 v[114:117], v0 offset:41536
	ds_read_b128 v[118:121], v66 offset:55360
	ds_read_b128 v[130:133], v66 offset:59968
	s_waitcnt vmcnt(9)
	ds_write_b128 v67, v[78:81] offset:4608
	s_waitcnt vmcnt(8)
	ds_write_b128 v67, v[102:105] offset:23040
	global_load_dwordx4 v[78:81], v70, s[0:1] offset:2176
	global_load_dwordx4 v[102:105], v70, s[36:37] offset:2176
	s_waitcnt lgkmcnt(3)
	v_mfma_f32_32x32x16_bf16 v[2:17], v[114:117], v[118:121], v[2:17]
	s_waitcnt lgkmcnt(2)
	v_mfma_f32_32x32x16_bf16 v[18:33], v[114:117], v[130:133], v[18:33]
	v_mfma_f32_32x32x16_bf16 v[34:49], v[110:113], v[118:121], v[34:49]
	v_mfma_f32_32x32x16_bf16 v[50:65], v[110:113], v[130:133], v[50:65]
	ds_read_b128 v[110:113], v0 offset:36960
	ds_read_b128 v[118:121], v0 offset:41568
	ds_read_b128 v[122:125], v66 offset:55392
	ds_read_b128 v[126:129], v66 offset:60000
	s_waitcnt vmcnt(9)
	ds_write_b128 v67, v[82:85] offset:9216
	s_waitcnt vmcnt(8)
	ds_write_b128 v67, v[106:109] offset:27648
	global_load_dwordx4 v[82:85], v69, s[0:1] offset:2176
	global_load_dwordx4 v[106:109], v69, s[36:37] offset:2176
	s_waitcnt lgkmcnt(3)
	v_mfma_f32_32x32x16_bf16 v[2:17], v[118:121], v[122:125], v[2:17]
	s_waitcnt vmcnt(9)
	ds_write_b128 v67, v[86:89] offset:13824
	s_waitcnt vmcnt(8)
	ds_write_b128 v67, v[90:93] offset:32256
	s_waitcnt lgkmcnt(4)
	v_mfma_f32_32x32x16_bf16 v[18:33], v[118:121], v[126:129], v[18:33]
	v_mfma_f32_32x32x16_bf16 v[34:49], v[110:113], v[122:125], v[34:49]
	v_mfma_f32_32x32x16_bf16 v[50:65], v[110:113], v[126:129], v[50:65]
	s_waitcnt lgkmcnt(0)
	s_barrier
	ds_read_b128 v[86:89], v0
	ds_read_b128 v[90:93], v66 offset:18432
	ds_read_b128 v[110:113], v0 offset:32
	ds_read_b128 v[114:117], v66 offset:18464
	ds_read_b128 v[118:121], v0 offset:4608
	ds_read_b128 v[122:125], v0 offset:4640
	s_waitcnt lgkmcnt(4)
	v_mfma_f32_32x32x16_bf16 v[34:49], v[86:89], v[90:93], v[34:49]
	s_waitcnt lgkmcnt(1)
	v_mfma_f32_32x32x16_bf16 v[2:17], v[118:121], v[90:93], v[2:17]
	ds_read_b128 v[90:93], v66 offset:23040
	ds_read_b128 v[126:129], v66 offset:23072
	s_waitcnt lgkmcnt(1)
	v_mfma_f32_32x32x16_bf16 v[50:65], v[86:89], v[90:93], v[50:65]
	global_load_dwordx4 v[86:89], v72, s[0:1] offset:2304
	global_load_dwordx4 v[130:133], v72, s[36:37] offset:2304
	s_waitcnt vmcnt(9)
	ds_write_b128 v67, v[94:97] offset:36864
	s_waitcnt vmcnt(8)
	ds_write_b128 v67, v[134:137] offset:55296
	v_mfma_f32_32x32x16_bf16 v[18:33], v[118:121], v[90:93], v[18:33]
	global_load_dwordx4 v[90:93], v71, s[0:1] offset:2304
	global_load_dwordx4 v[94:97], v71, s[36:37] offset:2304
	v_mfma_f32_32x32x16_bf16 v[2:17], v[122:125], v[114:117], v[2:17]
	s_waitcnt lgkmcnt(2)
	v_mfma_f32_32x32x16_bf16 v[18:33], v[122:125], v[126:129], v[18:33]
	v_mfma_f32_32x32x16_bf16 v[34:49], v[110:113], v[114:117], v[34:49]
	v_mfma_f32_32x32x16_bf16 v[50:65], v[110:113], v[126:129], v[50:65]
	ds_read_b128 v[110:113], v0 offset:64
	ds_read_b128 v[114:117], v0 offset:4672
	ds_read_b128 v[118:121], v66 offset:18496
	ds_read_b128 v[134:137], v66 offset:23104
	s_waitcnt vmcnt(9)
	ds_write_b128 v67, v[74:77] offset:41472
	s_waitcnt vmcnt(8)
	ds_write_b128 v67, v[98:101] offset:59904
	global_load_dwordx4 v[74:77], v70, s[0:1] offset:2304
	global_load_dwordx4 v[98:101], v70, s[36:37] offset:2304
	s_waitcnt lgkmcnt(3)
	v_mfma_f32_32x32x16_bf16 v[2:17], v[114:117], v[118:121], v[2:17]
	s_waitcnt lgkmcnt(2)
	v_mfma_f32_32x32x16_bf16 v[18:33], v[114:117], v[134:137], v[18:33]
	v_mfma_f32_32x32x16_bf16 v[34:49], v[110:113], v[118:121], v[34:49]
	v_mfma_f32_32x32x16_bf16 v[50:65], v[110:113], v[134:137], v[50:65]
	ds_read_b128 v[110:113], v0 offset:96
	ds_read_b128 v[118:121], v0 offset:4704
	ds_read_b128 v[122:125], v66 offset:18528
	ds_read_b128 v[126:129], v66 offset:23136
	s_waitcnt vmcnt(9)
	ds_write_b128 v67, v[78:81] offset:46080
	s_waitcnt vmcnt(8)
	ds_write_b128 v67, v[102:105] offset:64512
	global_load_dwordx4 v[78:81], v69, s[0:1] offset:2304
	global_load_dwordx4 v[102:105], v69, s[36:37] offset:2304
	s_waitcnt lgkmcnt(3)
	v_mfma_f32_32x32x16_bf16 v[2:17], v[118:121], v[122:125], v[2:17]
	s_waitcnt vmcnt(9)
	ds_write_b128 v67, v[82:85] offset:50688
	s_waitcnt vmcnt(8)
	ds_write_b128 v68, v[106:109] offset:13824
	s_waitcnt lgkmcnt(4)
	v_mfma_f32_32x32x16_bf16 v[18:33], v[118:121], v[126:129], v[18:33]
	v_mfma_f32_32x32x16_bf16 v[34:49], v[110:113], v[122:125], v[34:49]
	v_mfma_f32_32x32x16_bf16 v[50:65], v[110:113], v[126:129], v[50:65]
	s_waitcnt lgkmcnt(0)
	s_barrier
; #define GL1_(RA, RB, i) { RA[i] = *(const u32x4*)(ap + (aoff + (i) * astep)); if ((i) < NB) RB[(i) < NB ? (i) : 0] = *(const u32x4*)(bp + (boff + (i) * bstep)); }
; #define LS1_(RA, RB, ST, i) { char* sn_ = lds + (ST) * STAGE; *(u32x4*)(sn_ + wofs + (i) * 32 * LROW) = RA[i]; \
;                               if ((i) < NB) *(u32x4*)(sn_ + STAGE_OP + wofs + (i) * 32 * LROW) = RB[(i) < NB ? (i) : 0]; }
; template <int NJ> DI void gemm_mainloop_reg(const bf16_t* __restrict__ A, int lda, const bf16_t* __restrict__ Bt, int ldb, int K, f32x16 (&acc)[2][NJ], char* lds) {
;     ...
; #pragma unroll
;   for (int i = 0; i < 4; ++i) GL1_(ra0, rb0, i);
;   ap += 128; bp += 128;
; #pragma unroll
;   for (int i = 0; i < 4; ++i) GL1_(ra1, rb1, i);
;   ap += 128; bp += 128;
; #pragma unroll
;   for (int i = 0; i < 4; ++i) LS1_(ra0, rb0, 0, i);
;   __syncthreads();
;   const int nk = K >> 6;
;   for (int kt = 0; kt < nk; kt += 2) {
;     const bool l0 = (kt + 2 < nk), l1 = (kt + 3 < nk);
;     STEP_(0, l0, ra0, rb0, true, ra1, rb1);
;     __syncthreads();
;     STEP_(1, l1, ra1, rb1, l0, ra0, rb0);
;     __syncthreads();
	ds_read_b128 v[82:85], v0 offset:36864
	ds_read_b128 v[106:109], v66 offset:55296
	ds_read_b128 v[110:113], v0 offset:36896
	ds_read_b128 v[114:117], v66 offset:55328
	ds_read_b128 v[118:121], v0 offset:41472
	ds_read_b128 v[122:125], v0 offset:41504
	s_waitcnt lgkmcnt(4)
	v_mfma_f32_32x32x16_bf16 v[34:49], v[82:85], v[106:109], v[34:49]
	s_waitcnt lgkmcnt(1)
	v_mfma_f32_32x32x16_bf16 v[2:17], v[118:121], v[106:109], v[2:17]
	ds_read_b128 v[106:109], v66 offset:59904
	ds_read_b128 v[126:129], v66 offset:59936
	s_waitcnt lgkmcnt(1)
	v_mfma_f32_32x32x16_bf16 v[50:65], v[82:85], v[106:109], v[50:65]
	global_load_dwordx4 v[82:85], v72, s[0:1] offset:2432
	global_load_dwordx4 v[134:137], v72, s[36:37] offset:2432
	s_waitcnt vmcnt(9)
	ds_write_b128 v67, v[86:89]
	s_waitcnt vmcnt(8)
	ds_write_b128 v67, v[130:133] offset:18432
	v_mfma_f32_32x32x16_bf16 v[18:33], v[118:121], v[106:109], v[18:33]
	global_load_dwordx4 v[86:89], v71, s[0:1] offset:2432
	global_load_dwordx4 v[106:109], v71, s[36:37] offset:2432
	v_mfma_f32_32x32x16_bf16 v[2:17], v[122:125], v[114:117], v[2:17]
	s_waitcnt lgkmcnt(2)
	v_mfma_f32_32x32x16_bf16 v[18:33], v[122:125], v[126:129], v[18:33]
	v_mfma_f32_32x32x16_bf16 v[34:49], v[110:113], v[114:117], v[34:49]
	v_mfma_f32_32x32x16_bf16 v[50:65], v[110:113], v[126:129], v[50:65]
	ds_read_b128 v[110:113], v0 offset:36928
	ds_read_b128 v[114:117], v0 offset:41536
	ds_read_b128 v[118:121], v66 offset:55360
	ds_read_b128 v[130:133], v66 offset:59968
	s_waitcnt vmcnt(9)
	ds_write_b128 v67, v[90:93] offset:4608
	s_waitcnt vmcnt(8)
	ds_write_b128 v67, v[94:97] offset:23040
	global_load_dwordx4 v[90:93], v70, s[0:1] offset:2432
	global_load_dwordx4 v[94:97], v70, s[36:37] offset:2432
	s_waitcnt lgkmcnt(3)
	v_mfma_f32_32x32x16_bf16 v[2:17], v[114:117], v[118:121], v[2:17]
	s_waitcnt lgkmcnt(2)
	v_mfma_f32_32x32x16_bf16 v[18:33], v[114:117], v[130:133], v[18:33]
	v_mfma_f32_32x32x16_bf16 v[34:49], v[110:113], v[118:121], v[34:49]
	v_mfma_f32_32x32x16_bf16 v[50:65], v[110:113], v[130:133], v[50:65]
	ds_read_b128 v[110:113], v0 offset:36960
	ds_read_b128 v[118:121], v0 offset:41568
	ds_read_b128 v[122:125], v66 offset:55392
	ds_read_b128 v[126:129], v66 offset:60000
	s_waitcnt vmcnt(9)
	ds_write_b128 v67, v[74:77] offset:9216
	s_waitcnt vmcnt(8)
	ds_write_b128 v67, v[98:101] offset:27648
	global_load_dwordx4 v[74:77], v69, s[0:1] offset:2432
	global_load_dwordx4 v[98:101], v69, s[36:37] offset:2432
	s_waitcnt lgkmcnt(3)
	v_mfma_f32_32x32x16_bf16 v[2:17], v[118:121], v[122:125], v[2:17]
	s_waitcnt vmcnt(9)
	ds_write_b128 v67, v[78:81] offset:13824
	s_waitcnt vmcnt(8)
	ds_write_b128 v67, v[102:105] offset:32256
	s_waitcnt lgkmcnt(4)
	v_mfma_f32_32x32x16_bf16 v[18:33], v[118:121], v[126:129], v[18:33]
	v_mfma_f32_32x32x16_bf16 v[34:49], v[110:113], v[122:125], v[34:49]
	v_mfma_f32_32x32x16_bf16 v[50:65], v[110:113], v[126:129], v[50:65]
	s_waitcnt lgkmcnt(0)
	s_barrier
	ds_read_b128 v[78:81], v0
	ds_read_b128 v[102:105], v66 offset:18432
	ds_read_b128 v[110:113], v0 offset:32
	ds_read_b128 v[114:117], v66 offset:18464
	ds_read_b128 v[118:121], v0 offset:4608
	ds_read_b128 v[122:125], v0 offset:4640
	s_waitcnt lgkmcnt(4)
	v_mfma_f32_32x32x16_bf16 v[34:49], v[78:81], v[102:105], v[34:49]
	s_waitcnt lgkmcnt(1)
	v_mfma_f32_32x32x16_bf16 v[2:17], v[118:121], v[102:105], v[2:17]
	ds_read_b128 v[102:105], v66 offset:23040
	ds_read_b128 v[126:129], v66 offset:23072
	s_waitcnt lgkmcnt(1)
	v_mfma_f32_32x32x16_bf16 v[50:65], v[78:81], v[102:105], v[50:65]
	global_load_dwordx4 v[78:81], v72, s[0:1] offset:2560
	global_load_dwordx4 v[130:133], v72, s[36:37] offset:2560
	s_waitcnt vmcnt(9)
	ds_write_b128 v67, v[82:85] offset:36864
	s_waitcnt vmcnt(8)
	ds_write_b128 v67, v[134:137] offset:55296
	v_mfma_f32_32x32x16_bf16 v[18:33], v[118:121], v[102:105], v[18:33]
	global_load_dwordx4 v[82:85], v71, s[0:1] offset:2560
	global_load_dwordx4 v[102:105], v71, s[36:37] offset:2560
	v_mfma_f32_32x32x16_bf16 v[2:17], v[122:125], v[114:117], v[2:17]
	s_waitcnt lgkmcnt(2)
	v_mfma_f32_32x32x16_bf16 v[18:33], v[122:125], v[126:129], v[18:33]
	v_mfma_f32_32x32x16_bf16 v[34:49], v[110:113], v[114:117], v[34:49]
	v_mfma_f32_32x32x16_bf16 v[50:65], v[110:113], v[126:129], v[50:65]
	ds_read_b128 v[110:113], v0 offset:64
	ds_read_b128 v[114:117], v0 offset:4672
	ds_read_b128 v[118:121], v66 offset:18496
	ds_read_b128 v[134:137], v66 offset:23104
	s_waitcnt vmcnt(9)
	ds_write_b128 v67, v[86:89] offset:41472
	s_waitcnt vmcnt(8)
	ds_write_b128 v67, v[106:109] offset:59904
	global_load_dwordx4 v[86:89], v70, s[0:1] offset:2560
	global_load_dwordx4 v[106:109], v70, s[36:37] offset:2560
	s_waitcnt lgkmcnt(3)
	v_mfma_f32_32x32x16_bf16 v[2:17], v[114:117], v[118:121], v[2:17]
	s_waitcnt lgkmcnt(2)
	v_mfma_f32_32x32x16_bf16 v[18:33], v[114:117], v[134:137], v[18:33]
	v_mfma_f32_32x32x16_bf16 v[34:49], v[110:113], v[118:121], v[34:49]
	v_mfma_f32_32x32x16_bf16 v[50:65], v[110:113], v[134:137], v[50:65]
	ds_read_b128 v[110:113], v0 offset:96
	ds_read_b128 v[118:121], v0 offset:4704
	ds_read_b128 v[122:125], v66 offset:18528
	ds_read_b128 v[126:129], v66 offset:23136
	s_waitcnt vmcnt(9)
	ds_write_b128 v67, v[90:93] offset:46080
	s_waitcnt vmcnt(8)
	ds_write_b128 v67, v[94:97] offset:64512
	global_load_dwordx4 v[90:93], v69, s[0:1] offset:2560
	global_load_dwordx4 v[94:97], v69, s[36:37] offset:2560
	s_waitcnt lgkmcnt(3)
	v_mfma_f32_32x32x16_bf16 v[2:17], v[118:121], v[122:125], v[2:17]
	s_waitcnt vmcnt(9)
	ds_write_b128 v67, v[74:77] offset:50688
	s_waitcnt vmcnt(8)
	ds_write_b128 v68, v[98:101] offset:13824
	s_waitcnt lgkmcnt(4)
	v_mfma_f32_32x32x16_bf16 v[18:33], v[118:121], v[126:129], v[18:33]
	v_mfma_f32_32x32x16_bf16 v[34:49], v[110:113], v[122:125], v[34:49]
	v_mfma_f32_32x32x16_bf16 v[50:65], v[110:113], v[126:129], v[50:65]
	s_waitcnt lgkmcnt(0)
	s_barrier
; #define GL1_(RA, RB, i) { RA[i] = *(const u32x4*)(ap + (aoff + (i) * astep)); if ((i) < NB) RB[(i) < NB ? (i) : 0] = *(const u32x4*)(bp + (boff + (i) * bstep)); }
; #define LS1_(RA, RB, ST, i) { char* sn_ = lds + (ST) * STAGE; *(u32x4*)(sn_ + wofs + (i) * 32 * LROW) = RA[i]; \
;                               if ((i) < NB) *(u32x4*)(sn_ + STAGE_OP + wofs + (i) * 32 * LROW) = RB[(i) < NB ? (i) : 0]; }
; template <int NJ> DI void gemm_mainloop_reg(const bf16_t* __restrict__ A, int lda, const bf16_t* __restrict__ Bt, int ldb, int K, f32x16 (&acc)[2][NJ], char* lds) {
;     ...
; #pragma unroll
;   for (int i = 0; i < 4; ++i) GL1_(ra0, rb0, i);
;   ap += 128; bp += 128;
; #pragma unroll
;   for (int i = 0; i < 4; ++i) GL1_(ra1, rb1, i);
;   ap += 128; bp += 128;
; #pragma unroll
;   for (int i = 0; i < 4; ++i) LS1_(ra0, rb0, 0, i);
;   __syncthreads();
;   const int nk = K >> 6;
;   for (int kt = 0; kt < nk; kt += 2) {
;     const bool l0 = (kt + 2 < nk), l1 = (kt + 3 < nk);
;     STEP_(0, l0, ra0, rb0, true, ra1, rb1);
;     __syncthreads();
;     STEP_(1, l1, ra1, rb1, l0, ra0, rb0);
;     __syncthreads();
	ds_read_b128 v[74:77], v0 offset:36864
	ds_read_b128 v[98:101], v66 offset:55296
	ds_read_b128 v[110:113], v0 offset:36896
	ds_read_b128 v[114:117], v66 offset:55328
	ds_read_b128 v[118:121], v0 offset:41472
	ds_read_b128 v[122:125], v0 offset:41504
	s_waitcnt lgkmcnt(4)
	v_mfma_f32_32x32x16_bf16 v[34:49], v[74:77], v[98:101], v[34:49]
	s_waitcnt lgkmcnt(1)
	v_mfma_f32_32x32x16_bf16 v[2:17], v[118:121], v[98:101], v[2:17]
	ds_read_b128 v[98:101], v66 offset:59904
	ds_read_b128 v[126:129], v66 offset:59936
	s_waitcnt lgkmcnt(1)
	v_mfma_f32_32x32x16_bf16 v[50:65], v[74:77], v[98:101], v[50:65]
	global_load_dwordx4 v[74:77], v72, s[0:1] offset:2688
	global_load_dwordx4 v[134:137], v72, s[36:37] offset:2688
	s_waitcnt vmcnt(9)
	ds_write_b128 v67, v[78:81]
	s_waitcnt vmcnt(8)
	ds_write_b128 v67, v[130:133] offset:18432
	v_mfma_f32_32x32x16_bf16 v[18:33], v[118:121], v[98:101], v[18:33]
	global_load_dwordx4 v[78:81], v71, s[0:1] offset:2688
	global_load_dwordx4 v[98:101], v71, s[36:37] offset:2688
	v_mfma_f32_32x32x16_bf16 v[2:17], v[122:125], v[114:117], v[2:17]
	s_waitcnt lgkmcnt(2)
	v_mfma_f32_32x32x16_bf16 v[18:33], v[122:125], v[126:129], v[18:33]
	v_mfma_f32_32x32x16_bf16 v[34:49], v[110:113], v[114:117], v[34:49]
	v_mfma_f32_32x32x16_bf16 v[50:65], v[110:113], v[126:129], v[50:65]
	ds_read_b128 v[110:113], v0 offset:36928
	ds_read_b128 v[114:117], v0 offset:41536
	ds_read_b128 v[118:121], v66 offset:55360
	ds_read_b128 v[130:133], v66 offset:59968
	s_waitcnt vmcnt(9)
	ds_write_b128 v67, v[82:85] offset:4608
	s_waitcnt vmcnt(8)
	ds_write_b128 v67, v[102:105] offset:23040
	global_load_dwordx4 v[82:85], v70, s[0:1] offset:2688
	global_load_dwordx4 v[102:105], v70, s[36:37] offset:2688
	s_waitcnt lgkmcnt(3)
	v_mfma_f32_32x32x16_bf16 v[2:17], v[114:117], v[118:121], v[2:17]
	s_waitcnt lgkmcnt(2)
	v_mfma_f32_32x32x16_bf16 v[18:33], v[114:117], v[130:133], v[18:33]
	v_mfma_f32_32x32x16_bf16 v[34:49], v[110:113], v[118:121], v[34:49]
	v_mfma_f32_32x32x16_bf16 v[50:65], v[110:113], v[130:133], v[50:65]
	ds_read_b128 v[110:113], v0 offset:36960
	ds_read_b128 v[118:121], v0 offset:41568
	ds_read_b128 v[122:125], v66 offset:55392
	ds_read_b128 v[126:129], v66 offset:60000
	s_waitcnt vmcnt(9)
	ds_write_b128 v67, v[86:89] offset:9216
	s_waitcnt vmcnt(8)
	ds_write_b128 v67, v[106:109] offset:27648
	global_load_dwordx4 v[86:89], v69, s[0:1] offset:2688
	global_load_dwordx4 v[106:109], v69, s[36:37] offset:2688
	s_waitcnt lgkmcnt(3)
	v_mfma_f32_32x32x16_bf16 v[2:17], v[118:121], v[122:125], v[2:17]
	s_waitcnt vmcnt(9)
	ds_write_b128 v67, v[90:93] offset:13824
	s_waitcnt vmcnt(8)
	ds_write_b128 v67, v[94:97] offset:32256
	s_waitcnt lgkmcnt(4)
	v_mfma_f32_32x32x16_bf16 v[18:33], v[118:121], v[126:129], v[18:33]
	v_mfma_f32_32x32x16_bf16 v[34:49], v[110:113], v[122:125], v[34:49]
	v_mfma_f32_32x32x16_bf16 v[50:65], v[110:113], v[126:129], v[50:65]
	s_waitcnt lgkmcnt(0)
	s_barrier
	ds_read_b128 v[90:93], v0
	ds_read_b128 v[94:97], v66 offset:18432
	ds_read_b128 v[110:113], v0 offset:32
	ds_read_b128 v[114:117], v66 offset:18464
	ds_read_b128 v[118:121], v0 offset:4608
	ds_read_b128 v[122:125], v0 offset:4640
	s_waitcnt lgkmcnt(4)
	v_mfma_f32_32x32x16_bf16 v[34:49], v[90:93], v[94:97], v[34:49]
	s_waitcnt lgkmcnt(1)
	v_mfma_f32_32x32x16_bf16 v[2:17], v[118:121], v[94:97], v[2:17]
	ds_read_b128 v[94:97], v66 offset:23040
	ds_read_b128 v[126:129], v66 offset:23072
	s_waitcnt lgkmcnt(1)
	v_mfma_f32_32x32x16_bf16 v[50:65], v[90:93], v[94:97], v[50:65]
	global_load_dwordx4 v[90:93], v72, s[0:1] offset:2816
	global_load_dwordx4 v[130:133], v72, s[36:37] offset:2816
	s_waitcnt vmcnt(9)
	ds_write_b128 v67, v[74:77] offset:36864
	s_waitcnt vmcnt(8)
	ds_write_b128 v67, v[134:137] offset:55296
	v_mfma_f32_32x32x16_bf16 v[18:33], v[118:121], v[94:97], v[18:33]
	global_load_dwordx4 v[74:77], v71, s[0:1] offset:2816
	global_load_dwordx4 v[94:97], v71, s[36:37] offset:2816
	v_mfma_f32_32x32x16_bf16 v[2:17], v[122:125], v[114:117], v[2:17]
	s_waitcnt lgkmcnt(2)
	v_mfma_f32_32x32x16_bf16 v[18:33], v[122:125], v[126:129], v[18:33]
	v_mfma_f32_32x32x16_bf16 v[34:49], v[110:113], v[114:117], v[34:49]
	v_mfma_f32_32x32x16_bf16 v[50:65], v[110:113], v[126:129], v[50:65]
	ds_read_b128 v[110:113], v0 offset:64
	ds_read_b128 v[114:117], v0 offset:4672
	ds_read_b128 v[118:121], v66 offset:18496
	ds_read_b128 v[134:137], v66 offset:23104
	s_waitcnt vmcnt(9)
	ds_write_b128 v67, v[78:81] offset:41472
	s_waitcnt vmcnt(8)
	ds_write_b128 v67, v[98:101] offset:59904
	global_load_dwordx4 v[78:81], v70, s[0:1] offset:2816
	global_load_dwordx4 v[98:101], v70, s[36:37] offset:2816
	s_waitcnt lgkmcnt(3)
	v_mfma_f32_32x32x16_bf16 v[2:17], v[114:117], v[118:121], v[2:17]
	s_waitcnt lgkmcnt(2)
	v_mfma_f32_32x32x16_bf16 v[18:33], v[114:117], v[134:137], v[18:33]
	v_mfma_f32_32x32x16_bf16 v[34:49], v[110:113], v[118:121], v[34:49]
	v_mfma_f32_32x32x16_bf16 v[50:65], v[110:113], v[134:137], v[50:65]
	ds_read_b128 v[110:113], v0 offset:96
	ds_read_b128 v[118:121], v0 offset:4704
	ds_read_b128 v[122:125], v66 offset:18528
	ds_read_b128 v[126:129], v66 offset:23136
	s_waitcnt vmcnt(9)
	ds_write_b128 v67, v[82:85] offset:46080
	s_waitcnt vmcnt(8)
	ds_write_b128 v67, v[102:105] offset:64512
	global_load_dwordx4 v[82:85], v69, s[0:1] offset:2816
	global_load_dwordx4 v[102:105], v69, s[36:37] offset:2816
	s_waitcnt lgkmcnt(3)
	v_mfma_f32_32x32x16_bf16 v[2:17], v[118:121], v[122:125], v[2:17]
	s_waitcnt vmcnt(9)
	ds_write_b128 v67, v[86:89] offset:50688
	s_waitcnt vmcnt(8)
	ds_write_b128 v68, v[106:109] offset:13824
	s_waitcnt lgkmcnt(4)
	v_mfma_f32_32x32x16_bf16 v[18:33], v[118:121], v[126:129], v[18:33]
	v_mfma_f32_32x32x16_bf16 v[34:49], v[110:113], v[122:125], v[34:49]
	v_mfma_f32_32x32x16_bf16 v[50:65], v[110:113], v[126:129], v[50:65]
	s_waitcnt lgkmcnt(0)
	s_barrier
; #define GL1_(RA, RB, i) { RA[i] = *(const u32x4*)(ap + (aoff + (i) * astep)); if ((i) < NB) RB[(i) < NB ? (i) : 0] = *(const u32x4*)(bp + (boff + (i) * bstep)); }
; #define LS1_(RA, RB, ST, i) { char* sn_ = lds + (ST) * STAGE; *(u32x4*)(sn_ + wofs + (i) * 32 * LROW) = RA[i]; \
;                               if ((i) < NB) *(u32x4*)(sn_ + STAGE_OP + wofs + (i) * 32 * LROW) = RB[(i) < NB ? (i) : 0]; }
; template <int NJ> DI void gemm_mainloop_reg(const bf16_t* __restrict__ A, int lda, const bf16_t* __restrict__ Bt, int ldb, int K, f32x16 (&acc)[2][NJ], char* lds) {
;     ...
; #pragma unroll
;   for (int i = 0; i < 4; ++i) GL1_(ra0, rb0, i);
;   ap += 128; bp += 128;
; #pragma unroll
;   for (int i = 0; i < 4; ++i) GL1_(ra1, rb1, i);
;   ap += 128; bp += 128;
; #pragma unroll
;   for (int i = 0; i < 4; ++i) LS1_(ra0, rb0, 0, i);
;   __syncthreads();
;   const int nk = K >> 6;
;   for (int kt = 0; kt < nk; kt += 2) {
;     const bool l0 = (kt + 2 < nk), l1 = (kt + 3 < nk);
;     STEP_(0, l0, ra0, rb0, true, ra1, rb1);
;     __syncthreads();
;     STEP_(1, l1, ra1, rb1, l0, ra0, rb0);
;     __syncthreads();
;   }
	ds_read_b128 v[86:89], v0 offset:36864
	ds_read_b128 v[106:109], v66 offset:55296
	ds_read_b128 v[110:113], v0 offset:36896
	ds_read_b128 v[114:117], v66 offset:55328
	ds_read_b128 v[118:121], v0 offset:41472
	ds_read_b128 v[122:125], v0 offset:41504
	s_waitcnt lgkmcnt(4)
	v_mfma_f32_32x32x16_bf16 v[34:49], v[86:89], v[106:109], v[34:49]
	s_waitcnt lgkmcnt(1)
	v_mfma_f32_32x32x16_bf16 v[2:17], v[118:121], v[106:109], v[2:17]
	ds_read_b128 v[106:109], v66 offset:59904
	ds_read_b128 v[126:129], v66 offset:59936
	s_waitcnt lgkmcnt(1)
	v_mfma_f32_32x32x16_bf16 v[50:65], v[86:89], v[106:109], v[50:65]
	global_load_dwordx4 v[86:89], v72, s[0:1] offset:2944
	global_load_dwordx4 v[134:137], v72, s[36:37] offset:2944
	s_waitcnt vmcnt(9)
	ds_write_b128 v67, v[90:93]
	s_waitcnt vmcnt(8)
	ds_write_b128 v67, v[130:133] offset:18432
	v_mfma_f32_32x32x16_bf16 v[18:33], v[118:121], v[106:109], v[18:33]
	global_load_dwordx4 v[90:93], v71, s[0:1] offset:2944
	global_load_dwordx4 v[106:109], v71, s[36:37] offset:2944
	v_mfma_f32_32x32x16_bf16 v[2:17], v[122:125], v[114:117], v[2:17]
	s_waitcnt lgkmcnt(2)
	v_mfma_f32_32x32x16_bf16 v[18:33], v[122:125], v[126:129], v[18:33]
	v_mfma_f32_32x32x16_bf16 v[34:49], v[110:113], v[114:117], v[34:49]
	v_mfma_f32_32x32x16_bf16 v[50:65], v[110:113], v[126:129], v[50:65]
	ds_read_b128 v[110:113], v0 offset:36928
	ds_read_b128 v[114:117], v0 offset:41536
	ds_read_b128 v[118:121], v66 offset:55360
	ds_read_b128 v[130:133], v66 offset:59968
	s_waitcnt vmcnt(9)
	ds_write_b128 v67, v[74:77] offset:4608
	s_waitcnt vmcnt(8)
	ds_write_b128 v67, v[94:97] offset:23040
	global_load_dwordx4 v[74:77], v70, s[0:1] offset:2944
	global_load_dwordx4 v[94:97], v70, s[36:37] offset:2944
	s_waitcnt lgkmcnt(3)
	v_mfma_f32_32x32x16_bf16 v[2:17], v[114:117], v[118:121], v[2:17]
	s_waitcnt lgkmcnt(2)
	v_mfma_f32_32x32x16_bf16 v[18:33], v[114:117], v[130:133], v[18:33]
	v_mfma_f32_32x32x16_bf16 v[34:49], v[110:113], v[118:121], v[34:49]
	v_mfma_f32_32x32x16_bf16 v[50:65], v[110:113], v[130:133], v[50:65]
	ds_read_b128 v[110:113], v0 offset:36960
	ds_read_b128 v[118:121], v0 offset:41568
	ds_read_b128 v[122:125], v66 offset:55392
	ds_read_b128 v[126:129], v66 offset:60000
	s_waitcnt vmcnt(9)
	ds_write_b128 v67, v[78:81] offset:9216
	s_waitcnt vmcnt(8)
	ds_write_b128 v67, v[98:101] offset:27648
	global_load_dwordx4 v[78:81], v69, s[0:1] offset:2944
	global_load_dwordx4 v[98:101], v69, s[36:37] offset:2944
	s_waitcnt lgkmcnt(3)
	v_mfma_f32_32x32x16_bf16 v[2:17], v[118:121], v[122:125], v[2:17]
	s_waitcnt vmcnt(9)
	ds_write_b128 v67, v[82:85] offset:13824
	s_waitcnt vmcnt(8)
	ds_write_b128 v67, v[102:105] offset:32256
	s_waitcnt lgkmcnt(4)
	v_mfma_f32_32x32x16_bf16 v[18:33], v[118:121], v[126:129], v[18:33]
	v_mfma_f32_32x32x16_bf16 v[34:49], v[110:113], v[122:125], v[34:49]
	v_mfma_f32_32x32x16_bf16 v[50:65], v[110:113], v[126:129], v[50:65]
	s_waitcnt lgkmcnt(0)
	s_barrier
	ds_read_b128 v[82:85], v0
	ds_read_b128 v[102:105], v66 offset:18432
	ds_read_b128 v[110:113], v0 offset:32
	ds_read_b128 v[114:117], v66 offset:18464
	ds_read_b128 v[118:121], v0 offset:4608
	ds_read_b128 v[122:125], v0 offset:4640
	s_waitcnt lgkmcnt(4)
	v_mfma_f32_32x32x16_bf16 v[34:49], v[82:85], v[102:105], v[34:49]
	s_waitcnt lgkmcnt(1)
	v_mfma_f32_32x32x16_bf16 v[2:17], v[118:121], v[102:105], v[2:17]
	ds_read_b128 v[102:105], v66 offset:23040
	ds_read_b128 v[126:129], v66 offset:23072
	s_waitcnt lgkmcnt(1)
	v_mfma_f32_32x32x16_bf16 v[50:65], v[82:85], v[102:105], v[50:65]
	global_load_dwordx4 v[82:85], v72, s[0:1] offset:3072
	global_load_dwordx4 v[130:133], v72, s[36:37] offset:3072
	s_waitcnt vmcnt(9)
	ds_write_b128 v67, v[86:89] offset:36864
	s_waitcnt vmcnt(8)
	ds_write_b128 v67, v[134:137] offset:55296
	v_mfma_f32_32x32x16_bf16 v[18:33], v[118:121], v[102:105], v[18:33]
	global_load_dwordx4 v[86:89], v71, s[0:1] offset:3072
	global_load_dwordx4 v[102:105], v71, s[36:37] offset:3072
	v_mfma_f32_32x32x16_bf16 v[2:17], v[122:125], v[114:117], v[2:17]
	s_waitcnt lgkmcnt(2)
	v_mfma_f32_32x32x16_bf16 v[18:33], v[122:125], v[126:129], v[18:33]
	v_mfma_f32_32x32x16_bf16 v[34:49], v[110:113], v[114:117], v[34:49]
	v_mfma_f32_32x32x16_bf16 v[50:65], v[110:113], v[126:129], v[50:65]
	ds_read_b128 v[110:113], v0 offset:64
	ds_read_b128 v[114:117], v0 offset:4672
	ds_read_b128 v[118:121], v66 offset:18496
	ds_read_b128 v[134:137], v66 offset:23104
	s_waitcnt vmcnt(9)
	ds_write_b128 v67, v[90:93] offset:41472
	s_waitcnt vmcnt(8)
	ds_write_b128 v67, v[106:109] offset:59904
	global_load_dwordx4 v[90:93], v70, s[0:1] offset:3072
	global_load_dwordx4 v[106:109], v70, s[36:37] offset:3072
	s_waitcnt lgkmcnt(3)
	v_mfma_f32_32x32x16_bf16 v[2:17], v[114:117], v[118:121], v[2:17]
	s_waitcnt lgkmcnt(2)
	v_mfma_f32_32x32x16_bf16 v[18:33], v[114:117], v[134:137], v[18:33]
	v_mfma_f32_32x32x16_bf16 v[34:49], v[110:113], v[118:121], v[34:49]
	v_mfma_f32_32x32x16_bf16 v[50:65], v[110:113], v[134:137], v[50:65]
	ds_read_b128 v[110:113], v0 offset:96
	ds_read_b128 v[118:121], v0 offset:4704
	ds_read_b128 v[122:125], v66 offset:18528
	ds_read_b128 v[126:129], v66 offset:23136
	s_waitcnt vmcnt(9)
	ds_write_b128 v67, v[74:77] offset:46080
	s_waitcnt vmcnt(8)
	ds_write_b128 v67, v[94:97] offset:64512
	global_load_dwordx4 v[74:77], v69, s[0:1] offset:3072
	global_load_dwordx4 v[94:97], v69, s[36:37] offset:3072
	s_waitcnt lgkmcnt(3)
	v_mfma_f32_32x32x16_bf16 v[2:17], v[118:121], v[122:125], v[2:17]
	s_waitcnt vmcnt(9)
	ds_write_b128 v67, v[78:81] offset:50688
	s_waitcnt vmcnt(8)
	ds_write_b128 v68, v[98:101] offset:13824
	s_waitcnt lgkmcnt(4)
	v_mfma_f32_32x32x16_bf16 v[18:33], v[118:121], v[126:129], v[18:33]
	v_mfma_f32_32x32x16_bf16 v[34:49], v[110:113], v[122:125], v[34:49]
	v_mfma_f32_32x32x16_bf16 v[50:65], v[110:113], v[126:129], v[50:65]
	s_waitcnt lgkmcnt(0)
	s_barrier
; #define GL1_(RA, RB, i) { RA[i] = *(const u32x4*)(ap + (aoff + (i) * astep)); if ((i) < NB) RB[(i) < NB ? (i) : 0] = *(const u32x4*)(bp + (boff + (i) * bstep)); }
; #define LS1_(RA, RB, ST, i) { char* sn_ = lds + (ST) * STAGE; *(u32x4*)(sn_ + wofs + (i) * 32 * LROW) = RA[i]; \
;                               if ((i) < NB) *(u32x4*)(sn_ + STAGE_OP + wofs + (i) * 32 * LROW) = RB[(i) < NB ? (i) : 0]; }
; template <int NJ> DI void gemm_mainloop_reg(const bf16_t* __restrict__ A, int lda, const bf16_t* __restrict__ Bt, int ldb, int K, f32x16 (&acc)[2][NJ], char* lds) {
;     ...
; #pragma unroll
;   for (int i = 0; i < 4; ++i) GL1_(ra0, rb0, i);
;   ap += 128; bp += 128;
; #pragma unroll
;   for (int i = 0; i < 4; ++i) GL1_(ra1, rb1, i);
;   ap += 128; bp += 128;
; #pragma unroll
;   for (int i = 0; i < 4; ++i) LS1_(ra0, rb0, 0, i);
;   __syncthreads();
;   const int nk = K >> 6;
;   for (int kt = 0; kt < nk; kt += 2) {
;     const bool l0 = (kt + 2 < nk), l1 = (kt + 3 < nk);
;     STEP_(0, l0, ra0, rb0, true, ra1, rb1);
;     __syncthreads();
;     STEP_(1, l1, ra1, rb1, l0, ra0, rb0);
;     __syncthreads();
;   }
	ds_read_b128 v[78:81], v0 offset:36864
	ds_read_b128 v[98:101], v66 offset:55296
	ds_read_b128 v[110:113], v0 offset:36896
	ds_read_b128 v[114:117], v66 offset:55328
	ds_read_b128 v[118:121], v0 offset:41472
	ds_read_b128 v[122:125], v0 offset:41504
	s_waitcnt lgkmcnt(4)
	v_mfma_f32_32x32x16_bf16 v[34:49], v[78:81], v[98:101], v[34:49]
	s_waitcnt lgkmcnt(1)
	v_mfma_f32_32x32x16_bf16 v[2:17], v[118:121], v[98:101], v[2:17]
	ds_read_b128 v[98:101], v66 offset:59904
	ds_read_b128 v[126:129], v66 offset:59936
	s_waitcnt lgkmcnt(1)
	v_mfma_f32_32x32x16_bf16 v[50:65], v[78:81], v[98:101], v[50:65]
	global_load_dwordx4 v[78:81], v72, s[0:1] offset:3200
	global_load_dwordx4 v[134:137], v72, s[36:37] offset:3200
	s_waitcnt vmcnt(9)
	ds_write_b128 v67, v[82:85]
	s_waitcnt vmcnt(8)
	ds_write_b128 v67, v[130:133] offset:18432
	v_mfma_f32_32x32x16_bf16 v[18:33], v[118:121], v[98:101], v[18:33]
	global_load_dwordx4 v[82:85], v71, s[0:1] offset:3200
	global_load_dwordx4 v[98:101], v71, s[36:37] offset:3200
	v_mfma_f32_32x32x16_bf16 v[2:17], v[122:125], v[114:117], v[2:17]
	s_waitcnt lgkmcnt(2)
	v_mfma_f32_32x32x16_bf16 v[18:33], v[122:125], v[126:129], v[18:33]
	v_mfma_f32_32x32x16_bf16 v[34:49], v[110:113], v[114:117], v[34:49]
	v_mfma_f32_32x32x16_bf16 v[50:65], v[110:113], v[126:129], v[50:65]
	ds_read_b128 v[110:113], v0 offset:36928
	ds_read_b128 v[114:117], v0 offset:41536
	ds_read_b128 v[118:121], v66 offset:55360
	ds_read_b128 v[130:133], v66 offset:59968
	s_waitcnt vmcnt(9)
	ds_write_b128 v67, v[86:89] offset:4608
	s_waitcnt vmcnt(8)
	ds_write_b128 v67, v[102:105] offset:23040
	global_load_dwordx4 v[86:89], v70, s[0:1] offset:3200
	global_load_dwordx4 v[102:105], v70, s[36:37] offset:3200
	s_waitcnt lgkmcnt(3)
	v_mfma_f32_32x32x16_bf16 v[2:17], v[114:117], v[118:121], v[2:17]
	s_waitcnt lgkmcnt(2)
	v_mfma_f32_32x32x16_bf16 v[18:33], v[114:117], v[130:133], v[18:33]
	v_mfma_f32_32x32x16_bf16 v[34:49], v[110:113], v[118:121], v[34:49]
	v_mfma_f32_32x32x16_bf16 v[50:65], v[110:113], v[130:133], v[50:65]
	ds_read_b128 v[110:113], v0 offset:36960
	ds_read_b128 v[118:121], v0 offset:41568
	ds_read_b128 v[122:125], v66 offset:55392
	ds_read_b128 v[126:129], v66 offset:60000
	s_waitcnt vmcnt(9)
	ds_write_b128 v67, v[90:93] offset:9216
	s_waitcnt vmcnt(8)
	ds_write_b128 v67, v[106:109] offset:27648
	global_load_dwordx4 v[90:93], v69, s[0:1] offset:3200
	global_load_dwordx4 v[106:109], v69, s[36:37] offset:3200
	s_waitcnt lgkmcnt(3)
	v_mfma_f32_32x32x16_bf16 v[2:17], v[118:121], v[122:125], v[2:17]
	s_waitcnt vmcnt(9)
	ds_write_b128 v67, v[74:77] offset:13824
	s_waitcnt vmcnt(8)
	ds_write_b128 v67, v[94:97] offset:32256
	s_waitcnt lgkmcnt(4)
	v_mfma_f32_32x32x16_bf16 v[18:33], v[118:121], v[126:129], v[18:33]
	v_mfma_f32_32x32x16_bf16 v[34:49], v[110:113], v[122:125], v[34:49]
	v_mfma_f32_32x32x16_bf16 v[50:65], v[110:113], v[126:129], v[50:65]
	s_waitcnt lgkmcnt(0)
	s_barrier
	ds_read_b128 v[74:77], v0
	ds_read_b128 v[94:97], v66 offset:18432
	ds_read_b128 v[110:113], v0 offset:32
	ds_read_b128 v[114:117], v66 offset:18464
	ds_read_b128 v[118:121], v0 offset:4608
	ds_read_b128 v[122:125], v0 offset:4640
	s_waitcnt lgkmcnt(4)
	v_mfma_f32_32x32x16_bf16 v[34:49], v[74:77], v[94:97], v[34:49]
	s_waitcnt lgkmcnt(1)
	v_mfma_f32_32x32x16_bf16 v[2:17], v[118:121], v[94:97], v[2:17]
	ds_read_b128 v[94:97], v66 offset:23040
	ds_read_b128 v[126:129], v66 offset:23072
	s_waitcnt lgkmcnt(1)
	v_mfma_f32_32x32x16_bf16 v[50:65], v[74:77], v[94:97], v[50:65]
	global_load_dwordx4 v[74:77], v72, s[0:1] offset:3328
	global_load_dwordx4 v[130:133], v72, s[36:37] offset:3328
	s_waitcnt vmcnt(9)
	ds_write_b128 v67, v[78:81] offset:36864
	s_waitcnt vmcnt(8)
	ds_write_b128 v67, v[134:137] offset:55296
	v_mfma_f32_32x32x16_bf16 v[18:33], v[118:121], v[94:97], v[18:33]
	global_load_dwordx4 v[78:81], v71, s[0:1] offset:3328
	global_load_dwordx4 v[94:97], v71, s[36:37] offset:3328
	v_mfma_f32_32x32x16_bf16 v[2:17], v[122:125], v[114:117], v[2:17]
	s_waitcnt lgkmcnt(2)
	v_mfma_f32_32x32x16_bf16 v[18:33], v[122:125], v[126:129], v[18:33]
	v_mfma_f32_32x32x16_bf16 v[34:49], v[110:113], v[114:117], v[34:49]
	v_mfma_f32_32x32x16_bf16 v[50:65], v[110:113], v[126:129], v[50:65]
	ds_read_b128 v[110:113], v0 offset:64
	ds_read_b128 v[114:117], v0 offset:4672
	ds_read_b128 v[118:121], v66 offset:18496
	ds_read_b128 v[134:137], v66 offset:23104
	s_waitcnt vmcnt(9)
	ds_write_b128 v67, v[82:85] offset:41472
	s_waitcnt vmcnt(8)
	ds_write_b128 v67, v[98:101] offset:59904
	global_load_dwordx4 v[82:85], v70, s[0:1] offset:3328
	global_load_dwordx4 v[98:101], v70, s[36:37] offset:3328
	s_waitcnt lgkmcnt(3)
	v_mfma_f32_32x32x16_bf16 v[2:17], v[114:117], v[118:121], v[2:17]
	s_waitcnt lgkmcnt(2)
	v_mfma_f32_32x32x16_bf16 v[18:33], v[114:117], v[134:137], v[18:33]
	v_mfma_f32_32x32x16_bf16 v[34:49], v[110:113], v[118:121], v[34:49]
	v_mfma_f32_32x32x16_bf16 v[50:65], v[110:113], v[134:137], v[50:65]
	ds_read_b128 v[110:113], v0 offset:96
	ds_read_b128 v[118:121], v0 offset:4704
	ds_read_b128 v[122:125], v66 offset:18528
	ds_read_b128 v[126:129], v66 offset:23136
	s_waitcnt vmcnt(9)
	ds_write_b128 v67, v[86:89] offset:46080
	s_waitcnt vmcnt(8)
	ds_write_b128 v67, v[102:105] offset:64512
	global_load_dwordx4 v[86:89], v69, s[0:1] offset:3328
	global_load_dwordx4 v[102:105], v69, s[36:37] offset:3328
	s_waitcnt lgkmcnt(3)
	v_mfma_f32_32x32x16_bf16 v[2:17], v[118:121], v[122:125], v[2:17]
	s_waitcnt vmcnt(9)
	ds_write_b128 v67, v[90:93] offset:50688
	s_waitcnt vmcnt(8)
	ds_write_b128 v68, v[106:109] offset:13824
	s_waitcnt lgkmcnt(4)
	v_mfma_f32_32x32x16_bf16 v[18:33], v[118:121], v[126:129], v[18:33]
	v_mfma_f32_32x32x16_bf16 v[34:49], v[110:113], v[122:125], v[34:49]
	v_mfma_f32_32x32x16_bf16 v[50:65], v[110:113], v[126:129], v[50:65]
	s_waitcnt lgkmcnt(0)
	s_barrier
; #define GL1_(RA, RB, i) { RA[i] = *(const u32x4*)(ap + (aoff + (i) * astep)); if ((i) < NB) RB[(i) < NB ? (i) : 0] = *(const u32x4*)(bp + (boff + (i) * bstep)); }
; #define LS1_(RA, RB, ST, i) { char* sn_ = lds + (ST) * STAGE; *(u32x4*)(sn_ + wofs + (i) * 32 * LROW) = RA[i]; \
;                               if ((i) < NB) *(u32x4*)(sn_ + STAGE_OP + wofs + (i) * 32 * LROW) = RB[(i) < NB ? (i) : 0]; }
; template <int NJ> DI void gemm_mainloop_reg(const bf16_t* __restrict__ A, int lda, const bf16_t* __restrict__ Bt, int ldb, int K, f32x16 (&acc)[2][NJ], char* lds) {
;     ...
; #pragma unroll
;   for (int i = 0; i < 4; ++i) GL1_(ra0, rb0, i);
;   ap += 128; bp += 128;
; #pragma unroll
;   for (int i = 0; i < 4; ++i) GL1_(ra1, rb1, i);
;   ap += 128; bp += 128;
; #pragma unroll
;   for (int i = 0; i < 4; ++i) LS1_(ra0, rb0, 0, i);
;   __syncthreads();
;   const int nk = K >> 6;
;   for (int kt = 0; kt < nk; kt += 2) {
;     const bool l0 = (kt + 2 < nk), l1 = (kt + 3 < nk);
;     STEP_(0, l0, ra0, rb0, true, ra1, rb1);
;     __syncthreads();
;     STEP_(1, l1, ra1, rb1, l0, ra0, rb0);
;     __syncthreads();
;   }
	ds_read_b128 v[90:93], v0 offset:36864
	ds_read_b128 v[106:109], v66 offset:55296
	ds_read_b128 v[110:113], v0 offset:36896
	ds_read_b128 v[114:117], v66 offset:55328
	ds_read_b128 v[118:121], v0 offset:41472
	ds_read_b128 v[122:125], v0 offset:41504
	s_waitcnt lgkmcnt(4)
	v_mfma_f32_32x32x16_bf16 v[34:49], v[90:93], v[106:109], v[34:49]
	s_waitcnt lgkmcnt(1)
	v_mfma_f32_32x32x16_bf16 v[2:17], v[118:121], v[106:109], v[2:17]
	ds_read_b128 v[106:109], v66 offset:59904
	ds_read_b128 v[126:129], v66 offset:59936
	s_waitcnt lgkmcnt(1)
	v_mfma_f32_32x32x16_bf16 v[50:65], v[90:93], v[106:109], v[50:65]
	global_load_dwordx4 v[90:93], v72, s[0:1] offset:3456
	global_load_dwordx4 v[134:137], v72, s[36:37] offset:3456
	s_waitcnt vmcnt(9)
	ds_write_b128 v67, v[74:77]
	s_waitcnt vmcnt(8)
	ds_write_b128 v67, v[130:133] offset:18432
	v_mfma_f32_32x32x16_bf16 v[18:33], v[118:121], v[106:109], v[18:33]
	global_load_dwordx4 v[74:77], v71, s[0:1] offset:3456
	global_load_dwordx4 v[106:109], v71, s[36:37] offset:3456
	v_mfma_f32_32x32x16_bf16 v[2:17], v[122:125], v[114:117], v[2:17]
	s_waitcnt lgkmcnt(2)
	v_mfma_f32_32x32x16_bf16 v[18:33], v[122:125], v[126:129], v[18:33]
	v_mfma_f32_32x32x16_bf16 v[34:49], v[110:113], v[114:117], v[34:49]
	v_mfma_f32_32x32x16_bf16 v[50:65], v[110:113], v[126:129], v[50:65]
	ds_read_b128 v[110:113], v0 offset:36928
	ds_read_b128 v[114:117], v0 offset:41536
	ds_read_b128 v[118:121], v66 offset:55360
	ds_read_b128 v[130:133], v66 offset:59968
	s_waitcnt vmcnt(9)
	ds_write_b128 v67, v[78:81] offset:4608
	s_waitcnt vmcnt(8)
	ds_write_b128 v67, v[94:97] offset:23040
	global_load_dwordx4 v[78:81], v70, s[0:1] offset:3456
	global_load_dwordx4 v[94:97], v70, s[36:37] offset:3456
	s_waitcnt lgkmcnt(3)
	v_mfma_f32_32x32x16_bf16 v[2:17], v[114:117], v[118:121], v[2:17]
	s_waitcnt lgkmcnt(2)
	v_mfma_f32_32x32x16_bf16 v[18:33], v[114:117], v[130:133], v[18:33]
	v_mfma_f32_32x32x16_bf16 v[34:49], v[110:113], v[118:121], v[34:49]
	v_mfma_f32_32x32x16_bf16 v[50:65], v[110:113], v[130:133], v[50:65]
	ds_read_b128 v[110:113], v0 offset:36960
	ds_read_b128 v[118:121], v0 offset:41568
	ds_read_b128 v[122:125], v66 offset:55392
	ds_read_b128 v[126:129], v66 offset:60000
	s_waitcnt vmcnt(9)
	ds_write_b128 v67, v[82:85] offset:9216
	s_waitcnt vmcnt(8)
	ds_write_b128 v67, v[98:101] offset:27648
	global_load_dwordx4 v[82:85], v69, s[0:1] offset:3456
	global_load_dwordx4 v[98:101], v69, s[36:37] offset:3456
	s_waitcnt lgkmcnt(3)
	v_mfma_f32_32x32x16_bf16 v[2:17], v[118:121], v[122:125], v[2:17]
	s_waitcnt vmcnt(9)
	ds_write_b128 v67, v[86:89] offset:13824
	s_waitcnt vmcnt(8)
	ds_write_b128 v67, v[102:105] offset:32256
	s_waitcnt lgkmcnt(4)
	v_mfma_f32_32x32x16_bf16 v[18:33], v[118:121], v[126:129], v[18:33]
	v_mfma_f32_32x32x16_bf16 v[34:49], v[110:113], v[122:125], v[34:49]
	v_mfma_f32_32x32x16_bf16 v[50:65], v[110:113], v[126:129], v[50:65]
	s_waitcnt lgkmcnt(0)
	s_barrier
	ds_read_b128 v[86:89], v0
	ds_read_b128 v[102:105], v66 offset:18432
	ds_read_b128 v[110:113], v0 offset:32
	ds_read_b128 v[114:117], v66 offset:18464
	ds_read_b128 v[118:121], v0 offset:4608
	ds_read_b128 v[122:125], v0 offset:4640
	s_waitcnt lgkmcnt(4)
	v_mfma_f32_32x32x16_bf16 v[34:49], v[86:89], v[102:105], v[34:49]
	s_waitcnt lgkmcnt(1)
	v_mfma_f32_32x32x16_bf16 v[2:17], v[118:121], v[102:105], v[2:17]
	ds_read_b128 v[102:105], v66 offset:23040
	ds_read_b128 v[126:129], v66 offset:23072
	s_waitcnt lgkmcnt(1)
	v_mfma_f32_32x32x16_bf16 v[50:65], v[86:89], v[102:105], v[50:65]
	global_load_dwordx4 v[86:89], v72, s[0:1] offset:3584
	global_load_dwordx4 v[130:133], v72, s[36:37] offset:3584
	s_waitcnt vmcnt(9)
	ds_write_b128 v67, v[90:93] offset:36864
	s_waitcnt vmcnt(8)
	ds_write_b128 v67, v[134:137] offset:55296
	v_mfma_f32_32x32x16_bf16 v[18:33], v[118:121], v[102:105], v[18:33]
	global_load_dwordx4 v[90:93], v71, s[0:1] offset:3584
	global_load_dwordx4 v[102:105], v71, s[36:37] offset:3584
	v_mfma_f32_32x32x16_bf16 v[2:17], v[122:125], v[114:117], v[2:17]
	s_waitcnt lgkmcnt(2)
	v_mfma_f32_32x32x16_bf16 v[18:33], v[122:125], v[126:129], v[18:33]
	v_mfma_f32_32x32x16_bf16 v[34:49], v[110:113], v[114:117], v[34:49]
	v_mfma_f32_32x32x16_bf16 v[50:65], v[110:113], v[126:129], v[50:65]
	ds_read_b128 v[110:113], v0 offset:64
	ds_read_b128 v[114:117], v0 offset:4672
	ds_read_b128 v[118:121], v66 offset:18496
	ds_read_b128 v[134:137], v66 offset:23104
	s_waitcnt vmcnt(9)
	ds_write_b128 v67, v[74:77] offset:41472
	s_waitcnt vmcnt(8)
	ds_write_b128 v67, v[106:109] offset:59904
	global_load_dwordx4 v[74:77], v70, s[0:1] offset:3584
	global_load_dwordx4 v[106:109], v70, s[36:37] offset:3584
	s_waitcnt lgkmcnt(3)
	v_mfma_f32_32x32x16_bf16 v[2:17], v[114:117], v[118:121], v[2:17]
	s_waitcnt lgkmcnt(2)
	v_mfma_f32_32x32x16_bf16 v[18:33], v[114:117], v[134:137], v[18:33]
	v_mfma_f32_32x32x16_bf16 v[34:49], v[110:113], v[118:121], v[34:49]
	v_mfma_f32_32x32x16_bf16 v[50:65], v[110:113], v[134:137], v[50:65]
	ds_read_b128 v[110:113], v0 offset:96
	ds_read_b128 v[118:121], v0 offset:4704
	ds_read_b128 v[122:125], v66 offset:18528
	ds_read_b128 v[126:129], v66 offset:23136
	s_waitcnt vmcnt(9)
	ds_write_b128 v67, v[78:81] offset:46080
	s_waitcnt vmcnt(8)
	ds_write_b128 v67, v[94:97] offset:64512
	global_load_dwordx4 v[78:81], v69, s[0:1] offset:3584
	global_load_dwordx4 v[94:97], v69, s[36:37] offset:3584
	s_waitcnt lgkmcnt(3)
	v_mfma_f32_32x32x16_bf16 v[2:17], v[118:121], v[122:125], v[2:17]
	s_waitcnt vmcnt(9)
	ds_write_b128 v67, v[82:85] offset:50688
	s_waitcnt vmcnt(8)
	ds_write_b128 v68, v[98:101] offset:13824
	s_waitcnt lgkmcnt(4)
	v_mfma_f32_32x32x16_bf16 v[18:33], v[118:121], v[126:129], v[18:33]
	v_mfma_f32_32x32x16_bf16 v[34:49], v[110:113], v[122:125], v[34:49]
	v_mfma_f32_32x32x16_bf16 v[50:65], v[110:113], v[126:129], v[50:65]
	s_waitcnt lgkmcnt(0)
	s_barrier
; #define GL1_(RA, RB, i) { RA[i] = *(const u32x4*)(ap + (aoff + (i) * astep)); if ((i) < NB) RB[(i) < NB ? (i) : 0] = *(const u32x4*)(bp + (boff + (i) * bstep)); }
; #define LS1_(RA, RB, ST, i) { char* sn_ = lds + (ST) * STAGE; *(u32x4*)(sn_ + wofs + (i) * 32 * LROW) = RA[i]; \
;                               if ((i) < NB) *(u32x4*)(sn_ + STAGE_OP + wofs + (i) * 32 * LROW) = RB[(i) < NB ? (i) : 0]; }
; template <int NJ> DI void gemm_mainloop_reg(const bf16_t* __restrict__ A, int lda, const bf16_t* __restrict__ Bt, int ldb, int K, f32x16 (&acc)[2][NJ], char* lds) {
;     ...
; #pragma unroll
;   for (int i = 0; i < 4; ++i) GL1_(ra0, rb0, i);
;   ap += 128; bp += 128;
; #pragma unroll
;   for (int i = 0; i < 4; ++i) GL1_(ra1, rb1, i);
;   ap += 128; bp += 128;
; #pragma unroll
;   for (int i = 0; i < 4; ++i) LS1_(ra0, rb0, 0, i);
;   __syncthreads();
;   const int nk = K >> 6;
;   for (int kt = 0; kt < nk; kt += 2) {
;     const bool l0 = (kt + 2 < nk), l1 = (kt + 3 < nk);
;     STEP_(0, l0, ra0, rb0, true, ra1, rb1);
;     __syncthreads();
;     STEP_(1, l1, ra1, rb1, l0, ra0, rb0);
;     __syncthreads();
;   }
	ds_read_b128 v[82:85], v0 offset:36864
	ds_read_b128 v[98:101], v66 offset:55296
	ds_read_b128 v[110:113], v0 offset:36896
	ds_read_b128 v[114:117], v66 offset:55328
	ds_read_b128 v[118:121], v0 offset:41472
	ds_read_b128 v[122:125], v0 offset:41504
	s_waitcnt lgkmcnt(4)
	v_mfma_f32_32x32x16_bf16 v[34:49], v[82:85], v[98:101], v[34:49]
	s_waitcnt lgkmcnt(1)
	v_mfma_f32_32x32x16_bf16 v[2:17], v[118:121], v[98:101], v[2:17]
	ds_read_b128 v[98:101], v66 offset:59904
	ds_read_b128 v[126:129], v66 offset:59936
	s_waitcnt lgkmcnt(1)
	v_mfma_f32_32x32x16_bf16 v[50:65], v[82:85], v[98:101], v[50:65]
	global_load_dwordx4 v[82:85], v72, s[0:1] offset:3712
	global_load_dwordx4 v[134:137], v72, s[36:37] offset:3712
	s_waitcnt vmcnt(9)
	ds_write_b128 v67, v[86:89]
	s_waitcnt vmcnt(8)
	ds_write_b128 v67, v[130:133] offset:18432
	v_mfma_f32_32x32x16_bf16 v[18:33], v[118:121], v[98:101], v[18:33]
	global_load_dwordx4 v[86:89], v71, s[0:1] offset:3712
	global_load_dwordx4 v[98:101], v71, s[36:37] offset:3712
	v_mfma_f32_32x32x16_bf16 v[2:17], v[122:125], v[114:117], v[2:17]
	s_waitcnt lgkmcnt(2)
	v_mfma_f32_32x32x16_bf16 v[18:33], v[122:125], v[126:129], v[18:33]
	v_mfma_f32_32x32x16_bf16 v[34:49], v[110:113], v[114:117], v[34:49]
	v_mfma_f32_32x32x16_bf16 v[50:65], v[110:113], v[126:129], v[50:65]
	ds_read_b128 v[110:113], v0 offset:36928
	ds_read_b128 v[114:117], v0 offset:41536
	ds_read_b128 v[118:121], v66 offset:55360
	ds_read_b128 v[130:133], v66 offset:59968
	s_waitcnt vmcnt(9)
	ds_write_b128 v67, v[90:93] offset:4608
	s_waitcnt vmcnt(8)
	ds_write_b128 v67, v[102:105] offset:23040
	global_load_dwordx4 v[90:93], v70, s[0:1] offset:3712
	global_load_dwordx4 v[102:105], v70, s[36:37] offset:3712
	s_waitcnt lgkmcnt(3)
	v_mfma_f32_32x32x16_bf16 v[2:17], v[114:117], v[118:121], v[2:17]
	s_waitcnt lgkmcnt(2)
	v_mfma_f32_32x32x16_bf16 v[18:33], v[114:117], v[130:133], v[18:33]
	v_mfma_f32_32x32x16_bf16 v[34:49], v[110:113], v[118:121], v[34:49]
	v_mfma_f32_32x32x16_bf16 v[50:65], v[110:113], v[130:133], v[50:65]
	ds_read_b128 v[110:113], v0 offset:36960
	ds_read_b128 v[118:121], v0 offset:41568
	ds_read_b128 v[122:125], v66 offset:55392
	ds_read_b128 v[126:129], v66 offset:60000
	s_waitcnt vmcnt(9)
	ds_write_b128 v67, v[74:77] offset:9216
	s_waitcnt vmcnt(8)
	ds_write_b128 v67, v[106:109] offset:27648
	global_load_dwordx4 v[74:77], v69, s[0:1] offset:3712
	global_load_dwordx4 v[106:109], v69, s[36:37] offset:3712
	s_waitcnt lgkmcnt(3)
	v_mfma_f32_32x32x16_bf16 v[2:17], v[118:121], v[122:125], v[2:17]
	s_waitcnt vmcnt(9)
	ds_write_b128 v67, v[78:81] offset:13824
	s_waitcnt vmcnt(8)
	ds_write_b128 v67, v[94:97] offset:32256
	s_waitcnt lgkmcnt(4)
	v_mfma_f32_32x32x16_bf16 v[18:33], v[118:121], v[126:129], v[18:33]
	v_mfma_f32_32x32x16_bf16 v[34:49], v[110:113], v[122:125], v[34:49]
	v_mfma_f32_32x32x16_bf16 v[50:65], v[110:113], v[126:129], v[50:65]
	s_waitcnt lgkmcnt(0)
	s_barrier
	ds_read_b128 v[78:81], v0
	ds_read_b128 v[94:97], v66 offset:18432
	ds_read_b128 v[110:113], v0 offset:32
	ds_read_b128 v[114:117], v66 offset:18464
	ds_read_b128 v[118:121], v0 offset:4608
	ds_read_b128 v[122:125], v0 offset:4640
	s_waitcnt lgkmcnt(4)
	v_mfma_f32_32x32x16_bf16 v[34:49], v[78:81], v[94:97], v[34:49]
	s_waitcnt lgkmcnt(1)
	v_mfma_f32_32x32x16_bf16 v[2:17], v[118:121], v[94:97], v[2:17]
	ds_read_b128 v[94:97], v66 offset:23040
	ds_read_b128 v[126:129], v66 offset:23072
	s_waitcnt lgkmcnt(1)
	v_mfma_f32_32x32x16_bf16 v[50:65], v[78:81], v[94:97], v[50:65]
	global_load_dwordx4 v[78:81], v72, s[0:1] offset:3840
	global_load_dwordx4 v[130:133], v72, s[36:37] offset:3840
	s_waitcnt vmcnt(9)
	ds_write_b128 v67, v[82:85] offset:36864
	s_waitcnt vmcnt(8)
	ds_write_b128 v67, v[134:137] offset:55296
	v_mfma_f32_32x32x16_bf16 v[18:33], v[118:121], v[94:97], v[18:33]
	global_load_dwordx4 v[82:85], v71, s[0:1] offset:3840
	global_load_dwordx4 v[94:97], v71, s[36:37] offset:3840
	v_mfma_f32_32x32x16_bf16 v[2:17], v[122:125], v[114:117], v[2:17]
	s_waitcnt lgkmcnt(2)
	v_mfma_f32_32x32x16_bf16 v[18:33], v[122:125], v[126:129], v[18:33]
	v_mfma_f32_32x32x16_bf16 v[34:49], v[110:113], v[114:117], v[34:49]
	v_mfma_f32_32x32x16_bf16 v[50:65], v[110:113], v[126:129], v[50:65]
	ds_read_b128 v[110:113], v0 offset:64
	ds_read_b128 v[114:117], v0 offset:4672
	ds_read_b128 v[118:121], v66 offset:18496
	ds_read_b128 v[134:137], v66 offset:23104
	s_waitcnt vmcnt(9)
	ds_write_b128 v67, v[86:89] offset:41472
	s_waitcnt vmcnt(8)
	ds_write_b128 v67, v[98:101] offset:59904
	global_load_dwordx4 v[86:89], v70, s[0:1] offset:3840
	global_load_dwordx4 v[98:101], v70, s[36:37] offset:3840
	s_waitcnt lgkmcnt(3)
	v_mfma_f32_32x32x16_bf16 v[2:17], v[114:117], v[118:121], v[2:17]
	s_waitcnt lgkmcnt(2)
	v_mfma_f32_32x32x16_bf16 v[18:33], v[114:117], v[134:137], v[18:33]
	v_mfma_f32_32x32x16_bf16 v[34:49], v[110:113], v[118:121], v[34:49]
	v_mfma_f32_32x32x16_bf16 v[50:65], v[110:113], v[134:137], v[50:65]
	ds_read_b128 v[110:113], v0 offset:96
	ds_read_b128 v[118:121], v0 offset:4704
	ds_read_b128 v[122:125], v66 offset:18528
	ds_read_b128 v[126:129], v66 offset:23136
	s_waitcnt vmcnt(9)
	ds_write_b128 v67, v[90:93] offset:46080
	s_waitcnt vmcnt(8)
	ds_write_b128 v67, v[102:105] offset:64512
	global_load_dwordx4 v[90:93], v69, s[0:1] offset:3840
	global_load_dwordx4 v[102:105], v69, s[36:37] offset:3840
	s_waitcnt lgkmcnt(3)
	v_mfma_f32_32x32x16_bf16 v[2:17], v[118:121], v[122:125], v[2:17]
	s_waitcnt vmcnt(9)
	ds_write_b128 v67, v[74:77] offset:50688
	s_waitcnt vmcnt(8)
	ds_write_b128 v68, v[106:109] offset:13824
	s_waitcnt lgkmcnt(4)
	v_mfma_f32_32x32x16_bf16 v[18:33], v[118:121], v[126:129], v[18:33]
	v_mfma_f32_32x32x16_bf16 v[34:49], v[110:113], v[122:125], v[34:49]
	v_mfma_f32_32x32x16_bf16 v[50:65], v[110:113], v[126:129], v[50:65]
	s_waitcnt lgkmcnt(0)
	s_barrier
; #define GL1_(RA, RB, i) { RA[i] = *(const u32x4*)(ap + (aoff + (i) * astep)); if ((i) < NB) RB[(i) < NB ? (i) : 0] = *(const u32x4*)(bp + (boff + (i) * bstep)); }
; #define LS1_(RA, RB, ST, i) { char* sn_ = lds + (ST) * STAGE; *(u32x4*)(sn_ + wofs + (i) * 32 * LROW) = RA[i]; \
;                               if ((i) < NB) *(u32x4*)(sn_ + STAGE_OP + wofs + (i) * 32 * LROW) = RB[(i) < NB ? (i) : 0]; }
; template <int NJ> DI void gemm_mainloop_reg(const bf16_t* __restrict__ A, int lda, const bf16_t* __restrict__ Bt, int ldb, int K, f32x16 (&acc)[2][NJ], char* lds) {
;     ...
; #pragma unroll
;   for (int i = 0; i < 4; ++i) GL1_(ra0, rb0, i);
;   ap += 128; bp += 128;
; #pragma unroll
;   for (int i = 0; i < 4; ++i) GL1_(ra1, rb1, i);
;   ap += 128; bp += 128;
; #pragma unroll
;   for (int i = 0; i < 4; ++i) LS1_(ra0, rb0, 0, i);
;   __syncthreads();
;   const int nk = K >> 6;
;   for (int kt = 0; kt < nk; kt += 2) {
;     const bool l0 = (kt + 2 < nk), l1 = (kt + 3 < nk);
;     STEP_(0, l0, ra0, rb0, true, ra1, rb1);
;     __syncthreads();
;     STEP_(1, l1, ra1, rb1, l0, ra0, rb0);
;     __syncthreads();
;   }
	ds_read_b128 v[74:77], v0 offset:36864
	ds_read_b128 v[106:109], v66 offset:55296
	ds_read_b128 v[110:113], v0 offset:36896
	ds_read_b128 v[114:117], v66 offset:55328
	ds_read_b128 v[118:121], v0 offset:41472
	ds_read_b128 v[122:125], v0 offset:41504
	s_waitcnt lgkmcnt(4)
	v_mfma_f32_32x32x16_bf16 v[34:49], v[74:77], v[106:109], v[34:49]
	s_waitcnt lgkmcnt(1)
	v_mfma_f32_32x32x16_bf16 v[2:17], v[118:121], v[106:109], v[2:17]
	ds_read_b128 v[106:109], v66 offset:59904
	ds_read_b128 v[126:129], v66 offset:59936
	s_waitcnt lgkmcnt(1)
	v_mfma_f32_32x32x16_bf16 v[50:65], v[74:77], v[106:109], v[50:65]
	global_load_dwordx4 v[74:77], v72, s[0:1] offset:3968
	global_load_dwordx4 v[134:137], v72, s[36:37] offset:3968
	s_waitcnt vmcnt(9)
	ds_write_b128 v67, v[78:81]
	s_waitcnt vmcnt(8)
	ds_write_b128 v67, v[130:133] offset:18432
	v_mfma_f32_32x32x16_bf16 v[18:33], v[118:121], v[106:109], v[18:33]
	global_load_dwordx4 v[78:81], v71, s[0:1] offset:3968
	global_load_dwordx4 v[106:109], v71, s[36:37] offset:3968
	v_mfma_f32_32x32x16_bf16 v[2:17], v[122:125], v[114:117], v[2:17]
	s_waitcnt lgkmcnt(2)
	v_mfma_f32_32x32x16_bf16 v[18:33], v[122:125], v[126:129], v[18:33]
	v_mfma_f32_32x32x16_bf16 v[34:49], v[110:113], v[114:117], v[34:49]
	v_mfma_f32_32x32x16_bf16 v[50:65], v[110:113], v[126:129], v[50:65]
	ds_read_b128 v[110:113], v0 offset:36928
	ds_read_b128 v[114:117], v0 offset:41536
	ds_read_b128 v[118:121], v66 offset:55360
	ds_read_b128 v[130:133], v66 offset:59968
	s_waitcnt vmcnt(9)
	ds_write_b128 v67, v[82:85] offset:4608
	s_waitcnt vmcnt(8)
	ds_write_b128 v67, v[94:97] offset:23040
	global_load_dwordx4 v[82:85], v70, s[0:1] offset:3968
	global_load_dwordx4 v[94:97], v70, s[36:37] offset:3968
	s_waitcnt lgkmcnt(3)
	v_mfma_f32_32x32x16_bf16 v[2:17], v[114:117], v[118:121], v[2:17]
	s_waitcnt lgkmcnt(2)
	v_mfma_f32_32x32x16_bf16 v[18:33], v[114:117], v[130:133], v[18:33]
	v_mfma_f32_32x32x16_bf16 v[34:49], v[110:113], v[118:121], v[34:49]
	v_mfma_f32_32x32x16_bf16 v[50:65], v[110:113], v[130:133], v[50:65]
	ds_read_b128 v[110:113], v0 offset:36960
	ds_read_b128 v[118:121], v0 offset:41568
	ds_read_b128 v[122:125], v66 offset:55392
	ds_read_b128 v[126:129], v66 offset:60000
	s_waitcnt vmcnt(9)
	ds_write_b128 v67, v[86:89] offset:9216
	s_waitcnt vmcnt(8)
	ds_write_b128 v67, v[98:101] offset:27648
	global_load_dwordx4 v[86:89], v69, s[0:1] offset:3968
	global_load_dwordx4 v[98:101], v69, s[36:37] offset:3968
	s_waitcnt lgkmcnt(3)
	v_mfma_f32_32x32x16_bf16 v[2:17], v[118:121], v[122:125], v[2:17]
	s_waitcnt vmcnt(9)
	ds_write_b128 v67, v[90:93] offset:13824
	s_waitcnt vmcnt(8)
	ds_write_b128 v67, v[102:105] offset:32256
	s_waitcnt lgkmcnt(4)
	v_mfma_f32_32x32x16_bf16 v[18:33], v[118:121], v[126:129], v[18:33]
	v_mfma_f32_32x32x16_bf16 v[34:49], v[110:113], v[122:125], v[34:49]
	v_mfma_f32_32x32x16_bf16 v[50:65], v[110:113], v[126:129], v[50:65]
	s_waitcnt lgkmcnt(0)
	s_barrier
	ds_read_b128 v[90:93], v0
	ds_read_b128 v[102:105], v66 offset:18432
	ds_read_b128 v[110:113], v0 offset:32
	ds_read_b128 v[114:117], v66 offset:18464
	ds_read_b128 v[118:121], v0 offset:4608
	ds_read_b128 v[122:125], v0 offset:4640
	s_waitcnt lgkmcnt(4)
	v_mfma_f32_32x32x16_bf16 v[34:49], v[90:93], v[102:105], v[34:49]
	s_add_u32 s2, s36, 0x1000
	s_addc_u32 s3, s37, 0
	s_add_u32 s26, s0, 0x1000
	s_addc_u32 s27, s1, 0
	ds_read_b128 v[126:129], v66 offset:23072
	s_waitcnt lgkmcnt(2)
	v_mfma_f32_32x32x16_bf16 v[2:17], v[118:121], v[102:105], v[2:17]
	ds_read_b128 v[102:105], v66 offset:23040
	s_waitcnt lgkmcnt(0)
	v_mfma_f32_32x32x16_bf16 v[50:65], v[90:93], v[102:105], v[50:65]
	global_load_dwordx4 v[90:93], v72, s[26:27]
	global_load_dwordx4 v[130:133], v72, s[2:3]
	s_waitcnt vmcnt(9)
	ds_write_b128 v67, v[74:77] offset:36864
	s_waitcnt vmcnt(8)
	ds_write_b128 v67, v[134:137] offset:55296
	v_mfma_f32_32x32x16_bf16 v[18:33], v[118:121], v[102:105], v[18:33]
	global_load_dwordx4 v[74:77], v71, s[26:27]
	global_load_dwordx4 v[102:105], v71, s[2:3]
	v_mfma_f32_32x32x16_bf16 v[2:17], v[122:125], v[114:117], v[2:17]
	v_mfma_f32_32x32x16_bf16 v[18:33], v[122:125], v[126:129], v[18:33]
	v_mfma_f32_32x32x16_bf16 v[34:49], v[110:113], v[114:117], v[34:49]
	v_mfma_f32_32x32x16_bf16 v[50:65], v[110:113], v[126:129], v[50:65]
	ds_read_b128 v[110:113], v0 offset:64
	ds_read_b128 v[114:117], v0 offset:4672
	ds_read_b128 v[118:121], v66 offset:18496
	ds_read_b128 v[134:137], v66 offset:23104
	s_waitcnt vmcnt(9)
	ds_write_b128 v67, v[78:81] offset:41472
	s_waitcnt vmcnt(8)
	ds_write_b128 v67, v[106:109] offset:59904
	global_load_dwordx4 v[78:81], v70, s[26:27]
	global_load_dwordx4 v[106:109], v70, s[2:3]
	s_waitcnt lgkmcnt(3)
	v_mfma_f32_32x32x16_bf16 v[2:17], v[114:117], v[118:121], v[2:17]
	s_waitcnt lgkmcnt(2)
	v_mfma_f32_32x32x16_bf16 v[18:33], v[114:117], v[134:137], v[18:33]
	v_mfma_f32_32x32x16_bf16 v[34:49], v[110:113], v[118:121], v[34:49]
	v_mfma_f32_32x32x16_bf16 v[50:65], v[110:113], v[134:137], v[50:65]
	ds_read_b128 v[110:113], v0 offset:96
	ds_read_b128 v[118:121], v0 offset:4704
	ds_read_b128 v[122:125], v66 offset:18528
	ds_read_b128 v[126:129], v66 offset:23136
	s_waitcnt vmcnt(9)
	ds_write_b128 v67, v[82:85] offset:46080
	s_waitcnt vmcnt(8)
	ds_write_b128 v67, v[94:97] offset:64512
	global_load_dwordx4 v[82:85], v69, s[26:27]
	global_load_dwordx4 v[94:97], v69, s[2:3]
	s_waitcnt lgkmcnt(3)
	v_mfma_f32_32x32x16_bf16 v[2:17], v[118:121], v[122:125], v[2:17]
	s_waitcnt vmcnt(9)
	ds_write_b128 v67, v[86:89] offset:50688
	s_waitcnt vmcnt(8)
	ds_write_b128 v68, v[98:101] offset:13824
	s_waitcnt lgkmcnt(4)
	v_mfma_f32_32x32x16_bf16 v[18:33], v[118:121], v[126:129], v[18:33]
	v_mfma_f32_32x32x16_bf16 v[34:49], v[110:113], v[122:125], v[34:49]
	v_mfma_f32_32x32x16_bf16 v[50:65], v[110:113], v[126:129], v[50:65]
	s_waitcnt lgkmcnt(0)
	s_barrier
; #define GL1_(RA, RB, i) { RA[i] = *(const u32x4*)(ap + (aoff + (i) * astep)); if ((i) < NB) RB[(i) < NB ? (i) : 0] = *(const u32x4*)(bp + (boff + (i) * bstep)); }
; #define LS1_(RA, RB, ST, i) { char* sn_ = lds + (ST) * STAGE; *(u32x4*)(sn_ + wofs + (i) * 32 * LROW) = RA[i]; \
;                               if ((i) < NB) *(u32x4*)(sn_ + STAGE_OP + wofs + (i) * 32 * LROW) = RB[(i) < NB ? (i) : 0]; }
; template <int NJ> DI void gemm_mainloop_reg(const bf16_t* __restrict__ A, int lda, const bf16_t* __restrict__ Bt, int ldb, int K, f32x16 (&acc)[2][NJ], char* lds) {
;     ...
; #pragma unroll
;   for (int i = 0; i < 4; ++i) GL1_(ra0, rb0, i);
;   ap += 128; bp += 128;
; #pragma unroll
;   for (int i = 0; i < 4; ++i) GL1_(ra1, rb1, i);
;   ap += 128; bp += 128;
; #pragma unroll
;   for (int i = 0; i < 4; ++i) LS1_(ra0, rb0, 0, i);
;   __syncthreads();
;   const int nk = K >> 6;
;   for (int kt = 0; kt < nk; kt += 2) {
;     const bool l0 = (kt + 2 < nk), l1 = (kt + 3 < nk);
;     STEP_(0, l0, ra0, rb0, true, ra1, rb1);
;     __syncthreads();
;     STEP_(1, l1, ra1, rb1, l0, ra0, rb0);
;     __syncthreads();
;   }
	ds_read_b128 v[86:89], v0 offset:36864
	ds_read_b128 v[98:101], v66 offset:55296
	ds_read_b128 v[110:113], v0 offset:36896
	ds_read_b128 v[114:117], v66 offset:55328
	ds_read_b128 v[118:121], v0 offset:41472
	ds_read_b128 v[122:125], v0 offset:41504
	s_waitcnt lgkmcnt(4)
	v_mfma_f32_32x32x16_bf16 v[34:49], v[86:89], v[98:101], v[34:49]
	s_add_u32 s2, s36, 0x1080
	s_addc_u32 s3, s37, 0
	s_add_u32 s26, s0, 0x1080
	s_addc_u32 s27, s1, 0
	ds_read_b128 v[126:129], v66 offset:59936
	s_waitcnt lgkmcnt(2)
	v_mfma_f32_32x32x16_bf16 v[2:17], v[118:121], v[98:101], v[2:17]
	ds_read_b128 v[98:101], v66 offset:59904
	s_waitcnt lgkmcnt(0)
	v_mfma_f32_32x32x16_bf16 v[50:65], v[86:89], v[98:101], v[50:65]
	global_load_dwordx4 v[86:89], v72, s[26:27]
	global_load_dwordx4 v[134:137], v72, s[2:3]
	s_waitcnt vmcnt(9)
	ds_write_b128 v67, v[90:93]
	s_waitcnt vmcnt(8)
	ds_write_b128 v67, v[130:133] offset:18432
	v_mfma_f32_32x32x16_bf16 v[18:33], v[118:121], v[98:101], v[18:33]
	global_load_dwordx4 v[90:93], v71, s[26:27]
	global_load_dwordx4 v[98:101], v71, s[2:3]
	v_mfma_f32_32x32x16_bf16 v[2:17], v[122:125], v[114:117], v[2:17]
	v_mfma_f32_32x32x16_bf16 v[18:33], v[122:125], v[126:129], v[18:33]
	v_mfma_f32_32x32x16_bf16 v[34:49], v[110:113], v[114:117], v[34:49]
	v_mfma_f32_32x32x16_bf16 v[50:65], v[110:113], v[126:129], v[50:65]
	ds_read_b128 v[110:113], v0 offset:36928
	ds_read_b128 v[114:117], v0 offset:41536
	ds_read_b128 v[118:121], v66 offset:55360
	ds_read_b128 v[130:133], v66 offset:59968
	s_waitcnt vmcnt(9)
	ds_write_b128 v67, v[74:77] offset:4608
	s_waitcnt vmcnt(8)
	ds_write_b128 v67, v[102:105] offset:23040
	global_load_dwordx4 v[74:77], v70, s[26:27]
	global_load_dwordx4 v[102:105], v70, s[2:3]
	s_waitcnt lgkmcnt(3)
	v_mfma_f32_32x32x16_bf16 v[2:17], v[114:117], v[118:121], v[2:17]
	s_waitcnt lgkmcnt(2)
	v_mfma_f32_32x32x16_bf16 v[18:33], v[114:117], v[130:133], v[18:33]
	v_mfma_f32_32x32x16_bf16 v[34:49], v[110:113], v[118:121], v[34:49]
	v_mfma_f32_32x32x16_bf16 v[50:65], v[110:113], v[130:133], v[50:65]
	ds_read_b128 v[110:113], v0 offset:36960
	ds_read_b128 v[118:121], v0 offset:41568
	ds_read_b128 v[122:125], v66 offset:55392
	ds_read_b128 v[126:129], v66 offset:60000
	s_waitcnt vmcnt(9)
	ds_write_b128 v67, v[78:81] offset:9216
	s_waitcnt vmcnt(8)
	ds_write_b128 v67, v[106:109] offset:27648
	global_load_dwordx4 v[78:81], v69, s[26:27]
	global_load_dwordx4 v[106:109], v69, s[2:3]
	s_waitcnt lgkmcnt(3)
	v_mfma_f32_32x32x16_bf16 v[2:17], v[118:121], v[122:125], v[2:17]
	s_waitcnt vmcnt(9)
	ds_write_b128 v67, v[82:85] offset:13824
	s_waitcnt vmcnt(8)
	ds_write_b128 v67, v[94:97] offset:32256
	s_waitcnt lgkmcnt(4)
	v_mfma_f32_32x32x16_bf16 v[18:33], v[118:121], v[126:129], v[18:33]
	v_mfma_f32_32x32x16_bf16 v[34:49], v[110:113], v[122:125], v[34:49]
	v_mfma_f32_32x32x16_bf16 v[50:65], v[110:113], v[126:129], v[50:65]
	s_waitcnt lgkmcnt(0)
	s_barrier
	ds_read_b128 v[82:85], v0
	ds_read_b128 v[94:97], v66 offset:18432
	ds_read_b128 v[110:113], v0 offset:32
	ds_read_b128 v[114:117], v66 offset:18464
	ds_read_b128 v[118:121], v0 offset:4608
	ds_read_b128 v[122:125], v0 offset:4640
	s_waitcnt lgkmcnt(4)
	v_mfma_f32_32x32x16_bf16 v[34:49], v[82:85], v[94:97], v[34:49]
	s_add_u32 s2, s36, 0x1100
	s_addc_u32 s3, s37, 0
	s_add_u32 s26, s0, 0x1100
	s_addc_u32 s27, s1, 0
	ds_read_b128 v[126:129], v66 offset:23072
	s_waitcnt lgkmcnt(2)
	v_mfma_f32_32x32x16_bf16 v[2:17], v[118:121], v[94:97], v[2:17]
	ds_read_b128 v[94:97], v66 offset:23040
	s_waitcnt lgkmcnt(0)
	v_mfma_f32_32x32x16_bf16 v[50:65], v[82:85], v[94:97], v[50:65]
	global_load_dwordx4 v[82:85], v72, s[26:27]
	global_load_dwordx4 v[130:133], v72, s[2:3]
	s_waitcnt vmcnt(9)
	ds_write_b128 v67, v[86:89] offset:36864
	s_waitcnt vmcnt(8)
	ds_write_b128 v67, v[134:137] offset:55296
	v_mfma_f32_32x32x16_bf16 v[18:33], v[118:121], v[94:97], v[18:33]
	global_load_dwordx4 v[86:89], v71, s[26:27]
	global_load_dwordx4 v[94:97], v71, s[2:3]
	v_mfma_f32_32x32x16_bf16 v[2:17], v[122:125], v[114:117], v[2:17]
	v_mfma_f32_32x32x16_bf16 v[18:33], v[122:125], v[126:129], v[18:33]
	v_mfma_f32_32x32x16_bf16 v[34:49], v[110:113], v[114:117], v[34:49]
	v_mfma_f32_32x32x16_bf16 v[50:65], v[110:113], v[126:129], v[50:65]
	ds_read_b128 v[110:113], v0 offset:64
	ds_read_b128 v[114:117], v0 offset:4672
	ds_read_b128 v[118:121], v66 offset:18496
	ds_read_b128 v[134:137], v66 offset:23104
	s_waitcnt vmcnt(9)
	ds_write_b128 v67, v[90:93] offset:41472
	s_waitcnt vmcnt(8)
	ds_write_b128 v67, v[98:101] offset:59904
	global_load_dwordx4 v[90:93], v70, s[26:27]
	global_load_dwordx4 v[98:101], v70, s[2:3]
	s_waitcnt lgkmcnt(3)
	v_mfma_f32_32x32x16_bf16 v[2:17], v[114:117], v[118:121], v[2:17]
	s_waitcnt lgkmcnt(2)
	v_mfma_f32_32x32x16_bf16 v[18:33], v[114:117], v[134:137], v[18:33]
	v_mfma_f32_32x32x16_bf16 v[34:49], v[110:113], v[118:121], v[34:49]
	v_mfma_f32_32x32x16_bf16 v[50:65], v[110:113], v[134:137], v[50:65]
	ds_read_b128 v[110:113], v0 offset:96
	ds_read_b128 v[118:121], v0 offset:4704
	ds_read_b128 v[122:125], v66 offset:18528
	ds_read_b128 v[126:129], v66 offset:23136
	s_waitcnt vmcnt(9)
	ds_write_b128 v67, v[74:77] offset:46080
	s_waitcnt vmcnt(8)
	ds_write_b128 v67, v[102:105] offset:64512
	global_load_dwordx4 v[74:77], v69, s[26:27]
	global_load_dwordx4 v[102:105], v69, s[2:3]
	s_waitcnt lgkmcnt(3)
	v_mfma_f32_32x32x16_bf16 v[2:17], v[118:121], v[122:125], v[2:17]
	s_waitcnt vmcnt(9)
	ds_write_b128 v67, v[78:81] offset:50688
	s_waitcnt vmcnt(8)
	ds_write_b128 v68, v[106:109] offset:13824
	s_waitcnt lgkmcnt(4)
	v_mfma_f32_32x32x16_bf16 v[18:33], v[118:121], v[126:129], v[18:33]
	v_mfma_f32_32x32x16_bf16 v[34:49], v[110:113], v[122:125], v[34:49]
	v_mfma_f32_32x32x16_bf16 v[50:65], v[110:113], v[126:129], v[50:65]
	s_waitcnt lgkmcnt(0)
	s_barrier
; #define GL1_(RA, RB, i) { RA[i] = *(const u32x4*)(ap + (aoff + (i) * astep)); if ((i) < NB) RB[(i) < NB ? (i) : 0] = *(const u32x4*)(bp + (boff + (i) * bstep)); }
; #define LS1_(RA, RB, ST, i) { char* sn_ = lds + (ST) * STAGE; *(u32x4*)(sn_ + wofs + (i) * 32 * LROW) = RA[i]; \
;                               if ((i) < NB) *(u32x4*)(sn_ + STAGE_OP + wofs + (i) * 32 * LROW) = RB[(i) < NB ? (i) : 0]; }
; template <int NJ> DI void gemm_mainloop_reg(const bf16_t* __restrict__ A, int lda, const bf16_t* __restrict__ Bt, int ldb, int K, f32x16 (&acc)[2][NJ], char* lds) {
;     ...
; #pragma unroll
;   for (int i = 0; i < 4; ++i) GL1_(ra0, rb0, i);
;   ap += 128; bp += 128;
; #pragma unroll
;   for (int i = 0; i < 4; ++i) GL1_(ra1, rb1, i);
;   ap += 128; bp += 128;
; #pragma unroll
;   for (int i = 0; i < 4; ++i) LS1_(ra0, rb0, 0, i);
;   __syncthreads();
;   const int nk = K >> 6;
;   for (int kt = 0; kt < nk; kt += 2) {
;     const bool l0 = (kt + 2 < nk), l1 = (kt + 3 < nk);
;     STEP_(0, l0, ra0, rb0, true, ra1, rb1);
;     __syncthreads();
;     STEP_(1, l1, ra1, rb1, l0, ra0, rb0);
;     __syncthreads();
;   }
	ds_read_b128 v[78:81], v0 offset:36864
	ds_read_b128 v[106:109], v66 offset:55296
	ds_read_b128 v[110:113], v0 offset:36896
	ds_read_b128 v[114:117], v66 offset:55328
	ds_read_b128 v[118:121], v0 offset:41472
	ds_read_b128 v[122:125], v0 offset:41504
	s_waitcnt lgkmcnt(4)
	v_mfma_f32_32x32x16_bf16 v[34:49], v[78:81], v[106:109], v[34:49]
	s_add_u32 s2, s36, 0x1180
	s_addc_u32 s3, s37, 0
	s_add_u32 s26, s0, 0x1180
	s_addc_u32 s27, s1, 0
	ds_read_b128 v[126:129], v66 offset:59936
	s_waitcnt lgkmcnt(2)
	v_mfma_f32_32x32x16_bf16 v[2:17], v[118:121], v[106:109], v[2:17]
	ds_read_b128 v[106:109], v66 offset:59904
	s_waitcnt lgkmcnt(0)
	v_mfma_f32_32x32x16_bf16 v[50:65], v[78:81], v[106:109], v[50:65]
	global_load_dwordx4 v[78:81], v72, s[26:27]
	global_load_dwordx4 v[134:137], v72, s[2:3]
	s_waitcnt vmcnt(9)
	ds_write_b128 v67, v[82:85]
	s_waitcnt vmcnt(8)
	ds_write_b128 v67, v[130:133] offset:18432
	v_mfma_f32_32x32x16_bf16 v[18:33], v[118:121], v[106:109], v[18:33]
	global_load_dwordx4 v[82:85], v71, s[26:27]
	global_load_dwordx4 v[106:109], v71, s[2:3]
	v_mfma_f32_32x32x16_bf16 v[2:17], v[122:125], v[114:117], v[2:17]
	v_mfma_f32_32x32x16_bf16 v[18:33], v[122:125], v[126:129], v[18:33]
	v_mfma_f32_32x32x16_bf16 v[34:49], v[110:113], v[114:117], v[34:49]
	v_mfma_f32_32x32x16_bf16 v[50:65], v[110:113], v[126:129], v[50:65]
	ds_read_b128 v[110:113], v0 offset:36928
	ds_read_b128 v[114:117], v0 offset:41536
	ds_read_b128 v[118:121], v66 offset:55360
	ds_read_b128 v[130:133], v66 offset:59968
	s_waitcnt vmcnt(9)
	ds_write_b128 v67, v[86:89] offset:4608
	s_waitcnt vmcnt(8)
	ds_write_b128 v67, v[94:97] offset:23040
	global_load_dwordx4 v[86:89], v70, s[26:27]
	global_load_dwordx4 v[94:97], v70, s[2:3]
	s_waitcnt lgkmcnt(3)
	v_mfma_f32_32x32x16_bf16 v[2:17], v[114:117], v[118:121], v[2:17]
	s_waitcnt lgkmcnt(2)
	v_mfma_f32_32x32x16_bf16 v[18:33], v[114:117], v[130:133], v[18:33]
	v_mfma_f32_32x32x16_bf16 v[34:49], v[110:113], v[118:121], v[34:49]
	v_mfma_f32_32x32x16_bf16 v[50:65], v[110:113], v[130:133], v[50:65]
	ds_read_b128 v[110:113], v0 offset:36960
	ds_read_b128 v[118:121], v0 offset:41568
	ds_read_b128 v[122:125], v66 offset:55392
	ds_read_b128 v[126:129], v66 offset:60000
	s_waitcnt vmcnt(9)
	ds_write_b128 v67, v[90:93] offset:9216
	s_waitcnt vmcnt(8)
	ds_write_b128 v67, v[98:101] offset:27648
	global_load_dwordx4 v[90:93], v69, s[26:27]
	global_load_dwordx4 v[98:101], v69, s[2:3]
	s_waitcnt lgkmcnt(3)
	v_mfma_f32_32x32x16_bf16 v[2:17], v[118:121], v[122:125], v[2:17]
	s_waitcnt vmcnt(9)
	ds_write_b128 v67, v[74:77] offset:13824
	s_waitcnt vmcnt(8)
	ds_write_b128 v67, v[102:105] offset:32256
	s_waitcnt lgkmcnt(4)
	v_mfma_f32_32x32x16_bf16 v[18:33], v[118:121], v[126:129], v[18:33]
	v_mfma_f32_32x32x16_bf16 v[34:49], v[110:113], v[122:125], v[34:49]
	v_mfma_f32_32x32x16_bf16 v[50:65], v[110:113], v[126:129], v[50:65]
	s_waitcnt lgkmcnt(0)
	s_barrier
	ds_read_b128 v[74:77], v0
	ds_read_b128 v[102:105], v66 offset:18432
	ds_read_b128 v[110:113], v0 offset:32
	ds_read_b128 v[114:117], v66 offset:18464
	ds_read_b128 v[118:121], v0 offset:4608
	ds_read_b128 v[122:125], v0 offset:4640
	s_waitcnt lgkmcnt(4)
	v_mfma_f32_32x32x16_bf16 v[34:49], v[74:77], v[102:105], v[34:49]
	s_add_u32 s2, s36, 0x1200
	s_addc_u32 s3, s37, 0
	s_add_u32 s26, s0, 0x1200
	s_addc_u32 s27, s1, 0
	ds_read_b128 v[126:129], v66 offset:23072
	s_waitcnt lgkmcnt(2)
	v_mfma_f32_32x32x16_bf16 v[2:17], v[118:121], v[102:105], v[2:17]
	ds_read_b128 v[102:105], v66 offset:23040
	s_waitcnt lgkmcnt(0)
	v_mfma_f32_32x32x16_bf16 v[50:65], v[74:77], v[102:105], v[50:65]
	global_load_dwordx4 v[74:77], v72, s[26:27]
	global_load_dwordx4 v[130:133], v72, s[2:3]
	s_waitcnt vmcnt(9)
	ds_write_b128 v67, v[78:81] offset:36864
	s_waitcnt vmcnt(8)
	ds_write_b128 v67, v[134:137] offset:55296
	v_mfma_f32_32x32x16_bf16 v[18:33], v[118:121], v[102:105], v[18:33]
	global_load_dwordx4 v[78:81], v71, s[26:27]
	global_load_dwordx4 v[102:105], v71, s[2:3]
	v_mfma_f32_32x32x16_bf16 v[2:17], v[122:125], v[114:117], v[2:17]
	v_mfma_f32_32x32x16_bf16 v[18:33], v[122:125], v[126:129], v[18:33]
	v_mfma_f32_32x32x16_bf16 v[34:49], v[110:113], v[114:117], v[34:49]
	v_mfma_f32_32x32x16_bf16 v[50:65], v[110:113], v[126:129], v[50:65]
	ds_read_b128 v[110:113], v0 offset:64
	ds_read_b128 v[114:117], v0 offset:4672
	ds_read_b128 v[118:121], v66 offset:18496
	ds_read_b128 v[134:137], v66 offset:23104
	s_waitcnt vmcnt(9)
	ds_write_b128 v67, v[82:85] offset:41472
	s_waitcnt vmcnt(8)
	ds_write_b128 v67, v[106:109] offset:59904
	global_load_dwordx4 v[82:85], v70, s[26:27]
	global_load_dwordx4 v[106:109], v70, s[2:3]
	s_waitcnt lgkmcnt(3)
	v_mfma_f32_32x32x16_bf16 v[2:17], v[114:117], v[118:121], v[2:17]
	s_waitcnt lgkmcnt(2)
	v_mfma_f32_32x32x16_bf16 v[18:33], v[114:117], v[134:137], v[18:33]
	v_mfma_f32_32x32x16_bf16 v[34:49], v[110:113], v[118:121], v[34:49]
	v_mfma_f32_32x32x16_bf16 v[50:65], v[110:113], v[134:137], v[50:65]
	ds_read_b128 v[110:113], v0 offset:96
	ds_read_b128 v[118:121], v0 offset:4704
	ds_read_b128 v[122:125], v66 offset:18528
	ds_read_b128 v[126:129], v66 offset:23136
	s_waitcnt vmcnt(9)
	ds_write_b128 v67, v[86:89] offset:46080
	s_waitcnt vmcnt(8)
	ds_write_b128 v67, v[94:97] offset:64512
	global_load_dwordx4 v[86:89], v69, s[26:27]
	global_load_dwordx4 v[94:97], v69, s[2:3]
	s_waitcnt lgkmcnt(3)
	v_mfma_f32_32x32x16_bf16 v[2:17], v[118:121], v[122:125], v[2:17]
	s_waitcnt vmcnt(9)
	ds_write_b128 v67, v[90:93] offset:50688
	s_waitcnt vmcnt(8)
	ds_write_b128 v68, v[98:101] offset:13824
	s_waitcnt lgkmcnt(4)
	v_mfma_f32_32x32x16_bf16 v[18:33], v[118:121], v[126:129], v[18:33]
	v_mfma_f32_32x32x16_bf16 v[34:49], v[110:113], v[122:125], v[34:49]
	v_mfma_f32_32x32x16_bf16 v[50:65], v[110:113], v[126:129], v[50:65]
	s_waitcnt lgkmcnt(0)
	s_barrier
; #define GL1_(RA, RB, i) { RA[i] = *(const u32x4*)(ap + (aoff + (i) * astep)); if ((i) < NB) RB[(i) < NB ? (i) : 0] = *(const u32x4*)(bp + (boff + (i) * bstep)); }
; #define LS1_(RA, RB, ST, i) { char* sn_ = lds + (ST) * STAGE; *(u32x4*)(sn_ + wofs + (i) * 32 * LROW) = RA[i]; \
;                               if ((i) < NB) *(u32x4*)(sn_ + STAGE_OP + wofs + (i) * 32 * LROW) = RB[(i) < NB ? (i) : 0]; }
; template <int NJ> DI void gemm_mainloop_reg(const bf16_t* __restrict__ A, int lda, const bf16_t* __restrict__ Bt, int ldb, int K, f32x16 (&acc)[2][NJ], char* lds) {
;     ...
; #pragma unroll
;   for (int i = 0; i < 4; ++i) GL1_(ra0, rb0, i);
;   ap += 128; bp += 128;
; #pragma unroll
;   for (int i = 0; i < 4; ++i) GL1_(ra1, rb1, i);
;   ap += 128; bp += 128;
; #pragma unroll
;   for (int i = 0; i < 4; ++i) LS1_(ra0, rb0, 0, i);
;   __syncthreads();
;   const int nk = K >> 6;
;   for (int kt = 0; kt < nk; kt += 2) {
;     const bool l0 = (kt + 2 < nk), l1 = (kt + 3 < nk);
;     STEP_(0, l0, ra0, rb0, true, ra1, rb1);
;     __syncthreads();
;     STEP_(1, l1, ra1, rb1, l0, ra0, rb0);
;     __syncthreads();
;   }
	ds_read_b128 v[90:93], v0 offset:36864
	ds_read_b128 v[98:101], v66 offset:55296
	ds_read_b128 v[110:113], v0 offset:36896
	ds_read_b128 v[114:117], v66 offset:55328
	ds_read_b128 v[118:121], v0 offset:41472
	ds_read_b128 v[122:125], v0 offset:41504
	s_waitcnt lgkmcnt(4)
	v_mfma_f32_32x32x16_bf16 v[34:49], v[90:93], v[98:101], v[34:49]
	s_add_u32 s2, s36, 0x1280
	s_addc_u32 s3, s37, 0
	s_add_u32 s26, s0, 0x1280
	s_addc_u32 s27, s1, 0
	ds_read_b128 v[126:129], v66 offset:59936
	s_waitcnt lgkmcnt(2)
	v_mfma_f32_32x32x16_bf16 v[2:17], v[118:121], v[98:101], v[2:17]
	ds_read_b128 v[98:101], v66 offset:59904
	s_waitcnt lgkmcnt(0)
	v_mfma_f32_32x32x16_bf16 v[50:65], v[90:93], v[98:101], v[50:65]
	global_load_dwordx4 v[90:93], v72, s[26:27]
	global_load_dwordx4 v[134:137], v72, s[2:3]
	s_waitcnt vmcnt(9)
	ds_write_b128 v67, v[74:77]
	s_waitcnt vmcnt(8)
	ds_write_b128 v67, v[130:133] offset:18432
	v_mfma_f32_32x32x16_bf16 v[18:33], v[118:121], v[98:101], v[18:33]
	global_load_dwordx4 v[74:77], v71, s[26:27]
	global_load_dwordx4 v[98:101], v71, s[2:3]
	v_mfma_f32_32x32x16_bf16 v[2:17], v[122:125], v[114:117], v[2:17]
	v_mfma_f32_32x32x16_bf16 v[18:33], v[122:125], v[126:129], v[18:33]
	v_mfma_f32_32x32x16_bf16 v[34:49], v[110:113], v[114:117], v[34:49]
	v_mfma_f32_32x32x16_bf16 v[50:65], v[110:113], v[126:129], v[50:65]
	ds_read_b128 v[110:113], v0 offset:36928
	ds_read_b128 v[114:117], v0 offset:41536
	ds_read_b128 v[118:121], v66 offset:55360
	ds_read_b128 v[130:133], v66 offset:59968
	s_waitcnt vmcnt(9)
	ds_write_b128 v67, v[78:81] offset:4608
	s_waitcnt vmcnt(8)
	ds_write_b128 v67, v[102:105] offset:23040
	global_load_dwordx4 v[78:81], v70, s[26:27]
	global_load_dwordx4 v[102:105], v70, s[2:3]
	s_waitcnt lgkmcnt(3)
	v_mfma_f32_32x32x16_bf16 v[2:17], v[114:117], v[118:121], v[2:17]
	s_waitcnt lgkmcnt(2)
	v_mfma_f32_32x32x16_bf16 v[18:33], v[114:117], v[130:133], v[18:33]
	v_mfma_f32_32x32x16_bf16 v[34:49], v[110:113], v[118:121], v[34:49]
	v_mfma_f32_32x32x16_bf16 v[50:65], v[110:113], v[130:133], v[50:65]
	ds_read_b128 v[110:113], v0 offset:36960
	ds_read_b128 v[118:121], v0 offset:41568
	ds_read_b128 v[122:125], v66 offset:55392
	ds_read_b128 v[126:129], v66 offset:60000
	s_waitcnt vmcnt(9)
	ds_write_b128 v67, v[82:85] offset:9216
	s_waitcnt vmcnt(8)
	ds_write_b128 v67, v[106:109] offset:27648
	global_load_dwordx4 v[82:85], v69, s[26:27]
	global_load_dwordx4 v[106:109], v69, s[2:3]
	s_waitcnt lgkmcnt(3)
	v_mfma_f32_32x32x16_bf16 v[2:17], v[118:121], v[122:125], v[2:17]
	s_waitcnt vmcnt(9)
	ds_write_b128 v67, v[86:89] offset:13824
	s_waitcnt vmcnt(8)
	ds_write_b128 v67, v[94:97] offset:32256
	s_waitcnt lgkmcnt(4)
	v_mfma_f32_32x32x16_bf16 v[18:33], v[118:121], v[126:129], v[18:33]
	v_mfma_f32_32x32x16_bf16 v[34:49], v[110:113], v[122:125], v[34:49]
	v_mfma_f32_32x32x16_bf16 v[50:65], v[110:113], v[126:129], v[50:65]
	s_waitcnt lgkmcnt(0)
	s_barrier
	ds_read_b128 v[86:89], v0
	ds_read_b128 v[94:97], v66 offset:18432
	ds_read_b128 v[110:113], v0 offset:32
	ds_read_b128 v[114:117], v66 offset:18464
	ds_read_b128 v[118:121], v0 offset:4608
	ds_read_b128 v[122:125], v0 offset:4640
	s_waitcnt lgkmcnt(4)
	v_mfma_f32_32x32x16_bf16 v[34:49], v[86:89], v[94:97], v[34:49]
	s_add_u32 s2, s36, 0x1300
	s_addc_u32 s3, s37, 0
	s_add_u32 s26, s0, 0x1300
	s_addc_u32 s27, s1, 0
	ds_read_b128 v[126:129], v66 offset:23072
	s_waitcnt lgkmcnt(2)
	v_mfma_f32_32x32x16_bf16 v[2:17], v[118:121], v[94:97], v[2:17]
	ds_read_b128 v[94:97], v66 offset:23040
	s_waitcnt lgkmcnt(0)
	v_mfma_f32_32x32x16_bf16 v[50:65], v[86:89], v[94:97], v[50:65]
	global_load_dwordx4 v[86:89], v72, s[26:27]
	global_load_dwordx4 v[130:133], v72, s[2:3]
	s_waitcnt vmcnt(9)
	ds_write_b128 v67, v[90:93] offset:36864
	s_waitcnt vmcnt(8)
	ds_write_b128 v67, v[134:137] offset:55296
	v_mfma_f32_32x32x16_bf16 v[18:33], v[118:121], v[94:97], v[18:33]
	global_load_dwordx4 v[90:93], v71, s[26:27]
	global_load_dwordx4 v[94:97], v71, s[2:3]
	v_mfma_f32_32x32x16_bf16 v[2:17], v[122:125], v[114:117], v[2:17]
	v_mfma_f32_32x32x16_bf16 v[18:33], v[122:125], v[126:129], v[18:33]
	v_mfma_f32_32x32x16_bf16 v[34:49], v[110:113], v[114:117], v[34:49]
	v_mfma_f32_32x32x16_bf16 v[50:65], v[110:113], v[126:129], v[50:65]
	ds_read_b128 v[110:113], v0 offset:64
	ds_read_b128 v[114:117], v0 offset:4672
	ds_read_b128 v[118:121], v66 offset:18496
	ds_read_b128 v[134:137], v66 offset:23104
	s_waitcnt vmcnt(9)
	ds_write_b128 v67, v[74:77] offset:41472
	s_waitcnt vmcnt(8)
	ds_write_b128 v67, v[98:101] offset:59904
	global_load_dwordx4 v[74:77], v70, s[26:27]
	global_load_dwordx4 v[98:101], v70, s[2:3]
	s_waitcnt lgkmcnt(3)
	v_mfma_f32_32x32x16_bf16 v[2:17], v[114:117], v[118:121], v[2:17]
	s_waitcnt lgkmcnt(2)
	v_mfma_f32_32x32x16_bf16 v[18:33], v[114:117], v[134:137], v[18:33]
	v_mfma_f32_32x32x16_bf16 v[34:49], v[110:113], v[118:121], v[34:49]
	v_mfma_f32_32x32x16_bf16 v[50:65], v[110:113], v[134:137], v[50:65]
	ds_read_b128 v[110:113], v0 offset:96
	ds_read_b128 v[118:121], v0 offset:4704
	ds_read_b128 v[122:125], v66 offset:18528
	ds_read_b128 v[126:129], v66 offset:23136
	s_waitcnt vmcnt(9)
	ds_write_b128 v67, v[78:81] offset:46080
	s_waitcnt vmcnt(8)
	ds_write_b128 v67, v[102:105] offset:64512
	global_load_dwordx4 v[78:81], v69, s[26:27]
	global_load_dwordx4 v[102:105], v69, s[2:3]
	s_waitcnt lgkmcnt(3)
	v_mfma_f32_32x32x16_bf16 v[2:17], v[118:121], v[122:125], v[2:17]
	s_waitcnt vmcnt(9)
	ds_write_b128 v67, v[82:85] offset:50688
	s_waitcnt vmcnt(8)
	ds_write_b128 v68, v[106:109] offset:13824
	s_waitcnt lgkmcnt(4)
	v_mfma_f32_32x32x16_bf16 v[18:33], v[118:121], v[126:129], v[18:33]
	v_mfma_f32_32x32x16_bf16 v[34:49], v[110:113], v[122:125], v[34:49]
	v_mfma_f32_32x32x16_bf16 v[50:65], v[110:113], v[126:129], v[50:65]
	s_waitcnt lgkmcnt(0)
	s_barrier
; #define GL1_(RA, RB, i) { RA[i] = *(const u32x4*)(ap + (aoff + (i) * astep)); if ((i) < NB) RB[(i) < NB ? (i) : 0] = *(const u32x4*)(bp + (boff + (i) * bstep)); }
; #define LS1_(RA, RB, ST, i) { char* sn_ = lds + (ST) * STAGE; *(u32x4*)(sn_ + wofs + (i) * 32 * LROW) = RA[i]; \
;                               if ((i) < NB) *(u32x4*)(sn_ + STAGE_OP + wofs + (i) * 32 * LROW) = RB[(i) < NB ? (i) : 0]; }
; template <int NJ> DI void gemm_mainloop_reg(const bf16_t* __restrict__ A, int lda, const bf16_t* __restrict__ Bt, int ldb, int K, f32x16 (&acc)[2][NJ], char* lds) {
;     ...
; #pragma unroll
;   for (int i = 0; i < 4; ++i) GL1_(ra0, rb0, i);
;   ap += 128; bp += 128;
; #pragma unroll
;   for (int i = 0; i < 4; ++i) GL1_(ra1, rb1, i);
;   ap += 128; bp += 128;
; #pragma unroll
;   for (int i = 0; i < 4; ++i) LS1_(ra0, rb0, 0, i);
;   __syncthreads();
;   const int nk = K >> 6;
;   for (int kt = 0; kt < nk; kt += 2) {
;     const bool l0 = (kt + 2 < nk), l1 = (kt + 3 < nk);
;     STEP_(0, l0, ra0, rb0, true, ra1, rb1);
;     __syncthreads();
;     STEP_(1, l1, ra1, rb1, l0, ra0, rb0);
;     __syncthreads();
;   }
	ds_read_b128 v[82:85], v0 offset:36864
	ds_read_b128 v[106:109], v66 offset:55296
	ds_read_b128 v[110:113], v0 offset:36896
	ds_read_b128 v[114:117], v66 offset:55328
	ds_read_b128 v[118:121], v0 offset:41472
	ds_read_b128 v[122:125], v0 offset:41504
	s_waitcnt lgkmcnt(4)
	v_mfma_f32_32x32x16_bf16 v[34:49], v[82:85], v[106:109], v[34:49]
	s_add_u32 s2, s36, 0x1380
	s_addc_u32 s3, s37, 0
	s_add_u32 s26, s0, 0x1380
	s_addc_u32 s27, s1, 0
	ds_read_b128 v[126:129], v66 offset:59936
	s_waitcnt lgkmcnt(2)
	v_mfma_f32_32x32x16_bf16 v[2:17], v[118:121], v[106:109], v[2:17]
	ds_read_b128 v[106:109], v66 offset:59904
	s_waitcnt lgkmcnt(0)
	v_mfma_f32_32x32x16_bf16 v[50:65], v[82:85], v[106:109], v[50:65]
	global_load_dwordx4 v[82:85], v72, s[26:27]
	global_load_dwordx4 v[134:137], v72, s[2:3]
	s_waitcnt vmcnt(9)
	ds_write_b128 v67, v[86:89]
	s_waitcnt vmcnt(8)
	ds_write_b128 v67, v[130:133] offset:18432
	v_mfma_f32_32x32x16_bf16 v[18:33], v[118:121], v[106:109], v[18:33]
	global_load_dwordx4 v[86:89], v71, s[26:27]
	global_load_dwordx4 v[106:109], v71, s[2:3]
	v_mfma_f32_32x32x16_bf16 v[2:17], v[122:125], v[114:117], v[2:17]
	v_mfma_f32_32x32x16_bf16 v[18:33], v[122:125], v[126:129], v[18:33]
	v_mfma_f32_32x32x16_bf16 v[34:49], v[110:113], v[114:117], v[34:49]
	v_mfma_f32_32x32x16_bf16 v[50:65], v[110:113], v[126:129], v[50:65]
	ds_read_b128 v[110:113], v0 offset:36928
	ds_read_b128 v[114:117], v0 offset:41536
	ds_read_b128 v[118:121], v66 offset:55360
	ds_read_b128 v[130:133], v66 offset:59968
	s_waitcnt vmcnt(9)
	ds_write_b128 v67, v[90:93] offset:4608
	s_waitcnt vmcnt(8)
	ds_write_b128 v67, v[94:97] offset:23040
	global_load_dwordx4 v[90:93], v70, s[26:27]
	global_load_dwordx4 v[94:97], v70, s[2:3]
	s_waitcnt lgkmcnt(3)
	v_mfma_f32_32x32x16_bf16 v[2:17], v[114:117], v[118:121], v[2:17]
	s_waitcnt lgkmcnt(2)
	v_mfma_f32_32x32x16_bf16 v[18:33], v[114:117], v[130:133], v[18:33]
	v_mfma_f32_32x32x16_bf16 v[34:49], v[110:113], v[118:121], v[34:49]
	v_mfma_f32_32x32x16_bf16 v[50:65], v[110:113], v[130:133], v[50:65]
	ds_read_b128 v[110:113], v0 offset:36960
	ds_read_b128 v[118:121], v0 offset:41568
	ds_read_b128 v[122:125], v66 offset:55392
	ds_read_b128 v[126:129], v66 offset:60000
	s_waitcnt vmcnt(9)
	ds_write_b128 v67, v[74:77] offset:9216
	s_waitcnt vmcnt(8)
	ds_write_b128 v67, v[98:101] offset:27648
	global_load_dwordx4 v[74:77], v69, s[26:27]
	global_load_dwordx4 v[98:101], v69, s[2:3]
	s_waitcnt lgkmcnt(3)
	v_mfma_f32_32x32x16_bf16 v[2:17], v[118:121], v[122:125], v[2:17]
	s_waitcnt vmcnt(9)
	ds_write_b128 v67, v[78:81] offset:13824
	s_waitcnt vmcnt(8)
	ds_write_b128 v67, v[102:105] offset:32256
	s_waitcnt lgkmcnt(4)
	v_mfma_f32_32x32x16_bf16 v[18:33], v[118:121], v[126:129], v[18:33]
	v_mfma_f32_32x32x16_bf16 v[34:49], v[110:113], v[122:125], v[34:49]
	v_mfma_f32_32x32x16_bf16 v[50:65], v[110:113], v[126:129], v[50:65]
	s_waitcnt lgkmcnt(0)
	s_barrier
	ds_read_b128 v[78:81], v0
	ds_read_b128 v[102:105], v66 offset:18432
	ds_read_b128 v[110:113], v0 offset:32
	ds_read_b128 v[114:117], v66 offset:18464
	ds_read_b128 v[118:121], v0 offset:4608
	ds_read_b128 v[122:125], v0 offset:4640
	s_waitcnt lgkmcnt(4)
	v_mfma_f32_32x32x16_bf16 v[34:49], v[78:81], v[102:105], v[34:49]
	s_add_u32 s2, s36, 0x1400
	s_addc_u32 s3, s37, 0
	s_add_u32 s26, s0, 0x1400
	s_addc_u32 s27, s1, 0
	ds_read_b128 v[126:129], v66 offset:23072
	s_waitcnt lgkmcnt(2)
	v_mfma_f32_32x32x16_bf16 v[2:17], v[118:121], v[102:105], v[2:17]
	ds_read_b128 v[102:105], v66 offset:23040
	s_waitcnt lgkmcnt(0)
	v_mfma_f32_32x32x16_bf16 v[50:65], v[78:81], v[102:105], v[50:65]
	global_load_dwordx4 v[78:81], v72, s[26:27]
	global_load_dwordx4 v[130:133], v72, s[2:3]
	s_waitcnt vmcnt(9)
	ds_write_b128 v67, v[82:85] offset:36864
	s_waitcnt vmcnt(8)
	ds_write_b128 v67, v[134:137] offset:55296
	v_mfma_f32_32x32x16_bf16 v[18:33], v[118:121], v[102:105], v[18:33]
	global_load_dwordx4 v[82:85], v71, s[26:27]
	global_load_dwordx4 v[102:105], v71, s[2:3]
	v_mfma_f32_32x32x16_bf16 v[2:17], v[122:125], v[114:117], v[2:17]
	v_mfma_f32_32x32x16_bf16 v[18:33], v[122:125], v[126:129], v[18:33]
	v_mfma_f32_32x32x16_bf16 v[34:49], v[110:113], v[114:117], v[34:49]
	v_mfma_f32_32x32x16_bf16 v[50:65], v[110:113], v[126:129], v[50:65]
	ds_read_b128 v[110:113], v0 offset:64
	ds_read_b128 v[114:117], v0 offset:4672
	ds_read_b128 v[118:121], v66 offset:18496
	ds_read_b128 v[134:137], v66 offset:23104
	s_waitcnt vmcnt(9)
	ds_write_b128 v67, v[86:89] offset:41472
	s_waitcnt vmcnt(8)
	ds_write_b128 v67, v[106:109] offset:59904
	global_load_dwordx4 v[86:89], v70, s[26:27]
	global_load_dwordx4 v[106:109], v70, s[2:3]
	s_waitcnt lgkmcnt(3)
	v_mfma_f32_32x32x16_bf16 v[2:17], v[114:117], v[118:121], v[2:17]
	s_waitcnt lgkmcnt(2)
	v_mfma_f32_32x32x16_bf16 v[18:33], v[114:117], v[134:137], v[18:33]
	v_mfma_f32_32x32x16_bf16 v[34:49], v[110:113], v[118:121], v[34:49]
	v_mfma_f32_32x32x16_bf16 v[50:65], v[110:113], v[134:137], v[50:65]
	ds_read_b128 v[110:113], v0 offset:96
	ds_read_b128 v[118:121], v0 offset:4704
	ds_read_b128 v[122:125], v66 offset:18528
	ds_read_b128 v[126:129], v66 offset:23136
	s_waitcnt vmcnt(9)
	ds_write_b128 v67, v[90:93] offset:46080
	s_waitcnt vmcnt(8)
	ds_write_b128 v67, v[94:97] offset:64512
	global_load_dwordx4 v[90:93], v69, s[26:27]
	global_load_dwordx4 v[94:97], v69, s[2:3]
	s_waitcnt lgkmcnt(3)
	v_mfma_f32_32x32x16_bf16 v[2:17], v[118:121], v[122:125], v[2:17]
	s_waitcnt vmcnt(9)
	ds_write_b128 v67, v[74:77] offset:50688
	s_waitcnt vmcnt(8)
	ds_write_b128 v68, v[98:101] offset:13824
	s_waitcnt lgkmcnt(4)
	v_mfma_f32_32x32x16_bf16 v[18:33], v[118:121], v[126:129], v[18:33]
	v_mfma_f32_32x32x16_bf16 v[34:49], v[110:113], v[122:125], v[34:49]
	v_mfma_f32_32x32x16_bf16 v[50:65], v[110:113], v[126:129], v[50:65]
	s_waitcnt lgkmcnt(0)
	s_barrier
; #define GL1_(RA, RB, i) { RA[i] = *(const u32x4*)(ap + (aoff + (i) * astep)); if ((i) < NB) RB[(i) < NB ? (i) : 0] = *(const u32x4*)(bp + (boff + (i) * bstep)); }
; #define LS1_(RA, RB, ST, i) { char* sn_ = lds + (ST) * STAGE; *(u32x4*)(sn_ + wofs + (i) * 32 * LROW) = RA[i]; \
;                               if ((i) < NB) *(u32x4*)(sn_ + STAGE_OP + wofs + (i) * 32 * LROW) = RB[(i) < NB ? (i) : 0]; }
; template <int NJ> DI void gemm_mainloop_reg(const bf16_t* __restrict__ A, int lda, const bf16_t* __restrict__ Bt, int ldb, int K, f32x16 (&acc)[2][NJ], char* lds) {
;     ...
; #pragma unroll
;   for (int i = 0; i < 4; ++i) GL1_(ra0, rb0, i);
;   ap += 128; bp += 128;
; #pragma unroll
;   for (int i = 0; i < 4; ++i) GL1_(ra1, rb1, i);
;   ap += 128; bp += 128;
; #pragma unroll
;   for (int i = 0; i < 4; ++i) LS1_(ra0, rb0, 0, i);
;   __syncthreads();
;   const int nk = K >> 6;
;   for (int kt = 0; kt < nk; kt += 2) {
;     const bool l0 = (kt + 2 < nk), l1 = (kt + 3 < nk);
;     STEP_(0, l0, ra0, rb0, true, ra1, rb1);
;     __syncthreads();
;     STEP_(1, l1, ra1, rb1, l0, ra0, rb0);
;     __syncthreads();
;   }
	ds_read_b128 v[74:77], v0 offset:36864
	ds_read_b128 v[98:101], v66 offset:55296
	ds_read_b128 v[110:113], v0 offset:36896
	ds_read_b128 v[114:117], v66 offset:55328
	ds_read_b128 v[118:121], v0 offset:41472
	ds_read_b128 v[122:125], v0 offset:41504
	s_waitcnt lgkmcnt(4)
	v_mfma_f32_32x32x16_bf16 v[34:49], v[74:77], v[98:101], v[34:49]
	s_add_u32 s2, s36, 0x1480
	s_addc_u32 s3, s37, 0
	s_add_u32 s26, s0, 0x1480
	s_addc_u32 s27, s1, 0
	ds_read_b128 v[126:129], v66 offset:59936
	s_waitcnt lgkmcnt(2)
	v_mfma_f32_32x32x16_bf16 v[2:17], v[118:121], v[98:101], v[2:17]
	ds_read_b128 v[98:101], v66 offset:59904
	s_waitcnt lgkmcnt(0)
	v_mfma_f32_32x32x16_bf16 v[50:65], v[74:77], v[98:101], v[50:65]
	global_load_dwordx4 v[74:77], v72, s[26:27]
	global_load_dwordx4 v[134:137], v72, s[2:3]
	s_waitcnt vmcnt(9)
	ds_write_b128 v67, v[78:81]
	s_waitcnt vmcnt(8)
	ds_write_b128 v67, v[130:133] offset:18432
	v_mfma_f32_32x32x16_bf16 v[18:33], v[118:121], v[98:101], v[18:33]
	global_load_dwordx4 v[78:81], v71, s[26:27]
	global_load_dwordx4 v[98:101], v71, s[2:3]
	v_mfma_f32_32x32x16_bf16 v[2:17], v[122:125], v[114:117], v[2:17]
	v_mfma_f32_32x32x16_bf16 v[18:33], v[122:125], v[126:129], v[18:33]
	v_mfma_f32_32x32x16_bf16 v[34:49], v[110:113], v[114:117], v[34:49]
	v_mfma_f32_32x32x16_bf16 v[50:65], v[110:113], v[126:129], v[50:65]
	ds_read_b128 v[110:113], v0 offset:36928
	ds_read_b128 v[114:117], v0 offset:41536
	ds_read_b128 v[118:121], v66 offset:55360
	ds_read_b128 v[130:133], v66 offset:59968
	s_waitcnt vmcnt(9)
	ds_write_b128 v67, v[82:85] offset:4608
	s_waitcnt vmcnt(8)
	ds_write_b128 v67, v[102:105] offset:23040
	global_load_dwordx4 v[82:85], v70, s[26:27]
	global_load_dwordx4 v[102:105], v70, s[2:3]
	s_waitcnt lgkmcnt(3)
	v_mfma_f32_32x32x16_bf16 v[2:17], v[114:117], v[118:121], v[2:17]
	s_waitcnt lgkmcnt(2)
	v_mfma_f32_32x32x16_bf16 v[18:33], v[114:117], v[130:133], v[18:33]
	v_mfma_f32_32x32x16_bf16 v[34:49], v[110:113], v[118:121], v[34:49]
	v_mfma_f32_32x32x16_bf16 v[50:65], v[110:113], v[130:133], v[50:65]
	ds_read_b128 v[110:113], v0 offset:36960
	ds_read_b128 v[118:121], v0 offset:41568
	ds_read_b128 v[122:125], v66 offset:55392
	ds_read_b128 v[126:129], v66 offset:60000
	s_waitcnt vmcnt(9)
	ds_write_b128 v67, v[86:89] offset:9216
	s_waitcnt vmcnt(8)
	ds_write_b128 v67, v[106:109] offset:27648
	global_load_dwordx4 v[86:89], v69, s[26:27]
	global_load_dwordx4 v[106:109], v69, s[2:3]
	s_waitcnt lgkmcnt(3)
	v_mfma_f32_32x32x16_bf16 v[2:17], v[118:121], v[122:125], v[2:17]
	s_waitcnt vmcnt(9)
	ds_write_b128 v67, v[90:93] offset:13824
	s_waitcnt vmcnt(8)
	ds_write_b128 v67, v[94:97] offset:32256
	s_waitcnt lgkmcnt(4)
	v_mfma_f32_32x32x16_bf16 v[18:33], v[118:121], v[126:129], v[18:33]
	v_mfma_f32_32x32x16_bf16 v[34:49], v[110:113], v[122:125], v[34:49]
	v_mfma_f32_32x32x16_bf16 v[50:65], v[110:113], v[126:129], v[50:65]
	s_waitcnt lgkmcnt(0)
	s_barrier
	ds_read_b128 v[90:93], v0
	ds_read_b128 v[94:97], v66 offset:18432
	ds_read_b128 v[110:113], v0 offset:32
	ds_read_b128 v[114:117], v66 offset:18464
	ds_read_b128 v[118:121], v0 offset:4608
	ds_read_b128 v[122:125], v0 offset:4640
	s_waitcnt lgkmcnt(4)
	v_mfma_f32_32x32x16_bf16 v[34:49], v[90:93], v[94:97], v[34:49]
	s_add_u32 s2, s36, 0x1500
	s_addc_u32 s3, s37, 0
	s_add_u32 s26, s0, 0x1500
	s_addc_u32 s27, s1, 0
	ds_read_b128 v[126:129], v66 offset:23072
	s_waitcnt lgkmcnt(2)
	v_mfma_f32_32x32x16_bf16 v[2:17], v[118:121], v[94:97], v[2:17]
	ds_read_b128 v[94:97], v66 offset:23040
	s_waitcnt lgkmcnt(0)
	v_mfma_f32_32x32x16_bf16 v[50:65], v[90:93], v[94:97], v[50:65]
	global_load_dwordx4 v[90:93], v72, s[26:27]
	global_load_dwordx4 v[130:133], v72, s[2:3]
	s_waitcnt vmcnt(9)
	ds_write_b128 v67, v[74:77] offset:36864
	s_waitcnt vmcnt(8)
	ds_write_b128 v67, v[134:137] offset:55296
	v_mfma_f32_32x32x16_bf16 v[18:33], v[118:121], v[94:97], v[18:33]
	global_load_dwordx4 v[74:77], v71, s[26:27]
	global_load_dwordx4 v[94:97], v71, s[2:3]
	v_mfma_f32_32x32x16_bf16 v[2:17], v[122:125], v[114:117], v[2:17]
	v_mfma_f32_32x32x16_bf16 v[18:33], v[122:125], v[126:129], v[18:33]
	v_mfma_f32_32x32x16_bf16 v[34:49], v[110:113], v[114:117], v[34:49]
	v_mfma_f32_32x32x16_bf16 v[50:65], v[110:113], v[126:129], v[50:65]
	ds_read_b128 v[110:113], v0 offset:64
	ds_read_b128 v[114:117], v0 offset:4672
	ds_read_b128 v[118:121], v66 offset:18496
	ds_read_b128 v[134:137], v66 offset:23104
	s_waitcnt vmcnt(9)
	ds_write_b128 v67, v[78:81] offset:41472
	s_waitcnt vmcnt(8)
	ds_write_b128 v67, v[98:101] offset:59904
	global_load_dwordx4 v[78:81], v70, s[26:27]
	global_load_dwordx4 v[98:101], v70, s[2:3]
	s_waitcnt lgkmcnt(3)
	v_mfma_f32_32x32x16_bf16 v[2:17], v[114:117], v[118:121], v[2:17]
	s_waitcnt lgkmcnt(2)
	v_mfma_f32_32x32x16_bf16 v[18:33], v[114:117], v[134:137], v[18:33]
	v_mfma_f32_32x32x16_bf16 v[34:49], v[110:113], v[118:121], v[34:49]
	v_mfma_f32_32x32x16_bf16 v[50:65], v[110:113], v[134:137], v[50:65]
	ds_read_b128 v[110:113], v0 offset:96
	ds_read_b128 v[118:121], v0 offset:4704
	ds_read_b128 v[122:125], v66 offset:18528
	ds_read_b128 v[126:129], v66 offset:23136
	s_waitcnt vmcnt(9)
	ds_write_b128 v67, v[82:85] offset:46080
	s_waitcnt vmcnt(8)
	ds_write_b128 v67, v[102:105] offset:64512
	global_load_dwordx4 v[82:85], v69, s[26:27]
	global_load_dwordx4 v[102:105], v69, s[2:3]
	s_waitcnt lgkmcnt(3)
	v_mfma_f32_32x32x16_bf16 v[2:17], v[118:121], v[122:125], v[2:17]
	s_waitcnt vmcnt(9)
	ds_write_b128 v67, v[86:89] offset:50688
	s_waitcnt vmcnt(8)
	ds_write_b128 v68, v[106:109] offset:13824
	s_waitcnt lgkmcnt(4)
	v_mfma_f32_32x32x16_bf16 v[18:33], v[118:121], v[126:129], v[18:33]
	v_mfma_f32_32x32x16_bf16 v[34:49], v[110:113], v[122:125], v[34:49]
	v_mfma_f32_32x32x16_bf16 v[50:65], v[110:113], v[126:129], v[50:65]
	s_waitcnt lgkmcnt(0)
	s_barrier
; #define GL1_(RA, RB, i) { RA[i] = *(const u32x4*)(ap + (aoff + (i) * astep)); if ((i) < NB) RB[(i) < NB ? (i) : 0] = *(const u32x4*)(bp + (boff + (i) * bstep)); }
; #define LS1_(RA, RB, ST, i) { char* sn_ = lds + (ST) * STAGE; *(u32x4*)(sn_ + wofs + (i) * 32 * LROW) = RA[i]; \
;                               if ((i) < NB) *(u32x4*)(sn_ + STAGE_OP + wofs + (i) * 32 * LROW) = RB[(i) < NB ? (i) : 0]; }
; template <int NJ> DI void gemm_mainloop_reg(const bf16_t* __restrict__ A, int lda, const bf16_t* __restrict__ Bt, int ldb, int K, f32x16 (&acc)[2][NJ], char* lds) {
;     ...
; #pragma unroll
;   for (int i = 0; i < 4; ++i) GL1_(ra0, rb0, i);
;   ap += 128; bp += 128;
; #pragma unroll
;   for (int i = 0; i < 4; ++i) GL1_(ra1, rb1, i);
;   ap += 128; bp += 128;
; #pragma unroll
;   for (int i = 0; i < 4; ++i) LS1_(ra0, rb0, 0, i);
;   __syncthreads();
;   const int nk = K >> 6;
;   for (int kt = 0; kt < nk; kt += 2) {
;     const bool l0 = (kt + 2 < nk), l1 = (kt + 3 < nk);
;     STEP_(0, l0, ra0, rb0, true, ra1, rb1);
;     __syncthreads();
;     STEP_(1, l1, ra1, rb1, l0, ra0, rb0);
;     __syncthreads();
;   }
	ds_read_b128 v[86:89], v0 offset:36864
	ds_read_b128 v[106:109], v66 offset:55296
	ds_read_b128 v[110:113], v0 offset:41472
	s_waitcnt lgkmcnt(1)
	v_mfma_f32_32x32x16_bf16 v[34:49], v[86:89], v[106:109], v[34:49]
	s_add_u32 s2, s36, 0x1580
	s_addc_u32 s3, s37, 0
	s_add_u32 s0, s0, 0x1580
	s_addc_u32 s1, s1, 0
	s_waitcnt lgkmcnt(0)
	v_mfma_f32_32x32x16_bf16 v[2:17], v[110:113], v[106:109], v[2:17]
	ds_read_b128 v[106:109], v66 offset:59904
	s_waitcnt lgkmcnt(0)
	v_mfma_f32_32x32x16_bf16 v[50:65], v[86:89], v[106:109], v[50:65]
	global_load_dwordx4 v[86:89], v72, s[0:1]
	global_load_dwordx4 v[114:117], v72, s[2:3]
	ds_read_b128 v[118:121], v0 offset:36896
	ds_read_b128 v[122:125], v66 offset:55328
	ds_read_b128 v[126:129], v0 offset:41504
	ds_read_b128 v[134:137], v66 offset:59936
	s_waitcnt vmcnt(9)
	ds_write_b128 v67, v[90:93]
	s_waitcnt vmcnt(8)
	ds_write_b128 v67, v[130:133] offset:18432
	v_mfma_f32_32x32x16_bf16 v[18:33], v[110:113], v[106:109], v[18:33]
	global_load_dwordx4 v[90:93], v71, s[0:1]
	global_load_dwordx4 v[106:109], v71, s[2:3]
	s_waitcnt lgkmcnt(3)
	v_mfma_f32_32x32x16_bf16 v[2:17], v[126:129], v[122:125], v[2:17]
	s_waitcnt lgkmcnt(2)
	v_mfma_f32_32x32x16_bf16 v[18:33], v[126:129], v[134:137], v[18:33]
	v_mfma_f32_32x32x16_bf16 v[34:49], v[118:121], v[122:125], v[34:49]
	v_mfma_f32_32x32x16_bf16 v[50:65], v[118:121], v[134:137], v[50:65]
	ds_read_b128 v[110:113], v0 offset:36928
	ds_read_b128 v[118:121], v0 offset:41536
	ds_read_b128 v[122:125], v66 offset:55360
	ds_read_b128 v[130:133], v66 offset:59968
	s_waitcnt vmcnt(9)
	ds_write_b128 v67, v[74:77] offset:4608
	s_waitcnt vmcnt(8)
	ds_write_b128 v67, v[94:97] offset:23040
	global_load_dwordx4 v[72:75], v70, s[0:1]
	global_load_dwordx4 v[94:97], v70, s[2:3]
	s_waitcnt lgkmcnt(3)
	v_mfma_f32_32x32x16_bf16 v[2:17], v[118:121], v[122:125], v[2:17]
	s_waitcnt lgkmcnt(2)
	v_mfma_f32_32x32x16_bf16 v[18:33], v[118:121], v[130:133], v[18:33]
	v_mfma_f32_32x32x16_bf16 v[34:49], v[110:113], v[122:125], v[34:49]
	v_mfma_f32_32x32x16_bf16 v[50:65], v[110:113], v[130:133], v[50:65]
	ds_read_b128 v[110:113], v0 offset:36960
	ds_read_b128 v[122:125], v0 offset:41568
	ds_read_b128 v[126:129], v66 offset:55392
	ds_read_b128 v[134:137], v66 offset:60000
	s_waitcnt vmcnt(9)
	ds_write_b128 v67, v[78:81] offset:9216
	s_waitcnt vmcnt(8)
	ds_write_b128 v67, v[98:101] offset:27648
	global_load_dwordx4 v[76:79], v69, s[0:1]
	global_load_dwordx4 v[98:101], v69, s[2:3]
	s_waitcnt lgkmcnt(3)
	v_mfma_f32_32x32x16_bf16 v[2:17], v[122:125], v[126:129], v[2:17]
	s_waitcnt vmcnt(9)
	ds_write_b128 v67, v[82:85] offset:13824
	s_waitcnt vmcnt(8)
	ds_write_b128 v67, v[102:105] offset:32256
	s_waitcnt lgkmcnt(4)
	v_mfma_f32_32x32x16_bf16 v[18:33], v[122:125], v[134:137], v[18:33]
	v_mfma_f32_32x32x16_bf16 v[34:49], v[110:113], v[126:129], v[34:49]
	v_mfma_f32_32x32x16_bf16 v[50:65], v[110:113], v[134:137], v[50:65]
	s_waitcnt lgkmcnt(0)
	s_barrier
	ds_read_b128 v[80:83], v0
	ds_read_b128 v[102:105], v66 offset:18432
	ds_read_b128 v[110:113], v0 offset:4608
	s_waitcnt lgkmcnt(1)
	v_mfma_f32_32x32x16_bf16 v[34:49], v[80:83], v[102:105], v[34:49]
	s_waitcnt lgkmcnt(0)
	v_mfma_f32_32x32x16_bf16 v[2:17], v[110:113], v[102:105], v[2:17]
	ds_read_b128 v[102:105], v66 offset:23040
	s_waitcnt lgkmcnt(0)
	v_mfma_f32_32x32x16_bf16 v[18:33], v[110:113], v[102:105], v[18:33]
	v_mfma_f32_32x32x16_bf16 v[50:65], v[80:83], v[102:105], v[50:65]
	ds_read_b128 v[80:83], v0 offset:32
	ds_read_b128 v[118:121], v66 offset:18464
	ds_read_b128 v[122:125], v0 offset:4640
	ds_read_b128 v[126:129], v66 offset:23072
	s_waitcnt vmcnt(7)
	ds_write_b128 v67, v[86:89] offset:36864
	s_waitcnt vmcnt(6)
	ds_write_b128 v67, v[114:117] offset:55296
	s_waitcnt lgkmcnt(3)
	v_mfma_f32_32x32x16_bf16 v[2:17], v[122:125], v[118:121], v[2:17]
	s_waitcnt lgkmcnt(2)
	v_mfma_f32_32x32x16_bf16 v[18:33], v[122:125], v[126:129], v[18:33]
	v_mfma_f32_32x32x16_bf16 v[34:49], v[80:83], v[118:121], v[34:49]
	v_mfma_f32_32x32x16_bf16 v[50:65], v[80:83], v[126:129], v[50:65]
	ds_read_b128 v[80:83], v0 offset:64
	ds_read_b128 v[84:87], v0 offset:4672
	ds_read_b128 v[102:105], v66 offset:18496
	ds_read_b128 v[110:113], v66 offset:23104
	s_waitcnt vmcnt(5)
	ds_write_b128 v67, v[90:93] offset:41472
	s_waitcnt vmcnt(4)
	ds_write_b128 v67, v[106:109] offset:59904
	s_waitcnt lgkmcnt(3)
	v_mfma_f32_32x32x16_bf16 v[2:17], v[84:87], v[102:105], v[2:17]
	s_waitcnt lgkmcnt(2)
	v_mfma_f32_32x32x16_bf16 v[18:33], v[84:87], v[110:113], v[18:33]
	v_mfma_f32_32x32x16_bf16 v[34:49], v[80:83], v[102:105], v[34:49]
	v_mfma_f32_32x32x16_bf16 v[50:65], v[80:83], v[110:113], v[50:65]
	ds_read_b128 v[80:83], v0 offset:96
	ds_read_b128 v[88:91], v0 offset:4704
	ds_read_b128 v[102:105], v66 offset:18528
	ds_read_b128 v[106:109], v66 offset:23136
	s_waitcnt vmcnt(3)
	ds_write_b128 v67, v[72:75] offset:46080
	s_waitcnt vmcnt(2)
	ds_write_b128 v67, v[94:97] offset:64512
	s_waitcnt lgkmcnt(3)
	v_mfma_f32_32x32x16_bf16 v[2:17], v[88:91], v[102:105], v[2:17]
	s_waitcnt vmcnt(1)
	ds_write_b128 v67, v[76:79] offset:50688
	s_waitcnt vmcnt(0)
	ds_write_b128 v68, v[98:101] offset:13824
	s_waitcnt lgkmcnt(4)
	v_mfma_f32_32x32x16_bf16 v[18:33], v[88:91], v[106:109], v[18:33]
	v_mfma_f32_32x32x16_bf16 v[34:49], v[80:83], v[102:105], v[34:49]
	v_mfma_f32_32x32x16_bf16 v[50:65], v[80:83], v[106:109], v[50:65]
	s_waitcnt lgkmcnt(0)
	s_barrier
; DI int tid_() { int t = threadIdx.x; asm volatile("" : "+v"(t)); return t; }
; #define GL1_(RA, RB, i) { RA[i] = *(const u32x4*)(ap + (aoff + (i) * astep)); if ((i) < NB) RB[(i) < NB ? (i) : 0] = *(const u32x4*)(bp + (boff + (i) * bstep)); }
; #define LS1_(RA, RB, ST, i) { char* sn_ = lds + (ST) * STAGE; *(u32x4*)(sn_ + wofs + (i) * 32 * LROW) = RA[i]; \
;                               if ((i) < NB) *(u32x4*)(sn_ + STAGE_OP + wofs + (i) * 32 * LROW) = RB[(i) < NB ? (i) : 0]; }
; template <int NJ> DI void gemm_mainloop_reg(const bf16_t* __restrict__ A, int lda, const bf16_t* __restrict__ Bt, int ldb, int K, f32x16 (&acc)[2][NJ], char* lds) {
;     ...
; #pragma unroll
;   for (int i = 0; i < 4; ++i) GL1_(ra0, rb0, i);
;   ap += 128; bp += 128;
; #pragma unroll
;   for (int i = 0; i < 4; ++i) GL1_(ra1, rb1, i);
;   ap += 128; bp += 128;
; #pragma unroll
;   for (int i = 0; i < 4; ++i) LS1_(ra0, rb0, 0, i);
;   __syncthreads();
;   const int nk = K >> 6;
;   for (int kt = 0; kt < nk; kt += 2) {
;     const bool l0 = (kt + 2 < nk), l1 = (kt + 3 < nk);
;     STEP_(0, l0, ra0, rb0, true, ra1, rb1);
;     __syncthreads();
;     STEP_(1, l1, ra1, rb1, l0, ra0, rb0);
;     __syncthreads();
;   }
; template <int NJ> DI void acc_to_lds(const f32x16 (&acc)[2][NJ], float* cl) {
;   const int tid = tid_(), lane = tid & 63, w = tid >> 6, wm = w >> 1, wn = w & 1, h = lane >> 5, c = lane & 31;
; #pragma unroll
;   for (int i = 0; i < 2; ++i)
; #pragma unroll
;     for (int j = 0; j < NJ; ++j)
; #pragma unroll
;       for (int r = 0; r < 16; ++r) {
;         const int row = wm * 64 + i * 32 + (r & 3) + 8 * (r >> 2) + 4 * h;
;         cl[row * CLD + wn * 32 * NJ + j * 32 + c] = acc[i][j][r];
;       }
; }
; template <int NJ> DI void resid_epilogue(float* __restrict__ x, bf16_t* __restrict__ xb, float* __restrict__ ssn, int mt, int nt, const float* cl, float scale) {
;   constexpr int LPR = 16 * NJ, RPP = 256 / LPR, NP = 128 / RPP;
;   const int tid = tid_(), c4 = (tid & (LPR - 1)) * 4, r0 = tid / LPR;
; #pragma unroll 4
;   for (int it = 0; it < NP; ++it) {
;     const int row = r0 + RPP * it;
;     const f32x4 c = *(const f32x4*)(cl + row * CLD + c4);
;     const size_t gi = (size_t)(mt * 128 + row) * DM + nt * (64 * NJ) + c4;
	ds_read_b128 v[68:71], v0 offset:36864
	ds_read_b128 v[72:75], v66 offset:55296
	ds_read_b128 v[76:79], v0 offset:41472
	s_waitcnt lgkmcnt(1)
	v_mfma_f32_32x32x16_bf16 v[34:49], v[68:71], v[72:75], v[34:49]
	s_waitcnt lgkmcnt(0)
	v_mfma_f32_32x32x16_bf16 v[2:17], v[76:79], v[72:75], v[2:17]
	ds_read_b128 v[72:75], v66 offset:59904
	s_waitcnt lgkmcnt(0)
	v_mfma_f32_32x32x16_bf16 v[18:33], v[76:79], v[72:75], v[18:33]
	v_mfma_f32_32x32x16_bf16 v[50:65], v[68:71], v[72:75], v[50:65]
	ds_read_b128 v[68:71], v0 offset:36896
	ds_read_b128 v[80:83], v66 offset:55328
	ds_read_b128 v[84:87], v0 offset:41504
	ds_read_b128 v[88:91], v66 offset:59936
	s_waitcnt lgkmcnt(1)
	v_mfma_f32_32x32x16_bf16 v[2:17], v[84:87], v[80:83], v[2:17]
	s_waitcnt lgkmcnt(0)
	v_mfma_f32_32x32x16_bf16 v[18:33], v[84:87], v[88:91], v[18:33]
	v_mfma_f32_32x32x16_bf16 v[34:49], v[68:71], v[80:83], v[34:49]
	v_mfma_f32_32x32x16_bf16 v[50:65], v[68:71], v[88:91], v[50:65]
	ds_read_b128 v[68:71], v0 offset:36928
	ds_read_b128 v[72:75], v0 offset:41536
	ds_read_b128 v[76:79], v66 offset:55360
	ds_read_b128 v[80:83], v66 offset:59968
	s_waitcnt lgkmcnt(1)
	v_mfma_f32_32x32x16_bf16 v[2:17], v[72:75], v[76:79], v[2:17]
	s_waitcnt lgkmcnt(0)
	v_mfma_f32_32x32x16_bf16 v[18:33], v[72:75], v[80:83], v[18:33]
	v_mfma_f32_32x32x16_bf16 v[34:49], v[68:71], v[76:79], v[34:49]
	v_mfma_f32_32x32x16_bf16 v[50:65], v[68:71], v[80:83], v[50:65]
	ds_read_b128 v[68:71], v0 offset:36960
	ds_read_b128 v[76:79], v0 offset:41568
	ds_read_b128 v[84:87], v66 offset:55392
	ds_read_b128 v[88:91], v66 offset:60000
	s_waitcnt lgkmcnt(1)
	v_mfma_f32_32x32x16_bf16 v[2:17], v[76:79], v[84:87], v[2:17]
	s_waitcnt lgkmcnt(0)
	v_mfma_f32_32x32x16_bf16 v[18:33], v[76:79], v[88:91], v[18:33]
	v_mfma_f32_32x32x16_bf16 v[34:49], v[68:71], v[84:87], v[34:49]
	v_mfma_f32_32x32x16_bf16 v[50:65], v[68:71], v[88:91], v[50:65]
	s_setprio 0
	v_mov_b32_e32 v0, v199
	s_barrier
	s_add_i32 s0, s38, s11
	v_lshrrev_b32_e32 v67, 3, v0
	v_lshrrev_b32_e32 v66, 1, v0
	v_and_b32_e32 v67, 4, v67
	v_and_b32_e32 v0, 0x5f, v0
	v_and_or_b32 v66, v66, s17, v67
	v_mul_lo_u32 v66, v66, s15
	v_lshlrev_b32_e32 v0, 2, v0
	v_add3_u32 v0, 0, v66, v0
	s_nop 0
	ds_write2_b32 v0, v34, v50 offset1:32
	ds_write2_b32 v0, v35, v51 offset0:132 offset1:164
	v_add_u32_e32 v34, 0x400, v0
	ds_write2_b32 v34, v36, v52 offset0:8 offset1:40
	ds_write2_b32 v34, v37, v53 offset0:140 offset1:172
	v_add_u32_e32 v34, 0x1000, v0
	ds_write2_b32 v34, v38, v54 offset0:32 offset1:64
	ds_write2_b32 v34, v39, v55 offset0:164 offset1:196
	v_add_u32_e32 v34, 0x1400, v0
	ds_write2_b32 v34, v40, v56 offset0:40 offset1:72
	ds_write2_b32 v34, v41, v57 offset0:172 offset1:204
	v_add_u32_e32 v34, 0x2000, v0
	ds_write2_b32 v34, v42, v58 offset0:64 offset1:96
	ds_write2_b32 v34, v43, v59 offset0:196 offset1:228
	v_add_u32_e32 v34, 0x2400, v0
	ds_write2_b32 v34, v44, v60 offset0:72 offset1:104
	ds_write2_b32 v34, v45, v61 offset0:204 offset1:236
	v_add_u32_e32 v34, 0x3000, v0
	ds_write2_b32 v34, v46, v62 offset0:96 offset1:128
	v_add_u32_e32 v34, 0x3200, v0
	ds_write2_b32 v34, v47, v63 offset0:100 offset1:132
	v_add_u32_e32 v34, 0x3400, v0
	ds_write2_b32 v34, v48, v64 offset0:104 offset1:136
	v_add_u32_e32 v34, 0x3600, v0
	ds_write2_b32 v34, v49, v65 offset0:108 offset1:140
	v_add_u32_e32 v34, 0x4000, v0
	ds_write2_b32 v34, v2, v18 offset0:128 offset1:160
	v_add_u32_e32 v2, 0x4400, v0
	ds_write2_b32 v2, v3, v19 offset0:4 offset1:36
	ds_write2_b32 v2, v4, v20 offset0:136 offset1:168
	v_add_u32_e32 v2, 0x4800, v0
	ds_write2_b32 v2, v5, v21 offset0:12 offset1:44
	v_add_u32_e32 v2, 0x5000, v0
	ds_write2_b32 v2, v6, v22 offset0:160 offset1:192
	v_add_u32_e32 v2, 0x5400, v0
	ds_write2_b32 v2, v7, v23 offset0:36 offset1:68
	ds_write2_b32 v2, v8, v24 offset0:168 offset1:200
	v_add_u32_e32 v2, 0x5800, v0
	ds_write2_b32 v2, v9, v25 offset0:44 offset1:76
	v_add_u32_e32 v2, 0x6000, v0
	ds_write2_b32 v2, v10, v26 offset0:192 offset1:224
	v_add_u32_e32 v2, 0x6400, v0
	ds_write2_b32 v2, v11, v27 offset0:68 offset1:100
	ds_write2_b32 v2, v12, v28 offset0:200 offset1:232
	v_add_u32_e32 v2, 0x6800, v0
	ds_write2_b32 v2, v13, v29 offset0:76 offset1:108
	v_add_u32_e32 v2, 0x7200, v0
	ds_write2_b32 v2, v14, v30 offset0:96 offset1:128
	v_add_u32_e32 v2, 0x7400, v0
	ds_write2_b32 v2, v15, v31 offset0:100 offset1:132
	v_add_u32_e32 v2, 0x7600, v0
	v_add_u32_e32 v0, 0x7800, v0
	ds_write2_b32 v0, v17, v33 offset0:108 offset1:140
	v_mov_b32_e32 v0, v199
	ds_write2_b32 v2, v16, v32 offset0:104 offset1:136
	s_waitcnt lgkmcnt(0)
	s_barrier
	v_mov_b64_e32 v[18:19], s[72:73]
	v_ashrrev_i32_e32 v2, 31, v0
	v_lshrrev_b32_e32 v2, 27, v2
	v_and_b32_e32 v6, 31, v0
	v_add_u32_e32 v0, v0, v2
	v_ashrrev_i32_e32 v14, 5, v0
	v_add_u32_e32 v4, s0, v14
	v_mad_i64_i32 v[2:3], s[0:1], v4, s9, v[18:19]
	v_cmp_lt_i32_e32 vcc, v222, v220
	s_add_i32 s0, s38, s12
	v_add_u32_e32 v10, s0, v14
	v_cndmask_b32_e32 v0, v219, v222, vcc
	v_cmp_lt_i32_e32 vcc, v223, v220
	v_lshlrev_b32_e32 v22, 2, v0
	v_mad_i64_i32 v[8:9], s[0:1], v10, s9, v[18:19]
	v_cndmask_b32_e32 v0, v219, v223, vcc
	v_cmp_lt_i32_e32 vcc, v224, v220
	v_lshlrev_b32_e32 v23, 2, v0
	s_add_u32 s0, s39, s6
	v_cndmask_b32_e32 v0, v219, v224, vcc
	v_cmp_lt_i32_e32 vcc, v225, v220
	v_lshlrev_b32_e32 v24, 2, v0
	s_addc_u32 s1, 0, s7
	v_cndmask_b32_e32 v0, v219, v225, vcc
	v_cmp_lt_i32_e32 vcc, v226, v220
	s_add_i32 s38, s38, s13
	v_lshlrev_b32_e32 v25, 2, v0
	v_cndmask_b32_e32 v0, v219, v226, vcc
	v_add_u32_e32 v20, s40, v14
	v_add_u32_e32 v16, s38, v14
	v_lshlrev_b32_e32 v26, 2, v0
	v_cmp_eq_u32_e32 vcc, 0, v6
	v_ashrrev_i32_e32 v15, 31, v14
	v_ashrrev_i32_e32 v5, 31, v4
	v_lshlrev_b32_e32 v0, 3, v6
	v_lshlrev_b32_e32 v28, 4, v6
	v_mul_lo_u32 v6, v14, s15
	v_ashrrev_i32_e32 v21, 31, v20
	v_ashrrev_i32_e32 v11, 31, v10
	v_ashrrev_i32_e32 v17, 31, v16
	v_lshlrev_b64 v[4:5], 12, v[4:5]
	v_add3_u32 v27, v6, v28, 0
	v_lshlrev_b64 v[6:7], 12, v[20:21]
	v_lshlrev_b64 v[10:11], 12, v[10:11]
	v_lshl_add_u64 v[12:13], v[14:15], 2, s[0:1]
	v_mad_i64_i32 v[14:15], s[0:1], v16, s9, v[18:19]
	v_lshlrev_b64 v[16:17], 12, v[16:17]
	v_mad_i64_i32 v[18:19], s[0:1], v20, s9, v[18:19]
	v_lshl_add_u64 v[2:3], v[2:3], 0, v[0:1]
	v_or3_b32 v4, v4, s35, v28
	v_or3_b32 v6, v6, s35, v28
	v_lshl_add_u64 v[8:9], v[8:9], 0, v[0:1]
	v_or3_b32 v10, v10, s35, v28
	v_lshl_add_u64 v[14:15], v[14:15], 0, v[0:1]
	v_or3_b32 v16, v16, s35, v28
	v_lshl_add_u64 v[18:19], v[18:19], 0, v[0:1]
	v_lshl_add_u64 v[2:3], v[2:3], 0, s[80:81]
	v_lshl_add_u64 v[4:5], s[92:93], 0, v[4:5]
	v_lshl_add_u64 v[6:7], s[92:93], 0, v[6:7]
	v_lshl_add_u64 v[8:9], v[8:9], 0, s[80:81]
	v_lshl_add_u64 v[10:11], s[92:93], 0, v[10:11]
	v_lshl_add_u64 v[14:15], v[14:15], 0, s[80:81]
	v_lshl_add_u64 v[16:17], s[92:93], 0, v[16:17]
	v_lshl_add_u64 v[18:19], v[18:19], 0, s[80:81]
	s_mov_b64 s[0:1], 0
	s_branch .LBB0_1158

; #define MFMA(a, b, c) __builtin_amdgcn_mfma_f32_32x32x16_bf16((a), (b), (c), 0, 0, 0)
; template <int NJ> DI void gemm_mainloop_glds(const bf16_t* __restrict__ A, int lda, const bf16_t* __restrict__ Bt, int ldb, int K, f32x16 (&acc)[2][NJ], char* lds) {
;     ...
;   GSTAGE_(0);
;   asm volatile("s_waitcnt vmcnt(0)" ::: "memory");
;   __syncthreads();
;   const int nk = K >> 6;
;   for (int kt = 0; kt < nk; ++kt) {
;     const int cur = kt & 1;
;     if (kt + 1 < nk) GSTAGE_(cur ^ 1);
;     const char* st_ = lds + cur * GSTG;
; #pragma unroll
;     for (int ks = 0; ks < 4; ++ks) {
;       const bf16x8 a0 = *(const bf16x8*)(st_ + a_rd[ks]);
;       const bf16x8 a1 = *(const bf16x8*)(st_ + a_rd[ks] + 4096);
; #pragma unroll
;       for (int j = 0; j < NJ; ++j) {
;         const bf16x8 b = *(const bf16x8*)(st_ + b_rd[ks] + j * 4096);
;         acc[0][j] = MFMA(a0, b, acc[0][j]); acc[1][j] = MFMA(a1, b, acc[1][j]);
;       }
;     }
;     asm volatile("s_waitcnt vmcnt(0)" ::: "memory");
;     __syncthreads();
;   }
.LBB0_1225:
	s_and_b32 s43, s37, 0x8000
	s_xor_b32 s44, s43, 0x8000
	s_add_i32 s44, s36, s44
	v_lshl_add_u64 v[94:95], v[72:73], 0, s[0:1]
	s_mov_b32 m0, s44
	s_add_i32 s43, s43, 0
	global_load_lds_dwordx4 v[94:95], off
	v_lshl_add_u64 v[94:95], v[70:71], 0, s[0:1]
	s_add_i32 m0, s44, 0x1000
	v_add_u32_e32 v0, s43, v91
	global_load_lds_dwordx4 v[94:95], off
	v_lshl_add_u64 v[94:95], v[68:69], 0, s[0:1]
	s_add_i32 m0, s44, 0x2000
	s_nop 0
	global_load_lds_dwordx4 v[94:95], off
	v_lshl_add_u64 v[94:95], v[66:67], 0, s[0:1]
	s_add_i32 m0, s44, 0x3000
	s_nop 0
	global_load_lds_dwordx4 v[94:95], off
	s_add_i32 m0, s44, 0x4000
	v_lshl_add_u64 v[94:95], v[80:81], 0, s[0:1]
	global_load_lds_dwordx4 v[94:95], off
	v_lshl_add_u64 v[94:95], v[78:79], 0, s[0:1]
	s_add_i32 m0, s44, 0x5000
	s_nop 0
	global_load_lds_dwordx4 v[94:95], off
	v_lshl_add_u64 v[94:95], v[76:77], 0, s[0:1]
	s_add_i32 m0, s44, 0x6000
	s_nop 0
	global_load_lds_dwordx4 v[94:95], off
	v_lshl_add_u64 v[94:95], v[74:75], 0, s[0:1]
	s_add_i32 m0, s44, 0x7000
	s_add_u32 s0, s0, 0x80
	global_load_lds_dwordx4 v[94:95], off
	ds_read_b128 v[94:97], v0
	ds_read_b128 v[98:101], v0 offset:4096
	v_add_u32_e32 v0, s43, v92
	ds_read_b128 v[102:105], v0 offset:16384
	s_waitcnt lgkmcnt(0)
	s_setprio 1
	v_mfma_f32_32x32x16_bf16 v[50:65], v[94:97], v[102:105], v[50:65]
	s_addc_u32 s1, s1, 0
	s_add_i32 s37, s37, 0x8000
	s_cmpk_eq_i32 s0, 0x780
	v_mfma_f32_32x32x16_bf16 v[18:33], v[98:101], v[102:105], v[18:33]
	ds_read_b128 v[102:105], v0 offset:20480
	v_add_u32_e32 v0, s43, v88
	s_waitcnt lgkmcnt(0)
	v_mfma_f32_32x32x16_bf16 v[34:49], v[94:97], v[102:105], v[34:49]
	v_mfma_f32_32x32x16_bf16 v[2:17], v[98:101], v[102:105], v[2:17]
	ds_read_b128 v[94:97], v0
	ds_read_b128 v[98:101], v0 offset:4096
	v_add_u32_e32 v0, s43, v90
	ds_read_b128 v[102:105], v0 offset:16384
	s_waitcnt lgkmcnt(0)
	v_mfma_f32_32x32x16_bf16 v[50:65], v[94:97], v[102:105], v[50:65]
	v_mfma_f32_32x32x16_bf16 v[18:33], v[98:101], v[102:105], v[18:33]
	ds_read_b128 v[102:105], v0 offset:20480
	v_add_u32_e32 v0, s43, v86
	s_waitcnt lgkmcnt(0)
	v_mfma_f32_32x32x16_bf16 v[34:49], v[94:97], v[102:105], v[34:49]
	v_mfma_f32_32x32x16_bf16 v[2:17], v[98:101], v[102:105], v[2:17]
	ds_read_b128 v[94:97], v0
	ds_read_b128 v[98:101], v0 offset:4096
	v_add_u32_e32 v0, s43, v89
	ds_read_b128 v[102:105], v0 offset:16384
	s_waitcnt lgkmcnt(0)
	v_mfma_f32_32x32x16_bf16 v[50:65], v[94:97], v[102:105], v[50:65]
	v_mfma_f32_32x32x16_bf16 v[18:33], v[98:101], v[102:105], v[18:33]
	ds_read_b128 v[102:105], v0 offset:20480
	v_add_u32_e32 v0, s43, v85
	s_waitcnt lgkmcnt(0)
	v_mfma_f32_32x32x16_bf16 v[34:49], v[94:97], v[102:105], v[34:49]
	v_mfma_f32_32x32x16_bf16 v[2:17], v[98:101], v[102:105], v[2:17]
	ds_read_b128 v[94:97], v0
	ds_read_b128 v[98:101], v0 offset:4096
	v_add_u32_e32 v0, s43, v87
	ds_read_b128 v[102:105], v0 offset:16384
	s_waitcnt lgkmcnt(0)
	v_mfma_f32_32x32x16_bf16 v[50:65], v[94:97], v[102:105], v[50:65]
	v_mfma_f32_32x32x16_bf16 v[18:33], v[98:101], v[102:105], v[18:33]
	ds_read_b128 v[102:105], v0 offset:20480
	s_waitcnt vmcnt(0)
	s_waitcnt vmcnt(0) lgkmcnt(0)
	s_barrier
	v_mfma_f32_32x32x16_bf16 v[34:49], v[94:97], v[102:105], v[34:49]
	v_mfma_f32_32x32x16_bf16 v[2:17], v[98:101], v[102:105], v[2:17]
	s_cbranch_scc0 .LBB0_1225
	v_add_u32_e32 v0, 0, v91
	ds_read_b128 v[66:69], v0 offset:32768
	ds_read_b128 v[70:73], v0 offset:36864
	v_add_u32_e32 v0, 0, v92
	ds_read_b128 v[74:77], v0 offset:49152
	s_lshl_b32 s44, s3, 7
	s_add_i32 s46, s10, s44
	s_lshl_b32 s72, s2, 8
	s_waitcnt lgkmcnt(0)
	v_mfma_f32_32x32x16_bf16 v[50:65], v[66:69], v[74:77], v[50:65]
	s_lshl_b32 s43, s2, 9
	s_lshl_b32 s45, s46, 2
	s_mulk_i32 s26, 0x280
	s_add_u32 s2, s4, s26
	s_addc_u32 s3, s5, 0
	s_mulk_i32 s27, 0x280
	s_add_u32 s0, s22, s27
	v_mfma_f32_32x32x16_bf16 v[18:33], v[70:73], v[74:77], v[18:33]
	ds_read_b128 v[74:77], v0 offset:53248
	v_add_u32_e32 v0, 0, v88
	s_addc_u32 s1, s23, 0
	s_mov_b64 s[56:57], 0x100
	s_waitcnt lgkmcnt(0)
	v_mfma_f32_32x32x16_bf16 v[34:49], v[66:69], v[74:77], v[34:49]
	v_mfma_f32_32x32x16_bf16 v[2:17], v[70:73], v[74:77], v[2:17]
	ds_read_b128 v[66:69], v0 offset:32768
	ds_read_b128 v[70:73], v0 offset:36864
	v_add_u32_e32 v0, 0, v90
	ds_read_b128 v[74:77], v0 offset:49152
	s_waitcnt lgkmcnt(0)
	v_mfma_f32_32x32x16_bf16 v[50:65], v[66:69], v[74:77], v[50:65]
	v_mfma_f32_32x32x16_bf16 v[18:33], v[70:73], v[74:77], v[18:33]
	ds_read_b128 v[74:77], v0 offset:53248
	v_add_u32_e32 v0, 0, v86
	s_waitcnt lgkmcnt(0)
	v_mfma_f32_32x32x16_bf16 v[34:49], v[66:69], v[74:77], v[34:49]
	v_mfma_f32_32x32x16_bf16 v[2:17], v[70:73], v[74:77], v[2:17]
	ds_read_b128 v[66:69], v0 offset:32768
	ds_read_b128 v[70:73], v0 offset:36864
	v_add_u32_e32 v0, 0, v89
	ds_read_b128 v[74:77], v0 offset:49152
	s_waitcnt lgkmcnt(0)
	v_mfma_f32_32x32x16_bf16 v[50:65], v[66:69], v[74:77], v[50:65]
	v_mfma_f32_32x32x16_bf16 v[18:33], v[70:73], v[74:77], v[18:33]
	ds_read_b128 v[74:77], v0 offset:53248
	v_add_u32_e32 v0, 0, v85
	s_waitcnt lgkmcnt(0)
	v_mfma_f32_32x32x16_bf16 v[34:49], v[66:69], v[74:77], v[34:49]
	v_mfma_f32_32x32x16_bf16 v[2:17], v[70:73], v[74:77], v[2:17]
	ds_read_b128 v[66:69], v0 offset:32768
	ds_read_b128 v[70:73], v0 offset:36864
	v_add_u32_e32 v0, 0, v87
	ds_read_b128 v[74:77], v0 offset:49152
	s_waitcnt lgkmcnt(0)
	v_mfma_f32_32x32x16_bf16 v[50:65], v[66:69], v[74:77], v[50:65]
	v_mfma_f32_32x32x16_bf16 v[18:33], v[70:73], v[74:77], v[18:33]
	ds_read_b128 v[74:77], v0 offset:53248
	s_waitcnt vmcnt(0)
	s_waitcnt lgkmcnt(0)
	s_barrier
; DI unsigned pk2(float a, float b) { f32x2 v = {a, b}; bf16x2_t r = __builtin_convertvector(v, bf16x2_t); return __builtin_bit_cast(unsigned, r); }
; DI float sigmoidf_(float x) { return __builtin_amdgcn_rcpf(1.0f + __builtin_amdgcn_exp2f(-x * LOG2E)); }
; DI void phase_ple(const Ctx& c, bool probe = false) {
;     ...
; #pragma unroll
;       for (int i = 0; i < 2; ++i)
; #pragma unroll
;         for (int j = 0; j < 2; ++j)
; #pragma unroll
;           for (int r2 = 0; r2 < 8; ++r2) {
;             const int ra = 2 * r2, rb = 2 * r2 + 1;
;             const float r_a = rr[wm * 64 + i * 32 + (ra & 3) + 8 * (ra >> 2) + 4 * h];
;             const float r_b = rr[wm * 64 + i * 32 + (rb & 3) + 8 * (rb >> 2) + 4 * h];
;             gp[i][j][r2] = pk2(sigmoidf_(g[i][j][ra] * r_a), sigmoidf_(g[i][j][rb] * r_b));
;           }
	v_mfma_f32_32x32x16_bf16 v[34:49], v[66:69], v[74:77], v[34:49]
	v_mfma_f32_32x32x16_bf16 v[2:17], v[70:73], v[74:77], v[2:17]
	s_setprio 0
	ds_read_b128 v[70:73], v84
	ds_read_b128 v[66:69], v84 offset:32
	s_waitcnt lgkmcnt(1)
	s_nop 2
	v_mul_f32_e32 v0, v50, v70
	v_mul_f32_e32 v50, v51, v71
	v_mul_f32_e32 v0, 0xbfb8aa3b, v0
	v_mul_f32_e32 v50, 0xbfb8aa3b, v50
	v_exp_f32_e32 v0, v0
	v_exp_f32_e32 v50, v50
	v_add_f32_e32 v0, 1.0, v0
	v_add_f32_e32 v50, 1.0, v50
	v_rcp_f32_e32 v0, v0
	v_rcp_f32_e32 v50, v50
	s_nop 0
	v_cvt_pk_bf16_f32 v85, v0, v50
	v_mul_f32_e32 v0, v52, v72
	v_mul_f32_e32 v50, v53, v73
	v_mul_f32_e32 v0, 0xbfb8aa3b, v0
	v_mul_f32_e32 v50, 0xbfb8aa3b, v50
	v_exp_f32_e32 v0, v0
	v_exp_f32_e32 v50, v50
	v_add_f32_e32 v0, 1.0, v0
	v_add_f32_e32 v50, 1.0, v50
	v_rcp_f32_e32 v0, v0
	v_rcp_f32_e32 v50, v50
	s_nop 0
	v_cvt_pk_bf16_f32 v86, v0, v50
	s_waitcnt lgkmcnt(0)
	v_mul_f32_e32 v0, v54, v66
	v_mul_f32_e32 v50, v55, v67
	v_mul_f32_e32 v0, 0xbfb8aa3b, v0
	v_mul_f32_e32 v50, 0xbfb8aa3b, v50
	v_exp_f32_e32 v0, v0
	v_exp_f32_e32 v50, v50
	v_add_f32_e32 v0, 1.0, v0
	v_add_f32_e32 v50, 1.0, v50
	v_rcp_f32_e32 v0, v0
	v_rcp_f32_e32 v50, v50
	s_nop 0
	v_cvt_pk_bf16_f32 v87, v0, v50
	v_mul_f32_e32 v0, v56, v68
	v_mul_f32_e32 v50, v57, v69
	v_mul_f32_e32 v0, 0xbfb8aa3b, v0
	v_mul_f32_e32 v50, 0xbfb8aa3b, v50
	v_exp_f32_e32 v0, v0
	v_exp_f32_e32 v50, v50
	v_add_f32_e32 v0, 1.0, v0
	v_add_f32_e32 v50, 1.0, v50
	v_rcp_f32_e32 v0, v0
	v_rcp_f32_e32 v50, v50
	s_nop 0
	v_cvt_pk_bf16_f32 v88, v0, v50
	ds_read_b128 v[50:53], v84 offset:64
	s_waitcnt lgkmcnt(0)
	v_mul_f32_e32 v0, v58, v50
	v_mul_f32_e32 v54, v59, v51
	v_mul_f32_e32 v0, 0xbfb8aa3b, v0
	v_mul_f32_e32 v54, 0xbfb8aa3b, v54
	v_exp_f32_e32 v0, v0
	v_exp_f32_e32 v54, v54
	v_add_f32_e32 v0, 1.0, v0
	v_add_f32_e32 v54, 1.0, v54
	v_rcp_f32_e32 v0, v0
	v_rcp_f32_e32 v54, v54
	s_nop 0
	v_cvt_pk_bf16_f32 v89, v0, v54
	v_mul_f32_e32 v0, v60, v52
	v_mul_f32_e32 v54, v61, v53
	v_mul_f32_e32 v0, 0xbfb8aa3b, v0
	v_mul_f32_e32 v54, 0xbfb8aa3b, v54
	v_exp_f32_e32 v0, v0
	v_exp_f32_e32 v54, v54
	v_add_f32_e32 v0, 1.0, v0
	v_add_f32_e32 v54, 1.0, v54
	v_rcp_f32_e32 v0, v0
	v_rcp_f32_e32 v54, v54
	s_nop 0
	v_cvt_pk_bf16_f32 v90, v0, v54
	ds_read_b128 v[54:57], v84 offset:96
	s_waitcnt lgkmcnt(0)
	v_mul_f32_e32 v0, v62, v54
	v_mul_f32_e32 v58, v63, v55
	v_mul_f32_e32 v0, 0xbfb8aa3b, v0
	v_mul_f32_e32 v58, 0xbfb8aa3b, v58
	v_exp_f32_e32 v0, v0
	v_exp_f32_e32 v58, v58
	v_add_f32_e32 v0, 1.0, v0
	v_add_f32_e32 v58, 1.0, v58
	v_rcp_f32_e32 v0, v0
	v_rcp_f32_e32 v58, v58
	s_nop 0
	v_cvt_pk_bf16_f32 v91, v0, v58
	v_mul_f32_e32 v0, v64, v56
	v_mul_f32_e32 v58, v65, v57
	v_mul_f32_e32 v0, 0xbfb8aa3b, v0
	v_mul_f32_e32 v58, 0xbfb8aa3b, v58
	v_exp_f32_e32 v0, v0
	v_exp_f32_e32 v58, v58
	v_add_f32_e32 v0, 1.0, v0
	v_add_f32_e32 v58, 1.0, v58
	v_rcp_f32_e32 v0, v0
	v_rcp_f32_e32 v58, v58
	s_nop 0
	v_cvt_pk_bf16_f32 v92, v0, v58
	v_mul_f32_e32 v0, v34, v70
	v_mul_f32_e32 v34, v35, v71
	v_mul_f32_e32 v0, 0xbfb8aa3b, v0
	v_mul_f32_e32 v34, 0xbfb8aa3b, v34
	v_exp_f32_e32 v0, v0
	v_exp_f32_e32 v34, v34
	v_add_f32_e32 v0, 1.0, v0
	v_add_f32_e32 v34, 1.0, v34
	v_rcp_f32_e32 v0, v0
	v_rcp_f32_e32 v34, v34
	s_nop 0
	v_cvt_pk_bf16_f32 v93, v0, v34
	v_mul_f32_e32 v0, v36, v72
	v_mul_f32_e32 v34, v37, v73
	v_mul_f32_e32 v0, 0xbfb8aa3b, v0
	v_mul_f32_e32 v34, 0xbfb8aa3b, v34
	v_exp_f32_e32 v0, v0
	v_exp_f32_e32 v34, v34
	v_add_f32_e32 v0, 1.0, v0
	v_add_f32_e32 v34, 1.0, v34
	v_rcp_f32_e32 v0, v0
	v_rcp_f32_e32 v34, v34
	s_nop 0
	v_cvt_pk_bf16_f32 v94, v0, v34
	v_mul_f32_e32 v0, v38, v66
	v_mul_f32_e32 v34, v39, v67
	v_mul_f32_e32 v0, 0xbfb8aa3b, v0
	v_mul_f32_e32 v34, 0xbfb8aa3b, v34
	v_exp_f32_e32 v0, v0
	v_exp_f32_e32 v34, v34
	v_add_f32_e32 v0, 1.0, v0
	v_add_f32_e32 v34, 1.0, v34
	v_rcp_f32_e32 v0, v0
	v_rcp_f32_e32 v34, v34
	s_nop 0
	v_cvt_pk_bf16_f32 v95, v0, v34
	v_mul_f32_e32 v0, v40, v68
	v_mul_f32_e32 v34, v41, v69
	v_mul_f32_e32 v0, 0xbfb8aa3b, v0
	v_mul_f32_e32 v34, 0xbfb8aa3b, v34
	v_exp_f32_e32 v0, v0
	v_exp_f32_e32 v34, v34
	v_add_f32_e32 v0, 1.0, v0
	v_add_f32_e32 v34, 1.0, v34
	v_rcp_f32_e32 v0, v0
	v_rcp_f32_e32 v34, v34
	s_nop 0
	v_cvt_pk_bf16_f32 v96, v0, v34
	v_mul_f32_e32 v0, v42, v50
	v_mul_f32_e32 v34, v43, v51
	v_mul_f32_e32 v0, 0xbfb8aa3b, v0
	v_mul_f32_e32 v34, 0xbfb8aa3b, v34
	v_exp_f32_e32 v0, v0
	v_exp_f32_e32 v34, v34
	v_add_f32_e32 v0, 1.0, v0
	v_add_f32_e32 v34, 1.0, v34
	v_rcp_f32_e32 v0, v0
	v_rcp_f32_e32 v34, v34
	s_nop 0
	v_cvt_pk_bf16_f32 v97, v0, v34
	v_mul_f32_e32 v0, v44, v52
	v_mul_f32_e32 v34, v45, v53
	v_mul_f32_e32 v0, 0xbfb8aa3b, v0
	v_mul_f32_e32 v34, 0xbfb8aa3b, v34
	v_exp_f32_e32 v0, v0
	v_exp_f32_e32 v34, v34
	v_add_f32_e32 v0, 1.0, v0
	v_add_f32_e32 v34, 1.0, v34
	v_rcp_f32_e32 v0, v0
	v_rcp_f32_e32 v34, v34
	s_nop 0
	v_cvt_pk_bf16_f32 v98, v0, v34
	v_mul_f32_e32 v0, v46, v54
	v_mul_f32_e32 v34, v47, v55
	v_mul_f32_e32 v0, 0xbfb8aa3b, v0
	v_mul_f32_e32 v34, 0xbfb8aa3b, v34
	v_exp_f32_e32 v0, v0
	v_exp_f32_e32 v34, v34
	v_add_f32_e32 v0, 1.0, v0
	v_add_f32_e32 v34, 1.0, v34
	v_rcp_f32_e32 v0, v0
	v_rcp_f32_e32 v34, v34
	s_nop 0
	v_cvt_pk_bf16_f32 v99, v0, v34
	v_mul_f32_e32 v0, v48, v56
	v_mul_f32_e32 v34, v49, v57
	v_mul_f32_e32 v0, 0xbfb8aa3b, v0
	v_mul_f32_e32 v34, 0xbfb8aa3b, v34
	v_exp_f32_e32 v0, v0
	v_exp_f32_e32 v34, v34
	v_add_f32_e32 v0, 1.0, v0
	v_add_f32_e32 v34, 1.0, v34
	v_rcp_f32_e32 v0, v0
	v_rcp_f32_e32 v34, v34
	s_nop 0
	v_cvt_pk_bf16_f32 v100, v0, v34
	ds_read_b128 v[34:37], v84 offset:128
	s_waitcnt lgkmcnt(0)
; DI int tid_() { int t = threadIdx.x; asm volatile("" : "+v"(t)); return t; }
; DI unsigned pk2(float a, float b) { f32x2 v = {a, b}; bf16x2_t r = __builtin_convertvector(v, bf16x2_t); return __builtin_bit_cast(unsigned, r); }
; DI float sigmoidf_(float x) { return __builtin_amdgcn_rcpf(1.0f + __builtin_amdgcn_exp2f(-x * LOG2E)); }
; template <int NJ> DI void gemm_mainloop_glds(const bf16_t* __restrict__ A, int lda, const bf16_t* __restrict__ Bt, int ldb, int K, f32x16 (&acc)[2][NJ], char* lds) {
;   const int tid = tid_(), lane = tid & 63, w = __builtin_amdgcn_readfirstlane(tid >> 6), wm = w >> 1, wn = w & 1;
;   const int ql = lane & 31, h = lane >> 5;
;   const int sw_s = (4 * (w & 1) + (lane >> 4)) & 7;
;   const int csrc = (lane & 7) ^ sw_s;
;   const char* ap = (const char*)A;
;   const char* bp = (const char*)Bt;
;   const unsigned aoff = (unsigned)((8 * w + (lane >> 3)) * lda + csrc * 8) * 2u, boff = (unsigned)((8 * w + (lane >> 3)) * ldb + csrc * 8) * 2u;
;   const unsigned astep = (unsigned)(32 * lda) * 2u, bstep = (unsigned)(32 * ldb) * 2u;
;   constexpr int NB = 2 * NJ;
;   const int sw_r = (ql >> 1) & 7;
;   int a_rd[4], b_rd[4];
; #pragma unroll
;   for (int ks = 0; ks < 4; ++ks) { const int pos = ((2 * ks + h) ^ sw_r) * 16; a_rd[ks] = (wm * 64 + ql) * 128 + pos; b_rd[ks] = GSTG_B + (wn * 32 * NJ + ql) * 128 + pos; }
; DI void phase_ple(const Ctx& c, bool probe = false) {
;     ...
;           for (int r2 = 0; r2 < 8; ++r2) {
;             const int ra = 2 * r2, rb = 2 * r2 + 1;
;             const float r_a = rr[wm * 64 + i * 32 + (ra & 3) + 8 * (ra >> 2) + 4 * h];
;             const float r_b = rr[wm * 64 + i * 32 + (rb & 3) + 8 * (rb >> 2) + 4 * h];
;             gp[i][j][r2] = pk2(sigmoidf_(g[i][j][ra] * r_a), sigmoidf_(g[i][j][rb] * r_b));
;           }
	v_mul_f32_e32 v0, v18, v34
	v_mul_f32_e32 v18, v19, v35
	v_mul_f32_e32 v0, 0xbfb8aa3b, v0
	v_mul_f32_e32 v18, 0xbfb8aa3b, v18
	v_exp_f32_e32 v0, v0
	v_exp_f32_e32 v18, v18
	v_add_f32_e32 v0, 1.0, v0
	v_add_f32_e32 v18, 1.0, v18
	v_rcp_f32_e32 v0, v0
	v_rcp_f32_e32 v18, v18
	s_nop 0
	v_cvt_pk_bf16_f32 v101, v0, v18
	v_mul_f32_e32 v0, v20, v36
	v_mul_f32_e32 v18, v21, v37
	v_mul_f32_e32 v0, 0xbfb8aa3b, v0
	v_mul_f32_e32 v18, 0xbfb8aa3b, v18
	v_exp_f32_e32 v0, v0
	v_exp_f32_e32 v18, v18
	v_add_f32_e32 v0, 1.0, v0
	v_add_f32_e32 v18, 1.0, v18
	v_rcp_f32_e32 v0, v0
	v_rcp_f32_e32 v18, v18
	s_nop 0
	v_cvt_pk_bf16_f32 v102, v0, v18
	ds_read_b128 v[18:21], v84 offset:160
	s_waitcnt lgkmcnt(0)
	v_mul_f32_e32 v0, v22, v18
	v_mul_f32_e32 v22, v23, v19
	v_mul_f32_e32 v0, 0xbfb8aa3b, v0
	v_mul_f32_e32 v22, 0xbfb8aa3b, v22
	v_exp_f32_e32 v0, v0
	v_exp_f32_e32 v22, v22
	v_add_f32_e32 v0, 1.0, v0
	v_add_f32_e32 v22, 1.0, v22
	v_rcp_f32_e32 v0, v0
	v_rcp_f32_e32 v22, v22
	s_nop 0
	v_cvt_pk_bf16_f32 v103, v0, v22
	v_mul_f32_e32 v0, v24, v20
	v_mul_f32_e32 v22, v25, v21
	v_mul_f32_e32 v0, 0xbfb8aa3b, v0
	v_mul_f32_e32 v22, 0xbfb8aa3b, v22
	v_exp_f32_e32 v0, v0
	v_exp_f32_e32 v22, v22
	v_add_f32_e32 v0, 1.0, v0
	v_add_f32_e32 v22, 1.0, v22
	v_rcp_f32_e32 v0, v0
	v_rcp_f32_e32 v22, v22
	s_nop 0
	v_cvt_pk_bf16_f32 v104, v0, v22
	ds_read_b128 v[22:25], v84 offset:192
	s_waitcnt lgkmcnt(0)
	v_mul_f32_e32 v0, v26, v22
	v_mul_f32_e32 v26, v27, v23
	v_mul_f32_e32 v0, 0xbfb8aa3b, v0
	v_mul_f32_e32 v26, 0xbfb8aa3b, v26
	v_exp_f32_e32 v0, v0
	v_exp_f32_e32 v26, v26
	v_add_f32_e32 v0, 1.0, v0
	v_add_f32_e32 v26, 1.0, v26
	v_rcp_f32_e32 v0, v0
	v_rcp_f32_e32 v26, v26
	s_nop 0
	v_cvt_pk_bf16_f32 v105, v0, v26
	v_mul_f32_e32 v0, v28, v24
	v_mul_f32_e32 v26, v29, v25
	v_mul_f32_e32 v0, 0xbfb8aa3b, v0
	v_mul_f32_e32 v26, 0xbfb8aa3b, v26
	v_exp_f32_e32 v0, v0
	v_exp_f32_e32 v26, v26
	v_add_f32_e32 v0, 1.0, v0
	v_add_f32_e32 v26, 1.0, v26
	v_rcp_f32_e32 v0, v0
	v_rcp_f32_e32 v26, v26
	s_nop 0
	v_cvt_pk_bf16_f32 v106, v0, v26
	ds_read_b128 v[26:29], v84 offset:224
	s_waitcnt lgkmcnt(0)
	v_mul_f32_e32 v0, v30, v26
	v_mul_f32_e32 v30, v31, v27
	v_mul_f32_e32 v0, 0xbfb8aa3b, v0
	v_mul_f32_e32 v30, 0xbfb8aa3b, v30
	v_exp_f32_e32 v0, v0
	v_exp_f32_e32 v30, v30
	v_add_f32_e32 v0, 1.0, v0
	v_add_f32_e32 v30, 1.0, v30
	v_rcp_f32_e32 v0, v0
	v_rcp_f32_e32 v30, v30
	s_nop 0
	v_cvt_pk_bf16_f32 v107, v0, v30
	v_mul_f32_e32 v0, v32, v28
	v_mul_f32_e32 v30, v33, v29
	v_mul_f32_e32 v0, 0xbfb8aa3b, v0
	v_mul_f32_e32 v30, 0xbfb8aa3b, v30
	v_exp_f32_e32 v0, v0
	v_exp_f32_e32 v30, v30
	v_add_f32_e32 v0, 1.0, v0
	v_add_f32_e32 v30, 1.0, v30
	v_rcp_f32_e32 v0, v0
	v_rcp_f32_e32 v30, v30
	s_nop 0
	v_cvt_pk_bf16_f32 v108, v0, v30
	v_mul_f32_e32 v0, v2, v34
	v_mul_f32_e32 v2, v3, v35
	v_mul_f32_e32 v0, 0xbfb8aa3b, v0
	v_mul_f32_e32 v2, 0xbfb8aa3b, v2
	v_exp_f32_e32 v0, v0
	v_exp_f32_e32 v2, v2
	v_add_f32_e32 v0, 1.0, v0
	v_add_f32_e32 v2, 1.0, v2
	v_rcp_f32_e32 v0, v0
	v_rcp_f32_e32 v2, v2
	s_nop 0
	v_cvt_pk_bf16_f32 v109, v0, v2
	v_mul_f32_e32 v0, v4, v36
	v_mul_f32_e32 v2, v5, v37
	v_mul_f32_e32 v0, 0xbfb8aa3b, v0
	v_mul_f32_e32 v2, 0xbfb8aa3b, v2
	v_exp_f32_e32 v0, v0
	v_exp_f32_e32 v2, v2
	v_add_f32_e32 v0, 1.0, v0
	v_add_f32_e32 v2, 1.0, v2
	v_rcp_f32_e32 v0, v0
	v_rcp_f32_e32 v2, v2
	s_nop 0
	v_cvt_pk_bf16_f32 v110, v0, v2
	v_mul_f32_e32 v0, v6, v18
	v_mul_f32_e32 v2, v7, v19
	v_mul_f32_e32 v0, 0xbfb8aa3b, v0
	v_mul_f32_e32 v2, 0xbfb8aa3b, v2
	v_exp_f32_e32 v0, v0
	v_exp_f32_e32 v2, v2
	v_add_f32_e32 v0, 1.0, v0
	v_add_f32_e32 v2, 1.0, v2
	v_rcp_f32_e32 v0, v0
	v_rcp_f32_e32 v2, v2
	s_nop 0
	v_cvt_pk_bf16_f32 v111, v0, v2
	v_mul_f32_e32 v0, v8, v20
	v_mul_f32_e32 v2, v9, v21
	v_mul_f32_e32 v0, 0xbfb8aa3b, v0
	v_mul_f32_e32 v2, 0xbfb8aa3b, v2
	v_exp_f32_e32 v0, v0
	v_exp_f32_e32 v2, v2
	v_add_f32_e32 v0, 1.0, v0
	v_add_f32_e32 v2, 1.0, v2
	v_rcp_f32_e32 v0, v0
	v_rcp_f32_e32 v2, v2
	s_nop 0
	v_cvt_pk_bf16_f32 v112, v0, v2
	v_mul_f32_e32 v0, v10, v22
	v_mul_f32_e32 v2, v11, v23
	v_mul_f32_e32 v0, 0xbfb8aa3b, v0
	v_mul_f32_e32 v2, 0xbfb8aa3b, v2
	v_exp_f32_e32 v0, v0
	v_exp_f32_e32 v2, v2
	v_add_f32_e32 v0, 1.0, v0
	v_add_f32_e32 v2, 1.0, v2
	v_rcp_f32_e32 v0, v0
	v_rcp_f32_e32 v2, v2
	s_nop 0
	v_cvt_pk_bf16_f32 v113, v0, v2
	v_mul_f32_e32 v0, v12, v24
	v_mul_f32_e32 v2, v13, v25
	v_mul_f32_e32 v0, 0xbfb8aa3b, v0
	v_mul_f32_e32 v2, 0xbfb8aa3b, v2
	v_exp_f32_e32 v0, v0
	v_exp_f32_e32 v2, v2
	v_add_f32_e32 v0, 1.0, v0
	v_add_f32_e32 v2, 1.0, v2
	v_rcp_f32_e32 v0, v0
	v_rcp_f32_e32 v2, v2
	s_nop 0
	v_cvt_pk_bf16_f32 v114, v0, v2
	v_mul_f32_e32 v0, v14, v26
	v_mul_f32_e32 v2, v15, v27
	v_mul_f32_e32 v0, 0xbfb8aa3b, v0
	v_mul_f32_e32 v2, 0xbfb8aa3b, v2
	v_exp_f32_e32 v0, v0
	v_exp_f32_e32 v2, v2
	v_add_f32_e32 v0, 1.0, v0
	v_add_f32_e32 v2, 1.0, v2
	v_rcp_f32_e32 v0, v0
	v_rcp_f32_e32 v2, v2
	s_nop 0
	v_cvt_pk_bf16_f32 v115, v0, v2
	v_mul_f32_e32 v0, v16, v28
	v_mul_f32_e32 v2, v17, v29
	v_mul_f32_e32 v0, 0xbfb8aa3b, v0
	v_mul_f32_e32 v2, 0xbfb8aa3b, v2
	v_exp_f32_e32 v0, v0
	v_exp_f32_e32 v2, v2
	v_add_f32_e32 v0, 1.0, v0
	v_add_f32_e32 v2, 1.0, v2
	v_rcp_f32_e32 v0, v0
	v_rcp_f32_e32 v2, v2
	s_nop 0
	v_cvt_pk_bf16_f32 v116, v0, v2
	v_mov_b32_e32 v0, v199
	s_nop 0
	v_readfirstlane_b32 s26, v0
	s_ashr_i32 s27, s26, 6
	s_lshr_b32 s26, s26, 1
	s_and_b32 s36, s27, 1
	v_and_b32_e32 v2, 31, v0
	s_and_b32 s26, s26, 0x1ffffc0
	v_bfe_u32 v3, v0, 5, 1
	s_lshl_b32 s37, s36, 2
	v_bfe_u32 v4, v0, 4, 2
	v_and_b32_e32 v5, 7, v0
	v_lshrrev_b32_e32 v6, 1, v0
	v_or_b32_e32 v7, s26, v2
	v_lshlrev_b32_e32 v2, 7, v2
	v_bitop3_b32 v4, s37, v5, v4 bitop3:0x36
	v_bfe_u32 v5, v0, 3, 3
	v_bfe_u32 v0, v0, 1, 3
; #define MFMA(a, b, c) __builtin_amdgcn_mfma_f32_32x32x16_bf16((a), (b), (c), 0, 0, 0)
; template <int NJ> DI void gemm_mainloop_glds(const bf16_t* __restrict__ A, int lda, const bf16_t* __restrict__ Bt, int ldb, int K, f32x16 (&acc)[2][NJ], char* lds) {
;     ...
;   GSTAGE_(0);
;   asm volatile("s_waitcnt vmcnt(0)" ::: "memory");
;   __syncthreads();
;   const int nk = K >> 6;
;   for (int kt = 0; kt < nk; ++kt) {
;     const int cur = kt & 1;
;     if (kt + 1 < nk) GSTAGE_(cur ^ 1);
;     const char* st_ = lds + cur * GSTG;
; #pragma unroll
;     for (int ks = 0; ks < 4; ++ks) {
;       const bf16x8 a0 = *(const bf16x8*)(st_ + a_rd[ks]);
;       const bf16x8 a1 = *(const bf16x8*)(st_ + a_rd[ks] + 4096);
; #pragma unroll
;       for (int j = 0; j < NJ; ++j) {
;         const bf16x8 b = *(const bf16x8*)(st_ + b_rd[ks] + j * 4096);
;         acc[0][j] = MFMA(a0, b, acc[0][j]); acc[1][j] = MFMA(a1, b, acc[1][j]);
;       }
;     }
	v_lshl_or_b32 v124, s36, 13, v2
	v_bitop3_b32 v2, v3, v6, 7 bitop3:0x78
	v_lshlrev_b32_e32 v8, 4, v2
	v_bitop3_b32 v2, v3, v0, 2 bitop3:0x36
	v_lshl_or_b32 v5, s27, 3, v5
	v_lshlrev_b32_e32 v117, 4, v2
	v_bitop3_b32 v2, v3, v0, 4 bitop3:0x36
	v_bitop3_b32 v0, v3, v0, 6 bitop3:0x36
	s_lshl_b32 s26, s27, 10
	v_lshlrev_b32_e32 v125, 4, v0
	v_mul_lo_u32 v0, v5, s68
	s_add_i32 s47, s26, 0
	v_lshl_or_b32 v0, v4, 4, v0
	s_mov_b32 m0, s47
	s_add_i32 s48, s47, 0x1000
	v_lshlrev_b32_e32 v138, 4, v2
	global_load_lds_dwordx4 v0, s[2:3]
	v_add_u32_e32 v2, 0x5000, v0
	s_mov_b32 m0, s48
	s_add_i32 s49, s47, 0x2000
	global_load_lds_dwordx4 v2, s[2:3]
	v_add_u32_e32 v4, 0xa000, v0
	s_mov_b32 m0, s49
	s_add_i32 s50, s47, 0x3000
	global_load_lds_dwordx4 v4, s[2:3]
	v_add_u32_e32 v6, 0xf000, v0
	s_mov_b32 m0, s50
	s_add_i32 s51, s47, 0x4000
	global_load_lds_dwordx4 v6, s[2:3]
	s_mov_b32 m0, s51
	s_add_i32 s52, s47, 0x5000
	global_load_lds_dwordx4 v0, s[0:1]
	s_mov_b32 m0, s52
	s_add_i32 s53, s47, 0x6000
	v_lshlrev_b32_e32 v7, 7, v7
	global_load_lds_dwordx4 v2, s[0:1]
	s_mov_b32 m0, s53
	s_add_i32 s54, s47, 0x7000
	v_or_b32_e32 v9, v7, v8
	v_or_b32_e32 v118, v117, v7
	v_or_b32_e32 v121, v138, v7
	v_or_b32_e32 v120, v125, v7
	v_mov_b32_e32 v3, v1
	v_mov_b32_e32 v5, v1
	v_mov_b32_e32 v7, v1
	global_load_lds_dwordx4 v4, s[0:1]
	s_mov_b32 m0, s54
	v_lshl_add_u64 v[66:67], s[2:3], 0, v[0:1]
	v_lshl_add_u64 v[74:75], s[0:1], 0, v[0:1]
	v_lshl_add_u64 v[76:77], s[0:1], 0, v[2:3]
	v_lshl_add_u64 v[78:79], s[0:1], 0, v[4:5]
	v_lshl_add_u64 v[80:81], s[0:1], 0, v[6:7]
	global_load_lds_dwordx4 v6, s[0:1]
	s_add_i32 s0, s47, 0x8000
	v_lshl_add_u64 v[68:69], s[2:3], 0, v[2:3]
	v_lshl_add_u64 v[2:3], v[66:67], 0, s[76:77]
	s_mov_b32 m0, s0
	s_add_i32 s1, s47, 0x9000
	v_lshl_add_u64 v[70:71], s[2:3], 0, v[4:5]
	v_lshl_add_u64 v[72:73], s[2:3], 0, v[6:7]
	s_waitcnt vmcnt(0)
	s_waitcnt vmcnt(0) lgkmcnt(0)
	s_barrier
	global_load_lds_dwordx4 v[2:3], off
	v_lshl_add_u64 v[2:3], v[68:69], 0, s[76:77]
	s_mov_b32 m0, s1
	s_add_i32 s2, s47, 0xa000
	global_load_lds_dwordx4 v[2:3], off
	v_lshl_add_u64 v[2:3], v[70:71], 0, s[76:77]
	s_mov_b32 m0, s2
	s_add_i32 s3, s47, 0xb000
	global_load_lds_dwordx4 v[2:3], off
	v_lshl_add_u64 v[2:3], v[72:73], 0, s[76:77]
	s_mov_b32 m0, s3
	s_add_i32 s26, s47, 0xc000
	global_load_lds_dwordx4 v[2:3], off
	v_lshl_add_u64 v[2:3], v[74:75], 0, s[76:77]
	s_mov_b32 m0, s26
	s_add_i32 s27, s47, 0xd000
	global_load_lds_dwordx4 v[2:3], off
	v_lshl_add_u64 v[2:3], v[76:77], 0, s[76:77]
	s_mov_b32 m0, s27
	s_add_i32 s36, s47, 0xe000
	global_load_lds_dwordx4 v[2:3], off
	v_lshl_add_u64 v[2:3], v[78:79], 0, s[76:77]
	s_mov_b32 m0, s36
	s_add_i32 s37, s47, 0xf000
	global_load_lds_dwordx4 v[2:3], off
	v_lshl_add_u64 v[2:3], v[80:81], 0, s[76:77]
	s_mov_b32 m0, s37
	v_or_b32_e32 v0, v124, v8
	global_load_lds_dwordx4 v[2:3], off
	v_add_u32_e32 v123, 0, v9
	v_add_u32_e32 v119, 0, v0
	ds_read_b128 v[18:21], v123
	ds_read_b128 v[22:25], v123 offset:4096
	ds_read_b128 v[2:5], v119 offset:16384
	ds_read_b128 v[26:29], v119 offset:20480
	s_waitcnt lgkmcnt(0)
	s_setprio 1
	v_mfma_f32_32x32x16_bf16 v[34:49], v[18:21], v[2:5], 0
	v_or_b32_e32 v0, v124, v117
	v_add_u32_e32 v122, 0, v118
	v_add_u32_e32 v118, 0, v0
	ds_read_b128 v[126:129], v122
	ds_read_b128 v[130:133], v122 offset:4096
	ds_read_b128 v[134:137], v118 offset:16384
	v_or_b32_e32 v0, v124, v138
	v_add_u32_e32 v121, 0, v121
	v_mfma_f32_32x32x16_bf16 v[2:17], v[22:25], v[2:5], 0
	v_add_u32_e32 v117, 0, v0
	v_or_b32_e32 v0, v124, v125
	v_add_u32_e32 v120, 0, v120
	v_add_u32_e32 v0, 0, v0
	v_lshl_add_u64 v[124:125], v[66:67], 0, s[56:57]
	s_mov_b32 m0, s47
	v_mfma_f32_32x32x16_bf16 v[50:65], v[18:21], v[26:29], 0
	v_mfma_f32_32x32x16_bf16 v[18:33], v[22:25], v[26:29], 0
	s_waitcnt lgkmcnt(0)
	v_mfma_f32_32x32x16_bf16 v[34:49], v[126:129], v[134:137], v[34:49]
	v_mfma_f32_32x32x16_bf16 v[2:17], v[130:133], v[134:137], v[2:17]
	ds_read_b128 v[134:137], v118 offset:20480
	s_waitcnt lgkmcnt(0)
	v_mfma_f32_32x32x16_bf16 v[50:65], v[126:129], v[134:137], v[50:65]
	v_mfma_f32_32x32x16_bf16 v[18:33], v[130:133], v[134:137], v[18:33]
	ds_read_b128 v[126:129], v121
	ds_read_b128 v[130:133], v121 offset:4096
	ds_read_b128 v[134:137], v117 offset:16384
	s_waitcnt lgkmcnt(0)
	v_mfma_f32_32x32x16_bf16 v[34:49], v[126:129], v[134:137], v[34:49]
	v_mfma_f32_32x32x16_bf16 v[2:17], v[130:133], v[134:137], v[2:17]
	ds_read_b128 v[134:137], v117 offset:20480
	s_waitcnt lgkmcnt(0)
	v_mfma_f32_32x32x16_bf16 v[50:65], v[126:129], v[134:137], v[50:65]
	v_mfma_f32_32x32x16_bf16 v[18:33], v[130:133], v[134:137], v[18:33]
	ds_read_b128 v[126:129], v120
	ds_read_b128 v[130:133], v120 offset:4096
	ds_read_b128 v[134:137], v0 offset:16384
	s_waitcnt lgkmcnt(0)
	v_mfma_f32_32x32x16_bf16 v[34:49], v[126:129], v[134:137], v[34:49]
	v_mfma_f32_32x32x16_bf16 v[2:17], v[130:133], v[134:137], v[2:17]
	ds_read_b128 v[134:137], v0 offset:20480
	s_waitcnt vmcnt(0)
	s_waitcnt vmcnt(0) lgkmcnt(0)
	s_barrier
; #define MFMA(a, b, c) __builtin_amdgcn_mfma_f32_32x32x16_bf16((a), (b), (c), 0, 0, 0)
; template <int NJ> DI void gemm_mainloop_glds(const bf16_t* __restrict__ A, int lda, const bf16_t* __restrict__ Bt, int ldb, int K, f32x16 (&acc)[2][NJ], char* lds) {
;     ...
;   GSTAGE_(0);
;   asm volatile("s_waitcnt vmcnt(0)" ::: "memory");
;   __syncthreads();
;   const int nk = K >> 6;
;   for (int kt = 0; kt < nk; ++kt) {
;     const int cur = kt & 1;
;     if (kt + 1 < nk) GSTAGE_(cur ^ 1);
;     const char* st_ = lds + cur * GSTG;
; #pragma unroll
;     for (int ks = 0; ks < 4; ++ks) {
;       const bf16x8 a0 = *(const bf16x8*)(st_ + a_rd[ks]);
;       const bf16x8 a1 = *(const bf16x8*)(st_ + a_rd[ks] + 4096);
; #pragma unroll
;       for (int j = 0; j < NJ; ++j) {
;         const bf16x8 b = *(const bf16x8*)(st_ + b_rd[ks] + j * 4096);
;         acc[0][j] = MFMA(a0, b, acc[0][j]); acc[1][j] = MFMA(a1, b, acc[1][j]);
;       }
;     }
;     asm volatile("s_waitcnt vmcnt(0)" ::: "memory");
;     __syncthreads();
;   }
	global_load_lds_dwordx4 v[124:125], off
	v_lshl_add_u64 v[124:125], v[68:69], 0, s[56:57]
	s_mov_b32 m0, s48
	v_mfma_f32_32x32x16_bf16 v[50:65], v[126:129], v[134:137], v[50:65]
	global_load_lds_dwordx4 v[124:125], off
	v_lshl_add_u64 v[124:125], v[70:71], 0, s[56:57]
	s_mov_b32 m0, s49
	s_mov_b64 s[48:49], 0x180
	global_load_lds_dwordx4 v[124:125], off
	v_lshl_add_u64 v[124:125], v[72:73], 0, s[56:57]
	s_mov_b32 m0, s50
	v_mfma_f32_32x32x16_bf16 v[18:33], v[130:133], v[134:137], v[18:33]
	global_load_lds_dwordx4 v[124:125], off
	v_lshl_add_u64 v[124:125], v[74:75], 0, s[56:57]
	s_mov_b32 m0, s51
	v_lshl_add_u64 v[66:67], v[66:67], 0, s[48:49]
	global_load_lds_dwordx4 v[124:125], off
	v_lshl_add_u64 v[124:125], v[76:77], 0, s[56:57]
	s_mov_b32 m0, s52
	s_nop 0
	global_load_lds_dwordx4 v[124:125], off
	v_lshl_add_u64 v[124:125], v[78:79], 0, s[56:57]
	s_mov_b32 m0, s53
	s_nop 0
	global_load_lds_dwordx4 v[124:125], off
	v_lshl_add_u64 v[124:125], v[80:81], 0, s[56:57]
	s_mov_b32 m0, s54
	s_nop 0
	global_load_lds_dwordx4 v[124:125], off
	ds_read_b128 v[124:127], v123 offset:32768
	ds_read_b128 v[128:131], v123 offset:36864
	ds_read_b128 v[132:135], v119 offset:49152
	s_waitcnt lgkmcnt(0)
	v_mfma_f32_32x32x16_bf16 v[34:49], v[124:127], v[132:135], v[34:49]
	s_mov_b32 m0, s0
	v_mfma_f32_32x32x16_bf16 v[2:17], v[128:131], v[132:135], v[2:17]
	ds_read_b128 v[132:135], v119 offset:53248
	s_waitcnt lgkmcnt(0)
	v_mfma_f32_32x32x16_bf16 v[50:65], v[124:127], v[132:135], v[50:65]
	v_mfma_f32_32x32x16_bf16 v[18:33], v[128:131], v[132:135], v[18:33]
	ds_read_b128 v[124:127], v122 offset:32768
	ds_read_b128 v[128:131], v122 offset:36864
	ds_read_b128 v[132:135], v118 offset:49152
	s_waitcnt lgkmcnt(0)
	v_mfma_f32_32x32x16_bf16 v[34:49], v[124:127], v[132:135], v[34:49]
	v_mfma_f32_32x32x16_bf16 v[2:17], v[128:131], v[132:135], v[2:17]
	ds_read_b128 v[132:135], v118 offset:53248
	s_waitcnt lgkmcnt(0)
	v_mfma_f32_32x32x16_bf16 v[50:65], v[124:127], v[132:135], v[50:65]
	v_mfma_f32_32x32x16_bf16 v[18:33], v[128:131], v[132:135], v[18:33]
	ds_read_b128 v[124:127], v121 offset:32768
	ds_read_b128 v[128:131], v121 offset:36864
	ds_read_b128 v[132:135], v117 offset:49152
	s_waitcnt lgkmcnt(0)
	v_mfma_f32_32x32x16_bf16 v[34:49], v[124:127], v[132:135], v[34:49]
	v_mfma_f32_32x32x16_bf16 v[2:17], v[128:131], v[132:135], v[2:17]
	ds_read_b128 v[132:135], v117 offset:53248
	s_waitcnt lgkmcnt(0)
	v_mfma_f32_32x32x16_bf16 v[50:65], v[124:127], v[132:135], v[50:65]
	v_mfma_f32_32x32x16_bf16 v[18:33], v[128:131], v[132:135], v[18:33]
	ds_read_b128 v[124:127], v120 offset:32768
	ds_read_b128 v[128:131], v120 offset:36864
	ds_read_b128 v[132:135], v0 offset:49152
	s_waitcnt lgkmcnt(0)
	v_mfma_f32_32x32x16_bf16 v[34:49], v[124:127], v[132:135], v[34:49]
	v_mfma_f32_32x32x16_bf16 v[2:17], v[128:131], v[132:135], v[2:17]
	ds_read_b128 v[132:135], v0 offset:53248
	s_waitcnt vmcnt(0)
	s_waitcnt vmcnt(0) lgkmcnt(0)
	s_barrier
	global_load_lds_dwordx4 v[66:67], off
	v_lshl_add_u64 v[66:67], v[68:69], 0, s[48:49]
	s_mov_b32 m0, s1
	v_mfma_f32_32x32x16_bf16 v[50:65], v[124:127], v[132:135], v[50:65]
	global_load_lds_dwordx4 v[66:67], off
	v_lshl_add_u64 v[66:67], v[70:71], 0, s[48:49]
	s_mov_b32 m0, s2
	v_cmp_lt_i32_e64 s[0:1], v222, v220
	global_load_lds_dwordx4 v[66:67], off
	v_lshl_add_u64 v[66:67], v[72:73], 0, s[48:49]
	s_mov_b32 m0, s3
	v_mfma_f32_32x32x16_bf16 v[18:33], v[128:131], v[132:135], v[18:33]
	global_load_lds_dwordx4 v[66:67], off
	v_lshl_add_u64 v[66:67], v[74:75], 0, s[48:49]
	s_mov_b32 m0, s26
	s_mov_b64 s[2:3], 0x9735900
	global_load_lds_dwordx4 v[66:67], off
	v_lshl_add_u64 v[66:67], v[76:77], 0, s[48:49]
	s_mov_b32 m0, s27
	s_nop 0
	global_load_lds_dwordx4 v[66:67], off
	v_lshl_add_u64 v[66:67], v[78:79], 0, s[48:49]
	s_mov_b32 m0, s36
	s_nop 0
	global_load_lds_dwordx4 v[66:67], off
	v_lshl_add_u64 v[66:67], v[80:81], 0, s[48:49]
	s_mov_b32 m0, s37
	s_nop 0
	global_load_lds_dwordx4 v[66:67], off
	ds_read_b128 v[66:69], v123
	ds_read_b128 v[70:73], v123 offset:4096
	ds_read_b128 v[74:77], v119 offset:16384
	s_waitcnt lgkmcnt(0)
	v_mfma_f32_32x32x16_bf16 v[34:49], v[66:69], v[74:77], v[34:49]
	v_mfma_f32_32x32x16_bf16 v[2:17], v[70:73], v[74:77], v[2:17]
	ds_read_b128 v[74:77], v119 offset:20480
	s_waitcnt lgkmcnt(0)
	v_mfma_f32_32x32x16_bf16 v[50:65], v[66:69], v[74:77], v[50:65]
	v_mfma_f32_32x32x16_bf16 v[18:33], v[70:73], v[74:77], v[18:33]
	ds_read_b128 v[66:69], v122
	ds_read_b128 v[70:73], v122 offset:4096
	ds_read_b128 v[74:77], v118 offset:16384
	s_waitcnt lgkmcnt(0)
	v_mfma_f32_32x32x16_bf16 v[34:49], v[66:69], v[74:77], v[34:49]
	v_mfma_f32_32x32x16_bf16 v[2:17], v[70:73], v[74:77], v[2:17]
	ds_read_b128 v[74:77], v118 offset:20480
	s_waitcnt lgkmcnt(0)
	v_mfma_f32_32x32x16_bf16 v[50:65], v[66:69], v[74:77], v[50:65]
	v_mfma_f32_32x32x16_bf16 v[18:33], v[70:73], v[74:77], v[18:33]
	ds_read_b128 v[66:69], v121
	ds_read_b128 v[70:73], v121 offset:4096
	ds_read_b128 v[74:77], v117 offset:16384
	s_waitcnt lgkmcnt(0)
	v_mfma_f32_32x32x16_bf16 v[34:49], v[66:69], v[74:77], v[34:49]
	v_mfma_f32_32x32x16_bf16 v[2:17], v[70:73], v[74:77], v[2:17]
	ds_read_b128 v[74:77], v117 offset:20480
	s_waitcnt lgkmcnt(0)
	v_mfma_f32_32x32x16_bf16 v[50:65], v[66:69], v[74:77], v[50:65]
	v_mfma_f32_32x32x16_bf16 v[18:33], v[70:73], v[74:77], v[18:33]
	ds_read_b128 v[66:69], v120
	ds_read_b128 v[70:73], v120 offset:4096
	ds_read_b128 v[74:77], v0 offset:16384
	s_waitcnt lgkmcnt(0)
	v_mfma_f32_32x32x16_bf16 v[34:49], v[66:69], v[74:77], v[34:49]
	v_mfma_f32_32x32x16_bf16 v[2:17], v[70:73], v[74:77], v[2:17]
	ds_read_b128 v[74:77], v0 offset:20480
	s_waitcnt vmcnt(0)
	s_waitcnt vmcnt(0) lgkmcnt(0)
	s_barrier
; #define MFMA(a, b, c) __builtin_amdgcn_mfma_f32_32x32x16_bf16((a), (b), (c), 0, 0, 0)
; template <int NJ> DI void gemm_mainloop_glds(const bf16_t* __restrict__ A, int lda, const bf16_t* __restrict__ Bt, int ldb, int K, f32x16 (&acc)[2][NJ], char* lds) {
;     ...
; #pragma unroll
;     for (int ks = 0; ks < 4; ++ks) {
;       const bf16x8 a0 = *(const bf16x8*)(st_ + a_rd[ks]);
;       const bf16x8 a1 = *(const bf16x8*)(st_ + a_rd[ks] + 4096);
; #pragma unroll
;       for (int j = 0; j < NJ; ++j) {
;         const bf16x8 b = *(const bf16x8*)(st_ + b_rd[ks] + j * 4096);
;         acc[0][j] = MFMA(a0, b, acc[0][j]); acc[1][j] = MFMA(a1, b, acc[1][j]);
;       }
; DI void phase_ple(const Ctx& c, bool probe = false) {
;     ...
; #pragma unroll
;     for (int i = 0; i < 2; ++i)
; #pragma unroll
;       for (int j = 0; j < 2; ++j)
; #pragma unroll
;         for (int r2 = 0; r2 < 8; ++r2) {
;           const unsigned g2 = gp[i][j][r2];
;           acc[i][j][2 * r2] *= __uint_as_float(g2 << 16);
;           acc[i][j][2 * r2 + 1] *= __uint_as_float(g2 & 0xffff0000u);
;         }
	v_mfma_f32_32x32x16_bf16 v[50:65], v[66:69], v[74:77], v[50:65]
	v_mfma_f32_32x32x16_bf16 v[18:33], v[70:73], v[74:77], v[18:33]
	ds_read_b128 v[66:69], v123 offset:32768
	ds_read_b128 v[70:73], v123 offset:36864
	ds_read_b128 v[74:77], v119 offset:49152
	s_waitcnt lgkmcnt(0)
	v_mfma_f32_32x32x16_bf16 v[34:49], v[66:69], v[74:77], v[34:49]
	v_mfma_f32_32x32x16_bf16 v[2:17], v[70:73], v[74:77], v[2:17]
	ds_read_b128 v[74:77], v119 offset:53248
	s_waitcnt lgkmcnt(0)
	v_mfma_f32_32x32x16_bf16 v[50:65], v[66:69], v[74:77], v[50:65]
	v_mfma_f32_32x32x16_bf16 v[18:33], v[70:73], v[74:77], v[18:33]
	ds_read_b128 v[66:69], v122 offset:32768
	ds_read_b128 v[70:73], v122 offset:36864
	ds_read_b128 v[74:77], v118 offset:49152
	s_waitcnt lgkmcnt(0)
	v_mfma_f32_32x32x16_bf16 v[34:49], v[66:69], v[74:77], v[34:49]
	v_mfma_f32_32x32x16_bf16 v[2:17], v[70:73], v[74:77], v[2:17]
	ds_read_b128 v[74:77], v118 offset:53248
	s_waitcnt lgkmcnt(0)
	v_mfma_f32_32x32x16_bf16 v[50:65], v[66:69], v[74:77], v[50:65]
	v_mfma_f32_32x32x16_bf16 v[18:33], v[70:73], v[74:77], v[18:33]
	ds_read_b128 v[66:69], v121 offset:32768
	ds_read_b128 v[70:73], v121 offset:36864
	ds_read_b128 v[74:77], v117 offset:49152
	s_waitcnt lgkmcnt(0)
	v_mfma_f32_32x32x16_bf16 v[34:49], v[66:69], v[74:77], v[34:49]
	v_mfma_f32_32x32x16_bf16 v[2:17], v[70:73], v[74:77], v[2:17]
	ds_read_b128 v[74:77], v117 offset:53248
	s_waitcnt lgkmcnt(0)
	v_mfma_f32_32x32x16_bf16 v[50:65], v[66:69], v[74:77], v[50:65]
	v_mfma_f32_32x32x16_bf16 v[18:33], v[70:73], v[74:77], v[18:33]
	ds_read_b128 v[66:69], v120 offset:32768
	ds_read_b128 v[70:73], v120 offset:36864
	ds_read_b128 v[74:77], v0 offset:49152
	s_waitcnt lgkmcnt(0)
	v_mfma_f32_32x32x16_bf16 v[34:49], v[66:69], v[74:77], v[34:49]
	v_mfma_f32_32x32x16_bf16 v[2:17], v[70:73], v[74:77], v[2:17]
	ds_read_b128 v[74:77], v0 offset:53248
	v_lshlrev_b32_e32 v0, 16, v85
	s_nop 8
	v_mul_f32_e32 v0, v34, v0
	v_and_b32_e32 v34, 0xffff0000, v85
	v_mul_f32_e32 v34, v35, v34
	v_lshlrev_b32_e32 v35, 16, v86
	v_mul_f32_e32 v35, v36, v35
	v_and_b32_e32 v36, 0xffff0000, v86
	v_mul_f32_e32 v36, v37, v36
	v_lshlrev_b32_e32 v37, 16, v87
	v_mul_f32_e32 v37, v38, v37
	v_and_b32_e32 v38, 0xffff0000, v87
	v_mul_f32_e32 v38, v39, v38
	v_lshlrev_b32_e32 v39, 16, v88
	v_mul_f32_e32 v39, v40, v39
	v_and_b32_e32 v40, 0xffff0000, v88
	v_mul_f32_e32 v40, v41, v40
	v_lshlrev_b32_e32 v41, 16, v89
	s_waitcnt lgkmcnt(0)
	v_mfma_f32_32x32x16_bf16 v[50:65], v[66:69], v[74:77], v[50:65]
	s_setprio 0
	v_mul_f32_e32 v41, v42, v41
	v_and_b32_e32 v42, 0xffff0000, v89
	v_mul_f32_e32 v42, v43, v42
	v_lshlrev_b32_e32 v43, 16, v90
	v_mul_f32_e32 v43, v44, v43
	v_and_b32_e32 v44, 0xffff0000, v90
	v_mul_f32_e32 v44, v45, v44
	v_lshlrev_b32_e32 v45, 16, v91
	v_mul_f32_e32 v45, v46, v45
	v_and_b32_e32 v46, 0xffff0000, v91
	v_mul_f32_e32 v46, v47, v46
	v_lshlrev_b32_e32 v47, 16, v92
	v_mul_f32_e32 v47, v48, v47
	v_and_b32_e32 v48, 0xffff0000, v92
	v_mul_f32_e32 v48, v49, v48
	v_lshlrev_b32_e32 v49, 16, v93
	v_mul_f32_e32 v49, v50, v49
	v_and_b32_e32 v50, 0xffff0000, v93
	v_mul_f32_e32 v50, v51, v50
	v_lshlrev_b32_e32 v51, 16, v94
	v_mul_f32_e32 v51, v52, v51
	v_and_b32_e32 v52, 0xffff0000, v94
	v_mul_f32_e32 v52, v53, v52
	v_lshlrev_b32_e32 v53, 16, v95
	v_mul_f32_e32 v53, v54, v53
	v_and_b32_e32 v54, 0xffff0000, v95
	v_mul_f32_e32 v54, v55, v54
	v_lshlrev_b32_e32 v55, 16, v96
	v_mul_f32_e32 v55, v56, v55
	v_and_b32_e32 v56, 0xffff0000, v96
	v_mul_f32_e32 v56, v57, v56
	v_lshlrev_b32_e32 v57, 16, v97
	v_mul_f32_e32 v57, v58, v57
	v_and_b32_e32 v58, 0xffff0000, v97
	v_mul_f32_e32 v58, v59, v58
	v_lshlrev_b32_e32 v59, 16, v98
	v_mul_f32_e32 v59, v60, v59
	v_and_b32_e32 v60, 0xffff0000, v98
	v_mul_f32_e32 v60, v61, v60
	v_lshlrev_b32_e32 v61, 16, v99
	v_mul_f32_e32 v61, v62, v61
	v_and_b32_e32 v62, 0xffff0000, v99
	v_mul_f32_e32 v62, v63, v62
	v_lshlrev_b32_e32 v63, 16, v100
	v_mul_f32_e32 v63, v64, v63
	v_and_b32_e32 v64, 0xffff0000, v100
	v_mul_f32_e32 v64, v65, v64
	v_lshlrev_b32_e32 v65, 16, v101
	v_mul_f32_e32 v2, v2, v65
	v_and_b32_e32 v65, 0xffff0000, v101
	v_mul_f32_e32 v3, v3, v65
	v_lshlrev_b32_e32 v65, 16, v102
	v_mul_f32_e32 v4, v4, v65
	v_and_b32_e32 v65, 0xffff0000, v102
	v_mul_f32_e32 v5, v5, v65
	v_lshlrev_b32_e32 v65, 16, v103
	v_mul_f32_e32 v6, v6, v65
	v_and_b32_e32 v65, 0xffff0000, v103
	v_mul_f32_e32 v7, v7, v65
	v_lshlrev_b32_e32 v65, 16, v104
	v_mul_f32_e32 v8, v8, v65
	v_and_b32_e32 v65, 0xffff0000, v104
	v_mul_f32_e32 v9, v9, v65
	v_lshlrev_b32_e32 v65, 16, v105
	v_mfma_f32_32x32x16_bf16 v[18:33], v[70:73], v[74:77], v[18:33]
	v_mul_f32_e32 v10, v10, v65
	v_and_b32_e32 v65, 0xffff0000, v105
	v_mul_f32_e32 v11, v11, v65
	v_lshlrev_b32_e32 v65, 16, v106
	v_mul_f32_e32 v12, v12, v65
	v_and_b32_e32 v65, 0xffff0000, v106
	v_mul_f32_e32 v13, v13, v65
	v_lshlrev_b32_e32 v65, 16, v107
	v_mul_f32_e32 v14, v14, v65
	v_and_b32_e32 v65, 0xffff0000, v107
	v_mul_f32_e32 v15, v15, v65
	v_lshlrev_b32_e32 v65, 16, v108
	v_mul_f32_e32 v16, v16, v65
	v_and_b32_e32 v65, 0xffff0000, v108
	v_mul_f32_e32 v17, v17, v65
	v_lshlrev_b32_e32 v65, 16, v109
	v_mul_f32_e32 v18, v18, v65
	v_and_b32_e32 v65, 0xffff0000, v109
	v_mul_f32_e32 v19, v19, v65
	v_lshlrev_b32_e32 v65, 16, v110
	v_mul_f32_e32 v20, v20, v65
	v_and_b32_e32 v65, 0xffff0000, v110
	v_mul_f32_e32 v21, v21, v65
	v_lshlrev_b32_e32 v65, 16, v111
	v_mul_f32_e32 v22, v22, v65
	v_and_b32_e32 v65, 0xffff0000, v111
	v_mul_f32_e32 v23, v23, v65
	v_lshlrev_b32_e32 v65, 16, v112
	v_mul_f32_e32 v24, v24, v65
	v_and_b32_e32 v65, 0xffff0000, v112
	v_mul_f32_e32 v25, v25, v65
	v_lshlrev_b32_e32 v65, 16, v113
	v_mul_f32_e32 v26, v26, v65
	v_and_b32_e32 v65, 0xffff0000, v113
	v_mul_f32_e32 v27, v27, v65
	v_lshlrev_b32_e32 v65, 16, v114
	v_mul_f32_e32 v28, v28, v65
	v_and_b32_e32 v65, 0xffff0000, v114
	v_mul_f32_e32 v29, v29, v65
	v_lshlrev_b32_e32 v65, 16, v115
	v_mul_f32_e32 v30, v30, v65
	v_and_b32_e32 v65, 0xffff0000, v115
	v_mul_f32_e32 v31, v31, v65
	v_lshlrev_b32_e32 v65, 16, v116
	v_mul_f32_e32 v32, v32, v65
	v_and_b32_e32 v65, 0xffff0000, v116
	v_mul_f32_e32 v33, v33, v65
	v_mov_b32_e32 v65, v199
	s_waitcnt vmcnt(0)
	s_barrier
; DI int tid_() { int t = threadIdx.x; asm volatile("" : "+v"(t)); return t; }
; template <int NJ> DI void acc_to_lds(const f32x16 (&acc)[2][NJ], float* cl) {
;   const int tid = tid_(), lane = tid & 63, w = tid >> 6, wm = w >> 1, wn = w & 1, h = lane >> 5, c = lane & 31;
; #pragma unroll
;   for (int i = 0; i < 2; ++i)
; #pragma unroll
;     for (int j = 0; j < NJ; ++j)
; #pragma unroll
;       for (int r = 0; r < 16; ++r) {
;         const int row = wm * 64 + i * 32 + (r & 3) + 8 * (r >> 2) + 4 * h;
;         cl[row * CLD + wn * 32 * NJ + j * 32 + c] = acc[i][j][r];
;       }
; }
; template <int NJ> DI void resid_epilogue(float* __restrict__ x, bf16_t* __restrict__ xb, float* __restrict__ ssn, int mt, int nt, const float* cl, float scale) {
;   constexpr int LPR = 16 * NJ, RPP = 256 / LPR, NP = 128 / RPP;
;   const int tid = tid_(), c4 = (tid & (LPR - 1)) * 4, r0 = tid / LPR;
; #pragma unroll 4
;   for (int it = 0; it < NP; ++it) {
;     const int row = r0 + RPP * it;
;     const f32x4 c = *(const f32x4*)(cl + row * CLD + c4);
;     const size_t gi = (size_t)(mt * 128 + row) * DM + nt * (64 * NJ) + c4;
	s_nop 0
	v_lshrrev_b32_e32 v67, 3, v65
	v_lshrrev_b32_e32 v66, 1, v65
	v_and_b32_e32 v67, 4, v67
	v_and_b32_e32 v65, 0x5f, v65
	v_and_or_b32 v66, v66, s17, v67
	v_mul_lo_u32 v66, v66, s15
	v_lshlrev_b32_e32 v65, 2, v65
	v_add3_u32 v65, 0, v66, v65
	ds_write2_b32 v65, v0, v49 offset1:32
	ds_write2_b32 v65, v34, v50 offset0:132 offset1:164
	v_add_u32_e32 v0, 0x400, v65
	ds_write2_b32 v0, v35, v51 offset0:8 offset1:40
	ds_write2_b32 v0, v36, v52 offset0:140 offset1:172
	v_add_u32_e32 v0, 0x1000, v65
	ds_write2_b32 v0, v37, v53 offset0:32 offset1:64
	ds_write2_b32 v0, v38, v54 offset0:164 offset1:196
	v_add_u32_e32 v0, 0x1400, v65
	ds_write2_b32 v0, v39, v55 offset0:40 offset1:72
	ds_write2_b32 v0, v40, v56 offset0:172 offset1:204
	v_add_u32_e32 v0, 0x2000, v65
	ds_write2_b32 v0, v41, v57 offset0:64 offset1:96
	ds_write2_b32 v0, v42, v58 offset0:196 offset1:228
	v_add_u32_e32 v0, 0x2400, v65
	ds_write2_b32 v0, v43, v59 offset0:72 offset1:104
	ds_write2_b32 v0, v44, v60 offset0:204 offset1:236
	v_add_u32_e32 v0, 0x3000, v65
	ds_write2_b32 v0, v45, v61 offset0:96 offset1:128
	v_add_u32_e32 v0, 0x3200, v65
	ds_write2_b32 v0, v46, v62 offset0:100 offset1:132
	v_add_u32_e32 v0, 0x3400, v65
	ds_write2_b32 v0, v47, v63 offset0:104 offset1:136
	v_add_u32_e32 v0, 0x3600, v65
	ds_write2_b32 v0, v48, v64 offset0:108 offset1:140
	v_add_u32_e32 v0, 0x4000, v65
	ds_write2_b32 v0, v2, v18 offset0:128 offset1:160
	v_add_u32_e32 v0, 0x4400, v65
	ds_write2_b32 v0, v3, v19 offset0:4 offset1:36
	ds_write2_b32 v0, v4, v20 offset0:136 offset1:168
	v_add_u32_e32 v0, 0x4800, v65
	ds_write2_b32 v0, v5, v21 offset0:12 offset1:44
	v_add_u32_e32 v0, 0x5000, v65
	ds_write2_b32 v0, v6, v22 offset0:160 offset1:192
	v_add_u32_e32 v0, 0x5400, v65
	ds_write2_b32 v0, v7, v23 offset0:36 offset1:68
	ds_write2_b32 v0, v8, v24 offset0:168 offset1:200
	v_add_u32_e32 v0, 0x5800, v65
	ds_write2_b32 v0, v9, v25 offset0:44 offset1:76
	v_add_u32_e32 v0, 0x6000, v65
	ds_write2_b32 v0, v10, v26 offset0:192 offset1:224
	v_add_u32_e32 v0, 0x6400, v65
	ds_write2_b32 v0, v11, v27 offset0:68 offset1:100
	ds_write2_b32 v0, v12, v28 offset0:200 offset1:232
	v_add_u32_e32 v0, 0x6800, v65
	ds_write2_b32 v0, v13, v29 offset0:76 offset1:108
	v_add_u32_e32 v0, 0x7200, v65
	ds_write2_b32 v0, v14, v30 offset0:96 offset1:128
	v_add_u32_e32 v0, 0x7400, v65
	ds_write2_b32 v0, v15, v31 offset0:100 offset1:132
	v_add_u32_e32 v0, 0x7600, v65
	ds_write2_b32 v0, v16, v32 offset0:104 offset1:136
	v_add_u32_e32 v0, 0x7800, v65
	ds_write2_b32 v0, v17, v33 offset0:108 offset1:140
	v_mov_b32_e32 v0, v199
	s_waitcnt lgkmcnt(0)
	s_barrier
	v_mov_b64_e32 v[18:19], s[72:73]
	v_ashrrev_i32_e32 v2, 31, v0
	v_lshrrev_b32_e32 v2, 27, v2
	v_and_b32_e32 v6, 31, v0
	v_add_u32_e32 v0, v0, v2
	v_ashrrev_i32_e32 v14, 5, v0
	v_cndmask_b32_e64 v0, v219, v222, s[0:1]
	v_cmp_lt_i32_e64 s[0:1], v223, v220
	v_lshlrev_b32_e32 v22, 2, v0
	v_add_u32_e32 v20, s46, v14
	v_cndmask_b32_e64 v0, v219, v223, s[0:1]
	v_cmp_lt_i32_e64 s[0:1], v224, v220
	v_lshlrev_b32_e32 v23, 2, v0
	v_cmp_eq_u32_e64 s[36:37], 0, v6
	v_cndmask_b32_e64 v0, v219, v224, s[0:1]
	v_cmp_lt_i32_e64 s[0:1], v225, v220
	v_lshlrev_b32_e32 v24, 2, v0
	v_ashrrev_i32_e32 v15, 31, v14
	v_cndmask_b32_e64 v0, v219, v225, s[0:1]
	v_cmp_lt_i32_e64 s[0:1], v226, v220
	v_lshlrev_b32_e32 v25, 2, v0
	v_lshlrev_b32_e32 v28, 4, v6
	v_cndmask_b32_e64 v0, v219, v226, s[0:1]
	s_add_i32 s0, s44, s11
	v_add_u32_e32 v4, s0, v14
	v_mad_i64_i32 v[2:3], s[0:1], v4, s9, v[18:19]
	s_add_i32 s0, s44, s12
	s_nop 0
	v_add_u32_e32 v10, s0, v14
	v_mad_i64_i32 v[8:9], s[0:1], v10, s9, v[18:19]
	s_add_u32 s0, s45, s34
	s_addc_u32 s1, 0, s35
	s_add_i32 s44, s44, s13
	v_add_u32_e32 v16, s44, v14
	v_lshlrev_b32_e32 v26, 2, v0
	v_ashrrev_i32_e32 v5, 31, v4
	v_lshlrev_b32_e32 v0, 3, v6
	v_mul_lo_u32 v6, v14, s15
	v_ashrrev_i32_e32 v21, 31, v20
	v_ashrrev_i32_e32 v11, 31, v10
	v_ashrrev_i32_e32 v17, 31, v16
	v_lshlrev_b64 v[4:5], 12, v[4:5]
	v_add3_u32 v27, v6, v28, 0
	v_lshlrev_b64 v[6:7], 12, v[20:21]
	v_lshlrev_b64 v[10:11], 12, v[10:11]
	v_lshl_add_u64 v[12:13], v[14:15], 2, s[0:1]
	v_mad_i64_i32 v[14:15], s[0:1], v16, s9, v[18:19]
	v_lshlrev_b64 v[16:17], 12, v[16:17]
	v_mad_i64_i32 v[18:19], s[0:1], v20, s9, v[18:19]
	v_lshl_add_u64 v[2:3], v[2:3], 0, v[0:1]
	v_or3_b32 v4, v4, s43, v28
	v_or3_b32 v6, v6, s43, v28
	v_lshl_add_u64 v[8:9], v[8:9], 0, v[0:1]
	v_or3_b32 v10, v10, s43, v28
	v_lshl_add_u64 v[14:15], v[14:15], 0, v[0:1]
	v_or3_b32 v16, v16, s43, v28
	v_lshl_add_u64 v[18:19], v[18:19], 0, v[0:1]
	v_lshl_add_u64 v[2:3], v[2:3], 0, s[2:3]
	v_lshl_add_u64 v[4:5], s[92:93], 0, v[4:5]
	v_lshl_add_u64 v[6:7], s[92:93], 0, v[6:7]
	v_lshl_add_u64 v[8:9], v[8:9], 0, s[2:3]
	v_lshl_add_u64 v[10:11], s[92:93], 0, v[10:11]
	v_lshl_add_u64 v[14:15], v[14:15], 0, s[2:3]
	v_lshl_add_u64 v[16:17], s[92:93], 0, v[16:17]
	v_lshl_add_u64 v[18:19], v[18:19], 0, s[2:3]
	s_mov_b64 s[0:1], 0
	s_branch .LBB0_1228
